# cache-policy experiment: nt hint on all 426 16-byte global stores (GEMM epilogues, transposes, final_norm, fixups), on top of v15
# speedup vs baseline: 1.0105x; 1.0001x over previous
; #define LAS __attribute__((address_space(3)))
; DI unsigned pk2(float lo, float hi) { unsigned r; asm volatile("v_cvt_pk_bf16_f32 %0, %1, %2" : "=v"(r) : "v"(lo), "v"(hi)); return r; }
; #define LDS_WAIT() asm volatile("s_waitcnt lgkmcnt(0)" ::: "memory")
; DI void transpose_item(const float* W, int N, bf16_t* WT, size_t ldo, const float* sc, LAS float* scr, int item, int lane) {
;     ...
;     for (int i = 0; i < 8; ++i) { const int kk = 8 * i + (lane >> 3), n4 = (lane & 7) * 4;
;         f32x4 w = *(const f32x4*)(W + (size_t)(k0 + kk) * N + n0 + n4); if (sc) w = w * sc[k0 + kk];
;         LAS float* d = scr + kk * 33 + n4; d[0] = w.x; d[1] = w.y; d[2] = w.z; d[3] = w.w; }
;     LDS_WAIT();
;     const int c = lane & 7;
; #pragma unroll
;     for (int j = 0; j < 4; ++j) { const int n = (lane >> 3) + 8 * j; const LAS float* s = scr + (8 * c) * 33 + n;
;         u32x4v o; o.x = pk2(s[0 * 33], s[1 * 33]); o.y = pk2(s[2 * 33], s[3 * 33]); o.z = pk2(s[4 * 33], s[5 * 33]); o.w = pk2(s[6 * 33], s[7 * 33]);
;         *(u32x4v*)(WT + (size_t)(n0 + n) * ldo + k0 + 8 * c) = o; }
;     LDS_WAIT();
.LBB0_8:
	s_waitcnt vmcnt(0)
	v_add_u32_e32 v2, 0x1ce0, v61
	ds_write2_b32 v2, v6, v7 offset1:1
	v_add_u32_e32 v2, 0x1ce8, v61
	ds_write2_b32 v2, v8, v9 offset1:1
	s_waitcnt lgkmcnt(0)
	v_add_u32_e32 v10, s36, v158
	ds_read2_b32 v[2:3], v60 offset1:33
	v_ashrrev_i32_e32 v11, 31, v10
	s_waitcnt lgkmcnt(0)
	v_cvt_pk_bf16_f32 v2, v2, v3
	ds_read2_b32 v[4:5], v60 offset0:66 offset1:99
	v_lshl_add_u64 v[8:9], s[38:39], 1, v[46:47]
	v_lshlrev_b64 v[12:13], 11, v[10:11]
	s_waitcnt lgkmcnt(0)
	v_cvt_pk_bf16_f32 v3, v4, v5
	ds_read2_b32 v[4:5], v60 offset0:132 offset1:165
	v_lshl_add_u64 v[12:13], v[8:9], 0, v[12:13]
	s_waitcnt lgkmcnt(0)
	v_cvt_pk_bf16_f32 v4, v4, v5
	ds_read2_b32 v[6:7], v60 offset0:198 offset1:231
	s_waitcnt lgkmcnt(0)
	v_cvt_pk_bf16_f32 v5, v6, v7
	global_store_dwordx4 v[12:13], v[2:5], off nt
	v_add_u32_e32 v12, 8, v10
	v_ashrrev_i32_e32 v13, 31, v12
	ds_read2_b32 v[6:7], v60 offset0:8 offset1:41
	s_waitcnt lgkmcnt(0)
	v_cvt_pk_bf16_f32 v2, v6, v7
	ds_read2_b32 v[4:5], v60 offset0:74 offset1:107
	v_lshlrev_b64 v[12:13], 11, v[12:13]
	s_waitcnt lgkmcnt(0)
	v_cvt_pk_bf16_f32 v3, v4, v5
	ds_read2_b32 v[4:5], v60 offset0:140 offset1:173
	v_lshl_add_u64 v[12:13], v[8:9], 0, v[12:13]
	s_waitcnt lgkmcnt(0)
	v_cvt_pk_bf16_f32 v4, v4, v5
	ds_read2_b32 v[6:7], v60 offset0:206 offset1:239
	s_waitcnt lgkmcnt(0)
	v_cvt_pk_bf16_f32 v5, v6, v7
	global_store_dwordx4 v[12:13], v[2:5], off nt
	v_add_u32_e32 v12, 16, v10
	ds_read2_b32 v[6:7], v60 offset0:16 offset1:49
	s_waitcnt lgkmcnt(0)
	v_cvt_pk_bf16_f32 v2, v6, v7
	ds_read2_b32 v[4:5], v60 offset0:82 offset1:115
	v_ashrrev_i32_e32 v13, 31, v12
	s_waitcnt lgkmcnt(0)
	v_cvt_pk_bf16_f32 v3, v4, v5
	ds_read2_b32 v[4:5], v60 offset0:148 offset1:181
	v_lshlrev_b64 v[12:13], 11, v[12:13]
	s_waitcnt lgkmcnt(0)
	v_cvt_pk_bf16_f32 v4, v4, v5
	ds_read2_b32 v[6:7], v60 offset0:214 offset1:247
	s_waitcnt lgkmcnt(0)
	v_cvt_pk_bf16_f32 v5, v6, v7
	v_lshl_add_u64 v[12:13], v[8:9], 0, v[12:13]
	ds_read2_b32 v[6:7], v60 offset0:24 offset1:57
	global_store_dwordx4 v[12:13], v[2:5], off nt
	v_add_u32_e32 v10, 24, v10
	v_ashrrev_i32_e32 v11, 31, v10
	s_waitcnt lgkmcnt(0)
	v_cvt_pk_bf16_f32 v2, v6, v7
	ds_read2_b32 v[4:5], v60 offset0:90 offset1:123
	s_waitcnt lgkmcnt(0)
	v_cvt_pk_bf16_f32 v3, v4, v5
	ds_read2_b32 v[4:5], v60 offset0:156 offset1:189
	s_waitcnt lgkmcnt(0)
	v_cvt_pk_bf16_f32 v4, v4, v5
	ds_read2_b32 v[6:7], v60 offset0:222 offset1:255
	v_lshlrev_b64 v[10:11], 11, v[10:11]
	s_waitcnt lgkmcnt(0)
	v_cvt_pk_bf16_f32 v5, v6, v7
	v_lshl_add_u64 v[6:7], v[8:9], 0, v[10:11]
	global_store_dwordx4 v[6:7], v[2:5], off nt
	s_waitcnt lgkmcnt(0)
	v_readlane_b32 s2, v254, 50
	s_mov_b32 s28, s2
	v_readlane_b32 s3, v254, 51

; #define LAS __attribute__((address_space(3)))
; DI unsigned pk2(float lo, float hi) { unsigned r; asm volatile("v_cvt_pk_bf16_f32 %0, %1, %2" : "=v"(r) : "v"(lo), "v"(hi)); return r; }
; DI void transpose_item(const float* W, int N, bf16_t* WT, size_t ldo, const float* sc, LAS float* scr, int item, int lane) {
;     const int nblk = N / 32, kb = item / nblk, nb = item % nblk, k0 = 64 * kb, n0 = 32 * nb;
; #pragma unroll
;     for (int i = 0; i < 8; ++i) { const int kk = 8 * i + (lane >> 3), n4 = (lane & 7) * 4;
;         f32x4 w = *(const f32x4*)(W + (size_t)(k0 + kk) * N + n0 + n4); if (sc) w = w * sc[k0 + kk];
;         LAS float* d = scr + kk * 33 + n4; d[0] = w.x; d[1] = w.y; d[2] = w.z; d[3] = w.w; }
;     LDS_WAIT();
;     const int c = lane & 7;
; #pragma unroll
;     for (int j = 0; j < 4; ++j) { const int n = (lane >> 3) + 8 * j; const LAS float* s = scr + (8 * c) * 33 + n;
;         u32x4v o; o.x = pk2(s[0 * 33], s[1 * 33]); o.y = pk2(s[2 * 33], s[3 * 33]); o.z = pk2(s[4 * 33], s[5 * 33]); o.w = pk2(s[6 * 33], s[7 * 33]);
;         *(u32x4v*)(WT + (size_t)(n0 + n) * ldo + k0 + 8 * c) = o; }
;     LDS_WAIT();
; DI void phase_prologue(const Prm& p, LAS unsigned char* lds, int tid, int lane, int wave) {
;     ...
;     for (int it = gw; it < NITEMS; it += NGW) {
;         int r = it;
;         if (r < I1) { transpose_item(p.w_in_even, 2560, p.Wt1, 1024, p.ln_mix, scr, r, lane); continue; } r -= I1;
;         if (r < I2) { transpose_item(p.w_glu, 512, p.Wglu, 512, nullptr, scr, r, lane); continue; } r -= I2;
;         if (r < I3) { transpose_item(p.w_out_even, 1024, p.Wo0, 1024, nullptr, scr, r, lane); continue; } r -= I3;
;         if (r < I4) { transpose_item(p.w_up, 4096, p.Wup0, 1024, p.ln_mlp, scr, r, lane); continue; } r -= I4;
;         if (r < I5) { transpose_item(p.w_down, 1024, p.Wdn0, 4096, nullptr, scr, r, lane); continue; } r -= I5;
;         if (r < I6) { transpose_item(p.w_in_odd, 3072, p.Wqkv, 1024, p.ln_mix + 1024, scr, r, lane); continue; } r -= I6;
;         if (r < I3) { transpose_item(p.w_out_odd, 1024, p.Wo1, 1024, nullptr, scr, r, lane); continue; } r -= I3;
;         if (r < I4) { transpose_item(p.w_up + (size_t)1024 * 4096, 4096, p.Wup1, 1024, p.ln_mlp + 1024, scr, r, lane); continue; } r -= I4;
;         transpose_item(p.w_down + (size_t)4096 * 1024, 1024, p.Wdn1, 4096, nullptr, scr, r, lane);
.LBB0_10:
	s_cmpk_gt_i32 s43, 0x4ff
	s_mov_b64 s[2:3], -1
	s_cbranch_scc0 .LBB0_57
	s_cmpk_gt_u32 s43, 0x57f
	s_cbranch_scc0 .LBB0_54
	s_cmpk_gt_u32 s43, 0x77f
	s_cbranch_scc0 .LBB0_51
	s_cmpk_gt_u32 s43, 0xf7f
	s_cbranch_scc0 .LBB0_31
	s_cmpk_gt_u32 s43, 0x177f
	s_cbranch_scc0 .LBB0_28
	s_cmpk_gt_u32 s43, 0x1d7f
	s_cbranch_scc0 .LBB0_25
	s_cmpk_gt_u32 s43, 0x1f7f
	s_cbranch_scc0 .LBB0_22
	s_cmpk_gt_u32 s43, 0x277f
	s_cbranch_scc0 .LBB0_19
	s_and_b32 s3, s29, 0x1ffc0
	s_and_b32 s2, s31, 0x3e0
	s_lshl_b32 s26, s2, 2
	v_or_b32_e32 v2, s3, v158
	v_lshl_add_u64 v[52:53], v[48:49], 0, s[26:27]
	v_lshlrev_b32_e32 v14, 12, v2
	v_or_b32_e32 v4, s3, v1
	v_lshl_add_u64 v[2:3], v[52:53], 0, v[14:15]
	v_lshlrev_b32_e32 v14, 12, v4
	v_or_b32_e32 v10, s3, v54
	v_lshl_add_u64 v[6:7], v[52:53], 0, v[14:15]
	v_lshlrev_b32_e32 v14, 12, v10
	v_or_b32_e32 v12, s3, v55
	v_lshl_add_u64 v[10:11], v[52:53], 0, v[14:15]
	v_lshlrev_b32_e32 v14, 12, v12
	v_lshl_add_u64 v[68:69], v[52:53], 0, v[14:15]
	v_or_b32_e32 v14, s3, v56
	v_lshlrev_b32_e32 v14, 12, v14
	v_lshl_add_u64 v[72:73], v[52:53], 0, v[14:15]
	v_or_b32_e32 v14, s3, v57
	v_lshlrev_b32_e32 v14, 12, v14
	v_lshl_add_u64 v[76:77], v[52:53], 0, v[14:15]
	global_load_dwordx4 v[2:5], v[2:3], off
	s_nop 0
	global_load_dwordx4 v[6:9], v[6:7], off
	s_nop 0
	global_load_dwordx4 v[10:13], v[10:11], off
	s_nop 0
	global_load_dwordx4 v[68:71], v[68:69], off
	s_nop 0
	global_load_dwordx4 v[72:75], v[72:73], off
	s_nop 0
	global_load_dwordx4 v[76:79], v[76:77], off
	v_or_b32_e32 v14, s3, v58
	v_lshlrev_b32_e32 v14, 12, v14
	v_lshl_add_u64 v[80:81], v[52:53], 0, v[14:15]
	v_or_b32_e32 v14, s3, v59
	global_load_dwordx4 v[80:83], v[80:81], off
	v_lshlrev_b32_e32 v14, 12, v14
	v_lshl_add_u64 v[52:53], v[52:53], 0, v[14:15]
	global_load_dwordx4 v[84:87], v[52:53], off
	v_add_u32_e32 v14, 0x1080, v61
	v_add_u32_e32 v52, 0x1088, v61
	v_add_u32_e32 v53, 0x14a0, v61
	v_add_u32_e32 v88, 0x14a8, v61
	v_add_u32_e32 v89, 0x18c0, v61
	v_add_u32_e32 v90, 0x18c8, v61
	v_add_u32_e32 v91, 0x1ce0, v61
	v_add_u32_e32 v92, 0x1ce8, v61
	s_lshl_b32 s26, s3, 1
	s_waitcnt vmcnt(7)
	ds_write2_b32 v61, v2, v3 offset1:1
	ds_write2_b32 v61, v4, v5 offset0:2 offset1:3
	s_waitcnt vmcnt(6)
	ds_write2_b32 v62, v6, v7 offset1:1
	ds_write2_b32 v63, v8, v9 offset1:1
	s_waitcnt vmcnt(5)
	ds_write2_b32 v64, v10, v11 offset1:1
	ds_write2_b32 v65, v12, v13 offset1:1
	s_waitcnt vmcnt(4)
	ds_write2_b32 v66, v68, v69 offset1:1
	ds_write2_b32 v67, v70, v71 offset1:1
	s_waitcnt vmcnt(3)
	ds_write2_b32 v14, v72, v73 offset1:1
	ds_write2_b32 v52, v74, v75 offset1:1
	s_waitcnt vmcnt(2)
	ds_write2_b32 v53, v76, v77 offset1:1
	ds_write2_b32 v88, v78, v79 offset1:1
	s_waitcnt vmcnt(1)
	ds_write2_b32 v89, v80, v81 offset1:1
	ds_write2_b32 v90, v82, v83 offset1:1
	s_waitcnt vmcnt(0)
	ds_write2_b32 v91, v84, v85 offset1:1
	ds_write2_b32 v92, v86, v87 offset1:1
	s_waitcnt lgkmcnt(0)
	ds_read2_b32 v[2:3], v60 offset1:33
	s_waitcnt lgkmcnt(0)
	v_cvt_pk_bf16_f32 v2, v2, v3
	ds_read2_b32 v[4:5], v60 offset0:66 offset1:99
	v_or_b32_e32 v10, s2, v158
	s_waitcnt lgkmcnt(0)
	v_cvt_pk_bf16_f32 v3, v4, v5
	ds_read2_b32 v[4:5], v60 offset0:132 offset1:165
	v_lshl_add_u64 v[8:9], v[16:17], 0, s[26:27]
	v_lshlrev_b32_e32 v14, 13, v10
	s_waitcnt lgkmcnt(0)
	v_cvt_pk_bf16_f32 v4, v4, v5
	ds_read2_b32 v[6:7], v60 offset0:198 offset1:231
	s_waitcnt lgkmcnt(0)
	v_cvt_pk_bf16_f32 v5, v6, v7
	v_lshl_add_u64 v[10:11], v[8:9], 0, v[14:15]
	ds_read2_b32 v[6:7], v60 offset0:8 offset1:41
	global_store_dwordx4 v[10:11], v[2:5], off nt
	v_or_b32_e32 v10, s2, v1
	v_lshlrev_b32_e32 v14, 13, v10
	s_waitcnt lgkmcnt(0)
	v_cvt_pk_bf16_f32 v2, v6, v7
	ds_read2_b32 v[4:5], v60 offset0:74 offset1:107
	s_waitcnt lgkmcnt(0)
	v_cvt_pk_bf16_f32 v3, v4, v5
	ds_read2_b32 v[4:5], v60 offset0:140 offset1:173
	s_waitcnt lgkmcnt(0)
	v_cvt_pk_bf16_f32 v4, v4, v5
	ds_read2_b32 v[6:7], v60 offset0:206 offset1:239
	s_waitcnt lgkmcnt(0)
	v_cvt_pk_bf16_f32 v5, v6, v7
	v_lshl_add_u64 v[10:11], v[8:9], 0, v[14:15]
	ds_read2_b32 v[6:7], v60 offset0:16 offset1:49
	global_store_dwordx4 v[10:11], v[2:5], off nt
	v_or_b32_e32 v10, s2, v54
	v_lshlrev_b32_e32 v14, 13, v10
	s_waitcnt lgkmcnt(0)
	v_cvt_pk_bf16_f32 v2, v6, v7
	ds_read2_b32 v[4:5], v60 offset0:82 offset1:115
	s_waitcnt lgkmcnt(0)
	v_cvt_pk_bf16_f32 v3, v4, v5
	ds_read2_b32 v[4:5], v60 offset0:148 offset1:181
	s_waitcnt lgkmcnt(0)
	v_cvt_pk_bf16_f32 v4, v4, v5
	ds_read2_b32 v[6:7], v60 offset0:214 offset1:247
	s_waitcnt lgkmcnt(0)
	v_cvt_pk_bf16_f32 v5, v6, v7
	v_lshl_add_u64 v[10:11], v[8:9], 0, v[14:15]
	ds_read2_b32 v[6:7], v60 offset0:24 offset1:57
	global_store_dwordx4 v[10:11], v[2:5], off nt
	s_waitcnt lgkmcnt(0)
	s_nop 0
	v_cvt_pk_bf16_f32 v2, v6, v7
	ds_read2_b32 v[4:5], v60 offset0:90 offset1:123
	s_waitcnt lgkmcnt(0)
	v_cvt_pk_bf16_f32 v3, v4, v5
	ds_read2_b32 v[4:5], v60 offset0:156 offset1:189
	s_waitcnt lgkmcnt(0)
	v_cvt_pk_bf16_f32 v4, v4, v5
	v_or_b32_e32 v5, s2, v55
	ds_read2_b32 v[6:7], v60 offset0:222 offset1:255
	v_lshlrev_b32_e32 v14, 13, v5
	s_waitcnt lgkmcnt(0)
	v_cvt_pk_bf16_f32 v5, v6, v7
	v_lshl_add_u64 v[6:7], v[8:9], 0, v[14:15]
	global_store_dwordx4 v[6:7], v[2:5], off nt
	s_waitcnt lgkmcnt(0)
	s_mov_b64 s[2:3], 0
; #define LAS __attribute__((address_space(3)))
; DI unsigned pk2(float lo, float hi) { unsigned r; asm volatile("v_cvt_pk_bf16_f32 %0, %1, %2" : "=v"(r) : "v"(lo), "v"(hi)); return r; }
; #define LDS_WAIT() asm volatile("s_waitcnt lgkmcnt(0)" ::: "memory")
; DI void transpose_item(const float* W, int N, bf16_t* WT, size_t ldo, const float* sc, LAS float* scr, int item, int lane) {
;     const int nblk = N / 32, kb = item / nblk, nb = item % nblk, k0 = 64 * kb, n0 = 32 * nb;
; #pragma unroll
;     for (int i = 0; i < 8; ++i) { const int kk = 8 * i + (lane >> 3), n4 = (lane & 7) * 4;
;         f32x4 w = *(const f32x4*)(W + (size_t)(k0 + kk) * N + n0 + n4); if (sc) w = w * sc[k0 + kk];
;         LAS float* d = scr + kk * 33 + n4; d[0] = w.x; d[1] = w.y; d[2] = w.z; d[3] = w.w; }
;     LDS_WAIT();
;     const int c = lane & 7;
; #pragma unroll
;     for (int j = 0; j < 4; ++j) { const int n = (lane >> 3) + 8 * j; const LAS float* s = scr + (8 * c) * 33 + n;
;         u32x4v o; o.x = pk2(s[0 * 33], s[1 * 33]); o.y = pk2(s[2 * 33], s[3 * 33]); o.z = pk2(s[4 * 33], s[5 * 33]); o.w = pk2(s[6 * 33], s[7 * 33]);
;         *(u32x4v*)(WT + (size_t)(n0 + n) * ldo + k0 + 8 * c) = o; }
;     LDS_WAIT();
; DI void phase_prologue(const Prm& p, LAS unsigned char* lds, int tid, int lane, int wave) {
;     ...
;         if (r < I4) { transpose_item(p.w_up + (size_t)1024 * 4096, 4096, p.Wup1, 1024, p.ln_mlp + 1024, scr, r, lane); continue; } r -= I4;
.LBB0_19:
	s_andn2_b64 vcc, exec, s[2:3]
	s_cbranch_vccnz .LBB0_21
	s_add_i32 s2, s43, 0xe080
	s_lshr_b32 s2, s2, 1
	s_and_b32 s3, s2, 0x7fc0
	s_and_b32 s2, s31, 0xfe0
	s_lshl_b32 s26, s2, 2
	v_or_b32_e32 v6, s3, v158
	v_lshl_add_u64 v[52:53], v[50:51], 0, s[26:27]
	v_lshlrev_b32_e32 v14, 14, v6
	v_or_b32_e32 v10, s3, v1
	v_lshl_add_u64 v[2:3], v[52:53], 0, v[14:15]
	v_lshlrev_b32_e32 v6, 2, v6
	v_lshlrev_b32_e32 v14, 14, v10
	v_lshlrev_b32_e32 v10, 2, v10
	v_or_b32_e32 v68, s3, v54
	global_load_dword v88, v6, s[4:5]
	global_load_dword v90, v10, s[4:5]
	v_lshl_add_u64 v[6:7], v[52:53], 0, v[14:15]
	v_lshlrev_b32_e32 v14, 14, v68
	v_lshl_add_u64 v[10:11], v[52:53], 0, v[14:15]
	v_lshlrev_b32_e32 v14, 2, v68
	v_or_b32_e32 v72, s3, v55
	global_load_dword v92, v14, s[4:5]
	v_lshlrev_b32_e32 v14, 14, v72
	v_lshl_add_u64 v[68:69], v[52:53], 0, v[14:15]
	v_lshlrev_b32_e32 v14, 2, v72
	v_or_b32_e32 v76, s3, v56
	global_load_dword v94, v14, s[4:5]
	v_lshlrev_b32_e32 v14, 14, v76
	global_load_dwordx4 v[2:5], v[2:3], off
	v_lshl_add_u64 v[72:73], v[52:53], 0, v[14:15]
	v_lshlrev_b32_e32 v14, 2, v76
	v_or_b32_e32 v80, s3, v57
	global_load_dwordx4 v[6:9], v[6:7], off
	v_or_b32_e32 v84, s3, v58
	global_load_dword v96, v14, s[4:5]
	v_lshlrev_b32_e32 v14, 14, v80
	global_load_dwordx4 v[10:13], v[10:11], off
	v_lshl_add_u64 v[76:77], v[52:53], 0, v[14:15]
	v_lshlrev_b32_e32 v14, 2, v80
	global_load_dwordx4 v[68:71], v[68:69], off
	v_add_u32_e32 v89, 0x14a0, v61
	global_load_dword v98, v14, s[4:5]
	v_lshlrev_b32_e32 v14, 14, v84
	global_load_dwordx4 v[72:75], v[72:73], off
	v_lshl_add_u64 v[80:81], v[52:53], 0, v[14:15]
	v_lshlrev_b32_e32 v14, 2, v84
	v_or_b32_e32 v84, s3, v59
	global_load_dwordx4 v[76:79], v[76:77], off
	v_add_u32_e32 v91, 0x14a8, v61
	global_load_dword v100, v14, s[4:5]
	v_lshlrev_b32_e32 v14, 14, v84
	global_load_dwordx4 v[80:83], v[80:81], off
	v_lshl_add_u64 v[52:53], v[52:53], 0, v[14:15]
	v_lshlrev_b32_e32 v14, 2, v84
	global_load_dword v14, v14, s[4:5]
	s_nop 0
	global_load_dwordx4 v[84:87], v[52:53], off
	v_add_u32_e32 v93, 0x18c0, v61
	v_add_u32_e32 v95, 0x18c8, v61
	v_add_u32_e32 v97, 0x1ce0, v61
	v_add_u32_e32 v52, 0x1080, v61
	v_add_u32_e32 v99, 0x1ce8, v61
	v_add_u32_e32 v53, 0x1088, v61
	s_lshl_b32 s26, s3, 1
	s_waitcnt vmcnt(11)
	v_pk_mul_f32 v[4:5], v[4:5], v[88:89] op_sel_hi:[1,0]
	v_pk_mul_f32 v[2:3], v[2:3], v[88:89] op_sel_hi:[1,0]
	ds_write2_b32 v61, v2, v3 offset1:1
	ds_write2_b32 v61, v4, v5 offset0:2 offset1:3
	s_waitcnt vmcnt(10)
	v_pk_mul_f32 v[4:5], v[6:7], v[90:91] op_sel_hi:[1,0]
	v_pk_mul_f32 v[2:3], v[8:9], v[90:91] op_sel_hi:[1,0]
	ds_write2_b32 v62, v4, v5 offset1:1
	ds_write2_b32 v63, v2, v3 offset1:1
	v_lshl_add_u64 v[8:9], v[18:19], 0, s[26:27]
	s_waitcnt vmcnt(8)
	v_pk_mul_f32 v[4:5], v[10:11], v[92:93] op_sel_hi:[1,0]
	v_pk_mul_f32 v[2:3], v[12:13], v[92:93] op_sel_hi:[1,0]
	ds_write2_b32 v64, v4, v5 offset1:1
	ds_write2_b32 v65, v2, v3 offset1:1
	s_waitcnt vmcnt(7)
	v_pk_mul_f32 v[4:5], v[68:69], v[94:95] op_sel_hi:[1,0]
	v_pk_mul_f32 v[2:3], v[70:71], v[94:95] op_sel_hi:[1,0]
	ds_write2_b32 v66, v4, v5 offset1:1
	ds_write2_b32 v67, v2, v3 offset1:1
	v_or_b32_e32 v10, s2, v158
	s_waitcnt vmcnt(5)
	v_pk_mul_f32 v[4:5], v[72:73], v[96:97] op_sel_hi:[1,0]
	v_pk_mul_f32 v[2:3], v[74:75], v[96:97] op_sel_hi:[1,0]
	ds_write2_b32 v52, v4, v5 offset1:1
	ds_write2_b32 v53, v2, v3 offset1:1
	s_waitcnt vmcnt(4)
	v_pk_mul_f32 v[4:5], v[76:77], v[98:99] op_sel_hi:[1,0]
	v_pk_mul_f32 v[2:3], v[78:79], v[98:99] op_sel_hi:[1,0]
	ds_write2_b32 v89, v4, v5 offset1:1
	ds_write2_b32 v91, v2, v3 offset1:1
	s_waitcnt vmcnt(2)
	v_pk_mul_f32 v[4:5], v[80:81], v[100:101] op_sel_hi:[1,0]
	v_pk_mul_f32 v[2:3], v[82:83], v[100:101] op_sel_hi:[1,0]
	ds_write2_b32 v93, v4, v5 offset1:1
	ds_write2_b32 v95, v2, v3 offset1:1
	s_waitcnt vmcnt(0)
	v_pk_mul_f32 v[4:5], v[84:85], v[14:15] op_sel_hi:[1,0]
	v_pk_mul_f32 v[2:3], v[86:87], v[14:15] op_sel_hi:[1,0]
	ds_write2_b32 v97, v4, v5 offset1:1
	ds_write2_b32 v99, v2, v3 offset1:1
	s_waitcnt lgkmcnt(0)
	ds_read2_b32 v[2:3], v60 offset1:33
	s_waitcnt lgkmcnt(0)
	v_cvt_pk_bf16_f32 v2, v2, v3
	ds_read2_b32 v[4:5], v60 offset0:66 offset1:99
	s_waitcnt lgkmcnt(0)
	v_cvt_pk_bf16_f32 v3, v4, v5
	ds_read2_b32 v[4:5], v60 offset0:132 offset1:165
	v_lshlrev_b32_e32 v14, 11, v10
	s_waitcnt lgkmcnt(0)
	v_cvt_pk_bf16_f32 v4, v4, v5
	ds_read2_b32 v[6:7], v60 offset0:198 offset1:231
	s_waitcnt lgkmcnt(0)
	v_cvt_pk_bf16_f32 v5, v6, v7
	v_lshl_add_u64 v[10:11], v[8:9], 0, v[14:15]
	ds_read2_b32 v[6:7], v60 offset0:8 offset1:41
	global_store_dwordx4 v[10:11], v[2:5], off nt
	v_or_b32_e32 v10, s2, v1
	v_lshlrev_b32_e32 v14, 11, v10
	s_waitcnt lgkmcnt(0)
	v_cvt_pk_bf16_f32 v2, v6, v7
	ds_read2_b32 v[4:5], v60 offset0:74 offset1:107
	s_waitcnt lgkmcnt(0)
	v_cvt_pk_bf16_f32 v3, v4, v5
	ds_read2_b32 v[4:5], v60 offset0:140 offset1:173
	s_waitcnt lgkmcnt(0)
	v_cvt_pk_bf16_f32 v4, v4, v5
	ds_read2_b32 v[6:7], v60 offset0:206 offset1:239
	s_waitcnt lgkmcnt(0)
	v_cvt_pk_bf16_f32 v5, v6, v7
	v_lshl_add_u64 v[10:11], v[8:9], 0, v[14:15]
	ds_read2_b32 v[6:7], v60 offset0:16 offset1:49
	global_store_dwordx4 v[10:11], v[2:5], off nt
	v_or_b32_e32 v10, s2, v54
	v_lshlrev_b32_e32 v14, 11, v10
	s_waitcnt lgkmcnt(0)
	v_cvt_pk_bf16_f32 v2, v6, v7
	ds_read2_b32 v[4:5], v60 offset0:82 offset1:115
	s_waitcnt lgkmcnt(0)
	v_cvt_pk_bf16_f32 v3, v4, v5
	ds_read2_b32 v[4:5], v60 offset0:148 offset1:181
	s_waitcnt lgkmcnt(0)
	v_cvt_pk_bf16_f32 v4, v4, v5
	ds_read2_b32 v[6:7], v60 offset0:214 offset1:247
	s_waitcnt lgkmcnt(0)
	v_cvt_pk_bf16_f32 v5, v6, v7
	v_lshl_add_u64 v[10:11], v[8:9], 0, v[14:15]
	ds_read2_b32 v[6:7], v60 offset0:24 offset1:57
	global_store_dwordx4 v[10:11], v[2:5], off nt
	s_waitcnt lgkmcnt(0)
	s_nop 0
	v_cvt_pk_bf16_f32 v2, v6, v7
	ds_read2_b32 v[4:5], v60 offset0:90 offset1:123
	s_waitcnt lgkmcnt(0)
	v_cvt_pk_bf16_f32 v3, v4, v5
	ds_read2_b32 v[4:5], v60 offset0:156 offset1:189
	s_waitcnt lgkmcnt(0)
	v_cvt_pk_bf16_f32 v4, v4, v5
	v_or_b32_e32 v5, s2, v55
	ds_read2_b32 v[6:7], v60 offset0:222 offset1:255
	v_lshlrev_b32_e32 v14, 11, v5
	s_waitcnt lgkmcnt(0)
	v_cvt_pk_bf16_f32 v5, v6, v7
	v_lshl_add_u64 v[6:7], v[8:9], 0, v[14:15]
	global_store_dwordx4 v[6:7], v[2:5], off nt
	s_waitcnt lgkmcnt(0)

; #define LAS __attribute__((address_space(3)))
; DI unsigned pk2(float lo, float hi) { unsigned r; asm volatile("v_cvt_pk_bf16_f32 %0, %1, %2" : "=v"(r) : "v"(lo), "v"(hi)); return r; }
; #define LDS_WAIT() asm volatile("s_waitcnt lgkmcnt(0)" ::: "memory")
; DI void transpose_item(const float* W, int N, bf16_t* WT, size_t ldo, const float* sc, LAS float* scr, int item, int lane) {
;     const int nblk = N / 32, kb = item / nblk, nb = item % nblk, k0 = 64 * kb, n0 = 32 * nb;
; #pragma unroll
;     for (int i = 0; i < 8; ++i) { const int kk = 8 * i + (lane >> 3), n4 = (lane & 7) * 4;
;         f32x4 w = *(const f32x4*)(W + (size_t)(k0 + kk) * N + n0 + n4); if (sc) w = w * sc[k0 + kk];
;         LAS float* d = scr + kk * 33 + n4; d[0] = w.x; d[1] = w.y; d[2] = w.z; d[3] = w.w; }
;     LDS_WAIT();
;     const int c = lane & 7;
; #pragma unroll
;     for (int j = 0; j < 4; ++j) { const int n = (lane >> 3) + 8 * j; const LAS float* s = scr + (8 * c) * 33 + n;
;         u32x4v o; o.x = pk2(s[0 * 33], s[1 * 33]); o.y = pk2(s[2 * 33], s[3 * 33]); o.z = pk2(s[4 * 33], s[5 * 33]); o.w = pk2(s[6 * 33], s[7 * 33]);
;         *(u32x4v*)(WT + (size_t)(n0 + n) * ldo + k0 + 8 * c) = o; }
;     LDS_WAIT();
; DI void phase_prologue(const Prm& p, LAS unsigned char* lds, int tid, int lane, int wave) {
;     ...
;         if (r < I3) { transpose_item(p.w_out_odd, 1024, p.Wo1, 1024, nullptr, scr, r, lane); continue; } r -= I3;
.LBB0_22:
	s_andn2_b64 vcc, exec, s[2:3]
	s_cbranch_vccnz .LBB0_24
	s_add_i32 s2, s29, 0x1400
	s_and_b32 s3, s2, 0x1ffc0
	s_and_b32 s2, s31, 0x3e0
	s_lshl_b32 s26, s2, 2
	v_or_b32_e32 v2, s3, v158
	v_lshl_add_u64 v[52:53], v[20:21], 0, s[26:27]
	v_lshlrev_b32_e32 v14, 12, v2
	v_or_b32_e32 v4, s3, v1
	v_lshl_add_u64 v[2:3], v[52:53], 0, v[14:15]
	v_lshlrev_b32_e32 v14, 12, v4
	v_or_b32_e32 v10, s3, v54
	v_lshl_add_u64 v[6:7], v[52:53], 0, v[14:15]
	v_lshlrev_b32_e32 v14, 12, v10
	v_or_b32_e32 v12, s3, v55
	v_lshl_add_u64 v[10:11], v[52:53], 0, v[14:15]
	v_lshlrev_b32_e32 v14, 12, v12
	v_lshl_add_u64 v[68:69], v[52:53], 0, v[14:15]
	v_or_b32_e32 v14, s3, v56
	v_lshlrev_b32_e32 v14, 12, v14
	v_lshl_add_u64 v[72:73], v[52:53], 0, v[14:15]
	v_or_b32_e32 v14, s3, v57
	v_lshlrev_b32_e32 v14, 12, v14
	v_lshl_add_u64 v[76:77], v[52:53], 0, v[14:15]
	global_load_dwordx4 v[2:5], v[2:3], off
	s_nop 0
	global_load_dwordx4 v[6:9], v[6:7], off
	s_nop 0
	global_load_dwordx4 v[10:13], v[10:11], off
	s_nop 0
	global_load_dwordx4 v[68:71], v[68:69], off
	s_nop 0
	global_load_dwordx4 v[72:75], v[72:73], off
	s_nop 0
	global_load_dwordx4 v[76:79], v[76:77], off
	v_or_b32_e32 v14, s3, v58
	v_lshlrev_b32_e32 v14, 12, v14
	v_lshl_add_u64 v[80:81], v[52:53], 0, v[14:15]
	v_or_b32_e32 v14, s3, v59
	global_load_dwordx4 v[80:83], v[80:81], off
	v_lshlrev_b32_e32 v14, 12, v14
	v_lshl_add_u64 v[52:53], v[52:53], 0, v[14:15]
	global_load_dwordx4 v[84:87], v[52:53], off
	v_add_u32_e32 v14, 0x1080, v61
	v_add_u32_e32 v52, 0x1088, v61
	v_add_u32_e32 v53, 0x14a0, v61
	v_add_u32_e32 v88, 0x14a8, v61
	v_add_u32_e32 v89, 0x18c0, v61
	v_add_u32_e32 v90, 0x18c8, v61
	v_add_u32_e32 v91, 0x1ce0, v61
	v_add_u32_e32 v92, 0x1ce8, v61
	s_lshl_b32 s26, s3, 1
	s_waitcnt vmcnt(7)
	ds_write2_b32 v61, v2, v3 offset1:1
	ds_write2_b32 v61, v4, v5 offset0:2 offset1:3
	s_waitcnt vmcnt(6)
	ds_write2_b32 v62, v6, v7 offset1:1
	ds_write2_b32 v63, v8, v9 offset1:1
	s_waitcnt vmcnt(5)
	ds_write2_b32 v64, v10, v11 offset1:1
	ds_write2_b32 v65, v12, v13 offset1:1
	s_waitcnt vmcnt(4)
	ds_write2_b32 v66, v68, v69 offset1:1
	ds_write2_b32 v67, v70, v71 offset1:1
	s_waitcnt vmcnt(3)
	ds_write2_b32 v14, v72, v73 offset1:1
	ds_write2_b32 v52, v74, v75 offset1:1
	s_waitcnt vmcnt(2)
	ds_write2_b32 v53, v76, v77 offset1:1
	ds_write2_b32 v88, v78, v79 offset1:1
	s_waitcnt vmcnt(1)
	ds_write2_b32 v89, v80, v81 offset1:1
	ds_write2_b32 v90, v82, v83 offset1:1
	s_waitcnt vmcnt(0)
	ds_write2_b32 v91, v84, v85 offset1:1
	ds_write2_b32 v92, v86, v87 offset1:1
	s_waitcnt lgkmcnt(0)
	ds_read2_b32 v[2:3], v60 offset1:33
	s_waitcnt lgkmcnt(0)
	v_cvt_pk_bf16_f32 v2, v2, v3
	ds_read2_b32 v[4:5], v60 offset0:66 offset1:99
	v_or_b32_e32 v10, s2, v158
	s_waitcnt lgkmcnt(0)
	v_cvt_pk_bf16_f32 v3, v4, v5
	ds_read2_b32 v[4:5], v60 offset0:132 offset1:165
	v_lshl_add_u64 v[8:9], v[22:23], 0, s[26:27]
	v_lshlrev_b32_e32 v14, 11, v10
	s_waitcnt lgkmcnt(0)
	v_cvt_pk_bf16_f32 v4, v4, v5
	ds_read2_b32 v[6:7], v60 offset0:198 offset1:231
	s_waitcnt lgkmcnt(0)
	v_cvt_pk_bf16_f32 v5, v6, v7
	v_lshl_add_u64 v[10:11], v[8:9], 0, v[14:15]
	ds_read2_b32 v[6:7], v60 offset0:8 offset1:41
	global_store_dwordx4 v[10:11], v[2:5], off nt
	v_or_b32_e32 v10, s2, v1
	v_lshlrev_b32_e32 v14, 11, v10
	s_waitcnt lgkmcnt(0)
	v_cvt_pk_bf16_f32 v2, v6, v7
	ds_read2_b32 v[4:5], v60 offset0:74 offset1:107
	s_waitcnt lgkmcnt(0)
	v_cvt_pk_bf16_f32 v3, v4, v5
	ds_read2_b32 v[4:5], v60 offset0:140 offset1:173
	s_waitcnt lgkmcnt(0)
	v_cvt_pk_bf16_f32 v4, v4, v5
	ds_read2_b32 v[6:7], v60 offset0:206 offset1:239
	s_waitcnt lgkmcnt(0)
	v_cvt_pk_bf16_f32 v5, v6, v7
	v_lshl_add_u64 v[10:11], v[8:9], 0, v[14:15]
	ds_read2_b32 v[6:7], v60 offset0:16 offset1:49
	global_store_dwordx4 v[10:11], v[2:5], off nt
	v_or_b32_e32 v10, s2, v54
	v_lshlrev_b32_e32 v14, 11, v10
	s_waitcnt lgkmcnt(0)
	v_cvt_pk_bf16_f32 v2, v6, v7
	ds_read2_b32 v[4:5], v60 offset0:82 offset1:115
	s_waitcnt lgkmcnt(0)
	v_cvt_pk_bf16_f32 v3, v4, v5
	ds_read2_b32 v[4:5], v60 offset0:148 offset1:181
	s_waitcnt lgkmcnt(0)
	v_cvt_pk_bf16_f32 v4, v4, v5
	ds_read2_b32 v[6:7], v60 offset0:214 offset1:247
	s_waitcnt lgkmcnt(0)
	v_cvt_pk_bf16_f32 v5, v6, v7
	v_lshl_add_u64 v[10:11], v[8:9], 0, v[14:15]
	ds_read2_b32 v[6:7], v60 offset0:24 offset1:57
	global_store_dwordx4 v[10:11], v[2:5], off nt
	s_waitcnt lgkmcnt(0)
	s_nop 0
	v_cvt_pk_bf16_f32 v2, v6, v7
	ds_read2_b32 v[4:5], v60 offset0:90 offset1:123
	s_waitcnt lgkmcnt(0)
	v_cvt_pk_bf16_f32 v3, v4, v5
	ds_read2_b32 v[4:5], v60 offset0:156 offset1:189
	s_waitcnt lgkmcnt(0)
	v_cvt_pk_bf16_f32 v4, v4, v5
	v_or_b32_e32 v5, s2, v55
	ds_read2_b32 v[6:7], v60 offset0:222 offset1:255
	v_lshlrev_b32_e32 v14, 11, v5
	s_waitcnt lgkmcnt(0)
	v_cvt_pk_bf16_f32 v5, v6, v7
	v_lshl_add_u64 v[6:7], v[8:9], 0, v[14:15]
	global_store_dwordx4 v[6:7], v[2:5], off nt
	s_waitcnt lgkmcnt(0)

; #define LAS __attribute__((address_space(3)))
; DI unsigned pk2(float lo, float hi) { unsigned r; asm volatile("v_cvt_pk_bf16_f32 %0, %1, %2" : "=v"(r) : "v"(lo), "v"(hi)); return r; }
; #define LDS_WAIT() asm volatile("s_waitcnt lgkmcnt(0)" ::: "memory")
; DI void transpose_item(const float* W, int N, bf16_t* WT, size_t ldo, const float* sc, LAS float* scr, int item, int lane) {
;     const int nblk = N / 32, kb = item / nblk, nb = item % nblk, k0 = 64 * kb, n0 = 32 * nb;
; #pragma unroll
;     for (int i = 0; i < 8; ++i) { const int kk = 8 * i + (lane >> 3), n4 = (lane & 7) * 4;
;         f32x4 w = *(const f32x4*)(W + (size_t)(k0 + kk) * N + n0 + n4); if (sc) w = w * sc[k0 + kk];
;         LAS float* d = scr + kk * 33 + n4; d[0] = w.x; d[1] = w.y; d[2] = w.z; d[3] = w.w; }
;     LDS_WAIT();
;     const int c = lane & 7;
; #pragma unroll
;     for (int j = 0; j < 4; ++j) { const int n = (lane >> 3) + 8 * j; const LAS float* s = scr + (8 * c) * 33 + n;
;         u32x4v o; o.x = pk2(s[0 * 33], s[1 * 33]); o.y = pk2(s[2 * 33], s[3 * 33]); o.z = pk2(s[4 * 33], s[5 * 33]); o.w = pk2(s[6 * 33], s[7 * 33]);
;         *(u32x4v*)(WT + (size_t)(n0 + n) * ldo + k0 + 8 * c) = o; }
;     LDS_WAIT();
; DI void phase_prologue(const Prm& p, LAS unsigned char* lds, int tid, int lane, int wave) {
;     ...
;         if (r < I6) { transpose_item(p.w_in_odd, 3072, p.Wqkv, 1024, p.ln_mix + 1024, scr, r, lane); continue; } r -= I6;
.LBB0_25:
	s_andn2_b64 vcc, exec, s[2:3]
	s_cbranch_vccnz .LBB0_27
	s_add_i32 s2, s43, 0xe880
	s_and_b32 s3, s2, 0xffff
	s_mul_i32 s3, s3, 0xaaab
	s_lshr_b32 s26, s3, 16
	s_lshr_b32 s3, s3, 22
	s_mulk_i32 s3, 0x60
	s_sub_i32 s2, s2, s3
	s_lshl_b32 s2, s2, 5
	s_and_b32 s2, s2, 0xffe0
	s_and_b32 s3, s26, 0xffc0
	s_lshl_b32 s26, s2, 2
	v_lshl_add_u64 v[52:53], v[24:25], 0, s[26:27]
	v_or_b32_e32 v6, s3, v158
	v_mad_u64_u32 v[2:3], s[36:37], v6, s41, v[52:53]
	v_lshlrev_b32_e32 v6, 2, v6
	v_or_b32_e32 v10, s3, v1
	global_load_dword v14, v6, s[6:7]
	v_mad_u64_u32 v[6:7], s[36:37], v10, s41, v[52:53]
	v_lshlrev_b32_e32 v10, 2, v10
	v_or_b32_e32 v68, s3, v54
	global_load_dword v88, v10, s[6:7]
	v_mad_u64_u32 v[10:11], s[36:37], v68, s41, v[52:53]
	v_lshlrev_b32_e32 v68, 2, v68
	v_or_b32_e32 v72, s3, v55
	global_load_dword v90, v68, s[6:7]
	v_mad_u64_u32 v[68:69], s[36:37], v72, s41, v[52:53]
	v_lshlrev_b32_e32 v72, 2, v72
	v_or_b32_e32 v76, s3, v56
	global_load_dword v92, v72, s[6:7]
	v_mad_u64_u32 v[72:73], s[36:37], v76, s41, v[52:53]
	v_lshlrev_b32_e32 v76, 2, v76
	v_or_b32_e32 v80, s3, v57
	global_load_dword v94, v76, s[6:7]
	v_mad_u64_u32 v[76:77], s[36:37], v80, s41, v[52:53]
	v_lshlrev_b32_e32 v80, 2, v80
	v_or_b32_e32 v84, s3, v58
	global_load_dword v96, v80, s[6:7]
	v_mad_u64_u32 v[80:81], s[36:37], v84, s41, v[52:53]
	v_lshlrev_b32_e32 v84, 2, v84
	global_load_dword v98, v84, s[6:7]
	v_or_b32_e32 v84, s3, v59
	global_load_dwordx4 v[2:5], v[2:3], off
	v_mad_u64_u32 v[52:53], s[36:37], v84, s41, v[52:53]
	global_load_dwordx4 v[6:9], v[6:7], off
	v_lshlrev_b32_e32 v84, 2, v84
	global_load_dwordx4 v[10:13], v[10:11], off
	v_add_u32_e32 v89, 0x1080, v61
	global_load_dwordx4 v[68:71], v[68:69], off
	v_add_u32_e32 v91, 0x1088, v61
	global_load_dwordx4 v[72:75], v[72:73], off
	v_add_u32_e32 v93, 0x14a0, v61
	global_load_dwordx4 v[76:79], v[76:77], off
	v_add_u32_e32 v95, 0x14a8, v61
	global_load_dwordx4 v[80:83], v[80:81], off
	s_nop 0
	global_load_dword v100, v84, s[6:7]
	s_nop 0
	global_load_dwordx4 v[84:87], v[52:53], off
	v_add_u32_e32 v97, 0x18c0, v61
	v_add_u32_e32 v99, 0x18c8, v61
	s_lshl_b32 s26, s3, 1
	v_readlane_b32 s36, v254, 50
	s_mov_b32 s28, s36
	v_readlane_b32 s37, v254, 51
	s_waitcnt vmcnt(8)
	v_pk_mul_f32 v[4:5], v[4:5], v[14:15] op_sel_hi:[1,0]
	v_pk_mul_f32 v[2:3], v[2:3], v[14:15] op_sel_hi:[1,0]
	s_waitcnt vmcnt(7)
	v_pk_mul_f32 v[6:7], v[6:7], v[88:89] op_sel_hi:[1,0]
	v_pk_mul_f32 v[8:9], v[8:9], v[88:89] op_sel_hi:[1,0]
	s_waitcnt vmcnt(6)
	v_pk_mul_f32 v[12:13], v[12:13], v[90:91] op_sel_hi:[1,0]
	v_pk_mul_f32 v[10:11], v[10:11], v[90:91] op_sel_hi:[1,0]
	s_waitcnt vmcnt(5)
	v_pk_mul_f32 v[52:53], v[70:71], v[92:93] op_sel_hi:[1,0]
	v_pk_mul_f32 v[68:69], v[68:69], v[92:93] op_sel_hi:[1,0]
	s_waitcnt vmcnt(4)
	v_pk_mul_f32 v[70:71], v[74:75], v[94:95] op_sel_hi:[1,0]
	v_pk_mul_f32 v[72:73], v[72:73], v[94:95] op_sel_hi:[1,0]
	s_waitcnt vmcnt(3)
	v_pk_mul_f32 v[74:75], v[78:79], v[96:97] op_sel_hi:[1,0]
	v_pk_mul_f32 v[76:77], v[76:77], v[96:97] op_sel_hi:[1,0]
	s_waitcnt vmcnt(2)
	v_pk_mul_f32 v[78:79], v[82:83], v[98:99] op_sel_hi:[1,0]
	v_pk_mul_f32 v[80:81], v[80:81], v[98:99] op_sel_hi:[1,0]
	ds_write2_b32 v61, v2, v3 offset1:1
	ds_write2_b32 v61, v4, v5 offset0:2 offset1:3
	ds_write2_b32 v62, v6, v7 offset1:1
	ds_write2_b32 v63, v8, v9 offset1:1
	ds_write2_b32 v64, v10, v11 offset1:1
	ds_write2_b32 v65, v12, v13 offset1:1
	ds_write2_b32 v66, v68, v69 offset1:1
	ds_write2_b32 v67, v52, v53 offset1:1
	ds_write2_b32 v89, v72, v73 offset1:1
	ds_write2_b32 v91, v70, v71 offset1:1
	ds_write2_b32 v93, v76, v77 offset1:1
	ds_write2_b32 v95, v74, v75 offset1:1
	ds_write2_b32 v97, v80, v81 offset1:1
	ds_write2_b32 v99, v78, v79 offset1:1
	s_waitcnt vmcnt(0)
	v_pk_mul_f32 v[4:5], v[84:85], v[100:101] op_sel_hi:[1,0]
	v_add_u32_e32 v6, 0x1ce0, v61
	v_pk_mul_f32 v[2:3], v[86:87], v[100:101] op_sel_hi:[1,0]
	ds_write2_b32 v6, v4, v5 offset1:1
	v_add_u32_e32 v4, 0x1ce8, v61
	ds_write2_b32 v4, v2, v3 offset1:1
	s_waitcnt lgkmcnt(0)
	ds_read2_b32 v[2:3], v60 offset1:33
	s_waitcnt lgkmcnt(0)
	v_cvt_pk_bf16_f32 v2, v2, v3
	ds_read2_b32 v[4:5], v60 offset0:66 offset1:99
	v_or_b32_e32 v8, s2, v158
	s_waitcnt lgkmcnt(0)
	v_cvt_pk_bf16_f32 v3, v4, v5
	ds_read2_b32 v[4:5], v60 offset0:132 offset1:165
	v_lshlrev_b32_e32 v14, 11, v8
	v_lshl_add_u64 v[8:9], v[26:27], 0, s[26:27]
	s_waitcnt lgkmcnt(0)
	v_cvt_pk_bf16_f32 v4, v4, v5
	ds_read2_b32 v[6:7], v60 offset0:198 offset1:231
	s_waitcnt lgkmcnt(0)
	v_cvt_pk_bf16_f32 v5, v6, v7
	v_lshl_add_u64 v[10:11], v[8:9], 0, v[14:15]
	ds_read2_b32 v[6:7], v60 offset0:8 offset1:41
	global_store_dwordx4 v[10:11], v[2:5], off nt
	v_or_b32_e32 v10, s2, v1
	v_lshlrev_b32_e32 v14, 11, v10
	s_waitcnt lgkmcnt(0)
	v_cvt_pk_bf16_f32 v2, v6, v7
	ds_read2_b32 v[4:5], v60 offset0:74 offset1:107
	s_waitcnt lgkmcnt(0)
	v_cvt_pk_bf16_f32 v3, v4, v5
	ds_read2_b32 v[4:5], v60 offset0:140 offset1:173
	s_waitcnt lgkmcnt(0)
	v_cvt_pk_bf16_f32 v4, v4, v5
	ds_read2_b32 v[6:7], v60 offset0:206 offset1:239
	s_waitcnt lgkmcnt(0)
	v_cvt_pk_bf16_f32 v5, v6, v7
	v_lshl_add_u64 v[10:11], v[8:9], 0, v[14:15]
	ds_read2_b32 v[6:7], v60 offset0:16 offset1:49
	global_store_dwordx4 v[10:11], v[2:5], off nt
	v_or_b32_e32 v10, s2, v54
	v_lshlrev_b32_e32 v14, 11, v10
	s_waitcnt lgkmcnt(0)
	v_cvt_pk_bf16_f32 v2, v6, v7
	ds_read2_b32 v[4:5], v60 offset0:82 offset1:115
	s_waitcnt lgkmcnt(0)
	v_cvt_pk_bf16_f32 v3, v4, v5
	ds_read2_b32 v[4:5], v60 offset0:148 offset1:181
	s_waitcnt lgkmcnt(0)
	v_cvt_pk_bf16_f32 v4, v4, v5
	ds_read2_b32 v[6:7], v60 offset0:214 offset1:247
	s_waitcnt lgkmcnt(0)
	v_cvt_pk_bf16_f32 v5, v6, v7
	v_lshl_add_u64 v[10:11], v[8:9], 0, v[14:15]
	ds_read2_b32 v[6:7], v60 offset0:24 offset1:57
	global_store_dwordx4 v[10:11], v[2:5], off nt
	s_waitcnt lgkmcnt(0)
	s_nop 0
	v_cvt_pk_bf16_f32 v2, v6, v7
	ds_read2_b32 v[4:5], v60 offset0:90 offset1:123
	s_waitcnt lgkmcnt(0)
	v_cvt_pk_bf16_f32 v3, v4, v5
	ds_read2_b32 v[4:5], v60 offset0:156 offset1:189
	s_waitcnt lgkmcnt(0)
	v_cvt_pk_bf16_f32 v4, v4, v5
	v_or_b32_e32 v5, s2, v55
	ds_read2_b32 v[6:7], v60 offset0:222 offset1:255
	v_lshlrev_b32_e32 v14, 11, v5
	s_waitcnt lgkmcnt(0)
	v_cvt_pk_bf16_f32 v5, v6, v7
	v_lshl_add_u64 v[6:7], v[8:9], 0, v[14:15]
	global_store_dwordx4 v[6:7], v[2:5], off nt
	s_waitcnt lgkmcnt(0)

; #define LAS __attribute__((address_space(3)))
; DI unsigned pk2(float lo, float hi) { unsigned r; asm volatile("v_cvt_pk_bf16_f32 %0, %1, %2" : "=v"(r) : "v"(lo), "v"(hi)); return r; }
; #define LDS_WAIT() asm volatile("s_waitcnt lgkmcnt(0)" ::: "memory")
; DI void transpose_item(const float* W, int N, bf16_t* WT, size_t ldo, const float* sc, LAS float* scr, int item, int lane) {
;     const int nblk = N / 32, kb = item / nblk, nb = item % nblk, k0 = 64 * kb, n0 = 32 * nb;
; #pragma unroll
;     for (int i = 0; i < 8; ++i) { const int kk = 8 * i + (lane >> 3), n4 = (lane & 7) * 4;
;         f32x4 w = *(const f32x4*)(W + (size_t)(k0 + kk) * N + n0 + n4); if (sc) w = w * sc[k0 + kk];
;         LAS float* d = scr + kk * 33 + n4; d[0] = w.x; d[1] = w.y; d[2] = w.z; d[3] = w.w; }
;     LDS_WAIT();
;     const int c = lane & 7;
; #pragma unroll
;     for (int j = 0; j < 4; ++j) { const int n = (lane >> 3) + 8 * j; const LAS float* s = scr + (8 * c) * 33 + n;
;         u32x4v o; o.x = pk2(s[0 * 33], s[1 * 33]); o.y = pk2(s[2 * 33], s[3 * 33]); o.z = pk2(s[4 * 33], s[5 * 33]); o.w = pk2(s[6 * 33], s[7 * 33]);
;         *(u32x4v*)(WT + (size_t)(n0 + n) * ldo + k0 + 8 * c) = o; }
;     LDS_WAIT();
; DI void phase_prologue(const Prm& p, LAS unsigned char* lds, int tid, int lane, int wave) {
;     ...
;         if (r < I5) { transpose_item(p.w_down, 1024, p.Wdn0, 4096, nullptr, scr, r, lane); continue; } r -= I5;
.LBB0_28:
	s_andn2_b64 vcc, exec, s[2:3]
	s_cbranch_vccnz .LBB0_30
	s_add_i32 s2, s29, 0x3000
	s_and_b32 s3, s2, 0x1ffc0
	s_and_b32 s2, s31, 0x3e0
	s_lshl_b32 s26, s2, 2
	v_or_b32_e32 v2, s3, v158
	v_lshl_add_u64 v[52:53], v[28:29], 0, s[26:27]
	v_lshlrev_b32_e32 v14, 12, v2
	v_or_b32_e32 v4, s3, v1
	v_lshl_add_u64 v[2:3], v[52:53], 0, v[14:15]
	v_lshlrev_b32_e32 v14, 12, v4
	v_or_b32_e32 v10, s3, v54
	v_lshl_add_u64 v[6:7], v[52:53], 0, v[14:15]
	v_lshlrev_b32_e32 v14, 12, v10
	v_or_b32_e32 v12, s3, v55
	v_lshl_add_u64 v[10:11], v[52:53], 0, v[14:15]
	v_lshlrev_b32_e32 v14, 12, v12
	v_lshl_add_u64 v[68:69], v[52:53], 0, v[14:15]
	v_or_b32_e32 v14, s3, v56
	v_lshlrev_b32_e32 v14, 12, v14
	v_lshl_add_u64 v[72:73], v[52:53], 0, v[14:15]
	v_or_b32_e32 v14, s3, v57
	v_lshlrev_b32_e32 v14, 12, v14
	v_lshl_add_u64 v[76:77], v[52:53], 0, v[14:15]
	global_load_dwordx4 v[2:5], v[2:3], off
	s_nop 0
	global_load_dwordx4 v[6:9], v[6:7], off
	s_nop 0
	global_load_dwordx4 v[10:13], v[10:11], off
	s_nop 0
	global_load_dwordx4 v[68:71], v[68:69], off
	s_nop 0
	global_load_dwordx4 v[72:75], v[72:73], off
	s_nop 0
	global_load_dwordx4 v[76:79], v[76:77], off
	v_or_b32_e32 v14, s3, v58
	v_lshlrev_b32_e32 v14, 12, v14
	v_lshl_add_u64 v[80:81], v[52:53], 0, v[14:15]
	v_or_b32_e32 v14, s3, v59
	global_load_dwordx4 v[80:83], v[80:81], off
	v_lshlrev_b32_e32 v14, 12, v14
	v_lshl_add_u64 v[52:53], v[52:53], 0, v[14:15]
	global_load_dwordx4 v[84:87], v[52:53], off
	v_add_u32_e32 v14, 0x1080, v61
	v_add_u32_e32 v52, 0x1088, v61
	v_add_u32_e32 v53, 0x14a0, v61
	v_add_u32_e32 v88, 0x14a8, v61
	v_add_u32_e32 v89, 0x18c0, v61
	v_add_u32_e32 v90, 0x18c8, v61
	v_add_u32_e32 v91, 0x1ce0, v61
	v_add_u32_e32 v92, 0x1ce8, v61
	s_lshl_b32 s26, s3, 1
	s_waitcnt vmcnt(7)
	ds_write2_b32 v61, v2, v3 offset1:1
	ds_write2_b32 v61, v4, v5 offset0:2 offset1:3
	s_waitcnt vmcnt(6)
	ds_write2_b32 v62, v6, v7 offset1:1
	ds_write2_b32 v63, v8, v9 offset1:1
	s_waitcnt vmcnt(5)
	ds_write2_b32 v64, v10, v11 offset1:1
	ds_write2_b32 v65, v12, v13 offset1:1
	s_waitcnt vmcnt(4)
	ds_write2_b32 v66, v68, v69 offset1:1
	ds_write2_b32 v67, v70, v71 offset1:1
	s_waitcnt vmcnt(3)
	ds_write2_b32 v14, v72, v73 offset1:1
	ds_write2_b32 v52, v74, v75 offset1:1
	s_waitcnt vmcnt(2)
	ds_write2_b32 v53, v76, v77 offset1:1
	ds_write2_b32 v88, v78, v79 offset1:1
	s_waitcnt vmcnt(1)
	ds_write2_b32 v89, v80, v81 offset1:1
	ds_write2_b32 v90, v82, v83 offset1:1
	s_waitcnt vmcnt(0)
	ds_write2_b32 v91, v84, v85 offset1:1
	ds_write2_b32 v92, v86, v87 offset1:1
	s_waitcnt lgkmcnt(0)
	ds_read2_b32 v[2:3], v60 offset1:33
	s_waitcnt lgkmcnt(0)
	v_cvt_pk_bf16_f32 v2, v2, v3
	ds_read2_b32 v[4:5], v60 offset0:66 offset1:99
	v_or_b32_e32 v10, s2, v158
	s_waitcnt lgkmcnt(0)
	v_cvt_pk_bf16_f32 v3, v4, v5
	ds_read2_b32 v[4:5], v60 offset0:132 offset1:165
	v_lshl_add_u64 v[8:9], v[30:31], 0, s[26:27]
	v_lshlrev_b32_e32 v14, 13, v10
	s_waitcnt lgkmcnt(0)
	v_cvt_pk_bf16_f32 v4, v4, v5
	ds_read2_b32 v[6:7], v60 offset0:198 offset1:231
	s_waitcnt lgkmcnt(0)
	v_cvt_pk_bf16_f32 v5, v6, v7
	v_lshl_add_u64 v[10:11], v[8:9], 0, v[14:15]
	ds_read2_b32 v[6:7], v60 offset0:8 offset1:41
	global_store_dwordx4 v[10:11], v[2:5], off nt
	v_or_b32_e32 v10, s2, v1
	v_lshlrev_b32_e32 v14, 13, v10
	s_waitcnt lgkmcnt(0)
	v_cvt_pk_bf16_f32 v2, v6, v7
	ds_read2_b32 v[4:5], v60 offset0:74 offset1:107
	s_waitcnt lgkmcnt(0)
	v_cvt_pk_bf16_f32 v3, v4, v5
	ds_read2_b32 v[4:5], v60 offset0:140 offset1:173
	s_waitcnt lgkmcnt(0)
	v_cvt_pk_bf16_f32 v4, v4, v5
	ds_read2_b32 v[6:7], v60 offset0:206 offset1:239
	s_waitcnt lgkmcnt(0)
	v_cvt_pk_bf16_f32 v5, v6, v7
	v_lshl_add_u64 v[10:11], v[8:9], 0, v[14:15]
	ds_read2_b32 v[6:7], v60 offset0:16 offset1:49
	global_store_dwordx4 v[10:11], v[2:5], off nt
	v_or_b32_e32 v10, s2, v54
	v_lshlrev_b32_e32 v14, 13, v10
	s_waitcnt lgkmcnt(0)
	v_cvt_pk_bf16_f32 v2, v6, v7
	ds_read2_b32 v[4:5], v60 offset0:82 offset1:115
	s_waitcnt lgkmcnt(0)
	v_cvt_pk_bf16_f32 v3, v4, v5
	ds_read2_b32 v[4:5], v60 offset0:148 offset1:181
	s_waitcnt lgkmcnt(0)
	v_cvt_pk_bf16_f32 v4, v4, v5
	ds_read2_b32 v[6:7], v60 offset0:214 offset1:247
	s_waitcnt lgkmcnt(0)
	v_cvt_pk_bf16_f32 v5, v6, v7
	v_lshl_add_u64 v[10:11], v[8:9], 0, v[14:15]
	ds_read2_b32 v[6:7], v60 offset0:24 offset1:57
	global_store_dwordx4 v[10:11], v[2:5], off nt
	s_waitcnt lgkmcnt(0)
	s_nop 0
	v_cvt_pk_bf16_f32 v2, v6, v7
	ds_read2_b32 v[4:5], v60 offset0:90 offset1:123
	s_waitcnt lgkmcnt(0)
	v_cvt_pk_bf16_f32 v3, v4, v5
	ds_read2_b32 v[4:5], v60 offset0:156 offset1:189
	s_waitcnt lgkmcnt(0)
	v_cvt_pk_bf16_f32 v4, v4, v5
	v_or_b32_e32 v5, s2, v55
	ds_read2_b32 v[6:7], v60 offset0:222 offset1:255
	v_lshlrev_b32_e32 v14, 13, v5
	s_waitcnt lgkmcnt(0)
	v_cvt_pk_bf16_f32 v5, v6, v7
	v_lshl_add_u64 v[6:7], v[8:9], 0, v[14:15]
	global_store_dwordx4 v[6:7], v[2:5], off nt
	s_waitcnt lgkmcnt(0)

; #define LAS __attribute__((address_space(3)))
; DI unsigned pk2(float lo, float hi) { unsigned r; asm volatile("v_cvt_pk_bf16_f32 %0, %1, %2" : "=v"(r) : "v"(lo), "v"(hi)); return r; }
; #define LDS_WAIT() asm volatile("s_waitcnt lgkmcnt(0)" ::: "memory")
; DI void transpose_item(const float* W, int N, bf16_t* WT, size_t ldo, const float* sc, LAS float* scr, int item, int lane) {
;     ...
;     LDS_WAIT();
;     const int c = lane & 7;
; #pragma unroll
;     for (int j = 0; j < 4; ++j) { const int n = (lane >> 3) + 8 * j; const LAS float* s = scr + (8 * c) * 33 + n;
;         u32x4v o; o.x = pk2(s[0 * 33], s[1 * 33]); o.y = pk2(s[2 * 33], s[3 * 33]); o.z = pk2(s[4 * 33], s[5 * 33]); o.w = pk2(s[6 * 33], s[7 * 33]);
;         *(u32x4v*)(WT + (size_t)(n0 + n) * ldo + k0 + 8 * c) = o; }
;     LDS_WAIT();
.LBB0_49:
	s_waitcnt vmcnt(0)
	v_add_u32_e32 v2, 0x1ce0, v61
	ds_write2_b32 v2, v6, v7 offset1:1
	v_add_u32_e32 v2, 0x1ce8, v61
	ds_write2_b32 v2, v8, v9 offset1:1
	s_waitcnt lgkmcnt(0)
	ds_read2_b32 v[2:3], v60 offset1:33
	s_waitcnt lgkmcnt(0)
	v_cvt_pk_bf16_f32 v2, v2, v3
	ds_read2_b32 v[4:5], v60 offset0:66 offset1:99
	s_lshl_b32 s26, s37, 1
	v_or_b32_e32 v10, s36, v158
	s_waitcnt lgkmcnt(0)
	v_cvt_pk_bf16_f32 v3, v4, v5
	ds_read2_b32 v[4:5], v60 offset0:132 offset1:165
	v_lshl_add_u64 v[8:9], v[34:35], 0, s[26:27]
	v_lshlrev_b32_e32 v14, 11, v10
	s_waitcnt lgkmcnt(0)
	v_cvt_pk_bf16_f32 v4, v4, v5
	ds_read2_b32 v[6:7], v60 offset0:198 offset1:231
	s_waitcnt lgkmcnt(0)
	v_cvt_pk_bf16_f32 v5, v6, v7
	v_lshl_add_u64 v[10:11], v[8:9], 0, v[14:15]
	ds_read2_b32 v[6:7], v60 offset0:8 offset1:41
	global_store_dwordx4 v[10:11], v[2:5], off nt
	v_or_b32_e32 v10, s36, v1
	v_lshlrev_b32_e32 v14, 11, v10
	s_waitcnt lgkmcnt(0)
	v_cvt_pk_bf16_f32 v2, v6, v7
	ds_read2_b32 v[4:5], v60 offset0:74 offset1:107
	s_waitcnt lgkmcnt(0)
	v_cvt_pk_bf16_f32 v3, v4, v5
	ds_read2_b32 v[4:5], v60 offset0:140 offset1:173
	s_waitcnt lgkmcnt(0)
	v_cvt_pk_bf16_f32 v4, v4, v5
	ds_read2_b32 v[6:7], v60 offset0:206 offset1:239
	s_waitcnt lgkmcnt(0)
	v_cvt_pk_bf16_f32 v5, v6, v7
	v_lshl_add_u64 v[10:11], v[8:9], 0, v[14:15]
	ds_read2_b32 v[6:7], v60 offset0:16 offset1:49
	global_store_dwordx4 v[10:11], v[2:5], off nt
	v_or_b32_e32 v10, s36, v54
	v_lshlrev_b32_e32 v14, 11, v10
	s_waitcnt lgkmcnt(0)
	v_cvt_pk_bf16_f32 v2, v6, v7
	ds_read2_b32 v[4:5], v60 offset0:82 offset1:115
	s_waitcnt lgkmcnt(0)
	v_cvt_pk_bf16_f32 v3, v4, v5
	ds_read2_b32 v[4:5], v60 offset0:148 offset1:181
	s_waitcnt lgkmcnt(0)
	v_cvt_pk_bf16_f32 v4, v4, v5
	ds_read2_b32 v[6:7], v60 offset0:214 offset1:247
	s_waitcnt lgkmcnt(0)
	v_cvt_pk_bf16_f32 v5, v6, v7
	v_lshl_add_u64 v[10:11], v[8:9], 0, v[14:15]
	ds_read2_b32 v[6:7], v60 offset0:24 offset1:57
	global_store_dwordx4 v[10:11], v[2:5], off nt
	v_readlane_b32 s2, v254, 50
	s_mov_b32 s28, s2
	s_waitcnt lgkmcnt(0)
	v_cvt_pk_bf16_f32 v2, v6, v7
	ds_read2_b32 v[4:5], v60 offset0:90 offset1:123
	s_waitcnt lgkmcnt(0)
	v_cvt_pk_bf16_f32 v3, v4, v5
	ds_read2_b32 v[4:5], v60 offset0:156 offset1:189
	s_waitcnt lgkmcnt(0)
	v_cvt_pk_bf16_f32 v4, v4, v5
	v_or_b32_e32 v5, s36, v55
	ds_read2_b32 v[6:7], v60 offset0:222 offset1:255
	v_lshlrev_b32_e32 v14, 11, v5
	s_waitcnt lgkmcnt(0)
	v_cvt_pk_bf16_f32 v5, v6, v7
	v_lshl_add_u64 v[6:7], v[8:9], 0, v[14:15]
	global_store_dwordx4 v[6:7], v[2:5], off nt
	s_waitcnt lgkmcnt(0)
	v_readlane_b32 s3, v254, 51

; #define LAS __attribute__((address_space(3)))
; DI unsigned pk2(float lo, float hi) { unsigned r; asm volatile("v_cvt_pk_bf16_f32 %0, %1, %2" : "=v"(r) : "v"(lo), "v"(hi)); return r; }
; #define LDS_WAIT() asm volatile("s_waitcnt lgkmcnt(0)" ::: "memory")
; DI void transpose_item(const float* W, int N, bf16_t* WT, size_t ldo, const float* sc, LAS float* scr, int item, int lane) {
;     const int nblk = N / 32, kb = item / nblk, nb = item % nblk, k0 = 64 * kb, n0 = 32 * nb;
; #pragma unroll
;     for (int i = 0; i < 8; ++i) { const int kk = 8 * i + (lane >> 3), n4 = (lane & 7) * 4;
;         f32x4 w = *(const f32x4*)(W + (size_t)(k0 + kk) * N + n0 + n4); if (sc) w = w * sc[k0 + kk];
;         LAS float* d = scr + kk * 33 + n4; d[0] = w.x; d[1] = w.y; d[2] = w.z; d[3] = w.w; }
;     LDS_WAIT();
;     const int c = lane & 7;
; #pragma unroll
;     for (int j = 0; j < 4; ++j) { const int n = (lane >> 3) + 8 * j; const LAS float* s = scr + (8 * c) * 33 + n;
;         u32x4v o; o.x = pk2(s[0 * 33], s[1 * 33]); o.y = pk2(s[2 * 33], s[3 * 33]); o.z = pk2(s[4 * 33], s[5 * 33]); o.w = pk2(s[6 * 33], s[7 * 33]);
;         *(u32x4v*)(WT + (size_t)(n0 + n) * ldo + k0 + 8 * c) = o; }
;     LDS_WAIT();
; DI void phase_prologue(const Prm& p, LAS unsigned char* lds, int tid, int lane, int wave) {
;     ...
;         if (r < I3) { transpose_item(p.w_out_even, 1024, p.Wo0, 1024, nullptr, scr, r, lane); continue; } r -= I3;
.LBB0_51:
	s_andn2_b64 vcc, exec, s[2:3]
	s_cbranch_vccnz .LBB0_53
	s_add_i32 s2, s29, 0x4400
	s_and_b32 s3, s2, 0x1ffc0
	s_and_b32 s2, s31, 0x3e0
	s_lshl_b32 s26, s2, 2
	v_or_b32_e32 v2, s3, v158
	v_lshl_add_u64 v[52:53], v[36:37], 0, s[26:27]
	v_lshlrev_b32_e32 v14, 12, v2
	v_or_b32_e32 v4, s3, v1
	v_lshl_add_u64 v[2:3], v[52:53], 0, v[14:15]
	v_lshlrev_b32_e32 v14, 12, v4
	v_or_b32_e32 v10, s3, v54
	v_lshl_add_u64 v[6:7], v[52:53], 0, v[14:15]
	v_lshlrev_b32_e32 v14, 12, v10
	v_or_b32_e32 v12, s3, v55
	v_lshl_add_u64 v[10:11], v[52:53], 0, v[14:15]
	v_lshlrev_b32_e32 v14, 12, v12
	v_lshl_add_u64 v[68:69], v[52:53], 0, v[14:15]
	v_or_b32_e32 v14, s3, v56
	v_lshlrev_b32_e32 v14, 12, v14
	v_lshl_add_u64 v[72:73], v[52:53], 0, v[14:15]
	v_or_b32_e32 v14, s3, v57
	v_lshlrev_b32_e32 v14, 12, v14
	v_lshl_add_u64 v[76:77], v[52:53], 0, v[14:15]
	global_load_dwordx4 v[2:5], v[2:3], off
	s_nop 0
	global_load_dwordx4 v[6:9], v[6:7], off
	s_nop 0
	global_load_dwordx4 v[10:13], v[10:11], off
	s_nop 0
	global_load_dwordx4 v[68:71], v[68:69], off
	s_nop 0
	global_load_dwordx4 v[72:75], v[72:73], off
	s_nop 0
	global_load_dwordx4 v[76:79], v[76:77], off
	v_or_b32_e32 v14, s3, v58
	v_lshlrev_b32_e32 v14, 12, v14
	v_lshl_add_u64 v[80:81], v[52:53], 0, v[14:15]
	v_or_b32_e32 v14, s3, v59
	global_load_dwordx4 v[80:83], v[80:81], off
	v_lshlrev_b32_e32 v14, 12, v14
	v_lshl_add_u64 v[52:53], v[52:53], 0, v[14:15]
	global_load_dwordx4 v[84:87], v[52:53], off
	v_add_u32_e32 v14, 0x1080, v61
	v_add_u32_e32 v52, 0x1088, v61
	v_add_u32_e32 v53, 0x14a0, v61
	v_add_u32_e32 v88, 0x14a8, v61
	v_add_u32_e32 v89, 0x18c0, v61
	v_add_u32_e32 v90, 0x18c8, v61
	v_add_u32_e32 v91, 0x1ce0, v61
	v_add_u32_e32 v92, 0x1ce8, v61
	s_lshl_b32 s26, s3, 1
	s_waitcnt vmcnt(7)
	ds_write2_b32 v61, v2, v3 offset1:1
	ds_write2_b32 v61, v4, v5 offset0:2 offset1:3
	s_waitcnt vmcnt(6)
	ds_write2_b32 v62, v6, v7 offset1:1
	ds_write2_b32 v63, v8, v9 offset1:1
	s_waitcnt vmcnt(5)
	ds_write2_b32 v64, v10, v11 offset1:1
	ds_write2_b32 v65, v12, v13 offset1:1
	s_waitcnt vmcnt(4)
	ds_write2_b32 v66, v68, v69 offset1:1
	ds_write2_b32 v67, v70, v71 offset1:1
	s_waitcnt vmcnt(3)
	ds_write2_b32 v14, v72, v73 offset1:1
	ds_write2_b32 v52, v74, v75 offset1:1
	s_waitcnt vmcnt(2)
	ds_write2_b32 v53, v76, v77 offset1:1
	ds_write2_b32 v88, v78, v79 offset1:1
	s_waitcnt vmcnt(1)
	ds_write2_b32 v89, v80, v81 offset1:1
	ds_write2_b32 v90, v82, v83 offset1:1
	s_waitcnt vmcnt(0)
	ds_write2_b32 v91, v84, v85 offset1:1
	ds_write2_b32 v92, v86, v87 offset1:1
	s_waitcnt lgkmcnt(0)
	ds_read2_b32 v[2:3], v60 offset1:33
	s_waitcnt lgkmcnt(0)
	v_cvt_pk_bf16_f32 v2, v2, v3
	ds_read2_b32 v[4:5], v60 offset0:66 offset1:99
	v_or_b32_e32 v10, s2, v158
	s_waitcnt lgkmcnt(0)
	v_cvt_pk_bf16_f32 v3, v4, v5
	ds_read2_b32 v[4:5], v60 offset0:132 offset1:165
	v_lshl_add_u64 v[8:9], v[38:39], 0, s[26:27]
	v_lshlrev_b32_e32 v14, 11, v10
	s_waitcnt lgkmcnt(0)
	v_cvt_pk_bf16_f32 v4, v4, v5
	ds_read2_b32 v[6:7], v60 offset0:198 offset1:231
	s_waitcnt lgkmcnt(0)
	v_cvt_pk_bf16_f32 v5, v6, v7
	v_lshl_add_u64 v[10:11], v[8:9], 0, v[14:15]
	ds_read2_b32 v[6:7], v60 offset0:8 offset1:41
	global_store_dwordx4 v[10:11], v[2:5], off nt
	v_or_b32_e32 v10, s2, v1
	v_lshlrev_b32_e32 v14, 11, v10
	s_waitcnt lgkmcnt(0)
	v_cvt_pk_bf16_f32 v2, v6, v7
	ds_read2_b32 v[4:5], v60 offset0:74 offset1:107
	s_waitcnt lgkmcnt(0)
	v_cvt_pk_bf16_f32 v3, v4, v5
	ds_read2_b32 v[4:5], v60 offset0:140 offset1:173
	s_waitcnt lgkmcnt(0)
	v_cvt_pk_bf16_f32 v4, v4, v5
	ds_read2_b32 v[6:7], v60 offset0:206 offset1:239
	s_waitcnt lgkmcnt(0)
	v_cvt_pk_bf16_f32 v5, v6, v7
	v_lshl_add_u64 v[10:11], v[8:9], 0, v[14:15]
	ds_read2_b32 v[6:7], v60 offset0:16 offset1:49
	global_store_dwordx4 v[10:11], v[2:5], off nt
	v_or_b32_e32 v10, s2, v54
	v_lshlrev_b32_e32 v14, 11, v10
	s_waitcnt lgkmcnt(0)
	v_cvt_pk_bf16_f32 v2, v6, v7
	ds_read2_b32 v[4:5], v60 offset0:82 offset1:115
	s_waitcnt lgkmcnt(0)
	v_cvt_pk_bf16_f32 v3, v4, v5
	ds_read2_b32 v[4:5], v60 offset0:148 offset1:181
	s_waitcnt lgkmcnt(0)
	v_cvt_pk_bf16_f32 v4, v4, v5
	ds_read2_b32 v[6:7], v60 offset0:214 offset1:247
	s_waitcnt lgkmcnt(0)
	v_cvt_pk_bf16_f32 v5, v6, v7
	v_lshl_add_u64 v[10:11], v[8:9], 0, v[14:15]
	ds_read2_b32 v[6:7], v60 offset0:24 offset1:57
	global_store_dwordx4 v[10:11], v[2:5], off nt
	s_waitcnt lgkmcnt(0)
	s_nop 0
	v_cvt_pk_bf16_f32 v2, v6, v7
	ds_read2_b32 v[4:5], v60 offset0:90 offset1:123
	s_waitcnt lgkmcnt(0)
	v_cvt_pk_bf16_f32 v3, v4, v5
	ds_read2_b32 v[4:5], v60 offset0:156 offset1:189
	s_waitcnt lgkmcnt(0)
	v_cvt_pk_bf16_f32 v4, v4, v5
	v_or_b32_e32 v5, s2, v55
	ds_read2_b32 v[6:7], v60 offset0:222 offset1:255
	v_lshlrev_b32_e32 v14, 11, v5
	s_waitcnt lgkmcnt(0)
	v_cvt_pk_bf16_f32 v5, v6, v7
	v_lshl_add_u64 v[6:7], v[8:9], 0, v[14:15]
	global_store_dwordx4 v[6:7], v[2:5], off nt
	s_waitcnt lgkmcnt(0)

; #define LAS __attribute__((address_space(3)))
; DI unsigned pk2(float lo, float hi) { unsigned r; asm volatile("v_cvt_pk_bf16_f32 %0, %1, %2" : "=v"(r) : "v"(lo), "v"(hi)); return r; }
; #define LDS_WAIT() asm volatile("s_waitcnt lgkmcnt(0)" ::: "memory")
; DI void transpose_item(const float* W, int N, bf16_t* WT, size_t ldo, const float* sc, LAS float* scr, int item, int lane) {
;     const int nblk = N / 32, kb = item / nblk, nb = item % nblk, k0 = 64 * kb, n0 = 32 * nb;
; #pragma unroll
;     for (int i = 0; i < 8; ++i) { const int kk = 8 * i + (lane >> 3), n4 = (lane & 7) * 4;
;         f32x4 w = *(const f32x4*)(W + (size_t)(k0 + kk) * N + n0 + n4); if (sc) w = w * sc[k0 + kk];
;         LAS float* d = scr + kk * 33 + n4; d[0] = w.x; d[1] = w.y; d[2] = w.z; d[3] = w.w; }
;     LDS_WAIT();
;     const int c = lane & 7;
; #pragma unroll
;     for (int j = 0; j < 4; ++j) { const int n = (lane >> 3) + 8 * j; const LAS float* s = scr + (8 * c) * 33 + n;
;         u32x4v o; o.x = pk2(s[0 * 33], s[1 * 33]); o.y = pk2(s[2 * 33], s[3 * 33]); o.z = pk2(s[4 * 33], s[5 * 33]); o.w = pk2(s[6 * 33], s[7 * 33]);
;         *(u32x4v*)(WT + (size_t)(n0 + n) * ldo + k0 + 8 * c) = o; }
;     LDS_WAIT();
; DI void phase_prologue(const Prm& p, LAS unsigned char* lds, int tid, int lane, int wave) {
;     ...
;         if (r < I2) { transpose_item(p.w_glu, 512, p.Wglu, 512, nullptr, scr, r, lane); continue; } r -= I2;
.LBB0_54:
	s_andn2_b64 vcc, exec, s[2:3]
	s_cbranch_vccnz .LBB0_56
	s_and_b32 s3, s35, 0x3c0
	s_and_b32 s2, s31, 0x1e0
	s_lshl_b32 s26, s2, 2
	v_or_b32_e32 v2, s3, v158
	v_lshl_add_u64 v[52:53], v[40:41], 0, s[26:27]
	v_lshlrev_b32_e32 v14, 11, v2
	v_or_b32_e32 v4, s3, v1
	v_lshl_add_u64 v[2:3], v[52:53], 0, v[14:15]
	v_lshlrev_b32_e32 v14, 11, v4
	v_or_b32_e32 v10, s3, v54
	v_lshl_add_u64 v[6:7], v[52:53], 0, v[14:15]
	v_lshlrev_b32_e32 v14, 11, v10
	v_or_b32_e32 v12, s3, v55
	v_lshl_add_u64 v[10:11], v[52:53], 0, v[14:15]
	v_lshlrev_b32_e32 v14, 11, v12
	v_lshl_add_u64 v[68:69], v[52:53], 0, v[14:15]
	v_or_b32_e32 v14, s3, v56
	v_lshlrev_b32_e32 v14, 11, v14
	v_lshl_add_u64 v[72:73], v[52:53], 0, v[14:15]
	v_or_b32_e32 v14, s3, v57
	v_lshlrev_b32_e32 v14, 11, v14
	v_lshl_add_u64 v[76:77], v[52:53], 0, v[14:15]
	global_load_dwordx4 v[2:5], v[2:3], off
	s_nop 0
	global_load_dwordx4 v[6:9], v[6:7], off
	s_nop 0
	global_load_dwordx4 v[10:13], v[10:11], off
	s_nop 0
	global_load_dwordx4 v[68:71], v[68:69], off
	s_nop 0
	global_load_dwordx4 v[72:75], v[72:73], off
	s_nop 0
	global_load_dwordx4 v[76:79], v[76:77], off
	v_or_b32_e32 v14, s3, v58
	v_lshlrev_b32_e32 v14, 11, v14
	v_lshl_add_u64 v[80:81], v[52:53], 0, v[14:15]
	v_or_b32_e32 v14, s3, v59
	global_load_dwordx4 v[80:83], v[80:81], off
	v_lshlrev_b32_e32 v14, 11, v14
	v_lshl_add_u64 v[52:53], v[52:53], 0, v[14:15]
	global_load_dwordx4 v[84:87], v[52:53], off
	v_add_u32_e32 v14, 0x1080, v61
	v_add_u32_e32 v52, 0x1088, v61
	v_add_u32_e32 v53, 0x14a0, v61
	v_add_u32_e32 v88, 0x14a8, v61
	v_add_u32_e32 v89, 0x18c0, v61
	v_add_u32_e32 v90, 0x18c8, v61
	v_add_u32_e32 v91, 0x1ce0, v61
	v_add_u32_e32 v92, 0x1ce8, v61
	s_lshl_b32 s26, s3, 1
	s_waitcnt vmcnt(7)
	ds_write2_b32 v61, v2, v3 offset1:1
	ds_write2_b32 v61, v4, v5 offset0:2 offset1:3
	s_waitcnt vmcnt(6)
	ds_write2_b32 v62, v6, v7 offset1:1
	ds_write2_b32 v63, v8, v9 offset1:1
	s_waitcnt vmcnt(5)
	ds_write2_b32 v64, v10, v11 offset1:1
	ds_write2_b32 v65, v12, v13 offset1:1
	s_waitcnt vmcnt(4)
	ds_write2_b32 v66, v68, v69 offset1:1
	ds_write2_b32 v67, v70, v71 offset1:1
	s_waitcnt vmcnt(3)
	ds_write2_b32 v14, v72, v73 offset1:1
	ds_write2_b32 v52, v74, v75 offset1:1
	s_waitcnt vmcnt(2)
	ds_write2_b32 v53, v76, v77 offset1:1
	ds_write2_b32 v88, v78, v79 offset1:1
	s_waitcnt vmcnt(1)
	ds_write2_b32 v89, v80, v81 offset1:1
	ds_write2_b32 v90, v82, v83 offset1:1
	s_waitcnt vmcnt(0)
	ds_write2_b32 v91, v84, v85 offset1:1
	ds_write2_b32 v92, v86, v87 offset1:1
	s_waitcnt lgkmcnt(0)
	ds_read2_b32 v[2:3], v60 offset1:33
	s_waitcnt lgkmcnt(0)
	v_cvt_pk_bf16_f32 v2, v2, v3
	ds_read2_b32 v[4:5], v60 offset0:66 offset1:99
	v_or_b32_e32 v10, s2, v158
	s_waitcnt lgkmcnt(0)
	v_cvt_pk_bf16_f32 v3, v4, v5
	ds_read2_b32 v[4:5], v60 offset0:132 offset1:165
	v_lshl_add_u64 v[8:9], v[42:43], 0, s[26:27]
	v_lshlrev_b32_e32 v14, 10, v10
	s_waitcnt lgkmcnt(0)
	v_cvt_pk_bf16_f32 v4, v4, v5
	ds_read2_b32 v[6:7], v60 offset0:198 offset1:231
	s_waitcnt lgkmcnt(0)
	v_cvt_pk_bf16_f32 v5, v6, v7
	v_lshl_add_u64 v[10:11], v[8:9], 0, v[14:15]
	ds_read2_b32 v[6:7], v60 offset0:8 offset1:41
	global_store_dwordx4 v[10:11], v[2:5], off nt
	v_or_b32_e32 v10, s2, v1
	v_lshlrev_b32_e32 v14, 10, v10
	s_waitcnt lgkmcnt(0)
	v_cvt_pk_bf16_f32 v2, v6, v7
	ds_read2_b32 v[4:5], v60 offset0:74 offset1:107
	s_waitcnt lgkmcnt(0)
	v_cvt_pk_bf16_f32 v3, v4, v5
	ds_read2_b32 v[4:5], v60 offset0:140 offset1:173
	s_waitcnt lgkmcnt(0)
	v_cvt_pk_bf16_f32 v4, v4, v5
	ds_read2_b32 v[6:7], v60 offset0:206 offset1:239
	s_waitcnt lgkmcnt(0)
	v_cvt_pk_bf16_f32 v5, v6, v7
	v_lshl_add_u64 v[10:11], v[8:9], 0, v[14:15]
	ds_read2_b32 v[6:7], v60 offset0:16 offset1:49
	global_store_dwordx4 v[10:11], v[2:5], off nt
	v_or_b32_e32 v10, s2, v54
	v_lshlrev_b32_e32 v14, 10, v10
	s_waitcnt lgkmcnt(0)
	v_cvt_pk_bf16_f32 v2, v6, v7
	ds_read2_b32 v[4:5], v60 offset0:82 offset1:115
	s_waitcnt lgkmcnt(0)
	v_cvt_pk_bf16_f32 v3, v4, v5
	ds_read2_b32 v[4:5], v60 offset0:148 offset1:181
	s_waitcnt lgkmcnt(0)
	v_cvt_pk_bf16_f32 v4, v4, v5
	ds_read2_b32 v[6:7], v60 offset0:214 offset1:247
	s_waitcnt lgkmcnt(0)
	v_cvt_pk_bf16_f32 v5, v6, v7
	v_lshl_add_u64 v[10:11], v[8:9], 0, v[14:15]
	ds_read2_b32 v[6:7], v60 offset0:24 offset1:57
	global_store_dwordx4 v[10:11], v[2:5], off nt
	s_waitcnt lgkmcnt(0)
	s_nop 0
	v_cvt_pk_bf16_f32 v2, v6, v7
	ds_read2_b32 v[4:5], v60 offset0:90 offset1:123
	s_waitcnt lgkmcnt(0)
	v_cvt_pk_bf16_f32 v3, v4, v5
	ds_read2_b32 v[4:5], v60 offset0:156 offset1:189
	s_waitcnt lgkmcnt(0)
	v_cvt_pk_bf16_f32 v4, v4, v5
	v_or_b32_e32 v5, s2, v55
	ds_read2_b32 v[6:7], v60 offset0:222 offset1:255
	v_lshlrev_b32_e32 v14, 10, v5
	s_waitcnt lgkmcnt(0)
	v_cvt_pk_bf16_f32 v5, v6, v7
	v_lshl_add_u64 v[6:7], v[8:9], 0, v[14:15]
	global_store_dwordx4 v[6:7], v[2:5], off nt
	s_waitcnt lgkmcnt(0)

; DI unsigned pk2(float lo, float hi) { unsigned r; asm volatile("v_cvt_pk_bf16_f32 %0, %1, %2" : "=v"(r) : "v"(lo), "v"(hi)); return r; }
; DI float sigm(float x) { return __builtin_amdgcn_rcpf(1.f + __expf(-x)); }
; template <class Epi, class Sched>
; __device__ __forceinline__ void gemm_phase(PG8_LAS unsigned char* lds, const Gemm g, const Sched& S, const Epi& E) {
;     ...
;         if (!has_next) break;
;     DI void operator()(const f32x4 (&acc)[2][2][4][2], const Unit& u, int wr, int wc, int fr, int fq, const Pre& pre) const {
;     ...
;                     for (int n = 0; n < 2; ++n) { f32x4 v = acc[ai][bj][m][n] * r;
;                         if (seg == 1) { const f32x4 lb = lbv[bj][n]; f32x4 f;
; #pragma unroll
;                             for (int e = 0; e < 4; ++e) f[e] = __logf(lb[e] + (1.f - lb[e]) * sigm(v[e]));
;                             w[2 * n] = pkh2(f[0], f[1]); w[2 * n + 1] = pkh2(f[2], f[3]); }
;                         else { if (seg == 3) {
; #pragma unroll
;                                 for (int e = 0; e < 4; ++e) v[e] = v[e] * sigm(v[e]); }
;                             w[2 * n] = pk2(v[0], v[1]); w[2 * n + 1] = pk2(v[2], v[3]); } }
;                     o.x = w[0]; o.y = w[1]; o.z = w[2]; o.w = w[3];
;                     *(u32x4v*)(dst + (size_t)row * 512 + cb + bj * 128) = o; } }
.LBB0_186:
	s_andn2_b64 vcc, exec, s[90:91]
	s_mov_b32 s10, s12
	s_mov_b32 s0, s14
	s_mov_b64 s[20:21], s[18:19]
	s_mov_b64 s[22:23], s[16:17]
	global_store_dwordx4 v[20:21], v[4:7], off offset:256 nt
	s_cbranch_vccz .LBB0_529

; DI unsigned pk2(float lo, float hi) { unsigned r; asm volatile("v_cvt_pk_bf16_f32 %0, %1, %2" : "=v"(r) : "v"(lo), "v"(hi)); return r; }
; DI float sigm(float x) { return __builtin_amdgcn_rcpf(1.f + __expf(-x)); }
;     DI void operator()(const f32x4 (&acc)[2][2][4][2], const Unit& u, int wr, int wc, int fr, int fq, const Pre& pre) const {
;     ...
;             for (int m = 0; m < 4; ++m) { const int row = row0 + ai * 128 + m * 16; const float r = rs[ai][m];
; #pragma unroll
;                 for (int bj = 0; bj < 2; ++bj) { u32x4v o; unsigned w[4];
; #pragma unroll
;                     for (int n = 0; n < 2; ++n) { f32x4 v = acc[ai][bj][m][n] * r;
;                         if (seg == 1) { const f32x4 lb = lbv[bj][n]; f32x4 f;
; #pragma unroll
;                             for (int e = 0; e < 4; ++e) f[e] = __logf(lb[e] + (1.f - lb[e]) * sigm(v[e]));
;                             w[2 * n] = pkh2(f[0], f[1]); w[2 * n + 1] = pkh2(f[2], f[3]); }
;                         else { if (seg == 3) {
; #pragma unroll
;                                 for (int e = 0; e < 4; ++e) v[e] = v[e] * sigm(v[e]); }
;                             w[2 * n] = pk2(v[0], v[1]); w[2 * n + 1] = pk2(v[2], v[3]); } }
;                     o.x = w[0]; o.y = w[1]; o.z = w[2]; o.w = w[3];
;                     *(u32x4v*)(dst + (size_t)row * 512 + cb + bj * 128) = o; } }
.LBB0_225:
	v_lshlrev_b32_e32 v172, 1, v172
	v_lshl_add_u64 v[146:147], s[20:21], 0, v[172:173]
	v_lshlrev_b64 v[136:137], 10, v[206:207]
	v_lshl_add_u64 v[144:145], v[146:147], 0, v[136:137]
	v_mov_b32_e32 v136, v197
	v_mov_b32_e32 v137, v197
	v_pk_mul_f32 v[138:139], v[134:135], v[136:137]
	v_pk_mul_f32 v[136:137], v[132:133], v[148:149]
	s_mov_b64 s[20:21], -1
	s_mov_b64 s[0:1], 0
	s_cmp_lt_i32 s13, 3
	s_mov_b64 s[10:11], 0
	global_store_dwordx4 v[144:145], v[140:143], off nt
	s_cbranch_scc1 .LBB0_251
	s_nop 0
	v_mov_b64_e32 v[142:143], v[138:139]
	s_cmp_eq_u32 s13, 3
	v_mov_b64_e32 v[140:141], v[136:137]
	s_cbranch_scc0 .LBB0_228
	v_mul_f32_e32 v132, 0xbfb8aa3b, v136
	v_mul_f32_e32 v133, 0xbfb8aa3b, v137
	v_mul_f32_e32 v134, 0xbfb8aa3b, v138
	v_mul_f32_e32 v135, 0xbfb8aa3b, v139
	v_exp_f32_e32 v132, v132
	v_exp_f32_e32 v133, v133
	v_exp_f32_e32 v134, v134
	v_exp_f32_e32 v135, v135
	v_add_f32_e32 v132, 1.0, v132
	v_add_f32_e32 v133, 1.0, v133
	v_add_f32_e32 v134, 1.0, v134
	v_add_f32_e32 v135, 1.0, v135
	v_rcp_f32_e32 v132, v132
	v_rcp_f32_e32 v134, v134
	v_rcp_f32_e32 v135, v135
	v_rcp_f32_e32 v133, v133
	v_pk_mul_f32 v[142:143], v[138:139], v[134:135]
	v_pk_mul_f32 v[140:141], v[136:137], v[132:133]

; DI unsigned pk2(float lo, float hi) { unsigned r; asm volatile("v_cvt_pk_bf16_f32 %0, %1, %2" : "=v"(r) : "v"(lo), "v"(hi)); return r; }
; DI float sigm(float x) { return __builtin_amdgcn_rcpf(1.f + __expf(-x)); }
;     DI void operator()(const f32x4 (&acc)[2][2][4][2], const Unit& u, int wr, int wc, int fr, int fq, const Pre& pre) const {
;     ...
;             for (int m = 0; m < 4; ++m) { const int row = row0 + ai * 128 + m * 16; const float r = rs[ai][m];
; #pragma unroll
;                 for (int bj = 0; bj < 2; ++bj) { u32x4v o; unsigned w[4];
; #pragma unroll
;                     for (int n = 0; n < 2; ++n) { f32x4 v = acc[ai][bj][m][n] * r;
;                         if (seg == 1) { const f32x4 lb = lbv[bj][n]; f32x4 f;
; #pragma unroll
;                             for (int e = 0; e < 4; ++e) f[e] = __logf(lb[e] + (1.f - lb[e]) * sigm(v[e]));
;                             w[2 * n] = pkh2(f[0], f[1]); w[2 * n + 1] = pkh2(f[2], f[3]); }
;                         else { if (seg == 3) {
; #pragma unroll
;                                 for (int e = 0; e < 4; ++e) v[e] = v[e] * sigm(v[e]); }
;                             w[2 * n] = pk2(v[0], v[1]); w[2 * n + 1] = pk2(v[2], v[3]); } }
;                     o.x = w[0]; o.y = w[1]; o.z = w[2]; o.w = w[3];
;                     *(u32x4v*)(dst + (size_t)row * 512 + cb + bj * 128) = o; } }
.LBB0_241:
	v_pk_mul_f32 v[128:129], v[124:125], v[200:201] op_sel_hi:[1,0]
	v_pk_mul_f32 v[130:131], v[126:127], v[200:201] op_sel_hi:[1,0]
	s_mov_b64 s[20:21], -1
	s_mov_b64 s[0:1], 0
	s_cmp_lt_i32 s13, 3
	s_mov_b64 s[10:11], 0
	global_store_dwordx4 v[144:145], v[132:135], off offset:256 nt
	s_cbranch_scc1 .LBB0_255
	s_nop 0
	v_mov_b64_e32 v[134:135], v[130:131]
	s_cmp_eq_u32 s13, 3
	v_mov_b64_e32 v[132:133], v[128:129]
	s_cbranch_scc0 .LBB0_244
	v_mul_f32_e32 v124, 0xbfb8aa3b, v128
	v_mul_f32_e32 v125, 0xbfb8aa3b, v129
	v_mul_f32_e32 v126, 0xbfb8aa3b, v130
	v_mul_f32_e32 v127, 0xbfb8aa3b, v131
	v_exp_f32_e32 v124, v124
	v_exp_f32_e32 v125, v125
	v_exp_f32_e32 v126, v126
	v_exp_f32_e32 v127, v127
	v_add_f32_e32 v124, 1.0, v124
	v_add_f32_e32 v125, 1.0, v125
	v_add_f32_e32 v126, 1.0, v126
	v_add_f32_e32 v127, 1.0, v127
	v_rcp_f32_e32 v124, v124
	v_rcp_f32_e32 v126, v126
	v_rcp_f32_e32 v127, v127
	v_rcp_f32_e32 v125, v125
	v_pk_mul_f32 v[134:135], v[130:131], v[126:127]
	v_pk_mul_f32 v[132:133], v[128:129], v[124:125]

; DI unsigned pk2(float lo, float hi) { unsigned r; asm volatile("v_cvt_pk_bf16_f32 %0, %1, %2" : "=v"(r) : "v"(lo), "v"(hi)); return r; }
; DI float sigm(float x) { return __builtin_amdgcn_rcpf(1.f + __expf(-x)); }
;     DI void operator()(const f32x4 (&acc)[2][2][4][2], const Unit& u, int wr, int wc, int fr, int fq, const Pre& pre) const {
;     ...
;             for (int m = 0; m < 4; ++m) { const int row = row0 + ai * 128 + m * 16; const float r = rs[ai][m];
; #pragma unroll
;                 for (int bj = 0; bj < 2; ++bj) { u32x4v o; unsigned w[4];
; #pragma unroll
;                     for (int n = 0; n < 2; ++n) { f32x4 v = acc[ai][bj][m][n] * r;
;                         if (seg == 1) { const f32x4 lb = lbv[bj][n]; f32x4 f;
; #pragma unroll
;                             for (int e = 0; e < 4; ++e) f[e] = __logf(lb[e] + (1.f - lb[e]) * sigm(v[e]));
;                             w[2 * n] = pkh2(f[0], f[1]); w[2 * n + 1] = pkh2(f[2], f[3]); }
;                         else { if (seg == 3) {
; #pragma unroll
;                                 for (int e = 0; e < 4; ++e) v[e] = v[e] * sigm(v[e]); }
;                             w[2 * n] = pk2(v[0], v[1]); w[2 * n + 1] = pk2(v[2], v[3]); } }
;                     o.x = w[0]; o.y = w[1]; o.z = w[2]; o.w = w[3];
;                     *(u32x4v*)(dst + (size_t)row * 512 + cb + bj * 128) = o; } }
.LBB0_269:
	v_ashrrev_i32_e32 v205, 31, v204
	v_lshlrev_b64 v[120:121], 10, v[204:205]
	v_lshl_add_u64 v[128:129], v[146:147], 0, v[120:121]
	v_mov_b32_e32 v120, v200
	v_mov_b32_e32 v121, v200
	v_pk_mul_f32 v[122:123], v[118:119], v[120:121]
	v_pk_mul_f32 v[120:121], v[116:117], v[130:131]
	s_mov_b64 s[20:21], -1
	s_mov_b64 s[0:1], 0
	s_cmp_lt_i32 s13, 3
	s_mov_b64 s[10:11], 0
	global_store_dwordx4 v[128:129], v[124:127], off nt
	s_cbranch_scc1 .LBB0_275
	s_nop 0
	v_mov_b64_e32 v[126:127], v[122:123]
	s_cmp_eq_u32 s13, 3
	v_mov_b64_e32 v[124:125], v[120:121]
	s_cbranch_scc0 .LBB0_272
	v_mul_f32_e32 v116, 0xbfb8aa3b, v120
	v_mul_f32_e32 v117, 0xbfb8aa3b, v121
	v_mul_f32_e32 v118, 0xbfb8aa3b, v122
	v_mul_f32_e32 v119, 0xbfb8aa3b, v123
	v_exp_f32_e32 v116, v116
	v_exp_f32_e32 v117, v117
	v_exp_f32_e32 v118, v118
	v_exp_f32_e32 v119, v119
	v_add_f32_e32 v116, 1.0, v116
	v_add_f32_e32 v117, 1.0, v117
	v_add_f32_e32 v118, 1.0, v118
	v_add_f32_e32 v119, 1.0, v119
	v_rcp_f32_e32 v116, v116
	v_rcp_f32_e32 v118, v118
	v_rcp_f32_e32 v119, v119
	v_rcp_f32_e32 v117, v117
	v_pk_mul_f32 v[126:127], v[122:123], v[118:119]
	v_pk_mul_f32 v[124:125], v[120:121], v[116:117]

; DI unsigned pk2(float lo, float hi) { unsigned r; asm volatile("v_cvt_pk_bf16_f32 %0, %1, %2" : "=v"(r) : "v"(lo), "v"(hi)); return r; }
; DI float sigm(float x) { return __builtin_amdgcn_rcpf(1.f + __expf(-x)); }
;     DI void operator()(const f32x4 (&acc)[2][2][4][2], const Unit& u, int wr, int wc, int fr, int fq, const Pre& pre) const {
;     ...
;             for (int m = 0; m < 4; ++m) { const int row = row0 + ai * 128 + m * 16; const float r = rs[ai][m];
; #pragma unroll
;                 for (int bj = 0; bj < 2; ++bj) { u32x4v o; unsigned w[4];
; #pragma unroll
;                     for (int n = 0; n < 2; ++n) { f32x4 v = acc[ai][bj][m][n] * r;
;                         if (seg == 1) { const f32x4 lb = lbv[bj][n]; f32x4 f;
; #pragma unroll
;                             for (int e = 0; e < 4; ++e) f[e] = __logf(lb[e] + (1.f - lb[e]) * sigm(v[e]));
;                             w[2 * n] = pkh2(f[0], f[1]); w[2 * n + 1] = pkh2(f[2], f[3]); }
;                         else { if (seg == 3) {
; #pragma unroll
;                                 for (int e = 0; e < 4; ++e) v[e] = v[e] * sigm(v[e]); }
;                             w[2 * n] = pk2(v[0], v[1]); w[2 * n + 1] = pk2(v[2], v[3]); } }
;                     o.x = w[0]; o.y = w[1]; o.z = w[2]; o.w = w[3];
;                     *(u32x4v*)(dst + (size_t)row * 512 + cb + bj * 128) = o; } }
.LBB0_289:
	v_pk_mul_f32 v[112:113], v[108:109], v[200:201] op_sel:[0,1]
	v_pk_mul_f32 v[114:115], v[110:111], v[200:201] op_sel:[0,1]
	s_mov_b64 s[20:21], -1
	s_mov_b64 s[0:1], 0
	s_cmp_lt_i32 s13, 3
	s_mov_b64 s[10:11], 0
	global_store_dwordx4 v[128:129], v[116:119], off offset:256 nt
	s_cbranch_scc1 .LBB0_295
	s_nop 0
	v_mov_b64_e32 v[118:119], v[114:115]
	s_cmp_eq_u32 s13, 3
	v_mov_b64_e32 v[116:117], v[112:113]
	s_cbranch_scc0 .LBB0_292
	v_mul_f32_e32 v108, 0xbfb8aa3b, v112
	v_mul_f32_e32 v109, 0xbfb8aa3b, v113
	v_mul_f32_e32 v110, 0xbfb8aa3b, v114
	v_mul_f32_e32 v111, 0xbfb8aa3b, v115
	v_exp_f32_e32 v108, v108
	v_exp_f32_e32 v109, v109
	v_exp_f32_e32 v110, v110
	v_exp_f32_e32 v111, v111
	v_add_f32_e32 v108, 1.0, v108
	v_add_f32_e32 v109, 1.0, v109
	v_add_f32_e32 v110, 1.0, v110
	v_add_f32_e32 v111, 1.0, v111
	v_rcp_f32_e32 v108, v108
	v_rcp_f32_e32 v110, v110
	v_rcp_f32_e32 v111, v111
	v_rcp_f32_e32 v109, v109
	v_pk_mul_f32 v[118:119], v[114:115], v[110:111]
	v_pk_mul_f32 v[116:117], v[112:113], v[108:109]

; DI unsigned pk2(float lo, float hi) { unsigned r; asm volatile("v_cvt_pk_bf16_f32 %0, %1, %2" : "=v"(r) : "v"(lo), "v"(hi)); return r; }
; DI float sigm(float x) { return __builtin_amdgcn_rcpf(1.f + __expf(-x)); }
;     DI void operator()(const f32x4 (&acc)[2][2][4][2], const Unit& u, int wr, int wc, int fr, int fq, const Pre& pre) const {
;     ...
;             for (int m = 0; m < 4; ++m) { const int row = row0 + ai * 128 + m * 16; const float r = rs[ai][m];
; #pragma unroll
;                 for (int bj = 0; bj < 2; ++bj) { u32x4v o; unsigned w[4];
; #pragma unroll
;                     for (int n = 0; n < 2; ++n) { f32x4 v = acc[ai][bj][m][n] * r;
;                         if (seg == 1) { const f32x4 lb = lbv[bj][n]; f32x4 f;
; #pragma unroll
;                             for (int e = 0; e < 4; ++e) f[e] = __logf(lb[e] + (1.f - lb[e]) * sigm(v[e]));
;                             w[2 * n] = pkh2(f[0], f[1]); w[2 * n + 1] = pkh2(f[2], f[3]); }
;                         else { if (seg == 3) {
; #pragma unroll
;                                 for (int e = 0; e < 4; ++e) v[e] = v[e] * sigm(v[e]); }
;                             w[2 * n] = pk2(v[0], v[1]); w[2 * n + 1] = pk2(v[2], v[3]); } }
;                     o.x = w[0]; o.y = w[1]; o.z = w[2]; o.w = w[3];
;                     *(u32x4v*)(dst + (size_t)row * 512 + cb + bj * 128) = o; } }
.LBB0_309:
	v_ashrrev_i32_e32 v203, 31, v202
	v_lshlrev_b64 v[104:105], 10, v[202:203]
	v_lshl_add_u64 v[112:113], v[146:147], 0, v[104:105]
	v_mov_b32_e32 v104, v201
	v_mov_b32_e32 v105, v201
	v_pk_mul_f32 v[106:107], v[102:103], v[104:105]
	v_pk_mul_f32 v[104:105], v[100:101], v[200:201]
	s_mov_b64 s[20:21], -1
	s_mov_b64 s[0:1], 0
	s_cmp_lt_i32 s13, 3
	s_mov_b64 s[10:11], 0
	global_store_dwordx4 v[112:113], v[108:111], off nt
	s_cbranch_scc1 .LBB0_315
	s_nop 0
	v_mov_b64_e32 v[110:111], v[106:107]
	s_cmp_eq_u32 s13, 3
	v_mov_b64_e32 v[108:109], v[104:105]
	s_cbranch_scc0 .LBB0_312
	v_mul_f32_e32 v100, 0xbfb8aa3b, v104
	v_mul_f32_e32 v101, 0xbfb8aa3b, v105
	v_mul_f32_e32 v102, 0xbfb8aa3b, v106
	v_mul_f32_e32 v103, 0xbfb8aa3b, v107
	v_exp_f32_e32 v100, v100
	v_exp_f32_e32 v101, v101
	v_exp_f32_e32 v102, v102
	v_exp_f32_e32 v103, v103
	v_add_f32_e32 v100, 1.0, v100
	v_add_f32_e32 v101, 1.0, v101
	v_add_f32_e32 v102, 1.0, v102
	v_add_f32_e32 v103, 1.0, v103
	v_rcp_f32_e32 v100, v100
	v_rcp_f32_e32 v102, v102
	v_rcp_f32_e32 v103, v103
	v_rcp_f32_e32 v101, v101
	v_pk_mul_f32 v[110:111], v[106:107], v[102:103]
	v_pk_mul_f32 v[108:109], v[104:105], v[100:101]

; DI unsigned pk2(float lo, float hi) { unsigned r; asm volatile("v_cvt_pk_bf16_f32 %0, %1, %2" : "=v"(r) : "v"(lo), "v"(hi)); return r; }
; DI float sigm(float x) { return __builtin_amdgcn_rcpf(1.f + __expf(-x)); }
;     DI void operator()(const f32x4 (&acc)[2][2][4][2], const Unit& u, int wr, int wc, int fr, int fq, const Pre& pre) const {
;     ...
;             for (int m = 0; m < 4; ++m) { const int row = row0 + ai * 128 + m * 16; const float r = rs[ai][m];
; #pragma unroll
;                 for (int bj = 0; bj < 2; ++bj) { u32x4v o; unsigned w[4];
; #pragma unroll
;                     for (int n = 0; n < 2; ++n) { f32x4 v = acc[ai][bj][m][n] * r;
;                         if (seg == 1) { const f32x4 lb = lbv[bj][n]; f32x4 f;
; #pragma unroll
;                             for (int e = 0; e < 4; ++e) f[e] = __logf(lb[e] + (1.f - lb[e]) * sigm(v[e]));
;                             w[2 * n] = pkh2(f[0], f[1]); w[2 * n + 1] = pkh2(f[2], f[3]); }
;                         else { if (seg == 3) {
; #pragma unroll
;                                 for (int e = 0; e < 4; ++e) v[e] = v[e] * sigm(v[e]); }
;                             w[2 * n] = pk2(v[0], v[1]); w[2 * n + 1] = pk2(v[2], v[3]); } }
;                     o.x = w[0]; o.y = w[1]; o.z = w[2]; o.w = w[3];
;                     *(u32x4v*)(dst + (size_t)row * 512 + cb + bj * 128) = o; } }
.LBB0_329:
	v_pk_mul_f32 v[96:97], v[92:93], v[196:197] op_sel_hi:[1,0]
	v_pk_mul_f32 v[98:99], v[94:95], v[196:197] op_sel_hi:[1,0]
	s_mov_b64 s[20:21], -1
	s_mov_b64 s[0:1], 0
	s_cmp_lt_i32 s13, 3
	s_mov_b64 s[10:11], 0
	global_store_dwordx4 v[112:113], v[100:103], off offset:256 nt
	s_cbranch_scc1 .LBB0_335
	s_nop 0
	v_mov_b64_e32 v[102:103], v[98:99]
	s_cmp_eq_u32 s13, 3
	v_mov_b64_e32 v[100:101], v[96:97]
	s_cbranch_scc0 .LBB0_332
	v_mul_f32_e32 v92, 0xbfb8aa3b, v96
	v_mul_f32_e32 v93, 0xbfb8aa3b, v97
	v_mul_f32_e32 v94, 0xbfb8aa3b, v98
	v_mul_f32_e32 v95, 0xbfb8aa3b, v99
	v_exp_f32_e32 v92, v92
	v_exp_f32_e32 v93, v93
	v_exp_f32_e32 v94, v94
	v_exp_f32_e32 v95, v95
	v_add_f32_e32 v92, 1.0, v92
	v_add_f32_e32 v93, 1.0, v93
	v_add_f32_e32 v94, 1.0, v94
	v_add_f32_e32 v95, 1.0, v95
	v_rcp_f32_e32 v92, v92
	v_rcp_f32_e32 v94, v94
	v_rcp_f32_e32 v95, v95
	v_rcp_f32_e32 v93, v93
	v_pk_mul_f32 v[102:103], v[98:99], v[94:95]
	v_pk_mul_f32 v[100:101], v[96:97], v[92:93]

; DI unsigned pk2(float lo, float hi) { unsigned r; asm volatile("v_cvt_pk_bf16_f32 %0, %1, %2" : "=v"(r) : "v"(lo), "v"(hi)); return r; }
; DI float sigm(float x) { return __builtin_amdgcn_rcpf(1.f + __expf(-x)); }
;     DI void operator()(const f32x4 (&acc)[2][2][4][2], const Unit& u, int wr, int wc, int fr, int fq, const Pre& pre) const {
;     ...
;             for (int m = 0; m < 4; ++m) { const int row = row0 + ai * 128 + m * 16; const float r = rs[ai][m];
; #pragma unroll
;                 for (int bj = 0; bj < 2; ++bj) { u32x4v o; unsigned w[4];
; #pragma unroll
;                     for (int n = 0; n < 2; ++n) { f32x4 v = acc[ai][bj][m][n] * r;
;                         if (seg == 1) { const f32x4 lb = lbv[bj][n]; f32x4 f;
; #pragma unroll
;                             for (int e = 0; e < 4; ++e) f[e] = __logf(lb[e] + (1.f - lb[e]) * sigm(v[e]));
;                             w[2 * n] = pkh2(f[0], f[1]); w[2 * n + 1] = pkh2(f[2], f[3]); }
;                         else { if (seg == 3) {
; #pragma unroll
;                                 for (int e = 0; e < 4; ++e) v[e] = v[e] * sigm(v[e]); }
;                             w[2 * n] = pk2(v[0], v[1]); w[2 * n + 1] = pk2(v[2], v[3]); } }
;                     o.x = w[0]; o.y = w[1]; o.z = w[2]; o.w = w[3];
;                     *(u32x4v*)(dst + (size_t)row * 512 + cb + bj * 128) = o; } }
.LBB0_349:
	v_ashrrev_i32_e32 v199, 31, v198
	v_lshlrev_b64 v[88:89], 10, v[198:199]
	v_lshl_add_u64 v[96:97], v[146:147], 0, v[88:89]
	v_mov_b32_e32 v88, v196
	v_mov_b32_e32 v89, v196
	v_pk_mul_f32 v[90:91], v[86:87], v[88:89]
	v_pk_mul_f32 v[88:89], v[84:85], v[196:197]
	s_mov_b64 s[20:21], -1
	s_mov_b64 s[0:1], 0
	s_cmp_lt_i32 s13, 3
	s_mov_b64 s[10:11], 0
	global_store_dwordx4 v[96:97], v[92:95], off nt
	s_cbranch_scc1 .LBB0_355
	s_nop 0
	v_mov_b64_e32 v[94:95], v[90:91]
	s_cmp_eq_u32 s13, 3
	v_mov_b64_e32 v[92:93], v[88:89]
	s_cbranch_scc0 .LBB0_352
	v_mul_f32_e32 v84, 0xbfb8aa3b, v88
	v_mul_f32_e32 v85, 0xbfb8aa3b, v89
	v_mul_f32_e32 v86, 0xbfb8aa3b, v90
	v_mul_f32_e32 v87, 0xbfb8aa3b, v91
	v_exp_f32_e32 v84, v84
	v_exp_f32_e32 v85, v85
	v_exp_f32_e32 v86, v86
	v_exp_f32_e32 v87, v87
	v_add_f32_e32 v84, 1.0, v84
	v_add_f32_e32 v85, 1.0, v85
	v_add_f32_e32 v86, 1.0, v86
	v_add_f32_e32 v87, 1.0, v87
	v_rcp_f32_e32 v84, v84
	v_rcp_f32_e32 v86, v86
	v_rcp_f32_e32 v87, v87
	v_rcp_f32_e32 v85, v85
	v_pk_mul_f32 v[94:95], v[90:91], v[86:87]
	v_pk_mul_f32 v[92:93], v[88:89], v[84:85]

; DI unsigned pk2(float lo, float hi) { unsigned r; asm volatile("v_cvt_pk_bf16_f32 %0, %1, %2" : "=v"(r) : "v"(lo), "v"(hi)); return r; }
; DI float sigm(float x) { return __builtin_amdgcn_rcpf(1.f + __expf(-x)); }
;     DI void operator()(const f32x4 (&acc)[2][2][4][2], const Unit& u, int wr, int wc, int fr, int fq, const Pre& pre) const {
;     ...
;             for (int m = 0; m < 4; ++m) { const int row = row0 + ai * 128 + m * 16; const float r = rs[ai][m];
; #pragma unroll
;                 for (int bj = 0; bj < 2; ++bj) { u32x4v o; unsigned w[4];
; #pragma unroll
;                     for (int n = 0; n < 2; ++n) { f32x4 v = acc[ai][bj][m][n] * r;
;                         if (seg == 1) { const f32x4 lb = lbv[bj][n]; f32x4 f;
; #pragma unroll
;                             for (int e = 0; e < 4; ++e) f[e] = __logf(lb[e] + (1.f - lb[e]) * sigm(v[e]));
;                             w[2 * n] = pkh2(f[0], f[1]); w[2 * n + 1] = pkh2(f[2], f[3]); }
;                         else { if (seg == 3) {
; #pragma unroll
;                                 for (int e = 0; e < 4; ++e) v[e] = v[e] * sigm(v[e]); }
;                             w[2 * n] = pk2(v[0], v[1]); w[2 * n + 1] = pk2(v[2], v[3]); } }
;                     o.x = w[0]; o.y = w[1]; o.z = w[2]; o.w = w[3];
;                     *(u32x4v*)(dst + (size_t)row * 512 + cb + bj * 128) = o; } }
.LBB0_369:
	v_pk_mul_f32 v[80:81], v[76:77], v[194:195] op_sel_hi:[1,0]
	v_pk_mul_f32 v[82:83], v[78:79], v[194:195] op_sel_hi:[1,0]
	s_mov_b64 s[20:21], -1
	s_mov_b64 s[0:1], 0
	s_cmp_lt_i32 s13, 3
	s_mov_b64 s[10:11], 0
	global_store_dwordx4 v[96:97], v[84:87], off offset:256 nt
	s_cbranch_scc1 .LBB0_375
	s_nop 0
	v_mov_b64_e32 v[86:87], v[82:83]
	s_cmp_eq_u32 s13, 3
	v_mov_b64_e32 v[84:85], v[80:81]
	s_cbranch_scc0 .LBB0_372
	v_mul_f32_e32 v76, 0xbfb8aa3b, v80
	v_mul_f32_e32 v77, 0xbfb8aa3b, v81
	v_mul_f32_e32 v78, 0xbfb8aa3b, v82
	v_mul_f32_e32 v79, 0xbfb8aa3b, v83
	v_exp_f32_e32 v76, v76
	v_exp_f32_e32 v77, v77
	v_exp_f32_e32 v78, v78
	v_exp_f32_e32 v79, v79
	v_add_f32_e32 v76, 1.0, v76
	v_add_f32_e32 v77, 1.0, v77
	v_add_f32_e32 v78, 1.0, v78
	v_add_f32_e32 v79, 1.0, v79
	v_rcp_f32_e32 v76, v76
	v_rcp_f32_e32 v78, v78
	v_rcp_f32_e32 v79, v79
	v_rcp_f32_e32 v77, v77
	v_pk_mul_f32 v[86:87], v[82:83], v[78:79]
	v_pk_mul_f32 v[84:85], v[80:81], v[76:77]

; DI unsigned pk2(float lo, float hi) { unsigned r; asm volatile("v_cvt_pk_bf16_f32 %0, %1, %2" : "=v"(r) : "v"(lo), "v"(hi)); return r; }
; DI float sigm(float x) { return __builtin_amdgcn_rcpf(1.f + __expf(-x)); }
;     DI void operator()(const f32x4 (&acc)[2][2][4][2], const Unit& u, int wr, int wc, int fr, int fq, const Pre& pre) const {
;     ...
;             for (int m = 0; m < 4; ++m) { const int row = row0 + ai * 128 + m * 16; const float r = rs[ai][m];
; #pragma unroll
;                 for (int bj = 0; bj < 2; ++bj) { u32x4v o; unsigned w[4];
; #pragma unroll
;                     for (int n = 0; n < 2; ++n) { f32x4 v = acc[ai][bj][m][n] * r;
;                         if (seg == 1) { const f32x4 lb = lbv[bj][n]; f32x4 f;
; #pragma unroll
;                             for (int e = 0; e < 4; ++e) f[e] = __logf(lb[e] + (1.f - lb[e]) * sigm(v[e]));
;                             w[2 * n] = pkh2(f[0], f[1]); w[2 * n + 1] = pkh2(f[2], f[3]); }
;                         else { if (seg == 3) {
; #pragma unroll
;                                 for (int e = 0; e < 4; ++e) v[e] = v[e] * sigm(v[e]); }
;                             w[2 * n] = pk2(v[0], v[1]); w[2 * n + 1] = pk2(v[2], v[3]); } }
;                     o.x = w[0]; o.y = w[1]; o.z = w[2]; o.w = w[3];
;                     *(u32x4v*)(dst + (size_t)row * 512 + cb + bj * 128) = o; } }
.LBB0_389:
	v_add_co_u32_e32 v72, vcc, 0x20000, v144
	s_mov_b64 s[0:1], 0x20000
	s_nop 0
	v_addc_co_u32_e32 v73, vcc, 0, v145, vcc
	global_store_dwordx4 v[72:73], v[76:79], off nt
	v_mov_b32_e32 v72, v194
	v_mov_b32_e32 v73, v194
	v_lshl_add_u64 v[80:81], v[144:145], 0, s[0:1]
	v_pk_mul_f32 v[74:75], v[70:71], v[72:73]
	v_pk_mul_f32 v[72:73], v[68:69], v[82:83]
	s_mov_b64 s[20:21], -1
	s_mov_b64 s[0:1], 0
	s_cmp_lt_i32 s13, 3
	s_mov_b64 s[10:11], 0
	s_cbranch_scc1 .LBB0_395
	v_mov_b64_e32 v[78:79], v[74:75]
	s_cmp_eq_u32 s13, 3
	v_mov_b64_e32 v[76:77], v[72:73]
	s_cbranch_scc0 .LBB0_392
	v_mul_f32_e32 v68, 0xbfb8aa3b, v72
	v_mul_f32_e32 v69, 0xbfb8aa3b, v73
	v_mul_f32_e32 v70, 0xbfb8aa3b, v74
	v_mul_f32_e32 v71, 0xbfb8aa3b, v75
	v_exp_f32_e32 v68, v68
	v_exp_f32_e32 v69, v69
	v_exp_f32_e32 v70, v70
	v_exp_f32_e32 v71, v71
	v_add_f32_e32 v68, 1.0, v68
	v_add_f32_e32 v69, 1.0, v69
	v_add_f32_e32 v70, 1.0, v70
	v_add_f32_e32 v71, 1.0, v71
	v_rcp_f32_e32 v68, v68
	v_rcp_f32_e32 v70, v70
	v_rcp_f32_e32 v71, v71
	v_rcp_f32_e32 v69, v69
	v_pk_mul_f32 v[78:79], v[74:75], v[70:71]
	v_pk_mul_f32 v[76:77], v[72:73], v[68:69]

; DI unsigned pk2(float lo, float hi) { unsigned r; asm volatile("v_cvt_pk_bf16_f32 %0, %1, %2" : "=v"(r) : "v"(lo), "v"(hi)); return r; }
; DI float sigm(float x) { return __builtin_amdgcn_rcpf(1.f + __expf(-x)); }
;     DI void operator()(const f32x4 (&acc)[2][2][4][2], const Unit& u, int wr, int wc, int fr, int fq, const Pre& pre) const {
;     ...
;             for (int m = 0; m < 4; ++m) { const int row = row0 + ai * 128 + m * 16; const float r = rs[ai][m];
; #pragma unroll
;                 for (int bj = 0; bj < 2; ++bj) { u32x4v o; unsigned w[4];
; #pragma unroll
;                     for (int n = 0; n < 2; ++n) { f32x4 v = acc[ai][bj][m][n] * r;
;                         if (seg == 1) { const f32x4 lb = lbv[bj][n]; f32x4 f;
; #pragma unroll
;                             for (int e = 0; e < 4; ++e) f[e] = __logf(lb[e] + (1.f - lb[e]) * sigm(v[e]));
;                             w[2 * n] = pkh2(f[0], f[1]); w[2 * n + 1] = pkh2(f[2], f[3]); }
;                         else { if (seg == 3) {
; #pragma unroll
;                                 for (int e = 0; e < 4; ++e) v[e] = v[e] * sigm(v[e]); }
;                             w[2 * n] = pk2(v[0], v[1]); w[2 * n + 1] = pk2(v[2], v[3]); } }
;                     o.x = w[0]; o.y = w[1]; o.z = w[2]; o.w = w[3];
;                     *(u32x4v*)(dst + (size_t)row * 512 + cb + bj * 128) = o; } }
.LBB0_409:
	v_pk_mul_f32 v[64:65], v[60:61], v[194:195] op_sel:[0,1]
	v_pk_mul_f32 v[66:67], v[62:63], v[194:195] op_sel:[0,1]
	s_mov_b64 s[20:21], -1
	s_mov_b64 s[0:1], 0
	s_cmp_lt_i32 s13, 3
	s_mov_b64 s[10:11], 0
	global_store_dwordx4 v[80:81], v[68:71], off offset:256 nt
	s_cbranch_scc1 .LBB0_415
	s_nop 0
	v_mov_b64_e32 v[70:71], v[66:67]
	s_cmp_eq_u32 s13, 3
	v_mov_b64_e32 v[68:69], v[64:65]
	s_cbranch_scc0 .LBB0_412
	v_mul_f32_e32 v60, 0xbfb8aa3b, v64
	v_mul_f32_e32 v61, 0xbfb8aa3b, v65
	v_mul_f32_e32 v62, 0xbfb8aa3b, v66
	v_mul_f32_e32 v63, 0xbfb8aa3b, v67
	v_exp_f32_e32 v60, v60
	v_exp_f32_e32 v61, v61
	v_exp_f32_e32 v62, v62
	v_exp_f32_e32 v63, v63
	v_add_f32_e32 v60, 1.0, v60
	v_add_f32_e32 v61, 1.0, v61
	v_add_f32_e32 v62, 1.0, v62
	v_add_f32_e32 v63, 1.0, v63
	v_rcp_f32_e32 v60, v60
	v_rcp_f32_e32 v62, v62
	v_rcp_f32_e32 v63, v63
	v_rcp_f32_e32 v61, v61
	v_pk_mul_f32 v[70:71], v[66:67], v[62:63]
	v_pk_mul_f32 v[68:69], v[64:65], v[60:61]

; DI unsigned pk2(float lo, float hi) { unsigned r; asm volatile("v_cvt_pk_bf16_f32 %0, %1, %2" : "=v"(r) : "v"(lo), "v"(hi)); return r; }
; DI float sigm(float x) { return __builtin_amdgcn_rcpf(1.f + __expf(-x)); }
;     DI void operator()(const f32x4 (&acc)[2][2][4][2], const Unit& u, int wr, int wc, int fr, int fq, const Pre& pre) const {
;     ...
;             for (int m = 0; m < 4; ++m) { const int row = row0 + ai * 128 + m * 16; const float r = rs[ai][m];
; #pragma unroll
;                 for (int bj = 0; bj < 2; ++bj) { u32x4v o; unsigned w[4];
; #pragma unroll
;                     for (int n = 0; n < 2; ++n) { f32x4 v = acc[ai][bj][m][n] * r;
;                         if (seg == 1) { const f32x4 lb = lbv[bj][n]; f32x4 f;
; #pragma unroll
;                             for (int e = 0; e < 4; ++e) f[e] = __logf(lb[e] + (1.f - lb[e]) * sigm(v[e]));
;                             w[2 * n] = pkh2(f[0], f[1]); w[2 * n + 1] = pkh2(f[2], f[3]); }
;                         else { if (seg == 3) {
; #pragma unroll
;                                 for (int e = 0; e < 4; ++e) v[e] = v[e] * sigm(v[e]); }
;                             w[2 * n] = pk2(v[0], v[1]); w[2 * n + 1] = pk2(v[2], v[3]); } }
;                     o.x = w[0]; o.y = w[1]; o.z = w[2]; o.w = w[3];
;                     *(u32x4v*)(dst + (size_t)row * 512 + cb + bj * 128) = o; } }
.LBB0_429:
	v_add_co_u32_e32 v56, vcc, 0x24000, v144
	s_mov_b64 s[0:1], 0x24000
	s_nop 0
	v_addc_co_u32_e32 v57, vcc, 0, v145, vcc
	global_store_dwordx4 v[56:57], v[60:63], off nt
	v_mov_b32_e32 v56, v195
	v_mov_b32_e32 v57, v195
	v_lshl_add_u64 v[64:65], v[144:145], 0, s[0:1]
	v_pk_mul_f32 v[58:59], v[54:55], v[56:57]
	v_pk_mul_f32 v[56:57], v[52:53], v[194:195]
	s_mov_b64 s[20:21], -1
	s_mov_b64 s[0:1], 0
	s_cmp_lt_i32 s13, 3
	s_mov_b64 s[10:11], 0
	s_cbranch_scc1 .LBB0_435
	v_mov_b64_e32 v[62:63], v[58:59]
	s_cmp_eq_u32 s13, 3
	v_mov_b64_e32 v[60:61], v[56:57]
	s_cbranch_scc0 .LBB0_432
	v_mul_f32_e32 v52, 0xbfb8aa3b, v56
	v_mul_f32_e32 v53, 0xbfb8aa3b, v57
	v_mul_f32_e32 v54, 0xbfb8aa3b, v58
	v_mul_f32_e32 v55, 0xbfb8aa3b, v59
	v_exp_f32_e32 v52, v52
	v_exp_f32_e32 v53, v53
	v_exp_f32_e32 v54, v54
	v_exp_f32_e32 v55, v55
	v_add_f32_e32 v52, 1.0, v52
	v_add_f32_e32 v53, 1.0, v53
	v_add_f32_e32 v54, 1.0, v54
	v_add_f32_e32 v55, 1.0, v55
	v_rcp_f32_e32 v52, v52
	v_rcp_f32_e32 v54, v54
	v_rcp_f32_e32 v55, v55
	v_rcp_f32_e32 v53, v53
	v_pk_mul_f32 v[62:63], v[58:59], v[54:55]
	v_pk_mul_f32 v[60:61], v[56:57], v[52:53]

; DI unsigned pk2(float lo, float hi) { unsigned r; asm volatile("v_cvt_pk_bf16_f32 %0, %1, %2" : "=v"(r) : "v"(lo), "v"(hi)); return r; }
; DI float sigm(float x) { return __builtin_amdgcn_rcpf(1.f + __expf(-x)); }
;     DI void operator()(const f32x4 (&acc)[2][2][4][2], const Unit& u, int wr, int wc, int fr, int fq, const Pre& pre) const {
;     ...
;             for (int m = 0; m < 4; ++m) { const int row = row0 + ai * 128 + m * 16; const float r = rs[ai][m];
; #pragma unroll
;                 for (int bj = 0; bj < 2; ++bj) { u32x4v o; unsigned w[4];
; #pragma unroll
;                     for (int n = 0; n < 2; ++n) { f32x4 v = acc[ai][bj][m][n] * r;
;                         if (seg == 1) { const f32x4 lb = lbv[bj][n]; f32x4 f;
; #pragma unroll
;                             for (int e = 0; e < 4; ++e) f[e] = __logf(lb[e] + (1.f - lb[e]) * sigm(v[e]));
;                             w[2 * n] = pkh2(f[0], f[1]); w[2 * n + 1] = pkh2(f[2], f[3]); }
;                         else { if (seg == 3) {
; #pragma unroll
;                                 for (int e = 0; e < 4; ++e) v[e] = v[e] * sigm(v[e]); }
;                             w[2 * n] = pk2(v[0], v[1]); w[2 * n + 1] = pk2(v[2], v[3]); } }
;                     o.x = w[0]; o.y = w[1]; o.z = w[2]; o.w = w[3];
;                     *(u32x4v*)(dst + (size_t)row * 512 + cb + bj * 128) = o; } }
.LBB0_449:
	v_pk_mul_f32 v[48:49], v[44:45], v[192:193] op_sel_hi:[1,0]
	v_pk_mul_f32 v[50:51], v[46:47], v[192:193] op_sel_hi:[1,0]
	s_mov_b64 s[20:21], -1
	s_mov_b64 s[0:1], 0
	s_cmp_lt_i32 s13, 3
	s_mov_b64 s[10:11], 0
	global_store_dwordx4 v[64:65], v[52:55], off offset:256 nt
	s_cbranch_scc1 .LBB0_455
	s_nop 0
	v_mov_b64_e32 v[54:55], v[50:51]
	s_cmp_eq_u32 s13, 3
	v_mov_b64_e32 v[52:53], v[48:49]
	s_cbranch_scc0 .LBB0_452
	v_mul_f32_e32 v44, 0xbfb8aa3b, v48
	v_mul_f32_e32 v45, 0xbfb8aa3b, v49
	v_mul_f32_e32 v46, 0xbfb8aa3b, v50
	v_mul_f32_e32 v47, 0xbfb8aa3b, v51
	v_exp_f32_e32 v44, v44
	v_exp_f32_e32 v45, v45
	v_exp_f32_e32 v46, v46
	v_exp_f32_e32 v47, v47
	v_add_f32_e32 v44, 1.0, v44
	v_add_f32_e32 v45, 1.0, v45
	v_add_f32_e32 v46, 1.0, v46
	v_add_f32_e32 v47, 1.0, v47
	v_rcp_f32_e32 v44, v44
	v_rcp_f32_e32 v46, v46
	v_rcp_f32_e32 v47, v47
	v_rcp_f32_e32 v45, v45
	v_pk_mul_f32 v[54:55], v[50:51], v[46:47]
	v_pk_mul_f32 v[52:53], v[48:49], v[44:45]

; DI unsigned pk2(float lo, float hi) { unsigned r; asm volatile("v_cvt_pk_bf16_f32 %0, %1, %2" : "=v"(r) : "v"(lo), "v"(hi)); return r; }
; DI float sigm(float x) { return __builtin_amdgcn_rcpf(1.f + __expf(-x)); }
;     DI void operator()(const f32x4 (&acc)[2][2][4][2], const Unit& u, int wr, int wc, int fr, int fq, const Pre& pre) const {
;     ...
;             for (int m = 0; m < 4; ++m) { const int row = row0 + ai * 128 + m * 16; const float r = rs[ai][m];
; #pragma unroll
;                 for (int bj = 0; bj < 2; ++bj) { u32x4v o; unsigned w[4];
; #pragma unroll
;                     for (int n = 0; n < 2; ++n) { f32x4 v = acc[ai][bj][m][n] * r;
;                         if (seg == 1) { const f32x4 lb = lbv[bj][n]; f32x4 f;
; #pragma unroll
;                             for (int e = 0; e < 4; ++e) f[e] = __logf(lb[e] + (1.f - lb[e]) * sigm(v[e]));
;                             w[2 * n] = pkh2(f[0], f[1]); w[2 * n + 1] = pkh2(f[2], f[3]); }
;                         else { if (seg == 3) {
; #pragma unroll
;                                 for (int e = 0; e < 4; ++e) v[e] = v[e] * sigm(v[e]); }
;                             w[2 * n] = pk2(v[0], v[1]); w[2 * n + 1] = pk2(v[2], v[3]); } }
;                     o.x = w[0]; o.y = w[1]; o.z = w[2]; o.w = w[3];
;                     *(u32x4v*)(dst + (size_t)row * 512 + cb + bj * 128) = o; } }
.LBB0_469:
	v_add_co_u32_e32 v40, vcc, 0x28000, v144
	s_mov_b64 s[0:1], 0x28000
	s_nop 0
	v_addc_co_u32_e32 v41, vcc, 0, v145, vcc
	global_store_dwordx4 v[40:41], v[44:47], off nt
	v_mov_b32_e32 v40, v192
	v_mov_b32_e32 v41, v192
	v_lshl_add_u64 v[48:49], v[144:145], 0, s[0:1]
	v_pk_mul_f32 v[42:43], v[30:31], v[40:41]
	v_pk_mul_f32 v[40:41], v[28:29], v[50:51]
	s_mov_b64 s[20:21], -1
	s_mov_b64 s[0:1], 0
	s_cmp_lt_i32 s13, 3
	s_mov_b64 s[10:11], 0
	s_cbranch_scc1 .LBB0_475
	v_mov_b64_e32 v[46:47], v[42:43]
	s_cmp_eq_u32 s13, 3
	v_mov_b64_e32 v[44:45], v[40:41]
	s_cbranch_scc0 .LBB0_472
	v_mul_f32_e32 v28, 0xbfb8aa3b, v40
	v_mul_f32_e32 v29, 0xbfb8aa3b, v41
	v_mul_f32_e32 v30, 0xbfb8aa3b, v42
	v_mul_f32_e32 v31, 0xbfb8aa3b, v43
	v_exp_f32_e32 v28, v28
	v_exp_f32_e32 v29, v29
	v_exp_f32_e32 v30, v30
	v_exp_f32_e32 v31, v31
	v_add_f32_e32 v28, 1.0, v28
	v_add_f32_e32 v29, 1.0, v29
	v_add_f32_e32 v30, 1.0, v30
	v_add_f32_e32 v31, 1.0, v31
	v_rcp_f32_e32 v28, v28
	v_rcp_f32_e32 v30, v30
	v_rcp_f32_e32 v31, v31
	v_rcp_f32_e32 v29, v29
	v_pk_mul_f32 v[46:47], v[42:43], v[30:31]
	v_pk_mul_f32 v[44:45], v[40:41], v[28:29]

; DI unsigned pk2(float lo, float hi) { unsigned r; asm volatile("v_cvt_pk_bf16_f32 %0, %1, %2" : "=v"(r) : "v"(lo), "v"(hi)); return r; }
; DI float sigm(float x) { return __builtin_amdgcn_rcpf(1.f + __expf(-x)); }
;     DI void operator()(const f32x4 (&acc)[2][2][4][2], const Unit& u, int wr, int wc, int fr, int fq, const Pre& pre) const {
;     ...
;             for (int m = 0; m < 4; ++m) { const int row = row0 + ai * 128 + m * 16; const float r = rs[ai][m];
; #pragma unroll
;                 for (int bj = 0; bj < 2; ++bj) { u32x4v o; unsigned w[4];
; #pragma unroll
;                     for (int n = 0; n < 2; ++n) { f32x4 v = acc[ai][bj][m][n] * r;
;                         if (seg == 1) { const f32x4 lb = lbv[bj][n]; f32x4 f;
; #pragma unroll
;                             for (int e = 0; e < 4; ++e) f[e] = __logf(lb[e] + (1.f - lb[e]) * sigm(v[e]));
;                             w[2 * n] = pkh2(f[0], f[1]); w[2 * n + 1] = pkh2(f[2], f[3]); }
;                         else { if (seg == 3) {
; #pragma unroll
;                                 for (int e = 0; e < 4; ++e) v[e] = v[e] * sigm(v[e]); }
;                             w[2 * n] = pk2(v[0], v[1]); w[2 * n + 1] = pk2(v[2], v[3]); } }
;                     o.x = w[0]; o.y = w[1]; o.z = w[2]; o.w = w[3];
;                     *(u32x4v*)(dst + (size_t)row * 512 + cb + bj * 128) = o; } }
.LBB0_489:
	v_pk_mul_f32 v[20:21], v[16:17], v[192:193] op_sel:[0,1]
	v_pk_mul_f32 v[22:23], v[18:19], v[192:193] op_sel:[0,1]
	s_mov_b64 s[20:21], -1
	s_mov_b64 s[0:1], 0
	s_cmp_lt_i32 s13, 3
	s_mov_b64 s[10:11], 0
	global_store_dwordx4 v[48:49], v[28:31], off offset:256 nt
	s_cbranch_scc1 .LBB0_495
	s_nop 0
	v_mov_b64_e32 v[30:31], v[22:23]
	s_cmp_eq_u32 s13, 3
	v_mov_b64_e32 v[28:29], v[20:21]
	s_cbranch_scc0 .LBB0_492
	v_mul_f32_e32 v16, 0xbfb8aa3b, v20
	v_mul_f32_e32 v17, 0xbfb8aa3b, v21
	v_mul_f32_e32 v18, 0xbfb8aa3b, v22
	v_mul_f32_e32 v19, 0xbfb8aa3b, v23
	v_exp_f32_e32 v16, v16
	v_exp_f32_e32 v17, v17
	v_exp_f32_e32 v18, v18
	v_exp_f32_e32 v19, v19
	v_add_f32_e32 v16, 1.0, v16
	v_add_f32_e32 v17, 1.0, v17
	v_add_f32_e32 v18, 1.0, v18
	v_add_f32_e32 v19, 1.0, v19
	v_rcp_f32_e32 v16, v16
	v_rcp_f32_e32 v18, v18
	v_rcp_f32_e32 v19, v19
	v_rcp_f32_e32 v17, v17
	v_pk_mul_f32 v[30:31], v[22:23], v[18:19]
	v_pk_mul_f32 v[28:29], v[20:21], v[16:17]

; DI unsigned pk2(float lo, float hi) { unsigned r; asm volatile("v_cvt_pk_bf16_f32 %0, %1, %2" : "=v"(r) : "v"(lo), "v"(hi)); return r; }
; DI float sigm(float x) { return __builtin_amdgcn_rcpf(1.f + __expf(-x)); }
;     DI void operator()(const f32x4 (&acc)[2][2][4][2], const Unit& u, int wr, int wc, int fr, int fq, const Pre& pre) const {
;     ...
;             for (int m = 0; m < 4; ++m) { const int row = row0 + ai * 128 + m * 16; const float r = rs[ai][m];
; #pragma unroll
;                 for (int bj = 0; bj < 2; ++bj) { u32x4v o; unsigned w[4];
; #pragma unroll
;                     for (int n = 0; n < 2; ++n) { f32x4 v = acc[ai][bj][m][n] * r;
;                         if (seg == 1) { const f32x4 lb = lbv[bj][n]; f32x4 f;
; #pragma unroll
;                             for (int e = 0; e < 4; ++e) f[e] = __logf(lb[e] + (1.f - lb[e]) * sigm(v[e]));
;                             w[2 * n] = pkh2(f[0], f[1]); w[2 * n + 1] = pkh2(f[2], f[3]); }
;                         else { if (seg == 3) {
; #pragma unroll
;                                 for (int e = 0; e < 4; ++e) v[e] = v[e] * sigm(v[e]); }
;                             w[2 * n] = pk2(v[0], v[1]); w[2 * n + 1] = pk2(v[2], v[3]); } }
;                     o.x = w[0]; o.y = w[1]; o.z = w[2]; o.w = w[3];
;                     *(u32x4v*)(dst + (size_t)row * 512 + cb + bj * 128) = o; } }
.LBB0_509:
	v_add_co_u32_e32 v8, vcc, 0x2c000, v144
	s_mov_b64 s[0:1], 0x2c000
	s_nop 0
	v_addc_co_u32_e32 v9, vcc, 0, v145, vcc
	global_store_dwordx4 v[8:9], v[16:19], off nt
	v_mov_b32_e32 v8, v193
	v_mov_b32_e32 v9, v193
	v_lshl_add_u64 v[20:21], v[144:145], 0, s[0:1]
	v_pk_mul_f32 v[10:11], v[6:7], v[8:9]
	v_pk_mul_f32 v[8:9], v[4:5], v[192:193]
	s_mov_b64 s[20:21], -1
	s_mov_b64 s[0:1], 0
	s_cmp_lt_i32 s13, 3
	s_mov_b64 s[10:11], 0
	s_cbranch_scc1 .LBB0_515
	v_mov_b64_e32 v[18:19], v[10:11]
	s_cmp_eq_u32 s13, 3
	v_mov_b64_e32 v[16:17], v[8:9]
	s_cbranch_scc0 .LBB0_512
	v_mul_f32_e32 v4, 0xbfb8aa3b, v8
	v_mul_f32_e32 v5, 0xbfb8aa3b, v9
	v_mul_f32_e32 v6, 0xbfb8aa3b, v10
	v_mul_f32_e32 v7, 0xbfb8aa3b, v11
	v_exp_f32_e32 v4, v4
	v_exp_f32_e32 v5, v5
	v_exp_f32_e32 v6, v6
	v_exp_f32_e32 v7, v7
	v_add_f32_e32 v4, 1.0, v4
	v_add_f32_e32 v5, 1.0, v5
	v_add_f32_e32 v6, 1.0, v6
	v_add_f32_e32 v7, 1.0, v7
	v_rcp_f32_e32 v4, v4
	v_rcp_f32_e32 v6, v6
	v_rcp_f32_e32 v7, v7
	v_rcp_f32_e32 v5, v5
	v_pk_mul_f32 v[18:19], v[10:11], v[6:7]
	v_pk_mul_f32 v[16:17], v[8:9], v[4:5]

; #define LAS __attribute__((address_space(3)))
; DI void hgrn_b3_all(const Prm& p, LAS unsigned char* lds, int tid, int lane, int wave) {
;     ...
;         {
;             const int tt = wave >> 1;
; #pragma unroll
;             for (int i = 0; i < 2; ++i) { const int st = 2 * (wave & 1) + i; f32x4 acc = {0.f, 0.f, 0.f, 0.f};
; #pragma unroll
;                 for (int ks = 0; ks < 4; ++ks) { const bf16x8 a = *(const LAS bf16x8*)(lds + L_KT + ((16 * st + fr) * HP + 32 * ks + 8 * fq) * 2);
;                     const bf16x8 b = *(const LAS bf16x8*)(lds + L_QT + ((16 * tt + fr) * HP + 32 * ks + 8 * fq) * 2); acc = MFMA16(a, b, acc); }
;                 const int t = 16 * tt + fr, s0 = 16 * st + 4 * fq;
;                 u32x2 o; o.x = pk2(s0 <= t ? acc[0] : 0.f, s0 + 1 <= t ? acc[1] : 0.f); o.y = pk2(s0 + 2 <= t ? acc[2] : 0.f, s0 + 3 <= t ? acc[3] : 0.f);
;                 *(LAS u32x2*)(lds + L_ATT + (t * TPI + s0) * 2) = o; }
;         }
;         __syncthreads();
;         f32x4 oacc[4];
;         {   const int tt = wave & 3;
;             bf16x8 aa[2], aq[4];
; #pragma unroll
;             for (int ks = 0; ks < 2; ++ks) aa[ks] = *(const LAS bf16x8*)(lds + L_ATT + ((16 * tt + fr) * TPI + 32 * ks + 8 * fq) * 2);
; #pragma unroll
;             for (int ks = 0; ks < 4; ++ks) aq[ks] = *(const LAS bf16x8*)(lds + L_QH + ((16 * tt + fr) * HP + 32 * ks + 8 * fq) * 2);
; #pragma unroll
;             for (int i = 0; i < 4; ++i) { const int vt = 4 * (wave >> 2) + i; f32x4 acc = {0.f, 0.f, 0.f, 0.f};
; #pragma unroll
;                 for (int ks = 0; ks < 2; ++ks) { const bf16x8 b = *(const LAS bf16x8*)(lds + L_IVT + ((16 * vt + fr) * TPI + 32 * ks + 8 * fq) * 2); acc = MFMA16(aa[ks], b, acc); }
; #pragma unroll
;                 for (int ks = 0; ks < 4; ++ks) acc = MFMA16(aq[ks], sf[i][ks], acc);
;                 oacc[i] = acc; }
;         }
;         f32x4 gn[4];
; #pragma unroll
;         for (int j = 0; j < 4; ++j) gn[j] = ((const f32x4*)(p.hgrn_norm + 16 * nsg))[j];
;         __syncthreads();
;         {   const int tt = wave & 3; LAS float* ob = (LAS float*)(lds + L_OB);
; #pragma unroll
;             for (int i = 0; i < 4; ++i) { const int v = 16 * (4 * (wave >> 2) + i) + fr;
; #pragma unroll
;                 for (int j = 0; j < 4; ++j) ob[(16 * tt + 4 * fq + j) * 132 + v] = oacc[i][j]; }
;         }
.LBB0_1096:
	ds_read_b128 v[212:215], v192 offset:34816
	ds_read_b128 v[216:219], v193
	ds_read_b128 v[220:223], v192 offset:34880
	ds_read_b128 v[224:227], v193 offset:64
	s_waitcnt lgkmcnt(2)
	v_mfma_f32_16x16x32_bf16 v[212:215], v[212:215], v[216:219], 0
	ds_read_b128 v[216:219], v192 offset:34944
	ds_read_b128 v[228:231], v193 offset:128
	s_waitcnt lgkmcnt(2)
	v_mfma_f32_16x16x32_bf16 v[212:215], v[220:223], v[224:227], v[212:215]
	ds_read_b128 v[220:223], v192 offset:35008
	s_waitcnt lgkmcnt(1)
	v_mfma_f32_16x16x32_bf16 v[212:215], v[216:219], v[228:231], v[212:215]
	ds_read_b128 v[216:219], v193 offset:192
	s_waitcnt lgkmcnt(0)
	v_mfma_f32_16x16x32_bf16 v[212:215], v[220:223], v[216:219], v[212:215]
	s_nop 7
	v_cndmask_b32_e64 v112, v212, 0, s[4:5]
	v_cndmask_b32_e64 v113, 0, v213, s[6:7]
	v_cndmask_b32_e64 v211, v214, 0, s[8:9]
	v_cndmask_b32_e64 v212, v215, 0, s[12:13]
	v_cvt_pk_bf16_f32 v112, v112, v113
	v_cvt_pk_bf16_f32 v113, v211, v212
	ds_write_b64 v202, v[112:113]
	ds_read_b128 v[212:215], v194 offset:34816
	ds_read_b128 v[216:219], v193
	ds_read_b128 v[220:223], v194 offset:34880
	ds_read_b128 v[224:227], v193 offset:64
	s_waitcnt lgkmcnt(2)
	v_mfma_f32_16x16x32_bf16 v[212:215], v[212:215], v[216:219], 0
	ds_read_b128 v[216:219], v194 offset:34944
	ds_read_b128 v[228:231], v193 offset:128
	s_waitcnt lgkmcnt(2)
	v_mfma_f32_16x16x32_bf16 v[212:215], v[220:223], v[224:227], v[212:215]
	ds_read_b128 v[220:223], v194 offset:35008
	s_waitcnt lgkmcnt(1)
	v_mfma_f32_16x16x32_bf16 v[212:215], v[216:219], v[228:231], v[212:215]
	ds_read_b128 v[216:219], v193 offset:192
	s_waitcnt lgkmcnt(0)
	v_mfma_f32_16x16x32_bf16 v[212:215], v[220:223], v[216:219], v[212:215]
	s_nop 7
	v_cndmask_b32_e64 v112, v212, 0, s[14:15]
	v_cndmask_b32_e64 v113, 0, v213, s[16:17]
	v_cndmask_b32_e64 v212, v215, 0, s[20:21]
	v_cndmask_b32_e64 v211, v214, 0, s[18:19]
	v_cvt_pk_bf16_f32 v112, v112, v113
	v_cvt_pk_bf16_f32 v113, v211, v212
	ds_write_b64 v203, v[112:113]
	s_waitcnt lgkmcnt(0)
	s_barrier
	ds_read_b128 v[212:215], v195
	ds_read_b128 v[216:219], v197
	ds_read_b128 v[220:223], v197 offset:2304
	ds_read_b128 v[224:227], v197 offset:4608
	ds_read_b128 v[228:231], v195 offset:64
	ds_read_b128 v[232:235], v197 offset:64
	s_waitcnt lgkmcnt(4)
	v_mfma_f32_16x16x32_bf16 v[216:219], v[212:215], v[216:219], 0
	s_waitcnt lgkmcnt(0)
	v_mfma_f32_16x16x32_bf16 v[216:219], v[228:231], v[232:235], v[216:219]
	ds_read_b128 v[232:235], v197 offset:2368
	v_mfma_f32_16x16x32_bf16 v[220:223], v[212:215], v[220:223], 0
	s_waitcnt lgkmcnt(0)
	v_mfma_f32_16x16x32_bf16 v[220:223], v[228:231], v[232:235], v[220:223]
	ds_read_b128 v[232:235], v196 offset:17408
	s_waitcnt vmcnt(17) lgkmcnt(0)
	v_mfma_f32_16x16x32_bf16 v[92:95], v[232:235], v[92:95], v[216:219]
	s_nop 2
	ds_read_b128 v[216:219], v196 offset:17472
	s_waitcnt vmcnt(13)
	v_mfma_f32_16x16x32_bf16 v[100:103], v[232:235], v[100:103], v[220:223]
	s_waitcnt lgkmcnt(0)
	v_mfma_f32_16x16x32_bf16 v[84:87], v[216:219], v[84:87], v[92:95]
	s_waitcnt vmcnt(12)
	v_mfma_f32_16x16x32_bf16 v[92:95], v[216:219], v[96:99], v[100:103]
	ds_read_b128 v[96:99], v196 offset:17536
	s_waitcnt lgkmcnt(0)
	v_mfma_f32_16x16x32_bf16 v[76:79], v[96:99], v[76:79], v[84:87]
	s_waitcnt vmcnt(11)
	v_mfma_f32_16x16x32_bf16 v[84:87], v[96:99], v[88:91], v[92:95]
	ds_read_b128 v[88:91], v196 offset:17600
	s_waitcnt lgkmcnt(0)
	v_mfma_f32_16x16x32_bf16 v[72:75], v[88:91], v[72:75], v[76:79]
	s_waitcnt vmcnt(10)
	v_mfma_f32_16x16x32_bf16 v[76:79], v[88:91], v[80:83], v[84:87]
	ds_read_b128 v[80:83], v197 offset:4672
	v_mfma_f32_16x16x32_bf16 v[224:227], v[212:215], v[224:227], 0
	s_waitcnt lgkmcnt(0)
	v_mfma_f32_16x16x32_bf16 v[80:83], v[228:231], v[80:83], v[224:227]
	s_waitcnt vmcnt(9)
	v_mfma_f32_16x16x32_bf16 v[56:59], v[232:235], v[56:59], v[80:83]
	s_waitcnt vmcnt(8)
	v_mfma_f32_16x16x32_bf16 v[56:59], v[216:219], v[60:63], v[56:59]
	ds_read_b128 v[60:63], v198 offset:64
	s_waitcnt vmcnt(7)
	v_mfma_f32_16x16x32_bf16 v[56:59], v[96:99], v[64:67], v[56:59]
	s_waitcnt vmcnt(6)
	v_mfma_f32_16x16x32_bf16 v[68:71], v[88:91], v[68:71], v[56:59]
	s_nop 5
	ds_read_b128 v[56:59], v198
	s_waitcnt lgkmcnt(0)
	v_mfma_f32_16x16x32_bf16 v[56:59], v[212:215], v[56:59], 0
	v_mfma_f32_16x16x32_bf16 v[80:83], v[228:231], v[60:63], v[56:59]
	s_nop 6
	global_load_dwordx4 v[56:59], v[110:111], off offset:48
	global_load_dwordx4 v[60:63], v[110:111], off offset:32
	global_load_dwordx4 v[64:67], v[110:111], off offset:16
	s_waitcnt vmcnt(8)
	v_mfma_f32_16x16x32_bf16 v[80:83], v[232:235], v[52:55], v[80:83]
	global_load_dwordx4 v[52:55], v[110:111], off
	s_barrier
	s_waitcnt vmcnt(8)
	v_mfma_f32_16x16x32_bf16 v[48:51], v[216:219], v[48:51], v[80:83]
	ds_write2_b32 v199, v72, v76 offset1:16
	ds_write2_b32 v199, v73, v77 offset0:132 offset1:148
	s_waitcnt vmcnt(7)
	v_mfma_f32_16x16x32_bf16 v[44:47], v[96:99], v[44:47], v[48:51]
	s_waitcnt vmcnt(6)
	v_mfma_f32_16x16x32_bf16 v[40:43], v[88:91], v[40:43], v[44:47]
	s_nop 1
	v_add_u32_e32 v48, 0x400, v199
	ds_write2_b32 v48, v74, v78 offset0:8 offset1:24
	ds_write2_b32 v48, v75, v79 offset0:140 offset1:156
	s_nop 2
	ds_write2_b32 v199, v68, v40 offset0:32 offset1:48
	ds_write2_b32 v199, v69, v41 offset0:164 offset1:180
	ds_write2_b32 v48, v70, v42 offset0:40 offset1:56
	ds_write2_b32 v48, v71, v43 offset0:172 offset1:188
	s_waitcnt lgkmcnt(0)
	s_barrier
; #define LAS __attribute__((address_space(3)))
; DI unsigned pk2(float lo, float hi) { unsigned r; asm volatile("v_cvt_pk_bf16_f32 %0, %1, %2" : "=v"(r) : "v"(lo), "v"(hi)); return r; }
; DI float bflo(unsigned u) { return __uint_as_float(u << 16); }
; DI float bfhi(unsigned u) { return __uint_as_float(u & 0xffff0000u); }
; DI void hgrn_b3_all(const Prm& p, LAS unsigned char* lds, int tid, int lane, int wave) {
;     ...
;         {   const int t = nt_, sg = nsg; const LAS float* ob = (const LAS float*)(lds + L_OB) + t * 132 + 16 * sg;
;             f32x4 x[4]; float ss = 0.f;
; #pragma unroll
;             for (int j = 0; j < 4; ++j) { x[j] = ((const LAS f32x4*)ob)[j]; ss += (x[j].x * x[j].x + x[j].y * x[j].y) + (x[j].z * x[j].z + x[j].w * x[j].w); }
;             ss += __shfl_xor(ss, 1); ss += __shfl_xor(ss, 2); ss += __shfl_xor(ss, 4);
;             const float rr = rsqrtf(ss * (1.f / 128.f) + EPSN);
;             if (t < it.L) { const size_t row = it.row0 + t; const int c0 = it.h * 128 + 16 * sg;
;                 const f32x4 n0 = gn[0], n1 = gn[1], n2 = gn[2], n3 = gn[3];
;                 u32x4v o0, o1;
;                 o0.x = pk2(x[0].x * rr * n0.x * bflo(g0.x), x[0].y * rr * n0.y * bfhi(g0.x)); o0.y = pk2(x[0].z * rr * n0.z * bflo(g0.y), x[0].w * rr * n0.w * bfhi(g0.y));
;                 o0.z = pk2(x[1].x * rr * n1.x * bflo(g0.z), x[1].y * rr * n1.y * bfhi(g0.z)); o0.w = pk2(x[1].z * rr * n1.z * bflo(g0.w), x[1].w * rr * n1.w * bfhi(g0.w));
;                 o1.x = pk2(x[2].x * rr * n2.x * bflo(g1.x), x[2].y * rr * n2.y * bfhi(g1.x)); o1.y = pk2(x[2].z * rr * n2.z * bflo(g1.y), x[2].w * rr * n2.w * bfhi(g1.y));
;                 o1.z = pk2(x[3].x * rr * n3.x * bflo(g1.z), x[3].y * rr * n3.y * bfhi(g1.z)); o1.w = pk2(x[3].z * rr * n3.z * bflo(g1.w), x[3].w * rr * n3.w * bfhi(g1.w));
;                 *(u32x4v*)(p.CAT + row * 1024 + c0) = o0; *(u32x4v*)(p.CAT + row * 1024 + c0 + 8) = o1; }
	ds_read_b128 v[68:71], v174
	ds_read_b128 v[48:51], v174 offset:16
	ds_read_b128 v[44:47], v174 offset:32
	ds_read_b128 v[40:43], v174 offset:48
	s_waitcnt lgkmcnt(3)
	v_mul_f32_e32 v72, v69, v69
	v_mul_f32_e32 v73, v71, v71
	v_fmac_f32_e32 v72, v68, v68
	v_fmac_f32_e32 v73, v70, v70
	v_add_f32_e32 v72, v72, v73
	s_waitcnt lgkmcnt(2)
	v_mul_f32_e32 v73, v49, v49
	v_mul_f32_e32 v74, v51, v51
	v_fmac_f32_e32 v73, v48, v48
	v_fmac_f32_e32 v74, v50, v50
	v_add_f32_e32 v73, v73, v74
	v_add_f32_e32 v72, v72, v73
	s_waitcnt lgkmcnt(1)
	v_mul_f32_e32 v73, v45, v45
	v_mul_f32_e32 v74, v47, v47
	v_fmac_f32_e32 v73, v44, v44
	v_fmac_f32_e32 v74, v46, v46
	v_add_f32_e32 v73, v73, v74
	v_add_f32_e32 v72, v72, v73
	s_waitcnt lgkmcnt(0)
	v_mul_f32_e32 v73, v41, v41
	v_mul_f32_e32 v74, v43, v43
	v_fmac_f32_e32 v73, v40, v40
	v_fmac_f32_e32 v74, v42, v42
	v_add_f32_e32 v73, v73, v74
	v_and_b32_e32 v74, 64, v200
	v_add_f32_e32 v72, v72, v73
	v_xor_b32_e32 v73, 1, v200
	v_add_u32_e32 v74, 64, v74
	v_cmp_lt_i32_e32 vcc, v73, v74
	s_nop 1
	v_cndmask_b32_e32 v73, v200, v73, vcc
	v_lshlrev_b32_e32 v73, 2, v73
	ds_bpermute_b32 v73, v73, v72
	s_waitcnt lgkmcnt(0)
	v_add_f32_e32 v72, v72, v73
	v_xor_b32_e32 v73, 2, v200
	v_cmp_lt_i32_e32 vcc, v73, v74
	s_nop 1
	v_cndmask_b32_e32 v73, v200, v73, vcc
	v_lshlrev_b32_e32 v73, 2, v73
	ds_bpermute_b32 v73, v73, v72
	s_waitcnt lgkmcnt(0)
	v_add_f32_e32 v72, v72, v73
	v_xor_b32_e32 v73, 4, v200
	v_cmp_lt_i32_e32 vcc, v73, v74
	s_nop 1
	v_cndmask_b32_e32 v73, v200, v73, vcc
	v_lshlrev_b32_e32 v73, 2, v73
	ds_bpermute_b32 v73, v73, v72
	s_and_saveexec_b64 s[40:41], s[22:23]
	s_cbranch_execz .LBB0_1009
	s_waitcnt lgkmcnt(0)
	v_add_f32_e32 v72, v72, v73
	v_fmamk_f32 v72, v72, 0x3c000000, v201
	s_mov_b32 s11, 0x800000
	v_cmp_gt_f32_e32 vcc, s11, v72
	v_mul_f32_e32 v73, 0x4b800000, v72
	v_readlane_b32 s68, v255, 8
	v_cndmask_b32_e32 v72, v72, v73, vcc
	v_rsq_f32_e32 v72, v72
	v_readlane_b32 s78, v255, 18
	v_readlane_b32 s79, v255, 19
	v_readlane_b32 s69, v255, 9
	v_mul_f32_e32 v73, 0x45800000, v72
	v_cndmask_b32_e32 v74, v72, v73, vcc
	v_mul_f32_e32 v68, v68, v74
	s_waitcnt vmcnt(0)
	v_mul_f32_e32 v52, v52, v68
	v_lshlrev_b32_e32 v68, 16, v36
	v_mul_f32_e32 v52, v52, v68
	v_mul_f32_e32 v68, v69, v74
	v_mul_f32_e32 v53, v53, v68
	v_and_b32_e32 v36, 0xffff0000, v36
	v_mul_f32_e32 v36, v53, v36
	v_cvt_pk_bf16_f32 v36, v52, v36
	v_mul_f32_e32 v52, v70, v74
	v_mul_f32_e32 v52, v54, v52
	v_lshlrev_b32_e32 v53, 16, v37
	v_mul_f32_e32 v52, v52, v53
	v_mul_f32_e32 v53, v71, v74
	v_mul_f32_e32 v53, v55, v53
	v_and_b32_e32 v37, 0xffff0000, v37
	v_mul_f32_e32 v37, v53, v37
	v_mul_f32_e32 v48, v48, v74
	v_mul_f32_e32 v49, v49, v74
	v_cvt_pk_bf16_f32 v37, v52, v37
	v_mul_f32_e32 v48, v64, v48
	v_lshlrev_b32_e32 v52, 16, v38
	v_mul_f32_e32 v49, v65, v49
	v_and_b32_e32 v38, 0xffff0000, v38
	v_mul_f32_e32 v48, v48, v52
	v_mul_f32_e32 v38, v49, v38
	v_cvt_pk_bf16_f32 v38, v48, v38
	v_mul_f32_e32 v48, v50, v74
	v_mul_f32_e32 v48, v66, v48
	v_lshlrev_b32_e32 v49, 16, v39
	v_mul_f32_e32 v48, v48, v49
	v_mul_f32_e32 v49, v51, v74
	v_mul_f32_e32 v49, v67, v49
	v_and_b32_e32 v39, 0xffff0000, v39
	v_mul_f32_e32 v39, v49, v39
	v_mul_f32_e32 v44, v44, v74
	v_mul_f32_e32 v45, v45, v74
	v_cvt_pk_bf16_f32 v39, v48, v39
	v_mul_f32_e32 v44, v60, v44
	v_lshlrev_b32_e32 v48, 16, v32
	v_mul_f32_e32 v45, v61, v45
	v_and_b32_e32 v32, 0xffff0000, v32
	v_mul_f32_e32 v44, v44, v48
	v_mul_f32_e32 v32, v45, v32
	v_cvt_pk_bf16_f32 v32, v44, v32
	v_mul_f32_e32 v44, v46, v74
	v_mul_f32_e32 v44, v62, v44
	v_lshlrev_b32_e32 v45, 16, v33
	v_mul_f32_e32 v44, v44, v45
	v_mul_f32_e32 v45, v47, v74
	v_mul_f32_e32 v45, v63, v45
	v_and_b32_e32 v33, 0xffff0000, v33
	v_mul_f32_e32 v33, v45, v33
	v_mul_f32_e32 v40, v40, v74
	v_mul_f32_e32 v41, v41, v74
	v_cvt_pk_bf16_f32 v33, v44, v33
	v_mul_f32_e32 v40, v56, v40
	v_lshlrev_b32_e32 v44, 16, v34
	v_mul_f32_e32 v41, v57, v41
	v_and_b32_e32 v34, 0xffff0000, v34
	v_mul_f32_e32 v40, v40, v44
	v_mul_f32_e32 v34, v41, v34
	v_cvt_pk_bf16_f32 v34, v40, v34
	v_mul_f32_e32 v40, v42, v74
	v_mul_f32_e32 v40, v58, v40
	v_lshlrev_b32_e32 v41, 16, v35
	v_mul_f32_e32 v40, v40, v41
	v_mul_f32_e32 v41, v43, v74
	v_add_u32_e32 v72, s34, v114
	v_mul_f32_e32 v41, v59, v41
	v_and_b32_e32 v35, 0xffff0000, v35
	v_ashrrev_i32_e32 v73, 31, v72
	v_mul_f32_e32 v35, v41, v35
	v_cvt_pk_bf16_f32 v35, v40, v35
	v_lshlrev_b64 v[40:41], 11, v[72:73]
	v_lshl_add_u64 v[40:41], s[78:79], 0, v[40:41]
	v_lshl_add_u64 v[40:41], v[40:41], 0, v[106:107]
	v_readlane_b32 s70, v255, 10
	v_readlane_b32 s71, v255, 11
	v_readlane_b32 s72, v255, 12
	v_readlane_b32 s73, v255, 13
	v_readlane_b32 s74, v255, 14
	v_readlane_b32 s75, v255, 15
	v_readlane_b32 s76, v255, 16
	v_readlane_b32 s77, v255, 17
	v_readlane_b32 s80, v255, 20
	v_readlane_b32 s81, v255, 21
	v_readlane_b32 s82, v255, 22
	v_readlane_b32 s83, v255, 23
	global_store_dwordx4 v[40:41], v[36:39], off nt
	global_store_dwordx4 v[40:41], v[32:35], off offset:16 nt
	s_branch .LBB0_1009

; #define PG8_STAGE(bufoff, gbase, voff) do { _Pragma("unroll") for (int _i = 0; _i < 2; ++_i) \
;         __builtin_amdgcn_global_load_lds((const unsigned*)((const char*)(gbase) + (voff)[_i]), (PG8_LAS unsigned*)(lds + (bufoff) + ldsw + _i * 8192), 16, 0, 0); } while (0)
; #define PG8_LDA(dst, b, h) do { _Pragma("unroll") for (int m = 0; m < 4; ++m) _Pragma("unroll") for (int k = 0; k < 2; ++k) dst[m][k] = *(const PG8_LAS bf16x8*)(lds + PG8_SA(b, h) + aoff + m * 2048 + k * 1024); } while (0)
; #define PG8_LDB(dst, b, h) do { _Pragma("unroll") for (int n = 0; n < 2; ++n) _Pragma("unroll") for (int k = 0; k < 2; ++k) dst[n][k] = *(const PG8_LAS bf16x8*)(lds + PG8_SB(b, h) + boff + n * 2048 + k * 1024); } while (0)
; #define PG8_MMA(ai, bj, At, Bt) do { __builtin_amdgcn_s_setprio(1); _Pragma("unroll") for (int m = 0; m < 4; ++m) _Pragma("unroll") for (int n = 0; n < 2; ++n) _Pragma("unroll") for (int k = 0; k < 2; ++k) \
;         acc[ai][bj][m][n] = __builtin_amdgcn_mfma_f32_16x16x32_bf16(Bt[n][k], At[m][k], acc[ai][bj][m][n], 0, 0, 0); __builtin_amdgcn_s_setprio(0); } while (0)
; #define PG8_WAIT_L(n) asm volatile("s_waitcnt lgkmcnt(" #n ")" ::: "memory")
; #define PG8_BAR __builtin_amdgcn_s_barrier()
; #define PG8_SCHED __builtin_amdgcn_sched_barrier(0)
; template <class Epi, class Sched>
; __device__ __forceinline__ void gemm_phase(PG8_LAS unsigned char* lds, const Gemm g, const Sched& S, const Epi& E) {
;     ...
;             PG8_LDB(B0, 0, 0); PG8_SCHED; PG8_LDA(At, 0, 0); PG8_STAGE(PG8_SA(1, 1), a1 + hstep, voffA);
;             PG8_WAIT_L(8); PG8_BAR; PG8_WAIT_L(0); PG8_MMA(0, 0, At, B0); PG8_BAR; PG8_SCHED;
;             PG8_LDB(B1, 0, 1); PG8_STAGE(PG8_SB(0, 0), b2, voffB);
;             PG8_BAR; PG8_WAIT_L(0); PG8_MMA(0, 1, At, B1); PG8_BAR;
;             PG8_LDA(At, 0, 1); PG8_STAGE(PG8_SA(0, 0), a2, voffA);
;             PG8_BAR; PG8_WAIT_L(0); PG8_MMA(1, 0, At, B0); PG8_BAR; PG8_SCHED;
.LBB0_1191:
	ds_read_b128 v[128:131], v163
	ds_read_b128 v[132:135], v163 offset:1024
	ds_read_b128 v[136:139], v163 offset:2048
	ds_read_b128 v[168:171], v163 offset:3072
	s_add_u32 s16, s14, 0xfffe0080
	s_addc_u32 s17, s15, -1
	s_cmp_eq_u32 s41, 4
	s_cselect_b32 s19, s7, s17
	s_cselect_b32 s18, s37, s16
	s_cselect_b32 s17, s5, s40
	s_cselect_b32 s16, s38, s39
	v_lshl_add_u64 v[206:207], s[14:15], 0, v[148:149]
	s_add_i32 m0, s13, 0xc000
	ds_read_b128 v[172:175], v176
	ds_read_b128 v[178:181], v176 offset:1024
	ds_read_b128 v[182:185], v176 offset:2048
	ds_read_b128 v[186:189], v176 offset:3072
	ds_read_b128 v[190:193], v176 offset:4096
	ds_read_b128 v[194:197], v176 offset:5120
	ds_read_b128 v[198:201], v176 offset:6144
	ds_read_b128 v[202:205], v176 offset:7168
	global_load_lds_dwordx4 v[206:207], off
	s_add_i32 m0, s13, 0xe000
	v_lshl_add_u64 v[206:207], s[14:15], 0, v[150:151]
	global_load_lds_dwordx4 v[206:207], off
	s_waitcnt lgkmcnt(8)
	s_barrier
	s_waitcnt lgkmcnt(0)
	s_setprio 1
	v_mfma_f32_16x16x32_bf16 v[124:127], v[128:131], v[172:175], v[124:127]
	v_mfma_f32_16x16x32_bf16 v[120:123], v[136:139], v[172:175], v[120:123]
	v_mfma_f32_16x16x32_bf16 v[108:111], v[128:131], v[182:185], v[108:111]
	v_mfma_f32_16x16x32_bf16 v[104:107], v[136:139], v[182:185], v[104:107]
	v_mfma_f32_16x16x32_bf16 v[92:95], v[128:131], v[190:193], v[92:95]
	v_mfma_f32_16x16x32_bf16 v[88:91], v[136:139], v[190:193], v[88:91]
	v_mfma_f32_16x16x32_bf16 v[76:79], v[128:131], v[198:201], v[76:79]
	v_mfma_f32_16x16x32_bf16 v[72:75], v[136:139], v[198:201], v[72:75]
	v_mfma_f32_16x16x32_bf16 v[124:127], v[132:135], v[178:181], v[124:127]
	v_mfma_f32_16x16x32_bf16 v[120:123], v[168:171], v[178:181], v[120:123]
	v_mfma_f32_16x16x32_bf16 v[108:111], v[132:135], v[186:189], v[108:111]
	v_mfma_f32_16x16x32_bf16 v[104:107], v[168:171], v[186:189], v[104:107]
	v_mfma_f32_16x16x32_bf16 v[92:95], v[132:135], v[194:197], v[92:95]
	v_mfma_f32_16x16x32_bf16 v[88:91], v[168:171], v[194:197], v[88:91]
	v_mfma_f32_16x16x32_bf16 v[76:79], v[132:135], v[202:205], v[76:79]
	v_mfma_f32_16x16x32_bf16 v[72:75], v[168:171], v[202:205], v[72:75]
	s_setprio 0
	s_barrier
	s_add_i32 s30, s34, s22
	v_lshl_add_u64 v[222:223], s[16:17], 0, v[142:143]
	s_mov_b32 m0, s30
	ds_read_b128 v[206:209], v177
	ds_read_b128 v[210:213], v177 offset:1024
	ds_read_b128 v[214:217], v177 offset:2048
	ds_read_b128 v[218:221], v177 offset:3072
	global_load_lds_dwordx4 v[222:223], off
	s_add_i32 m0, s30, 0x2000
	v_lshl_add_u64 v[224:225], s[16:17], 0, v[146:147]
	global_load_lds_dwordx4 v[224:225], off
	s_barrier
	s_waitcnt lgkmcnt(0)
	s_setprio 1
	v_mfma_f32_16x16x32_bf16 v[116:119], v[206:209], v[172:175], v[116:119]
	v_mfma_f32_16x16x32_bf16 v[112:115], v[214:217], v[172:175], v[112:115]
	v_mfma_f32_16x16x32_bf16 v[100:103], v[206:209], v[182:185], v[100:103]
	v_mfma_f32_16x16x32_bf16 v[96:99], v[214:217], v[182:185], v[96:99]
	v_mfma_f32_16x16x32_bf16 v[84:87], v[206:209], v[190:193], v[84:87]
	v_mfma_f32_16x16x32_bf16 v[80:83], v[214:217], v[190:193], v[80:83]
	v_mfma_f32_16x16x32_bf16 v[68:71], v[206:209], v[198:201], v[68:71]
	v_mfma_f32_16x16x32_bf16 v[64:67], v[214:217], v[198:201], v[64:67]
	v_mfma_f32_16x16x32_bf16 v[116:119], v[210:213], v[178:181], v[116:119]
	v_mfma_f32_16x16x32_bf16 v[112:115], v[218:221], v[178:181], v[112:115]
	v_mfma_f32_16x16x32_bf16 v[100:103], v[210:213], v[186:189], v[100:103]
	v_mfma_f32_16x16x32_bf16 v[96:99], v[218:221], v[186:189], v[96:99]
	v_mfma_f32_16x16x32_bf16 v[84:87], v[210:213], v[194:197], v[84:87]
	v_mfma_f32_16x16x32_bf16 v[80:83], v[218:221], v[194:197], v[80:83]
	v_mfma_f32_16x16x32_bf16 v[68:71], v[210:213], v[202:205], v[68:71]
	v_mfma_f32_16x16x32_bf16 v[64:67], v[218:221], v[202:205], v[64:67]
	s_setprio 0
	s_mov_b32 m0, s13
	v_lshl_add_u64 v[226:227], s[18:19], 0, v[140:141]
	s_barrier
	ds_read_b128 v[172:175], v176 offset:16384
	ds_read_b128 v[178:181], v176 offset:17408
	ds_read_b128 v[182:185], v176 offset:18432
	ds_read_b128 v[186:189], v176 offset:19456
	ds_read_b128 v[190:193], v176 offset:20480
	ds_read_b128 v[194:197], v176 offset:21504
	ds_read_b128 v[198:201], v176 offset:22528
	ds_read_b128 v[202:205], v176 offset:23552
	global_load_lds_dwordx4 v[226:227], off
	s_mov_b32 m0, s23
	v_lshl_add_u64 v[228:229], s[18:19], 0, v[144:145]
	global_load_lds_dwordx4 v[228:229], off
	s_barrier
	s_waitcnt lgkmcnt(0)
	s_setprio 1
	v_mfma_f32_16x16x32_bf16 v[60:63], v[128:131], v[172:175], v[60:63]
	v_mfma_f32_16x16x32_bf16 v[56:59], v[136:139], v[172:175], v[56:59]
	v_mfma_f32_16x16x32_bf16 v[44:47], v[128:131], v[182:185], v[44:47]
	v_mfma_f32_16x16x32_bf16 v[40:43], v[136:139], v[182:185], v[40:43]
	v_mfma_f32_16x16x32_bf16 v[28:31], v[128:131], v[190:193], v[28:31]
	v_mfma_f32_16x16x32_bf16 v[24:27], v[136:139], v[190:193], v[24:27]
	v_mfma_f32_16x16x32_bf16 v[12:15], v[128:131], v[198:201], v[12:15]
	v_mfma_f32_16x16x32_bf16 v[8:11], v[136:139], v[198:201], v[8:11]
	v_mfma_f32_16x16x32_bf16 v[60:63], v[132:135], v[178:181], v[60:63]
	v_mfma_f32_16x16x32_bf16 v[56:59], v[168:171], v[178:181], v[56:59]
	v_mfma_f32_16x16x32_bf16 v[44:47], v[132:135], v[186:189], v[44:47]
	v_mfma_f32_16x16x32_bf16 v[40:43], v[168:171], v[186:189], v[40:43]
	v_mfma_f32_16x16x32_bf16 v[28:31], v[132:135], v[194:197], v[28:31]
	v_mfma_f32_16x16x32_bf16 v[24:27], v[168:171], v[194:197], v[24:27]
	v_mfma_f32_16x16x32_bf16 v[12:15], v[132:135], v[202:205], v[12:15]
	v_mfma_f32_16x16x32_bf16 v[8:11], v[168:171], v[202:205], v[8:11]
	s_setprio 0
	s_barrier
; #define PG8_STAGE(bufoff, gbase, voff) do { _Pragma("unroll") for (int _i = 0; _i < 2; ++_i) \
;         __builtin_amdgcn_global_load_lds((const unsigned*)((const char*)(gbase) + (voff)[_i]), (PG8_LAS unsigned*)(lds + (bufoff) + ldsw + _i * 8192), 16, 0, 0); } while (0)
; #define PG8_LDA(dst, b, h) do { _Pragma("unroll") for (int m = 0; m < 4; ++m) _Pragma("unroll") for (int k = 0; k < 2; ++k) dst[m][k] = *(const PG8_LAS bf16x8*)(lds + PG8_SA(b, h) + aoff + m * 2048 + k * 1024); } while (0)
; #define PG8_LDB(dst, b, h) do { _Pragma("unroll") for (int n = 0; n < 2; ++n) _Pragma("unroll") for (int k = 0; k < 2; ++k) dst[n][k] = *(const PG8_LAS bf16x8*)(lds + PG8_SB(b, h) + boff + n * 2048 + k * 1024); } while (0)
; #define PG8_MMA(ai, bj, At, Bt) do { __builtin_amdgcn_s_setprio(1); _Pragma("unroll") for (int m = 0; m < 4; ++m) _Pragma("unroll") for (int n = 0; n < 2; ++n) _Pragma("unroll") for (int k = 0; k < 2; ++k) \
;         acc[ai][bj][m][n] = __builtin_amdgcn_mfma_f32_16x16x32_bf16(Bt[n][k], At[m][k], acc[ai][bj][m][n], 0, 0, 0); __builtin_amdgcn_s_setprio(0); } while (0)
; #define PG8_WAIT_V(n) asm volatile("s_waitcnt vmcnt(" #n ")" ::: "memory")
; #define PG8_WAIT_L(n) asm volatile("s_waitcnt lgkmcnt(" #n ")" ::: "memory")
; #define PG8_BAR __builtin_amdgcn_s_barrier()
; #define PG8_SCHED __builtin_amdgcn_sched_barrier(0)
; template <class Epi, class Sched>
; __device__ __forceinline__ void gemm_phase(PG8_LAS unsigned char* lds, const Gemm g, const Sched& S, const Epi& E) {
;     ...
;             PG8_STAGE(PG8_SB(0, 1), b2 + hstep, voffB);
;             PG8_WAIT_V(6); PG8_BAR; PG8_MMA(1, 1, At, B1); PG8_BAR;
;             PG8_LDB(B0, 1, 0); PG8_SCHED; PG8_LDA(At, 1, 0); PG8_STAGE(PG8_SA(0, 1), a2 + hstep, voffA);
;             PG8_WAIT_L(8); PG8_BAR; PG8_WAIT_L(0); PG8_MMA(0, 0, At, B0); PG8_BAR; PG8_SCHED;
;             PG8_LDB(B1, 1, 1); PG8_STAGE(PG8_SB(1, 0), b3, voffB);
;             PG8_BAR; PG8_WAIT_L(0); PG8_MMA(0, 1, At, B1); PG8_BAR;
;             PG8_LDA(At, 1, 1); PG8_STAGE(PG8_SA(1, 0), a3, voffA);
;             PG8_BAR; PG8_WAIT_L(0); PG8_MMA(1, 0, At, B0); PG8_BAR; PG8_SCHED;
	s_add_u32 s42, s16, 0x20000
	s_addc_u32 s43, s17, 0
	s_add_i32 s30, s35, s22
	s_mov_b32 m0, s30
	v_lshl_add_u64 v[128:129], s[42:43], 0, v[142:143]
	global_load_lds_dwordx4 v[128:129], off
	s_add_i32 m0, s30, 0x2000
	v_lshl_add_u64 v[128:129], s[42:43], 0, v[146:147]
	global_load_lds_dwordx4 v[128:129], off
	s_waitcnt vmcnt(6)
	s_barrier
	s_setprio 1
	v_mfma_f32_16x16x32_bf16 v[52:55], v[206:209], v[172:175], v[52:55]
	v_mfma_f32_16x16x32_bf16 v[48:51], v[214:217], v[172:175], v[48:51]
	v_mfma_f32_16x16x32_bf16 v[36:39], v[206:209], v[182:185], v[36:39]
	v_mfma_f32_16x16x32_bf16 v[32:35], v[214:217], v[182:185], v[32:35]
	v_mfma_f32_16x16x32_bf16 v[20:23], v[206:209], v[190:193], v[20:23]
	v_mfma_f32_16x16x32_bf16 v[16:19], v[214:217], v[190:193], v[16:19]
	v_mfma_f32_16x16x32_bf16 v[4:7], v[206:209], v[198:201], v[4:7]
	v_mfma_f32_16x16x32_bf16 v[0:3], v[214:217], v[198:201], v[0:3]
	v_mfma_f32_16x16x32_bf16 v[52:55], v[210:213], v[178:181], v[52:55]
	v_mfma_f32_16x16x32_bf16 v[48:51], v[218:221], v[178:181], v[48:51]
	v_mfma_f32_16x16x32_bf16 v[36:39], v[210:213], v[186:189], v[36:39]
	v_mfma_f32_16x16x32_bf16 v[32:35], v[218:221], v[186:189], v[32:35]
	v_mfma_f32_16x16x32_bf16 v[20:23], v[210:213], v[194:197], v[20:23]
	v_mfma_f32_16x16x32_bf16 v[16:19], v[218:221], v[194:197], v[16:19]
	v_mfma_f32_16x16x32_bf16 v[4:7], v[210:213], v[202:205], v[4:7]
	v_mfma_f32_16x16x32_bf16 v[0:3], v[218:221], v[202:205], v[0:3]
	s_setprio 0
	s_add_i32 s30, 0, 0x18000
	v_add_u32_e32 v168, s30, v159
	s_barrier
	ds_read_b128 v[128:131], v168
	ds_read_b128 v[132:135], v168 offset:1024
	ds_read_b128 v[136:139], v168 offset:2048
	ds_read_b128 v[168:171], v168 offset:3072
	s_add_u32 s18, s18, 0x20000
	s_addc_u32 s19, s19, 0
	s_mov_b32 m0, s24
	v_lshl_add_u64 v[206:207], s[18:19], 0, v[140:141]
	ds_read_b128 v[172:175], v176 offset:32768
	ds_read_b128 v[178:181], v176 offset:33792
	ds_read_b128 v[182:185], v176 offset:34816
	ds_read_b128 v[186:189], v176 offset:35840
	ds_read_b128 v[190:193], v176 offset:36864
	ds_read_b128 v[194:197], v176 offset:37888
	ds_read_b128 v[198:201], v176 offset:38912
	ds_read_b128 v[202:205], v176 offset:39936
	global_load_lds_dwordx4 v[206:207], off
	s_mov_b32 m0, s25
	v_lshl_add_u64 v[206:207], s[18:19], 0, v[144:145]
	global_load_lds_dwordx4 v[206:207], off
	s_waitcnt lgkmcnt(8)
	s_barrier
	s_waitcnt lgkmcnt(0)
	s_setprio 1
	v_mfma_f32_16x16x32_bf16 v[124:127], v[128:131], v[172:175], v[124:127]
	v_mfma_f32_16x16x32_bf16 v[120:123], v[136:139], v[172:175], v[120:123]
	v_mfma_f32_16x16x32_bf16 v[108:111], v[128:131], v[182:185], v[108:111]
	v_mfma_f32_16x16x32_bf16 v[104:107], v[136:139], v[182:185], v[104:107]
	v_mfma_f32_16x16x32_bf16 v[92:95], v[128:131], v[190:193], v[92:95]
	v_mfma_f32_16x16x32_bf16 v[88:91], v[136:139], v[190:193], v[88:91]
	v_mfma_f32_16x16x32_bf16 v[76:79], v[128:131], v[198:201], v[76:79]
	v_mfma_f32_16x16x32_bf16 v[72:75], v[136:139], v[198:201], v[72:75]
	v_mfma_f32_16x16x32_bf16 v[124:127], v[132:135], v[178:181], v[124:127]
	v_mfma_f32_16x16x32_bf16 v[120:123], v[168:171], v[178:181], v[120:123]
	v_mfma_f32_16x16x32_bf16 v[108:111], v[132:135], v[186:189], v[108:111]
	v_mfma_f32_16x16x32_bf16 v[104:107], v[168:171], v[186:189], v[104:107]
	v_mfma_f32_16x16x32_bf16 v[92:95], v[132:135], v[194:197], v[92:95]
	v_mfma_f32_16x16x32_bf16 v[88:91], v[168:171], v[194:197], v[88:91]
	v_mfma_f32_16x16x32_bf16 v[76:79], v[132:135], v[202:205], v[76:79]
	v_mfma_f32_16x16x32_bf16 v[72:75], v[168:171], v[202:205], v[72:75]
	s_setprio 0
	s_barrier
	s_add_i32 s18, 0, 0x1c000
	s_add_i32 s19, s30, s22
	v_add_u32_e32 v218, s18, v159
	v_lshl_add_u64 v[222:223], v[222:223], 0, s[2:3]
	s_mov_b32 m0, s19
	ds_read_b128 v[206:209], v218
	ds_read_b128 v[210:213], v218 offset:1024
	ds_read_b128 v[214:217], v218 offset:2048
	ds_read_b128 v[218:221], v218 offset:3072
	global_load_lds_dwordx4 v[222:223], off
	s_add_i32 m0, s19, 0x2000
	v_lshl_add_u64 v[222:223], v[224:225], 0, s[2:3]
	global_load_lds_dwordx4 v[222:223], off
	s_barrier
	s_waitcnt lgkmcnt(0)
	s_setprio 1
	v_mfma_f32_16x16x32_bf16 v[116:119], v[206:209], v[172:175], v[116:119]
	v_mfma_f32_16x16x32_bf16 v[112:115], v[214:217], v[172:175], v[112:115]
	v_mfma_f32_16x16x32_bf16 v[100:103], v[206:209], v[182:185], v[100:103]
	v_mfma_f32_16x16x32_bf16 v[96:99], v[214:217], v[182:185], v[96:99]
	v_mfma_f32_16x16x32_bf16 v[84:87], v[206:209], v[190:193], v[84:87]
	v_mfma_f32_16x16x32_bf16 v[80:83], v[214:217], v[190:193], v[80:83]
	v_mfma_f32_16x16x32_bf16 v[68:71], v[206:209], v[198:201], v[68:71]
	v_mfma_f32_16x16x32_bf16 v[64:67], v[214:217], v[198:201], v[64:67]
	v_mfma_f32_16x16x32_bf16 v[116:119], v[210:213], v[178:181], v[116:119]
	v_mfma_f32_16x16x32_bf16 v[112:115], v[218:221], v[178:181], v[112:115]
	v_mfma_f32_16x16x32_bf16 v[100:103], v[210:213], v[186:189], v[100:103]
	v_mfma_f32_16x16x32_bf16 v[96:99], v[218:221], v[186:189], v[96:99]
	v_mfma_f32_16x16x32_bf16 v[84:87], v[210:213], v[194:197], v[84:87]
	v_mfma_f32_16x16x32_bf16 v[80:83], v[218:221], v[194:197], v[80:83]
	v_mfma_f32_16x16x32_bf16 v[68:71], v[210:213], v[202:205], v[68:71]
	v_mfma_f32_16x16x32_bf16 v[64:67], v[218:221], v[202:205], v[64:67]
	s_setprio 0
	s_mov_b32 m0, s27
	v_lshl_add_u64 v[222:223], v[226:227], 0, s[2:3]
	s_barrier
	ds_read_b128 v[172:175], v176 offset:49152
	ds_read_b128 v[178:181], v176 offset:50176
	ds_read_b128 v[182:185], v176 offset:51200
	ds_read_b128 v[186:189], v176 offset:52224
	ds_read_b128 v[190:193], v176 offset:53248
	ds_read_b128 v[194:197], v176 offset:54272
	ds_read_b128 v[198:201], v176 offset:55296
	ds_read_b128 v[202:205], v176 offset:56320
	global_load_lds_dwordx4 v[222:223], off
	s_mov_b32 m0, s29
	v_lshl_add_u64 v[222:223], v[228:229], 0, s[2:3]
	global_load_lds_dwordx4 v[222:223], off
	s_barrier
; #define PG8_STAGE(bufoff, gbase, voff) do { _Pragma("unroll") for (int _i = 0; _i < 2; ++_i) \
;         __builtin_amdgcn_global_load_lds((const unsigned*)((const char*)(gbase) + (voff)[_i]), (PG8_LAS unsigned*)(lds + (bufoff) + ldsw + _i * 8192), 16, 0, 0); } while (0)
; #define PG8_LDA(dst, b, h) do { _Pragma("unroll") for (int m = 0; m < 4; ++m) _Pragma("unroll") for (int k = 0; k < 2; ++k) dst[m][k] = *(const PG8_LAS bf16x8*)(lds + PG8_SA(b, h) + aoff + m * 2048 + k * 1024); } while (0)
; #define PG8_MMA(ai, bj, At, Bt) do { __builtin_amdgcn_s_setprio(1); _Pragma("unroll") for (int m = 0; m < 4; ++m) _Pragma("unroll") for (int n = 0; n < 2; ++n) _Pragma("unroll") for (int k = 0; k < 2; ++k) \
;         acc[ai][bj][m][n] = __builtin_amdgcn_mfma_f32_16x16x32_bf16(Bt[n][k], At[m][k], acc[ai][bj][m][n], 0, 0, 0); __builtin_amdgcn_s_setprio(0); } while (0)
; #define PG8_WAIT_V(n) asm volatile("s_waitcnt vmcnt(" #n ")" ::: "memory")
; #define PG8_WAIT_L(n) asm volatile("s_waitcnt lgkmcnt(" #n ")" ::: "memory")
; template <class Epi, class Sched>
; __device__ __forceinline__ void gemm_phase(PG8_LAS unsigned char* lds, const Gemm g, const Sched& S, const Epi& E) {
;     ...
;             PG8_BAR; PG8_WAIT_L(0); PG8_MMA(0, 1, At, B1); PG8_BAR;
;             PG8_LDA(At, 1, 1); PG8_STAGE(PG8_SA(1, 0), a3, voffA);
;             PG8_BAR; PG8_WAIT_L(0); PG8_MMA(1, 0, At, B0); PG8_BAR; PG8_SCHED;
;             PG8_STAGE(PG8_SB(1, 1), b3 + hstep, voffB);
;             PG8_WAIT_V(6); PG8_BAR; PG8_MMA(1, 1, At, B1); PG8_BAR;
;         }
;     DI void operator()(const f32x4 (&acc)[2][2][4][2], const Unit& u, int wr, int wc, int fr, int fq, const Pre& pre) const {
;     ...
;                 for (int bj = 0; bj < 2; ++bj) y[m][bj] = *(const u32x4v*)(YG + (size_t)(row0 + ai * 128 + m * 16) * 512 + cb + bj * 128);
; #pragma unroll
;             for (int m = 0; m < 4; ++m) { const int row = row0 + ai * 128 + m * 16;
; #pragma unroll
;                 for (int bj = 0; bj < 2; ++bj) { const f32x4 v0 = acc[ai][bj][m][0], v1 = acc[ai][bj][m][1]; const u32x4v yy = y[m][bj]; u32x4v o;
;                     o.x = pk2(bflo(yy.x) * sigm(v0[0]), bfhi(yy.x) * sigm(v0[1])); o.y = pk2(bflo(yy.y) * sigm(v0[2]), bfhi(yy.y) * sigm(v0[3]));
;                     o.z = pk2(bflo(yy.z) * sigm(v1[0]), bfhi(yy.z) * sigm(v1[1])); o.w = pk2(bflo(yy.w) * sigm(v1[2]), bfhi(yy.w) * sigm(v1[3]));
	s_waitcnt lgkmcnt(0)
	s_setprio 1
	v_mfma_f32_16x16x32_bf16 v[60:63], v[128:131], v[172:175], v[60:63]
	v_mfma_f32_16x16x32_bf16 v[56:59], v[136:139], v[172:175], v[56:59]
	v_mfma_f32_16x16x32_bf16 v[44:47], v[128:131], v[182:185], v[44:47]
	v_mfma_f32_16x16x32_bf16 v[40:43], v[136:139], v[182:185], v[40:43]
	v_mfma_f32_16x16x32_bf16 v[28:31], v[128:131], v[190:193], v[28:31]
	v_mfma_f32_16x16x32_bf16 v[24:27], v[136:139], v[190:193], v[24:27]
	v_mfma_f32_16x16x32_bf16 v[12:15], v[128:131], v[198:201], v[12:15]
	v_mfma_f32_16x16x32_bf16 v[8:11], v[136:139], v[198:201], v[8:11]
	v_mfma_f32_16x16x32_bf16 v[60:63], v[132:135], v[178:181], v[60:63]
	v_mfma_f32_16x16x32_bf16 v[56:59], v[168:171], v[178:181], v[56:59]
	v_mfma_f32_16x16x32_bf16 v[44:47], v[132:135], v[186:189], v[44:47]
	v_mfma_f32_16x16x32_bf16 v[40:43], v[168:171], v[186:189], v[40:43]
	v_mfma_f32_16x16x32_bf16 v[28:31], v[132:135], v[194:197], v[28:31]
	v_mfma_f32_16x16x32_bf16 v[24:27], v[168:171], v[194:197], v[24:27]
	v_mfma_f32_16x16x32_bf16 v[12:15], v[132:135], v[202:205], v[12:15]
	v_mfma_f32_16x16x32_bf16 v[8:11], v[168:171], v[202:205], v[8:11]
	s_setprio 0
	s_barrier
	s_add_u32 s16, s16, 0x20080
	s_addc_u32 s17, s17, 0
	s_add_i32 s18, s18, s22
	s_mov_b32 m0, s18
	v_lshl_add_u64 v[128:129], s[16:17], 0, v[142:143]
	global_load_lds_dwordx4 v[128:129], off
	s_add_i32 m0, s18, 0x2000
	v_lshl_add_u64 v[128:129], s[16:17], 0, v[146:147]
	global_load_lds_dwordx4 v[128:129], off
	s_waitcnt vmcnt(6)
	s_barrier
	s_setprio 1
	v_mfma_f32_16x16x32_bf16 v[52:55], v[206:209], v[172:175], v[52:55]
	v_mfma_f32_16x16x32_bf16 v[48:51], v[214:217], v[172:175], v[48:51]
	v_mfma_f32_16x16x32_bf16 v[36:39], v[206:209], v[182:185], v[36:39]
	v_mfma_f32_16x16x32_bf16 v[32:35], v[214:217], v[182:185], v[32:35]
	v_mfma_f32_16x16x32_bf16 v[20:23], v[206:209], v[190:193], v[20:23]
	v_mfma_f32_16x16x32_bf16 v[16:19], v[214:217], v[190:193], v[16:19]
	v_mfma_f32_16x16x32_bf16 v[4:7], v[206:209], v[198:201], v[4:7]
	v_mfma_f32_16x16x32_bf16 v[0:3], v[214:217], v[198:201], v[0:3]
	v_mfma_f32_16x16x32_bf16 v[52:55], v[210:213], v[178:181], v[52:55]
	v_mfma_f32_16x16x32_bf16 v[48:51], v[218:221], v[178:181], v[48:51]
	v_mfma_f32_16x16x32_bf16 v[36:39], v[210:213], v[186:189], v[36:39]
	v_mfma_f32_16x16x32_bf16 v[32:35], v[218:221], v[186:189], v[32:35]
	v_mfma_f32_16x16x32_bf16 v[20:23], v[210:213], v[194:197], v[20:23]
	v_mfma_f32_16x16x32_bf16 v[16:19], v[218:221], v[194:197], v[16:19]
	v_mfma_f32_16x16x32_bf16 v[4:7], v[210:213], v[202:205], v[4:7]
	v_mfma_f32_16x16x32_bf16 v[0:3], v[218:221], v[202:205], v[0:3]
	s_setprio 0
	s_add_i32 s41, s41, 2
	s_add_u32 s14, s14, 0x100
	s_addc_u32 s15, s15, 0
	s_add_u32 s39, s39, 0x100
	s_addc_u32 s40, s40, 0
	s_cmp_lt_u32 s41, 6
	s_barrier
	s_cbranch_scc1 .LBB0_1191
	v_lshl_or_b32 v128, s36, 8, v161
	v_lshl_add_u32 v170, s12, 8, v157
	v_ashrrev_i32_e32 v129, 31, v128
	v_readlane_b32 s36, v255, 8
	v_lshlrev_b64 v[168:169], 1, v[128:129]
	v_readlane_b32 s44, v255, 16
	v_readlane_b32 s45, v255, 17
	v_ashrrev_i32_e32 v171, 31, v170
	v_lshlrev_b64 v[128:129], 10, v[170:171]
	v_lshl_add_u64 v[172:173], s[44:45], 0, v[168:169]
	v_lshl_add_u64 v[128:129], v[172:173], 0, v[128:129]
	global_load_dwordx4 v[178:181], v[128:129], off
	global_load_dwordx4 v[182:185], v[128:129], off offset:256
	v_or_b32_e32 v190, 16, v170
	v_or_b32_e32 v174, 32, v170
	v_mul_f32_e32 v124, 0xbfb8aa3b, v124
	v_mul_f32_e32 v125, 0xbfb8aa3b, v125
	v_mul_f32_e32 v120, 0xbfb8aa3b, v120
	v_mul_f32_e32 v121, 0xbfb8aa3b, v121
	v_mul_f32_e32 v122, 0xbfb8aa3b, v122
	v_mul_f32_e32 v123, 0xbfb8aa3b, v123
	v_mul_f32_e32 v128, 0xbfb8aa3b, v116
	v_mul_f32_e32 v117, 0xbfb8aa3b, v117
	v_or_b32_e32 v116, 48, v170
	v_ashrrev_i32_e32 v191, 31, v190
	v_ashrrev_i32_e32 v175, 31, v174
	v_readlane_b32 s46, v255, 18
	v_readlane_b32 s47, v255, 19
	v_mul_f32_e32 v126, 0xbfb8aa3b, v126
	v_mul_f32_e32 v127, 0xbfb8aa3b, v127
	v_exp_f32_e32 v196, v124
	v_exp_f32_e32 v197, v125
	v_exp_f32_e32 v200, v120
	v_exp_f32_e32 v201, v121
	v_exp_f32_e32 v202, v122
	v_exp_f32_e32 v203, v123
	v_exp_f32_e32 v205, v117
	v_ashrrev_i32_e32 v117, 31, v116
	v_lshlrev_b64 v[120:121], 11, v[170:171]
	v_lshlrev_b64 v[122:123], 10, v[190:191]
	v_lshlrev_b64 v[124:125], 10, v[174:175]
	v_exp_f32_e32 v198, v126
	v_exp_f32_e32 v199, v127
	v_lshlrev_b64 v[126:127], 10, v[116:117]
	v_lshl_add_u64 v[120:121], s[46:47], 0, v[120:121]
	v_lshl_add_u64 v[122:123], v[172:173], 0, v[122:123]
	v_lshl_add_u64 v[124:125], v[172:173], 0, v[124:125]
	v_exp_f32_e32 v204, v128
	v_lshl_add_u64 v[192:193], v[172:173], 0, v[126:127]
	v_lshl_add_u64 v[194:195], v[120:121], 0, v[168:169]
	global_load_dwordx4 v[186:189], v[122:123], off
	global_load_dwordx4 v[136:139], v[122:123], off offset:256
	global_load_dwordx4 v[132:135], v[124:125], off
	global_load_dwordx4 v[128:131], v[124:125], off offset:256
	s_nop 0
	global_load_dwordx4 v[124:127], v[192:193], off
	global_load_dwordx4 v[120:123], v[192:193], off offset:256
	v_add_f32_e32 v192, 1.0, v197
	v_add_f32_e32 v171, 1.0, v196
	v_add_f32_e32 v193, 1.0, v198
	v_add_f32_e32 v196, 1.0, v199
	v_add_f32_e32 v197, 1.0, v200
	v_add_f32_e32 v198, 1.0, v201
	v_add_f32_e32 v200, 1.0, v203
	v_rcp_f32_e32 v192, v192
	v_add_f32_e32 v199, 1.0, v202
	v_rcp_f32_e32 v171, v171
	v_rcp_f32_e32 v196, v196
	v_rcp_f32_e32 v198, v198
	v_rcp_f32_e32 v200, v200
	v_rcp_f32_e32 v193, v193
	v_rcp_f32_e32 v197, v197
	v_rcp_f32_e32 v199, v199
	v_mul_f32_e32 v118, 0xbfb8aa3b, v118
	v_add_f32_e32 v201, 1.0, v204
	v_exp_f32_e32 v118, v118
	v_mul_f32_e32 v119, 0xbfb8aa3b, v119
	v_exp_f32_e32 v119, v119
	v_mul_f32_e32 v112, 0xbfb8aa3b, v112
	v_exp_f32_e32 v112, v112
	v_mul_f32_e32 v113, 0xbfb8aa3b, v113
	v_exp_f32_e32 v113, v113
	v_add_f32_e32 v118, 1.0, v118
	v_rcp_f32_e32 v118, v118
	v_add_f32_e32 v119, 1.0, v119
	v_rcp_f32_e32 v119, v119
	v_add_f32_e32 v112, 1.0, v112
	v_rcp_f32_e32 v112, v112
	v_add_f32_e32 v113, 1.0, v113
	v_mul_f32_e32 v114, 0xbfb8aa3b, v114
	v_rcp_f32_e32 v113, v113
	v_exp_f32_e32 v114, v114
	v_mul_f32_e32 v115, 0xbfb8aa3b, v115
	v_exp_f32_e32 v115, v115
	v_mul_f32_e32 v108, 0xbfb8aa3b, v108
	v_exp_f32_e32 v108, v108
	v_mul_f32_e32 v109, 0xbfb8aa3b, v109
	s_waitcnt vmcnt(0)
; DI unsigned pk2(float lo, float hi) { unsigned r; asm volatile("v_cvt_pk_bf16_f32 %0, %1, %2" : "=v"(r) : "v"(lo), "v"(hi)); return r; }
; DI float bflo(unsigned u) { return __uint_as_float(u << 16); }
; DI float bfhi(unsigned u) { return __uint_as_float(u & 0xffff0000u); }
; DI float sigm(float x) { return __builtin_amdgcn_rcpf(1.f + __expf(-x)); }
;     DI void operator()(const f32x4 (&acc)[2][2][4][2], const Unit& u, int wr, int wc, int fr, int fq, const Pre& pre) const {
;     ...
;                 for (int bj = 0; bj < 2; ++bj) y[m][bj] = *(const u32x4v*)(YG + (size_t)(row0 + ai * 128 + m * 16) * 512 + cb + bj * 128);
; #pragma unroll
;             for (int m = 0; m < 4; ++m) { const int row = row0 + ai * 128 + m * 16;
; #pragma unroll
;                 for (int bj = 0; bj < 2; ++bj) { const f32x4 v0 = acc[ai][bj][m][0], v1 = acc[ai][bj][m][1]; const u32x4v yy = y[m][bj]; u32x4v o;
;                     o.x = pk2(bflo(yy.x) * sigm(v0[0]), bfhi(yy.x) * sigm(v0[1])); o.y = pk2(bflo(yy.y) * sigm(v0[2]), bfhi(yy.y) * sigm(v0[3]));
;                     o.z = pk2(bflo(yy.z) * sigm(v1[0]), bfhi(yy.z) * sigm(v1[1])); o.w = pk2(bflo(yy.w) * sigm(v1[2]), bfhi(yy.w) * sigm(v1[3]));
;                     *(u32x4v*)(CAT + (size_t)row * 1024 + 512 + cb + bj * 128) = o; } } }
	v_lshlrev_b32_e32 v202, 16, v178
	v_and_b32_e32 v178, 0xffff0000, v178
	v_lshlrev_b32_e32 v203, 16, v179
	v_and_b32_e32 v179, 0xffff0000, v179
	v_lshlrev_b32_e32 v204, 16, v180
	v_and_b32_e32 v180, 0xffff0000, v180
	v_lshlrev_b32_e32 v206, 16, v181
	v_and_b32_e32 v181, 0xffff0000, v181
	v_mul_f32_e32 v178, v192, v178
	v_mul_f32_e32 v171, v171, v202
	v_mul_f32_e32 v179, v196, v179
	v_mul_f32_e32 v180, v198, v180
	v_mul_f32_e32 v181, v200, v181
	v_cvt_pk_bf16_f32 v178, v171, v178
	v_mul_f32_e32 v192, v193, v203
	v_mul_f32_e32 v193, v197, v204
	v_mul_f32_e32 v196, v199, v206
	v_cvt_pk_bf16_f32 v179, v192, v179
	v_cvt_pk_bf16_f32 v180, v193, v180
	v_cvt_pk_bf16_f32 v181, v196, v181
	global_store_dwordx4 v[194:195], v[178:181], off offset:1024 nt
	v_rcp_f32_e32 v171, v201
	v_exp_f32_e32 v109, v109
	v_add_f32_e32 v178, 1.0, v205
	v_rcp_f32_e32 v178, v178
	v_lshlrev_b32_e32 v179, 16, v182
	v_mul_f32_e32 v171, v171, v179
	v_and_b32_e32 v179, 0xffff0000, v182
	v_mul_f32_e32 v178, v178, v179
	v_cvt_pk_bf16_f32 v178, v171, v178
	v_lshlrev_b32_e32 v171, 16, v183
	v_mul_f32_e32 v118, v118, v171
	v_and_b32_e32 v171, 0xffff0000, v183
	v_mul_f32_e32 v119, v119, v171
	v_cvt_pk_bf16_f32 v179, v118, v119
	v_lshlrev_b32_e32 v118, 16, v184
	v_mul_f32_e32 v112, v112, v118
	v_and_b32_e32 v118, 0xffff0000, v184
	v_mul_f32_e32 v113, v113, v118
	v_cvt_pk_bf16_f32 v180, v112, v113
	v_add_f32_e32 v112, 1.0, v114
	v_rcp_f32_e32 v112, v112
	v_add_f32_e32 v113, 1.0, v115
	v_rcp_f32_e32 v113, v113
	v_add_f32_e32 v108, 1.0, v108
	v_rcp_f32_e32 v108, v108
	v_add_f32_e32 v109, 1.0, v109
	v_lshlrev_b32_e32 v114, 16, v185
	v_rcp_f32_e32 v109, v109
	v_mul_f32_e32 v110, 0xbfb8aa3b, v110
	v_mul_f32_e32 v112, v112, v114
	v_and_b32_e32 v114, 0xffff0000, v185
	v_exp_f32_e32 v110, v110
	v_mul_f32_e32 v111, 0xbfb8aa3b, v111
	v_mul_f32_e32 v113, v113, v114
	v_lshlrev_b32_e32 v114, 16, v186
	v_exp_f32_e32 v111, v111
	v_mul_f32_e32 v108, v108, v114
	v_and_b32_e32 v114, 0xffff0000, v186
	v_mul_f32_e32 v104, 0xbfb8aa3b, v104
	v_mul_f32_e32 v109, v109, v114
	v_exp_f32_e32 v104, v104
	v_mul_f32_e32 v105, 0xbfb8aa3b, v105
	v_cvt_pk_bf16_f32 v181, v112, v113
	global_store_dwordx4 v[194:195], v[178:181], off offset:1280 nt
	v_cvt_pk_bf16_f32 v108, v108, v109
	v_add_f32_e32 v109, 1.0, v110
	v_exp_f32_e32 v105, v105
	v_rcp_f32_e32 v109, v109
	v_add_f32_e32 v110, 1.0, v111
	v_rcp_f32_e32 v110, v110
	v_add_f32_e32 v104, 1.0, v104
	v_lshlrev_b32_e32 v111, 16, v187
	v_rcp_f32_e32 v104, v104
	v_add_f32_e32 v105, 1.0, v105
	v_mul_f32_e32 v106, 0xbfb8aa3b, v106
	v_mul_f32_e32 v109, v109, v111
	v_and_b32_e32 v111, 0xffff0000, v187
	v_rcp_f32_e32 v105, v105
	v_exp_f32_e32 v106, v106
	v_mul_f32_e32 v107, 0xbfb8aa3b, v107
	v_mul_f32_e32 v110, v110, v111
	v_exp_f32_e32 v107, v107
	v_mul_f32_e32 v100, 0xbfb8aa3b, v100
	v_cvt_pk_bf16_f32 v109, v109, v110
	v_lshlrev_b32_e32 v110, 16, v188
	v_exp_f32_e32 v100, v100
	v_mul_f32_e32 v101, 0xbfb8aa3b, v101
	v_mul_f32_e32 v104, v104, v110
	v_and_b32_e32 v110, 0xffff0000, v188
	v_exp_f32_e32 v101, v101
	v_mul_f32_e32 v105, v105, v110
	v_cvt_pk_bf16_f32 v110, v104, v105
	v_add_f32_e32 v104, 1.0, v106
	v_rcp_f32_e32 v104, v104
	v_add_f32_e32 v105, 1.0, v107
	v_rcp_f32_e32 v105, v105
	v_add_f32_e32 v100, 1.0, v100
	v_rcp_f32_e32 v100, v100
	v_add_f32_e32 v101, 1.0, v101
	v_lshlrev_b32_e32 v106, 16, v189
	v_rcp_f32_e32 v101, v101
	v_mul_f32_e32 v102, 0xbfb8aa3b, v102
	v_mul_f32_e32 v104, v104, v106
	v_and_b32_e32 v106, 0xffff0000, v189
	v_exp_f32_e32 v102, v102
	v_mul_f32_e32 v103, 0xbfb8aa3b, v103
	v_lshlrev_b64 v[112:113], 11, v[190:191]
	v_mul_f32_e32 v105, v105, v106
	v_lshlrev_b32_e32 v106, 16, v136
	v_exp_f32_e32 v103, v103
	v_cvt_pk_bf16_f32 v111, v104, v105
	v_lshl_add_u64 v[104:105], s[46:47], 0, v[112:113]
	v_mul_f32_e32 v100, v100, v106
	v_and_b32_e32 v106, 0xffff0000, v136
	v_mul_f32_e32 v96, 0xbfb8aa3b, v96
	v_lshl_add_u64 v[104:105], v[104:105], 0, v[168:169]
	v_mul_f32_e32 v101, v101, v106
	v_exp_f32_e32 v96, v96
	v_mul_f32_e32 v97, 0xbfb8aa3b, v97
	global_store_dwordx4 v[104:105], v[108:111], off offset:1024 nt
	v_cvt_pk_bf16_f32 v100, v100, v101
	v_add_f32_e32 v101, 1.0, v102
	v_exp_f32_e32 v97, v97
	v_rcp_f32_e32 v101, v101
	v_add_f32_e32 v102, 1.0, v103
	v_rcp_f32_e32 v102, v102
	v_add_f32_e32 v96, 1.0, v96
	v_lshlrev_b32_e32 v103, 16, v137
	v_rcp_f32_e32 v96, v96
	v_add_f32_e32 v97, 1.0, v97
	v_mul_f32_e32 v98, 0xbfb8aa3b, v98
	v_mul_f32_e32 v101, v101, v103
	v_and_b32_e32 v103, 0xffff0000, v137
	v_rcp_f32_e32 v97, v97
	v_exp_f32_e32 v98, v98
	v_mul_f32_e32 v99, 0xbfb8aa3b, v99
	v_mul_f32_e32 v102, v102, v103
	v_exp_f32_e32 v99, v99
	v_mul_f32_e32 v92, 0xbfb8aa3b, v92
	v_cvt_pk_bf16_f32 v101, v101, v102
	v_lshlrev_b32_e32 v102, 16, v138
	v_exp_f32_e32 v92, v92
	v_mul_f32_e32 v93, 0xbfb8aa3b, v93
	v_mul_f32_e32 v96, v96, v102
	v_and_b32_e32 v102, 0xffff0000, v138
	v_exp_f32_e32 v93, v93
	v_mul_f32_e32 v97, v97, v102
	v_cvt_pk_bf16_f32 v102, v96, v97
	v_add_f32_e32 v96, 1.0, v98
	v_rcp_f32_e32 v96, v96
	v_add_f32_e32 v97, 1.0, v99
	v_rcp_f32_e32 v97, v97
	v_add_f32_e32 v92, 1.0, v92
	v_rcp_f32_e32 v92, v92
	v_add_f32_e32 v93, 1.0, v93
	v_lshlrev_b32_e32 v98, 16, v139
	v_rcp_f32_e32 v93, v93
	v_mul_f32_e32 v94, 0xbfb8aa3b, v94
	v_mul_f32_e32 v96, v96, v98
	v_and_b32_e32 v98, 0xffff0000, v139
	v_exp_f32_e32 v94, v94
	v_mul_f32_e32 v95, 0xbfb8aa3b, v95
	v_mul_f32_e32 v97, v97, v98
	v_lshlrev_b32_e32 v98, 16, v132
	v_exp_f32_e32 v95, v95
	v_mul_f32_e32 v92, v92, v98
	v_and_b32_e32 v98, 0xffff0000, v132
	v_mul_f32_e32 v88, 0xbfb8aa3b, v88
	v_mul_f32_e32 v93, v93, v98
	v_exp_f32_e32 v88, v88
	v_mul_f32_e32 v89, 0xbfb8aa3b, v89
	v_cvt_pk_bf16_f32 v103, v96, v97
; DI unsigned pk2(float lo, float hi) { unsigned r; asm volatile("v_cvt_pk_bf16_f32 %0, %1, %2" : "=v"(r) : "v"(lo), "v"(hi)); return r; }
; DI float bflo(unsigned u) { return __uint_as_float(u << 16); }
; DI float bfhi(unsigned u) { return __uint_as_float(u & 0xffff0000u); }
; DI float sigm(float x) { return __builtin_amdgcn_rcpf(1.f + __expf(-x)); }
;     DI void operator()(const f32x4 (&acc)[2][2][4][2], const Unit& u, int wr, int wc, int fr, int fq, const Pre& pre) const {
;     ...
;                 for (int bj = 0; bj < 2; ++bj) { const f32x4 v0 = acc[ai][bj][m][0], v1 = acc[ai][bj][m][1]; const u32x4v yy = y[m][bj]; u32x4v o;
;                     o.x = pk2(bflo(yy.x) * sigm(v0[0]), bfhi(yy.x) * sigm(v0[1])); o.y = pk2(bflo(yy.y) * sigm(v0[2]), bfhi(yy.y) * sigm(v0[3]));
;                     o.z = pk2(bflo(yy.z) * sigm(v1[0]), bfhi(yy.z) * sigm(v1[1])); o.w = pk2(bflo(yy.w) * sigm(v1[2]), bfhi(yy.w) * sigm(v1[3]));
;                     *(u32x4v*)(CAT + (size_t)row * 1024 + 512 + cb + bj * 128) = o; } } }
	global_store_dwordx4 v[104:105], v[100:103], off offset:1280 nt
	v_cvt_pk_bf16_f32 v92, v92, v93
	v_add_f32_e32 v93, 1.0, v94
	v_exp_f32_e32 v89, v89
	v_rcp_f32_e32 v93, v93
	v_add_f32_e32 v94, 1.0, v95
	v_rcp_f32_e32 v94, v94
	v_add_f32_e32 v88, 1.0, v88
	v_lshlrev_b32_e32 v95, 16, v133
	v_rcp_f32_e32 v88, v88
	v_add_f32_e32 v89, 1.0, v89
	v_mul_f32_e32 v90, 0xbfb8aa3b, v90
	v_mul_f32_e32 v93, v93, v95
	v_and_b32_e32 v95, 0xffff0000, v133
	v_rcp_f32_e32 v89, v89
	v_exp_f32_e32 v90, v90
	v_mul_f32_e32 v91, 0xbfb8aa3b, v91
	v_mul_f32_e32 v94, v94, v95
	v_exp_f32_e32 v91, v91
	v_mul_f32_e32 v84, 0xbfb8aa3b, v84
	v_cvt_pk_bf16_f32 v93, v93, v94
	v_lshlrev_b32_e32 v94, 16, v134
	v_exp_f32_e32 v84, v84
	v_mul_f32_e32 v85, 0xbfb8aa3b, v85
	v_mul_f32_e32 v88, v88, v94
	v_and_b32_e32 v94, 0xffff0000, v134
	v_exp_f32_e32 v85, v85
	v_mul_f32_e32 v89, v89, v94
	v_cvt_pk_bf16_f32 v94, v88, v89
	v_add_f32_e32 v88, 1.0, v90
	v_rcp_f32_e32 v88, v88
	v_add_f32_e32 v89, 1.0, v91
	v_rcp_f32_e32 v89, v89
	v_add_f32_e32 v84, 1.0, v84
	v_rcp_f32_e32 v84, v84
	v_add_f32_e32 v85, 1.0, v85
	v_lshlrev_b32_e32 v90, 16, v135
	v_rcp_f32_e32 v85, v85
	v_mul_f32_e32 v86, 0xbfb8aa3b, v86
	v_mul_f32_e32 v88, v88, v90
	v_and_b32_e32 v90, 0xffff0000, v135
	v_exp_f32_e32 v86, v86
	v_mul_f32_e32 v87, 0xbfb8aa3b, v87
	v_lshlrev_b64 v[96:97], 11, v[174:175]
	v_mul_f32_e32 v89, v89, v90
	v_lshlrev_b32_e32 v90, 16, v128
	v_exp_f32_e32 v87, v87
	v_cvt_pk_bf16_f32 v95, v88, v89
	v_lshl_add_u64 v[88:89], s[46:47], 0, v[96:97]
	v_mul_f32_e32 v84, v84, v90
	v_and_b32_e32 v90, 0xffff0000, v128
	v_mul_f32_e32 v80, 0xbfb8aa3b, v80
	v_lshl_add_u64 v[88:89], v[88:89], 0, v[168:169]
	v_mul_f32_e32 v85, v85, v90
	v_exp_f32_e32 v80, v80
	v_mul_f32_e32 v81, 0xbfb8aa3b, v81
	global_store_dwordx4 v[88:89], v[92:95], off offset:1024 nt
	v_cvt_pk_bf16_f32 v84, v84, v85
	v_add_f32_e32 v85, 1.0, v86
	v_exp_f32_e32 v81, v81
	v_rcp_f32_e32 v85, v85
	v_add_f32_e32 v86, 1.0, v87
	v_rcp_f32_e32 v86, v86
	v_add_f32_e32 v80, 1.0, v80
	v_lshlrev_b32_e32 v87, 16, v129
	v_rcp_f32_e32 v80, v80
	v_add_f32_e32 v81, 1.0, v81
	v_mul_f32_e32 v82, 0xbfb8aa3b, v82
	v_mul_f32_e32 v85, v85, v87
	v_and_b32_e32 v87, 0xffff0000, v129
	v_rcp_f32_e32 v81, v81
	v_exp_f32_e32 v82, v82
	v_mul_f32_e32 v83, 0xbfb8aa3b, v83
	v_mul_f32_e32 v86, v86, v87
	v_exp_f32_e32 v83, v83
	v_mul_f32_e32 v76, 0xbfb8aa3b, v76
	v_cvt_pk_bf16_f32 v85, v85, v86
	v_lshlrev_b32_e32 v86, 16, v130
	v_exp_f32_e32 v76, v76
	v_mul_f32_e32 v77, 0xbfb8aa3b, v77
	v_mul_f32_e32 v80, v80, v86
	v_and_b32_e32 v86, 0xffff0000, v130
	v_exp_f32_e32 v77, v77
	v_mul_f32_e32 v81, v81, v86
	v_cvt_pk_bf16_f32 v86, v80, v81
	v_add_f32_e32 v80, 1.0, v82
	v_rcp_f32_e32 v80, v80
	v_add_f32_e32 v81, 1.0, v83
	v_rcp_f32_e32 v81, v81
	v_add_f32_e32 v76, 1.0, v76
	v_rcp_f32_e32 v76, v76
	v_add_f32_e32 v77, 1.0, v77
	v_lshlrev_b32_e32 v82, 16, v131
	v_rcp_f32_e32 v77, v77
	v_mul_f32_e32 v78, 0xbfb8aa3b, v78
	v_mul_f32_e32 v80, v80, v82
	v_and_b32_e32 v82, 0xffff0000, v131
	v_exp_f32_e32 v78, v78
	v_mul_f32_e32 v79, 0xbfb8aa3b, v79
	v_mul_f32_e32 v81, v81, v82
	v_lshlrev_b32_e32 v82, 16, v124
	v_exp_f32_e32 v79, v79
	v_mul_f32_e32 v76, v76, v82
	v_and_b32_e32 v82, 0xffff0000, v124
	v_mul_f32_e32 v72, 0xbfb8aa3b, v72
	v_mul_f32_e32 v77, v77, v82
	v_exp_f32_e32 v72, v72
	v_mul_f32_e32 v73, 0xbfb8aa3b, v73
	v_cvt_pk_bf16_f32 v87, v80, v81
	global_store_dwordx4 v[88:89], v[84:87], off offset:1280 nt
	v_cvt_pk_bf16_f32 v76, v76, v77
	v_add_f32_e32 v77, 1.0, v78
	v_exp_f32_e32 v73, v73
	v_rcp_f32_e32 v77, v77
	v_add_f32_e32 v78, 1.0, v79
	v_rcp_f32_e32 v78, v78
	v_add_f32_e32 v72, 1.0, v72
	v_lshlrev_b32_e32 v79, 16, v125
	v_rcp_f32_e32 v72, v72
	v_add_f32_e32 v73, 1.0, v73
	v_mul_f32_e32 v74, 0xbfb8aa3b, v74
	v_mul_f32_e32 v77, v77, v79
	v_and_b32_e32 v79, 0xffff0000, v125
	v_rcp_f32_e32 v73, v73
	v_exp_f32_e32 v74, v74
	v_mul_f32_e32 v75, 0xbfb8aa3b, v75
	v_mul_f32_e32 v78, v78, v79
	v_exp_f32_e32 v75, v75
	v_mul_f32_e32 v68, 0xbfb8aa3b, v68
	v_cvt_pk_bf16_f32 v77, v77, v78
	v_lshlrev_b32_e32 v78, 16, v126
	v_exp_f32_e32 v68, v68
	v_mul_f32_e32 v69, 0xbfb8aa3b, v69
	v_mul_f32_e32 v72, v72, v78
	v_and_b32_e32 v78, 0xffff0000, v126
	v_exp_f32_e32 v69, v69
	v_mul_f32_e32 v73, v73, v78
	v_cvt_pk_bf16_f32 v78, v72, v73
	v_add_f32_e32 v72, 1.0, v74
	v_rcp_f32_e32 v72, v72
	v_add_f32_e32 v73, 1.0, v75
	v_rcp_f32_e32 v73, v73
	v_add_f32_e32 v68, 1.0, v68
	v_rcp_f32_e32 v68, v68
	v_add_f32_e32 v69, 1.0, v69
	v_lshlrev_b32_e32 v74, 16, v127
	v_rcp_f32_e32 v69, v69
	v_mul_f32_e32 v70, 0xbfb8aa3b, v70
	v_mul_f32_e32 v72, v72, v74
	v_and_b32_e32 v74, 0xffff0000, v127
	v_exp_f32_e32 v70, v70
	v_mul_f32_e32 v71, 0xbfb8aa3b, v71
	v_lshlrev_b64 v[80:81], 11, v[116:117]
	v_mul_f32_e32 v73, v73, v74
	v_lshlrev_b32_e32 v74, 16, v120
	v_exp_f32_e32 v71, v71
	v_cvt_pk_bf16_f32 v79, v72, v73
	v_lshl_add_u64 v[72:73], s[46:47], 0, v[80:81]
	v_mul_f32_e32 v68, v68, v74
	v_and_b32_e32 v74, 0xffff0000, v120
	v_mul_f32_e32 v64, 0xbfb8aa3b, v64
	v_lshl_add_u64 v[72:73], v[72:73], 0, v[168:169]
	v_mul_f32_e32 v69, v69, v74
	v_exp_f32_e32 v64, v64
	v_mul_f32_e32 v65, 0xbfb8aa3b, v65
	global_store_dwordx4 v[72:73], v[76:79], off offset:1024 nt
	v_cvt_pk_bf16_f32 v68, v68, v69
	v_add_f32_e32 v69, 1.0, v70
	v_exp_f32_e32 v65, v65
	v_rcp_f32_e32 v69, v69
	v_add_f32_e32 v70, 1.0, v71
	v_rcp_f32_e32 v70, v70
	v_add_f32_e32 v64, 1.0, v64
	v_lshlrev_b32_e32 v71, 16, v121
	v_rcp_f32_e32 v64, v64
	v_add_f32_e32 v65, 1.0, v65
	v_mul_f32_e32 v66, 0xbfb8aa3b, v66
	v_mul_f32_e32 v69, v69, v71
	v_and_b32_e32 v71, 0xffff0000, v121
	v_rcp_f32_e32 v65, v65
	v_exp_f32_e32 v66, v66
	v_mul_f32_e32 v67, 0xbfb8aa3b, v67
; DI unsigned pk2(float lo, float hi) { unsigned r; asm volatile("v_cvt_pk_bf16_f32 %0, %1, %2" : "=v"(r) : "v"(lo), "v"(hi)); return r; }
; DI float bflo(unsigned u) { return __uint_as_float(u << 16); }
; DI float bfhi(unsigned u) { return __uint_as_float(u & 0xffff0000u); }
; DI float sigm(float x) { return __builtin_amdgcn_rcpf(1.f + __expf(-x)); }
;     DI void operator()(const f32x4 (&acc)[2][2][4][2], const Unit& u, int wr, int wc, int fr, int fq, const Pre& pre) const {
;     ...
;                 for (int bj = 0; bj < 2; ++bj) y[m][bj] = *(const u32x4v*)(YG + (size_t)(row0 + ai * 128 + m * 16) * 512 + cb + bj * 128);
; #pragma unroll
;             for (int m = 0; m < 4; ++m) { const int row = row0 + ai * 128 + m * 16;
; #pragma unroll
;                 for (int bj = 0; bj < 2; ++bj) { const f32x4 v0 = acc[ai][bj][m][0], v1 = acc[ai][bj][m][1]; const u32x4v yy = y[m][bj]; u32x4v o;
;                     o.x = pk2(bflo(yy.x) * sigm(v0[0]), bfhi(yy.x) * sigm(v0[1])); o.y = pk2(bflo(yy.y) * sigm(v0[2]), bfhi(yy.y) * sigm(v0[3]));
;                     o.z = pk2(bflo(yy.z) * sigm(v1[0]), bfhi(yy.z) * sigm(v1[1])); o.w = pk2(bflo(yy.w) * sigm(v1[2]), bfhi(yy.w) * sigm(v1[3]));
;                     *(u32x4v*)(CAT + (size_t)row * 1024 + 512 + cb + bj * 128) = o; } } }
	v_mul_f32_e32 v70, v70, v71
	v_exp_f32_e32 v67, v67
	v_cvt_pk_bf16_f32 v69, v69, v70
	v_lshlrev_b32_e32 v70, 16, v122
	v_mul_f32_e32 v64, v64, v70
	v_and_b32_e32 v70, 0xffff0000, v122
	v_mul_f32_e32 v65, v65, v70
	v_cvt_pk_bf16_f32 v70, v64, v65
	v_add_f32_e32 v64, 1.0, v66
	v_rcp_f32_e32 v64, v64
	v_add_f32_e32 v65, 1.0, v67
	v_rcp_f32_e32 v65, v65
	v_lshlrev_b32_e32 v66, 16, v123
	v_mul_f32_e32 v64, v64, v66
	v_and_b32_e32 v66, 0xffff0000, v123
	v_add_u32_e32 v100, 0x80, v170
	v_mul_f32_e32 v65, v65, v66
	v_ashrrev_i32_e32 v101, 31, v100
	v_cvt_pk_bf16_f32 v71, v64, v65
	v_lshlrev_b64 v[64:65], 10, v[100:101]
	global_store_dwordx4 v[72:73], v[68:71], off offset:1280 nt
	v_lshl_add_u64 v[64:65], v[172:173], 0, v[64:65]
	global_load_dwordx4 v[92:95], v[64:65], off
	global_load_dwordx4 v[96:99], v[64:65], off offset:256
	v_add_u32_e32 v102, 0x90, v170
	v_ashrrev_i32_e32 v103, 31, v102
	v_lshlrev_b64 v[64:65], 10, v[102:103]
	v_lshl_add_u64 v[64:65], v[172:173], 0, v[64:65]
	global_load_dwordx4 v[84:87], v[64:65], off
	global_load_dwordx4 v[80:83], v[64:65], off offset:256
	v_add_u32_e32 v90, 0xa0, v170
	v_ashrrev_i32_e32 v91, 31, v90
	v_lshlrev_b64 v[64:65], 10, v[90:91]
	v_lshl_add_u64 v[64:65], v[172:173], 0, v[64:65]
	v_mul_f32_e32 v60, 0xbfb8aa3b, v60
	v_mul_f32_e32 v61, 0xbfb8aa3b, v61
	global_load_dwordx4 v[76:79], v[64:65], off
	global_load_dwordx4 v[72:75], v[64:65], off offset:256
	v_exp_f32_e32 v60, v60
	v_exp_f32_e32 v61, v61
	v_mul_f32_e32 v62, 0xbfb8aa3b, v62
	v_add_u32_e32 v88, 0xb0, v170
	v_add_f32_e32 v60, 1.0, v60
	v_add_f32_e32 v61, 1.0, v61
	v_rcp_f32_e32 v60, v60
	v_rcp_f32_e32 v61, v61
	v_exp_f32_e32 v62, v62
	v_mul_f32_e32 v63, 0xbfb8aa3b, v63
	v_ashrrev_i32_e32 v89, 31, v88
	v_exp_f32_e32 v63, v63
	v_lshlrev_b64 v[64:65], 10, v[88:89]
	v_mul_f32_e32 v56, 0xbfb8aa3b, v56
	v_lshl_add_u64 v[64:65], v[172:173], 0, v[64:65]
	v_exp_f32_e32 v56, v56
	v_mul_f32_e32 v57, 0xbfb8aa3b, v57
	global_load_dwordx4 v[68:71], v[64:65], off
	s_nop 0
	global_load_dwordx4 v[64:67], v[64:65], off offset:256
	v_exp_f32_e32 v57, v57
	v_add_f32_e32 v56, 1.0, v56
	v_rcp_f32_e32 v56, v56
	v_mul_f32_e32 v58, 0xbfb8aa3b, v58
	v_add_f32_e32 v57, 1.0, v57
	v_rcp_f32_e32 v57, v57
	v_exp_f32_e32 v58, v58
	v_mul_f32_e32 v59, 0xbfb8aa3b, v59
	v_exp_f32_e32 v59, v59
	v_mul_f32_e32 v52, 0xbfb8aa3b, v52
	v_exp_f32_e32 v52, v52
	v_mul_f32_e32 v53, 0xbfb8aa3b, v53
	v_exp_f32_e32 v53, v53
	v_mul_f32_e32 v54, 0xbfb8aa3b, v54
	v_add_f32_e32 v52, 1.0, v52
	v_rcp_f32_e32 v52, v52
	v_add_f32_e32 v53, 1.0, v53
	v_rcp_f32_e32 v53, v53
	v_exp_f32_e32 v54, v54
	v_mul_f32_e32 v55, 0xbfb8aa3b, v55
	v_lshlrev_b64 v[100:101], 11, v[100:101]
	v_exp_f32_e32 v55, v55
	v_mul_f32_e32 v48, 0xbfb8aa3b, v48
	v_exp_f32_e32 v48, v48
	v_mul_f32_e32 v49, 0xbfb8aa3b, v49
	v_exp_f32_e32 v49, v49
	v_mul_f32_e32 v50, 0xbfb8aa3b, v50
	v_add_f32_e32 v48, 1.0, v48
	v_rcp_f32_e32 v48, v48
	v_add_f32_e32 v49, 1.0, v49
	v_rcp_f32_e32 v49, v49
	v_exp_f32_e32 v50, v50
	v_mul_f32_e32 v51, 0xbfb8aa3b, v51
	v_exp_f32_e32 v51, v51
	v_mul_f32_e32 v44, 0xbfb8aa3b, v44
	v_exp_f32_e32 v44, v44
	v_mul_f32_e32 v45, 0xbfb8aa3b, v45
	v_exp_f32_e32 v45, v45
	v_mul_f32_e32 v46, 0xbfb8aa3b, v46
	v_add_f32_e32 v44, 1.0, v44
	v_rcp_f32_e32 v44, v44
	v_add_f32_e32 v45, 1.0, v45
	v_rcp_f32_e32 v45, v45
	v_exp_f32_e32 v46, v46
	v_mul_f32_e32 v47, 0xbfb8aa3b, v47
	v_exp_f32_e32 v47, v47
	v_mul_f32_e32 v40, 0xbfb8aa3b, v40
	v_exp_f32_e32 v40, v40
	s_waitcnt vmcnt(0)
	v_lshlrev_b32_e32 v104, 16, v92
	v_and_b32_e32 v92, 0xffff0000, v92
	v_mul_f32_e32 v60, v60, v104
	v_mul_f32_e32 v61, v61, v92
	v_cvt_pk_bf16_f32 v60, v60, v61
	v_add_f32_e32 v61, 1.0, v62
	v_rcp_f32_e32 v61, v61
	v_add_f32_e32 v62, 1.0, v63
	v_rcp_f32_e32 v62, v62
	v_lshlrev_b32_e32 v63, 16, v93
	v_mul_f32_e32 v61, v61, v63
	v_and_b32_e32 v63, 0xffff0000, v93
	v_mul_f32_e32 v62, v62, v63
	v_cvt_pk_bf16_f32 v61, v61, v62
	v_lshlrev_b32_e32 v62, 16, v94
	v_mul_f32_e32 v56, v56, v62
	v_and_b32_e32 v62, 0xffff0000, v94
	v_mul_f32_e32 v57, v57, v62
	v_cvt_pk_bf16_f32 v62, v56, v57
	v_add_f32_e32 v56, 1.0, v58
	v_rcp_f32_e32 v56, v56
	v_add_f32_e32 v57, 1.0, v59
	v_rcp_f32_e32 v57, v57
	v_lshlrev_b32_e32 v58, 16, v95
	v_mul_f32_e32 v56, v56, v58
	v_and_b32_e32 v58, 0xffff0000, v95
	v_mul_f32_e32 v57, v57, v58
	v_lshlrev_b32_e32 v58, 16, v96
	v_cvt_pk_bf16_f32 v63, v56, v57
	v_lshl_add_u64 v[56:57], s[46:47], 0, v[100:101]
	v_mul_f32_e32 v52, v52, v58
	v_and_b32_e32 v58, 0xffff0000, v96
	v_lshl_add_u64 v[56:57], v[56:57], 0, v[168:169]
	v_mul_f32_e32 v53, v53, v58
	global_store_dwordx4 v[56:57], v[60:63], off offset:1024 nt
	v_cvt_pk_bf16_f32 v52, v52, v53
	v_add_f32_e32 v53, 1.0, v54
	v_rcp_f32_e32 v53, v53
	v_add_f32_e32 v54, 1.0, v55
	v_rcp_f32_e32 v54, v54
	v_lshlrev_b32_e32 v55, 16, v97
	v_mul_f32_e32 v53, v53, v55
	v_and_b32_e32 v55, 0xffff0000, v97
	v_mul_f32_e32 v54, v54, v55
	v_cvt_pk_bf16_f32 v53, v53, v54
	v_lshlrev_b32_e32 v54, 16, v98
	v_mul_f32_e32 v48, v48, v54
	v_and_b32_e32 v54, 0xffff0000, v98
	v_mul_f32_e32 v49, v49, v54
	v_cvt_pk_bf16_f32 v54, v48, v49
	v_add_f32_e32 v48, 1.0, v50
	v_rcp_f32_e32 v48, v48
	v_add_f32_e32 v49, 1.0, v51
	v_rcp_f32_e32 v49, v49
	v_lshlrev_b32_e32 v50, 16, v99
	v_mul_f32_e32 v48, v48, v50
	v_and_b32_e32 v50, 0xffff0000, v99
	v_mul_f32_e32 v49, v49, v50
	v_lshlrev_b32_e32 v50, 16, v84
	v_mul_f32_e32 v44, v44, v50
	v_and_b32_e32 v50, 0xffff0000, v84
	v_mul_f32_e32 v45, v45, v50
	v_mul_f32_e32 v41, 0xbfb8aa3b, v41
	v_cvt_pk_bf16_f32 v55, v48, v49
	global_store_dwordx4 v[56:57], v[52:55], off offset:1280 nt
	v_cvt_pk_bf16_f32 v44, v44, v45
	v_add_f32_e32 v45, 1.0, v46
	v_exp_f32_e32 v41, v41
	v_rcp_f32_e32 v45, v45
; DI unsigned pk2(float lo, float hi) { unsigned r; asm volatile("v_cvt_pk_bf16_f32 %0, %1, %2" : "=v"(r) : "v"(lo), "v"(hi)); return r; }
; DI float bflo(unsigned u) { return __uint_as_float(u << 16); }
; DI float bfhi(unsigned u) { return __uint_as_float(u & 0xffff0000u); }
; DI float sigm(float x) { return __builtin_amdgcn_rcpf(1.f + __expf(-x)); }
;     DI void operator()(const f32x4 (&acc)[2][2][4][2], const Unit& u, int wr, int wc, int fr, int fq, const Pre& pre) const {
;     ...
;                 for (int bj = 0; bj < 2; ++bj) { const f32x4 v0 = acc[ai][bj][m][0], v1 = acc[ai][bj][m][1]; const u32x4v yy = y[m][bj]; u32x4v o;
;                     o.x = pk2(bflo(yy.x) * sigm(v0[0]), bfhi(yy.x) * sigm(v0[1])); o.y = pk2(bflo(yy.y) * sigm(v0[2]), bfhi(yy.y) * sigm(v0[3]));
;                     o.z = pk2(bflo(yy.z) * sigm(v1[0]), bfhi(yy.z) * sigm(v1[1])); o.w = pk2(bflo(yy.w) * sigm(v1[2]), bfhi(yy.w) * sigm(v1[3]));
;                     *(u32x4v*)(CAT + (size_t)row * 1024 + 512 + cb + bj * 128) = o; } } }
	v_add_f32_e32 v46, 1.0, v47
	v_rcp_f32_e32 v46, v46
	v_add_f32_e32 v40, 1.0, v40
	v_lshlrev_b32_e32 v47, 16, v85
	v_rcp_f32_e32 v40, v40
	v_add_f32_e32 v41, 1.0, v41
	v_mul_f32_e32 v42, 0xbfb8aa3b, v42
	v_mul_f32_e32 v45, v45, v47
	v_and_b32_e32 v47, 0xffff0000, v85
	v_rcp_f32_e32 v41, v41
	v_exp_f32_e32 v42, v42
	v_mul_f32_e32 v43, 0xbfb8aa3b, v43
	v_mul_f32_e32 v46, v46, v47
	v_exp_f32_e32 v43, v43
	v_mul_f32_e32 v36, 0xbfb8aa3b, v36
	v_cvt_pk_bf16_f32 v45, v45, v46
	v_lshlrev_b32_e32 v46, 16, v86
	v_exp_f32_e32 v36, v36
	v_mul_f32_e32 v37, 0xbfb8aa3b, v37
	v_mul_f32_e32 v40, v40, v46
	v_and_b32_e32 v46, 0xffff0000, v86
	v_exp_f32_e32 v37, v37
	v_mul_f32_e32 v41, v41, v46
	v_cvt_pk_bf16_f32 v46, v40, v41
	v_add_f32_e32 v40, 1.0, v42
	v_rcp_f32_e32 v40, v40
	v_add_f32_e32 v41, 1.0, v43
	v_rcp_f32_e32 v41, v41
	v_add_f32_e32 v36, 1.0, v36
	v_rcp_f32_e32 v36, v36
	v_add_f32_e32 v37, 1.0, v37
	v_lshlrev_b32_e32 v42, 16, v87
	v_rcp_f32_e32 v37, v37
	v_mul_f32_e32 v38, 0xbfb8aa3b, v38
	v_mul_f32_e32 v40, v40, v42
	v_and_b32_e32 v42, 0xffff0000, v87
	v_exp_f32_e32 v38, v38
	v_mul_f32_e32 v39, 0xbfb8aa3b, v39
	v_lshlrev_b64 v[48:49], 11, v[102:103]
	v_mul_f32_e32 v41, v41, v42
	v_lshlrev_b32_e32 v42, 16, v80
	v_exp_f32_e32 v39, v39
	v_cvt_pk_bf16_f32 v47, v40, v41
	v_lshl_add_u64 v[40:41], s[46:47], 0, v[48:49]
	v_mul_f32_e32 v36, v36, v42
	v_and_b32_e32 v42, 0xffff0000, v80
	v_mul_f32_e32 v32, 0xbfb8aa3b, v32
	v_lshl_add_u64 v[40:41], v[40:41], 0, v[168:169]
	v_mul_f32_e32 v37, v37, v42
	v_exp_f32_e32 v32, v32
	v_mul_f32_e32 v33, 0xbfb8aa3b, v33
	global_store_dwordx4 v[40:41], v[44:47], off offset:1024 nt
	v_cvt_pk_bf16_f32 v36, v36, v37
	v_add_f32_e32 v37, 1.0, v38
	v_exp_f32_e32 v33, v33
	v_rcp_f32_e32 v37, v37
	v_add_f32_e32 v38, 1.0, v39
	v_rcp_f32_e32 v38, v38
	v_add_f32_e32 v32, 1.0, v32
	v_lshlrev_b32_e32 v39, 16, v81
	v_rcp_f32_e32 v32, v32
	v_add_f32_e32 v33, 1.0, v33
	v_mul_f32_e32 v34, 0xbfb8aa3b, v34
	v_mul_f32_e32 v37, v37, v39
	v_and_b32_e32 v39, 0xffff0000, v81
	v_rcp_f32_e32 v33, v33
	v_exp_f32_e32 v34, v34
	v_mul_f32_e32 v35, 0xbfb8aa3b, v35
	v_mul_f32_e32 v38, v38, v39
	v_exp_f32_e32 v35, v35
	v_mul_f32_e32 v28, 0xbfb8aa3b, v28
	v_cvt_pk_bf16_f32 v37, v37, v38
	v_lshlrev_b32_e32 v38, 16, v82
	v_exp_f32_e32 v28, v28
	v_mul_f32_e32 v29, 0xbfb8aa3b, v29
	v_mul_f32_e32 v32, v32, v38
	v_and_b32_e32 v38, 0xffff0000, v82
	v_exp_f32_e32 v29, v29
	v_mul_f32_e32 v33, v33, v38
	v_cvt_pk_bf16_f32 v38, v32, v33
	v_add_f32_e32 v32, 1.0, v34
	v_rcp_f32_e32 v32, v32
	v_add_f32_e32 v33, 1.0, v35
	v_rcp_f32_e32 v33, v33
	v_add_f32_e32 v28, 1.0, v28
	v_rcp_f32_e32 v28, v28
	v_add_f32_e32 v29, 1.0, v29
	v_lshlrev_b32_e32 v34, 16, v83
	v_rcp_f32_e32 v29, v29
	v_mul_f32_e32 v30, 0xbfb8aa3b, v30
	v_mul_f32_e32 v32, v32, v34
	v_and_b32_e32 v34, 0xffff0000, v83
	v_exp_f32_e32 v30, v30
	v_mul_f32_e32 v31, 0xbfb8aa3b, v31
	v_mul_f32_e32 v33, v33, v34
	v_lshlrev_b32_e32 v34, 16, v76
	v_exp_f32_e32 v31, v31
	v_mul_f32_e32 v28, v28, v34
	v_and_b32_e32 v34, 0xffff0000, v76
	v_mul_f32_e32 v24, 0xbfb8aa3b, v24
	v_mul_f32_e32 v29, v29, v34
	v_exp_f32_e32 v24, v24
	v_mul_f32_e32 v25, 0xbfb8aa3b, v25
	v_cvt_pk_bf16_f32 v39, v32, v33
	global_store_dwordx4 v[40:41], v[36:39], off offset:1280 nt
	v_cvt_pk_bf16_f32 v28, v28, v29
	v_add_f32_e32 v29, 1.0, v30
	v_exp_f32_e32 v25, v25
	v_rcp_f32_e32 v29, v29
	v_add_f32_e32 v30, 1.0, v31
	v_rcp_f32_e32 v30, v30
	v_add_f32_e32 v24, 1.0, v24
	v_lshlrev_b32_e32 v31, 16, v77
	v_rcp_f32_e32 v24, v24
	v_add_f32_e32 v25, 1.0, v25
	v_mul_f32_e32 v26, 0xbfb8aa3b, v26
	v_mul_f32_e32 v29, v29, v31
	v_and_b32_e32 v31, 0xffff0000, v77
	v_rcp_f32_e32 v25, v25
	v_exp_f32_e32 v26, v26
	v_mul_f32_e32 v27, 0xbfb8aa3b, v27
	v_mul_f32_e32 v30, v30, v31
	v_exp_f32_e32 v27, v27
	v_mul_f32_e32 v20, 0xbfb8aa3b, v20
	v_cvt_pk_bf16_f32 v29, v29, v30
	v_lshlrev_b32_e32 v30, 16, v78
	v_exp_f32_e32 v20, v20
	v_mul_f32_e32 v21, 0xbfb8aa3b, v21
	v_mul_f32_e32 v24, v24, v30
	v_and_b32_e32 v30, 0xffff0000, v78
	v_exp_f32_e32 v21, v21
	v_mul_f32_e32 v25, v25, v30
	v_cvt_pk_bf16_f32 v30, v24, v25
	v_add_f32_e32 v24, 1.0, v26
	v_rcp_f32_e32 v24, v24
	v_add_f32_e32 v25, 1.0, v27
	v_rcp_f32_e32 v25, v25
	v_add_f32_e32 v20, 1.0, v20
	v_rcp_f32_e32 v20, v20
	v_add_f32_e32 v21, 1.0, v21
	v_lshlrev_b32_e32 v26, 16, v79
	v_rcp_f32_e32 v21, v21
	v_mul_f32_e32 v22, 0xbfb8aa3b, v22
	v_mul_f32_e32 v24, v24, v26
	v_and_b32_e32 v26, 0xffff0000, v79
	v_exp_f32_e32 v22, v22
	v_mul_f32_e32 v23, 0xbfb8aa3b, v23
	v_lshlrev_b64 v[32:33], 11, v[90:91]
	v_mul_f32_e32 v25, v25, v26
	v_lshlrev_b32_e32 v26, 16, v72
	v_exp_f32_e32 v23, v23
	v_cvt_pk_bf16_f32 v31, v24, v25
	v_lshl_add_u64 v[24:25], s[46:47], 0, v[32:33]
	v_mul_f32_e32 v20, v20, v26
	v_and_b32_e32 v26, 0xffff0000, v72
	v_mul_f32_e32 v16, 0xbfb8aa3b, v16
	v_lshl_add_u64 v[24:25], v[24:25], 0, v[168:169]
	v_mul_f32_e32 v21, v21, v26
	v_exp_f32_e32 v16, v16
; #define PG8_WAIT_V(n) asm volatile("s_waitcnt vmcnt(" #n ")" ::: "memory")
; #define PG8_BAR __builtin_amdgcn_s_barrier()
; DI unsigned pk2(float lo, float hi) { unsigned r; asm volatile("v_cvt_pk_bf16_f32 %0, %1, %2" : "=v"(r) : "v"(lo), "v"(hi)); return r; }
; DI float bflo(unsigned u) { return __uint_as_float(u << 16); }
; DI float bfhi(unsigned u) { return __uint_as_float(u & 0xffff0000u); }
; DI float sigm(float x) { return __builtin_amdgcn_rcpf(1.f + __expf(-x)); }
; template <class Epi, class Sched>
; __device__ __forceinline__ void gemm_phase(PG8_LAS unsigned char* lds, const Gemm g, const Sched& S, const Epi& E) {
;     ...
;     PG8_WAIT_V(0);
;     if (wr == 0) PG8_BAR;
;     PG8_BAR;
;     DI void operator()(const f32x4 (&acc)[2][2][4][2], const Unit& u, int wr, int wc, int fr, int fq, const Pre& pre) const {
;     ...
;                 for (int bj = 0; bj < 2; ++bj) { const f32x4 v0 = acc[ai][bj][m][0], v1 = acc[ai][bj][m][1]; const u32x4v yy = y[m][bj]; u32x4v o;
;                     o.x = pk2(bflo(yy.x) * sigm(v0[0]), bfhi(yy.x) * sigm(v0[1])); o.y = pk2(bflo(yy.y) * sigm(v0[2]), bfhi(yy.y) * sigm(v0[3]));
;                     o.z = pk2(bflo(yy.z) * sigm(v1[0]), bfhi(yy.z) * sigm(v1[1])); o.w = pk2(bflo(yy.w) * sigm(v1[2]), bfhi(yy.w) * sigm(v1[3]));
;                     *(u32x4v*)(CAT + (size_t)row * 1024 + 512 + cb + bj * 128) = o; } } }
	v_mul_f32_e32 v17, 0xbfb8aa3b, v17
	global_store_dwordx4 v[24:25], v[28:31], off offset:1024 nt
	v_cvt_pk_bf16_f32 v20, v20, v21
	v_add_f32_e32 v21, 1.0, v22
	v_exp_f32_e32 v17, v17
	v_rcp_f32_e32 v21, v21
	v_add_f32_e32 v22, 1.0, v23
	v_rcp_f32_e32 v22, v22
	v_add_f32_e32 v16, 1.0, v16
	v_lshlrev_b32_e32 v23, 16, v73
	v_rcp_f32_e32 v16, v16
	v_add_f32_e32 v17, 1.0, v17
	v_mul_f32_e32 v18, 0xbfb8aa3b, v18
	v_mul_f32_e32 v21, v21, v23
	v_and_b32_e32 v23, 0xffff0000, v73
	v_rcp_f32_e32 v17, v17
	v_exp_f32_e32 v18, v18
	v_mul_f32_e32 v19, 0xbfb8aa3b, v19
	v_mul_f32_e32 v22, v22, v23
	v_exp_f32_e32 v19, v19
	v_mul_f32_e32 v12, 0xbfb8aa3b, v12
	v_cvt_pk_bf16_f32 v21, v21, v22
	v_lshlrev_b32_e32 v22, 16, v74
	v_exp_f32_e32 v12, v12
	v_mul_f32_e32 v13, 0xbfb8aa3b, v13
	v_mul_f32_e32 v16, v16, v22
	v_and_b32_e32 v22, 0xffff0000, v74
	v_exp_f32_e32 v13, v13
	v_mul_f32_e32 v17, v17, v22
	v_cvt_pk_bf16_f32 v22, v16, v17
	v_add_f32_e32 v16, 1.0, v18
	v_rcp_f32_e32 v16, v16
	v_add_f32_e32 v17, 1.0, v19
	v_rcp_f32_e32 v17, v17
	v_add_f32_e32 v12, 1.0, v12
	v_rcp_f32_e32 v12, v12
	v_add_f32_e32 v13, 1.0, v13
	v_lshlrev_b32_e32 v18, 16, v75
	v_rcp_f32_e32 v13, v13
	v_mul_f32_e32 v14, 0xbfb8aa3b, v14
	v_mul_f32_e32 v16, v16, v18
	v_and_b32_e32 v18, 0xffff0000, v75
	v_exp_f32_e32 v14, v14
	v_mul_f32_e32 v15, 0xbfb8aa3b, v15
	v_mul_f32_e32 v17, v17, v18
	v_lshlrev_b32_e32 v18, 16, v68
	v_exp_f32_e32 v15, v15
	v_mul_f32_e32 v12, v12, v18
	v_and_b32_e32 v18, 0xffff0000, v68
	v_mul_f32_e32 v8, 0xbfb8aa3b, v8
	v_mul_f32_e32 v13, v13, v18
	v_exp_f32_e32 v8, v8
	v_mul_f32_e32 v9, 0xbfb8aa3b, v9
	v_cvt_pk_bf16_f32 v23, v16, v17
	global_store_dwordx4 v[24:25], v[20:23], off offset:1280 nt
	v_cvt_pk_bf16_f32 v12, v12, v13
	v_add_f32_e32 v13, 1.0, v14
	v_exp_f32_e32 v9, v9
	v_rcp_f32_e32 v13, v13
	v_add_f32_e32 v14, 1.0, v15
	v_rcp_f32_e32 v14, v14
	v_add_f32_e32 v8, 1.0, v8
	v_lshlrev_b32_e32 v15, 16, v69
	v_rcp_f32_e32 v8, v8
	v_add_f32_e32 v9, 1.0, v9
	v_mul_f32_e32 v10, 0xbfb8aa3b, v10
	v_mul_f32_e32 v13, v13, v15
	v_and_b32_e32 v15, 0xffff0000, v69
	v_rcp_f32_e32 v9, v9
	v_exp_f32_e32 v10, v10
	v_mul_f32_e32 v11, 0xbfb8aa3b, v11
	v_mul_f32_e32 v14, v14, v15
	v_exp_f32_e32 v11, v11
	v_mul_f32_e32 v4, 0xbfb8aa3b, v4
	v_cvt_pk_bf16_f32 v13, v13, v14
	v_lshlrev_b32_e32 v14, 16, v70
	v_exp_f32_e32 v4, v4
	v_mul_f32_e32 v5, 0xbfb8aa3b, v5
	v_mul_f32_e32 v8, v8, v14
	v_and_b32_e32 v14, 0xffff0000, v70
	v_exp_f32_e32 v5, v5
	v_mul_f32_e32 v9, v9, v14
	v_cvt_pk_bf16_f32 v14, v8, v9
	v_add_f32_e32 v8, 1.0, v10
	v_rcp_f32_e32 v8, v8
	v_add_f32_e32 v9, 1.0, v11
	v_rcp_f32_e32 v9, v9
	v_add_f32_e32 v4, 1.0, v4
	v_rcp_f32_e32 v4, v4
	v_add_f32_e32 v5, 1.0, v5
	v_lshlrev_b32_e32 v10, 16, v71
	v_rcp_f32_e32 v5, v5
	v_mul_f32_e32 v6, 0xbfb8aa3b, v6
	v_mul_f32_e32 v8, v8, v10
	v_and_b32_e32 v10, 0xffff0000, v71
	v_exp_f32_e32 v6, v6
	v_mul_f32_e32 v7, 0xbfb8aa3b, v7
	v_lshlrev_b64 v[16:17], 11, v[88:89]
	v_mul_f32_e32 v9, v9, v10
	v_lshlrev_b32_e32 v10, 16, v64
	v_exp_f32_e32 v7, v7
	v_cvt_pk_bf16_f32 v15, v8, v9
	v_lshl_add_u64 v[8:9], s[46:47], 0, v[16:17]
	v_mul_f32_e32 v4, v4, v10
	v_and_b32_e32 v10, 0xffff0000, v64
	v_mul_f32_e32 v0, 0xbfb8aa3b, v0
	v_lshl_add_u64 v[8:9], v[8:9], 0, v[168:169]
	v_mul_f32_e32 v5, v5, v10
	v_exp_f32_e32 v0, v0
	v_mul_f32_e32 v1, 0xbfb8aa3b, v1
	global_store_dwordx4 v[8:9], v[12:15], off offset:1024 nt
	v_cvt_pk_bf16_f32 v4, v4, v5
	v_add_f32_e32 v5, 1.0, v6
	v_exp_f32_e32 v1, v1
	v_rcp_f32_e32 v5, v5
	v_add_f32_e32 v6, 1.0, v7
	v_rcp_f32_e32 v6, v6
	v_add_f32_e32 v0, 1.0, v0
	v_lshlrev_b32_e32 v7, 16, v65
	v_rcp_f32_e32 v0, v0
	v_add_f32_e32 v1, 1.0, v1
	v_mul_f32_e32 v2, 0xbfb8aa3b, v2
	v_mul_f32_e32 v5, v5, v7
	v_and_b32_e32 v7, 0xffff0000, v65
	v_rcp_f32_e32 v1, v1
	v_exp_f32_e32 v2, v2
	v_mul_f32_e32 v3, 0xbfb8aa3b, v3
	v_mul_f32_e32 v6, v6, v7
	v_exp_f32_e32 v3, v3
	v_cvt_pk_bf16_f32 v5, v5, v6
	v_lshlrev_b32_e32 v6, 16, v66
	v_mul_f32_e32 v0, v0, v6
	v_and_b32_e32 v6, 0xffff0000, v66
	v_mul_f32_e32 v1, v1, v6
	v_cvt_pk_bf16_f32 v6, v0, v1
	v_add_f32_e32 v0, 1.0, v2
	v_rcp_f32_e32 v0, v0
	v_add_f32_e32 v1, 1.0, v3
	v_rcp_f32_e32 v1, v1
	v_lshlrev_b32_e32 v2, 16, v67
	v_mul_f32_e32 v0, v0, v2
	v_and_b32_e32 v2, 0xffff0000, v67
	s_andn2_b64 vcc, exec, s[0:1]
	s_mov_b32 s12, s6
	s_mov_b32 s36, s4
	s_mov_b64 s[16:17], s[10:11]
	s_mov_b64 s[14:15], s[8:9]
	v_readlane_b32 s37, v255, 9
	v_readlane_b32 s38, v255, 10
	v_readlane_b32 s39, v255, 11
	v_readlane_b32 s40, v255, 12
	v_readlane_b32 s41, v255, 13
	v_readlane_b32 s42, v255, 14
	v_readlane_b32 s43, v255, 15
	v_readlane_b32 s48, v255, 20
	v_readlane_b32 s49, v255, 21
	v_readlane_b32 s50, v255, 22
	v_readlane_b32 s51, v255, 23
	v_mul_f32_e32 v1, v1, v2
	v_cvt_pk_bf16_f32 v7, v0, v1
	global_store_dwordx4 v[8:9], v[4:7], off offset:1280 nt
	s_cbranch_vccnz .LBB0_1184
	s_waitcnt vmcnt(0)
	s_cmpk_gt_u32 s20, 0xff
	s_cbranch_scc1 .LBB0_1195
	s_barrier

; template <class Epi, class Sched>
; __device__ __forceinline__ void gemm_phase(PG8_LAS unsigned char* lds, const Gemm g, const Sched& S, const Epi& E) {
;     ...
;             else { f32x4* pp = (f32x4*)g.part + (size_t)cur.part * 32 * 512 + tid;
; #pragma unroll
;                 for (int a = 0; a < 2; ++a)
; #pragma unroll
;                     for (int b = 0; b < 2; ++b)
; #pragma unroll
;                         for (int m = 0; m < 4; ++m)
; #pragma unroll
;                             for (int n = 0; n < 2; ++n) pp[(size_t)(((a * 2 + b) * 4 + m) * 2 + n) * 512] = acc[a][b][m][n]; }
.LBB0_1315:
	s_lshl_b64 s[40:41], s[8:9], 18
	v_lshl_add_u64 v[128:129], v[172:173], 0, s[40:41]
	v_add_co_u32_e32 v130, vcc, 0x2000, v128
	s_mov_b32 s8, 0x10000
	s_nop 0
	v_addc_co_u32_e32 v131, vcc, 0, v129, vcc
	global_store_dwordx4 v[130:131], v[120:123], off nt
	v_add_co_u32_e32 v130, vcc, 0x4000, v128
	global_store_dwordx4 v[128:129], v[124:127], off nt
	s_nop 0
	v_addc_co_u32_e32 v131, vcc, 0, v129, vcc
	global_store_dwordx4 v[130:131], v[108:111], off nt
	v_add_co_u32_e32 v130, vcc, 0x6000, v128
	s_mov_b64 s[40:41], 0
	s_nop 0
	v_addc_co_u32_e32 v131, vcc, 0, v129, vcc
	global_store_dwordx4 v[130:131], v[104:107], off nt
	v_add_co_u32_e32 v130, vcc, 0x8000, v128
	s_nop 1
	v_addc_co_u32_e32 v131, vcc, 0, v129, vcc
	global_store_dwordx4 v[130:131], v[92:95], off nt
	v_add_co_u32_e32 v130, vcc, 0xa000, v128
	s_nop 1
	v_addc_co_u32_e32 v131, vcc, 0, v129, vcc
	global_store_dwordx4 v[130:131], v[88:91], off nt
	v_add_co_u32_e32 v130, vcc, 0xc000, v128
	s_nop 1
	v_addc_co_u32_e32 v131, vcc, 0, v129, vcc
	global_store_dwordx4 v[130:131], v[76:79], off nt
	v_add_co_u32_e32 v130, vcc, 0xe000, v128
	s_nop 1
	v_addc_co_u32_e32 v131, vcc, 0, v129, vcc
	global_store_dwordx4 v[130:131], v[72:75], off nt
	v_add_co_u32_e32 v130, vcc, s8, v128
	s_mov_b32 s8, 0x12000
	s_nop 0
	v_addc_co_u32_e32 v131, vcc, 0, v129, vcc
	global_store_dwordx4 v[130:131], v[116:119], off nt
	v_add_co_u32_e32 v130, vcc, s8, v128
	s_mov_b32 s8, 0x14000
	s_nop 0
	v_addc_co_u32_e32 v131, vcc, 0, v129, vcc
	global_store_dwordx4 v[130:131], v[112:115], off nt
	v_add_co_u32_e32 v130, vcc, s8, v128
	s_mov_b32 s8, 0x16000
	s_nop 0
	v_addc_co_u32_e32 v131, vcc, 0, v129, vcc
	global_store_dwordx4 v[130:131], v[100:103], off nt
	v_add_co_u32_e32 v130, vcc, s8, v128
	s_mov_b32 s8, 0x18000
	s_nop 0
	v_addc_co_u32_e32 v131, vcc, 0, v129, vcc
	global_store_dwordx4 v[130:131], v[96:99], off nt
	v_add_co_u32_e32 v130, vcc, s8, v128
	s_mov_b32 s8, 0x1a000
	s_nop 0
	v_addc_co_u32_e32 v131, vcc, 0, v129, vcc
	global_store_dwordx4 v[130:131], v[84:87], off nt
	v_add_co_u32_e32 v130, vcc, s8, v128
	s_mov_b32 s8, 0x1c000
	s_nop 0
	v_addc_co_u32_e32 v131, vcc, 0, v129, vcc
	global_store_dwordx4 v[130:131], v[80:83], off nt
	v_add_co_u32_e32 v130, vcc, s8, v128
	s_mov_b32 s8, 0x1e000
	s_nop 0
	v_addc_co_u32_e32 v131, vcc, 0, v129, vcc
	global_store_dwordx4 v[130:131], v[68:71], off nt
	v_add_co_u32_e32 v130, vcc, s8, v128
	s_mov_b32 s8, 0x20000
	s_nop 0
	v_addc_co_u32_e32 v131, vcc, 0, v129, vcc
	global_store_dwordx4 v[130:131], v[64:67], off nt
	v_add_co_u32_e32 v130, vcc, s8, v128
	s_mov_b32 s8, 0x22000
	s_nop 0
	v_addc_co_u32_e32 v131, vcc, 0, v129, vcc
	global_store_dwordx4 v[130:131], v[60:63], off nt
	v_add_co_u32_e32 v130, vcc, s8, v128
	s_mov_b32 s8, 0x24000
	s_nop 0
	v_addc_co_u32_e32 v131, vcc, 0, v129, vcc
	global_store_dwordx4 v[130:131], v[56:59], off nt
	v_add_co_u32_e32 v130, vcc, s8, v128
	s_mov_b32 s8, 0x26000
	s_nop 0
	v_addc_co_u32_e32 v131, vcc, 0, v129, vcc
	global_store_dwordx4 v[130:131], v[44:47], off nt
	v_add_co_u32_e32 v130, vcc, s8, v128
	s_mov_b32 s8, 0x28000
	s_nop 0
	v_addc_co_u32_e32 v131, vcc, 0, v129, vcc
	global_store_dwordx4 v[130:131], v[40:43], off nt
	v_add_co_u32_e32 v130, vcc, s8, v128
	s_mov_b32 s8, 0x2a000
	s_nop 0
	v_addc_co_u32_e32 v131, vcc, 0, v129, vcc
	global_store_dwordx4 v[130:131], v[28:31], off nt
	v_add_co_u32_e32 v130, vcc, s8, v128
	s_mov_b32 s8, 0x2c000
	s_nop 0
	v_addc_co_u32_e32 v131, vcc, 0, v129, vcc
	global_store_dwordx4 v[130:131], v[24:27], off nt
	v_add_co_u32_e32 v130, vcc, s8, v128
	s_mov_b32 s8, 0x2e000
	s_nop 0
	v_addc_co_u32_e32 v131, vcc, 0, v129, vcc
	global_store_dwordx4 v[130:131], v[12:15], off nt
	v_add_co_u32_e32 v130, vcc, s8, v128
	s_mov_b32 s8, 0x30000
	s_nop 0
	v_addc_co_u32_e32 v131, vcc, 0, v129, vcc
	global_store_dwordx4 v[130:131], v[8:11], off nt
	v_add_co_u32_e32 v130, vcc, s8, v128
	s_mov_b32 s8, 0x32000
	s_nop 0
	v_addc_co_u32_e32 v131, vcc, 0, v129, vcc
	global_store_dwordx4 v[130:131], v[52:55], off nt
	v_add_co_u32_e32 v130, vcc, s8, v128
	s_mov_b32 s8, 0x34000
	s_nop 0
	v_addc_co_u32_e32 v131, vcc, 0, v129, vcc
	global_store_dwordx4 v[130:131], v[48:51], off nt
	v_add_co_u32_e32 v130, vcc, s8, v128
	s_mov_b32 s8, 0x36000
	s_nop 0
	v_addc_co_u32_e32 v131, vcc, 0, v129, vcc
	global_store_dwordx4 v[130:131], v[36:39], off nt
	v_add_co_u32_e32 v130, vcc, s8, v128
	s_mov_b32 s8, 0x38000
	s_nop 0
	v_addc_co_u32_e32 v131, vcc, 0, v129, vcc
	global_store_dwordx4 v[130:131], v[32:35], off nt
	v_add_co_u32_e32 v130, vcc, s8, v128
	s_mov_b32 s8, 0x3a000
	s_nop 0
	v_addc_co_u32_e32 v131, vcc, 0, v129, vcc
	global_store_dwordx4 v[130:131], v[20:23], off nt
	v_add_co_u32_e32 v130, vcc, s8, v128
	s_nop 1
	v_addc_co_u32_e32 v131, vcc, 0, v129, vcc
	global_store_dwordx4 v[130:131], v[16:19], off nt
	v_add_co_u32_e32 v130, vcc, 0x3c000, v128
	s_nop 1
	v_addc_co_u32_e32 v131, vcc, 0, v129, vcc
	v_add_co_u32_e32 v128, vcc, 0x3e000, v128
	global_store_dwordx4 v[130:131], v[4:7], off nt
	s_nop 0
	v_addc_co_u32_e32 v129, vcc, 0, v129, vcc
	global_store_dwordx4 v[128:129], v[0:3], off nt
; DI unsigned pk2(float lo, float hi) { unsigned r; asm volatile("v_cvt_pk_bf16_f32 %0, %1, %2" : "=v"(r) : "v"(lo), "v"(hi)); return r; }
; DI float bflo(unsigned u) { return __uint_as_float(u << 16); }
; DI float bfhi(unsigned u) { return __uint_as_float(u & 0xffff0000u); }
;     DI float upd(u32x4v* px, const u32x4v x, const f32x4 v0, const f32x4 v1) const {
;         u32x4v o; o.x = pk2(bflo(x.x) + v0[0], bfhi(x.x) + v0[1]); o.y = pk2(bflo(x.y) + v0[2], bfhi(x.y) + v0[3]);
;         o.z = pk2(bflo(x.z) + v1[0], bfhi(x.z) + v1[1]); o.w = pk2(bflo(x.w) + v1[2], bfhi(x.w) + v1[3]); *px = o;
;         const float a0 = bflo(o.x), a1 = bfhi(o.x), a2 = bflo(o.y), a3 = bfhi(o.y), a4 = bflo(o.z), a5 = bfhi(o.z), a6 = bflo(o.w), a7 = bfhi(o.w);
;         return ((a0 * a0 + a1 * a1) + (a2 * a2 + a3 * a3)) + ((a4 * a4 + a5 * a5) + (a6 * a6 + a7 * a7));
;     }
;     DI void operator()(const f32x4 (&acc)[2][2][4][2], const Unit& u, int wr, int wc, int fr, int fq, const Pre& pre) const {
;     ...
;             for (int m = 0; m < 4; ++m)
; #pragma unroll
;                 for (int bj = 0; bj < 2; ++bj) x[m][bj] = *(const u32x4v*)(XB + (size_t)(row0 + ai * 128 + m * 16) * 1024 + cb + bj * 128);
; #pragma unroll
;             for (int m = 0; m < 4; ++m) { const int row = row0 + ai * 128 + m * 16;
;                 float ss = upd((u32x4v*)(XB + (size_t)row * 1024 + cb), x[m][0], acc[ai][0][m][0], acc[ai][0][m][1])
;                          + upd((u32x4v*)(XB + (size_t)row * 1024 + cb + 128), x[m][1], acc[ai][1][m][0], acc[ai][1][m][1]);
;                 ss += __shfl_xor(ss, 16); ss += __shfl_xor(ss, 32);
;                 if (fq == 0) SSQ[(size_t)row * 16 + u.pn * 4 + wc] = ss; } }
.LBB0_1316:
	s_andn2_b64 vcc, exec, s[40:41]
	s_cbranch_vccnz .LBB0_1284
	v_lshl_or_b32 v180, s18, 8, v161
	v_lshl_add_u32 v182, s26, 8, v157
	v_ashrrev_i32_e32 v181, 31, v180
	v_readlane_b32 s52, v254, 28
	v_lshlrev_b64 v[128:129], 1, v[180:181]
	v_readlane_b32 s64, v254, 40
	v_readlane_b32 s65, v254, 41
	v_ashrrev_i32_e32 v183, 31, v182
	v_lshlrev_b64 v[130:131], 11, v[182:183]
	v_lshl_add_u64 v[184:185], s[64:65], 0, v[128:129]
	v_lshl_add_u64 v[132:133], v[184:185], 0, v[130:131]
	global_load_dwordx4 v[202:205], v[132:133], off
	global_load_dwordx4 v[206:209], v[132:133], off offset:256
	v_or_b32_e32 v192, 16, v182
	v_or_b32_e32 v188, 32, v182
	v_or_b32_e32 v186, 48, v182
	v_ashrrev_i32_e32 v193, 31, v192
	v_ashrrev_i32_e32 v189, 31, v188
	v_ashrrev_i32_e32 v187, 31, v186
	v_lshlrev_b64 v[196:197], 11, v[192:193]
	v_lshlrev_b64 v[194:195], 11, v[188:189]
	v_lshlrev_b64 v[190:191], 11, v[186:187]
	v_lshl_add_u64 v[130:131], s[64:65], 0, v[130:131]
	v_lshl_add_u64 v[132:133], v[184:185], 0, v[196:197]
	v_lshl_add_u64 v[134:135], v[184:185], 0, v[194:195]
	v_lshl_add_u64 v[210:211], v[184:185], 0, v[190:191]
	v_lshl_add_u64 v[212:213], v[130:131], 0, v[128:129]
	global_load_dwordx4 v[148:151], v[132:133], off
	global_load_dwordx4 v[144:147], v[132:133], off offset:256
	global_load_dwordx4 v[140:143], v[134:135], off
	global_load_dwordx4 v[136:139], v[134:135], off offset:256
	s_nop 0
	global_load_dwordx4 v[132:135], v[210:211], off
	global_load_dwordx4 v[128:131], v[210:211], off offset:256
	s_lshl_b32 s18, s18, 2
	v_readlane_b32 s66, v254, 42
	v_readlane_b32 s67, v254, 43
	s_ashr_i32 s19, s18, 31
	v_readlane_b32 s53, v254, 29
	v_readlane_b32 s54, v254, 30
	v_readlane_b32 s55, v254, 31
	v_readlane_b32 s56, v254, 32
	v_readlane_b32 s57, v254, 33
	v_readlane_b32 s58, v254, 34
	v_readlane_b32 s59, v254, 35
	v_readlane_b32 s60, v254, 36
	v_readlane_b32 s61, v254, 37
	v_readlane_b32 s62, v254, 38
	v_readlane_b32 s63, v254, 39
	s_waitcnt vmcnt(0)
	v_lshlrev_b32_e32 v201, 16, v202
	v_and_b32_e32 v202, 0xffff0000, v202
	v_lshlrev_b32_e32 v210, 16, v203
	v_and_b32_e32 v203, 0xffff0000, v203
	v_lshlrev_b32_e32 v211, 16, v204
	v_and_b32_e32 v204, 0xffff0000, v204
	v_lshlrev_b32_e32 v214, 16, v205
	v_and_b32_e32 v205, 0xffff0000, v205
	v_lshlrev_b32_e32 v217, 16, v208
	v_and_b32_e32 v208, 0xffff0000, v208
	v_lshlrev_b32_e32 v218, 16, v209
	v_and_b32_e32 v209, 0xffff0000, v209
	v_add_f32_e32 v124, v124, v201
	v_add_f32_e32 v125, v125, v202
	v_add_f32_e32 v126, v126, v210
	v_add_f32_e32 v127, v127, v203
	v_add_f32_e32 v120, v120, v211
	v_add_f32_e32 v121, v121, v204
	v_add_f32_e32 v122, v122, v214
	v_add_f32_e32 v123, v123, v205
	v_add_f32_e32 v201, v112, v217
	v_add_f32_e32 v202, v113, v208
	v_add_f32_e32 v203, v114, v218
	v_add_f32_e32 v204, v115, v209
	v_cvt_pk_bf16_f32 v112, v124, v125
	v_cvt_pk_bf16_f32 v113, v126, v127
	v_cvt_pk_bf16_f32 v114, v120, v121
	v_cvt_pk_bf16_f32 v115, v122, v123
	global_store_dwordx4 v[212:213], v[112:115], off nt
	v_lshlrev_b32_e32 v120, 16, v112
	v_lshlrev_b32_e32 v121, 16, v113
	v_and_b32_e32 v112, 0xffff0000, v112
	v_and_b32_e32 v113, 0xffff0000, v113
	v_lshlrev_b32_e32 v122, 16, v114
	v_and_b32_e32 v114, 0xffff0000, v114
	v_lshlrev_b32_e32 v123, 16, v115
	v_and_b32_e32 v115, 0xffff0000, v115
	v_lshlrev_b32_e32 v215, 16, v206
	v_and_b32_e32 v206, 0xffff0000, v206
	v_lshlrev_b32_e32 v216, 16, v207
	v_mul_f32_e32 v112, v112, v112
	v_mul_f32_e32 v113, v113, v113
	v_mul_f32_e32 v114, v114, v114
	v_mul_f32_e32 v115, v115, v115
	v_and_b32_e32 v207, 0xffff0000, v207
	v_add_f32_e32 v116, v116, v215
	v_add_f32_e32 v117, v117, v206
	v_add_f32_e32 v118, v118, v216
	v_fmac_f32_e32 v112, v120, v120
	v_fmac_f32_e32 v113, v121, v121
	v_fmac_f32_e32 v114, v122, v122
	v_fmac_f32_e32 v115, v123, v123
	v_add_f32_e32 v119, v119, v207
	v_cvt_pk_bf16_f32 v116, v116, v117
	v_cvt_pk_bf16_f32 v117, v118, v119
	v_cvt_pk_bf16_f32 v118, v201, v202
	v_add_f32_e32 v112, v112, v113
	v_add_f32_e32 v113, v114, v115
	v_and_b32_e32 v115, 0xffff0000, v118
	v_cvt_pk_bf16_f32 v119, v203, v204
	v_and_b32_e32 v125, 0xffff0000, v116
	v_add_f32_e32 v112, v112, v113
	v_and_b32_e32 v113, 0xffff0000, v117
	v_lshlrev_b32_e32 v114, 16, v118
	v_and_b32_e32 v121, 0xffff0000, v119
	v_mul_f32_e32 v115, v115, v115
	v_lshlrev_b32_e32 v124, 16, v116
	v_lshlrev_b32_e32 v126, 16, v117
	v_lshlrev_b32_e32 v120, 16, v119
	v_mul_f32_e32 v122, v125, v125
	v_mul_f32_e32 v113, v113, v113
	v_fmac_f32_e32 v115, v114, v114
	v_mul_f32_e32 v114, v121, v121
	v_fmac_f32_e32 v122, v124, v124
	v_fmac_f32_e32 v113, v126, v126
	v_fmac_f32_e32 v114, v120, v120
	v_add_f32_e32 v113, v122, v113
	v_add_f32_e32 v114, v115, v114
	v_add_f32_e32 v113, v113, v114
	v_and_b32_e32 v114, 64, v200
	v_add_f32_e32 v113, v112, v113
	v_xor_b32_e32 v112, 16, v200
	v_add_u32_e32 v115, 64, v114
	v_cmp_lt_i32_e32 vcc, v112, v115
	global_store_dwordx4 v[212:213], v[116:119], off offset:256 nt
	s_nop 0
	v_cndmask_b32_e32 v112, v200, v112, vcc
	v_lshlrev_b32_e32 v112, 2, v112
	ds_bpermute_b32 v114, v112, v113
	s_waitcnt lgkmcnt(0)
	v_add_f32_e32 v114, v113, v114
	v_xor_b32_e32 v113, 32, v200
	v_cmp_lt_i32_e32 vcc, v113, v115
	s_nop 1
	v_cndmask_b32_e32 v113, v200, v113, vcc
	v_lshlrev_b32_e32 v113, 2, v113
	ds_bpermute_b32 v115, v113, v114
	s_and_saveexec_b64 s[26:27], s[0:1]
	s_cbranch_execz .LBB0_1319
	v_lshlrev_b64 v[116:117], 6, v[182:183]
	v_lshl_add_u64 v[116:117], s[66:67], 0, v[116:117]
	v_lshl_add_u64 v[116:117], s[18:19], 2, v[116:117]
	s_lshl_b32 s8, s46, 2
	v_lshl_add_u64 v[116:117], v[116:117], 0, s[8:9]
	s_waitcnt lgkmcnt(0)
	v_add_f32_e32 v114, v114, v115
	global_store_dword v[116:117], v114, off
; DI unsigned pk2(float lo, float hi) { unsigned r; asm volatile("v_cvt_pk_bf16_f32 %0, %1, %2" : "=v"(r) : "v"(lo), "v"(hi)); return r; }
; DI float bflo(unsigned u) { return __uint_as_float(u << 16); }
; DI float bfhi(unsigned u) { return __uint_as_float(u & 0xffff0000u); }
;     DI float upd(u32x4v* px, const u32x4v x, const f32x4 v0, const f32x4 v1) const {
;         u32x4v o; o.x = pk2(bflo(x.x) + v0[0], bfhi(x.x) + v0[1]); o.y = pk2(bflo(x.y) + v0[2], bfhi(x.y) + v0[3]);
;         o.z = pk2(bflo(x.z) + v1[0], bfhi(x.z) + v1[1]); o.w = pk2(bflo(x.w) + v1[2], bfhi(x.w) + v1[3]); *px = o;
;         const float a0 = bflo(o.x), a1 = bfhi(o.x), a2 = bflo(o.y), a3 = bfhi(o.y), a4 = bflo(o.z), a5 = bfhi(o.z), a6 = bflo(o.w), a7 = bfhi(o.w);
;         return ((a0 * a0 + a1 * a1) + (a2 * a2 + a3 * a3)) + ((a4 * a4 + a5 * a5) + (a6 * a6 + a7 * a7));
;     }
;     DI void operator()(const f32x4 (&acc)[2][2][4][2], const Unit& u, int wr, int wc, int fr, int fq, const Pre& pre) const {
;     ...
;             for (int m = 0; m < 4; ++m)
; #pragma unroll
;                 for (int bj = 0; bj < 2; ++bj) x[m][bj] = *(const u32x4v*)(XB + (size_t)(row0 + ai * 128 + m * 16) * 1024 + cb + bj * 128);
; #pragma unroll
;             for (int m = 0; m < 4; ++m) { const int row = row0 + ai * 128 + m * 16;
;                 float ss = upd((u32x4v*)(XB + (size_t)row * 1024 + cb), x[m][0], acc[ai][0][m][0], acc[ai][0][m][1])
;                          + upd((u32x4v*)(XB + (size_t)row * 1024 + cb + 128), x[m][1], acc[ai][1][m][0], acc[ai][1][m][1]);
;                 ss += __shfl_xor(ss, 16); ss += __shfl_xor(ss, 32);
;                 if (fq == 0) SSQ[(size_t)row * 16 + u.pn * 4 + wc] = ss; } }
.LBB0_1319:
	s_or_b64 exec, exec, s[26:27]
	v_lshlrev_b32_e32 v116, 16, v148
	v_add_f32_e32 v108, v108, v116
	v_and_b32_e32 v116, 0xffff0000, v148
	v_add_f32_e32 v109, v109, v116
	v_cvt_pk_bf16_f32 v108, v108, v109
	v_lshlrev_b32_e32 v109, 16, v149
	v_add_f32_e32 v109, v110, v109
	v_and_b32_e32 v110, 0xffff0000, v149
	v_add_f32_e32 v110, v111, v110
	v_cvt_pk_bf16_f32 v109, v109, v110
	v_lshlrev_b32_e32 v110, 16, v150
	v_add_f32_e32 v104, v104, v110
	v_and_b32_e32 v110, 0xffff0000, v150
	v_add_f32_e32 v105, v105, v110
	v_cvt_pk_bf16_f32 v110, v104, v105
	v_and_b32_e32 v105, 0xffff0000, v151
	v_lshlrev_b32_e32 v104, 16, v151
	v_add_f32_e32 v105, v107, v105
	v_add_f32_e32 v104, v106, v104
	v_cvt_pk_bf16_f32 v111, v104, v105
	v_and_b32_e32 v105, 0xffff0000, v108
	s_waitcnt lgkmcnt(0)
	v_lshl_add_u64 v[114:115], s[64:65], 0, v[196:197]
	v_lshlrev_b32_e32 v104, 16, v108
	v_and_b32_e32 v107, 0xffff0000, v109
	v_mul_f32_e32 v105, v105, v105
	v_lshl_add_u64 v[114:115], v[180:181], 1, v[114:115]
	v_lshlrev_b32_e32 v106, 16, v109
	v_fmac_f32_e32 v105, v104, v104
	v_mul_f32_e32 v104, v107, v107
	global_store_dwordx4 v[114:115], v[108:111], off nt
	v_fmac_f32_e32 v104, v106, v106
	v_add_f32_e32 v104, v105, v104
	v_lshlrev_b32_e32 v108, 16, v110
	v_and_b32_e32 v109, 0xffff0000, v110
	v_lshlrev_b32_e32 v110, 16, v111
	v_and_b32_e32 v111, 0xffff0000, v111
	v_mul_f32_e32 v105, v109, v109
	v_mul_f32_e32 v106, v111, v111
	v_fmac_f32_e32 v105, v108, v108
	v_fmac_f32_e32 v106, v110, v110
	v_add_f32_e32 v105, v105, v106
	v_add_f32_e32 v104, v104, v105
	v_lshlrev_b32_e32 v105, 16, v144
	v_add_f32_e32 v100, v100, v105
	v_and_b32_e32 v105, 0xffff0000, v144
	v_add_f32_e32 v101, v101, v105
	v_cvt_pk_bf16_f32 v100, v100, v101
	v_lshlrev_b32_e32 v101, 16, v145
	v_add_f32_e32 v101, v102, v101
	v_and_b32_e32 v102, 0xffff0000, v145
	v_add_f32_e32 v102, v103, v102
	v_cvt_pk_bf16_f32 v101, v101, v102
	v_lshlrev_b32_e32 v102, 16, v146
	v_add_f32_e32 v96, v96, v102
	v_and_b32_e32 v102, 0xffff0000, v146
	v_add_f32_e32 v97, v97, v102
	v_cvt_pk_bf16_f32 v102, v96, v97
	v_and_b32_e32 v97, 0xffff0000, v147
	v_lshlrev_b32_e32 v96, 16, v147
	v_add_f32_e32 v97, v99, v97
	v_add_f32_e32 v96, v98, v96
	v_cvt_pk_bf16_f32 v103, v96, v97
	v_and_b32_e32 v97, 0xffff0000, v100
	v_lshlrev_b32_e32 v96, 16, v100
	v_and_b32_e32 v99, 0xffff0000, v101
	v_mul_f32_e32 v97, v97, v97
	v_lshlrev_b32_e32 v98, 16, v101
	v_fmac_f32_e32 v97, v96, v96
	v_mul_f32_e32 v96, v99, v99
	v_and_b32_e32 v106, 0xffff0000, v102
	v_and_b32_e32 v108, 0xffff0000, v103
	v_fmac_f32_e32 v96, v98, v98
	v_lshlrev_b32_e32 v105, 16, v102
	v_lshlrev_b32_e32 v107, 16, v103
	v_add_f32_e32 v96, v97, v96
	v_mul_f32_e32 v97, v106, v106
	v_mul_f32_e32 v98, v108, v108
	v_fmac_f32_e32 v97, v105, v105
	v_fmac_f32_e32 v98, v107, v107
	v_add_f32_e32 v97, v97, v98
	v_add_f32_e32 v96, v96, v97
	v_add_f32_e32 v96, v104, v96
	ds_bpermute_b32 v97, v112, v96
	global_store_dwordx4 v[114:115], v[100:103], off offset:256 nt
	s_waitcnt lgkmcnt(0)
	v_add_f32_e32 v96, v96, v97
	ds_bpermute_b32 v97, v113, v96
	s_and_saveexec_b64 s[26:27], s[0:1]
	s_cbranch_execz .LBB0_1321
	v_lshlrev_b64 v[98:99], 6, v[192:193]
	v_lshl_add_u64 v[98:99], s[66:67], 0, v[98:99]
	v_lshl_add_u64 v[98:99], s[18:19], 2, v[98:99]
	s_lshl_b32 s8, s46, 2
	v_lshl_add_u64 v[98:99], v[98:99], 0, s[8:9]
	s_waitcnt lgkmcnt(0)
	v_add_f32_e32 v96, v96, v97
	global_store_dword v[98:99], v96, off
.LBB0_1321:
	s_or_b64 exec, exec, s[26:27]
	v_lshlrev_b32_e32 v98, 16, v140
	v_add_f32_e32 v92, v92, v98
	v_and_b32_e32 v98, 0xffff0000, v140
	v_add_f32_e32 v93, v93, v98
	v_cvt_pk_bf16_f32 v92, v92, v93
	v_lshlrev_b32_e32 v93, 16, v141
	v_add_f32_e32 v93, v94, v93
	v_and_b32_e32 v94, 0xffff0000, v141
	v_add_f32_e32 v94, v95, v94
	v_cvt_pk_bf16_f32 v93, v93, v94
	v_lshlrev_b32_e32 v94, 16, v142
	v_add_f32_e32 v88, v88, v94
	v_and_b32_e32 v94, 0xffff0000, v142
	v_add_f32_e32 v89, v89, v94
	v_cvt_pk_bf16_f32 v94, v88, v89
	v_and_b32_e32 v89, 0xffff0000, v143
	v_lshlrev_b32_e32 v88, 16, v143
	v_add_f32_e32 v89, v91, v89
	v_add_f32_e32 v88, v90, v88
	v_cvt_pk_bf16_f32 v95, v88, v89
	v_and_b32_e32 v89, 0xffff0000, v92
	s_waitcnt lgkmcnt(0)
	v_lshl_add_u64 v[96:97], s[64:65], 0, v[194:195]
	v_lshlrev_b32_e32 v88, 16, v92
	v_and_b32_e32 v91, 0xffff0000, v93
	v_mul_f32_e32 v89, v89, v89
	v_lshl_add_u64 v[96:97], v[180:181], 1, v[96:97]
	v_lshlrev_b32_e32 v90, 16, v93
	v_fmac_f32_e32 v89, v88, v88
	v_mul_f32_e32 v88, v91, v91
	global_store_dwordx4 v[96:97], v[92:95], off nt
	v_fmac_f32_e32 v88, v90, v90
	v_add_f32_e32 v88, v89, v88
	v_lshlrev_b32_e32 v92, 16, v94
	v_and_b32_e32 v93, 0xffff0000, v94
	v_lshlrev_b32_e32 v94, 16, v95
	v_and_b32_e32 v95, 0xffff0000, v95
	v_mul_f32_e32 v89, v93, v93
	v_mul_f32_e32 v90, v95, v95
	v_fmac_f32_e32 v89, v92, v92
	v_fmac_f32_e32 v90, v94, v94
	v_add_f32_e32 v89, v89, v90
	v_add_f32_e32 v88, v88, v89
	v_lshlrev_b32_e32 v89, 16, v136
	v_add_f32_e32 v84, v84, v89
	v_and_b32_e32 v89, 0xffff0000, v136
	v_add_f32_e32 v85, v85, v89
	v_cvt_pk_bf16_f32 v84, v84, v85
	v_lshlrev_b32_e32 v85, 16, v137
	v_add_f32_e32 v85, v86, v85
	v_and_b32_e32 v86, 0xffff0000, v137
	v_add_f32_e32 v86, v87, v86
	v_cvt_pk_bf16_f32 v85, v85, v86
	v_lshlrev_b32_e32 v86, 16, v138
	v_add_f32_e32 v80, v80, v86
	v_and_b32_e32 v86, 0xffff0000, v138
	v_add_f32_e32 v81, v81, v86
	v_cvt_pk_bf16_f32 v86, v80, v81
	v_and_b32_e32 v81, 0xffff0000, v139
	v_lshlrev_b32_e32 v80, 16, v139
	v_add_f32_e32 v81, v83, v81
	v_add_f32_e32 v80, v82, v80
	v_cvt_pk_bf16_f32 v87, v80, v81
	v_and_b32_e32 v81, 0xffff0000, v84
	v_lshlrev_b32_e32 v80, 16, v84
	v_and_b32_e32 v83, 0xffff0000, v85
	v_mul_f32_e32 v81, v81, v81
	v_lshlrev_b32_e32 v82, 16, v85
	v_fmac_f32_e32 v81, v80, v80
	v_mul_f32_e32 v80, v83, v83
	v_and_b32_e32 v90, 0xffff0000, v86
	v_and_b32_e32 v92, 0xffff0000, v87
	v_fmac_f32_e32 v80, v82, v82
	v_lshlrev_b32_e32 v89, 16, v86
	v_lshlrev_b32_e32 v91, 16, v87
	v_add_f32_e32 v80, v81, v80
	v_mul_f32_e32 v81, v90, v90
	v_mul_f32_e32 v82, v92, v92
	v_fmac_f32_e32 v81, v89, v89
	v_fmac_f32_e32 v82, v91, v91
	v_add_f32_e32 v81, v81, v82
	v_add_f32_e32 v80, v80, v81
	v_add_f32_e32 v80, v88, v80
	ds_bpermute_b32 v81, v112, v80
	global_store_dwordx4 v[96:97], v[84:87], off offset:256 nt
	s_waitcnt lgkmcnt(0)
	v_add_f32_e32 v80, v80, v81
	ds_bpermute_b32 v81, v113, v80
	s_and_saveexec_b64 s[26:27], s[0:1]
	s_cbranch_execz .LBB0_1323
	v_lshlrev_b64 v[82:83], 6, v[188:189]
	v_lshl_add_u64 v[82:83], s[66:67], 0, v[82:83]
	v_lshl_add_u64 v[82:83], s[18:19], 2, v[82:83]
	s_lshl_b32 s8, s46, 2
	v_lshl_add_u64 v[82:83], v[82:83], 0, s[8:9]
	s_waitcnt lgkmcnt(0)
	v_add_f32_e32 v80, v80, v81
	global_store_dword v[82:83], v80, off
; DI unsigned pk2(float lo, float hi) { unsigned r; asm volatile("v_cvt_pk_bf16_f32 %0, %1, %2" : "=v"(r) : "v"(lo), "v"(hi)); return r; }
; DI float bflo(unsigned u) { return __uint_as_float(u << 16); }
; DI float bfhi(unsigned u) { return __uint_as_float(u & 0xffff0000u); }
;     DI float upd(u32x4v* px, const u32x4v x, const f32x4 v0, const f32x4 v1) const {
;         u32x4v o; o.x = pk2(bflo(x.x) + v0[0], bfhi(x.x) + v0[1]); o.y = pk2(bflo(x.y) + v0[2], bfhi(x.y) + v0[3]);
;         o.z = pk2(bflo(x.z) + v1[0], bfhi(x.z) + v1[1]); o.w = pk2(bflo(x.w) + v1[2], bfhi(x.w) + v1[3]); *px = o;
;         const float a0 = bflo(o.x), a1 = bfhi(o.x), a2 = bflo(o.y), a3 = bfhi(o.y), a4 = bflo(o.z), a5 = bfhi(o.z), a6 = bflo(o.w), a7 = bfhi(o.w);
;         return ((a0 * a0 + a1 * a1) + (a2 * a2 + a3 * a3)) + ((a4 * a4 + a5 * a5) + (a6 * a6 + a7 * a7));
;     }
;     DI void operator()(const f32x4 (&acc)[2][2][4][2], const Unit& u, int wr, int wc, int fr, int fq, const Pre& pre) const {
;     ...
;             for (int m = 0; m < 4; ++m)
; #pragma unroll
;                 for (int bj = 0; bj < 2; ++bj) x[m][bj] = *(const u32x4v*)(XB + (size_t)(row0 + ai * 128 + m * 16) * 1024 + cb + bj * 128);
; #pragma unroll
;             for (int m = 0; m < 4; ++m) { const int row = row0 + ai * 128 + m * 16;
;                 float ss = upd((u32x4v*)(XB + (size_t)row * 1024 + cb), x[m][0], acc[ai][0][m][0], acc[ai][0][m][1])
;                          + upd((u32x4v*)(XB + (size_t)row * 1024 + cb + 128), x[m][1], acc[ai][1][m][0], acc[ai][1][m][1]);
;                 ss += __shfl_xor(ss, 16); ss += __shfl_xor(ss, 32);
;                 if (fq == 0) SSQ[(size_t)row * 16 + u.pn * 4 + wc] = ss; } }
.LBB0_1323:
	s_or_b64 exec, exec, s[26:27]
	v_lshlrev_b32_e32 v82, 16, v132
	v_add_f32_e32 v76, v76, v82
	v_and_b32_e32 v82, 0xffff0000, v132
	v_add_f32_e32 v77, v77, v82
	v_cvt_pk_bf16_f32 v76, v76, v77
	v_lshlrev_b32_e32 v77, 16, v133
	v_add_f32_e32 v77, v78, v77
	v_and_b32_e32 v78, 0xffff0000, v133
	v_add_f32_e32 v78, v79, v78
	v_cvt_pk_bf16_f32 v77, v77, v78
	v_lshlrev_b32_e32 v78, 16, v134
	v_add_f32_e32 v72, v72, v78
	v_and_b32_e32 v78, 0xffff0000, v134
	v_add_f32_e32 v73, v73, v78
	v_cvt_pk_bf16_f32 v78, v72, v73
	v_and_b32_e32 v73, 0xffff0000, v135
	v_lshlrev_b32_e32 v72, 16, v135
	v_add_f32_e32 v73, v75, v73
	v_add_f32_e32 v72, v74, v72
	v_cvt_pk_bf16_f32 v79, v72, v73
	v_and_b32_e32 v73, 0xffff0000, v76
	s_waitcnt lgkmcnt(0)
	v_lshl_add_u64 v[80:81], s[64:65], 0, v[190:191]
	v_lshlrev_b32_e32 v72, 16, v76
	v_and_b32_e32 v75, 0xffff0000, v77
	v_mul_f32_e32 v73, v73, v73
	v_lshl_add_u64 v[80:81], v[180:181], 1, v[80:81]
	v_lshlrev_b32_e32 v74, 16, v77
	v_fmac_f32_e32 v73, v72, v72
	v_mul_f32_e32 v72, v75, v75
	global_store_dwordx4 v[80:81], v[76:79], off nt
	v_fmac_f32_e32 v72, v74, v74
	v_add_f32_e32 v72, v73, v72
	v_lshlrev_b32_e32 v76, 16, v78
	v_and_b32_e32 v77, 0xffff0000, v78
	v_lshlrev_b32_e32 v78, 16, v79
	v_and_b32_e32 v79, 0xffff0000, v79
	v_mul_f32_e32 v73, v77, v77
	v_mul_f32_e32 v74, v79, v79
	v_fmac_f32_e32 v73, v76, v76
	v_fmac_f32_e32 v74, v78, v78
	v_add_f32_e32 v73, v73, v74
	v_add_f32_e32 v72, v72, v73
	v_lshlrev_b32_e32 v73, 16, v128
	v_add_f32_e32 v68, v68, v73
	v_and_b32_e32 v73, 0xffff0000, v128
	v_add_f32_e32 v69, v69, v73
	v_cvt_pk_bf16_f32 v68, v68, v69
	v_lshlrev_b32_e32 v69, 16, v129
	v_add_f32_e32 v69, v70, v69
	v_and_b32_e32 v70, 0xffff0000, v129
	v_add_f32_e32 v70, v71, v70
	v_cvt_pk_bf16_f32 v69, v69, v70
	v_lshlrev_b32_e32 v70, 16, v130
	v_add_f32_e32 v64, v64, v70
	v_and_b32_e32 v70, 0xffff0000, v130
	v_add_f32_e32 v65, v65, v70
	v_cvt_pk_bf16_f32 v70, v64, v65
	v_and_b32_e32 v65, 0xffff0000, v131
	v_lshlrev_b32_e32 v64, 16, v131
	v_add_f32_e32 v65, v67, v65
	v_add_f32_e32 v64, v66, v64
	v_cvt_pk_bf16_f32 v71, v64, v65
	v_and_b32_e32 v65, 0xffff0000, v68
	v_lshlrev_b32_e32 v64, 16, v68
	v_and_b32_e32 v67, 0xffff0000, v69
	v_mul_f32_e32 v65, v65, v65
	v_lshlrev_b32_e32 v66, 16, v69
	v_fmac_f32_e32 v65, v64, v64
	v_mul_f32_e32 v64, v67, v67
	v_and_b32_e32 v74, 0xffff0000, v70
	v_and_b32_e32 v76, 0xffff0000, v71
	v_fmac_f32_e32 v64, v66, v66
	v_lshlrev_b32_e32 v73, 16, v70
	v_lshlrev_b32_e32 v75, 16, v71
	v_add_f32_e32 v64, v65, v64
	v_mul_f32_e32 v65, v74, v74
	v_mul_f32_e32 v66, v76, v76
	v_fmac_f32_e32 v65, v73, v73
	v_fmac_f32_e32 v66, v75, v75
	v_add_f32_e32 v65, v65, v66
	v_add_f32_e32 v64, v64, v65
	v_add_f32_e32 v64, v72, v64
	ds_bpermute_b32 v65, v112, v64
	global_store_dwordx4 v[80:81], v[68:71], off offset:256 nt
	s_waitcnt lgkmcnt(0)
	v_add_f32_e32 v64, v64, v65
	ds_bpermute_b32 v65, v113, v64
	s_and_saveexec_b64 s[26:27], s[0:1]
	s_cbranch_execz .LBB0_1325
	v_lshlrev_b64 v[66:67], 6, v[186:187]
	v_lshl_add_u64 v[66:67], s[66:67], 0, v[66:67]
	v_lshl_add_u64 v[66:67], s[18:19], 2, v[66:67]
	s_lshl_b32 s8, s46, 2
	v_lshl_add_u64 v[66:67], v[66:67], 0, s[8:9]
	s_waitcnt lgkmcnt(0)
	v_add_f32_e32 v64, v64, v65
	global_store_dword v[66:67], v64, off
.LBB0_1325:
	s_or_b64 exec, exec, s[26:27]
	v_add_u32_e32 v98, 0x80, v182
	v_ashrrev_i32_e32 v99, 31, v98
	s_waitcnt lgkmcnt(0)
	v_lshlrev_b64 v[64:65], 11, v[98:99]
	v_lshl_add_u64 v[66:67], v[184:185], 0, v[64:65]
	global_load_dwordx4 v[102:105], v[66:67], off
	global_load_dwordx4 v[106:109], v[66:67], off offset:256
	v_add_u32_e32 v94, 0x90, v182
	v_add_u32_e32 v90, 0xa0, v182
	v_add_u32_e32 v88, 0xb0, v182
	v_ashrrev_i32_e32 v95, 31, v94
	v_ashrrev_i32_e32 v91, 31, v90
	v_ashrrev_i32_e32 v89, 31, v88
	v_lshlrev_b64 v[100:101], 11, v[94:95]
	v_lshlrev_b64 v[96:97], 11, v[90:91]
	v_lshlrev_b64 v[92:93], 11, v[88:89]
	v_lshl_add_u64 v[66:67], v[184:185], 0, v[100:101]
	v_lshl_add_u64 v[68:69], v[184:185], 0, v[96:97]
	v_lshl_add_u64 v[110:111], v[184:185], 0, v[92:93]
	v_lshl_add_u64 v[114:115], s[64:65], 0, v[64:65]
	global_load_dwordx4 v[84:87], v[66:67], off
	global_load_dwordx4 v[80:83], v[66:67], off offset:256
	global_load_dwordx4 v[76:79], v[68:69], off
	global_load_dwordx4 v[72:75], v[68:69], off offset:256
	s_nop 0
	global_load_dwordx4 v[68:71], v[110:111], off
	global_load_dwordx4 v[64:67], v[110:111], off offset:256
	v_lshl_add_u64 v[110:111], v[180:181], 1, v[114:115]
	s_waitcnt vmcnt(7)
	v_lshlrev_b32_e32 v114, 16, v102
	v_and_b32_e32 v102, 0xffff0000, v102
	v_lshlrev_b32_e32 v115, 16, v103
	v_and_b32_e32 v103, 0xffff0000, v103
	v_lshlrev_b32_e32 v116, 16, v104
	v_and_b32_e32 v104, 0xffff0000, v104
	v_lshlrev_b32_e32 v117, 16, v105
	v_and_b32_e32 v105, 0xffff0000, v105
	s_waitcnt vmcnt(6)
; DI unsigned pk2(float lo, float hi) { unsigned r; asm volatile("v_cvt_pk_bf16_f32 %0, %1, %2" : "=v"(r) : "v"(lo), "v"(hi)); return r; }
; DI float bflo(unsigned u) { return __uint_as_float(u << 16); }
; DI float bfhi(unsigned u) { return __uint_as_float(u & 0xffff0000u); }
;     DI float upd(u32x4v* px, const u32x4v x, const f32x4 v0, const f32x4 v1) const {
;         u32x4v o; o.x = pk2(bflo(x.x) + v0[0], bfhi(x.x) + v0[1]); o.y = pk2(bflo(x.y) + v0[2], bfhi(x.y) + v0[3]);
;         o.z = pk2(bflo(x.z) + v1[0], bfhi(x.z) + v1[1]); o.w = pk2(bflo(x.w) + v1[2], bfhi(x.w) + v1[3]); *px = o;
;         const float a0 = bflo(o.x), a1 = bfhi(o.x), a2 = bflo(o.y), a3 = bfhi(o.y), a4 = bflo(o.z), a5 = bfhi(o.z), a6 = bflo(o.w), a7 = bfhi(o.w);
;         return ((a0 * a0 + a1 * a1) + (a2 * a2 + a3 * a3)) + ((a4 * a4 + a5 * a5) + (a6 * a6 + a7 * a7));
;     }
;     DI void operator()(const f32x4 (&acc)[2][2][4][2], const Unit& u, int wr, int wc, int fr, int fq, const Pre& pre) const {
;     ...
;             for (int m = 0; m < 4; ++m)
; #pragma unroll
;                 for (int bj = 0; bj < 2; ++bj) x[m][bj] = *(const u32x4v*)(XB + (size_t)(row0 + ai * 128 + m * 16) * 1024 + cb + bj * 128);
; #pragma unroll
;             for (int m = 0; m < 4; ++m) { const int row = row0 + ai * 128 + m * 16;
;                 float ss = upd((u32x4v*)(XB + (size_t)row * 1024 + cb), x[m][0], acc[ai][0][m][0], acc[ai][0][m][1])
;                          + upd((u32x4v*)(XB + (size_t)row * 1024 + cb + 128), x[m][1], acc[ai][1][m][0], acc[ai][1][m][1]);
;                 ss += __shfl_xor(ss, 16); ss += __shfl_xor(ss, 32);
;                 if (fq == 0) SSQ[(size_t)row * 16 + u.pn * 4 + wc] = ss; } }
	v_lshlrev_b32_e32 v120, 16, v108
	v_and_b32_e32 v108, 0xffff0000, v108
	v_lshlrev_b32_e32 v119, 16, v107
	v_and_b32_e32 v107, 0xffff0000, v107
	v_lshlrev_b32_e32 v121, 16, v109
	v_and_b32_e32 v109, 0xffff0000, v109
	v_add_f32_e32 v60, v60, v114
	v_add_f32_e32 v61, v61, v102
	v_add_f32_e32 v62, v62, v115
	v_add_f32_e32 v63, v63, v103
	v_add_f32_e32 v56, v56, v116
	v_add_f32_e32 v57, v57, v104
	v_add_f32_e32 v59, v59, v105
	v_add_f32_e32 v102, v48, v120
	v_add_f32_e32 v103, v49, v108
	v_cvt_pk_bf16_f32 v48, v60, v61
	v_cvt_pk_bf16_f32 v49, v62, v63
	v_lshlrev_b32_e32 v118, 16, v106
	v_and_b32_e32 v106, 0xffff0000, v106
	v_add_f32_e32 v58, v58, v117
	v_add_f32_e32 v54, v54, v119
	v_add_f32_e32 v55, v55, v107
	v_add_f32_e32 v104, v50, v121
	v_add_f32_e32 v105, v51, v109
	v_cvt_pk_bf16_f32 v50, v56, v57
	v_cvt_pk_bf16_f32 v51, v58, v59
	global_store_dwordx4 v[110:111], v[48:51], off nt
	v_lshlrev_b32_e32 v56, 16, v48
	v_lshlrev_b32_e32 v57, 16, v49
	v_and_b32_e32 v48, 0xffff0000, v48
	v_and_b32_e32 v49, 0xffff0000, v49
	v_and_b32_e32 v59, 0xffff0000, v50
	v_and_b32_e32 v61, 0xffff0000, v51
	v_add_f32_e32 v52, v52, v118
	v_add_f32_e32 v53, v53, v106
	v_lshlrev_b32_e32 v58, 16, v50
	v_lshlrev_b32_e32 v60, 16, v51
	v_cvt_pk_bf16_f32 v50, v52, v53
	v_cvt_pk_bf16_f32 v51, v54, v55
	v_mul_f32_e32 v48, v48, v48
	v_mul_f32_e32 v49, v49, v49
	v_mul_f32_e32 v54, v59, v59
	v_mul_f32_e32 v55, v61, v61
	v_and_b32_e32 v61, 0xffff0000, v50
	v_and_b32_e32 v63, 0xffff0000, v51
	v_fmac_f32_e32 v48, v56, v56
	v_fmac_f32_e32 v49, v57, v57
	v_fmac_f32_e32 v54, v58, v58
	v_fmac_f32_e32 v55, v60, v60
	v_lshlrev_b32_e32 v59, 16, v50
	v_lshlrev_b32_e32 v62, 16, v51
	v_add_f32_e32 v48, v48, v49
	v_add_f32_e32 v49, v54, v55
	v_mul_f32_e32 v55, v61, v61
	v_mul_f32_e32 v56, v63, v63
	v_cvt_pk_bf16_f32 v52, v102, v103
	v_cvt_pk_bf16_f32 v53, v104, v105
	v_fmac_f32_e32 v55, v59, v59
	v_and_b32_e32 v103, 0xffff0000, v52
	v_and_b32_e32 v54, 0xffff0000, v53
	v_fmac_f32_e32 v56, v62, v62
	v_lshlrev_b32_e32 v102, 16, v52
	v_add_f32_e32 v48, v48, v49
	v_lshlrev_b32_e32 v49, 16, v53
	v_add_f32_e32 v55, v55, v56
	v_mul_f32_e32 v56, v103, v103
	v_mul_f32_e32 v54, v54, v54
	v_fmac_f32_e32 v56, v102, v102
	v_fmac_f32_e32 v54, v49, v49
	v_add_f32_e32 v49, v56, v54
	v_add_f32_e32 v49, v55, v49
	v_add_f32_e32 v48, v48, v49
	ds_bpermute_b32 v49, v112, v48
	global_store_dwordx4 v[110:111], v[50:53], off offset:256 nt
	s_waitcnt lgkmcnt(0)
	v_add_f32_e32 v48, v48, v49
	ds_bpermute_b32 v49, v113, v48
	s_and_saveexec_b64 s[26:27], s[0:1]
	s_cbranch_execz .LBB0_1327
	v_lshlrev_b64 v[50:51], 6, v[98:99]
	v_lshl_add_u64 v[50:51], s[66:67], 0, v[50:51]
	v_lshl_add_u64 v[50:51], s[18:19], 2, v[50:51]
	s_lshl_b32 s8, s46, 2
	v_lshl_add_u64 v[50:51], v[50:51], 0, s[8:9]
	s_waitcnt lgkmcnt(0)
	v_add_f32_e32 v48, v48, v49
	global_store_dword v[50:51], v48, off
.LBB0_1327:
	s_or_b64 exec, exec, s[26:27]
	s_waitcnt vmcnt(7)
	v_lshlrev_b32_e32 v50, 16, v84
	v_add_f32_e32 v44, v44, v50
	v_and_b32_e32 v50, 0xffff0000, v84
	v_add_f32_e32 v45, v45, v50
	v_cvt_pk_bf16_f32 v44, v44, v45
	v_lshlrev_b32_e32 v45, 16, v85
	v_add_f32_e32 v45, v46, v45
	v_and_b32_e32 v46, 0xffff0000, v85
	v_add_f32_e32 v46, v47, v46
	v_cvt_pk_bf16_f32 v45, v45, v46
	v_lshlrev_b32_e32 v46, 16, v86
	v_add_f32_e32 v40, v40, v46
	v_and_b32_e32 v46, 0xffff0000, v86
	v_add_f32_e32 v41, v41, v46
	v_cvt_pk_bf16_f32 v46, v40, v41
	v_and_b32_e32 v41, 0xffff0000, v87
	v_lshlrev_b32_e32 v40, 16, v87
	v_add_f32_e32 v41, v43, v41
	v_add_f32_e32 v40, v42, v40
	v_cvt_pk_bf16_f32 v47, v40, v41
	v_and_b32_e32 v41, 0xffff0000, v44
	s_waitcnt lgkmcnt(0)
	v_lshl_add_u64 v[48:49], s[64:65], 0, v[100:101]
	v_lshlrev_b32_e32 v40, 16, v44
	v_and_b32_e32 v43, 0xffff0000, v45
	v_mul_f32_e32 v41, v41, v41
	v_lshl_add_u64 v[48:49], v[180:181], 1, v[48:49]
	v_lshlrev_b32_e32 v42, 16, v45
	v_fmac_f32_e32 v41, v40, v40
	v_mul_f32_e32 v40, v43, v43
	global_store_dwordx4 v[48:49], v[44:47], off nt
	v_fmac_f32_e32 v40, v42, v42
	v_add_f32_e32 v40, v41, v40
	v_lshlrev_b32_e32 v44, 16, v46
	v_and_b32_e32 v45, 0xffff0000, v46
	v_lshlrev_b32_e32 v46, 16, v47
	v_and_b32_e32 v47, 0xffff0000, v47
	v_mul_f32_e32 v41, v45, v45
	v_mul_f32_e32 v42, v47, v47
	v_fmac_f32_e32 v41, v44, v44
	v_fmac_f32_e32 v42, v46, v46
	v_add_f32_e32 v41, v41, v42
	v_add_f32_e32 v40, v40, v41
	s_waitcnt vmcnt(7)
	v_lshlrev_b32_e32 v41, 16, v80
	v_add_f32_e32 v36, v36, v41
	v_and_b32_e32 v41, 0xffff0000, v80
	v_add_f32_e32 v37, v37, v41
	v_cvt_pk_bf16_f32 v36, v36, v37
	v_lshlrev_b32_e32 v37, 16, v81
	v_add_f32_e32 v37, v38, v37
	v_and_b32_e32 v38, 0xffff0000, v81
	v_add_f32_e32 v38, v39, v38
	v_cvt_pk_bf16_f32 v37, v37, v38
	v_lshlrev_b32_e32 v38, 16, v82
	v_add_f32_e32 v32, v32, v38
	v_and_b32_e32 v38, 0xffff0000, v82
	v_add_f32_e32 v33, v33, v38
	v_cvt_pk_bf16_f32 v38, v32, v33
	v_and_b32_e32 v33, 0xffff0000, v83
	v_lshlrev_b32_e32 v32, 16, v83
	v_add_f32_e32 v33, v35, v33
	v_add_f32_e32 v32, v34, v32
	v_cvt_pk_bf16_f32 v39, v32, v33
	v_and_b32_e32 v33, 0xffff0000, v36
	v_lshlrev_b32_e32 v32, 16, v36
	v_and_b32_e32 v35, 0xffff0000, v37
	v_mul_f32_e32 v33, v33, v33
	v_lshlrev_b32_e32 v34, 16, v37
	v_fmac_f32_e32 v33, v32, v32
	v_mul_f32_e32 v32, v35, v35
	v_and_b32_e32 v42, 0xffff0000, v38
	v_and_b32_e32 v44, 0xffff0000, v39
	v_fmac_f32_e32 v32, v34, v34
	v_lshlrev_b32_e32 v41, 16, v38
	v_lshlrev_b32_e32 v43, 16, v39
	v_add_f32_e32 v32, v33, v32
	v_mul_f32_e32 v33, v42, v42
	v_mul_f32_e32 v34, v44, v44
	v_fmac_f32_e32 v33, v41, v41
	v_fmac_f32_e32 v34, v43, v43
	v_add_f32_e32 v33, v33, v34
	v_add_f32_e32 v32, v32, v33
	v_add_f32_e32 v32, v40, v32
	ds_bpermute_b32 v33, v112, v32
	global_store_dwordx4 v[48:49], v[36:39], off offset:256 nt
	s_waitcnt lgkmcnt(0)
	v_add_f32_e32 v32, v32, v33
	ds_bpermute_b32 v33, v113, v32
	s_and_saveexec_b64 s[26:27], s[0:1]
	s_cbranch_execz .LBB0_1329
	v_lshlrev_b64 v[34:35], 6, v[94:95]
	v_lshl_add_u64 v[34:35], s[66:67], 0, v[34:35]
	v_lshl_add_u64 v[34:35], s[18:19], 2, v[34:35]
	s_lshl_b32 s8, s46, 2
	v_lshl_add_u64 v[34:35], v[34:35], 0, s[8:9]
	s_waitcnt lgkmcnt(0)
	v_add_f32_e32 v32, v32, v33
	global_store_dword v[34:35], v32, off
; DI unsigned pk2(float lo, float hi) { unsigned r; asm volatile("v_cvt_pk_bf16_f32 %0, %1, %2" : "=v"(r) : "v"(lo), "v"(hi)); return r; }
; DI float bflo(unsigned u) { return __uint_as_float(u << 16); }
; DI float bfhi(unsigned u) { return __uint_as_float(u & 0xffff0000u); }
;     DI float upd(u32x4v* px, const u32x4v x, const f32x4 v0, const f32x4 v1) const {
;         u32x4v o; o.x = pk2(bflo(x.x) + v0[0], bfhi(x.x) + v0[1]); o.y = pk2(bflo(x.y) + v0[2], bfhi(x.y) + v0[3]);
;         o.z = pk2(bflo(x.z) + v1[0], bfhi(x.z) + v1[1]); o.w = pk2(bflo(x.w) + v1[2], bfhi(x.w) + v1[3]); *px = o;
;         const float a0 = bflo(o.x), a1 = bfhi(o.x), a2 = bflo(o.y), a3 = bfhi(o.y), a4 = bflo(o.z), a5 = bfhi(o.z), a6 = bflo(o.w), a7 = bfhi(o.w);
;         return ((a0 * a0 + a1 * a1) + (a2 * a2 + a3 * a3)) + ((a4 * a4 + a5 * a5) + (a6 * a6 + a7 * a7));
;     }
;     DI void operator()(const f32x4 (&acc)[2][2][4][2], const Unit& u, int wr, int wc, int fr, int fq, const Pre& pre) const {
;     ...
;             for (int m = 0; m < 4; ++m)
; #pragma unroll
;                 for (int bj = 0; bj < 2; ++bj) x[m][bj] = *(const u32x4v*)(XB + (size_t)(row0 + ai * 128 + m * 16) * 1024 + cb + bj * 128);
; #pragma unroll
;             for (int m = 0; m < 4; ++m) { const int row = row0 + ai * 128 + m * 16;
;                 float ss = upd((u32x4v*)(XB + (size_t)row * 1024 + cb), x[m][0], acc[ai][0][m][0], acc[ai][0][m][1])
;                          + upd((u32x4v*)(XB + (size_t)row * 1024 + cb + 128), x[m][1], acc[ai][1][m][0], acc[ai][1][m][1]);
;                 ss += __shfl_xor(ss, 16); ss += __shfl_xor(ss, 32);
;                 if (fq == 0) SSQ[(size_t)row * 16 + u.pn * 4 + wc] = ss; } }
.LBB0_1329:
	s_or_b64 exec, exec, s[26:27]
	s_waitcnt vmcnt(7)
	v_lshlrev_b32_e32 v34, 16, v76
	v_add_f32_e32 v28, v28, v34
	v_and_b32_e32 v34, 0xffff0000, v76
	v_add_f32_e32 v29, v29, v34
	v_cvt_pk_bf16_f32 v28, v28, v29
	v_lshlrev_b32_e32 v29, 16, v77
	v_add_f32_e32 v29, v30, v29
	v_and_b32_e32 v30, 0xffff0000, v77
	v_add_f32_e32 v30, v31, v30
	v_cvt_pk_bf16_f32 v29, v29, v30
	v_lshlrev_b32_e32 v30, 16, v78
	v_add_f32_e32 v24, v24, v30
	v_and_b32_e32 v30, 0xffff0000, v78
	v_add_f32_e32 v25, v25, v30
	v_cvt_pk_bf16_f32 v30, v24, v25
	v_and_b32_e32 v25, 0xffff0000, v79
	v_lshlrev_b32_e32 v24, 16, v79
	v_add_f32_e32 v25, v27, v25
	v_add_f32_e32 v24, v26, v24
	v_cvt_pk_bf16_f32 v31, v24, v25
	v_and_b32_e32 v25, 0xffff0000, v28
	s_waitcnt lgkmcnt(0)
	v_lshl_add_u64 v[32:33], s[64:65], 0, v[96:97]
	v_lshlrev_b32_e32 v24, 16, v28
	v_and_b32_e32 v27, 0xffff0000, v29
	v_mul_f32_e32 v25, v25, v25
	v_lshl_add_u64 v[32:33], v[180:181], 1, v[32:33]
	v_lshlrev_b32_e32 v26, 16, v29
	v_fmac_f32_e32 v25, v24, v24
	v_mul_f32_e32 v24, v27, v27
	global_store_dwordx4 v[32:33], v[28:31], off nt
	v_fmac_f32_e32 v24, v26, v26
	v_add_f32_e32 v24, v25, v24
	v_lshlrev_b32_e32 v28, 16, v30
	v_and_b32_e32 v29, 0xffff0000, v30
	v_lshlrev_b32_e32 v30, 16, v31
	v_and_b32_e32 v31, 0xffff0000, v31
	v_mul_f32_e32 v25, v29, v29
	v_mul_f32_e32 v26, v31, v31
	v_fmac_f32_e32 v25, v28, v28
	v_fmac_f32_e32 v26, v30, v30
	v_add_f32_e32 v25, v25, v26
	v_add_f32_e32 v24, v24, v25
	s_waitcnt vmcnt(7)
	v_lshlrev_b32_e32 v25, 16, v72
	v_add_f32_e32 v20, v20, v25
	v_and_b32_e32 v25, 0xffff0000, v72
	v_add_f32_e32 v21, v21, v25
	v_cvt_pk_bf16_f32 v20, v20, v21
	v_lshlrev_b32_e32 v21, 16, v73
	v_add_f32_e32 v21, v22, v21
	v_and_b32_e32 v22, 0xffff0000, v73
	v_add_f32_e32 v22, v23, v22
	v_cvt_pk_bf16_f32 v21, v21, v22
	v_lshlrev_b32_e32 v22, 16, v74
	v_add_f32_e32 v16, v16, v22
	v_and_b32_e32 v22, 0xffff0000, v74
	v_add_f32_e32 v17, v17, v22
	v_cvt_pk_bf16_f32 v22, v16, v17
	v_and_b32_e32 v17, 0xffff0000, v75
	v_lshlrev_b32_e32 v16, 16, v75
	v_add_f32_e32 v17, v19, v17
	v_add_f32_e32 v16, v18, v16
	v_cvt_pk_bf16_f32 v23, v16, v17
	v_and_b32_e32 v17, 0xffff0000, v20
	v_lshlrev_b32_e32 v16, 16, v20
	v_and_b32_e32 v19, 0xffff0000, v21
	v_mul_f32_e32 v17, v17, v17
	v_lshlrev_b32_e32 v18, 16, v21
	v_fmac_f32_e32 v17, v16, v16
	v_mul_f32_e32 v16, v19, v19
	v_and_b32_e32 v26, 0xffff0000, v22
	v_and_b32_e32 v28, 0xffff0000, v23
	v_fmac_f32_e32 v16, v18, v18
	v_lshlrev_b32_e32 v25, 16, v22
	v_lshlrev_b32_e32 v27, 16, v23
	v_add_f32_e32 v16, v17, v16
	v_mul_f32_e32 v17, v26, v26
	v_mul_f32_e32 v18, v28, v28
	v_fmac_f32_e32 v17, v25, v25
	v_fmac_f32_e32 v18, v27, v27
	v_add_f32_e32 v17, v17, v18
	v_add_f32_e32 v16, v16, v17
	v_add_f32_e32 v16, v24, v16
	ds_bpermute_b32 v17, v112, v16
	global_store_dwordx4 v[32:33], v[20:23], off offset:256 nt
	s_waitcnt lgkmcnt(0)
	v_add_f32_e32 v16, v16, v17
	ds_bpermute_b32 v17, v113, v16
	s_and_saveexec_b64 s[26:27], s[0:1]
	s_cbranch_execz .LBB0_1331
	v_lshlrev_b64 v[18:19], 6, v[90:91]
	v_lshl_add_u64 v[18:19], s[66:67], 0, v[18:19]
	v_lshl_add_u64 v[18:19], s[18:19], 2, v[18:19]
	s_lshl_b32 s8, s46, 2
	v_lshl_add_u64 v[18:19], v[18:19], 0, s[8:9]
	s_waitcnt lgkmcnt(0)
	v_add_f32_e32 v16, v16, v17
	global_store_dword v[18:19], v16, off
.LBB0_1331:
	s_or_b64 exec, exec, s[26:27]
	s_waitcnt vmcnt(7)
	v_lshlrev_b32_e32 v18, 16, v68
	v_add_f32_e32 v12, v12, v18
	v_and_b32_e32 v18, 0xffff0000, v68
	v_add_f32_e32 v13, v13, v18
	v_cvt_pk_bf16_f32 v12, v12, v13
	v_lshlrev_b32_e32 v13, 16, v69
	v_add_f32_e32 v13, v14, v13
	v_and_b32_e32 v14, 0xffff0000, v69
	v_add_f32_e32 v14, v15, v14
	v_cvt_pk_bf16_f32 v13, v13, v14
	v_lshlrev_b32_e32 v14, 16, v70
	v_add_f32_e32 v8, v8, v14
	v_and_b32_e32 v14, 0xffff0000, v70
	v_add_f32_e32 v9, v9, v14
	v_cvt_pk_bf16_f32 v14, v8, v9
	v_and_b32_e32 v9, 0xffff0000, v71
	v_lshlrev_b32_e32 v8, 16, v71
	v_add_f32_e32 v9, v11, v9
	v_add_f32_e32 v8, v10, v8
	v_cvt_pk_bf16_f32 v15, v8, v9
	v_and_b32_e32 v9, 0xffff0000, v12
	s_waitcnt lgkmcnt(0)
	v_lshl_add_u64 v[16:17], s[64:65], 0, v[92:93]
	v_lshlrev_b32_e32 v8, 16, v12
	v_and_b32_e32 v11, 0xffff0000, v13
	v_mul_f32_e32 v9, v9, v9
	v_lshl_add_u64 v[16:17], v[180:181], 1, v[16:17]
	v_lshlrev_b32_e32 v10, 16, v13
	v_fmac_f32_e32 v9, v8, v8
	v_mul_f32_e32 v8, v11, v11
	global_store_dwordx4 v[16:17], v[12:15], off nt
	v_fmac_f32_e32 v8, v10, v10
	v_add_f32_e32 v8, v9, v8
	v_lshlrev_b32_e32 v12, 16, v14
	v_and_b32_e32 v13, 0xffff0000, v14
	v_lshlrev_b32_e32 v14, 16, v15
	v_and_b32_e32 v15, 0xffff0000, v15
	v_mul_f32_e32 v9, v13, v13
	v_mul_f32_e32 v10, v15, v15
	v_fmac_f32_e32 v9, v12, v12
	v_fmac_f32_e32 v10, v14, v14
	v_add_f32_e32 v9, v9, v10
	v_add_f32_e32 v8, v8, v9
	s_waitcnt vmcnt(7)
	v_lshlrev_b32_e32 v9, 16, v64
	v_add_f32_e32 v4, v4, v9
	v_and_b32_e32 v9, 0xffff0000, v64
	v_add_f32_e32 v5, v5, v9
	v_cvt_pk_bf16_f32 v4, v4, v5
	v_lshlrev_b32_e32 v5, 16, v65
	v_add_f32_e32 v5, v6, v5
	v_and_b32_e32 v6, 0xffff0000, v65
	v_add_f32_e32 v6, v7, v6
	v_cvt_pk_bf16_f32 v5, v5, v6
	v_lshlrev_b32_e32 v6, 16, v66
	v_add_f32_e32 v0, v0, v6
	v_and_b32_e32 v6, 0xffff0000, v66
	v_add_f32_e32 v1, v1, v6
	v_cvt_pk_bf16_f32 v6, v0, v1
	v_and_b32_e32 v1, 0xffff0000, v67
	v_lshlrev_b32_e32 v0, 16, v67
	v_add_f32_e32 v1, v3, v1
	v_add_f32_e32 v0, v2, v0
	v_cvt_pk_bf16_f32 v7, v0, v1
	v_and_b32_e32 v1, 0xffff0000, v4
	v_lshlrev_b32_e32 v0, 16, v4
	v_and_b32_e32 v3, 0xffff0000, v5
	v_mul_f32_e32 v1, v1, v1
	v_lshlrev_b32_e32 v2, 16, v5
	v_fmac_f32_e32 v1, v0, v0
	v_mul_f32_e32 v0, v3, v3
	v_and_b32_e32 v10, 0xffff0000, v6
	v_and_b32_e32 v12, 0xffff0000, v7
	v_fmac_f32_e32 v0, v2, v2
	v_lshlrev_b32_e32 v9, 16, v6
	v_lshlrev_b32_e32 v11, 16, v7
	v_add_f32_e32 v0, v1, v0
	v_mul_f32_e32 v1, v10, v10
	v_mul_f32_e32 v2, v12, v12
	v_fmac_f32_e32 v1, v9, v9
	v_fmac_f32_e32 v2, v11, v11
	v_add_f32_e32 v1, v1, v2
	v_add_f32_e32 v0, v0, v1
	v_add_f32_e32 v0, v8, v0
	ds_bpermute_b32 v1, v112, v0
	global_store_dwordx4 v[16:17], v[4:7], off offset:256 nt
	s_waitcnt lgkmcnt(0)
	v_add_f32_e32 v0, v0, v1
	ds_bpermute_b32 v1, v113, v0
	s_and_saveexec_b64 s[26:27], s[0:1]
	s_cbranch_execz .LBB0_1283
	v_readlane_b32 s52, v254, 28
	v_lshlrev_b64 v[2:3], 6, v[88:89]
	v_readlane_b32 s66, v254, 42
	v_readlane_b32 s67, v254, 43
	s_lshl_b32 s8, s46, 2
	s_waitcnt lgkmcnt(0)
	v_add_f32_e32 v0, v0, v1
	v_lshl_add_u64 v[2:3], s[66:67], 0, v[2:3]
	v_lshl_add_u64 v[2:3], s[18:19], 2, v[2:3]
	v_lshl_add_u64 v[2:3], v[2:3], 0, s[8:9]
	v_readlane_b32 s53, v254, 29
	v_readlane_b32 s54, v254, 30
	v_readlane_b32 s55, v254, 31
	v_readlane_b32 s56, v254, 32
	v_readlane_b32 s57, v254, 33
	v_readlane_b32 s58, v254, 34
	v_readlane_b32 s59, v254, 35
	v_readlane_b32 s60, v254, 36
	v_readlane_b32 s61, v254, 37
	v_readlane_b32 s62, v254, 38
	v_readlane_b32 s63, v254, 39
	v_readlane_b32 s64, v254, 40
	v_readlane_b32 s65, v254, 41
	global_store_dword v[2:3], v0, off
	s_branch .LBB0_1283

;     DI void row(const f32x4 (&a4)[2][2], const Unit& u, int ai, int m, int wr, int wc, int fr, int fq) const {
;         const int cb = u.pn * 256 + wc * 32 + 8 * fq, row = u.pm * 256 + wr * 64 + fr + ai * 128 + m * 16;
;         u32x4v* p0 = (u32x4v*)(XB + (size_t)row * 1024 + cb); u32x4v* p1 = (u32x4v*)(XB + (size_t)row * 1024 + cb + 128);
;         const u32x4v x0 = *p0, x1 = *p1;
;         float ss = upd(p0, x0, a4[0][0], a4[0][1]) + upd(p1, x1, a4[1][0], a4[1][1]);
;         ss += __shfl_xor(ss, 16); ss += __shfl_xor(ss, 32);
;         if (fq == 0) SSQ[(size_t)row * 16 + u.pn * 4 + wc] = ss;
;     }
; template <class Epi> DI void gemm_fixup(int N, int K, const Epi& E, const float* part, int tid) {
;     ...
;     for (int it = blockIdx.x; it < S.ntail * 8; it += gridDim.x) { const int j = it >> 3, ai = (it >> 2) & 1, m = it & 3; Unit u; S.map(S.nwhole * S.G + j, u);
;         f32x4 a4[2][2];
; #pragma unroll
;         for (int b = 0; b < 2; ++b)
; #pragma unroll
;             for (int n = 0; n < 2; ++n) { const f32x4* pp = (const f32x4*)part + ((size_t)(j * S.S) * 32 + (((ai * 2 + b) * 4 + m) * 2 + n)) * 512 + tid;
;                 f32x4 v0 = {0.f, 0.f, 0.f, 0.f}, v1 = v0, v2 = v0, v3 = v0;
;                 for (int sl = 0; sl + 3 < S.S; sl += 4) { v0 += pp[(size_t)sl * 16384]; v1 += pp[(size_t)(sl + 1) * 16384]; v2 += pp[(size_t)(sl + 2) * 16384]; v3 += pp[(size_t)(sl + 3) * 16384]; }
;                 for (int sl = S.S & ~3; sl < S.S; ++sl) v0 += pp[(size_t)sl * 16384];
;                 a4[b][n] = (v0 + v1) + (v2 + v3); }
;         E.row(a4, u, ai, m, wr, wc, fr, fq); }
.LBB0_1425:
	s_add_i32 s2, s27, s18
	s_ashr_i32 s3, s2, 31
	s_lshr_b32 s3, s3, 27
	s_add_i32 s3, s2, s3
	s_ashr_i32 s4, s3, 5
	s_lshl_b32 s5, s4, 3
	s_sub_i32 s4, 0x83, s5
	s_min_i32 s18, s4, 8
	s_abs_i32 s4, s18
	v_cvt_f32_u32_e32 v1, s4
	s_sub_i32 s23, 0, s4
	s_andn2_b32 s3, s3, 31
	s_sub_i32 s2, s2, s3
	v_rcp_iflag_f32_e32 v1, v1
	s_abs_i32 s3, s2
	s_xor_b32 s22, s2, s18
	s_ashr_i32 s22, s22, 31
	v_mul_f32_e32 v1, 0x4f7ffffe, v1
	v_cvt_u32_f32_e32 v1, v1
	v_pk_add_f32 v[14:15], v[62:63], v[14:15]
	v_pk_add_f32 v[12:13], v[56:57], v[12:13]
	v_pk_add_f32 v[56:57], v[60:61], v[66:67]
	v_readfirstlane_b32 s27, v1
	s_mul_i32 s23, s23, s27
	s_mul_hi_u32 s23, s27, s23
	s_add_i32 s27, s27, s23
	s_mul_hi_u32 s23, s3, s27
	s_mul_i32 s27, s23, s4
	s_sub_i32 s3, s3, s27
	s_add_i32 s29, s23, 1
	s_sub_i32 s27, s3, s4
	s_cmp_ge_u32 s3, s4
	s_cselect_b32 s23, s29, s23
	s_cselect_b32 s3, s27, s3
	s_add_i32 s27, s23, 1
	s_cmp_ge_u32 s3, s4
	s_cselect_b32 s3, s27, s23
	s_xor_b32 s3, s3, s22
	s_sub_i32 s4, s3, s22
	s_mul_i32 s3, s4, s18
	s_sub_i32 s2, s2, s3
	s_add_i32 s5, s5, s2
	s_lshl_b32 s2, s5, 8
	s_lshl_b32 s3, s25, 7
	v_lshl_or_b32 v1, s26, 4, v81
	s_or_b32 s2, s2, s3
	v_add_u32_e32 v78, s2, v1
	v_ashrrev_i32_e32 v79, 31, v78
	v_lshl_or_b32 v84, s4, 8, v80
	v_lshlrev_b64 v[86:87], 11, v[78:79]
	v_lshl_add_u64 v[86:87], s[48:49], 0, v[86:87]
	v_ashrrev_i32_e32 v85, 31, v84
	v_lshl_add_u64 v[92:93], v[84:85], 1, v[86:87]
	global_load_dwordx4 v[84:87], v[92:93], off
	global_load_dwordx4 v[88:91], v[92:93], off offset:256
	v_pk_add_f32 v[58:59], v[58:59], v[64:65]
	v_pk_add_f32 v[10:11], v[50:51], v[10:11]
	v_pk_add_f32 v[8:9], v[44:45], v[8:9]
	v_pk_add_f32 v[44:45], v[48:49], v[54:55]
	v_pk_add_f32 v[46:47], v[46:47], v[52:53]
	v_pk_add_f32 v[6:7], v[42:43], v[6:7]
	v_pk_add_f32 v[4:5], v[32:33], v[4:5]
	v_pk_add_f32 v[32:33], v[40:41], v[36:37]
	v_pk_add_f32 v[34:35], v[38:39], v[34:35]
	v_pk_add_f32 v[18:19], v[72:73], v[18:19]
	v_pk_add_f32 v[16:17], v[68:69], v[16:17]
	v_pk_add_f32 v[36:37], v[70:71], v[76:77]
	v_pk_add_f32 v[2:3], v[2:3], v[74:75]
	v_pk_add_f32 v[14:15], v[58:59], v[14:15]
	v_pk_add_f32 v[12:13], v[56:57], v[12:13]
	v_pk_add_f32 v[10:11], v[46:47], v[10:11]
	v_pk_add_f32 v[8:9], v[44:45], v[8:9]
	v_pk_add_f32 v[6:7], v[34:35], v[6:7]
	v_pk_add_f32 v[4:5], v[32:33], v[4:5]
	v_pk_add_f32 v[2:3], v[2:3], v[18:19]
	v_pk_add_f32 v[16:17], v[36:37], v[16:17]
	s_waitcnt vmcnt(1)
	v_lshlrev_b32_e32 v1, 16, v84
	v_and_b32_e32 v18, 0xffff0000, v84
	v_lshlrev_b32_e32 v19, 16, v85
	v_and_b32_e32 v31, 0xffff0000, v85
	v_lshlrev_b32_e32 v32, 16, v86
	v_and_b32_e32 v33, 0xffff0000, v86
	v_lshlrev_b32_e32 v34, 16, v87
	v_and_b32_e32 v35, 0xffff0000, v87
	s_waitcnt vmcnt(0)
	v_lshlrev_b32_e32 v36, 16, v88
	v_and_b32_e32 v37, 0xffff0000, v88
	v_lshlrev_b32_e32 v38, 16, v89
	v_and_b32_e32 v39, 0xffff0000, v89
	v_lshlrev_b32_e32 v40, 16, v90
	v_and_b32_e32 v41, 0xffff0000, v90
	v_lshlrev_b32_e32 v42, 16, v91
	v_and_b32_e32 v43, 0xffff0000, v91
	v_add_f32_e32 v1, v4, v1
	v_add_f32_e32 v4, v5, v18
	v_add_f32_e32 v5, v6, v19
	v_add_f32_e32 v6, v7, v31
	v_add_f32_e32 v7, v8, v32
	v_add_f32_e32 v8, v9, v33
	v_add_f32_e32 v9, v10, v34
	v_add_f32_e32 v10, v11, v35
	v_add_f32_e32 v11, v12, v36
	v_add_f32_e32 v12, v13, v37
	v_add_f32_e32 v13, v14, v38
	v_add_f32_e32 v14, v15, v39
	v_add_f32_e32 v15, v16, v40
	v_add_f32_e32 v16, v17, v41
	v_add_f32_e32 v17, v2, v42
	v_add_f32_e32 v18, v3, v43
	v_cvt_pk_bf16_f32 v2, v1, v4
	v_cvt_pk_bf16_f32 v3, v5, v6
	v_cvt_pk_bf16_f32 v4, v7, v8
	v_cvt_pk_bf16_f32 v5, v9, v10
	global_store_dwordx4 v[92:93], v[2:5], off nt
	v_lshlrev_b32_e32 v1, 16, v2
	v_lshlrev_b32_e32 v7, 16, v3
	v_and_b32_e32 v2, 0xffff0000, v2
	v_and_b32_e32 v3, 0xffff0000, v3
	v_and_b32_e32 v9, 0xffff0000, v4
	v_and_b32_e32 v19, 0xffff0000, v5
	v_lshlrev_b32_e32 v8, 16, v4
	v_lshlrev_b32_e32 v10, 16, v5
	v_cvt_pk_bf16_f32 v4, v11, v12
	v_mul_f32_e32 v2, v2, v2
	v_mul_f32_e32 v3, v3, v3
	v_mul_f32_e32 v9, v9, v9
	v_mul_f32_e32 v11, v19, v19
	v_fmac_f32_e32 v2, v1, v1
	v_fmac_f32_e32 v3, v7, v7
	v_fmac_f32_e32 v9, v8, v8
	v_fmac_f32_e32 v11, v10, v10
	v_add_f32_e32 v1, v2, v3
	v_add_f32_e32 v2, v9, v11
	v_and_b32_e32 v3, 0xffff0000, v4
	v_cvt_pk_bf16_f32 v5, v13, v14
	v_add_f32_e32 v1, v1, v2
	v_lshlrev_b32_e32 v2, 16, v4
	v_and_b32_e32 v9, 0xffff0000, v5
	v_mul_f32_e32 v3, v3, v3
	v_lshlrev_b32_e32 v8, 16, v5
	v_fmac_f32_e32 v3, v2, v2
	v_mul_f32_e32 v2, v9, v9
	v_cvt_pk_bf16_f32 v6, v15, v16
	v_cvt_pk_bf16_f32 v7, v17, v18
	v_fmac_f32_e32 v2, v8, v8
	v_and_b32_e32 v11, 0xffff0000, v6
	v_and_b32_e32 v13, 0xffff0000, v7
	v_lshlrev_b32_e32 v10, 16, v6
	v_lshlrev_b32_e32 v12, 16, v7
	v_add_f32_e32 v2, v3, v2
	v_mul_f32_e32 v3, v11, v11
	v_mul_f32_e32 v8, v13, v13
	v_fmac_f32_e32 v3, v10, v10
	v_fmac_f32_e32 v8, v12, v12
	v_add_f32_e32 v3, v3, v8
	v_add_f32_e32 v2, v2, v3
	v_and_b32_e32 v3, 64, v82
	v_add_f32_e32 v1, v1, v2
	v_xor_b32_e32 v2, 16, v82
	v_add_u32_e32 v3, 64, v3
	v_cmp_lt_i32_e32 vcc, v2, v3
	global_store_dwordx4 v[92:93], v[4:7], off offset:256 nt
	s_nop 0
	v_cndmask_b32_e32 v2, v82, v2, vcc
	v_lshlrev_b32_e32 v2, 2, v2
	ds_bpermute_b32 v2, v2, v1
	s_waitcnt lgkmcnt(0)
	v_add_f32_e32 v1, v1, v2
	v_xor_b32_e32 v2, 32, v82
	v_cmp_lt_i32_e32 vcc, v2, v3
	s_nop 1
	v_cndmask_b32_e32 v2, v82, v2, vcc
	v_lshlrev_b32_e32 v2, 2, v2
	ds_bpermute_b32 v2, v2, v1
	s_and_saveexec_b64 s[2:3], s[0:1]
	s_xor_b64 s[2:3], exec, s[2:3]
	s_cbranch_execz .LBB0_1399
	s_waitcnt lgkmcnt(0)
	v_add_f32_e32 v1, v1, v2
	s_lshl_b32 s4, s4, 2
	v_lshlrev_b64 v[2:3], 6, v[78:79]
	s_ashr_i32 s5, s4, 31
	v_lshl_add_u64 v[2:3], s[50:51], 0, v[2:3]
	v_lshl_add_u64 v[2:3], s[4:5], 2, v[2:3]
	v_mov_b32_e32 v31, v0
	v_lshl_add_u64 v[2:3], v[2:3], 0, v[30:31]
	global_store_dword v[2:3], v1, off
	s_branch .LBB0_1399

; template <class Epi, class Sched>
; __device__ __forceinline__ void gemm_phase(PG8_LAS unsigned char* lds, const Gemm g, const Sched& S, const Epi& E) {
;     ...
;             else { f32x4* pp = (f32x4*)g.part + (size_t)cur.part * 32 * 512 + tid;
; #pragma unroll
;                 for (int a = 0; a < 2; ++a)
; #pragma unroll
;                     for (int b = 0; b < 2; ++b)
; #pragma unroll
;                         for (int m = 0; m < 4; ++m)
; #pragma unroll
;                             for (int n = 0; n < 2; ++n) pp[(size_t)(((a * 2 + b) * 4 + m) * 2 + n) * 512] = acc[a][b][m][n]; }
.LBB0_1638:
	s_lshl_b64 s[48:49], s[10:11], 18
	v_lshl_add_u64 v[128:129], v[172:173], 0, s[48:49]
	v_add_co_u32_e32 v130, vcc, 0x2000, v128
	s_mov_b32 s10, 0x10000
	s_nop 0
	v_addc_co_u32_e32 v131, vcc, 0, v129, vcc
	global_store_dwordx4 v[130:131], v[120:123], off nt
	v_add_co_u32_e32 v130, vcc, 0x4000, v128
	global_store_dwordx4 v[128:129], v[124:127], off nt
	s_nop 0
	v_addc_co_u32_e32 v131, vcc, 0, v129, vcc
	global_store_dwordx4 v[130:131], v[108:111], off nt
	v_add_co_u32_e32 v130, vcc, 0x6000, v128
	s_mov_b64 s[48:49], 0
	s_nop 0
	v_addc_co_u32_e32 v131, vcc, 0, v129, vcc
	global_store_dwordx4 v[130:131], v[104:107], off nt
	v_add_co_u32_e32 v130, vcc, 0x8000, v128
	s_nop 1
	v_addc_co_u32_e32 v131, vcc, 0, v129, vcc
	global_store_dwordx4 v[130:131], v[92:95], off nt
	v_add_co_u32_e32 v130, vcc, 0xa000, v128
	s_nop 1
	v_addc_co_u32_e32 v131, vcc, 0, v129, vcc
	global_store_dwordx4 v[130:131], v[88:91], off nt
	v_add_co_u32_e32 v130, vcc, 0xc000, v128
	s_nop 1
	v_addc_co_u32_e32 v131, vcc, 0, v129, vcc
	global_store_dwordx4 v[130:131], v[76:79], off nt
	v_add_co_u32_e32 v130, vcc, 0xe000, v128
	s_nop 1
	v_addc_co_u32_e32 v131, vcc, 0, v129, vcc
	global_store_dwordx4 v[130:131], v[72:75], off nt
	v_add_co_u32_e32 v130, vcc, s10, v128
	s_mov_b32 s10, 0x12000
	s_nop 0
	v_addc_co_u32_e32 v131, vcc, 0, v129, vcc
	global_store_dwordx4 v[130:131], v[116:119], off nt
	v_add_co_u32_e32 v130, vcc, s10, v128
	s_mov_b32 s10, 0x14000
	s_nop 0
	v_addc_co_u32_e32 v131, vcc, 0, v129, vcc
	global_store_dwordx4 v[130:131], v[112:115], off nt
	v_add_co_u32_e32 v130, vcc, s10, v128
	s_mov_b32 s10, 0x16000
	s_nop 0
	v_addc_co_u32_e32 v131, vcc, 0, v129, vcc
	global_store_dwordx4 v[130:131], v[100:103], off nt
	v_add_co_u32_e32 v130, vcc, s10, v128
	s_mov_b32 s10, 0x18000
	s_nop 0
	v_addc_co_u32_e32 v131, vcc, 0, v129, vcc
	global_store_dwordx4 v[130:131], v[96:99], off nt
	v_add_co_u32_e32 v130, vcc, s10, v128
	s_mov_b32 s10, 0x1a000
	s_nop 0
	v_addc_co_u32_e32 v131, vcc, 0, v129, vcc
	global_store_dwordx4 v[130:131], v[84:87], off nt
	v_add_co_u32_e32 v130, vcc, s10, v128
	s_mov_b32 s10, 0x1c000
	s_nop 0
	v_addc_co_u32_e32 v131, vcc, 0, v129, vcc
	global_store_dwordx4 v[130:131], v[80:83], off nt
	v_add_co_u32_e32 v130, vcc, s10, v128
	s_mov_b32 s10, 0x1e000
	s_nop 0
	v_addc_co_u32_e32 v131, vcc, 0, v129, vcc
	global_store_dwordx4 v[130:131], v[68:71], off nt
	v_add_co_u32_e32 v130, vcc, s10, v128
	s_mov_b32 s10, 0x20000
	s_nop 0
	v_addc_co_u32_e32 v131, vcc, 0, v129, vcc
	global_store_dwordx4 v[130:131], v[64:67], off nt
	v_add_co_u32_e32 v130, vcc, s10, v128
	s_mov_b32 s10, 0x22000
	s_nop 0
	v_addc_co_u32_e32 v131, vcc, 0, v129, vcc
	global_store_dwordx4 v[130:131], v[60:63], off nt
	v_add_co_u32_e32 v130, vcc, s10, v128
	s_mov_b32 s10, 0x24000
	s_nop 0
	v_addc_co_u32_e32 v131, vcc, 0, v129, vcc
	global_store_dwordx4 v[130:131], v[56:59], off nt
	v_add_co_u32_e32 v130, vcc, s10, v128
	s_mov_b32 s10, 0x26000
	s_nop 0
	v_addc_co_u32_e32 v131, vcc, 0, v129, vcc
	global_store_dwordx4 v[130:131], v[44:47], off nt
	v_add_co_u32_e32 v130, vcc, s10, v128
	s_mov_b32 s10, 0x28000
	s_nop 0
	v_addc_co_u32_e32 v131, vcc, 0, v129, vcc
	global_store_dwordx4 v[130:131], v[40:43], off nt
	v_add_co_u32_e32 v130, vcc, s10, v128
	s_mov_b32 s10, 0x2a000
	s_nop 0
	v_addc_co_u32_e32 v131, vcc, 0, v129, vcc
	global_store_dwordx4 v[130:131], v[28:31], off nt
	v_add_co_u32_e32 v130, vcc, s10, v128
	s_mov_b32 s10, 0x2c000
	s_nop 0
	v_addc_co_u32_e32 v131, vcc, 0, v129, vcc
	global_store_dwordx4 v[130:131], v[24:27], off nt
	v_add_co_u32_e32 v130, vcc, s10, v128
	s_mov_b32 s10, 0x2e000
	s_nop 0
	v_addc_co_u32_e32 v131, vcc, 0, v129, vcc
	global_store_dwordx4 v[130:131], v[12:15], off nt
	v_add_co_u32_e32 v130, vcc, s10, v128
	s_mov_b32 s10, 0x30000
	s_nop 0
	v_addc_co_u32_e32 v131, vcc, 0, v129, vcc
	global_store_dwordx4 v[130:131], v[8:11], off nt
	v_add_co_u32_e32 v130, vcc, s10, v128
	s_mov_b32 s10, 0x32000
	s_nop 0
	v_addc_co_u32_e32 v131, vcc, 0, v129, vcc
	global_store_dwordx4 v[130:131], v[52:55], off nt
	v_add_co_u32_e32 v130, vcc, s10, v128
	s_mov_b32 s10, 0x34000
	s_nop 0
	v_addc_co_u32_e32 v131, vcc, 0, v129, vcc
	global_store_dwordx4 v[130:131], v[48:51], off nt
	v_add_co_u32_e32 v130, vcc, s10, v128
	s_mov_b32 s10, 0x36000
	s_nop 0
	v_addc_co_u32_e32 v131, vcc, 0, v129, vcc
	global_store_dwordx4 v[130:131], v[36:39], off nt
	v_add_co_u32_e32 v130, vcc, s10, v128
	s_mov_b32 s10, 0x38000
	s_nop 0
	v_addc_co_u32_e32 v131, vcc, 0, v129, vcc
	global_store_dwordx4 v[130:131], v[32:35], off nt
	v_add_co_u32_e32 v130, vcc, s10, v128
	s_mov_b32 s10, 0x3a000
	s_nop 0
	v_addc_co_u32_e32 v131, vcc, 0, v129, vcc
	global_store_dwordx4 v[130:131], v[20:23], off nt
	v_add_co_u32_e32 v130, vcc, s10, v128
	s_nop 1
	v_addc_co_u32_e32 v131, vcc, 0, v129, vcc
	global_store_dwordx4 v[130:131], v[16:19], off nt
	v_add_co_u32_e32 v130, vcc, 0x3c000, v128
	s_nop 1
	v_addc_co_u32_e32 v131, vcc, 0, v129, vcc
	v_add_co_u32_e32 v128, vcc, 0x3e000, v128
	global_store_dwordx4 v[130:131], v[4:7], off nt
	s_nop 0
	v_addc_co_u32_e32 v129, vcc, 0, v129, vcc
	global_store_dwordx4 v[128:129], v[0:3], off nt
; DI unsigned pk2(float lo, float hi) { unsigned r; asm volatile("v_cvt_pk_bf16_f32 %0, %1, %2" : "=v"(r) : "v"(lo), "v"(hi)); return r; }
; DI float bflo(unsigned u) { return __uint_as_float(u << 16); }
; DI float bfhi(unsigned u) { return __uint_as_float(u & 0xffff0000u); }
;     DI float upd(u32x4v* px, const u32x4v x, const f32x4 v0, const f32x4 v1) const {
;         u32x4v o; o.x = pk2(bflo(x.x) + v0[0], bfhi(x.x) + v0[1]); o.y = pk2(bflo(x.y) + v0[2], bfhi(x.y) + v0[3]);
;         o.z = pk2(bflo(x.z) + v1[0], bfhi(x.z) + v1[1]); o.w = pk2(bflo(x.w) + v1[2], bfhi(x.w) + v1[3]); *px = o;
;         const float a0 = bflo(o.x), a1 = bfhi(o.x), a2 = bflo(o.y), a3 = bfhi(o.y), a4 = bflo(o.z), a5 = bfhi(o.z), a6 = bflo(o.w), a7 = bfhi(o.w);
;         return ((a0 * a0 + a1 * a1) + (a2 * a2 + a3 * a3)) + ((a4 * a4 + a5 * a5) + (a6 * a6 + a7 * a7));
;     }
;     DI void operator()(const f32x4 (&acc)[2][2][4][2], const Unit& u, int wr, int wc, int fr, int fq, const Pre& pre) const {
;     ...
;             for (int m = 0; m < 4; ++m)
; #pragma unroll
;                 for (int bj = 0; bj < 2; ++bj) x[m][bj] = *(const u32x4v*)(XB + (size_t)(row0 + ai * 128 + m * 16) * 1024 + cb + bj * 128);
; #pragma unroll
;             for (int m = 0; m < 4; ++m) { const int row = row0 + ai * 128 + m * 16;
;                 float ss = upd((u32x4v*)(XB + (size_t)row * 1024 + cb), x[m][0], acc[ai][0][m][0], acc[ai][0][m][1])
;                          + upd((u32x4v*)(XB + (size_t)row * 1024 + cb + 128), x[m][1], acc[ai][1][m][0], acc[ai][1][m][1]);
;                 ss += __shfl_xor(ss, 16); ss += __shfl_xor(ss, 32);
;                 if (fq == 0) SSQ[(size_t)row * 16 + u.pn * 4 + wc] = ss; } }
.LBB0_1639:
	s_andn2_b64 vcc, exec, s[48:49]
	s_cbranch_vccnz .LBB0_1607
	v_lshl_or_b32 v180, s36, 8, v161
	v_lshl_add_u32 v182, s44, 8, v157
	v_ashrrev_i32_e32 v181, 31, v180
	v_readlane_b32 s48, v254, 28
	v_lshlrev_b64 v[128:129], 1, v[180:181]
	v_readlane_b32 s60, v254, 40
	v_readlane_b32 s61, v254, 41
	v_ashrrev_i32_e32 v183, 31, v182
	v_lshlrev_b64 v[130:131], 11, v[182:183]
	v_lshl_add_u64 v[184:185], s[60:61], 0, v[128:129]
	v_lshl_add_u64 v[132:133], v[184:185], 0, v[130:131]
	global_load_dwordx4 v[202:205], v[132:133], off
	global_load_dwordx4 v[206:209], v[132:133], off offset:256
	v_or_b32_e32 v192, 16, v182
	v_or_b32_e32 v188, 32, v182
	v_or_b32_e32 v186, 48, v182
	v_ashrrev_i32_e32 v193, 31, v192
	v_ashrrev_i32_e32 v189, 31, v188
	v_ashrrev_i32_e32 v187, 31, v186
	v_lshlrev_b64 v[196:197], 11, v[192:193]
	v_lshlrev_b64 v[194:195], 11, v[188:189]
	v_lshlrev_b64 v[190:191], 11, v[186:187]
	v_lshl_add_u64 v[130:131], s[60:61], 0, v[130:131]
	v_lshl_add_u64 v[132:133], v[184:185], 0, v[196:197]
	v_lshl_add_u64 v[134:135], v[184:185], 0, v[194:195]
	v_lshl_add_u64 v[210:211], v[184:185], 0, v[190:191]
	v_lshl_add_u64 v[212:213], v[130:131], 0, v[128:129]
	global_load_dwordx4 v[148:151], v[132:133], off
	global_load_dwordx4 v[144:147], v[132:133], off offset:256
	global_load_dwordx4 v[140:143], v[134:135], off
	global_load_dwordx4 v[136:139], v[134:135], off offset:256
	s_nop 0
	global_load_dwordx4 v[132:135], v[210:211], off
	global_load_dwordx4 v[128:131], v[210:211], off offset:256
	s_lshl_b32 s36, s36, 2
	v_readlane_b32 s62, v254, 42
	v_readlane_b32 s63, v254, 43
	s_ashr_i32 s37, s36, 31
	v_readlane_b32 s49, v254, 29
	v_readlane_b32 s50, v254, 30
	v_readlane_b32 s51, v254, 31
	v_readlane_b32 s52, v254, 32
	v_readlane_b32 s53, v254, 33
	v_readlane_b32 s54, v254, 34
	v_readlane_b32 s55, v254, 35
	v_readlane_b32 s56, v254, 36
	v_readlane_b32 s57, v254, 37
	v_readlane_b32 s58, v254, 38
	v_readlane_b32 s59, v254, 39
	s_waitcnt vmcnt(0)
	v_lshlrev_b32_e32 v201, 16, v202
	v_and_b32_e32 v202, 0xffff0000, v202
	v_lshlrev_b32_e32 v210, 16, v203
	v_and_b32_e32 v203, 0xffff0000, v203
	v_lshlrev_b32_e32 v211, 16, v204
	v_and_b32_e32 v204, 0xffff0000, v204
	v_lshlrev_b32_e32 v214, 16, v205
	v_and_b32_e32 v205, 0xffff0000, v205
	v_lshlrev_b32_e32 v217, 16, v208
	v_and_b32_e32 v208, 0xffff0000, v208
	v_lshlrev_b32_e32 v218, 16, v209
	v_and_b32_e32 v209, 0xffff0000, v209
	v_add_f32_e32 v124, v124, v201
	v_add_f32_e32 v125, v125, v202
	v_add_f32_e32 v126, v126, v210
	v_add_f32_e32 v127, v127, v203
	v_add_f32_e32 v120, v120, v211
	v_add_f32_e32 v121, v121, v204
	v_add_f32_e32 v122, v122, v214
	v_add_f32_e32 v123, v123, v205
	v_add_f32_e32 v201, v112, v217
	v_add_f32_e32 v202, v113, v208
	v_add_f32_e32 v203, v114, v218
	v_add_f32_e32 v204, v115, v209
	v_cvt_pk_bf16_f32 v112, v124, v125
	v_cvt_pk_bf16_f32 v113, v126, v127
	v_cvt_pk_bf16_f32 v114, v120, v121
	v_cvt_pk_bf16_f32 v115, v122, v123
	global_store_dwordx4 v[212:213], v[112:115], off nt
	v_lshlrev_b32_e32 v120, 16, v112
	v_lshlrev_b32_e32 v121, 16, v113
	v_and_b32_e32 v112, 0xffff0000, v112
	v_and_b32_e32 v113, 0xffff0000, v113
	v_lshlrev_b32_e32 v122, 16, v114
	v_and_b32_e32 v114, 0xffff0000, v114
	v_lshlrev_b32_e32 v123, 16, v115
	v_and_b32_e32 v115, 0xffff0000, v115
	v_lshlrev_b32_e32 v215, 16, v206
	v_and_b32_e32 v206, 0xffff0000, v206
	v_lshlrev_b32_e32 v216, 16, v207
	v_mul_f32_e32 v112, v112, v112
	v_mul_f32_e32 v113, v113, v113
	v_mul_f32_e32 v114, v114, v114
	v_mul_f32_e32 v115, v115, v115
	v_and_b32_e32 v207, 0xffff0000, v207
	v_add_f32_e32 v116, v116, v215
	v_add_f32_e32 v117, v117, v206
	v_add_f32_e32 v118, v118, v216
	v_fmac_f32_e32 v112, v120, v120
	v_fmac_f32_e32 v113, v121, v121
	v_fmac_f32_e32 v114, v122, v122
	v_fmac_f32_e32 v115, v123, v123
	v_add_f32_e32 v119, v119, v207
	v_cvt_pk_bf16_f32 v116, v116, v117
	v_cvt_pk_bf16_f32 v117, v118, v119
	v_cvt_pk_bf16_f32 v118, v201, v202
	v_add_f32_e32 v112, v112, v113
	v_add_f32_e32 v113, v114, v115
	v_and_b32_e32 v115, 0xffff0000, v118
	v_cvt_pk_bf16_f32 v119, v203, v204
	v_and_b32_e32 v125, 0xffff0000, v116
	v_add_f32_e32 v112, v112, v113
	v_and_b32_e32 v113, 0xffff0000, v117
	v_lshlrev_b32_e32 v114, 16, v118
	v_and_b32_e32 v121, 0xffff0000, v119
	v_mul_f32_e32 v115, v115, v115
	v_lshlrev_b32_e32 v124, 16, v116
	v_lshlrev_b32_e32 v126, 16, v117
	v_lshlrev_b32_e32 v120, 16, v119
	v_mul_f32_e32 v122, v125, v125
	v_mul_f32_e32 v113, v113, v113
	v_fmac_f32_e32 v115, v114, v114
	v_mul_f32_e32 v114, v121, v121
	v_fmac_f32_e32 v122, v124, v124
	v_fmac_f32_e32 v113, v126, v126
	v_fmac_f32_e32 v114, v120, v120
	v_add_f32_e32 v113, v122, v113
	v_add_f32_e32 v114, v115, v114
	v_add_f32_e32 v113, v113, v114
	v_and_b32_e32 v114, 64, v200
	v_add_f32_e32 v113, v112, v113
	v_xor_b32_e32 v112, 16, v200
	v_add_u32_e32 v115, 64, v114
	v_cmp_lt_i32_e32 vcc, v112, v115
	global_store_dwordx4 v[212:213], v[116:119], off offset:256 nt
	s_nop 0
	v_cndmask_b32_e32 v112, v200, v112, vcc
	v_lshlrev_b32_e32 v112, 2, v112
	ds_bpermute_b32 v114, v112, v113
	s_waitcnt lgkmcnt(0)
	v_add_f32_e32 v114, v113, v114
	v_xor_b32_e32 v113, 32, v200
	v_cmp_lt_i32_e32 vcc, v113, v115
	s_nop 1
	v_cndmask_b32_e32 v113, v200, v113, vcc
	v_lshlrev_b32_e32 v113, 2, v113
	ds_bpermute_b32 v115, v113, v114
	s_and_saveexec_b64 s[44:45], s[0:1]
	s_cbranch_execz .LBB0_1642
	v_lshlrev_b64 v[116:117], 6, v[182:183]
	v_lshl_add_u64 v[116:117], s[62:63], 0, v[116:117]
	v_lshl_add_u64 v[116:117], s[36:37], 2, v[116:117]
	s_lshl_b32 s10, s19, 2
	v_lshl_add_u64 v[116:117], v[116:117], 0, s[10:11]
	s_waitcnt lgkmcnt(0)
	v_add_f32_e32 v114, v114, v115
	global_store_dword v[116:117], v114, off
; DI unsigned pk2(float lo, float hi) { unsigned r; asm volatile("v_cvt_pk_bf16_f32 %0, %1, %2" : "=v"(r) : "v"(lo), "v"(hi)); return r; }
; DI float bflo(unsigned u) { return __uint_as_float(u << 16); }
; DI float bfhi(unsigned u) { return __uint_as_float(u & 0xffff0000u); }
;     DI float upd(u32x4v* px, const u32x4v x, const f32x4 v0, const f32x4 v1) const {
;         u32x4v o; o.x = pk2(bflo(x.x) + v0[0], bfhi(x.x) + v0[1]); o.y = pk2(bflo(x.y) + v0[2], bfhi(x.y) + v0[3]);
;         o.z = pk2(bflo(x.z) + v1[0], bfhi(x.z) + v1[1]); o.w = pk2(bflo(x.w) + v1[2], bfhi(x.w) + v1[3]); *px = o;
;         const float a0 = bflo(o.x), a1 = bfhi(o.x), a2 = bflo(o.y), a3 = bfhi(o.y), a4 = bflo(o.z), a5 = bfhi(o.z), a6 = bflo(o.w), a7 = bfhi(o.w);
;         return ((a0 * a0 + a1 * a1) + (a2 * a2 + a3 * a3)) + ((a4 * a4 + a5 * a5) + (a6 * a6 + a7 * a7));
;     }
;     DI void operator()(const f32x4 (&acc)[2][2][4][2], const Unit& u, int wr, int wc, int fr, int fq, const Pre& pre) const {
;     ...
;             for (int m = 0; m < 4; ++m)
; #pragma unroll
;                 for (int bj = 0; bj < 2; ++bj) x[m][bj] = *(const u32x4v*)(XB + (size_t)(row0 + ai * 128 + m * 16) * 1024 + cb + bj * 128);
; #pragma unroll
;             for (int m = 0; m < 4; ++m) { const int row = row0 + ai * 128 + m * 16;
;                 float ss = upd((u32x4v*)(XB + (size_t)row * 1024 + cb), x[m][0], acc[ai][0][m][0], acc[ai][0][m][1])
;                          + upd((u32x4v*)(XB + (size_t)row * 1024 + cb + 128), x[m][1], acc[ai][1][m][0], acc[ai][1][m][1]);
;                 ss += __shfl_xor(ss, 16); ss += __shfl_xor(ss, 32);
;                 if (fq == 0) SSQ[(size_t)row * 16 + u.pn * 4 + wc] = ss; } }
.LBB0_1642:
	s_or_b64 exec, exec, s[44:45]
	v_lshlrev_b32_e32 v116, 16, v148
	v_add_f32_e32 v108, v108, v116
	v_and_b32_e32 v116, 0xffff0000, v148
	v_add_f32_e32 v109, v109, v116
	v_cvt_pk_bf16_f32 v108, v108, v109
	v_lshlrev_b32_e32 v109, 16, v149
	v_add_f32_e32 v109, v110, v109
	v_and_b32_e32 v110, 0xffff0000, v149
	v_add_f32_e32 v110, v111, v110
	v_cvt_pk_bf16_f32 v109, v109, v110
	v_lshlrev_b32_e32 v110, 16, v150
	v_add_f32_e32 v104, v104, v110
	v_and_b32_e32 v110, 0xffff0000, v150
	v_add_f32_e32 v105, v105, v110
	v_cvt_pk_bf16_f32 v110, v104, v105
	v_and_b32_e32 v105, 0xffff0000, v151
	v_lshlrev_b32_e32 v104, 16, v151
	v_add_f32_e32 v105, v107, v105
	v_add_f32_e32 v104, v106, v104
	v_cvt_pk_bf16_f32 v111, v104, v105
	v_and_b32_e32 v105, 0xffff0000, v108
	s_waitcnt lgkmcnt(0)
	v_lshl_add_u64 v[114:115], s[60:61], 0, v[196:197]
	v_lshlrev_b32_e32 v104, 16, v108
	v_and_b32_e32 v107, 0xffff0000, v109
	v_mul_f32_e32 v105, v105, v105
	v_lshl_add_u64 v[114:115], v[180:181], 1, v[114:115]
	v_lshlrev_b32_e32 v106, 16, v109
	v_fmac_f32_e32 v105, v104, v104
	v_mul_f32_e32 v104, v107, v107
	global_store_dwordx4 v[114:115], v[108:111], off nt
	v_fmac_f32_e32 v104, v106, v106
	v_add_f32_e32 v104, v105, v104
	v_lshlrev_b32_e32 v108, 16, v110
	v_and_b32_e32 v109, 0xffff0000, v110
	v_lshlrev_b32_e32 v110, 16, v111
	v_and_b32_e32 v111, 0xffff0000, v111
	v_mul_f32_e32 v105, v109, v109
	v_mul_f32_e32 v106, v111, v111
	v_fmac_f32_e32 v105, v108, v108
	v_fmac_f32_e32 v106, v110, v110
	v_add_f32_e32 v105, v105, v106
	v_add_f32_e32 v104, v104, v105
	v_lshlrev_b32_e32 v105, 16, v144
	v_add_f32_e32 v100, v100, v105
	v_and_b32_e32 v105, 0xffff0000, v144
	v_add_f32_e32 v101, v101, v105
	v_cvt_pk_bf16_f32 v100, v100, v101
	v_lshlrev_b32_e32 v101, 16, v145
	v_add_f32_e32 v101, v102, v101
	v_and_b32_e32 v102, 0xffff0000, v145
	v_add_f32_e32 v102, v103, v102
	v_cvt_pk_bf16_f32 v101, v101, v102
	v_lshlrev_b32_e32 v102, 16, v146
	v_add_f32_e32 v96, v96, v102
	v_and_b32_e32 v102, 0xffff0000, v146
	v_add_f32_e32 v97, v97, v102
	v_cvt_pk_bf16_f32 v102, v96, v97
	v_and_b32_e32 v97, 0xffff0000, v147
	v_lshlrev_b32_e32 v96, 16, v147
	v_add_f32_e32 v97, v99, v97
	v_add_f32_e32 v96, v98, v96
	v_cvt_pk_bf16_f32 v103, v96, v97
	v_and_b32_e32 v97, 0xffff0000, v100
	v_lshlrev_b32_e32 v96, 16, v100
	v_and_b32_e32 v99, 0xffff0000, v101
	v_mul_f32_e32 v97, v97, v97
	v_lshlrev_b32_e32 v98, 16, v101
	v_fmac_f32_e32 v97, v96, v96
	v_mul_f32_e32 v96, v99, v99
	v_and_b32_e32 v106, 0xffff0000, v102
	v_and_b32_e32 v108, 0xffff0000, v103
	v_fmac_f32_e32 v96, v98, v98
	v_lshlrev_b32_e32 v105, 16, v102
	v_lshlrev_b32_e32 v107, 16, v103
	v_add_f32_e32 v96, v97, v96
	v_mul_f32_e32 v97, v106, v106
	v_mul_f32_e32 v98, v108, v108
	v_fmac_f32_e32 v97, v105, v105
	v_fmac_f32_e32 v98, v107, v107
	v_add_f32_e32 v97, v97, v98
	v_add_f32_e32 v96, v96, v97
	v_add_f32_e32 v96, v104, v96
	ds_bpermute_b32 v97, v112, v96
	global_store_dwordx4 v[114:115], v[100:103], off offset:256 nt
	s_waitcnt lgkmcnt(0)
	v_add_f32_e32 v96, v96, v97
	ds_bpermute_b32 v97, v113, v96
	s_and_saveexec_b64 s[44:45], s[0:1]
	s_cbranch_execz .LBB0_1644
	v_lshlrev_b64 v[98:99], 6, v[192:193]
	v_lshl_add_u64 v[98:99], s[62:63], 0, v[98:99]
	v_lshl_add_u64 v[98:99], s[36:37], 2, v[98:99]
	s_lshl_b32 s10, s19, 2
	v_lshl_add_u64 v[98:99], v[98:99], 0, s[10:11]
	s_waitcnt lgkmcnt(0)
	v_add_f32_e32 v96, v96, v97
	global_store_dword v[98:99], v96, off
.LBB0_1644:
	s_or_b64 exec, exec, s[44:45]
	v_lshlrev_b32_e32 v98, 16, v140
	v_add_f32_e32 v92, v92, v98
	v_and_b32_e32 v98, 0xffff0000, v140
	v_add_f32_e32 v93, v93, v98
	v_cvt_pk_bf16_f32 v92, v92, v93
	v_lshlrev_b32_e32 v93, 16, v141
	v_add_f32_e32 v93, v94, v93
	v_and_b32_e32 v94, 0xffff0000, v141
	v_add_f32_e32 v94, v95, v94
	v_cvt_pk_bf16_f32 v93, v93, v94
	v_lshlrev_b32_e32 v94, 16, v142
	v_add_f32_e32 v88, v88, v94
	v_and_b32_e32 v94, 0xffff0000, v142
	v_add_f32_e32 v89, v89, v94
	v_cvt_pk_bf16_f32 v94, v88, v89
	v_and_b32_e32 v89, 0xffff0000, v143
	v_lshlrev_b32_e32 v88, 16, v143
	v_add_f32_e32 v89, v91, v89
	v_add_f32_e32 v88, v90, v88
	v_cvt_pk_bf16_f32 v95, v88, v89
	v_and_b32_e32 v89, 0xffff0000, v92
	s_waitcnt lgkmcnt(0)
	v_lshl_add_u64 v[96:97], s[60:61], 0, v[194:195]
	v_lshlrev_b32_e32 v88, 16, v92
	v_and_b32_e32 v91, 0xffff0000, v93
	v_mul_f32_e32 v89, v89, v89
	v_lshl_add_u64 v[96:97], v[180:181], 1, v[96:97]
	v_lshlrev_b32_e32 v90, 16, v93
	v_fmac_f32_e32 v89, v88, v88
	v_mul_f32_e32 v88, v91, v91
	global_store_dwordx4 v[96:97], v[92:95], off nt
	v_fmac_f32_e32 v88, v90, v90
	v_add_f32_e32 v88, v89, v88
	v_lshlrev_b32_e32 v92, 16, v94
	v_and_b32_e32 v93, 0xffff0000, v94
	v_lshlrev_b32_e32 v94, 16, v95
	v_and_b32_e32 v95, 0xffff0000, v95
	v_mul_f32_e32 v89, v93, v93
	v_mul_f32_e32 v90, v95, v95
	v_fmac_f32_e32 v89, v92, v92
	v_fmac_f32_e32 v90, v94, v94
	v_add_f32_e32 v89, v89, v90
	v_add_f32_e32 v88, v88, v89
	v_lshlrev_b32_e32 v89, 16, v136
	v_add_f32_e32 v84, v84, v89
	v_and_b32_e32 v89, 0xffff0000, v136
	v_add_f32_e32 v85, v85, v89
	v_cvt_pk_bf16_f32 v84, v84, v85
	v_lshlrev_b32_e32 v85, 16, v137
	v_add_f32_e32 v85, v86, v85
	v_and_b32_e32 v86, 0xffff0000, v137
	v_add_f32_e32 v86, v87, v86
	v_cvt_pk_bf16_f32 v85, v85, v86
	v_lshlrev_b32_e32 v86, 16, v138
	v_add_f32_e32 v80, v80, v86
	v_and_b32_e32 v86, 0xffff0000, v138
	v_add_f32_e32 v81, v81, v86
	v_cvt_pk_bf16_f32 v86, v80, v81
	v_and_b32_e32 v81, 0xffff0000, v139
	v_lshlrev_b32_e32 v80, 16, v139
	v_add_f32_e32 v81, v83, v81
	v_add_f32_e32 v80, v82, v80
	v_cvt_pk_bf16_f32 v87, v80, v81
	v_and_b32_e32 v81, 0xffff0000, v84
	v_lshlrev_b32_e32 v80, 16, v84
	v_and_b32_e32 v83, 0xffff0000, v85
	v_mul_f32_e32 v81, v81, v81
	v_lshlrev_b32_e32 v82, 16, v85
	v_fmac_f32_e32 v81, v80, v80
	v_mul_f32_e32 v80, v83, v83
	v_and_b32_e32 v90, 0xffff0000, v86
	v_and_b32_e32 v92, 0xffff0000, v87
	v_fmac_f32_e32 v80, v82, v82
	v_lshlrev_b32_e32 v89, 16, v86
	v_lshlrev_b32_e32 v91, 16, v87
	v_add_f32_e32 v80, v81, v80
	v_mul_f32_e32 v81, v90, v90
	v_mul_f32_e32 v82, v92, v92
	v_fmac_f32_e32 v81, v89, v89
	v_fmac_f32_e32 v82, v91, v91
	v_add_f32_e32 v81, v81, v82
	v_add_f32_e32 v80, v80, v81
	v_add_f32_e32 v80, v88, v80
	ds_bpermute_b32 v81, v112, v80
	global_store_dwordx4 v[96:97], v[84:87], off offset:256 nt
	s_waitcnt lgkmcnt(0)
	v_add_f32_e32 v80, v80, v81
	ds_bpermute_b32 v81, v113, v80
	s_and_saveexec_b64 s[44:45], s[0:1]
	s_cbranch_execz .LBB0_1646
	v_lshlrev_b64 v[82:83], 6, v[188:189]
	v_lshl_add_u64 v[82:83], s[62:63], 0, v[82:83]
	v_lshl_add_u64 v[82:83], s[36:37], 2, v[82:83]
	s_lshl_b32 s10, s19, 2
	v_lshl_add_u64 v[82:83], v[82:83], 0, s[10:11]
	s_waitcnt lgkmcnt(0)
	v_add_f32_e32 v80, v80, v81
	global_store_dword v[82:83], v80, off
; DI unsigned pk2(float lo, float hi) { unsigned r; asm volatile("v_cvt_pk_bf16_f32 %0, %1, %2" : "=v"(r) : "v"(lo), "v"(hi)); return r; }
; DI float bflo(unsigned u) { return __uint_as_float(u << 16); }
; DI float bfhi(unsigned u) { return __uint_as_float(u & 0xffff0000u); }
;     DI float upd(u32x4v* px, const u32x4v x, const f32x4 v0, const f32x4 v1) const {
;         u32x4v o; o.x = pk2(bflo(x.x) + v0[0], bfhi(x.x) + v0[1]); o.y = pk2(bflo(x.y) + v0[2], bfhi(x.y) + v0[3]);
;         o.z = pk2(bflo(x.z) + v1[0], bfhi(x.z) + v1[1]); o.w = pk2(bflo(x.w) + v1[2], bfhi(x.w) + v1[3]); *px = o;
;         const float a0 = bflo(o.x), a1 = bfhi(o.x), a2 = bflo(o.y), a3 = bfhi(o.y), a4 = bflo(o.z), a5 = bfhi(o.z), a6 = bflo(o.w), a7 = bfhi(o.w);
;         return ((a0 * a0 + a1 * a1) + (a2 * a2 + a3 * a3)) + ((a4 * a4 + a5 * a5) + (a6 * a6 + a7 * a7));
;     }
;     DI void operator()(const f32x4 (&acc)[2][2][4][2], const Unit& u, int wr, int wc, int fr, int fq, const Pre& pre) const {
;     ...
;             for (int m = 0; m < 4; ++m)
; #pragma unroll
;                 for (int bj = 0; bj < 2; ++bj) x[m][bj] = *(const u32x4v*)(XB + (size_t)(row0 + ai * 128 + m * 16) * 1024 + cb + bj * 128);
; #pragma unroll
;             for (int m = 0; m < 4; ++m) { const int row = row0 + ai * 128 + m * 16;
;                 float ss = upd((u32x4v*)(XB + (size_t)row * 1024 + cb), x[m][0], acc[ai][0][m][0], acc[ai][0][m][1])
;                          + upd((u32x4v*)(XB + (size_t)row * 1024 + cb + 128), x[m][1], acc[ai][1][m][0], acc[ai][1][m][1]);
;                 ss += __shfl_xor(ss, 16); ss += __shfl_xor(ss, 32);
;                 if (fq == 0) SSQ[(size_t)row * 16 + u.pn * 4 + wc] = ss; } }
.LBB0_1646:
	s_or_b64 exec, exec, s[44:45]
	v_lshlrev_b32_e32 v82, 16, v132
	v_add_f32_e32 v76, v76, v82
	v_and_b32_e32 v82, 0xffff0000, v132
	v_add_f32_e32 v77, v77, v82
	v_cvt_pk_bf16_f32 v76, v76, v77
	v_lshlrev_b32_e32 v77, 16, v133
	v_add_f32_e32 v77, v78, v77
	v_and_b32_e32 v78, 0xffff0000, v133
	v_add_f32_e32 v78, v79, v78
	v_cvt_pk_bf16_f32 v77, v77, v78
	v_lshlrev_b32_e32 v78, 16, v134
	v_add_f32_e32 v72, v72, v78
	v_and_b32_e32 v78, 0xffff0000, v134
	v_add_f32_e32 v73, v73, v78
	v_cvt_pk_bf16_f32 v78, v72, v73
	v_and_b32_e32 v73, 0xffff0000, v135
	v_lshlrev_b32_e32 v72, 16, v135
	v_add_f32_e32 v73, v75, v73
	v_add_f32_e32 v72, v74, v72
	v_cvt_pk_bf16_f32 v79, v72, v73
	v_and_b32_e32 v73, 0xffff0000, v76
	s_waitcnt lgkmcnt(0)
	v_lshl_add_u64 v[80:81], s[60:61], 0, v[190:191]
	v_lshlrev_b32_e32 v72, 16, v76
	v_and_b32_e32 v75, 0xffff0000, v77
	v_mul_f32_e32 v73, v73, v73
	v_lshl_add_u64 v[80:81], v[180:181], 1, v[80:81]
	v_lshlrev_b32_e32 v74, 16, v77
	v_fmac_f32_e32 v73, v72, v72
	v_mul_f32_e32 v72, v75, v75
	global_store_dwordx4 v[80:81], v[76:79], off nt
	v_fmac_f32_e32 v72, v74, v74
	v_add_f32_e32 v72, v73, v72
	v_lshlrev_b32_e32 v76, 16, v78
	v_and_b32_e32 v77, 0xffff0000, v78
	v_lshlrev_b32_e32 v78, 16, v79
	v_and_b32_e32 v79, 0xffff0000, v79
	v_mul_f32_e32 v73, v77, v77
	v_mul_f32_e32 v74, v79, v79
	v_fmac_f32_e32 v73, v76, v76
	v_fmac_f32_e32 v74, v78, v78
	v_add_f32_e32 v73, v73, v74
	v_add_f32_e32 v72, v72, v73
	v_lshlrev_b32_e32 v73, 16, v128
	v_add_f32_e32 v68, v68, v73
	v_and_b32_e32 v73, 0xffff0000, v128
	v_add_f32_e32 v69, v69, v73
	v_cvt_pk_bf16_f32 v68, v68, v69
	v_lshlrev_b32_e32 v69, 16, v129
	v_add_f32_e32 v69, v70, v69
	v_and_b32_e32 v70, 0xffff0000, v129
	v_add_f32_e32 v70, v71, v70
	v_cvt_pk_bf16_f32 v69, v69, v70
	v_lshlrev_b32_e32 v70, 16, v130
	v_add_f32_e32 v64, v64, v70
	v_and_b32_e32 v70, 0xffff0000, v130
	v_add_f32_e32 v65, v65, v70
	v_cvt_pk_bf16_f32 v70, v64, v65
	v_and_b32_e32 v65, 0xffff0000, v131
	v_lshlrev_b32_e32 v64, 16, v131
	v_add_f32_e32 v65, v67, v65
	v_add_f32_e32 v64, v66, v64
	v_cvt_pk_bf16_f32 v71, v64, v65
	v_and_b32_e32 v65, 0xffff0000, v68
	v_lshlrev_b32_e32 v64, 16, v68
	v_and_b32_e32 v67, 0xffff0000, v69
	v_mul_f32_e32 v65, v65, v65
	v_lshlrev_b32_e32 v66, 16, v69
	v_fmac_f32_e32 v65, v64, v64
	v_mul_f32_e32 v64, v67, v67
	v_and_b32_e32 v74, 0xffff0000, v70
	v_and_b32_e32 v76, 0xffff0000, v71
	v_fmac_f32_e32 v64, v66, v66
	v_lshlrev_b32_e32 v73, 16, v70
	v_lshlrev_b32_e32 v75, 16, v71
	v_add_f32_e32 v64, v65, v64
	v_mul_f32_e32 v65, v74, v74
	v_mul_f32_e32 v66, v76, v76
	v_fmac_f32_e32 v65, v73, v73
	v_fmac_f32_e32 v66, v75, v75
	v_add_f32_e32 v65, v65, v66
	v_add_f32_e32 v64, v64, v65
	v_add_f32_e32 v64, v72, v64
	ds_bpermute_b32 v65, v112, v64
	global_store_dwordx4 v[80:81], v[68:71], off offset:256 nt
	s_waitcnt lgkmcnt(0)
	v_add_f32_e32 v64, v64, v65
	ds_bpermute_b32 v65, v113, v64
	s_and_saveexec_b64 s[44:45], s[0:1]
	s_cbranch_execz .LBB0_1648
	v_lshlrev_b64 v[66:67], 6, v[186:187]
	v_lshl_add_u64 v[66:67], s[62:63], 0, v[66:67]
	v_lshl_add_u64 v[66:67], s[36:37], 2, v[66:67]
	s_lshl_b32 s10, s19, 2
	v_lshl_add_u64 v[66:67], v[66:67], 0, s[10:11]
	s_waitcnt lgkmcnt(0)
	v_add_f32_e32 v64, v64, v65
	global_store_dword v[66:67], v64, off
.LBB0_1648:
	s_or_b64 exec, exec, s[44:45]
	v_add_u32_e32 v98, 0x80, v182
	v_ashrrev_i32_e32 v99, 31, v98
	s_waitcnt lgkmcnt(0)
	v_lshlrev_b64 v[64:65], 11, v[98:99]
	v_lshl_add_u64 v[66:67], v[184:185], 0, v[64:65]
	global_load_dwordx4 v[102:105], v[66:67], off
	global_load_dwordx4 v[106:109], v[66:67], off offset:256
	v_add_u32_e32 v94, 0x90, v182
	v_add_u32_e32 v90, 0xa0, v182
	v_add_u32_e32 v88, 0xb0, v182
	v_ashrrev_i32_e32 v95, 31, v94
	v_ashrrev_i32_e32 v91, 31, v90
	v_ashrrev_i32_e32 v89, 31, v88
	v_lshlrev_b64 v[100:101], 11, v[94:95]
	v_lshlrev_b64 v[96:97], 11, v[90:91]
	v_lshlrev_b64 v[92:93], 11, v[88:89]
	v_lshl_add_u64 v[66:67], v[184:185], 0, v[100:101]
	v_lshl_add_u64 v[68:69], v[184:185], 0, v[96:97]
	v_lshl_add_u64 v[110:111], v[184:185], 0, v[92:93]
	v_lshl_add_u64 v[114:115], s[60:61], 0, v[64:65]
	global_load_dwordx4 v[84:87], v[66:67], off
	global_load_dwordx4 v[80:83], v[66:67], off offset:256
	global_load_dwordx4 v[76:79], v[68:69], off
	global_load_dwordx4 v[72:75], v[68:69], off offset:256
	s_nop 0
	global_load_dwordx4 v[68:71], v[110:111], off
	global_load_dwordx4 v[64:67], v[110:111], off offset:256
	v_lshl_add_u64 v[110:111], v[180:181], 1, v[114:115]
	s_waitcnt vmcnt(7)
	v_lshlrev_b32_e32 v114, 16, v102
	v_and_b32_e32 v102, 0xffff0000, v102
	v_lshlrev_b32_e32 v115, 16, v103
	v_and_b32_e32 v103, 0xffff0000, v103
	v_lshlrev_b32_e32 v116, 16, v104
	v_and_b32_e32 v104, 0xffff0000, v104
	v_lshlrev_b32_e32 v117, 16, v105
	v_and_b32_e32 v105, 0xffff0000, v105
	s_waitcnt vmcnt(6)
; DI unsigned pk2(float lo, float hi) { unsigned r; asm volatile("v_cvt_pk_bf16_f32 %0, %1, %2" : "=v"(r) : "v"(lo), "v"(hi)); return r; }
; DI float bflo(unsigned u) { return __uint_as_float(u << 16); }
; DI float bfhi(unsigned u) { return __uint_as_float(u & 0xffff0000u); }
;     DI float upd(u32x4v* px, const u32x4v x, const f32x4 v0, const f32x4 v1) const {
;         u32x4v o; o.x = pk2(bflo(x.x) + v0[0], bfhi(x.x) + v0[1]); o.y = pk2(bflo(x.y) + v0[2], bfhi(x.y) + v0[3]);
;         o.z = pk2(bflo(x.z) + v1[0], bfhi(x.z) + v1[1]); o.w = pk2(bflo(x.w) + v1[2], bfhi(x.w) + v1[3]); *px = o;
;         const float a0 = bflo(o.x), a1 = bfhi(o.x), a2 = bflo(o.y), a3 = bfhi(o.y), a4 = bflo(o.z), a5 = bfhi(o.z), a6 = bflo(o.w), a7 = bfhi(o.w);
;         return ((a0 * a0 + a1 * a1) + (a2 * a2 + a3 * a3)) + ((a4 * a4 + a5 * a5) + (a6 * a6 + a7 * a7));
;     }
;     DI void operator()(const f32x4 (&acc)[2][2][4][2], const Unit& u, int wr, int wc, int fr, int fq, const Pre& pre) const {
;     ...
;             for (int m = 0; m < 4; ++m)
; #pragma unroll
;                 for (int bj = 0; bj < 2; ++bj) x[m][bj] = *(const u32x4v*)(XB + (size_t)(row0 + ai * 128 + m * 16) * 1024 + cb + bj * 128);
; #pragma unroll
;             for (int m = 0; m < 4; ++m) { const int row = row0 + ai * 128 + m * 16;
;                 float ss = upd((u32x4v*)(XB + (size_t)row * 1024 + cb), x[m][0], acc[ai][0][m][0], acc[ai][0][m][1])
;                          + upd((u32x4v*)(XB + (size_t)row * 1024 + cb + 128), x[m][1], acc[ai][1][m][0], acc[ai][1][m][1]);
;                 ss += __shfl_xor(ss, 16); ss += __shfl_xor(ss, 32);
;                 if (fq == 0) SSQ[(size_t)row * 16 + u.pn * 4 + wc] = ss; } }
	v_lshlrev_b32_e32 v120, 16, v108
	v_and_b32_e32 v108, 0xffff0000, v108
	v_lshlrev_b32_e32 v119, 16, v107
	v_and_b32_e32 v107, 0xffff0000, v107
	v_lshlrev_b32_e32 v121, 16, v109
	v_and_b32_e32 v109, 0xffff0000, v109
	v_add_f32_e32 v60, v60, v114
	v_add_f32_e32 v61, v61, v102
	v_add_f32_e32 v62, v62, v115
	v_add_f32_e32 v63, v63, v103
	v_add_f32_e32 v56, v56, v116
	v_add_f32_e32 v57, v57, v104
	v_add_f32_e32 v59, v59, v105
	v_add_f32_e32 v102, v48, v120
	v_add_f32_e32 v103, v49, v108
	v_cvt_pk_bf16_f32 v48, v60, v61
	v_cvt_pk_bf16_f32 v49, v62, v63
	v_lshlrev_b32_e32 v118, 16, v106
	v_and_b32_e32 v106, 0xffff0000, v106
	v_add_f32_e32 v58, v58, v117
	v_add_f32_e32 v54, v54, v119
	v_add_f32_e32 v55, v55, v107
	v_add_f32_e32 v104, v50, v121
	v_add_f32_e32 v105, v51, v109
	v_cvt_pk_bf16_f32 v50, v56, v57
	v_cvt_pk_bf16_f32 v51, v58, v59
	global_store_dwordx4 v[110:111], v[48:51], off nt
	v_lshlrev_b32_e32 v56, 16, v48
	v_lshlrev_b32_e32 v57, 16, v49
	v_and_b32_e32 v48, 0xffff0000, v48
	v_and_b32_e32 v49, 0xffff0000, v49
	v_and_b32_e32 v59, 0xffff0000, v50
	v_and_b32_e32 v61, 0xffff0000, v51
	v_add_f32_e32 v52, v52, v118
	v_add_f32_e32 v53, v53, v106
	v_lshlrev_b32_e32 v58, 16, v50
	v_lshlrev_b32_e32 v60, 16, v51
	v_cvt_pk_bf16_f32 v50, v52, v53
	v_cvt_pk_bf16_f32 v51, v54, v55
	v_mul_f32_e32 v48, v48, v48
	v_mul_f32_e32 v49, v49, v49
	v_mul_f32_e32 v54, v59, v59
	v_mul_f32_e32 v55, v61, v61
	v_and_b32_e32 v61, 0xffff0000, v50
	v_and_b32_e32 v63, 0xffff0000, v51
	v_fmac_f32_e32 v48, v56, v56
	v_fmac_f32_e32 v49, v57, v57
	v_fmac_f32_e32 v54, v58, v58
	v_fmac_f32_e32 v55, v60, v60
	v_lshlrev_b32_e32 v59, 16, v50
	v_lshlrev_b32_e32 v62, 16, v51
	v_add_f32_e32 v48, v48, v49
	v_add_f32_e32 v49, v54, v55
	v_mul_f32_e32 v55, v61, v61
	v_mul_f32_e32 v56, v63, v63
	v_cvt_pk_bf16_f32 v52, v102, v103
	v_cvt_pk_bf16_f32 v53, v104, v105
	v_fmac_f32_e32 v55, v59, v59
	v_and_b32_e32 v103, 0xffff0000, v52
	v_and_b32_e32 v54, 0xffff0000, v53
	v_fmac_f32_e32 v56, v62, v62
	v_lshlrev_b32_e32 v102, 16, v52
	v_add_f32_e32 v48, v48, v49
	v_lshlrev_b32_e32 v49, 16, v53
	v_add_f32_e32 v55, v55, v56
	v_mul_f32_e32 v56, v103, v103
	v_mul_f32_e32 v54, v54, v54
	v_fmac_f32_e32 v56, v102, v102
	v_fmac_f32_e32 v54, v49, v49
	v_add_f32_e32 v49, v56, v54
	v_add_f32_e32 v49, v55, v49
	v_add_f32_e32 v48, v48, v49
	ds_bpermute_b32 v49, v112, v48
	global_store_dwordx4 v[110:111], v[50:53], off offset:256 nt
	s_waitcnt lgkmcnt(0)
	v_add_f32_e32 v48, v48, v49
	ds_bpermute_b32 v49, v113, v48
	s_and_saveexec_b64 s[44:45], s[0:1]
	s_cbranch_execz .LBB0_1650
	v_lshlrev_b64 v[50:51], 6, v[98:99]
	v_lshl_add_u64 v[50:51], s[62:63], 0, v[50:51]
	v_lshl_add_u64 v[50:51], s[36:37], 2, v[50:51]
	s_lshl_b32 s10, s19, 2
	v_lshl_add_u64 v[50:51], v[50:51], 0, s[10:11]
	s_waitcnt lgkmcnt(0)
	v_add_f32_e32 v48, v48, v49
	global_store_dword v[50:51], v48, off
.LBB0_1650:
	s_or_b64 exec, exec, s[44:45]
	s_waitcnt vmcnt(7)
	v_lshlrev_b32_e32 v50, 16, v84
	v_add_f32_e32 v44, v44, v50
	v_and_b32_e32 v50, 0xffff0000, v84
	v_add_f32_e32 v45, v45, v50
	v_cvt_pk_bf16_f32 v44, v44, v45
	v_lshlrev_b32_e32 v45, 16, v85
	v_add_f32_e32 v45, v46, v45
	v_and_b32_e32 v46, 0xffff0000, v85
	v_add_f32_e32 v46, v47, v46
	v_cvt_pk_bf16_f32 v45, v45, v46
	v_lshlrev_b32_e32 v46, 16, v86
	v_add_f32_e32 v40, v40, v46
	v_and_b32_e32 v46, 0xffff0000, v86
	v_add_f32_e32 v41, v41, v46
	v_cvt_pk_bf16_f32 v46, v40, v41
	v_and_b32_e32 v41, 0xffff0000, v87
	v_lshlrev_b32_e32 v40, 16, v87
	v_add_f32_e32 v41, v43, v41
	v_add_f32_e32 v40, v42, v40
	v_cvt_pk_bf16_f32 v47, v40, v41
	v_and_b32_e32 v41, 0xffff0000, v44
	s_waitcnt lgkmcnt(0)
	v_lshl_add_u64 v[48:49], s[60:61], 0, v[100:101]
	v_lshlrev_b32_e32 v40, 16, v44
	v_and_b32_e32 v43, 0xffff0000, v45
	v_mul_f32_e32 v41, v41, v41
	v_lshl_add_u64 v[48:49], v[180:181], 1, v[48:49]
	v_lshlrev_b32_e32 v42, 16, v45
	v_fmac_f32_e32 v41, v40, v40
	v_mul_f32_e32 v40, v43, v43
	global_store_dwordx4 v[48:49], v[44:47], off nt
	v_fmac_f32_e32 v40, v42, v42
	v_add_f32_e32 v40, v41, v40
	v_lshlrev_b32_e32 v44, 16, v46
	v_and_b32_e32 v45, 0xffff0000, v46
	v_lshlrev_b32_e32 v46, 16, v47
	v_and_b32_e32 v47, 0xffff0000, v47
	v_mul_f32_e32 v41, v45, v45
	v_mul_f32_e32 v42, v47, v47
	v_fmac_f32_e32 v41, v44, v44
	v_fmac_f32_e32 v42, v46, v46
	v_add_f32_e32 v41, v41, v42
	v_add_f32_e32 v40, v40, v41
	s_waitcnt vmcnt(7)
	v_lshlrev_b32_e32 v41, 16, v80
	v_add_f32_e32 v36, v36, v41
	v_and_b32_e32 v41, 0xffff0000, v80
	v_add_f32_e32 v37, v37, v41
	v_cvt_pk_bf16_f32 v36, v36, v37
	v_lshlrev_b32_e32 v37, 16, v81
	v_add_f32_e32 v37, v38, v37
	v_and_b32_e32 v38, 0xffff0000, v81
	v_add_f32_e32 v38, v39, v38
	v_cvt_pk_bf16_f32 v37, v37, v38
	v_lshlrev_b32_e32 v38, 16, v82
	v_add_f32_e32 v32, v32, v38
	v_and_b32_e32 v38, 0xffff0000, v82
	v_add_f32_e32 v33, v33, v38
	v_cvt_pk_bf16_f32 v38, v32, v33
	v_and_b32_e32 v33, 0xffff0000, v83
	v_lshlrev_b32_e32 v32, 16, v83
	v_add_f32_e32 v33, v35, v33
	v_add_f32_e32 v32, v34, v32
	v_cvt_pk_bf16_f32 v39, v32, v33
	v_and_b32_e32 v33, 0xffff0000, v36
	v_lshlrev_b32_e32 v32, 16, v36
	v_and_b32_e32 v35, 0xffff0000, v37
	v_mul_f32_e32 v33, v33, v33
	v_lshlrev_b32_e32 v34, 16, v37
	v_fmac_f32_e32 v33, v32, v32
	v_mul_f32_e32 v32, v35, v35
	v_and_b32_e32 v42, 0xffff0000, v38
	v_and_b32_e32 v44, 0xffff0000, v39
	v_fmac_f32_e32 v32, v34, v34
	v_lshlrev_b32_e32 v41, 16, v38
	v_lshlrev_b32_e32 v43, 16, v39
	v_add_f32_e32 v32, v33, v32
	v_mul_f32_e32 v33, v42, v42
	v_mul_f32_e32 v34, v44, v44
	v_fmac_f32_e32 v33, v41, v41
	v_fmac_f32_e32 v34, v43, v43
	v_add_f32_e32 v33, v33, v34
	v_add_f32_e32 v32, v32, v33
	v_add_f32_e32 v32, v40, v32
	ds_bpermute_b32 v33, v112, v32
	global_store_dwordx4 v[48:49], v[36:39], off offset:256 nt
	s_waitcnt lgkmcnt(0)
	v_add_f32_e32 v32, v32, v33
	ds_bpermute_b32 v33, v113, v32
	s_and_saveexec_b64 s[44:45], s[0:1]
	s_cbranch_execz .LBB0_1652
	v_lshlrev_b64 v[34:35], 6, v[94:95]
	v_lshl_add_u64 v[34:35], s[62:63], 0, v[34:35]
	v_lshl_add_u64 v[34:35], s[36:37], 2, v[34:35]
	s_lshl_b32 s10, s19, 2
	v_lshl_add_u64 v[34:35], v[34:35], 0, s[10:11]
	s_waitcnt lgkmcnt(0)
	v_add_f32_e32 v32, v32, v33
	global_store_dword v[34:35], v32, off
; DI unsigned pk2(float lo, float hi) { unsigned r; asm volatile("v_cvt_pk_bf16_f32 %0, %1, %2" : "=v"(r) : "v"(lo), "v"(hi)); return r; }
; DI float bflo(unsigned u) { return __uint_as_float(u << 16); }
; DI float bfhi(unsigned u) { return __uint_as_float(u & 0xffff0000u); }
;     DI float upd(u32x4v* px, const u32x4v x, const f32x4 v0, const f32x4 v1) const {
;         u32x4v o; o.x = pk2(bflo(x.x) + v0[0], bfhi(x.x) + v0[1]); o.y = pk2(bflo(x.y) + v0[2], bfhi(x.y) + v0[3]);
;         o.z = pk2(bflo(x.z) + v1[0], bfhi(x.z) + v1[1]); o.w = pk2(bflo(x.w) + v1[2], bfhi(x.w) + v1[3]); *px = o;
;         const float a0 = bflo(o.x), a1 = bfhi(o.x), a2 = bflo(o.y), a3 = bfhi(o.y), a4 = bflo(o.z), a5 = bfhi(o.z), a6 = bflo(o.w), a7 = bfhi(o.w);
;         return ((a0 * a0 + a1 * a1) + (a2 * a2 + a3 * a3)) + ((a4 * a4 + a5 * a5) + (a6 * a6 + a7 * a7));
;     }
;     DI void operator()(const f32x4 (&acc)[2][2][4][2], const Unit& u, int wr, int wc, int fr, int fq, const Pre& pre) const {
;     ...
;             for (int m = 0; m < 4; ++m)
; #pragma unroll
;                 for (int bj = 0; bj < 2; ++bj) x[m][bj] = *(const u32x4v*)(XB + (size_t)(row0 + ai * 128 + m * 16) * 1024 + cb + bj * 128);
; #pragma unroll
;             for (int m = 0; m < 4; ++m) { const int row = row0 + ai * 128 + m * 16;
;                 float ss = upd((u32x4v*)(XB + (size_t)row * 1024 + cb), x[m][0], acc[ai][0][m][0], acc[ai][0][m][1])
;                          + upd((u32x4v*)(XB + (size_t)row * 1024 + cb + 128), x[m][1], acc[ai][1][m][0], acc[ai][1][m][1]);
;                 ss += __shfl_xor(ss, 16); ss += __shfl_xor(ss, 32);
;                 if (fq == 0) SSQ[(size_t)row * 16 + u.pn * 4 + wc] = ss; } }
.LBB0_1652:
	s_or_b64 exec, exec, s[44:45]
	s_waitcnt vmcnt(7)
	v_lshlrev_b32_e32 v34, 16, v76
	v_add_f32_e32 v28, v28, v34
	v_and_b32_e32 v34, 0xffff0000, v76
	v_add_f32_e32 v29, v29, v34
	v_cvt_pk_bf16_f32 v28, v28, v29
	v_lshlrev_b32_e32 v29, 16, v77
	v_add_f32_e32 v29, v30, v29
	v_and_b32_e32 v30, 0xffff0000, v77
	v_add_f32_e32 v30, v31, v30
	v_cvt_pk_bf16_f32 v29, v29, v30
	v_lshlrev_b32_e32 v30, 16, v78
	v_add_f32_e32 v24, v24, v30
	v_and_b32_e32 v30, 0xffff0000, v78
	v_add_f32_e32 v25, v25, v30
	v_cvt_pk_bf16_f32 v30, v24, v25
	v_and_b32_e32 v25, 0xffff0000, v79
	v_lshlrev_b32_e32 v24, 16, v79
	v_add_f32_e32 v25, v27, v25
	v_add_f32_e32 v24, v26, v24
	v_cvt_pk_bf16_f32 v31, v24, v25
	v_and_b32_e32 v25, 0xffff0000, v28
	s_waitcnt lgkmcnt(0)
	v_lshl_add_u64 v[32:33], s[60:61], 0, v[96:97]
	v_lshlrev_b32_e32 v24, 16, v28
	v_and_b32_e32 v27, 0xffff0000, v29
	v_mul_f32_e32 v25, v25, v25
	v_lshl_add_u64 v[32:33], v[180:181], 1, v[32:33]
	v_lshlrev_b32_e32 v26, 16, v29
	v_fmac_f32_e32 v25, v24, v24
	v_mul_f32_e32 v24, v27, v27
	global_store_dwordx4 v[32:33], v[28:31], off nt
	v_fmac_f32_e32 v24, v26, v26
	v_add_f32_e32 v24, v25, v24
	v_lshlrev_b32_e32 v28, 16, v30
	v_and_b32_e32 v29, 0xffff0000, v30
	v_lshlrev_b32_e32 v30, 16, v31
	v_and_b32_e32 v31, 0xffff0000, v31
	v_mul_f32_e32 v25, v29, v29
	v_mul_f32_e32 v26, v31, v31
	v_fmac_f32_e32 v25, v28, v28
	v_fmac_f32_e32 v26, v30, v30
	v_add_f32_e32 v25, v25, v26
	v_add_f32_e32 v24, v24, v25
	s_waitcnt vmcnt(7)
	v_lshlrev_b32_e32 v25, 16, v72
	v_add_f32_e32 v20, v20, v25
	v_and_b32_e32 v25, 0xffff0000, v72
	v_add_f32_e32 v21, v21, v25
	v_cvt_pk_bf16_f32 v20, v20, v21
	v_lshlrev_b32_e32 v21, 16, v73
	v_add_f32_e32 v21, v22, v21
	v_and_b32_e32 v22, 0xffff0000, v73
	v_add_f32_e32 v22, v23, v22
	v_cvt_pk_bf16_f32 v21, v21, v22
	v_lshlrev_b32_e32 v22, 16, v74
	v_add_f32_e32 v16, v16, v22
	v_and_b32_e32 v22, 0xffff0000, v74
	v_add_f32_e32 v17, v17, v22
	v_cvt_pk_bf16_f32 v22, v16, v17
	v_and_b32_e32 v17, 0xffff0000, v75
	v_lshlrev_b32_e32 v16, 16, v75
	v_add_f32_e32 v17, v19, v17
	v_add_f32_e32 v16, v18, v16
	v_cvt_pk_bf16_f32 v23, v16, v17
	v_and_b32_e32 v17, 0xffff0000, v20
	v_lshlrev_b32_e32 v16, 16, v20
	v_and_b32_e32 v19, 0xffff0000, v21
	v_mul_f32_e32 v17, v17, v17
	v_lshlrev_b32_e32 v18, 16, v21
	v_fmac_f32_e32 v17, v16, v16
	v_mul_f32_e32 v16, v19, v19
	v_and_b32_e32 v26, 0xffff0000, v22
	v_and_b32_e32 v28, 0xffff0000, v23
	v_fmac_f32_e32 v16, v18, v18
	v_lshlrev_b32_e32 v25, 16, v22
	v_lshlrev_b32_e32 v27, 16, v23
	v_add_f32_e32 v16, v17, v16
	v_mul_f32_e32 v17, v26, v26
	v_mul_f32_e32 v18, v28, v28
	v_fmac_f32_e32 v17, v25, v25
	v_fmac_f32_e32 v18, v27, v27
	v_add_f32_e32 v17, v17, v18
	v_add_f32_e32 v16, v16, v17
	v_add_f32_e32 v16, v24, v16
	ds_bpermute_b32 v17, v112, v16
	global_store_dwordx4 v[32:33], v[20:23], off offset:256 nt
	s_waitcnt lgkmcnt(0)
	v_add_f32_e32 v16, v16, v17
	ds_bpermute_b32 v17, v113, v16
	s_and_saveexec_b64 s[44:45], s[0:1]
	s_cbranch_execz .LBB0_1654
	v_lshlrev_b64 v[18:19], 6, v[90:91]
	v_lshl_add_u64 v[18:19], s[62:63], 0, v[18:19]
	v_lshl_add_u64 v[18:19], s[36:37], 2, v[18:19]
	s_lshl_b32 s10, s19, 2
	v_lshl_add_u64 v[18:19], v[18:19], 0, s[10:11]
	s_waitcnt lgkmcnt(0)
	v_add_f32_e32 v16, v16, v17
	global_store_dword v[18:19], v16, off
.LBB0_1654:
	s_or_b64 exec, exec, s[44:45]
	s_waitcnt vmcnt(7)
	v_lshlrev_b32_e32 v18, 16, v68
	v_add_f32_e32 v12, v12, v18
	v_and_b32_e32 v18, 0xffff0000, v68
	v_add_f32_e32 v13, v13, v18
	v_cvt_pk_bf16_f32 v12, v12, v13
	v_lshlrev_b32_e32 v13, 16, v69
	v_add_f32_e32 v13, v14, v13
	v_and_b32_e32 v14, 0xffff0000, v69
	v_add_f32_e32 v14, v15, v14
	v_cvt_pk_bf16_f32 v13, v13, v14
	v_lshlrev_b32_e32 v14, 16, v70
	v_add_f32_e32 v8, v8, v14
	v_and_b32_e32 v14, 0xffff0000, v70
	v_add_f32_e32 v9, v9, v14
	v_cvt_pk_bf16_f32 v14, v8, v9
	v_and_b32_e32 v9, 0xffff0000, v71
	v_lshlrev_b32_e32 v8, 16, v71
	v_add_f32_e32 v9, v11, v9
	v_add_f32_e32 v8, v10, v8
	v_cvt_pk_bf16_f32 v15, v8, v9
	v_and_b32_e32 v9, 0xffff0000, v12
	s_waitcnt lgkmcnt(0)
	v_lshl_add_u64 v[16:17], s[60:61], 0, v[92:93]
	v_lshlrev_b32_e32 v8, 16, v12
	v_and_b32_e32 v11, 0xffff0000, v13
	v_mul_f32_e32 v9, v9, v9
	v_lshl_add_u64 v[16:17], v[180:181], 1, v[16:17]
	v_lshlrev_b32_e32 v10, 16, v13
	v_fmac_f32_e32 v9, v8, v8
	v_mul_f32_e32 v8, v11, v11
	global_store_dwordx4 v[16:17], v[12:15], off nt
	v_fmac_f32_e32 v8, v10, v10
	v_add_f32_e32 v8, v9, v8
	v_lshlrev_b32_e32 v12, 16, v14
	v_and_b32_e32 v13, 0xffff0000, v14
	v_lshlrev_b32_e32 v14, 16, v15
	v_and_b32_e32 v15, 0xffff0000, v15
	v_mul_f32_e32 v9, v13, v13
	v_mul_f32_e32 v10, v15, v15
	v_fmac_f32_e32 v9, v12, v12
	v_fmac_f32_e32 v10, v14, v14
	v_add_f32_e32 v9, v9, v10
	v_add_f32_e32 v8, v8, v9
	s_waitcnt vmcnt(7)
	v_lshlrev_b32_e32 v9, 16, v64
	v_add_f32_e32 v4, v4, v9
	v_and_b32_e32 v9, 0xffff0000, v64
	v_add_f32_e32 v5, v5, v9
	v_cvt_pk_bf16_f32 v4, v4, v5
	v_lshlrev_b32_e32 v5, 16, v65
	v_add_f32_e32 v5, v6, v5
	v_and_b32_e32 v6, 0xffff0000, v65
	v_add_f32_e32 v6, v7, v6
	v_cvt_pk_bf16_f32 v5, v5, v6
	v_lshlrev_b32_e32 v6, 16, v66
	v_add_f32_e32 v0, v0, v6
	v_and_b32_e32 v6, 0xffff0000, v66
	v_add_f32_e32 v1, v1, v6
	v_cvt_pk_bf16_f32 v6, v0, v1
	v_and_b32_e32 v1, 0xffff0000, v67
	v_lshlrev_b32_e32 v0, 16, v67
	v_add_f32_e32 v1, v3, v1
	v_add_f32_e32 v0, v2, v0
	v_cvt_pk_bf16_f32 v7, v0, v1
	v_and_b32_e32 v1, 0xffff0000, v4
	v_lshlrev_b32_e32 v0, 16, v4
	v_and_b32_e32 v3, 0xffff0000, v5
	v_mul_f32_e32 v1, v1, v1
	v_lshlrev_b32_e32 v2, 16, v5
	v_fmac_f32_e32 v1, v0, v0
	v_mul_f32_e32 v0, v3, v3
	v_and_b32_e32 v10, 0xffff0000, v6
	v_and_b32_e32 v12, 0xffff0000, v7
	v_fmac_f32_e32 v0, v2, v2
	v_lshlrev_b32_e32 v9, 16, v6
	v_lshlrev_b32_e32 v11, 16, v7
	v_add_f32_e32 v0, v1, v0
	v_mul_f32_e32 v1, v10, v10
	v_mul_f32_e32 v2, v12, v12
	v_fmac_f32_e32 v1, v9, v9
	v_fmac_f32_e32 v2, v11, v11
	v_add_f32_e32 v1, v1, v2
	v_add_f32_e32 v0, v0, v1
	v_add_f32_e32 v0, v8, v0
	ds_bpermute_b32 v1, v112, v0
	global_store_dwordx4 v[16:17], v[4:7], off offset:256 nt
	s_waitcnt lgkmcnt(0)
	v_add_f32_e32 v0, v0, v1
	ds_bpermute_b32 v1, v113, v0
	s_and_saveexec_b64 s[44:45], s[0:1]
	s_cbranch_execz .LBB0_1606
	v_readlane_b32 s48, v254, 28
	v_lshlrev_b64 v[2:3], 6, v[88:89]
	v_readlane_b32 s62, v254, 42
	v_readlane_b32 s63, v254, 43
	s_lshl_b32 s10, s19, 2
	s_waitcnt lgkmcnt(0)
	v_add_f32_e32 v0, v0, v1
	v_lshl_add_u64 v[2:3], s[62:63], 0, v[2:3]
	v_lshl_add_u64 v[2:3], s[36:37], 2, v[2:3]
	v_lshl_add_u64 v[2:3], v[2:3], 0, s[10:11]
	v_readlane_b32 s49, v254, 29
	v_readlane_b32 s50, v254, 30
	v_readlane_b32 s51, v254, 31
	v_readlane_b32 s52, v254, 32
	v_readlane_b32 s53, v254, 33
	v_readlane_b32 s54, v254, 34
	v_readlane_b32 s55, v254, 35
	v_readlane_b32 s56, v254, 36
	v_readlane_b32 s57, v254, 37
	v_readlane_b32 s58, v254, 38
	v_readlane_b32 s59, v254, 39
	v_readlane_b32 s60, v254, 40
	v_readlane_b32 s61, v254, 41
	global_store_dword v[2:3], v0, off
	s_branch .LBB0_1606

;     DI void row(const f32x4 (&a4)[2][2], const Unit& u, int ai, int m, int wr, int wc, int fr, int fq) const {
;         const int cb = u.pn * 256 + wc * 32 + 8 * fq, row = u.pm * 256 + wr * 64 + fr + ai * 128 + m * 16;
;         u32x4v* p0 = (u32x4v*)(XB + (size_t)row * 1024 + cb); u32x4v* p1 = (u32x4v*)(XB + (size_t)row * 1024 + cb + 128);
;         const u32x4v x0 = *p0, x1 = *p1;
;         float ss = upd(p0, x0, a4[0][0], a4[0][1]) + upd(p1, x1, a4[1][0], a4[1][1]);
;         ss += __shfl_xor(ss, 16); ss += __shfl_xor(ss, 32);
;         if (fq == 0) SSQ[(size_t)row * 16 + u.pn * 4 + wc] = ss;
;     }
; template <class Epi> DI void gemm_fixup(int N, int K, const Epi& E, const float* part, int tid) {
;     ...
;     for (int it = blockIdx.x; it < S.ntail * 8; it += gridDim.x) { const int j = it >> 3, ai = (it >> 2) & 1, m = it & 3; Unit u; S.map(S.nwhole * S.G + j, u);
;         f32x4 a4[2][2];
; #pragma unroll
;         for (int b = 0; b < 2; ++b)
; #pragma unroll
;             for (int n = 0; n < 2; ++n) { const f32x4* pp = (const f32x4*)part + ((size_t)(j * S.S) * 32 + (((ai * 2 + b) * 4 + m) * 2 + n)) * 512 + tid;
;                 f32x4 v0 = {0.f, 0.f, 0.f, 0.f}, v1 = v0, v2 = v0, v3 = v0;
;                 for (int sl = 0; sl + 3 < S.S; sl += 4) { v0 += pp[(size_t)sl * 16384]; v1 += pp[(size_t)(sl + 1) * 16384]; v2 += pp[(size_t)(sl + 2) * 16384]; v3 += pp[(size_t)(sl + 3) * 16384]; }
;                 for (int sl = S.S & ~3; sl < S.S; ++sl) v0 += pp[(size_t)sl * 16384];
;                 a4[b][n] = (v0 + v1) + (v2 + v3); }
;         E.row(a4, u, ai, m, wr, wc, fr, fq); }
.LBB0_1755:
	s_add_i32 s8, s18, s25
	s_ashr_i32 s9, s8, 31
	s_lshr_b32 s9, s9, 27
	s_add_i32 s9, s8, s9
	s_ashr_i32 s18, s9, 5
	s_lshl_b32 s19, s18, 3
	s_sub_i32 s18, 0x83, s19
	s_min_i32 s25, s18, 8
	s_abs_i32 s18, s25
	v_cvt_f32_u32_e32 v1, s18
	s_sub_i32 s27, 0, s18
	s_andn2_b32 s9, s9, 31
	s_sub_i32 s8, s8, s9
	v_rcp_iflag_f32_e32 v1, v1
	s_abs_i32 s9, s8
	s_xor_b32 s26, s8, s25
	s_ashr_i32 s26, s26, 31
	v_mul_f32_e32 v1, 0x4f7ffffe, v1
	v_cvt_u32_f32_e32 v1, v1
	v_readlane_b32 s52, v254, 28
	v_readlane_b32 s64, v254, 40
	v_readlane_b32 s65, v254, 41
	v_readfirstlane_b32 s29, v1
	s_mul_i32 s27, s27, s29
	s_mul_hi_u32 s27, s29, s27
	s_add_i32 s29, s29, s27
	s_mul_hi_u32 s27, s9, s29
	s_mul_i32 s29, s27, s18
	s_sub_i32 s9, s9, s29
	s_add_i32 s30, s27, 1
	s_sub_i32 s29, s9, s18
	s_cmp_ge_u32 s9, s18
	s_cselect_b32 s27, s30, s27
	s_cselect_b32 s9, s29, s9
	s_add_i32 s29, s27, 1
	s_cmp_ge_u32 s9, s18
	s_cselect_b32 s9, s29, s27
	s_xor_b32 s9, s9, s26
	s_sub_i32 s18, s9, s26
	s_mul_i32 s9, s18, s25
	s_sub_i32 s8, s8, s9
	s_and_b32 s24, s24, 1
	s_add_i32 s19, s19, s8
	s_and_b32 s8, s17, 3
	s_lshl_b32 s9, s19, 8
	s_lshl_b32 s19, s24, 7
	v_lshl_or_b32 v1, s8, 4, v87
	s_or_b32 s8, s9, s19
	v_add_u32_e32 v2, s8, v1
	v_ashrrev_i32_e32 v3, 31, v2
	v_lshl_or_b32 v90, s18, 8, v86
	v_lshlrev_b64 v[92:93], 11, v[2:3]
	v_lshl_add_u64 v[92:93], s[64:65], 0, v[92:93]
	v_ashrrev_i32_e32 v91, 31, v90
	v_lshl_add_u64 v[98:99], v[90:91], 1, v[92:93]
	global_load_dwordx4 v[90:93], v[98:99], off
	global_load_dwordx4 v[94:97], v[98:99], off offset:256
	v_pk_add_f32 v[6:7], v[48:49], v[6:7]
	v_pk_add_f32 v[4:5], v[46:47], v[4:5]
	v_pk_add_f32 v[38:39], v[44:45], v[38:39]
	v_pk_add_f32 v[40:41], v[42:43], v[40:41]
	v_pk_add_f32 v[10:11], v[60:61], v[10:11]
	v_pk_add_f32 v[8:9], v[58:59], v[8:9]
	v_pk_add_f32 v[50:51], v[56:57], v[50:51]
	v_pk_add_f32 v[52:53], v[54:55], v[52:53]
	v_pk_add_f32 v[16:17], v[82:83], v[16:17]
	v_pk_add_f32 v[42:43], v[80:81], v[74:75]
	v_pk_add_f32 v[6:7], v[40:41], v[6:7]
	v_pk_add_f32 v[4:5], v[38:39], v[4:5]
	v_pk_add_f32 v[14:15], v[72:73], v[14:15]
	v_pk_add_f32 v[12:13], v[70:71], v[12:13]
	v_pk_add_f32 v[62:63], v[68:69], v[62:63]
	v_pk_add_f32 v[64:65], v[66:67], v[64:65]
	v_pk_add_f32 v[18:19], v[84:85], v[18:19]
	v_pk_add_f32 v[44:45], v[78:79], v[76:77]
	v_pk_add_f32 v[10:11], v[52:53], v[10:11]
	v_pk_add_f32 v[8:9], v[50:51], v[8:9]
	v_pk_add_f32 v[16:17], v[42:43], v[16:17]
	v_pk_add_f32 v[14:15], v[64:65], v[14:15]
	v_pk_add_f32 v[12:13], v[62:63], v[12:13]
	v_pk_add_f32 v[18:19], v[44:45], v[18:19]
	v_readlane_b32 s53, v254, 29
	v_readlane_b32 s54, v254, 30
	v_readlane_b32 s55, v254, 31
	v_readlane_b32 s56, v254, 32
	v_readlane_b32 s57, v254, 33
	v_readlane_b32 s58, v254, 34
	v_readlane_b32 s59, v254, 35
	v_readlane_b32 s60, v254, 36
	v_readlane_b32 s61, v254, 37
	v_readlane_b32 s62, v254, 38
	v_readlane_b32 s63, v254, 39
	v_readlane_b32 s66, v254, 42
	v_readlane_b32 s67, v254, 43
	s_waitcnt vmcnt(1)
	v_lshlrev_b32_e32 v1, 16, v90
	v_and_b32_e32 v37, 0xffff0000, v90
	v_lshlrev_b32_e32 v38, 16, v91
	v_and_b32_e32 v39, 0xffff0000, v91
	v_lshlrev_b32_e32 v40, 16, v92
	v_and_b32_e32 v41, 0xffff0000, v92
	v_lshlrev_b32_e32 v42, 16, v93
	v_add_f32_e32 v1, v4, v1
	v_add_f32_e32 v4, v5, v37
	v_add_f32_e32 v5, v6, v38
	v_and_b32_e32 v43, 0xffff0000, v93
	s_waitcnt vmcnt(0)
	v_lshlrev_b32_e32 v44, 16, v94
	v_and_b32_e32 v45, 0xffff0000, v94
	v_lshlrev_b32_e32 v46, 16, v95
	v_and_b32_e32 v47, 0xffff0000, v95
	v_lshlrev_b32_e32 v48, 16, v96
	v_and_b32_e32 v49, 0xffff0000, v96
	v_lshlrev_b32_e32 v50, 16, v97
	v_add_f32_e32 v6, v7, v39
	v_add_f32_e32 v7, v8, v40
	v_add_f32_e32 v8, v9, v41
	v_add_f32_e32 v9, v10, v42
	v_cvt_pk_bf16_f32 v4, v1, v4
	v_cvt_pk_bf16_f32 v5, v5, v6
	v_add_f32_e32 v10, v11, v43
	v_add_f32_e32 v11, v12, v44
	v_add_f32_e32 v12, v13, v45
	v_add_f32_e32 v13, v14, v46
	v_add_f32_e32 v14, v15, v47
	v_add_f32_e32 v15, v16, v48
	v_add_f32_e32 v16, v17, v49
	v_add_f32_e32 v17, v18, v50
	v_cvt_pk_bf16_f32 v6, v7, v8
	v_cvt_pk_bf16_f32 v7, v9, v10
	global_store_dwordx4 v[98:99], v[4:7], off nt
	v_lshlrev_b32_e32 v1, 16, v4
	v_lshlrev_b32_e32 v9, 16, v5
	v_and_b32_e32 v4, 0xffff0000, v4
	v_and_b32_e32 v5, 0xffff0000, v5
	v_and_b32_e32 v18, 0xffff0000, v6
	v_and_b32_e32 v38, 0xffff0000, v7
	v_lshlrev_b32_e32 v10, 16, v6
	v_lshlrev_b32_e32 v37, 16, v7
	v_cvt_pk_bf16_f32 v6, v11, v12
	v_mul_f32_e32 v4, v4, v4
	v_mul_f32_e32 v5, v5, v5
	v_mul_f32_e32 v11, v18, v18
	v_mul_f32_e32 v12, v38, v38
	v_fmac_f32_e32 v4, v1, v1
	v_fmac_f32_e32 v5, v9, v9
	v_fmac_f32_e32 v11, v10, v10
	v_fmac_f32_e32 v12, v37, v37
	v_add_f32_e32 v1, v4, v5
	v_add_f32_e32 v4, v11, v12
	v_add_f32_e32 v1, v1, v4
	v_and_b32_e32 v4, 0xffff0000, v97
	v_add_f32_e32 v4, v19, v4
	v_and_b32_e32 v5, 0xffff0000, v6
	v_cvt_pk_bf16_f32 v7, v13, v14
	v_cvt_pk_bf16_f32 v8, v15, v16
	v_cvt_pk_bf16_f32 v9, v17, v4
	v_lshlrev_b32_e32 v4, 16, v6
	v_and_b32_e32 v11, 0xffff0000, v7
	v_mul_f32_e32 v5, v5, v5
	v_lshlrev_b32_e32 v10, 16, v7
	v_fmac_f32_e32 v5, v4, v4
	v_mul_f32_e32 v4, v11, v11
	v_and_b32_e32 v13, 0xffff0000, v8
	v_and_b32_e32 v15, 0xffff0000, v9
	v_fmac_f32_e32 v4, v10, v10
	v_lshlrev_b32_e32 v12, 16, v8
	v_lshlrev_b32_e32 v14, 16, v9
	v_add_f32_e32 v4, v5, v4
	v_mul_f32_e32 v5, v13, v13
	v_mul_f32_e32 v10, v15, v15
	v_fmac_f32_e32 v5, v12, v12
	v_fmac_f32_e32 v10, v14, v14
	v_add_f32_e32 v5, v5, v10
	v_add_f32_e32 v4, v4, v5
	v_and_b32_e32 v5, 64, v88
	v_add_f32_e32 v1, v1, v4
	v_xor_b32_e32 v4, 16, v88
	v_add_u32_e32 v5, 64, v5
	v_cmp_lt_i32_e32 vcc, v4, v5
	global_store_dwordx4 v[98:99], v[6:9], off offset:256 nt
	s_nop 0
	v_cndmask_b32_e32 v4, v88, v4, vcc
	v_lshlrev_b32_e32 v4, 2, v4
	ds_bpermute_b32 v4, v4, v1
	s_waitcnt lgkmcnt(0)
	v_add_f32_e32 v1, v1, v4
	v_xor_b32_e32 v4, 32, v88
	v_cmp_lt_i32_e32 vcc, v4, v5
	s_nop 1
	v_cndmask_b32_e32 v4, v88, v4, vcc
	v_lshlrev_b32_e32 v4, 2, v4
	ds_bpermute_b32 v4, v4, v1
	s_and_saveexec_b64 s[8:9], s[0:1]
	s_xor_b64 s[8:9], exec, s[8:9]
	s_cbranch_execz .LBB0_1722
	v_readlane_b32 s52, v254, 28
	s_lshl_b32 s18, s18, 2
	v_lshlrev_b64 v[2:3], 6, v[2:3]
	v_readlane_b32 s66, v254, 42
	v_readlane_b32 s67, v254, 43
	s_ashr_i32 s19, s18, 31
	v_mov_b32_e32 v37, v0
	v_lshl_add_u64 v[2:3], s[66:67], 0, v[2:3]
	v_lshl_add_u64 v[2:3], s[18:19], 2, v[2:3]
	s_waitcnt lgkmcnt(0)
	v_add_f32_e32 v1, v1, v4
	v_lshl_add_u64 v[2:3], v[2:3], 0, v[36:37]
	v_readlane_b32 s53, v254, 29
	v_readlane_b32 s54, v254, 30
	v_readlane_b32 s55, v254, 31
	v_readlane_b32 s56, v254, 32
	v_readlane_b32 s57, v254, 33
	v_readlane_b32 s58, v254, 34
	v_readlane_b32 s59, v254, 35
	v_readlane_b32 s60, v254, 36
	v_readlane_b32 s61, v254, 37
	v_readlane_b32 s62, v254, 38
	v_readlane_b32 s63, v254, 39
	v_readlane_b32 s64, v254, 40
	v_readlane_b32 s65, v254, 41
	global_store_dword v[2:3], v1, off
	s_branch .LBB0_1722

; DI unsigned pk2(float lo, float hi) { unsigned r; asm volatile("v_cvt_pk_bf16_f32 %0, %1, %2" : "=v"(r) : "v"(lo), "v"(hi)); return r; }
; DI size_t kf_index(int seqh, int nkt, int key, int d) { return ((((size_t)seqh * nkt + (key >> 5)) * 8 + (d >> 4)) * 64 + ((key & 31) + 32 * ((d >> 3) & 1))) * 8 + (d & 7); }
;     DI void operator()(const f32x4 (&acc)[2][2][4][2], const Unit& u, int wr, int wc, int fr, int fq, const Pre& pre) const {
;     ...
;             for (int m = 0; m < 4; ++m) { const int row = row0 + ai * 128 + m * 16; const float r = rs[ai][m];
;                 const bool smp = row >= NTP; const int s = row - NTP; const int b = smp ? (s >> 6) : row / TP, key = smp ? 1024 + (s & 63) : row - b * TP, nkt = smp ? 34 : 129;
; #pragma unroll
;                 for (int bj = 0; bj < 2; ++bj) { const int cs = cb + bj * 128; const f32x4 v0 = acc[ai][bj][m][0] * r, v1 = acc[ai][bj][m][1] * r;
;                     u32x4v o; o.x = pk2(v0[0], v0[1]); o.y = pk2(v0[2], v0[3]); o.z = pk2(v1[0], v1[1]); o.w = pk2(v1[2], v1[3]);
;                     if (third == 0) { *(u32x4v*)(Q + (size_t)row * 1024 + cs) = o; }
;                     else if (row < NT) { const int h = cs >> 7, d = cs & 127;
;                         float* ok = out + (smp ? O_KS + (size_t)s * 1024 : O_KP + (size_t)row * 1024) + cs; *(f32x4*)ok = v0; *(f32x4*)(ok + 4) = v1;
;                         *(u32x4v*)((smp ? KS : KP) + kf_index(b * 8 + h, nkt, key, d)) = o; } } }
.LBB0_1852:
	s_or_b64 exec, exec, s[12:13]
	s_lshl_b32 s0, s10, 8
	s_and_b32 s45, s0, 0x300
	s_and_b32 s5, s10, -4
	v_or_b32_e32 v217, s45, v161
	s_mov_b64 s[0:1], -1
	s_cmp_eq_u32 s5, 8
	v_cmp_lt_i32_e64 s[12:13], s28, v180
	v_cmp_gt_i32_e32 vcc, s6, v180
	s_cbranch_scc1 .LBB0_1982
	s_and_saveexec_b64 s[0:1], vcc
	s_xor_b64 s[0:1], exec, s[0:1]
	v_mul_hi_i32 v128, v180, s18
	v_lshrrev_b32_e32 v129, 31, v128
	v_ashrrev_i32_e32 v128, 11, v128
	v_add_u32_e32 v128, v128, v129
	s_or_saveexec_b64 s[0:1], s[0:1]
	v_add_u32_e32 v148, 0xffff7f80, v180
	v_mov_b64_e32 v[198:199], 0x81
	s_xor_b64 exec, exec, s[0:1]
	v_lshrrev_b32_e32 v128, 6, v148
	v_mov_b64_e32 v[198:199], 34
	s_or_b64 exec, exec, s[0:1]
	v_mad_u64_u32 v[130:131], s[0:1], v128, s19, v[180:181]
	s_cmp_gt_u32 s10, 3
	v_cndmask_b32_e64 v129, v130, v208, s[12:13]
	v_lshlrev_b64 v[130:131], 10, v[180:181]
	s_cselect_b64 s[10:11], -1, 0
	v_lshl_add_u64 v[202:203], v[130:131], 0, s[36:37]
	v_lshlrev_b64 v[130:131], 10, v[148:149]
	v_ashrrev_i32_e32 v200, 5, v129
	v_cmp_gt_i32_e64 s[14:15], s4, v180
	v_lshl_add_u64 v[204:205], v[130:131], 0, s[38:39]
	v_lshlrev_b32_e32 v189, 3, v128
	v_ashrrev_i32_e32 v201, 31, v200
	v_and_or_b32 v191, v129, 31, v163
	v_pk_mul_f32 v[134:135], v[126:127], v[184:185] op_sel:[0,1]
	v_pk_mul_f32 v[132:133], v[124:125], v[184:185] op_sel:[0,1]
	v_pk_mul_f32 v[138:139], v[122:123], v[184:185] op_sel:[0,1]
	v_pk_mul_f32 v[136:137], v[120:121], v[184:185] op_sel:[0,1]
	s_mov_b64 s[0:1], -1
	s_and_b64 vcc, exec, s[10:11]
	v_cvt_pk_bf16_f32 v128, v132, v133
	v_cvt_pk_bf16_f32 v129, v134, v135
	v_cvt_pk_bf16_f32 v130, v136, v137
	v_cvt_pk_bf16_f32 v131, v138, v139
	s_cbranch_vccz .LBB0_1861
	s_and_saveexec_b64 s[0:1], s[14:15]
	s_cbranch_execz .LBB0_1860
	v_readlane_b32 s76, v254, 12
	v_cndmask_b32_e64 v197, v203, v205, s[12:13]
	v_cndmask_b32_e64 v196, v202, v204, s[12:13]
	v_readlane_b32 s77, v254, 13
	v_readlane_b32 s78, v254, 14
	v_readlane_b32 s79, v254, 15
	v_readlane_b32 s80, v254, 16
	v_readlane_b32 s81, v254, 17
	v_readlane_b32 s82, v254, 18
	v_readlane_b32 s83, v254, 19
	v_readlane_b32 s84, v254, 20
	v_readlane_b32 s85, v254, 21
	v_lshlrev_b32_e32 v148, 2, v217
	v_readlane_b32 s76, v254, 0
	v_lshl_add_u64 v[196:197], v[196:197], 2, s[84:85]
	v_lshl_add_u64 v[196:197], v[196:197], 0, v[148:149]
	v_readlane_b32 s77, v254, 1
	v_readlane_b32 s79, v254, 3
	global_store_dwordx4 v[196:197], v[132:135], off nt
	global_store_dwordx4 v[196:197], v[136:139], off offset:16 nt
	v_readlane_b32 s78, v254, 2
	v_mov_b32_e32 v132, s77
	v_mov_b32_e32 v133, s79
	s_lshr_b32 s5, s45, 7
	v_cndmask_b32_e64 v133, v132, v133, s[12:13]
	v_mov_b32_e32 v132, s76
	v_mov_b32_e32 v134, s78
	v_cndmask_b32_e64 v132, v132, v134, s[12:13]
	v_or_b32_e32 v134, s5, v189
	v_mad_i64_i32 v[134:135], s[96:97], v198, v134, v[200:201]
	v_readlane_b32 s88, v254, 24
	v_readlane_b32 s89, v254, 25
	v_lshlrev_b64 v[134:135], 13, v[134:135]
	v_readlane_b32 s88, v255, 40
	v_lshlrev_b32_e32 v148, 4, v191
	v_lshl_add_u64 v[132:133], v[132:133], 0, v[134:135]
	v_readlane_b32 s89, v255, 41
	s_mov_b32 s84, s7
	v_lshl_add_u64 v[132:133], v[132:133], 0, v[148:149]
	v_readlane_b32 s86, v254, 22
	v_readlane_b32 s87, v254, 23
	v_readlane_b32 s90, v254, 26
	v_readlane_b32 s91, v254, 27
	v_readlane_b32 s80, v254, 4
	v_readlane_b32 s81, v254, 5
	v_readlane_b32 s82, v254, 6
	v_readlane_b32 s83, v254, 7
	global_store_dwordx4 v[132:133], v[128:131], off nt

; DI unsigned pk2(float lo, float hi) { unsigned r; asm volatile("v_cvt_pk_bf16_f32 %0, %1, %2" : "=v"(r) : "v"(lo), "v"(hi)); return r; }
; DI size_t kf_index(int seqh, int nkt, int key, int d) { return ((((size_t)seqh * nkt + (key >> 5)) * 8 + (d >> 4)) * 64 + ((key & 31) + 32 * ((d >> 3) & 1))) * 8 + (d & 7); }
;     DI void operator()(const f32x4 (&acc)[2][2][4][2], const Unit& u, int wr, int wc, int fr, int fq, const Pre& pre) const {
;     ...
;             for (int m = 0; m < 4; ++m) { const int row = row0 + ai * 128 + m * 16; const float r = rs[ai][m];
;                 const bool smp = row >= NTP; const int s = row - NTP; const int b = smp ? (s >> 6) : row / TP, key = smp ? 1024 + (s & 63) : row - b * TP, nkt = smp ? 34 : 129;
; #pragma unroll
;                 for (int bj = 0; bj < 2; ++bj) { const int cs = cb + bj * 128; const f32x4 v0 = acc[ai][bj][m][0] * r, v1 = acc[ai][bj][m][1] * r;
;                     u32x4v o; o.x = pk2(v0[0], v0[1]); o.y = pk2(v0[2], v0[3]); o.z = pk2(v1[0], v1[1]); o.w = pk2(v1[2], v1[3]);
;                     if (third == 0) { *(u32x4v*)(Q + (size_t)row * 1024 + cs) = o; }
;                     else if (row < NT) { const int h = cs >> 7, d = cs & 127;
;                         float* ok = out + (smp ? O_KS + (size_t)s * 1024 : O_KP + (size_t)row * 1024) + cs; *(f32x4*)ok = v0; *(f32x4*)(ok + 4) = v1;
;                         *(u32x4v*)((smp ? KS : KP) + kf_index(b * 8 + h, nkt, key, d)) = o; } } }
.LBB0_1861:
	s_mov_b64 s[68:69], s[88:89]
	s_mov_b32 s30, s84
	v_readlane_b32 s76, v255, 8
	v_lshlrev_b64 v[132:133], 11, v[180:181]
	v_readlane_b32 s90, v255, 22
	v_readlane_b32 s91, v255, 23
	s_andn2_b64 vcc, exec, s[0:1]
	v_lshlrev_b32_e32 v196, 1, v217
	v_lshl_add_u64 v[206:207], s[90:91], 0, v[132:133]
	v_readlane_b32 s77, v255, 9
	v_readlane_b32 s78, v255, 10
	v_readlane_b32 s79, v255, 11
	v_readlane_b32 s80, v255, 12
	v_readlane_b32 s81, v255, 13
	v_readlane_b32 s82, v255, 14
	v_readlane_b32 s83, v255, 15
	v_readlane_b32 s84, v255, 16
	v_readlane_b32 s85, v255, 17
	v_readlane_b32 s86, v255, 18
	v_readlane_b32 s87, v255, 19
	v_readlane_b32 s88, v255, 20
	v_readlane_b32 s89, v255, 21
	s_cbranch_vccnz .LBB0_1863
	v_mov_b32_e32 v197, v149
	v_lshl_add_u64 v[132:133], v[206:207], 0, v[196:197]
	global_store_dwordx4 v[132:133], v[128:131], off nt
.LBB0_1863:
	s_nop 1
	v_mov_b32_e32 v128, v185
	v_mov_b32_e32 v129, v185
	v_mov_b32_e32 v130, v185
	v_mov_b32_e32 v131, v185
	v_cndmask_b32_e64 v148, 0, 1, s[10:11]
	v_or_b32_e32 v218, 0x80, v217
	v_pk_mul_f32 v[134:135], v[118:119], v[130:131]
	v_pk_mul_f32 v[132:133], v[116:117], v[128:129]
	v_pk_mul_f32 v[138:139], v[114:115], v[130:131]
	v_pk_mul_f32 v[136:137], v[112:113], v[128:129]
	v_cmp_ne_u32_e64 s[0:1], 1, v148
	s_andn2_b64 vcc, exec, s[10:11]
	s_mov_b64 s[10:11], -1
	v_cvt_pk_bf16_f32 v128, v132, v133
	v_cvt_pk_bf16_f32 v129, v134, v135
	v_cvt_pk_bf16_f32 v130, v136, v137
	v_cvt_pk_bf16_f32 v131, v138, v139
	s_cbranch_vccnz .LBB0_1867
	s_and_saveexec_b64 s[10:11], s[14:15]
	s_cbranch_execz .LBB0_1866
	v_readlane_b32 s76, v254, 12
	v_cndmask_b32_e64 v203, v203, v205, s[12:13]
	v_cndmask_b32_e64 v202, v202, v204, s[12:13]
	v_readlane_b32 s77, v254, 13
	v_readlane_b32 s78, v254, 14
	v_readlane_b32 s79, v254, 15
	v_readlane_b32 s80, v254, 16
	v_readlane_b32 s81, v254, 17
	v_readlane_b32 s82, v254, 18
	v_readlane_b32 s83, v254, 19
	v_readlane_b32 s84, v254, 20
	v_readlane_b32 s85, v254, 21
	v_lshlrev_b32_e32 v148, 2, v217
	v_readlane_b32 s76, v254, 0
	v_lshl_add_u64 v[202:203], v[202:203], 2, s[84:85]
	v_lshl_add_u64 v[202:203], v[202:203], 0, v[148:149]
	v_readlane_b32 s77, v254, 1
	v_readlane_b32 s79, v254, 3
	global_store_dwordx4 v[202:203], v[132:135], off offset:512 nt
	global_store_dwordx4 v[202:203], v[136:139], off offset:528 nt
	v_readlane_b32 s78, v254, 2
	v_mov_b32_e32 v132, s77
	v_mov_b32_e32 v133, s79
	v_lshrrev_b32_e32 v195, 7, v218
	v_cndmask_b32_e64 v133, v132, v133, s[12:13]
	v_mov_b32_e32 v132, s76
	v_mov_b32_e32 v134, s78
	v_cndmask_b32_e64 v132, v132, v134, s[12:13]
	v_or_b32_e32 v134, v189, v195
	v_mad_i64_i32 v[134:135], s[12:13], v198, v134, v[200:201]
	v_lshlrev_b64 v[134:135], 13, v[134:135]
	v_readlane_b32 s68, v255, 40
	v_lshlrev_b32_e32 v148, 4, v191
	v_lshl_add_u64 v[132:133], v[132:133], 0, v[134:135]
	s_mov_b32 s30, s7
	v_readlane_b32 s69, v255, 41
	v_lshl_add_u64 v[132:133], v[132:133], 0, v[148:149]
	v_readlane_b32 s86, v254, 22
	v_readlane_b32 s87, v254, 23
	v_readlane_b32 s88, v254, 24
	v_readlane_b32 s89, v254, 25
	v_readlane_b32 s90, v254, 26
	v_readlane_b32 s91, v254, 27
	v_readlane_b32 s80, v254, 4
	v_readlane_b32 s81, v254, 5
	v_readlane_b32 s82, v254, 6
	v_readlane_b32 s83, v254, 7
	global_store_dwordx4 v[132:133], v[128:131], off nt

; DI unsigned pk2(float lo, float hi) { unsigned r; asm volatile("v_cvt_pk_bf16_f32 %0, %1, %2" : "=v"(r) : "v"(lo), "v"(hi)); return r; }
; DI size_t kf_index(int seqh, int nkt, int key, int d) { return ((((size_t)seqh * nkt + (key >> 5)) * 8 + (d >> 4)) * 64 + ((key & 31) + 32 * ((d >> 3) & 1))) * 8 + (d & 7); }
;     DI void operator()(const f32x4 (&acc)[2][2][4][2], const Unit& u, int wr, int wc, int fr, int fq, const Pre& pre) const {
;     ...
;             for (int m = 0; m < 4; ++m) { const int row = row0 + ai * 128 + m * 16; const float r = rs[ai][m];
;                 const bool smp = row >= NTP; const int s = row - NTP; const int b = smp ? (s >> 6) : row / TP, key = smp ? 1024 + (s & 63) : row - b * TP, nkt = smp ? 34 : 129;
; #pragma unroll
;                 for (int bj = 0; bj < 2; ++bj) { const int cs = cb + bj * 128; const f32x4 v0 = acc[ai][bj][m][0] * r, v1 = acc[ai][bj][m][1] * r;
;                     u32x4v o; o.x = pk2(v0[0], v0[1]); o.y = pk2(v0[2], v0[3]); o.z = pk2(v1[0], v1[1]); o.w = pk2(v1[2], v1[3]);
;                     if (third == 0) { *(u32x4v*)(Q + (size_t)row * 1024 + cs) = o; }
;                     else if (row < NT) { const int h = cs >> 7, d = cs & 127;
;                         float* ok = out + (smp ? O_KS + (size_t)s * 1024 : O_KP + (size_t)row * 1024) + cs; *(f32x4*)ok = v0; *(f32x4*)(ok + 4) = v1;
;                         *(u32x4v*)((smp ? KS : KP) + kf_index(b * 8 + h, nkt, key, d)) = o; } } }
.LBB0_1867:
	s_andn2_b64 vcc, exec, s[10:11]
	s_cbranch_vccnz .LBB0_1869
	v_mov_b32_e32 v197, v149
	v_lshl_add_u64 v[132:133], v[206:207], 0, v[196:197]
	global_store_dwordx4 v[132:133], v[128:131], off offset:256 nt
.LBB0_1869:
	v_cmp_lt_i32_e64 s[12:13], s28, v194
	v_cmp_gt_i32_e32 vcc, s6, v194
	s_and_saveexec_b64 s[10:11], vcc
	s_xor_b64 s[10:11], exec, s[10:11]
	v_mul_hi_i32 v128, v194, s18
	v_lshrrev_b32_e32 v129, 31, v128
	v_ashrrev_i32_e32 v128, 11, v128
	v_add_u32_e32 v128, v128, v129
	s_or_saveexec_b64 s[10:11], s[10:11]
	v_add_u32_e32 v148, 0xffff7f90, v180
	v_mov_b64_e32 v[198:199], 0x81
	s_xor_b64 exec, exec, s[10:11]
	v_lshrrev_b32_e32 v128, 6, v148
	v_mov_b64_e32 v[198:199], 34
	s_or_b64 exec, exec, s[10:11]
	v_mad_u64_u32 v[130:131], s[10:11], v128, s19, v[194:195]
	v_ashrrev_i32_e32 v195, 31, v194
	v_cndmask_b32_e64 v129, v130, v209, s[12:13]
	v_lshlrev_b64 v[130:131], 10, v[194:195]
	v_lshl_add_u64 v[202:203], v[130:131], 0, s[36:37]
	v_lshlrev_b64 v[130:131], 10, v[148:149]
	v_ashrrev_i32_e32 v200, 5, v129
	v_cmp_gt_i32_e64 s[14:15], s4, v194
	v_lshl_add_u64 v[204:205], v[130:131], 0, s[38:39]
	v_lshlrev_b32_e32 v189, 3, v128
	v_ashrrev_i32_e32 v201, 31, v200
	v_and_or_b32 v191, v129, 31, v163
	v_pk_mul_f32 v[134:135], v[110:111], v[192:193] op_sel_hi:[1,0]
	v_pk_mul_f32 v[132:133], v[108:109], v[192:193] op_sel_hi:[1,0]
	v_pk_mul_f32 v[138:139], v[106:107], v[192:193] op_sel_hi:[1,0]
	v_pk_mul_f32 v[136:137], v[104:105], v[192:193] op_sel_hi:[1,0]
	s_and_b64 vcc, exec, s[0:1]
	s_mov_b64 s[10:11], -1
	v_cvt_pk_bf16_f32 v128, v132, v133
	v_cvt_pk_bf16_f32 v129, v134, v135
	v_cvt_pk_bf16_f32 v130, v136, v137
	v_cvt_pk_bf16_f32 v131, v138, v139
	s_cbranch_vccnz .LBB0_1877
	s_and_saveexec_b64 s[10:11], s[14:15]
	s_cbranch_execz .LBB0_1876
	v_readlane_b32 s76, v254, 12
	v_cndmask_b32_e64 v207, v203, v205, s[12:13]
	v_cndmask_b32_e64 v206, v202, v204, s[12:13]
	v_readlane_b32 s77, v254, 13
	v_readlane_b32 s78, v254, 14
	v_readlane_b32 s79, v254, 15
	v_readlane_b32 s80, v254, 16
	v_readlane_b32 s81, v254, 17
	v_readlane_b32 s82, v254, 18
	v_readlane_b32 s83, v254, 19
	v_readlane_b32 s84, v254, 20
	v_readlane_b32 s85, v254, 21
	v_lshlrev_b32_e32 v148, 2, v217
	v_readlane_b32 s76, v254, 0
	v_lshl_add_u64 v[206:207], v[206:207], 2, s[84:85]
	v_lshl_add_u64 v[206:207], v[206:207], 0, v[148:149]
	v_readlane_b32 s77, v254, 1
	v_readlane_b32 s79, v254, 3
	global_store_dwordx4 v[206:207], v[132:135], off nt
	global_store_dwordx4 v[206:207], v[136:139], off offset:16 nt
	v_readlane_b32 s78, v254, 2
	v_mov_b32_e32 v132, s77
	v_mov_b32_e32 v133, s79
	s_lshr_b32 s5, s45, 7
	v_cndmask_b32_e64 v133, v132, v133, s[12:13]
	v_mov_b32_e32 v132, s76
	v_mov_b32_e32 v134, s78
	v_cndmask_b32_e64 v132, v132, v134, s[12:13]
	v_or_b32_e32 v134, s5, v189
	v_mad_i64_i32 v[134:135], s[96:97], v198, v134, v[200:201]
	v_lshlrev_b64 v[134:135], 13, v[134:135]
	v_readlane_b32 s68, v255, 40
	v_lshlrev_b32_e32 v148, 4, v191
	v_lshl_add_u64 v[132:133], v[132:133], 0, v[134:135]
	s_mov_b32 s30, s7
	v_readlane_b32 s69, v255, 41
	v_lshl_add_u64 v[132:133], v[132:133], 0, v[148:149]
	v_readlane_b32 s86, v254, 22
	v_readlane_b32 s87, v254, 23
	v_readlane_b32 s88, v254, 24
	v_readlane_b32 s89, v254, 25
	v_readlane_b32 s90, v254, 26
	v_readlane_b32 s91, v254, 27
	v_readlane_b32 s80, v254, 4
	v_readlane_b32 s81, v254, 5
	v_readlane_b32 s82, v254, 6
	v_readlane_b32 s83, v254, 7
	global_store_dwordx4 v[132:133], v[128:131], off nt

; DI unsigned pk2(float lo, float hi) { unsigned r; asm volatile("v_cvt_pk_bf16_f32 %0, %1, %2" : "=v"(r) : "v"(lo), "v"(hi)); return r; }
; DI size_t kf_index(int seqh, int nkt, int key, int d) { return ((((size_t)seqh * nkt + (key >> 5)) * 8 + (d >> 4)) * 64 + ((key & 31) + 32 * ((d >> 3) & 1))) * 8 + (d & 7); }
;     DI void operator()(const f32x4 (&acc)[2][2][4][2], const Unit& u, int wr, int wc, int fr, int fq, const Pre& pre) const {
;     ...
;             for (int m = 0; m < 4; ++m) { const int row = row0 + ai * 128 + m * 16; const float r = rs[ai][m];
;                 const bool smp = row >= NTP; const int s = row - NTP; const int b = smp ? (s >> 6) : row / TP, key = smp ? 1024 + (s & 63) : row - b * TP, nkt = smp ? 34 : 129;
; #pragma unroll
;                 for (int bj = 0; bj < 2; ++bj) { const int cs = cb + bj * 128; const f32x4 v0 = acc[ai][bj][m][0] * r, v1 = acc[ai][bj][m][1] * r;
;                     u32x4v o; o.x = pk2(v0[0], v0[1]); o.y = pk2(v0[2], v0[3]); o.z = pk2(v1[0], v1[1]); o.w = pk2(v1[2], v1[3]);
;                     if (third == 0) { *(u32x4v*)(Q + (size_t)row * 1024 + cs) = o; }
;                     else if (row < NT) { const int h = cs >> 7, d = cs & 127;
;                         float* ok = out + (smp ? O_KS + (size_t)s * 1024 : O_KP + (size_t)row * 1024) + cs; *(f32x4*)ok = v0; *(f32x4*)(ok + 4) = v1;
;                         *(u32x4v*)((smp ? KS : KP) + kf_index(b * 8 + h, nkt, key, d)) = o; } } }
.LBB0_1877:
	v_readlane_b32 s76, v255, 8
	v_lshlrev_b64 v[132:133], 11, v[194:195]
	v_readlane_b32 s90, v255, 22
	v_readlane_b32 s91, v255, 23
	s_andn2_b64 vcc, exec, s[10:11]
	v_readlane_b32 s77, v255, 9
	v_lshl_add_u64 v[206:207], s[90:91], 0, v[132:133]
	v_readlane_b32 s78, v255, 10
	v_readlane_b32 s79, v255, 11
	v_readlane_b32 s80, v255, 12
	v_readlane_b32 s81, v255, 13
	v_readlane_b32 s82, v255, 14
	v_readlane_b32 s83, v255, 15
	v_readlane_b32 s84, v255, 16
	v_readlane_b32 s85, v255, 17
	v_readlane_b32 s86, v255, 18
	v_readlane_b32 s87, v255, 19
	v_readlane_b32 s88, v255, 20
	v_readlane_b32 s89, v255, 21
	s_cbranch_vccnz .LBB0_1879
	v_mov_b32_e32 v197, v149
	v_lshl_add_u64 v[132:133], v[206:207], 0, v[196:197]
	global_store_dwordx4 v[132:133], v[128:131], off nt
.LBB0_1879:
	s_nop 1
	v_mov_b32_e32 v128, v192
	v_mov_b32_e32 v129, v192
	v_mov_b32_e32 v130, v192
	v_mov_b32_e32 v131, v192
	v_pk_mul_f32 v[134:135], v[102:103], v[130:131]
	v_pk_mul_f32 v[132:133], v[100:101], v[128:129]
	v_pk_mul_f32 v[138:139], v[98:99], v[130:131]
	v_pk_mul_f32 v[136:137], v[96:97], v[128:129]
	s_and_b64 vcc, exec, s[0:1]
	s_mov_b64 s[10:11], -1
	v_cvt_pk_bf16_f32 v128, v132, v133
	v_cvt_pk_bf16_f32 v129, v134, v135
	v_cvt_pk_bf16_f32 v130, v136, v137
	v_cvt_pk_bf16_f32 v131, v138, v139
	s_cbranch_vccnz .LBB0_1883
	s_and_saveexec_b64 s[10:11], s[14:15]
	s_cbranch_execz .LBB0_1882
	v_readlane_b32 s76, v254, 12
	v_cndmask_b32_e64 v203, v203, v205, s[12:13]
	v_cndmask_b32_e64 v202, v202, v204, s[12:13]
	v_readlane_b32 s77, v254, 13
	v_readlane_b32 s78, v254, 14
	v_readlane_b32 s79, v254, 15
	v_readlane_b32 s80, v254, 16
	v_readlane_b32 s81, v254, 17
	v_readlane_b32 s82, v254, 18
	v_readlane_b32 s83, v254, 19
	v_readlane_b32 s84, v254, 20
	v_readlane_b32 s85, v254, 21
	v_lshlrev_b32_e32 v148, 2, v217
	v_readlane_b32 s76, v254, 0
	v_lshl_add_u64 v[202:203], v[202:203], 2, s[84:85]
	v_lshl_add_u64 v[202:203], v[202:203], 0, v[148:149]
	v_readlane_b32 s77, v254, 1
	v_readlane_b32 s79, v254, 3
	global_store_dwordx4 v[202:203], v[132:135], off offset:512 nt
	global_store_dwordx4 v[202:203], v[136:139], off offset:528 nt
	v_readlane_b32 s78, v254, 2
	v_mov_b32_e32 v132, s77
	v_mov_b32_e32 v133, s79
	v_lshrrev_b32_e32 v195, 7, v218
	v_cndmask_b32_e64 v133, v132, v133, s[12:13]
	v_mov_b32_e32 v132, s76
	v_mov_b32_e32 v134, s78
	v_cndmask_b32_e64 v132, v132, v134, s[12:13]
	v_or_b32_e32 v134, v189, v195
	v_mad_i64_i32 v[134:135], s[12:13], v198, v134, v[200:201]
	v_lshlrev_b64 v[134:135], 13, v[134:135]
	v_readlane_b32 s68, v255, 40
	v_lshlrev_b32_e32 v148, 4, v191
	v_lshl_add_u64 v[132:133], v[132:133], 0, v[134:135]
	s_mov_b32 s30, s7
	v_readlane_b32 s69, v255, 41
	v_lshl_add_u64 v[132:133], v[132:133], 0, v[148:149]
	v_readlane_b32 s86, v254, 22
	v_readlane_b32 s87, v254, 23
	v_readlane_b32 s88, v254, 24
	v_readlane_b32 s89, v254, 25
	v_readlane_b32 s90, v254, 26
	v_readlane_b32 s91, v254, 27
	v_readlane_b32 s80, v254, 4
	v_readlane_b32 s81, v254, 5
	v_readlane_b32 s82, v254, 6
	v_readlane_b32 s83, v254, 7
	global_store_dwordx4 v[132:133], v[128:131], off nt

; DI unsigned pk2(float lo, float hi) { unsigned r; asm volatile("v_cvt_pk_bf16_f32 %0, %1, %2" : "=v"(r) : "v"(lo), "v"(hi)); return r; }
; DI size_t kf_index(int seqh, int nkt, int key, int d) { return ((((size_t)seqh * nkt + (key >> 5)) * 8 + (d >> 4)) * 64 + ((key & 31) + 32 * ((d >> 3) & 1))) * 8 + (d & 7); }
;     DI void operator()(const f32x4 (&acc)[2][2][4][2], const Unit& u, int wr, int wc, int fr, int fq, const Pre& pre) const {
;     ...
;             for (int m = 0; m < 4; ++m) { const int row = row0 + ai * 128 + m * 16; const float r = rs[ai][m];
;                 const bool smp = row >= NTP; const int s = row - NTP; const int b = smp ? (s >> 6) : row / TP, key = smp ? 1024 + (s & 63) : row - b * TP, nkt = smp ? 34 : 129;
; #pragma unroll
;                 for (int bj = 0; bj < 2; ++bj) { const int cs = cb + bj * 128; const f32x4 v0 = acc[ai][bj][m][0] * r, v1 = acc[ai][bj][m][1] * r;
;                     u32x4v o; o.x = pk2(v0[0], v0[1]); o.y = pk2(v0[2], v0[3]); o.z = pk2(v1[0], v1[1]); o.w = pk2(v1[2], v1[3]);
;                     if (third == 0) { *(u32x4v*)(Q + (size_t)row * 1024 + cs) = o; }
;                     else if (row < NT) { const int h = cs >> 7, d = cs & 127;
;                         float* ok = out + (smp ? O_KS + (size_t)s * 1024 : O_KP + (size_t)row * 1024) + cs; *(f32x4*)ok = v0; *(f32x4*)(ok + 4) = v1;
;                         *(u32x4v*)((smp ? KS : KP) + kf_index(b * 8 + h, nkt, key, d)) = o; } } }
.LBB0_1885:
	v_cmp_lt_i32_e64 s[12:13], s28, v190
	v_cmp_gt_i32_e32 vcc, s6, v190
	s_and_saveexec_b64 s[10:11], vcc
	s_xor_b64 s[10:11], exec, s[10:11]
	v_mul_hi_i32 v128, v190, s18
	v_lshrrev_b32_e32 v129, 31, v128
	v_ashrrev_i32_e32 v128, 11, v128
	v_add_u32_e32 v128, v128, v129
	s_or_saveexec_b64 s[10:11], s[10:11]
	v_add_u32_e32 v148, 0xffff7fa0, v180
	v_mov_b64_e32 v[198:199], 0x81
	s_xor_b64 exec, exec, s[10:11]
	v_lshrrev_b32_e32 v128, 6, v148
	v_mov_b64_e32 v[198:199], 34
	s_or_b64 exec, exec, s[10:11]
	v_mad_u64_u32 v[130:131], s[10:11], v128, s19, v[190:191]
	v_ashrrev_i32_e32 v191, 31, v190
	v_cndmask_b32_e64 v129, v130, v210, s[12:13]
	v_lshlrev_b64 v[130:131], 10, v[190:191]
	v_lshl_add_u64 v[202:203], v[130:131], 0, s[36:37]
	v_lshlrev_b64 v[130:131], 10, v[148:149]
	v_ashrrev_i32_e32 v200, 5, v129
	v_cmp_gt_i32_e64 s[14:15], s4, v190
	v_lshl_add_u64 v[204:205], v[130:131], 0, s[38:39]
	v_lshlrev_b32_e32 v189, 3, v128
	v_ashrrev_i32_e32 v201, 31, v200
	v_and_or_b32 v195, v129, 31, v163
	v_pk_mul_f32 v[134:135], v[94:95], v[192:193] op_sel:[0,1]
	v_pk_mul_f32 v[132:133], v[92:93], v[192:193] op_sel:[0,1]
	v_pk_mul_f32 v[138:139], v[90:91], v[192:193] op_sel:[0,1]
	v_pk_mul_f32 v[136:137], v[88:89], v[192:193] op_sel:[0,1]
	s_and_b64 vcc, exec, s[0:1]
	s_mov_b64 s[10:11], -1
	v_cvt_pk_bf16_f32 v128, v132, v133
	v_cvt_pk_bf16_f32 v129, v134, v135
	v_cvt_pk_bf16_f32 v130, v136, v137
	v_cvt_pk_bf16_f32 v131, v138, v139
	s_cbranch_vccnz .LBB0_1893
	s_and_saveexec_b64 s[10:11], s[14:15]
	s_cbranch_execz .LBB0_1892
	v_readlane_b32 s76, v254, 12
	v_cndmask_b32_e64 v207, v203, v205, s[12:13]
	v_cndmask_b32_e64 v206, v202, v204, s[12:13]
	v_readlane_b32 s77, v254, 13
	v_readlane_b32 s78, v254, 14
	v_readlane_b32 s79, v254, 15
	v_readlane_b32 s80, v254, 16
	v_readlane_b32 s81, v254, 17
	v_readlane_b32 s82, v254, 18
	v_readlane_b32 s83, v254, 19
	v_readlane_b32 s84, v254, 20
	v_readlane_b32 s85, v254, 21
	v_lshlrev_b32_e32 v148, 2, v217
	v_readlane_b32 s76, v254, 0
	v_lshl_add_u64 v[206:207], v[206:207], 2, s[84:85]
	v_lshl_add_u64 v[206:207], v[206:207], 0, v[148:149]
	v_readlane_b32 s77, v254, 1
	v_readlane_b32 s79, v254, 3
	global_store_dwordx4 v[206:207], v[132:135], off nt
	global_store_dwordx4 v[206:207], v[136:139], off offset:16 nt
	v_readlane_b32 s78, v254, 2
	v_mov_b32_e32 v132, s77
	v_mov_b32_e32 v133, s79
	s_lshr_b32 s5, s45, 7
	v_cndmask_b32_e64 v133, v132, v133, s[12:13]
	v_mov_b32_e32 v132, s76
	v_mov_b32_e32 v134, s78
	v_cndmask_b32_e64 v132, v132, v134, s[12:13]
	v_or_b32_e32 v134, s5, v189
	v_mad_i64_i32 v[134:135], s[96:97], v198, v134, v[200:201]
	v_lshlrev_b64 v[134:135], 13, v[134:135]
	v_readlane_b32 s68, v255, 40
	v_lshlrev_b32_e32 v148, 4, v195
	v_lshl_add_u64 v[132:133], v[132:133], 0, v[134:135]
	s_mov_b32 s30, s7
	v_readlane_b32 s69, v255, 41
	v_lshl_add_u64 v[132:133], v[132:133], 0, v[148:149]
	v_readlane_b32 s86, v254, 22
	v_readlane_b32 s87, v254, 23
	v_readlane_b32 s88, v254, 24
	v_readlane_b32 s89, v254, 25
	v_readlane_b32 s90, v254, 26
	v_readlane_b32 s91, v254, 27
	v_readlane_b32 s80, v254, 4
	v_readlane_b32 s81, v254, 5
	v_readlane_b32 s82, v254, 6
	v_readlane_b32 s83, v254, 7
	global_store_dwordx4 v[132:133], v[128:131], off nt

; DI unsigned pk2(float lo, float hi) { unsigned r; asm volatile("v_cvt_pk_bf16_f32 %0, %1, %2" : "=v"(r) : "v"(lo), "v"(hi)); return r; }
; DI size_t kf_index(int seqh, int nkt, int key, int d) { return ((((size_t)seqh * nkt + (key >> 5)) * 8 + (d >> 4)) * 64 + ((key & 31) + 32 * ((d >> 3) & 1))) * 8 + (d & 7); }
;     DI void operator()(const f32x4 (&acc)[2][2][4][2], const Unit& u, int wr, int wc, int fr, int fq, const Pre& pre) const {
;     ...
;         for (int ai = 0; ai < 2; ++ai)
; #pragma unroll
;             for (int m = 0; m < 4; ++m) { const int row = row0 + ai * 128 + m * 16; const float r = rs[ai][m];
;                 const bool smp = row >= NTP; const int s = row - NTP; const int b = smp ? (s >> 6) : row / TP, key = smp ? 1024 + (s & 63) : row - b * TP, nkt = smp ? 34 : 129;
; #pragma unroll
;                 for (int bj = 0; bj < 2; ++bj) { const int cs = cb + bj * 128; const f32x4 v0 = acc[ai][bj][m][0] * r, v1 = acc[ai][bj][m][1] * r;
;                     u32x4v o; o.x = pk2(v0[0], v0[1]); o.y = pk2(v0[2], v0[3]); o.z = pk2(v1[0], v1[1]); o.w = pk2(v1[2], v1[3]);
;                     if (third == 0) { *(u32x4v*)(Q + (size_t)row * 1024 + cs) = o; }
;                     else if (row < NT) { const int h = cs >> 7, d = cs & 127;
;                         float* ok = out + (smp ? O_KS + (size_t)s * 1024 : O_KP + (size_t)row * 1024) + cs; *(f32x4*)ok = v0; *(f32x4*)(ok + 4) = v1;
;                         *(u32x4v*)((smp ? KS : KP) + kf_index(b * 8 + h, nkt, key, d)) = o; } } }
.LBB0_1893:
	v_readlane_b32 s76, v255, 8
	v_lshlrev_b64 v[132:133], 11, v[190:191]
	v_readlane_b32 s90, v255, 22
	v_readlane_b32 s91, v255, 23
	s_andn2_b64 vcc, exec, s[10:11]
	v_readlane_b32 s77, v255, 9
	v_lshl_add_u64 v[206:207], s[90:91], 0, v[132:133]
	v_readlane_b32 s78, v255, 10
	v_readlane_b32 s79, v255, 11
	v_readlane_b32 s80, v255, 12
	v_readlane_b32 s81, v255, 13
	v_readlane_b32 s82, v255, 14
	v_readlane_b32 s83, v255, 15
	v_readlane_b32 s84, v255, 16
	v_readlane_b32 s85, v255, 17
	v_readlane_b32 s86, v255, 18
	v_readlane_b32 s87, v255, 19
	v_readlane_b32 s88, v255, 20
	v_readlane_b32 s89, v255, 21
	s_cbranch_vccnz .LBB0_1895
	v_mov_b32_e32 v197, v149
	v_lshl_add_u64 v[132:133], v[206:207], 0, v[196:197]
	global_store_dwordx4 v[132:133], v[128:131], off nt
.LBB0_1895:
	s_nop 1
	v_mov_b32_e32 v128, v193
	v_mov_b32_e32 v129, v193
	v_mov_b32_e32 v130, v193
	v_mov_b32_e32 v131, v193
	v_pk_mul_f32 v[134:135], v[86:87], v[130:131]
	v_pk_mul_f32 v[132:133], v[84:85], v[128:129]
	v_pk_mul_f32 v[138:139], v[82:83], v[130:131]
	v_pk_mul_f32 v[136:137], v[80:81], v[128:129]
	s_and_b64 vcc, exec, s[0:1]
	s_mov_b64 s[10:11], -1
	v_cvt_pk_bf16_f32 v128, v132, v133
	v_cvt_pk_bf16_f32 v129, v134, v135
	v_cvt_pk_bf16_f32 v130, v136, v137
	v_cvt_pk_bf16_f32 v131, v138, v139
	s_cbranch_vccnz .LBB0_1899
	s_and_saveexec_b64 s[10:11], s[14:15]
	s_cbranch_execz .LBB0_1898
	v_readlane_b32 s76, v254, 12
	v_cndmask_b32_e64 v203, v203, v205, s[12:13]
	v_cndmask_b32_e64 v202, v202, v204, s[12:13]
	v_readlane_b32 s77, v254, 13
	v_readlane_b32 s78, v254, 14
	v_readlane_b32 s79, v254, 15
	v_readlane_b32 s80, v254, 16
	v_readlane_b32 s81, v254, 17
	v_readlane_b32 s82, v254, 18
	v_readlane_b32 s83, v254, 19
	v_readlane_b32 s84, v254, 20
	v_readlane_b32 s85, v254, 21
	v_lshlrev_b32_e32 v148, 2, v217
	v_readlane_b32 s76, v254, 0
	v_lshl_add_u64 v[202:203], v[202:203], 2, s[84:85]
	v_lshl_add_u64 v[202:203], v[202:203], 0, v[148:149]
	v_readlane_b32 s77, v254, 1
	v_readlane_b32 s79, v254, 3
	global_store_dwordx4 v[202:203], v[132:135], off offset:512 nt
	global_store_dwordx4 v[202:203], v[136:139], off offset:528 nt
	v_readlane_b32 s78, v254, 2
	v_mov_b32_e32 v132, s77
	v_mov_b32_e32 v133, s79
	v_lshrrev_b32_e32 v191, 7, v218
	v_cndmask_b32_e64 v133, v132, v133, s[12:13]
	v_mov_b32_e32 v132, s76
	v_mov_b32_e32 v134, s78
	v_cndmask_b32_e64 v132, v132, v134, s[12:13]
	v_or_b32_e32 v134, v189, v191
	v_mad_i64_i32 v[134:135], s[12:13], v198, v134, v[200:201]
	v_lshlrev_b64 v[134:135], 13, v[134:135]
	v_readlane_b32 s68, v255, 40
	v_lshlrev_b32_e32 v148, 4, v195
	v_lshl_add_u64 v[132:133], v[132:133], 0, v[134:135]
	s_mov_b32 s30, s7
	v_readlane_b32 s69, v255, 41
	v_lshl_add_u64 v[132:133], v[132:133], 0, v[148:149]
	v_readlane_b32 s86, v254, 22
	v_readlane_b32 s87, v254, 23
	v_readlane_b32 s88, v254, 24
	v_readlane_b32 s89, v254, 25
	v_readlane_b32 s90, v254, 26
	v_readlane_b32 s91, v254, 27
	v_readlane_b32 s80, v254, 4
	v_readlane_b32 s81, v254, 5
	v_readlane_b32 s82, v254, 6
	v_readlane_b32 s83, v254, 7
	global_store_dwordx4 v[132:133], v[128:131], off nt

; DI unsigned pk2(float lo, float hi) { unsigned r; asm volatile("v_cvt_pk_bf16_f32 %0, %1, %2" : "=v"(r) : "v"(lo), "v"(hi)); return r; }
; DI size_t kf_index(int seqh, int nkt, int key, int d) { return ((((size_t)seqh * nkt + (key >> 5)) * 8 + (d >> 4)) * 64 + ((key & 31) + 32 * ((d >> 3) & 1))) * 8 + (d & 7); }
;     DI void operator()(const f32x4 (&acc)[2][2][4][2], const Unit& u, int wr, int wc, int fr, int fq, const Pre& pre) const {
;     ...
;         for (int ai = 0; ai < 2; ++ai)
; #pragma unroll
;             for (int m = 0; m < 4; ++m) { const int row = row0 + ai * 128 + m * 16; const float r = rs[ai][m];
;                 const bool smp = row >= NTP; const int s = row - NTP; const int b = smp ? (s >> 6) : row / TP, key = smp ? 1024 + (s & 63) : row - b * TP, nkt = smp ? 34 : 129;
; #pragma unroll
;                 for (int bj = 0; bj < 2; ++bj) { const int cs = cb + bj * 128; const f32x4 v0 = acc[ai][bj][m][0] * r, v1 = acc[ai][bj][m][1] * r;
;                     u32x4v o; o.x = pk2(v0[0], v0[1]); o.y = pk2(v0[2], v0[3]); o.z = pk2(v1[0], v1[1]); o.w = pk2(v1[2], v1[3]);
;                     if (third == 0) { *(u32x4v*)(Q + (size_t)row * 1024 + cs) = o; }
;                     else if (row < NT) { const int h = cs >> 7, d = cs & 127;
;                         float* ok = out + (smp ? O_KS + (size_t)s * 1024 : O_KP + (size_t)row * 1024) + cs; *(f32x4*)ok = v0; *(f32x4*)(ok + 4) = v1;
;                         *(u32x4v*)((smp ? KS : KP) + kf_index(b * 8 + h, nkt, key, d)) = o; } } }
.LBB0_1901:
	v_cmp_lt_i32_e64 s[12:13], s28, v188
	v_cmp_gt_i32_e32 vcc, s6, v188
	s_and_saveexec_b64 s[10:11], vcc
	s_xor_b64 s[10:11], exec, s[10:11]
	v_mul_hi_i32 v128, v188, s18
	v_lshrrev_b32_e32 v129, 31, v128
	v_ashrrev_i32_e32 v128, 11, v128
	v_add_u32_e32 v128, v128, v129
	s_or_saveexec_b64 s[10:11], s[10:11]
	v_add_u32_e32 v148, 0xffff7fb0, v180
	v_mov_b64_e32 v[198:199], 0x81
	s_xor_b64 exec, exec, s[10:11]
	v_lshrrev_b32_e32 v128, 6, v148
	v_mov_b64_e32 v[198:199], 34
	s_or_b64 exec, exec, s[10:11]
	v_mad_u64_u32 v[130:131], s[10:11], v128, s19, v[188:189]
	v_ashrrev_i32_e32 v189, 31, v188
	v_cndmask_b32_e64 v129, v130, v211, s[12:13]
	v_lshlrev_b64 v[130:131], 10, v[188:189]
	v_lshl_add_u64 v[202:203], v[130:131], 0, s[36:37]
	v_lshlrev_b64 v[130:131], 10, v[148:149]
	v_ashrrev_i32_e32 v200, 5, v129
	v_cmp_gt_i32_e64 s[14:15], s4, v188
	v_lshl_add_u64 v[204:205], v[130:131], 0, s[38:39]
	v_lshlrev_b32_e32 v191, 3, v128
	v_ashrrev_i32_e32 v201, 31, v200
	v_and_or_b32 v195, v129, 31, v163
	v_pk_mul_f32 v[134:135], v[78:79], v[186:187] op_sel_hi:[1,0]
	v_pk_mul_f32 v[132:133], v[76:77], v[186:187] op_sel_hi:[1,0]
	v_pk_mul_f32 v[138:139], v[74:75], v[186:187] op_sel_hi:[1,0]
	v_pk_mul_f32 v[136:137], v[72:73], v[186:187] op_sel_hi:[1,0]
	s_and_b64 vcc, exec, s[0:1]
	s_mov_b64 s[10:11], -1
	v_cvt_pk_bf16_f32 v128, v132, v133
	v_cvt_pk_bf16_f32 v129, v134, v135
	v_cvt_pk_bf16_f32 v130, v136, v137
	v_cvt_pk_bf16_f32 v131, v138, v139
	s_cbranch_vccnz .LBB0_1909
	s_and_saveexec_b64 s[10:11], s[14:15]
	s_cbranch_execz .LBB0_1908
	v_readlane_b32 s76, v254, 12
	v_cndmask_b32_e64 v207, v203, v205, s[12:13]
	v_cndmask_b32_e64 v206, v202, v204, s[12:13]
	v_readlane_b32 s77, v254, 13
	v_readlane_b32 s78, v254, 14
	v_readlane_b32 s79, v254, 15
	v_readlane_b32 s80, v254, 16
	v_readlane_b32 s81, v254, 17
	v_readlane_b32 s82, v254, 18
	v_readlane_b32 s83, v254, 19
	v_readlane_b32 s84, v254, 20
	v_readlane_b32 s85, v254, 21
	v_lshlrev_b32_e32 v148, 2, v217
	v_readlane_b32 s76, v254, 0
	v_lshl_add_u64 v[206:207], v[206:207], 2, s[84:85]
	v_lshl_add_u64 v[206:207], v[206:207], 0, v[148:149]
	v_readlane_b32 s77, v254, 1
	v_readlane_b32 s79, v254, 3
	global_store_dwordx4 v[206:207], v[132:135], off nt
	global_store_dwordx4 v[206:207], v[136:139], off offset:16 nt
	v_readlane_b32 s78, v254, 2
	v_mov_b32_e32 v132, s77
	v_mov_b32_e32 v133, s79
	s_lshr_b32 s5, s45, 7
	v_cndmask_b32_e64 v133, v132, v133, s[12:13]
	v_mov_b32_e32 v132, s76
	v_mov_b32_e32 v134, s78
	v_cndmask_b32_e64 v132, v132, v134, s[12:13]
	v_or_b32_e32 v134, s5, v191
	v_mad_i64_i32 v[134:135], s[96:97], v198, v134, v[200:201]
	v_lshlrev_b64 v[134:135], 13, v[134:135]
	v_readlane_b32 s68, v255, 40
	v_lshlrev_b32_e32 v148, 4, v195
	v_lshl_add_u64 v[132:133], v[132:133], 0, v[134:135]
	s_mov_b32 s30, s7
	v_readlane_b32 s69, v255, 41
	v_lshl_add_u64 v[132:133], v[132:133], 0, v[148:149]
	v_readlane_b32 s86, v254, 22
	v_readlane_b32 s87, v254, 23
	v_readlane_b32 s88, v254, 24
	v_readlane_b32 s89, v254, 25
	v_readlane_b32 s90, v254, 26
	v_readlane_b32 s91, v254, 27
	v_readlane_b32 s80, v254, 4
	v_readlane_b32 s81, v254, 5
	v_readlane_b32 s82, v254, 6
	v_readlane_b32 s83, v254, 7
	global_store_dwordx4 v[132:133], v[128:131], off nt

; DI unsigned pk2(float lo, float hi) { unsigned r; asm volatile("v_cvt_pk_bf16_f32 %0, %1, %2" : "=v"(r) : "v"(lo), "v"(hi)); return r; }
; DI size_t kf_index(int seqh, int nkt, int key, int d) { return ((((size_t)seqh * nkt + (key >> 5)) * 8 + (d >> 4)) * 64 + ((key & 31) + 32 * ((d >> 3) & 1))) * 8 + (d & 7); }
;     DI void operator()(const f32x4 (&acc)[2][2][4][2], const Unit& u, int wr, int wc, int fr, int fq, const Pre& pre) const {
;     ...
;         for (int ai = 0; ai < 2; ++ai)
; #pragma unroll
;             for (int m = 0; m < 4; ++m) { const int row = row0 + ai * 128 + m * 16; const float r = rs[ai][m];
;                 const bool smp = row >= NTP; const int s = row - NTP; const int b = smp ? (s >> 6) : row / TP, key = smp ? 1024 + (s & 63) : row - b * TP, nkt = smp ? 34 : 129;
; #pragma unroll
;                 for (int bj = 0; bj < 2; ++bj) { const int cs = cb + bj * 128; const f32x4 v0 = acc[ai][bj][m][0] * r, v1 = acc[ai][bj][m][1] * r;
;                     u32x4v o; o.x = pk2(v0[0], v0[1]); o.y = pk2(v0[2], v0[3]); o.z = pk2(v1[0], v1[1]); o.w = pk2(v1[2], v1[3]);
;                     if (third == 0) { *(u32x4v*)(Q + (size_t)row * 1024 + cs) = o; }
;                     else if (row < NT) { const int h = cs >> 7, d = cs & 127;
;                         float* ok = out + (smp ? O_KS + (size_t)s * 1024 : O_KP + (size_t)row * 1024) + cs; *(f32x4*)ok = v0; *(f32x4*)(ok + 4) = v1;
;                         *(u32x4v*)((smp ? KS : KP) + kf_index(b * 8 + h, nkt, key, d)) = o; } } }
.LBB0_1909:
	v_readlane_b32 s76, v255, 8
	v_lshlrev_b64 v[132:133], 11, v[188:189]
	v_readlane_b32 s90, v255, 22
	v_readlane_b32 s91, v255, 23
	s_andn2_b64 vcc, exec, s[10:11]
	v_readlane_b32 s77, v255, 9
	v_lshl_add_u64 v[206:207], s[90:91], 0, v[132:133]
	v_readlane_b32 s78, v255, 10
	v_readlane_b32 s79, v255, 11
	v_readlane_b32 s80, v255, 12
	v_readlane_b32 s81, v255, 13
	v_readlane_b32 s82, v255, 14
	v_readlane_b32 s83, v255, 15
	v_readlane_b32 s84, v255, 16
	v_readlane_b32 s85, v255, 17
	v_readlane_b32 s86, v255, 18
	v_readlane_b32 s87, v255, 19
	v_readlane_b32 s88, v255, 20
	v_readlane_b32 s89, v255, 21
	s_cbranch_vccnz .LBB0_1911
	v_mov_b32_e32 v197, v149
	v_lshl_add_u64 v[132:133], v[206:207], 0, v[196:197]
	global_store_dwordx4 v[132:133], v[128:131], off nt
.LBB0_1911:
	s_nop 1
	v_mov_b32_e32 v128, v186
	v_mov_b32_e32 v129, v186
	v_mov_b32_e32 v130, v186
	v_mov_b32_e32 v131, v186
	v_pk_mul_f32 v[134:135], v[70:71], v[130:131]
	v_pk_mul_f32 v[132:133], v[68:69], v[128:129]
	v_pk_mul_f32 v[138:139], v[66:67], v[130:131]
	v_pk_mul_f32 v[136:137], v[64:65], v[128:129]
	s_and_b64 vcc, exec, s[0:1]
	s_mov_b64 s[10:11], -1
	v_cvt_pk_bf16_f32 v128, v132, v133
	v_cvt_pk_bf16_f32 v129, v134, v135
	v_cvt_pk_bf16_f32 v130, v136, v137
	v_cvt_pk_bf16_f32 v131, v138, v139
	s_cbranch_vccnz .LBB0_1915
	s_and_saveexec_b64 s[10:11], s[14:15]
	s_cbranch_execz .LBB0_1914
	v_readlane_b32 s76, v254, 12
	v_cndmask_b32_e64 v203, v203, v205, s[12:13]
	v_cndmask_b32_e64 v202, v202, v204, s[12:13]
	v_readlane_b32 s77, v254, 13
	v_readlane_b32 s78, v254, 14
	v_readlane_b32 s79, v254, 15
	v_readlane_b32 s80, v254, 16
	v_readlane_b32 s81, v254, 17
	v_readlane_b32 s82, v254, 18
	v_readlane_b32 s83, v254, 19
	v_readlane_b32 s84, v254, 20
	v_readlane_b32 s85, v254, 21
	v_lshlrev_b32_e32 v148, 2, v217
	v_readlane_b32 s76, v254, 0
	v_lshl_add_u64 v[202:203], v[202:203], 2, s[84:85]
	v_lshl_add_u64 v[202:203], v[202:203], 0, v[148:149]
	v_readlane_b32 s77, v254, 1
	v_readlane_b32 s79, v254, 3
	global_store_dwordx4 v[202:203], v[132:135], off offset:512 nt
	global_store_dwordx4 v[202:203], v[136:139], off offset:528 nt
	v_readlane_b32 s78, v254, 2
	v_mov_b32_e32 v132, s77
	v_mov_b32_e32 v133, s79
	v_lshrrev_b32_e32 v189, 7, v218
	v_cndmask_b32_e64 v133, v132, v133, s[12:13]
	v_mov_b32_e32 v132, s76
	v_mov_b32_e32 v134, s78
	v_cndmask_b32_e64 v132, v132, v134, s[12:13]
	v_or_b32_e32 v134, v191, v189
	v_mad_i64_i32 v[134:135], s[12:13], v198, v134, v[200:201]
	v_lshlrev_b64 v[134:135], 13, v[134:135]
	v_readlane_b32 s68, v255, 40
	v_lshlrev_b32_e32 v148, 4, v195
	v_lshl_add_u64 v[132:133], v[132:133], 0, v[134:135]
	s_mov_b32 s30, s7
	v_readlane_b32 s69, v255, 41
	v_lshl_add_u64 v[132:133], v[132:133], 0, v[148:149]
	v_readlane_b32 s86, v254, 22
	v_readlane_b32 s87, v254, 23
	v_readlane_b32 s88, v254, 24
	v_readlane_b32 s89, v254, 25
	v_readlane_b32 s90, v254, 26
	v_readlane_b32 s91, v254, 27
	v_readlane_b32 s80, v254, 4
	v_readlane_b32 s81, v254, 5
	v_readlane_b32 s82, v254, 6
	v_readlane_b32 s83, v254, 7
	global_store_dwordx4 v[132:133], v[128:131], off nt

; DI unsigned pk2(float lo, float hi) { unsigned r; asm volatile("v_cvt_pk_bf16_f32 %0, %1, %2" : "=v"(r) : "v"(lo), "v"(hi)); return r; }
; DI size_t kf_index(int seqh, int nkt, int key, int d) { return ((((size_t)seqh * nkt + (key >> 5)) * 8 + (d >> 4)) * 64 + ((key & 31) + 32 * ((d >> 3) & 1))) * 8 + (d & 7); }
;     DI void operator()(const f32x4 (&acc)[2][2][4][2], const Unit& u, int wr, int wc, int fr, int fq, const Pre& pre) const {
;     ...
;         for (int ai = 0; ai < 2; ++ai)
; #pragma unroll
;             for (int m = 0; m < 4; ++m) { const int row = row0 + ai * 128 + m * 16; const float r = rs[ai][m];
;                 const bool smp = row >= NTP; const int s = row - NTP; const int b = smp ? (s >> 6) : row / TP, key = smp ? 1024 + (s & 63) : row - b * TP, nkt = smp ? 34 : 129;
; #pragma unroll
;                 for (int bj = 0; bj < 2; ++bj) { const int cs = cb + bj * 128; const f32x4 v0 = acc[ai][bj][m][0] * r, v1 = acc[ai][bj][m][1] * r;
;                     u32x4v o; o.x = pk2(v0[0], v0[1]); o.y = pk2(v0[2], v0[3]); o.z = pk2(v1[0], v1[1]); o.w = pk2(v1[2], v1[3]);
;                     if (third == 0) { *(u32x4v*)(Q + (size_t)row * 1024 + cs) = o; }
;                     else if (row < NT) { const int h = cs >> 7, d = cs & 127;
;                         float* ok = out + (smp ? O_KS + (size_t)s * 1024 : O_KP + (size_t)row * 1024) + cs; *(f32x4*)ok = v0; *(f32x4*)(ok + 4) = v1;
;                         *(u32x4v*)((smp ? KS : KP) + kf_index(b * 8 + h, nkt, key, d)) = o; } } }
.LBB0_1917:
	s_movk_i32 s5, 0x7fff
	v_cmp_lt_i32_e64 s[12:13], s5, v180
	s_mov_b32 s5, 0x8000
	v_add_u32_e32 v206, 0x80, v180
	v_cmp_gt_i32_e32 vcc, s5, v180
	s_and_saveexec_b64 s[10:11], vcc
	s_xor_b64 s[10:11], exec, s[10:11]
	v_mul_hi_i32 v128, v206, s18
	v_lshrrev_b32_e32 v129, 31, v128
	v_ashrrev_i32_e32 v128, 11, v128
	v_add_u32_e32 v128, v128, v129
	s_or_saveexec_b64 s[10:11], s[10:11]
	v_add_u32_e32 v148, 0xffff8000, v180
	v_mov_b64_e32 v[198:199], 0x81
	s_xor_b64 exec, exec, s[10:11]
	v_lshrrev_b32_e32 v128, 6, v148
	v_mov_b64_e32 v[198:199], 34
	s_or_b64 exec, exec, s[10:11]
	v_mad_u64_u32 v[130:131], s[10:11], v128, s19, v[206:207]
	v_ashrrev_i32_e32 v207, 31, v206
	v_cndmask_b32_e64 v129, v130, v208, s[12:13]
	v_lshlrev_b64 v[130:131], 10, v[206:207]
	s_mov_b32 s5, 0x8200
	v_lshl_add_u64 v[202:203], v[130:131], 0, s[36:37]
	v_lshlrev_b64 v[130:131], 10, v[148:149]
	v_ashrrev_i32_e32 v200, 5, v129
	v_cmp_gt_i32_e64 s[14:15], s5, v180
	v_lshl_add_u64 v[204:205], v[130:131], 0, s[38:39]
	v_lshlrev_b32_e32 v189, 3, v128
	v_ashrrev_i32_e32 v201, 31, v200
	v_and_or_b32 v191, v129, 31, v163
	v_pk_mul_f32 v[134:135], v[62:63], v[186:187] op_sel:[0,1]
	v_pk_mul_f32 v[132:133], v[60:61], v[186:187] op_sel:[0,1]
	v_pk_mul_f32 v[138:139], v[58:59], v[186:187] op_sel:[0,1]
	v_pk_mul_f32 v[136:137], v[56:57], v[186:187] op_sel:[0,1]
	s_and_b64 vcc, exec, s[0:1]
	s_mov_b64 s[10:11], -1
	v_cvt_pk_bf16_f32 v128, v132, v133
	v_cvt_pk_bf16_f32 v129, v134, v135
	v_cvt_pk_bf16_f32 v130, v136, v137
	v_cvt_pk_bf16_f32 v131, v138, v139
	s_cbranch_vccnz .LBB0_1925
	s_and_saveexec_b64 s[10:11], s[14:15]
	s_cbranch_execz .LBB0_1924
	v_readlane_b32 s76, v254, 12
	v_cndmask_b32_e64 v221, v203, v205, s[12:13]
	v_cndmask_b32_e64 v220, v202, v204, s[12:13]
	v_readlane_b32 s77, v254, 13
	v_readlane_b32 s78, v254, 14
	v_readlane_b32 s79, v254, 15
	v_readlane_b32 s80, v254, 16
	v_readlane_b32 s81, v254, 17
	v_readlane_b32 s82, v254, 18
	v_readlane_b32 s83, v254, 19
	v_readlane_b32 s84, v254, 20
	v_readlane_b32 s85, v254, 21
	v_lshlrev_b32_e32 v148, 2, v217
	v_readlane_b32 s76, v254, 0
	v_lshl_add_u64 v[220:221], v[220:221], 2, s[84:85]
	v_lshl_add_u64 v[220:221], v[220:221], 0, v[148:149]
	v_readlane_b32 s77, v254, 1
	v_readlane_b32 s79, v254, 3
	global_store_dwordx4 v[220:221], v[132:135], off nt
	global_store_dwordx4 v[220:221], v[136:139], off offset:16 nt
	v_readlane_b32 s78, v254, 2
	v_mov_b32_e32 v132, s77
	v_mov_b32_e32 v133, s79
	s_lshr_b32 s5, s45, 7
	v_cndmask_b32_e64 v133, v132, v133, s[12:13]
	v_mov_b32_e32 v132, s76
	v_mov_b32_e32 v134, s78
	v_cndmask_b32_e64 v132, v132, v134, s[12:13]
	v_or_b32_e32 v134, s5, v189
	v_mad_i64_i32 v[134:135], s[96:97], v198, v134, v[200:201]
	v_lshlrev_b64 v[134:135], 13, v[134:135]
	v_readlane_b32 s68, v255, 40
	v_lshlrev_b32_e32 v148, 4, v191
	v_lshl_add_u64 v[132:133], v[132:133], 0, v[134:135]
	s_mov_b32 s30, s7
	v_readlane_b32 s69, v255, 41
	v_lshl_add_u64 v[132:133], v[132:133], 0, v[148:149]
	v_readlane_b32 s86, v254, 22
	v_readlane_b32 s87, v254, 23
	v_readlane_b32 s88, v254, 24
	v_readlane_b32 s89, v254, 25
	v_readlane_b32 s90, v254, 26
	v_readlane_b32 s91, v254, 27
	v_readlane_b32 s80, v254, 4
	v_readlane_b32 s81, v254, 5
	v_readlane_b32 s82, v254, 6
	v_readlane_b32 s83, v254, 7
	global_store_dwordx4 v[132:133], v[128:131], off nt

; DI unsigned pk2(float lo, float hi) { unsigned r; asm volatile("v_cvt_pk_bf16_f32 %0, %1, %2" : "=v"(r) : "v"(lo), "v"(hi)); return r; }
; DI size_t kf_index(int seqh, int nkt, int key, int d) { return ((((size_t)seqh * nkt + (key >> 5)) * 8 + (d >> 4)) * 64 + ((key & 31) + 32 * ((d >> 3) & 1))) * 8 + (d & 7); }
;     DI void operator()(const f32x4 (&acc)[2][2][4][2], const Unit& u, int wr, int wc, int fr, int fq, const Pre& pre) const {
;     ...
;         for (int ai = 0; ai < 2; ++ai)
; #pragma unroll
;             for (int m = 0; m < 4; ++m) { const int row = row0 + ai * 128 + m * 16; const float r = rs[ai][m];
;                 const bool smp = row >= NTP; const int s = row - NTP; const int b = smp ? (s >> 6) : row / TP, key = smp ? 1024 + (s & 63) : row - b * TP, nkt = smp ? 34 : 129;
; #pragma unroll
;                 for (int bj = 0; bj < 2; ++bj) { const int cs = cb + bj * 128; const f32x4 v0 = acc[ai][bj][m][0] * r, v1 = acc[ai][bj][m][1] * r;
;                     u32x4v o; o.x = pk2(v0[0], v0[1]); o.y = pk2(v0[2], v0[3]); o.z = pk2(v1[0], v1[1]); o.w = pk2(v1[2], v1[3]);
;                     if (third == 0) { *(u32x4v*)(Q + (size_t)row * 1024 + cs) = o; }
;                     else if (row < NT) { const int h = cs >> 7, d = cs & 127;
;                         float* ok = out + (smp ? O_KS + (size_t)s * 1024 : O_KP + (size_t)row * 1024) + cs; *(f32x4*)ok = v0; *(f32x4*)(ok + 4) = v1;
;                         *(u32x4v*)((smp ? KS : KP) + kf_index(b * 8 + h, nkt, key, d)) = o; } } }
.LBB0_1925:
	v_readlane_b32 s76, v255, 8
	v_lshlrev_b64 v[132:133], 11, v[206:207]
	v_readlane_b32 s90, v255, 22
	v_readlane_b32 s91, v255, 23
	s_andn2_b64 vcc, exec, s[10:11]
	v_readlane_b32 s77, v255, 9
	v_lshl_add_u64 v[206:207], s[90:91], 0, v[132:133]
	v_readlane_b32 s78, v255, 10
	v_readlane_b32 s79, v255, 11
	v_readlane_b32 s80, v255, 12
	v_readlane_b32 s81, v255, 13
	v_readlane_b32 s82, v255, 14
	v_readlane_b32 s83, v255, 15
	v_readlane_b32 s84, v255, 16
	v_readlane_b32 s85, v255, 17
	v_readlane_b32 s86, v255, 18
	v_readlane_b32 s87, v255, 19
	v_readlane_b32 s88, v255, 20
	v_readlane_b32 s89, v255, 21
	s_cbranch_vccnz .LBB0_1927
	v_mov_b32_e32 v197, v149
	v_lshl_add_u64 v[132:133], v[206:207], 0, v[196:197]
	global_store_dwordx4 v[132:133], v[128:131], off nt
.LBB0_1927:
	s_nop 1
	v_mov_b32_e32 v128, v187
	v_mov_b32_e32 v129, v187
	v_mov_b32_e32 v130, v187
	v_mov_b32_e32 v131, v187
	v_pk_mul_f32 v[134:135], v[54:55], v[130:131]
	v_pk_mul_f32 v[132:133], v[52:53], v[128:129]
	v_pk_mul_f32 v[138:139], v[50:51], v[130:131]
	v_pk_mul_f32 v[136:137], v[48:49], v[128:129]
	s_and_b64 vcc, exec, s[0:1]
	s_mov_b64 s[10:11], -1
	v_cvt_pk_bf16_f32 v128, v132, v133
	v_cvt_pk_bf16_f32 v129, v134, v135
	v_cvt_pk_bf16_f32 v130, v136, v137
	v_cvt_pk_bf16_f32 v131, v138, v139
	s_cbranch_vccnz .LBB0_1931
	s_and_saveexec_b64 s[10:11], s[14:15]
	s_cbranch_execz .LBB0_1930
	v_readlane_b32 s76, v254, 12
	v_cndmask_b32_e64 v203, v203, v205, s[12:13]
	v_cndmask_b32_e64 v202, v202, v204, s[12:13]
	v_readlane_b32 s77, v254, 13
	v_readlane_b32 s78, v254, 14
	v_readlane_b32 s79, v254, 15
	v_readlane_b32 s80, v254, 16
	v_readlane_b32 s81, v254, 17
	v_readlane_b32 s82, v254, 18
	v_readlane_b32 s83, v254, 19
	v_readlane_b32 s84, v254, 20
	v_readlane_b32 s85, v254, 21
	v_lshlrev_b32_e32 v148, 2, v217
	v_readlane_b32 s76, v254, 0
	v_lshl_add_u64 v[202:203], v[202:203], 2, s[84:85]
	v_lshl_add_u64 v[202:203], v[202:203], 0, v[148:149]
	v_readlane_b32 s77, v254, 1
	v_readlane_b32 s79, v254, 3
	global_store_dwordx4 v[202:203], v[132:135], off offset:512 nt
	global_store_dwordx4 v[202:203], v[136:139], off offset:528 nt
	v_readlane_b32 s78, v254, 2
	v_mov_b32_e32 v132, s77
	v_mov_b32_e32 v133, s79
	v_lshrrev_b32_e32 v195, 7, v218
	v_cndmask_b32_e64 v133, v132, v133, s[12:13]
	v_mov_b32_e32 v132, s76
	v_mov_b32_e32 v134, s78
	v_cndmask_b32_e64 v132, v132, v134, s[12:13]
	v_or_b32_e32 v134, v189, v195
	v_mad_i64_i32 v[134:135], s[12:13], v198, v134, v[200:201]
	v_lshlrev_b64 v[134:135], 13, v[134:135]
	v_readlane_b32 s68, v255, 40
	v_lshlrev_b32_e32 v148, 4, v191
	v_lshl_add_u64 v[132:133], v[132:133], 0, v[134:135]
	s_mov_b32 s30, s7
	v_readlane_b32 s69, v255, 41
	v_lshl_add_u64 v[132:133], v[132:133], 0, v[148:149]
	v_readlane_b32 s86, v254, 22
	v_readlane_b32 s87, v254, 23
	v_readlane_b32 s88, v254, 24
	v_readlane_b32 s89, v254, 25
	v_readlane_b32 s90, v254, 26
	v_readlane_b32 s91, v254, 27
	v_readlane_b32 s80, v254, 4
	v_readlane_b32 s81, v254, 5
	v_readlane_b32 s82, v254, 6
	v_readlane_b32 s83, v254, 7
	global_store_dwordx4 v[132:133], v[128:131], off nt

; DI unsigned pk2(float lo, float hi) { unsigned r; asm volatile("v_cvt_pk_bf16_f32 %0, %1, %2" : "=v"(r) : "v"(lo), "v"(hi)); return r; }
; DI size_t kf_index(int seqh, int nkt, int key, int d) { return ((((size_t)seqh * nkt + (key >> 5)) * 8 + (d >> 4)) * 64 + ((key & 31) + 32 * ((d >> 3) & 1))) * 8 + (d & 7); }
;     DI void operator()(const f32x4 (&acc)[2][2][4][2], const Unit& u, int wr, int wc, int fr, int fq, const Pre& pre) const {
;     ...
;         for (int ai = 0; ai < 2; ++ai)
; #pragma unroll
;             for (int m = 0; m < 4; ++m) { const int row = row0 + ai * 128 + m * 16; const float r = rs[ai][m];
;                 const bool smp = row >= NTP; const int s = row - NTP; const int b = smp ? (s >> 6) : row / TP, key = smp ? 1024 + (s & 63) : row - b * TP, nkt = smp ? 34 : 129;
; #pragma unroll
;                 for (int bj = 0; bj < 2; ++bj) { const int cs = cb + bj * 128; const f32x4 v0 = acc[ai][bj][m][0] * r, v1 = acc[ai][bj][m][1] * r;
;                     u32x4v o; o.x = pk2(v0[0], v0[1]); o.y = pk2(v0[2], v0[3]); o.z = pk2(v1[0], v1[1]); o.w = pk2(v1[2], v1[3]);
;                     if (third == 0) { *(u32x4v*)(Q + (size_t)row * 1024 + cs) = o; }
;                     else if (row < NT) { const int h = cs >> 7, d = cs & 127;
;                         float* ok = out + (smp ? O_KS + (size_t)s * 1024 : O_KP + (size_t)row * 1024) + cs; *(f32x4*)ok = v0; *(f32x4*)(ok + 4) = v1;
;                         *(u32x4v*)((smp ? KS : KP) + kf_index(b * 8 + h, nkt, key, d)) = o; } } }
.LBB0_1933:
	s_movk_i32 s5, 0x7fef
	v_cmp_lt_i32_e64 s[12:13], s5, v180
	s_movk_i32 s5, 0x7ff0
	v_add_u32_e32 v206, 0x90, v180
	v_cmp_gt_i32_e32 vcc, s5, v180
	s_and_saveexec_b64 s[10:11], vcc
	s_xor_b64 s[10:11], exec, s[10:11]
	v_mul_hi_i32 v128, v206, s18
	v_lshrrev_b32_e32 v129, 31, v128
	v_ashrrev_i32_e32 v128, 11, v128
	v_add_u32_e32 v128, v128, v129
	s_or_saveexec_b64 s[10:11], s[10:11]
	v_add_u32_e32 v148, 0xffff8010, v180
	v_mov_b64_e32 v[198:199], 0x81
	s_xor_b64 exec, exec, s[10:11]
	v_lshrrev_b32_e32 v128, 6, v148
	v_mov_b64_e32 v[198:199], 34
	s_or_b64 exec, exec, s[10:11]
	v_mad_u64_u32 v[130:131], s[10:11], v128, s19, v[206:207]
	v_ashrrev_i32_e32 v207, 31, v206
	v_cndmask_b32_e64 v129, v130, v209, s[12:13]
	v_lshlrev_b64 v[130:131], 10, v[206:207]
	s_mov_b32 s5, 0x81f0
	v_lshl_add_u64 v[202:203], v[130:131], 0, s[36:37]
	v_lshlrev_b64 v[130:131], 10, v[148:149]
	v_ashrrev_i32_e32 v200, 5, v129
	v_cmp_gt_i32_e64 s[14:15], s5, v180
	v_lshl_add_u64 v[204:205], v[130:131], 0, s[38:39]
	v_lshlrev_b32_e32 v189, 3, v128
	v_ashrrev_i32_e32 v201, 31, v200
	v_and_or_b32 v191, v129, 31, v163
	v_pk_mul_f32 v[134:135], v[46:47], v[182:183] op_sel_hi:[1,0]
	v_pk_mul_f32 v[132:133], v[44:45], v[182:183] op_sel_hi:[1,0]
	v_pk_mul_f32 v[138:139], v[42:43], v[182:183] op_sel_hi:[1,0]
	v_pk_mul_f32 v[136:137], v[40:41], v[182:183] op_sel_hi:[1,0]
	s_and_b64 vcc, exec, s[0:1]
	s_mov_b64 s[10:11], -1
	v_cvt_pk_bf16_f32 v128, v132, v133
	v_cvt_pk_bf16_f32 v129, v134, v135
	v_cvt_pk_bf16_f32 v130, v136, v137
	v_cvt_pk_bf16_f32 v131, v138, v139
	s_cbranch_vccnz .LBB0_1941
	s_and_saveexec_b64 s[10:11], s[14:15]
	s_cbranch_execz .LBB0_1940
	v_readlane_b32 s76, v254, 12
	v_cndmask_b32_e64 v221, v203, v205, s[12:13]
	v_cndmask_b32_e64 v220, v202, v204, s[12:13]
	v_readlane_b32 s77, v254, 13
	v_readlane_b32 s78, v254, 14
	v_readlane_b32 s79, v254, 15
	v_readlane_b32 s80, v254, 16
	v_readlane_b32 s81, v254, 17
	v_readlane_b32 s82, v254, 18
	v_readlane_b32 s83, v254, 19
	v_readlane_b32 s84, v254, 20
	v_readlane_b32 s85, v254, 21
	v_lshlrev_b32_e32 v148, 2, v217
	v_readlane_b32 s76, v254, 0
	v_lshl_add_u64 v[220:221], v[220:221], 2, s[84:85]
	v_lshl_add_u64 v[220:221], v[220:221], 0, v[148:149]
	v_readlane_b32 s77, v254, 1
	v_readlane_b32 s79, v254, 3
	global_store_dwordx4 v[220:221], v[132:135], off nt
	global_store_dwordx4 v[220:221], v[136:139], off offset:16 nt
	v_readlane_b32 s78, v254, 2
	v_mov_b32_e32 v132, s77
	v_mov_b32_e32 v133, s79
	s_lshr_b32 s5, s45, 7
	v_cndmask_b32_e64 v133, v132, v133, s[12:13]
	v_mov_b32_e32 v132, s76
	v_mov_b32_e32 v134, s78
	v_cndmask_b32_e64 v132, v132, v134, s[12:13]
	v_or_b32_e32 v134, s5, v189
	v_mad_i64_i32 v[134:135], s[96:97], v198, v134, v[200:201]
	v_lshlrev_b64 v[134:135], 13, v[134:135]
	v_readlane_b32 s68, v255, 40
	v_lshlrev_b32_e32 v148, 4, v191
	v_lshl_add_u64 v[132:133], v[132:133], 0, v[134:135]
	s_mov_b32 s30, s7
	v_readlane_b32 s69, v255, 41
	v_lshl_add_u64 v[132:133], v[132:133], 0, v[148:149]
	v_readlane_b32 s86, v254, 22
	v_readlane_b32 s87, v254, 23
	v_readlane_b32 s88, v254, 24
	v_readlane_b32 s89, v254, 25
	v_readlane_b32 s90, v254, 26
	v_readlane_b32 s91, v254, 27
	v_readlane_b32 s80, v254, 4
	v_readlane_b32 s81, v254, 5
	v_readlane_b32 s82, v254, 6
	v_readlane_b32 s83, v254, 7
	global_store_dwordx4 v[132:133], v[128:131], off nt

; DI unsigned pk2(float lo, float hi) { unsigned r; asm volatile("v_cvt_pk_bf16_f32 %0, %1, %2" : "=v"(r) : "v"(lo), "v"(hi)); return r; }
; DI size_t kf_index(int seqh, int nkt, int key, int d) { return ((((size_t)seqh * nkt + (key >> 5)) * 8 + (d >> 4)) * 64 + ((key & 31) + 32 * ((d >> 3) & 1))) * 8 + (d & 7); }
;     DI void operator()(const f32x4 (&acc)[2][2][4][2], const Unit& u, int wr, int wc, int fr, int fq, const Pre& pre) const {
;     ...
;         for (int ai = 0; ai < 2; ++ai)
; #pragma unroll
;             for (int m = 0; m < 4; ++m) { const int row = row0 + ai * 128 + m * 16; const float r = rs[ai][m];
;                 const bool smp = row >= NTP; const int s = row - NTP; const int b = smp ? (s >> 6) : row / TP, key = smp ? 1024 + (s & 63) : row - b * TP, nkt = smp ? 34 : 129;
; #pragma unroll
;                 for (int bj = 0; bj < 2; ++bj) { const int cs = cb + bj * 128; const f32x4 v0 = acc[ai][bj][m][0] * r, v1 = acc[ai][bj][m][1] * r;
;                     u32x4v o; o.x = pk2(v0[0], v0[1]); o.y = pk2(v0[2], v0[3]); o.z = pk2(v1[0], v1[1]); o.w = pk2(v1[2], v1[3]);
;                     if (third == 0) { *(u32x4v*)(Q + (size_t)row * 1024 + cs) = o; }
;                     else if (row < NT) { const int h = cs >> 7, d = cs & 127;
;                         float* ok = out + (smp ? O_KS + (size_t)s * 1024 : O_KP + (size_t)row * 1024) + cs; *(f32x4*)ok = v0; *(f32x4*)(ok + 4) = v1;
;                         *(u32x4v*)((smp ? KS : KP) + kf_index(b * 8 + h, nkt, key, d)) = o; } } }
.LBB0_1943:
	s_nop 1
	v_mov_b32_e32 v128, v182
	v_mov_b32_e32 v129, v182
	v_mov_b32_e32 v130, v182
	v_mov_b32_e32 v131, v182
	v_pk_mul_f32 v[134:135], v[38:39], v[130:131]
	v_pk_mul_f32 v[132:133], v[36:37], v[128:129]
	v_pk_mul_f32 v[138:139], v[34:35], v[130:131]
	v_pk_mul_f32 v[136:137], v[32:33], v[128:129]
	s_and_b64 vcc, exec, s[0:1]
	s_mov_b64 s[10:11], -1
	v_cvt_pk_bf16_f32 v128, v132, v133
	v_cvt_pk_bf16_f32 v129, v134, v135
	v_cvt_pk_bf16_f32 v130, v136, v137
	v_cvt_pk_bf16_f32 v131, v138, v139
	s_cbranch_vccnz .LBB0_1947
	s_and_saveexec_b64 s[10:11], s[14:15]
	s_cbranch_execz .LBB0_1946
	v_readlane_b32 s76, v254, 12
	v_cndmask_b32_e64 v203, v203, v205, s[12:13]
	v_cndmask_b32_e64 v202, v202, v204, s[12:13]
	v_readlane_b32 s77, v254, 13
	v_readlane_b32 s78, v254, 14
	v_readlane_b32 s79, v254, 15
	v_readlane_b32 s80, v254, 16
	v_readlane_b32 s81, v254, 17
	v_readlane_b32 s82, v254, 18
	v_readlane_b32 s83, v254, 19
	v_readlane_b32 s84, v254, 20
	v_readlane_b32 s85, v254, 21
	v_lshlrev_b32_e32 v148, 2, v217
	v_readlane_b32 s76, v254, 0
	v_lshl_add_u64 v[202:203], v[202:203], 2, s[84:85]
	v_lshl_add_u64 v[202:203], v[202:203], 0, v[148:149]
	v_readlane_b32 s77, v254, 1
	v_readlane_b32 s79, v254, 3
	global_store_dwordx4 v[202:203], v[132:135], off offset:512 nt
	global_store_dwordx4 v[202:203], v[136:139], off offset:528 nt
	v_readlane_b32 s78, v254, 2
	v_mov_b32_e32 v132, s77
	v_mov_b32_e32 v133, s79
	v_lshrrev_b32_e32 v195, 7, v218
	v_cndmask_b32_e64 v133, v132, v133, s[12:13]
	v_mov_b32_e32 v132, s76
	v_mov_b32_e32 v134, s78
	v_cndmask_b32_e64 v132, v132, v134, s[12:13]
	v_or_b32_e32 v134, v189, v195
	v_mad_i64_i32 v[134:135], s[12:13], v198, v134, v[200:201]
	v_lshlrev_b64 v[134:135], 13, v[134:135]
	v_readlane_b32 s68, v255, 40
	v_lshlrev_b32_e32 v148, 4, v191
	v_lshl_add_u64 v[132:133], v[132:133], 0, v[134:135]
	s_mov_b32 s30, s7
	v_readlane_b32 s69, v255, 41
	v_lshl_add_u64 v[132:133], v[132:133], 0, v[148:149]
	v_readlane_b32 s86, v254, 22
	v_readlane_b32 s87, v254, 23
	v_readlane_b32 s88, v254, 24
	v_readlane_b32 s89, v254, 25
	v_readlane_b32 s90, v254, 26
	v_readlane_b32 s91, v254, 27
	v_readlane_b32 s80, v254, 4
	v_readlane_b32 s81, v254, 5
	v_readlane_b32 s82, v254, 6
	v_readlane_b32 s83, v254, 7
	global_store_dwordx4 v[132:133], v[128:131], off nt

; DI unsigned pk2(float lo, float hi) { unsigned r; asm volatile("v_cvt_pk_bf16_f32 %0, %1, %2" : "=v"(r) : "v"(lo), "v"(hi)); return r; }
; DI size_t kf_index(int seqh, int nkt, int key, int d) { return ((((size_t)seqh * nkt + (key >> 5)) * 8 + (d >> 4)) * 64 + ((key & 31) + 32 * ((d >> 3) & 1))) * 8 + (d & 7); }
;     DI void operator()(const f32x4 (&acc)[2][2][4][2], const Unit& u, int wr, int wc, int fr, int fq, const Pre& pre) const {
;     ...
;         for (int ai = 0; ai < 2; ++ai)
; #pragma unroll
;             for (int m = 0; m < 4; ++m) { const int row = row0 + ai * 128 + m * 16; const float r = rs[ai][m];
;                 const bool smp = row >= NTP; const int s = row - NTP; const int b = smp ? (s >> 6) : row / TP, key = smp ? 1024 + (s & 63) : row - b * TP, nkt = smp ? 34 : 129;
; #pragma unroll
;                 for (int bj = 0; bj < 2; ++bj) { const int cs = cb + bj * 128; const f32x4 v0 = acc[ai][bj][m][0] * r, v1 = acc[ai][bj][m][1] * r;
;                     u32x4v o; o.x = pk2(v0[0], v0[1]); o.y = pk2(v0[2], v0[3]); o.z = pk2(v1[0], v1[1]); o.w = pk2(v1[2], v1[3]);
;                     if (third == 0) { *(u32x4v*)(Q + (size_t)row * 1024 + cs) = o; }
;                     else if (row < NT) { const int h = cs >> 7, d = cs & 127;
;                         float* ok = out + (smp ? O_KS + (size_t)s * 1024 : O_KP + (size_t)row * 1024) + cs; *(f32x4*)ok = v0; *(f32x4*)(ok + 4) = v1;
;                         *(u32x4v*)((smp ? KS : KP) + kf_index(b * 8 + h, nkt, key, d)) = o; } } }
.LBB0_1949:
	s_movk_i32 s5, 0x7fdf
	v_add_u32_e32 v206, 0xa0, v180
	v_cmp_lt_i32_e64 s[12:13], s5, v180
	v_cmp_gt_i32_e32 vcc, s3, v180
	s_and_saveexec_b64 s[10:11], vcc
	s_xor_b64 s[10:11], exec, s[10:11]
	v_mul_hi_i32 v128, v206, s18
	v_lshrrev_b32_e32 v129, 31, v128
	v_ashrrev_i32_e32 v128, 11, v128
	v_add_u32_e32 v128, v128, v129
	s_or_saveexec_b64 s[10:11], s[10:11]
	v_add_u32_e32 v148, 0xffff8020, v180
	v_mov_b64_e32 v[198:199], 0x81
	s_xor_b64 exec, exec, s[10:11]
	v_lshrrev_b32_e32 v128, 6, v148
	v_mov_b64_e32 v[198:199], 34
	s_or_b64 exec, exec, s[10:11]
	v_mad_u64_u32 v[130:131], s[10:11], v128, s19, v[206:207]
	v_ashrrev_i32_e32 v207, 31, v206
	v_cndmask_b32_e64 v129, v130, v210, s[12:13]
	v_lshlrev_b64 v[130:131], 10, v[206:207]
	v_lshl_add_u64 v[202:203], v[130:131], 0, s[36:37]
	v_lshlrev_b64 v[130:131], 10, v[148:149]
	v_ashrrev_i32_e32 v200, 5, v129
	v_cmp_gt_i32_e64 s[14:15], s2, v180
	v_lshl_add_u64 v[204:205], v[130:131], 0, s[38:39]
	v_lshlrev_b32_e32 v189, 3, v128
	v_ashrrev_i32_e32 v201, 31, v200
	v_and_or_b32 v191, v129, 31, v163
	v_pk_mul_f32 v[134:135], v[30:31], v[182:183] op_sel:[0,1]
	v_pk_mul_f32 v[132:133], v[28:29], v[182:183] op_sel:[0,1]
	v_pk_mul_f32 v[138:139], v[26:27], v[182:183] op_sel:[0,1]
	v_pk_mul_f32 v[136:137], v[24:25], v[182:183] op_sel:[0,1]
	s_and_b64 vcc, exec, s[0:1]
	s_mov_b64 s[10:11], -1
	v_cvt_pk_bf16_f32 v128, v132, v133
	v_cvt_pk_bf16_f32 v129, v134, v135
	v_cvt_pk_bf16_f32 v130, v136, v137
	v_cvt_pk_bf16_f32 v131, v138, v139
	s_cbranch_vccnz .LBB0_1957
	s_and_saveexec_b64 s[10:11], s[14:15]
	s_cbranch_execz .LBB0_1956
	v_readlane_b32 s76, v254, 12
	v_cndmask_b32_e64 v221, v203, v205, s[12:13]
	v_cndmask_b32_e64 v220, v202, v204, s[12:13]
	v_readlane_b32 s77, v254, 13
	v_readlane_b32 s78, v254, 14
	v_readlane_b32 s79, v254, 15
	v_readlane_b32 s80, v254, 16
	v_readlane_b32 s81, v254, 17
	v_readlane_b32 s82, v254, 18
	v_readlane_b32 s83, v254, 19
	v_readlane_b32 s84, v254, 20
	v_readlane_b32 s85, v254, 21
	v_lshlrev_b32_e32 v148, 2, v217
	v_readlane_b32 s76, v254, 0
	v_lshl_add_u64 v[220:221], v[220:221], 2, s[84:85]
	v_lshl_add_u64 v[220:221], v[220:221], 0, v[148:149]
	v_readlane_b32 s77, v254, 1
	v_readlane_b32 s79, v254, 3
	global_store_dwordx4 v[220:221], v[132:135], off nt
	global_store_dwordx4 v[220:221], v[136:139], off offset:16 nt
	v_readlane_b32 s78, v254, 2
	v_mov_b32_e32 v132, s77
	v_mov_b32_e32 v133, s79
	s_lshr_b32 s5, s45, 7
	v_cndmask_b32_e64 v133, v132, v133, s[12:13]
	v_mov_b32_e32 v132, s76
	v_mov_b32_e32 v134, s78
	v_cndmask_b32_e64 v132, v132, v134, s[12:13]
	v_or_b32_e32 v134, s5, v189
	v_mad_i64_i32 v[134:135], s[96:97], v198, v134, v[200:201]
	v_lshlrev_b64 v[134:135], 13, v[134:135]
	v_readlane_b32 s68, v255, 40
	v_lshlrev_b32_e32 v148, 4, v191
	v_lshl_add_u64 v[132:133], v[132:133], 0, v[134:135]
	s_mov_b32 s30, s7
	v_readlane_b32 s69, v255, 41
	v_lshl_add_u64 v[132:133], v[132:133], 0, v[148:149]
	v_readlane_b32 s86, v254, 22
	v_readlane_b32 s87, v254, 23
	v_readlane_b32 s88, v254, 24
	v_readlane_b32 s89, v254, 25
	v_readlane_b32 s90, v254, 26
	v_readlane_b32 s91, v254, 27
	v_readlane_b32 s80, v254, 4
	v_readlane_b32 s81, v254, 5
	v_readlane_b32 s82, v254, 6
	v_readlane_b32 s83, v254, 7
	global_store_dwordx4 v[132:133], v[128:131], off nt

; DI unsigned pk2(float lo, float hi) { unsigned r; asm volatile("v_cvt_pk_bf16_f32 %0, %1, %2" : "=v"(r) : "v"(lo), "v"(hi)); return r; }
; DI size_t kf_index(int seqh, int nkt, int key, int d) { return ((((size_t)seqh * nkt + (key >> 5)) * 8 + (d >> 4)) * 64 + ((key & 31) + 32 * ((d >> 3) & 1))) * 8 + (d & 7); }
;     DI void operator()(const f32x4 (&acc)[2][2][4][2], const Unit& u, int wr, int wc, int fr, int fq, const Pre& pre) const {
;     ...
;         for (int ai = 0; ai < 2; ++ai)
; #pragma unroll
;             for (int m = 0; m < 4; ++m) { const int row = row0 + ai * 128 + m * 16; const float r = rs[ai][m];
;                 const bool smp = row >= NTP; const int s = row - NTP; const int b = smp ? (s >> 6) : row / TP, key = smp ? 1024 + (s & 63) : row - b * TP, nkt = smp ? 34 : 129;
; #pragma unroll
;                 for (int bj = 0; bj < 2; ++bj) { const int cs = cb + bj * 128; const f32x4 v0 = acc[ai][bj][m][0] * r, v1 = acc[ai][bj][m][1] * r;
;                     u32x4v o; o.x = pk2(v0[0], v0[1]); o.y = pk2(v0[2], v0[3]); o.z = pk2(v1[0], v1[1]); o.w = pk2(v1[2], v1[3]);
;                     if (third == 0) { *(u32x4v*)(Q + (size_t)row * 1024 + cs) = o; }
;                     else if (row < NT) { const int h = cs >> 7, d = cs & 127;
;                         float* ok = out + (smp ? O_KS + (size_t)s * 1024 : O_KP + (size_t)row * 1024) + cs; *(f32x4*)ok = v0; *(f32x4*)(ok + 4) = v1;
;                         *(u32x4v*)((smp ? KS : KP) + kf_index(b * 8 + h, nkt, key, d)) = o; } } }
.LBB0_1959:
	s_nop 1
	v_mov_b32_e32 v128, v183
	v_mov_b32_e32 v129, v183
	v_mov_b32_e32 v130, v183
	v_mov_b32_e32 v131, v183
	v_pk_mul_f32 v[134:135], v[22:23], v[130:131]
	v_pk_mul_f32 v[132:133], v[20:21], v[128:129]
	v_pk_mul_f32 v[138:139], v[18:19], v[130:131]
	v_pk_mul_f32 v[136:137], v[16:17], v[128:129]
	s_and_b64 vcc, exec, s[0:1]
	s_mov_b64 s[10:11], -1
	v_cvt_pk_bf16_f32 v128, v132, v133
	v_cvt_pk_bf16_f32 v129, v134, v135
	v_cvt_pk_bf16_f32 v130, v136, v137
	v_cvt_pk_bf16_f32 v131, v138, v139
	s_cbranch_vccnz .LBB0_1963
	s_and_saveexec_b64 s[10:11], s[14:15]
	s_cbranch_execz .LBB0_1962
	v_readlane_b32 s76, v254, 12
	v_cndmask_b32_e64 v203, v203, v205, s[12:13]
	v_cndmask_b32_e64 v202, v202, v204, s[12:13]
	v_readlane_b32 s77, v254, 13
	v_readlane_b32 s78, v254, 14
	v_readlane_b32 s79, v254, 15
	v_readlane_b32 s80, v254, 16
	v_readlane_b32 s81, v254, 17
	v_readlane_b32 s82, v254, 18
	v_readlane_b32 s83, v254, 19
	v_readlane_b32 s84, v254, 20
	v_readlane_b32 s85, v254, 21
	v_lshlrev_b32_e32 v148, 2, v217
	v_readlane_b32 s76, v254, 0
	v_lshl_add_u64 v[202:203], v[202:203], 2, s[84:85]
	v_lshl_add_u64 v[202:203], v[202:203], 0, v[148:149]
	v_readlane_b32 s77, v254, 1
	v_readlane_b32 s79, v254, 3
	global_store_dwordx4 v[202:203], v[132:135], off offset:512 nt
	global_store_dwordx4 v[202:203], v[136:139], off offset:528 nt
	v_readlane_b32 s78, v254, 2
	v_mov_b32_e32 v132, s77
	v_mov_b32_e32 v133, s79
	v_lshrrev_b32_e32 v195, 7, v218
	v_cndmask_b32_e64 v133, v132, v133, s[12:13]
	v_mov_b32_e32 v132, s76
	v_mov_b32_e32 v134, s78
	v_cndmask_b32_e64 v132, v132, v134, s[12:13]
	v_or_b32_e32 v134, v189, v195
	v_mad_i64_i32 v[134:135], s[12:13], v198, v134, v[200:201]
	v_lshlrev_b64 v[134:135], 13, v[134:135]
	v_readlane_b32 s68, v255, 40
	v_lshlrev_b32_e32 v148, 4, v191
	v_lshl_add_u64 v[132:133], v[132:133], 0, v[134:135]
	s_mov_b32 s30, s7
	v_readlane_b32 s69, v255, 41
	v_lshl_add_u64 v[132:133], v[132:133], 0, v[148:149]
	v_readlane_b32 s86, v254, 22
	v_readlane_b32 s87, v254, 23
	v_readlane_b32 s88, v254, 24
	v_readlane_b32 s89, v254, 25
	v_readlane_b32 s90, v254, 26
	v_readlane_b32 s91, v254, 27
	v_readlane_b32 s80, v254, 4
	v_readlane_b32 s81, v254, 5
	v_readlane_b32 s82, v254, 6
	v_readlane_b32 s83, v254, 7
	global_store_dwordx4 v[132:133], v[128:131], off nt

; DI unsigned pk2(float lo, float hi) { unsigned r; asm volatile("v_cvt_pk_bf16_f32 %0, %1, %2" : "=v"(r) : "v"(lo), "v"(hi)); return r; }
; DI size_t kf_index(int seqh, int nkt, int key, int d) { return ((((size_t)seqh * nkt + (key >> 5)) * 8 + (d >> 4)) * 64 + ((key & 31) + 32 * ((d >> 3) & 1))) * 8 + (d & 7); }
;     DI void operator()(const f32x4 (&acc)[2][2][4][2], const Unit& u, int wr, int wc, int fr, int fq, const Pre& pre) const {
;     ...
;         for (int ai = 0; ai < 2; ++ai)
; #pragma unroll
;             for (int m = 0; m < 4; ++m) { const int row = row0 + ai * 128 + m * 16; const float r = rs[ai][m];
;                 const bool smp = row >= NTP; const int s = row - NTP; const int b = smp ? (s >> 6) : row / TP, key = smp ? 1024 + (s & 63) : row - b * TP, nkt = smp ? 34 : 129;
; #pragma unroll
;                 for (int bj = 0; bj < 2; ++bj) { const int cs = cb + bj * 128; const f32x4 v0 = acc[ai][bj][m][0] * r, v1 = acc[ai][bj][m][1] * r;
;                     u32x4v o; o.x = pk2(v0[0], v0[1]); o.y = pk2(v0[2], v0[3]); o.z = pk2(v1[0], v1[1]); o.w = pk2(v1[2], v1[3]);
;                     if (third == 0) { *(u32x4v*)(Q + (size_t)row * 1024 + cs) = o; }
;                     else if (row < NT) { const int h = cs >> 7, d = cs & 127;
;                         float* ok = out + (smp ? O_KS + (size_t)s * 1024 : O_KP + (size_t)row * 1024) + cs; *(f32x4*)ok = v0; *(f32x4*)(ok + 4) = v1;
;                         *(u32x4v*)((smp ? KS : KP) + kf_index(b * 8 + h, nkt, key, d)) = o; } } }
.LBB0_1965:
	v_add_u32_e32 v206, 0xb0, v180
	v_cmp_lt_i32_e64 s[12:13], s35, v180
	v_cmp_gt_i32_e32 vcc, s23, v180
	s_and_saveexec_b64 s[10:11], vcc
	s_xor_b64 s[10:11], exec, s[10:11]
	v_mul_hi_i32 v128, v206, s18
	v_lshrrev_b32_e32 v129, 31, v128
	v_ashrrev_i32_e32 v128, 11, v128
	v_add_u32_e32 v128, v128, v129
	s_or_saveexec_b64 s[10:11], s[10:11]
	v_add_u32_e32 v148, 0xffff8030, v180
	v_mov_b64_e32 v[198:199], 0x81
	s_xor_b64 exec, exec, s[10:11]
	v_lshrrev_b32_e32 v128, 6, v148
	v_mov_b64_e32 v[198:199], 34
	s_or_b64 exec, exec, s[10:11]
	v_mad_u64_u32 v[130:131], s[10:11], v128, s19, v[206:207]
	v_ashrrev_i32_e32 v207, 31, v206
	v_cndmask_b32_e64 v129, v130, v211, s[12:13]
	v_lshlrev_b64 v[130:131], 10, v[206:207]
	v_lshl_add_u64 v[202:203], v[130:131], 0, s[36:37]
	v_lshlrev_b64 v[130:131], 10, v[148:149]
	v_ashrrev_i32_e32 v200, 5, v129
	v_cmp_gt_i32_e64 s[14:15], s31, v180
	v_lshl_add_u64 v[204:205], v[130:131], 0, s[38:39]
	v_lshlrev_b32_e32 v189, 3, v128
	v_ashrrev_i32_e32 v201, 31, v200
	v_and_or_b32 v191, v129, 31, v163
	v_pk_mul_f32 v[134:135], v[14:15], v[184:185] op_sel_hi:[1,0]
	v_pk_mul_f32 v[132:133], v[12:13], v[184:185] op_sel_hi:[1,0]
	v_pk_mul_f32 v[138:139], v[10:11], v[184:185] op_sel_hi:[1,0]
	v_pk_mul_f32 v[136:137], v[8:9], v[184:185] op_sel_hi:[1,0]
	s_and_b64 vcc, exec, s[0:1]
	s_mov_b64 s[10:11], -1
	v_cvt_pk_bf16_f32 v128, v132, v133
	v_cvt_pk_bf16_f32 v129, v134, v135
	v_cvt_pk_bf16_f32 v130, v136, v137
	v_cvt_pk_bf16_f32 v131, v138, v139
	s_cbranch_vccnz .LBB0_1973
	s_and_saveexec_b64 s[10:11], s[14:15]
	s_cbranch_execz .LBB0_1972
	v_readlane_b32 s76, v254, 12
	v_cndmask_b32_e64 v221, v203, v205, s[12:13]
	v_cndmask_b32_e64 v220, v202, v204, s[12:13]
	v_readlane_b32 s77, v254, 13
	v_readlane_b32 s78, v254, 14
	v_readlane_b32 s79, v254, 15
	v_readlane_b32 s80, v254, 16
	v_readlane_b32 s81, v254, 17
	v_readlane_b32 s82, v254, 18
	v_readlane_b32 s83, v254, 19
	v_readlane_b32 s84, v254, 20
	v_readlane_b32 s85, v254, 21
	v_lshlrev_b32_e32 v148, 2, v217
	v_readlane_b32 s76, v254, 0
	v_lshl_add_u64 v[220:221], v[220:221], 2, s[84:85]
	v_lshl_add_u64 v[220:221], v[220:221], 0, v[148:149]
	v_readlane_b32 s77, v254, 1
	v_readlane_b32 s79, v254, 3
	global_store_dwordx4 v[220:221], v[132:135], off nt
	global_store_dwordx4 v[220:221], v[136:139], off offset:16 nt
	v_readlane_b32 s78, v254, 2
	v_mov_b32_e32 v132, s77
	v_mov_b32_e32 v133, s79
	s_lshr_b32 s5, s45, 7
	v_cndmask_b32_e64 v133, v132, v133, s[12:13]
	v_mov_b32_e32 v132, s76
	v_mov_b32_e32 v134, s78
	v_cndmask_b32_e64 v132, v132, v134, s[12:13]
	v_or_b32_e32 v134, s5, v189
	v_mad_i64_i32 v[134:135], s[96:97], v198, v134, v[200:201]
	v_lshlrev_b64 v[134:135], 13, v[134:135]
	v_readlane_b32 s68, v255, 40
	v_lshlrev_b32_e32 v148, 4, v191
	v_lshl_add_u64 v[132:133], v[132:133], 0, v[134:135]
	s_mov_b32 s30, s7
	v_readlane_b32 s69, v255, 41
	v_lshl_add_u64 v[132:133], v[132:133], 0, v[148:149]
	v_readlane_b32 s86, v254, 22
	v_readlane_b32 s87, v254, 23
	v_readlane_b32 s88, v254, 24
	v_readlane_b32 s89, v254, 25
	v_readlane_b32 s90, v254, 26
	v_readlane_b32 s91, v254, 27
	v_readlane_b32 s80, v254, 4
	v_readlane_b32 s81, v254, 5
	v_readlane_b32 s82, v254, 6
	v_readlane_b32 s83, v254, 7
	global_store_dwordx4 v[132:133], v[128:131], off nt

; DI unsigned pk2(float lo, float hi) { unsigned r; asm volatile("v_cvt_pk_bf16_f32 %0, %1, %2" : "=v"(r) : "v"(lo), "v"(hi)); return r; }
; DI size_t kf_index(int seqh, int nkt, int key, int d) { return ((((size_t)seqh * nkt + (key >> 5)) * 8 + (d >> 4)) * 64 + ((key & 31) + 32 * ((d >> 3) & 1))) * 8 + (d & 7); }
;     DI void operator()(const f32x4 (&acc)[2][2][4][2], const Unit& u, int wr, int wc, int fr, int fq, const Pre& pre) const {
;     ...
;         for (int ai = 0; ai < 2; ++ai)
; #pragma unroll
;             for (int m = 0; m < 4; ++m) { const int row = row0 + ai * 128 + m * 16; const float r = rs[ai][m];
;                 const bool smp = row >= NTP; const int s = row - NTP; const int b = smp ? (s >> 6) : row / TP, key = smp ? 1024 + (s & 63) : row - b * TP, nkt = smp ? 34 : 129;
; #pragma unroll
;                 for (int bj = 0; bj < 2; ++bj) { const int cs = cb + bj * 128; const f32x4 v0 = acc[ai][bj][m][0] * r, v1 = acc[ai][bj][m][1] * r;
;                     u32x4v o; o.x = pk2(v0[0], v0[1]); o.y = pk2(v0[2], v0[3]); o.z = pk2(v1[0], v1[1]); o.w = pk2(v1[2], v1[3]);
;                     if (third == 0) { *(u32x4v*)(Q + (size_t)row * 1024 + cs) = o; }
;                     else if (row < NT) { const int h = cs >> 7, d = cs & 127;
;                         float* ok = out + (smp ? O_KS + (size_t)s * 1024 : O_KP + (size_t)row * 1024) + cs; *(f32x4*)ok = v0; *(f32x4*)(ok + 4) = v1;
;                         *(u32x4v*)((smp ? KS : KP) + kf_index(b * 8 + h, nkt, key, d)) = o; } } }
.LBB0_1975:
	s_nop 1
	v_mov_b32_e32 v128, v184
	v_mov_b32_e32 v129, v184
	v_mov_b32_e32 v130, v184
	v_mov_b32_e32 v131, v184
	v_pk_mul_f32 v[134:135], v[6:7], v[130:131]
	v_pk_mul_f32 v[132:133], v[4:5], v[128:129]
	v_pk_mul_f32 v[138:139], v[2:3], v[130:131]
	v_pk_mul_f32 v[136:137], v[0:1], v[128:129]
	s_and_b64 vcc, exec, s[0:1]
	s_mov_b64 s[0:1], -1
	s_mov_b32 s84, s30
	s_mov_b64 s[88:89], s[68:69]
	v_readlane_b32 s69, v255, 46
	v_cvt_pk_bf16_f32 v128, v132, v133
	v_cvt_pk_bf16_f32 v129, v134, v135
	v_cvt_pk_bf16_f32 v130, v136, v137
	v_cvt_pk_bf16_f32 v131, v138, v139
	s_cbranch_vccnz .LBB0_1979
	s_and_saveexec_b64 s[0:1], s[14:15]
	s_cbranch_execz .LBB0_1978
	v_readlane_b32 s76, v254, 12
	v_cndmask_b32_e64 v203, v203, v205, s[12:13]
	v_cndmask_b32_e64 v202, v202, v204, s[12:13]
	v_readlane_b32 s77, v254, 13
	v_readlane_b32 s78, v254, 14
	v_readlane_b32 s79, v254, 15
	v_readlane_b32 s80, v254, 16
	v_readlane_b32 s81, v254, 17
	v_readlane_b32 s82, v254, 18
	v_readlane_b32 s83, v254, 19
	v_readlane_b32 s84, v254, 20
	v_readlane_b32 s85, v254, 21
	v_lshlrev_b32_e32 v148, 2, v217
	v_readlane_b32 s76, v254, 0
	v_lshl_add_u64 v[202:203], v[202:203], 2, s[84:85]
	v_lshl_add_u64 v[202:203], v[202:203], 0, v[148:149]
	v_readlane_b32 s77, v254, 1
	v_readlane_b32 s79, v254, 3
	global_store_dwordx4 v[202:203], v[132:135], off offset:512 nt
	global_store_dwordx4 v[202:203], v[136:139], off offset:528 nt
	v_readlane_b32 s78, v254, 2
	v_mov_b32_e32 v132, s77
	v_mov_b32_e32 v133, s79
	v_lshrrev_b32_e32 v195, 7, v218
	v_cndmask_b32_e64 v133, v132, v133, s[12:13]
	v_mov_b32_e32 v132, s76
	v_mov_b32_e32 v134, s78
	v_cndmask_b32_e64 v132, v132, v134, s[12:13]
	v_or_b32_e32 v134, v189, v195
	v_mad_i64_i32 v[134:135], s[10:11], v198, v134, v[200:201]
	v_readlane_b32 s88, v254, 24
	v_readlane_b32 s89, v254, 25
	v_lshlrev_b64 v[134:135], 13, v[134:135]
	v_readlane_b32 s88, v255, 40
	v_lshlrev_b32_e32 v148, 4, v191
	v_lshl_add_u64 v[132:133], v[132:133], 0, v[134:135]
	v_readlane_b32 s89, v255, 41
	s_mov_b32 s84, s7
	v_lshl_add_u64 v[132:133], v[132:133], 0, v[148:149]
	v_readlane_b32 s86, v254, 22
	v_readlane_b32 s87, v254, 23
	v_readlane_b32 s90, v254, 26
	v_readlane_b32 s91, v254, 27
	v_readlane_b32 s80, v254, 4
	v_readlane_b32 s81, v254, 5
	v_readlane_b32 s82, v254, 6
	v_readlane_b32 s83, v254, 7
	global_store_dwordx4 v[132:133], v[128:131], off nt

; DI unsigned pk2(float lo, float hi) { unsigned r; asm volatile("v_cvt_pk_bf16_f32 %0, %1, %2" : "=v"(r) : "v"(lo), "v"(hi)); return r; }
;     DI void operator()(const f32x4 (&acc)[2][2][4][2], const Unit& u, int wr, int wc, int fr, int fq, const Pre& pre) const {
;     ...
;                 for (int bj = 0; bj < 2; ++bj) { const int cs = cb + bj * 128; const f32x4 v0 = acc[ai][bj][m][0] * r, v1 = acc[ai][bj][m][1] * r;
;                     u32x4v o; o.x = pk2(v0[0], v0[1]); o.y = pk2(v0[2], v0[3]); o.z = pk2(v1[0], v1[1]); o.w = pk2(v1[2], v1[3]);
;                     if (third == 0) { *(u32x4v*)(Q + (size_t)row * 1024 + cs) = o; }
.LBB0_1979:
	s_andn2_b64 vcc, exec, s[0:1]
	s_cbranch_vccnz .LBB0_1981
	v_mov_b32_e32 v197, v149
	v_lshl_add_u64 v[132:133], v[206:207], 0, v[196:197]
	global_store_dwordx4 v[132:133], v[128:131], off offset:256 nt

; #define LAS __attribute__((address_space(3)))
;     DI void operator()(const f32x4 (&acc)[2][2][4][2], const Unit& u, int wr, int wc, int fr, int fq, const Pre& pre) const {
;     ...
;         if (third == 2) {
;             LAS unsigned char* ws = scr + (wr * 4 + wc) * 1024; const int ln = fr + 16 * fq, dl = ln & 31, hf = ln >> 5;
;             LAS unsigned char* wsw = ws + fr * 64 + fq * 16; const LAS unsigned char* wsr = ws + hf * 256 + dl * 2;
; #pragma unroll
;             for (int ai = 0; ai < 2; ++ai)
; #pragma unroll
;                 for (int m = 0; m < 4; ++m) { const int row = row0 + ai * 128 + m * 16; const float r = rs[ai][m];
;                     const bool smp = row >= NTP; const int s = row - NTP; const int b = smp ? (s >> 6) : row / TP, key = smp ? 1024 + (s & 63) : row - b * TP, nkt = smp ? 34 : 129;
; #pragma unroll
;                     for (int bj = 0; bj < 2; ++bj) { const int cs = cb + bj * 128; const f32x4 v0 = acc[ai][bj][m][0] * r, v1 = acc[ai][bj][m][1] * r;
;                         if (row < NT) { const int h = cs >> 7, d = cs & 127;
;                             float* ov = out + (smp ? O_VS + (size_t)s * 1024 : O_VP + (size_t)row * 1024) + cs; *(f32x4*)ov = v0; *(f32x4*)(ov + 4) = v1;
;                             u32x4v o; o.x = pk2(v0[0], v0[1]); o.y = pk2(v0[2], v0[3]); o.z = pk2(v1[0], v1[1]); o.w = pk2(v1[2], v1[3]);
;                             *(LAS u32x4v*)wsw = o;
;                             asm volatile("s_waitcnt lgkmcnt(0)" ::: "memory");
;                             u32x4v t;
;                             t.x = (unsigned)*(const LAS unsigned short*)(wsr) | ((unsigned)*(const LAS unsigned short*)(wsr + 64) << 16);
;                             t.y = (unsigned)*(const LAS unsigned short*)(wsr + 128) | ((unsigned)*(const LAS unsigned short*)(wsr + 192) << 16);
;                             t.z = (unsigned)*(const LAS unsigned short*)(wsr + 512) | ((unsigned)*(const LAS unsigned short*)(wsr + 576) << 16);
;                             t.w = (unsigned)*(const LAS unsigned short*)(wsr + 640) | ((unsigned)*(const LAS unsigned short*)(wsr + 704) << 16);
;                             *(u32x4v*)((smp ? VTS : VTP) + vf_index(b * 8 + h, nkt, key - fr, d & ~31) + ln * 8) = t;
;                             asm volatile("s_waitcnt lgkmcnt(0)" ::: "memory"); } } }
.LBB0_1982:
	s_and_b64 vcc, exec, s[0:1]
	s_cbranch_vccz .LBB0_1839
	v_cmp_lt_i32_e32 vcc, s28, v180
	v_cmp_gt_i32_e64 s[0:1], s6, v180
	s_and_saveexec_b64 s[10:11], s[0:1]
	s_xor_b64 s[0:1], exec, s[10:11]
	v_mul_hi_i32 v128, v180, s18
	v_lshrrev_b32_e32 v129, 31, v128
	v_ashrrev_i32_e32 v128, 11, v128
	v_add_u32_e32 v129, v128, v129
	s_or_saveexec_b64 s[0:1], s[0:1]
	v_add_u32_e32 v148, 0xffff7f80, v180
	s_xor_b64 exec, exec, s[0:1]
	v_lshrrev_b32_e32 v129, 6, v148
	s_or_b64 exec, exec, s[0:1]
	v_or_b32_e32 v131, 0x80, v217
	v_cmp_gt_i32_e64 s[0:1], s4, v180
	v_lshlrev_b32_e32 v130, 2, v217
	v_lshlrev_b32_e32 v128, 1, v150
	v_lshrrev_b32_e32 v132, 7, v131
	s_and_saveexec_b64 s[10:11], s[0:1]
	s_cbranch_execz .LBB0_1989
	v_mad_u64_u32 v[134:135], s[0:1], v129, s19, v[180:181]
	v_cndmask_b32_e32 v131, v134, v208, vcc
	v_lshlrev_b64 v[136:137], 10, v[148:149]
	v_lshlrev_b64 v[138:139], 10, v[180:181]
	v_sub_u32_e32 v189, v131, v151
	v_lshl_add_u64 v[136:137], v[136:137], 0, s[40:41]
	v_lshl_add_u64 v[138:139], v[138:139], 0, s[42:43]
	v_readlane_b32 s76, v254, 12
	v_lshrrev_b32_e32 v131, 2, v189
	v_cndmask_b32_e32 v137, v139, v137, vcc
	v_cndmask_b32_e32 v136, v138, v136, vcc
	v_readlane_b32 s84, v254, 20
	v_readlane_b32 s85, v254, 21
	v_and_or_b32 v195, v131, 4, s70
	v_mov_b32_e32 v131, v149
	v_lshl_add_u64 v[136:137], v[136:137], 2, s[84:85]
	v_pk_mul_f32 v[126:127], v[126:127], v[184:185] op_sel:[0,1]
	v_pk_mul_f32 v[124:125], v[124:125], v[184:185] op_sel:[0,1]
	v_lshl_add_u64 v[136:137], v[136:137], 0, v[130:131]
	v_pk_mul_f32 v[122:123], v[122:123], v[184:185] op_sel:[0,1]
	v_pk_mul_f32 v[120:121], v[120:121], v[184:185] op_sel:[0,1]
	global_store_dwordx4 v[136:137], v[124:127], off nt
	global_store_dwordx4 v[136:137], v[120:123], off offset:16 nt
	v_readlane_b32 s77, v254, 13
	v_cvt_pk_bf16_f32 v124, v124, v125
	v_cvt_pk_bf16_f32 v125, v126, v127
	v_cvt_pk_bf16_f32 v126, v120, v121
	v_cvt_pk_bf16_f32 v127, v122, v123
	ds_write_b128 v215, v[124:127]
	s_waitcnt lgkmcnt(0)
	ds_read_u16 v120, v212
	ds_read_u16 v121, v212 offset:64
	ds_read_u16 v122, v212 offset:128
	ds_read_u16 v123, v212 offset:192
	ds_read_u16 v124, v212 offset:512
	ds_read_u16 v125, v212 offset:576
	ds_read_u16 v126, v212 offset:640
	ds_read_u16 v127, v212 offset:704
	v_readlane_b32 s78, v254, 14
	v_readlane_b32 s79, v254, 15
	v_readlane_b32 s80, v254, 16
	v_readlane_b32 s81, v254, 17
	v_readlane_b32 s82, v254, 18
	v_readlane_b32 s83, v254, 19
	v_readlane_b32 s76, v254, 0
	v_readlane_b32 s81, v254, 5
	v_readlane_b32 s83, v254, 7
	s_waitcnt lgkmcnt(0)
	v_lshl_or_b32 v120, v121, 16, v120
	v_lshl_or_b32 v121, v123, 16, v122
	v_lshl_or_b32 v122, v125, 16, v124
	v_readlane_b32 s80, v254, 4
	v_readlane_b32 s82, v254, 6
	v_mov_b32_e32 v124, s81
	v_mov_b32_e32 v125, s83
	v_ashrrev_i32_e32 v134, 5, v189
	v_lshlrev_b32_e32 v200, 3, v129
	s_lshr_b32 s0, s45, 7
	v_lshl_or_b32 v123, v127, 16, v126
	v_cndmask_b32_e32 v125, v124, v125, vcc
	v_mov_b32_e32 v124, s80
	v_mov_b32_e32 v126, s82
	v_cndmask_b32_e64 v133, v216, 34, vcc
	v_ashrrev_i32_e32 v135, 31, v134
	v_cndmask_b32_e32 v124, v124, v126, vcc
	v_or_b32_e32 v126, s0, v200
	v_mad_i64_i32 v[126:127], s[0:1], v133, v126, v[134:135]
	v_lshlrev_b64 v[126:127], 13, v[126:127]
	v_lshlrev_b32_e32 v148, 10, v195
	v_lshl_add_u64 v[126:127], v[124:125], 0, v[126:127]
	v_lshlrev_b32_e32 v129, 7, v189
	v_lshl_add_u64 v[126:127], v[126:127], 0, v[148:149]
	v_and_b32_e32 v138, 0x200, v129
	v_mov_b32_e32 v139, v149
	v_and_b32_e32 v191, 3, v189
	v_lshl_add_u64 v[126:127], v[126:127], 0, v[138:139]
	v_and_b32_e32 v196, 8, v189
	v_mov_b32_e32 v197, v149
	v_lshl_add_u64 v[126:127], v[126:127], 0, v[196:197]
	v_lshlrev_b32_e32 v198, 1, v191
	v_mov_b32_e32 v199, v149
	v_lshl_add_u64 v[126:127], v[126:127], 0, v[198:199]
	v_mov_b32_e32 v129, v149
	v_lshl_add_u64 v[126:127], v[126:127], 0, v[128:129]
	global_store_dwordx4 v[126:127], v[120:123], off nt
	v_pk_mul_f32 v[118:119], v[118:119], v[184:185] op_sel:[0,1]
	v_pk_mul_f32 v[116:117], v[116:117], v[184:185] op_sel:[0,1]
	s_waitcnt lgkmcnt(0)
	v_pk_mul_f32 v[114:115], v[114:115], v[184:185] op_sel:[0,1]
	v_pk_mul_f32 v[112:113], v[112:113], v[184:185] op_sel:[0,1]
	global_store_dwordx4 v[136:137], v[116:119], off offset:512 nt
	global_store_dwordx4 v[136:137], v[112:115], off offset:528 nt
	v_readlane_b32 s88, v254, 24
	v_cvt_pk_bf16_f32 v116, v116, v117
	v_cvt_pk_bf16_f32 v117, v118, v119
	v_cvt_pk_bf16_f32 v118, v112, v113
	v_cvt_pk_bf16_f32 v119, v114, v115
	ds_write_b128 v215, v[116:119]
	s_waitcnt lgkmcnt(0)
	ds_read_u16 v112, v212
	ds_read_u16 v113, v212 offset:64
	ds_read_u16 v114, v212 offset:128
	ds_read_u16 v115, v212 offset:192
	ds_read_u16 v116, v212 offset:512
	ds_read_u16 v117, v212 offset:576
	ds_read_u16 v118, v212 offset:640
	ds_read_u16 v119, v212 offset:704
	s_waitcnt lgkmcnt(6)
	v_lshl_or_b32 v112, v113, 16, v112
	s_waitcnt lgkmcnt(4)
	v_lshl_or_b32 v113, v115, 16, v114
	s_waitcnt lgkmcnt(2)
	v_lshl_or_b32 v114, v117, 16, v116
	v_or_b32_e32 v116, v200, v132
	v_mad_i64_i32 v[116:117], s[0:1], v133, v116, v[134:135]
	v_lshlrev_b64 v[116:117], 13, v[116:117]
	v_lshl_add_u64 v[116:117], v[124:125], 0, v[116:117]
	v_lshl_add_u64 v[116:117], v[116:117], 0, v[148:149]
	v_lshl_add_u64 v[116:117], v[116:117], 0, v[138:139]
	v_lshl_add_u64 v[116:117], v[116:117], 0, v[196:197]
	v_lshl_add_u64 v[116:117], v[116:117], 0, v[198:199]
	s_waitcnt lgkmcnt(0)
	v_lshl_or_b32 v115, v119, 16, v118
	v_lshl_add_u64 v[116:117], v[116:117], 0, v[128:129]
	global_store_dwordx4 v[116:117], v[112:115], off nt
	v_readlane_b32 s89, v254, 25
	s_waitcnt lgkmcnt(0)
	v_readlane_b32 s88, v255, 40
	v_readlane_b32 s89, v255, 41
	s_mov_b32 s84, s7
	v_readlane_b32 s86, v254, 22
	v_readlane_b32 s87, v254, 23
	v_readlane_b32 s90, v254, 26
	v_readlane_b32 s91, v254, 27
	v_readlane_b32 s77, v254, 1
	v_readlane_b32 s78, v254, 2
	v_readlane_b32 s79, v254, 3

; #define LAS __attribute__((address_space(3)))
;     DI void operator()(const f32x4 (&acc)[2][2][4][2], const Unit& u, int wr, int wc, int fr, int fq, const Pre& pre) const {
;     ...
;         if (third == 2) {
;             LAS unsigned char* ws = scr + (wr * 4 + wc) * 1024; const int ln = fr + 16 * fq, dl = ln & 31, hf = ln >> 5;
;             LAS unsigned char* wsw = ws + fr * 64 + fq * 16; const LAS unsigned char* wsr = ws + hf * 256 + dl * 2;
; #pragma unroll
;             for (int ai = 0; ai < 2; ++ai)
; #pragma unroll
;                 for (int m = 0; m < 4; ++m) { const int row = row0 + ai * 128 + m * 16; const float r = rs[ai][m];
;                     const bool smp = row >= NTP; const int s = row - NTP; const int b = smp ? (s >> 6) : row / TP, key = smp ? 1024 + (s & 63) : row - b * TP, nkt = smp ? 34 : 129;
; #pragma unroll
;                     for (int bj = 0; bj < 2; ++bj) { const int cs = cb + bj * 128; const f32x4 v0 = acc[ai][bj][m][0] * r, v1 = acc[ai][bj][m][1] * r;
;                         if (row < NT) { const int h = cs >> 7, d = cs & 127;
;                             float* ov = out + (smp ? O_VS + (size_t)s * 1024 : O_VP + (size_t)row * 1024) + cs; *(f32x4*)ov = v0; *(f32x4*)(ov + 4) = v1;
;                             u32x4v o; o.x = pk2(v0[0], v0[1]); o.y = pk2(v0[2], v0[3]); o.z = pk2(v1[0], v1[1]); o.w = pk2(v1[2], v1[3]);
;                             *(LAS u32x4v*)wsw = o;
;                             asm volatile("s_waitcnt lgkmcnt(0)" ::: "memory");
;                             u32x4v t;
;                             t.x = (unsigned)*(const LAS unsigned short*)(wsr) | ((unsigned)*(const LAS unsigned short*)(wsr + 64) << 16);
;                             t.y = (unsigned)*(const LAS unsigned short*)(wsr + 128) | ((unsigned)*(const LAS unsigned short*)(wsr + 192) << 16);
;                             t.z = (unsigned)*(const LAS unsigned short*)(wsr + 512) | ((unsigned)*(const LAS unsigned short*)(wsr + 576) << 16);
;                             t.w = (unsigned)*(const LAS unsigned short*)(wsr + 640) | ((unsigned)*(const LAS unsigned short*)(wsr + 704) << 16);
;                             *(u32x4v*)((smp ? VTS : VTP) + vf_index(b * 8 + h, nkt, key - fr, d & ~31) + ln * 8) = t;
;                             asm volatile("s_waitcnt lgkmcnt(0)" ::: "memory"); } } }
.LBB0_1992:
	v_mad_u64_u32 v[114:115], s[0:1], v112, s19, v[194:195]
	v_cndmask_b32_e32 v113, v114, v209, vcc
	v_sub_u32_e32 v118, v113, v151
	v_lshrrev_b32_e32 v113, 2, v118
	v_ashrrev_i32_e32 v195, 31, v194
	v_and_or_b32 v119, v113, 4, s70
	v_lshlrev_b32_e32 v123, 3, v112
	v_lshlrev_b64 v[112:113], 10, v[148:149]
	v_lshlrev_b64 v[116:117], 10, v[194:195]
	v_lshl_add_u64 v[112:113], v[112:113], 0, s[40:41]
	v_lshl_add_u64 v[116:117], v[116:117], 0, s[42:43]
	v_readlane_b32 s76, v254, 12
	v_cndmask_b32_e32 v113, v117, v113, vcc
	v_cndmask_b32_e32 v112, v116, v112, vcc
	v_readlane_b32 s84, v254, 20
	v_readlane_b32 s85, v254, 21
	v_mov_b32_e32 v131, v149
	v_pk_mul_f32 v[110:111], v[110:111], v[192:193] op_sel_hi:[1,0]
	v_lshl_add_u64 v[112:113], v[112:113], 2, s[84:85]
	v_pk_mul_f32 v[108:109], v[108:109], v[192:193] op_sel_hi:[1,0]
	v_lshl_add_u64 v[112:113], v[112:113], 0, v[130:131]
	v_pk_mul_f32 v[106:107], v[106:107], v[192:193] op_sel_hi:[1,0]
	v_pk_mul_f32 v[104:105], v[104:105], v[192:193] op_sel_hi:[1,0]
	global_store_dwordx4 v[112:113], v[108:111], off nt
	global_store_dwordx4 v[112:113], v[104:107], off offset:16 nt
	v_readlane_b32 s77, v254, 13
	v_cvt_pk_bf16_f32 v108, v108, v109
	v_cvt_pk_bf16_f32 v109, v110, v111
	v_cvt_pk_bf16_f32 v110, v104, v105
	v_cvt_pk_bf16_f32 v111, v106, v107
	ds_write_b128 v215, v[108:111]
	s_waitcnt lgkmcnt(0)
	ds_read_u16 v104, v212
	ds_read_u16 v105, v212 offset:64
	ds_read_u16 v106, v212 offset:128
	ds_read_u16 v107, v212 offset:192
	ds_read_u16 v108, v212 offset:512
	ds_read_u16 v109, v212 offset:576
	ds_read_u16 v110, v212 offset:640
	ds_read_u16 v111, v212 offset:704
	v_readlane_b32 s78, v254, 14
	v_readlane_b32 s79, v254, 15
	v_readlane_b32 s80, v254, 16
	v_readlane_b32 s81, v254, 17
	v_readlane_b32 s82, v254, 18
	v_readlane_b32 s83, v254, 19
	v_readlane_b32 s76, v254, 0
	v_readlane_b32 s81, v254, 5
	v_readlane_b32 s83, v254, 7
	s_waitcnt lgkmcnt(0)
	v_lshl_or_b32 v104, v105, 16, v104
	v_lshl_or_b32 v105, v107, 16, v106
	v_lshl_or_b32 v106, v109, 16, v108
	v_readlane_b32 s80, v254, 4
	v_readlane_b32 s82, v254, 6
	v_mov_b32_e32 v108, s81
	v_mov_b32_e32 v109, s83
	v_ashrrev_i32_e32 v114, 5, v118
	s_lshr_b32 s0, s45, 7
	v_lshl_or_b32 v107, v111, 16, v110
	v_cndmask_b32_e32 v109, v108, v109, vcc
	v_mov_b32_e32 v108, s80
	v_mov_b32_e32 v110, s82
	v_cndmask_b32_e64 v122, v216, 34, vcc
	v_ashrrev_i32_e32 v115, 31, v114
	v_cndmask_b32_e32 v108, v108, v110, vcc
	v_or_b32_e32 v110, s0, v123
	v_mad_i64_i32 v[110:111], s[0:1], v122, v110, v[114:115]
	v_lshlrev_b64 v[110:111], 13, v[110:111]
	v_lshlrev_b32_e32 v148, 10, v119
	v_lshl_add_u64 v[110:111], v[108:109], 0, v[110:111]
	v_lshlrev_b32_e32 v116, 7, v118
	v_lshl_add_u64 v[110:111], v[110:111], 0, v[148:149]
	v_and_b32_e32 v116, 0x200, v116
	v_mov_b32_e32 v117, v149
	v_and_b32_e32 v120, 3, v118
	v_lshl_add_u64 v[110:111], v[110:111], 0, v[116:117]
	v_and_b32_e32 v118, 8, v118
	v_mov_b32_e32 v119, v149
	v_lshl_add_u64 v[110:111], v[110:111], 0, v[118:119]
	v_lshlrev_b32_e32 v120, 1, v120
	v_mov_b32_e32 v121, v149
	v_lshl_add_u64 v[110:111], v[110:111], 0, v[120:121]
	v_mov_b32_e32 v129, v149
	v_lshl_add_u64 v[110:111], v[110:111], 0, v[128:129]
	global_store_dwordx4 v[110:111], v[104:107], off nt
	v_pk_mul_f32 v[102:103], v[102:103], v[192:193] op_sel_hi:[1,0]
	v_pk_mul_f32 v[100:101], v[100:101], v[192:193] op_sel_hi:[1,0]
	s_waitcnt lgkmcnt(0)
	v_pk_mul_f32 v[98:99], v[98:99], v[192:193] op_sel_hi:[1,0]
	v_pk_mul_f32 v[96:97], v[96:97], v[192:193] op_sel_hi:[1,0]
	global_store_dwordx4 v[112:113], v[100:103], off offset:512 nt
	global_store_dwordx4 v[112:113], v[96:99], off offset:528 nt
	v_readlane_b32 s88, v254, 24
	v_cvt_pk_bf16_f32 v100, v100, v101
	v_cvt_pk_bf16_f32 v101, v102, v103
	v_cvt_pk_bf16_f32 v102, v96, v97
	v_cvt_pk_bf16_f32 v103, v98, v99
	ds_write_b128 v215, v[100:103]
	s_waitcnt lgkmcnt(0)
	ds_read_u16 v96, v212
	ds_read_u16 v97, v212 offset:64
	ds_read_u16 v98, v212 offset:128
	ds_read_u16 v99, v212 offset:192
	ds_read_u16 v100, v212 offset:512
	ds_read_u16 v101, v212 offset:576
	ds_read_u16 v102, v212 offset:640
	ds_read_u16 v103, v212 offset:704
	s_waitcnt lgkmcnt(6)
	v_lshl_or_b32 v96, v97, 16, v96
	s_waitcnt lgkmcnt(4)
	v_lshl_or_b32 v97, v99, 16, v98
	s_waitcnt lgkmcnt(2)
	v_lshl_or_b32 v98, v101, 16, v100
	v_or_b32_e32 v100, v123, v132
	v_mad_i64_i32 v[100:101], s[0:1], v122, v100, v[114:115]
	v_lshlrev_b64 v[100:101], 13, v[100:101]
	v_lshl_add_u64 v[100:101], v[108:109], 0, v[100:101]
	v_lshl_add_u64 v[100:101], v[100:101], 0, v[148:149]
	v_lshl_add_u64 v[100:101], v[100:101], 0, v[116:117]
	v_lshl_add_u64 v[100:101], v[100:101], 0, v[118:119]
	v_lshl_add_u64 v[100:101], v[100:101], 0, v[120:121]
	s_waitcnt lgkmcnt(0)
	v_lshl_or_b32 v99, v103, 16, v102
	v_lshl_add_u64 v[100:101], v[100:101], 0, v[128:129]
	global_store_dwordx4 v[100:101], v[96:99], off nt
	v_readlane_b32 s89, v254, 25
	s_waitcnt lgkmcnt(0)
	v_readlane_b32 s88, v255, 40
	v_readlane_b32 s89, v255, 41
	s_mov_b32 s84, s7
	v_readlane_b32 s86, v254, 22
	v_readlane_b32 s87, v254, 23
	v_readlane_b32 s90, v254, 26
	v_readlane_b32 s91, v254, 27
	v_readlane_b32 s77, v254, 1
	v_readlane_b32 s78, v254, 2
	v_readlane_b32 s79, v254, 3

; #define LAS __attribute__((address_space(3)))
;     DI void operator()(const f32x4 (&acc)[2][2][4][2], const Unit& u, int wr, int wc, int fr, int fq, const Pre& pre) const {
;     ...
;         if (third == 2) {
;             LAS unsigned char* ws = scr + (wr * 4 + wc) * 1024; const int ln = fr + 16 * fq, dl = ln & 31, hf = ln >> 5;
;             LAS unsigned char* wsw = ws + fr * 64 + fq * 16; const LAS unsigned char* wsr = ws + hf * 256 + dl * 2;
; #pragma unroll
;             for (int ai = 0; ai < 2; ++ai)
; #pragma unroll
;                 for (int m = 0; m < 4; ++m) { const int row = row0 + ai * 128 + m * 16; const float r = rs[ai][m];
;                     const bool smp = row >= NTP; const int s = row - NTP; const int b = smp ? (s >> 6) : row / TP, key = smp ? 1024 + (s & 63) : row - b * TP, nkt = smp ? 34 : 129;
; #pragma unroll
;                     for (int bj = 0; bj < 2; ++bj) { const int cs = cb + bj * 128; const f32x4 v0 = acc[ai][bj][m][0] * r, v1 = acc[ai][bj][m][1] * r;
;                         if (row < NT) { const int h = cs >> 7, d = cs & 127;
;                             float* ov = out + (smp ? O_VS + (size_t)s * 1024 : O_VP + (size_t)row * 1024) + cs; *(f32x4*)ov = v0; *(f32x4*)(ov + 4) = v1;
;                             u32x4v o; o.x = pk2(v0[0], v0[1]); o.y = pk2(v0[2], v0[3]); o.z = pk2(v1[0], v1[1]); o.w = pk2(v1[2], v1[3]);
;                             *(LAS u32x4v*)wsw = o;
;                             asm volatile("s_waitcnt lgkmcnt(0)" ::: "memory");
;                             u32x4v t;
;                             t.x = (unsigned)*(const LAS unsigned short*)(wsr) | ((unsigned)*(const LAS unsigned short*)(wsr + 64) << 16);
;                             t.y = (unsigned)*(const LAS unsigned short*)(wsr + 128) | ((unsigned)*(const LAS unsigned short*)(wsr + 192) << 16);
;                             t.z = (unsigned)*(const LAS unsigned short*)(wsr + 512) | ((unsigned)*(const LAS unsigned short*)(wsr + 576) << 16);
;                             t.w = (unsigned)*(const LAS unsigned short*)(wsr + 640) | ((unsigned)*(const LAS unsigned short*)(wsr + 704) << 16);
;                             *(u32x4v*)((smp ? VTS : VTP) + vf_index(b * 8 + h, nkt, key - fr, d & ~31) + ln * 8) = t;
;                             asm volatile("s_waitcnt lgkmcnt(0)" ::: "memory"); } } }
.LBB0_1996:
	v_mad_u64_u32 v[98:99], s[0:1], v96, s19, v[190:191]
	v_cndmask_b32_e32 v97, v98, v210, vcc
	v_sub_u32_e32 v102, v97, v151
	v_lshrrev_b32_e32 v97, 2, v102
	v_ashrrev_i32_e32 v191, 31, v190
	v_and_or_b32 v103, v97, 4, s70
	v_lshlrev_b32_e32 v107, 3, v96
	v_lshlrev_b64 v[96:97], 10, v[148:149]
	v_lshlrev_b64 v[100:101], 10, v[190:191]
	v_lshl_add_u64 v[96:97], v[96:97], 0, s[40:41]
	v_lshl_add_u64 v[100:101], v[100:101], 0, s[42:43]
	v_readlane_b32 s76, v254, 12
	v_cndmask_b32_e32 v97, v101, v97, vcc
	v_cndmask_b32_e32 v96, v100, v96, vcc
	v_readlane_b32 s84, v254, 20
	v_readlane_b32 s85, v254, 21
	v_mov_b32_e32 v131, v149
	v_pk_mul_f32 v[94:95], v[94:95], v[192:193] op_sel:[0,1]
	v_lshl_add_u64 v[96:97], v[96:97], 2, s[84:85]
	v_pk_mul_f32 v[92:93], v[92:93], v[192:193] op_sel:[0,1]
	v_lshl_add_u64 v[96:97], v[96:97], 0, v[130:131]
	v_pk_mul_f32 v[90:91], v[90:91], v[192:193] op_sel:[0,1]
	v_pk_mul_f32 v[88:89], v[88:89], v[192:193] op_sel:[0,1]
	global_store_dwordx4 v[96:97], v[92:95], off nt
	global_store_dwordx4 v[96:97], v[88:91], off offset:16 nt
	v_readlane_b32 s77, v254, 13
	v_cvt_pk_bf16_f32 v92, v92, v93
	v_cvt_pk_bf16_f32 v93, v94, v95
	v_cvt_pk_bf16_f32 v94, v88, v89
	v_cvt_pk_bf16_f32 v95, v90, v91
	ds_write_b128 v215, v[92:95]
	s_waitcnt lgkmcnt(0)
	ds_read_u16 v88, v212
	ds_read_u16 v89, v212 offset:64
	ds_read_u16 v90, v212 offset:128
	ds_read_u16 v91, v212 offset:192
	ds_read_u16 v92, v212 offset:512
	ds_read_u16 v93, v212 offset:576
	ds_read_u16 v94, v212 offset:640
	ds_read_u16 v95, v212 offset:704
	v_readlane_b32 s78, v254, 14
	v_readlane_b32 s79, v254, 15
	v_readlane_b32 s80, v254, 16
	v_readlane_b32 s81, v254, 17
	v_readlane_b32 s82, v254, 18
	v_readlane_b32 s83, v254, 19
	v_readlane_b32 s76, v254, 0
	v_readlane_b32 s81, v254, 5
	v_readlane_b32 s83, v254, 7
	s_waitcnt lgkmcnt(0)
	v_lshl_or_b32 v88, v89, 16, v88
	v_lshl_or_b32 v89, v91, 16, v90
	v_lshl_or_b32 v90, v93, 16, v92
	v_readlane_b32 s80, v254, 4
	v_readlane_b32 s82, v254, 6
	v_mov_b32_e32 v92, s81
	v_mov_b32_e32 v93, s83
	v_ashrrev_i32_e32 v98, 5, v102
	s_lshr_b32 s0, s45, 7
	v_lshl_or_b32 v91, v95, 16, v94
	v_cndmask_b32_e32 v93, v92, v93, vcc
	v_mov_b32_e32 v92, s80
	v_mov_b32_e32 v94, s82
	v_cndmask_b32_e64 v106, v216, 34, vcc
	v_ashrrev_i32_e32 v99, 31, v98
	v_cndmask_b32_e32 v92, v92, v94, vcc
	v_or_b32_e32 v94, s0, v107
	v_mad_i64_i32 v[94:95], s[0:1], v106, v94, v[98:99]
	v_lshlrev_b64 v[94:95], 13, v[94:95]
	v_lshlrev_b32_e32 v148, 10, v103
	v_lshl_add_u64 v[94:95], v[92:93], 0, v[94:95]
	v_lshlrev_b32_e32 v100, 7, v102
	v_lshl_add_u64 v[94:95], v[94:95], 0, v[148:149]
	v_and_b32_e32 v100, 0x200, v100
	v_mov_b32_e32 v101, v149
	v_and_b32_e32 v104, 3, v102
	v_lshl_add_u64 v[94:95], v[94:95], 0, v[100:101]
	v_and_b32_e32 v102, 8, v102
	v_mov_b32_e32 v103, v149
	v_lshl_add_u64 v[94:95], v[94:95], 0, v[102:103]
	v_lshlrev_b32_e32 v104, 1, v104
	v_mov_b32_e32 v105, v149
	v_lshl_add_u64 v[94:95], v[94:95], 0, v[104:105]
	v_mov_b32_e32 v129, v149
	v_lshl_add_u64 v[94:95], v[94:95], 0, v[128:129]
	global_store_dwordx4 v[94:95], v[88:91], off nt
	v_pk_mul_f32 v[86:87], v[86:87], v[192:193] op_sel:[0,1]
	v_pk_mul_f32 v[84:85], v[84:85], v[192:193] op_sel:[0,1]
	s_waitcnt lgkmcnt(0)
	v_pk_mul_f32 v[82:83], v[82:83], v[192:193] op_sel:[0,1]
	v_pk_mul_f32 v[80:81], v[80:81], v[192:193] op_sel:[0,1]
	global_store_dwordx4 v[96:97], v[84:87], off offset:512 nt
	global_store_dwordx4 v[96:97], v[80:83], off offset:528 nt
	v_readlane_b32 s88, v254, 24
	v_cvt_pk_bf16_f32 v84, v84, v85
	v_cvt_pk_bf16_f32 v85, v86, v87
	v_cvt_pk_bf16_f32 v86, v80, v81
	v_cvt_pk_bf16_f32 v87, v82, v83
	ds_write_b128 v215, v[84:87]
	s_waitcnt lgkmcnt(0)
	ds_read_u16 v80, v212
	ds_read_u16 v81, v212 offset:64
	ds_read_u16 v82, v212 offset:128
	ds_read_u16 v83, v212 offset:192
	ds_read_u16 v84, v212 offset:512
	ds_read_u16 v85, v212 offset:576
	ds_read_u16 v86, v212 offset:640
	ds_read_u16 v87, v212 offset:704
	s_waitcnt lgkmcnt(6)
	v_lshl_or_b32 v80, v81, 16, v80
	s_waitcnt lgkmcnt(4)
	v_lshl_or_b32 v81, v83, 16, v82
	s_waitcnt lgkmcnt(2)
	v_lshl_or_b32 v82, v85, 16, v84
	v_or_b32_e32 v84, v107, v132
	v_mad_i64_i32 v[84:85], s[0:1], v106, v84, v[98:99]
	v_lshlrev_b64 v[84:85], 13, v[84:85]
	v_lshl_add_u64 v[84:85], v[92:93], 0, v[84:85]
	v_lshl_add_u64 v[84:85], v[84:85], 0, v[148:149]
	v_lshl_add_u64 v[84:85], v[84:85], 0, v[100:101]
	v_lshl_add_u64 v[84:85], v[84:85], 0, v[102:103]
	v_lshl_add_u64 v[84:85], v[84:85], 0, v[104:105]
	s_waitcnt lgkmcnt(0)
	v_lshl_or_b32 v83, v87, 16, v86
	v_lshl_add_u64 v[84:85], v[84:85], 0, v[128:129]
	global_store_dwordx4 v[84:85], v[80:83], off nt
	v_readlane_b32 s89, v254, 25
	s_waitcnt lgkmcnt(0)
	v_readlane_b32 s88, v255, 40
	v_readlane_b32 s89, v255, 41
	s_mov_b32 s84, s7
	v_readlane_b32 s86, v254, 22
	v_readlane_b32 s87, v254, 23
	v_readlane_b32 s90, v254, 26
	v_readlane_b32 s91, v254, 27
	v_readlane_b32 s77, v254, 1
	v_readlane_b32 s78, v254, 2
	v_readlane_b32 s79, v254, 3

; #define LAS __attribute__((address_space(3)))
;     DI void operator()(const f32x4 (&acc)[2][2][4][2], const Unit& u, int wr, int wc, int fr, int fq, const Pre& pre) const {
;     ...
;         if (third == 2) {
;             LAS unsigned char* ws = scr + (wr * 4 + wc) * 1024; const int ln = fr + 16 * fq, dl = ln & 31, hf = ln >> 5;
;             LAS unsigned char* wsw = ws + fr * 64 + fq * 16; const LAS unsigned char* wsr = ws + hf * 256 + dl * 2;
; #pragma unroll
;             for (int ai = 0; ai < 2; ++ai)
; #pragma unroll
;                 for (int m = 0; m < 4; ++m) { const int row = row0 + ai * 128 + m * 16; const float r = rs[ai][m];
;                     const bool smp = row >= NTP; const int s = row - NTP; const int b = smp ? (s >> 6) : row / TP, key = smp ? 1024 + (s & 63) : row - b * TP, nkt = smp ? 34 : 129;
; #pragma unroll
;                     for (int bj = 0; bj < 2; ++bj) { const int cs = cb + bj * 128; const f32x4 v0 = acc[ai][bj][m][0] * r, v1 = acc[ai][bj][m][1] * r;
;                         if (row < NT) { const int h = cs >> 7, d = cs & 127;
;                             float* ov = out + (smp ? O_VS + (size_t)s * 1024 : O_VP + (size_t)row * 1024) + cs; *(f32x4*)ov = v0; *(f32x4*)(ov + 4) = v1;
;                             u32x4v o; o.x = pk2(v0[0], v0[1]); o.y = pk2(v0[2], v0[3]); o.z = pk2(v1[0], v1[1]); o.w = pk2(v1[2], v1[3]);
;                             *(LAS u32x4v*)wsw = o;
;                             asm volatile("s_waitcnt lgkmcnt(0)" ::: "memory");
;                             u32x4v t;
;                             t.x = (unsigned)*(const LAS unsigned short*)(wsr) | ((unsigned)*(const LAS unsigned short*)(wsr + 64) << 16);
;                             t.y = (unsigned)*(const LAS unsigned short*)(wsr + 128) | ((unsigned)*(const LAS unsigned short*)(wsr + 192) << 16);
;                             t.z = (unsigned)*(const LAS unsigned short*)(wsr + 512) | ((unsigned)*(const LAS unsigned short*)(wsr + 576) << 16);
;                             t.w = (unsigned)*(const LAS unsigned short*)(wsr + 640) | ((unsigned)*(const LAS unsigned short*)(wsr + 704) << 16);
;                             *(u32x4v*)((smp ? VTS : VTP) + vf_index(b * 8 + h, nkt, key - fr, d & ~31) + ln * 8) = t;
;                             asm volatile("s_waitcnt lgkmcnt(0)" ::: "memory"); } } }
.LBB0_2000:
	v_mad_u64_u32 v[82:83], s[0:1], v80, s19, v[188:189]
	v_cndmask_b32_e32 v81, v82, v211, vcc
	v_sub_u32_e32 v86, v81, v151
	v_lshrrev_b32_e32 v81, 2, v86
	v_ashrrev_i32_e32 v189, 31, v188
	v_and_or_b32 v87, v81, 4, s70
	v_lshlrev_b32_e32 v91, 3, v80
	v_lshlrev_b64 v[80:81], 10, v[148:149]
	v_lshlrev_b64 v[84:85], 10, v[188:189]
	v_lshl_add_u64 v[80:81], v[80:81], 0, s[40:41]
	v_lshl_add_u64 v[84:85], v[84:85], 0, s[42:43]
	v_readlane_b32 s76, v254, 12
	v_cndmask_b32_e32 v81, v85, v81, vcc
	v_cndmask_b32_e32 v80, v84, v80, vcc
	v_readlane_b32 s84, v254, 20
	v_readlane_b32 s85, v254, 21
	v_mov_b32_e32 v131, v149
	v_pk_mul_f32 v[78:79], v[78:79], v[186:187] op_sel_hi:[1,0]
	v_lshl_add_u64 v[80:81], v[80:81], 2, s[84:85]
	v_pk_mul_f32 v[76:77], v[76:77], v[186:187] op_sel_hi:[1,0]
	v_lshl_add_u64 v[80:81], v[80:81], 0, v[130:131]
	v_pk_mul_f32 v[74:75], v[74:75], v[186:187] op_sel_hi:[1,0]
	v_pk_mul_f32 v[72:73], v[72:73], v[186:187] op_sel_hi:[1,0]
	global_store_dwordx4 v[80:81], v[76:79], off nt
	global_store_dwordx4 v[80:81], v[72:75], off offset:16 nt
	v_readlane_b32 s77, v254, 13
	v_cvt_pk_bf16_f32 v76, v76, v77
	v_cvt_pk_bf16_f32 v77, v78, v79
	v_cvt_pk_bf16_f32 v78, v72, v73
	v_cvt_pk_bf16_f32 v79, v74, v75
	ds_write_b128 v215, v[76:79]
	s_waitcnt lgkmcnt(0)
	ds_read_u16 v72, v212
	ds_read_u16 v73, v212 offset:64
	ds_read_u16 v74, v212 offset:128
	ds_read_u16 v75, v212 offset:192
	ds_read_u16 v76, v212 offset:512
	ds_read_u16 v77, v212 offset:576
	ds_read_u16 v78, v212 offset:640
	ds_read_u16 v79, v212 offset:704
	v_readlane_b32 s78, v254, 14
	v_readlane_b32 s79, v254, 15
	v_readlane_b32 s80, v254, 16
	v_readlane_b32 s81, v254, 17
	v_readlane_b32 s82, v254, 18
	v_readlane_b32 s83, v254, 19
	v_readlane_b32 s76, v254, 0
	v_readlane_b32 s81, v254, 5
	v_readlane_b32 s83, v254, 7
	s_waitcnt lgkmcnt(0)
	v_lshl_or_b32 v72, v73, 16, v72
	v_lshl_or_b32 v73, v75, 16, v74
	v_lshl_or_b32 v74, v77, 16, v76
	v_readlane_b32 s80, v254, 4
	v_readlane_b32 s82, v254, 6
	v_mov_b32_e32 v76, s81
	v_mov_b32_e32 v77, s83
	v_ashrrev_i32_e32 v82, 5, v86
	s_lshr_b32 s0, s45, 7
	v_lshl_or_b32 v75, v79, 16, v78
	v_cndmask_b32_e32 v77, v76, v77, vcc
	v_mov_b32_e32 v76, s80
	v_mov_b32_e32 v78, s82
	v_cndmask_b32_e64 v90, v216, 34, vcc
	v_ashrrev_i32_e32 v83, 31, v82
	v_cndmask_b32_e32 v76, v76, v78, vcc
	v_or_b32_e32 v78, s0, v91
	v_mad_i64_i32 v[78:79], s[0:1], v90, v78, v[82:83]
	v_lshlrev_b64 v[78:79], 13, v[78:79]
	v_lshlrev_b32_e32 v148, 10, v87
	v_lshl_add_u64 v[78:79], v[76:77], 0, v[78:79]
	v_lshlrev_b32_e32 v84, 7, v86
	v_lshl_add_u64 v[78:79], v[78:79], 0, v[148:149]
	v_and_b32_e32 v84, 0x200, v84
	v_mov_b32_e32 v85, v149
	v_and_b32_e32 v88, 3, v86
	v_lshl_add_u64 v[78:79], v[78:79], 0, v[84:85]
	v_and_b32_e32 v86, 8, v86
	v_mov_b32_e32 v87, v149
	v_lshl_add_u64 v[78:79], v[78:79], 0, v[86:87]
	v_lshlrev_b32_e32 v88, 1, v88
	v_mov_b32_e32 v89, v149
	v_lshl_add_u64 v[78:79], v[78:79], 0, v[88:89]
	v_mov_b32_e32 v129, v149
	v_lshl_add_u64 v[78:79], v[78:79], 0, v[128:129]
	global_store_dwordx4 v[78:79], v[72:75], off nt
	v_pk_mul_f32 v[70:71], v[70:71], v[186:187] op_sel_hi:[1,0]
	v_pk_mul_f32 v[68:69], v[68:69], v[186:187] op_sel_hi:[1,0]
	s_waitcnt lgkmcnt(0)
	v_pk_mul_f32 v[66:67], v[66:67], v[186:187] op_sel_hi:[1,0]
	v_pk_mul_f32 v[64:65], v[64:65], v[186:187] op_sel_hi:[1,0]
	global_store_dwordx4 v[80:81], v[68:71], off offset:512 nt
	global_store_dwordx4 v[80:81], v[64:67], off offset:528 nt
	v_readlane_b32 s88, v254, 24
	v_cvt_pk_bf16_f32 v68, v68, v69
	v_cvt_pk_bf16_f32 v69, v70, v71
	v_cvt_pk_bf16_f32 v70, v64, v65
	v_cvt_pk_bf16_f32 v71, v66, v67
	ds_write_b128 v215, v[68:71]
	s_waitcnt lgkmcnt(0)
	ds_read_u16 v64, v212
	ds_read_u16 v65, v212 offset:64
	ds_read_u16 v66, v212 offset:128
	ds_read_u16 v67, v212 offset:192
	ds_read_u16 v68, v212 offset:512
	ds_read_u16 v69, v212 offset:576
	ds_read_u16 v70, v212 offset:640
	ds_read_u16 v71, v212 offset:704
	s_waitcnt lgkmcnt(6)
	v_lshl_or_b32 v64, v65, 16, v64
	s_waitcnt lgkmcnt(4)
	v_lshl_or_b32 v65, v67, 16, v66
	s_waitcnt lgkmcnt(2)
	v_lshl_or_b32 v66, v69, 16, v68
	v_or_b32_e32 v68, v91, v132
	v_mad_i64_i32 v[68:69], s[0:1], v90, v68, v[82:83]
	v_lshlrev_b64 v[68:69], 13, v[68:69]
	v_lshl_add_u64 v[68:69], v[76:77], 0, v[68:69]
	v_lshl_add_u64 v[68:69], v[68:69], 0, v[148:149]
	v_lshl_add_u64 v[68:69], v[68:69], 0, v[84:85]
	v_lshl_add_u64 v[68:69], v[68:69], 0, v[86:87]
	v_lshl_add_u64 v[68:69], v[68:69], 0, v[88:89]
	s_waitcnt lgkmcnt(0)
	v_lshl_or_b32 v67, v71, 16, v70
	v_lshl_add_u64 v[68:69], v[68:69], 0, v[128:129]
	global_store_dwordx4 v[68:69], v[64:67], off nt
	v_readlane_b32 s89, v254, 25
	s_waitcnt lgkmcnt(0)
	v_readlane_b32 s88, v255, 40
	v_readlane_b32 s89, v255, 41
	s_mov_b32 s84, s7
	v_readlane_b32 s86, v254, 22
	v_readlane_b32 s87, v254, 23
	v_readlane_b32 s90, v254, 26
	v_readlane_b32 s91, v254, 27
	v_readlane_b32 s77, v254, 1
	v_readlane_b32 s78, v254, 2
	v_readlane_b32 s79, v254, 3
; #define LAS __attribute__((address_space(3)))
;     DI void operator()(const f32x4 (&acc)[2][2][4][2], const Unit& u, int wr, int wc, int fr, int fq, const Pre& pre) const {
;     ...
;         if (third == 2) {
;             LAS unsigned char* ws = scr + (wr * 4 + wc) * 1024; const int ln = fr + 16 * fq, dl = ln & 31, hf = ln >> 5;
;             LAS unsigned char* wsw = ws + fr * 64 + fq * 16; const LAS unsigned char* wsr = ws + hf * 256 + dl * 2;
; #pragma unroll
;             for (int ai = 0; ai < 2; ++ai)
; #pragma unroll
;                 for (int m = 0; m < 4; ++m) { const int row = row0 + ai * 128 + m * 16; const float r = rs[ai][m];
;                     const bool smp = row >= NTP; const int s = row - NTP; const int b = smp ? (s >> 6) : row / TP, key = smp ? 1024 + (s & 63) : row - b * TP, nkt = smp ? 34 : 129;
; #pragma unroll
;                     for (int bj = 0; bj < 2; ++bj) { const int cs = cb + bj * 128; const f32x4 v0 = acc[ai][bj][m][0] * r, v1 = acc[ai][bj][m][1] * r;
;                         if (row < NT) { const int h = cs >> 7, d = cs & 127;
;                             float* ov = out + (smp ? O_VS + (size_t)s * 1024 : O_VP + (size_t)row * 1024) + cs; *(f32x4*)ov = v0; *(f32x4*)(ov + 4) = v1;
;                             u32x4v o; o.x = pk2(v0[0], v0[1]); o.y = pk2(v0[2], v0[3]); o.z = pk2(v1[0], v1[1]); o.w = pk2(v1[2], v1[3]);
;                             *(LAS u32x4v*)wsw = o;
;                             asm volatile("s_waitcnt lgkmcnt(0)" ::: "memory");
;                             u32x4v t;
;                             t.x = (unsigned)*(const LAS unsigned short*)(wsr) | ((unsigned)*(const LAS unsigned short*)(wsr + 64) << 16);
;                             t.y = (unsigned)*(const LAS unsigned short*)(wsr + 128) | ((unsigned)*(const LAS unsigned short*)(wsr + 192) << 16);
;                             t.z = (unsigned)*(const LAS unsigned short*)(wsr + 512) | ((unsigned)*(const LAS unsigned short*)(wsr + 576) << 16);
;                             t.w = (unsigned)*(const LAS unsigned short*)(wsr + 640) | ((unsigned)*(const LAS unsigned short*)(wsr + 704) << 16);
;                             *(u32x4v*)((smp ? VTS : VTP) + vf_index(b * 8 + h, nkt, key - fr, d & ~31) + ln * 8) = t;
;                             asm volatile("s_waitcnt lgkmcnt(0)" ::: "memory"); } } }
.LBB0_2001:
	s_or_b64 exec, exec, s[10:11]
	s_movk_i32 s0, 0x7fff
	v_cmp_lt_i32_e32 vcc, s0, v180
	s_mov_b32 s0, 0x8000
	v_add_u32_e32 v64, 0x80, v180
	v_cmp_gt_i32_e64 s[0:1], s0, v180
	s_and_saveexec_b64 s[10:11], s[0:1]
	s_xor_b64 s[0:1], exec, s[10:11]
	v_mul_hi_i32 v65, v64, s18
	v_lshrrev_b32_e32 v66, 31, v65
	v_ashrrev_i32_e32 v65, 11, v65
	v_add_u32_e32 v65, v65, v66
	s_or_saveexec_b64 s[0:1], s[0:1]
	v_add_u32_e32 v148, 0xffff8000, v180
	s_xor_b64 exec, exec, s[0:1]
	v_lshrrev_b32_e32 v65, 6, v148
	s_or_b64 exec, exec, s[0:1]
	s_mov_b32 s0, 0x8200
	v_cmp_gt_i32_e64 s[0:1], s0, v180
	s_and_saveexec_b64 s[10:11], s[0:1]
	s_cbranch_execz .LBB0_2007
	v_mad_u64_u32 v[66:67], s[0:1], v65, s19, v[64:65]
	v_lshlrev_b32_e32 v75, 3, v65
	v_ashrrev_i32_e32 v65, 31, v64
	v_lshlrev_b64 v[68:69], 10, v[148:149]
	v_lshlrev_b64 v[64:65], 10, v[64:65]
	v_lshl_add_u64 v[68:69], v[68:69], 0, s[40:41]
	v_lshl_add_u64 v[64:65], v[64:65], 0, s[42:43]
	v_readlane_b32 s76, v254, 12
	v_cndmask_b32_e32 v65, v65, v69, vcc
	v_cndmask_b32_e32 v64, v64, v68, vcc
	v_readlane_b32 s84, v254, 20
	v_readlane_b32 s85, v254, 21
	v_mov_b32_e32 v131, v149
	v_pk_mul_f32 v[62:63], v[62:63], v[186:187] op_sel:[0,1]
	v_lshl_add_u64 v[64:65], v[64:65], 2, s[84:85]
	v_pk_mul_f32 v[60:61], v[60:61], v[186:187] op_sel:[0,1]
	v_lshl_add_u64 v[64:65], v[64:65], 0, v[130:131]
	v_pk_mul_f32 v[58:59], v[58:59], v[186:187] op_sel:[0,1]
	v_pk_mul_f32 v[56:57], v[56:57], v[186:187] op_sel:[0,1]
	global_store_dwordx4 v[64:65], v[60:63], off nt
	global_store_dwordx4 v[64:65], v[56:59], off offset:16 nt
	v_readlane_b32 s77, v254, 13
	v_cvt_pk_bf16_f32 v60, v60, v61
	v_cvt_pk_bf16_f32 v61, v62, v63
	v_cvt_pk_bf16_f32 v62, v56, v57
	v_cvt_pk_bf16_f32 v63, v58, v59
	ds_write_b128 v215, v[60:63]
	s_waitcnt lgkmcnt(0)
	ds_read_u16 v56, v212
	ds_read_u16 v57, v212 offset:64
	ds_read_u16 v58, v212 offset:128
	ds_read_u16 v59, v212 offset:192
	ds_read_u16 v60, v212 offset:512
	ds_read_u16 v61, v212 offset:576
	ds_read_u16 v62, v212 offset:640
	ds_read_u16 v63, v212 offset:704
	v_readlane_b32 s78, v254, 14
	v_readlane_b32 s79, v254, 15
	v_readlane_b32 s80, v254, 16
	v_readlane_b32 s81, v254, 17
	v_readlane_b32 s82, v254, 18
	v_readlane_b32 s83, v254, 19
	v_cndmask_b32_e32 v66, v66, v208, vcc
	v_readlane_b32 s76, v254, 0
	v_sub_u32_e32 v70, v66, v151
	v_readlane_b32 s81, v254, 5
	v_readlane_b32 s83, v254, 7
	v_lshrrev_b32_e32 v66, 2, v70
	s_waitcnt lgkmcnt(0)
	v_lshl_or_b32 v56, v57, 16, v56
	v_lshl_or_b32 v57, v59, 16, v58
	v_lshl_or_b32 v58, v61, 16, v60
	v_readlane_b32 s80, v254, 4
	v_readlane_b32 s82, v254, 6
	v_mov_b32_e32 v60, s81
	v_mov_b32_e32 v61, s83
	v_and_or_b32 v71, v66, 4, s70
	v_ashrrev_i32_e32 v66, 5, v70
	s_lshr_b32 s0, s45, 7
	v_lshl_or_b32 v59, v63, 16, v62
	v_cndmask_b32_e32 v61, v60, v61, vcc
	v_mov_b32_e32 v60, s80
	v_mov_b32_e32 v62, s82
	v_cndmask_b32_e64 v74, v216, 34, vcc
	v_ashrrev_i32_e32 v67, 31, v66
	v_cndmask_b32_e32 v60, v60, v62, vcc
	v_or_b32_e32 v62, s0, v75
	v_mad_i64_i32 v[62:63], s[0:1], v74, v62, v[66:67]
	v_lshlrev_b64 v[62:63], 13, v[62:63]
	v_lshlrev_b32_e32 v148, 10, v71
	v_lshl_add_u64 v[62:63], v[60:61], 0, v[62:63]
	v_lshlrev_b32_e32 v68, 7, v70
	v_lshl_add_u64 v[62:63], v[62:63], 0, v[148:149]
	v_and_b32_e32 v68, 0x200, v68
	v_mov_b32_e32 v69, v149
	v_and_b32_e32 v72, 3, v70
	v_lshl_add_u64 v[62:63], v[62:63], 0, v[68:69]
	v_and_b32_e32 v70, 8, v70
	v_mov_b32_e32 v71, v149
	v_lshl_add_u64 v[62:63], v[62:63], 0, v[70:71]
	v_lshlrev_b32_e32 v72, 1, v72
	v_mov_b32_e32 v73, v149
	v_lshl_add_u64 v[62:63], v[62:63], 0, v[72:73]
	v_mov_b32_e32 v129, v149
	v_lshl_add_u64 v[62:63], v[62:63], 0, v[128:129]
	global_store_dwordx4 v[62:63], v[56:59], off nt
	v_pk_mul_f32 v[54:55], v[54:55], v[186:187] op_sel:[0,1]
	v_pk_mul_f32 v[52:53], v[52:53], v[186:187] op_sel:[0,1]
	s_waitcnt lgkmcnt(0)
	v_pk_mul_f32 v[50:51], v[50:51], v[186:187] op_sel:[0,1]
	v_pk_mul_f32 v[48:49], v[48:49], v[186:187] op_sel:[0,1]
	global_store_dwordx4 v[64:65], v[52:55], off offset:512 nt
	global_store_dwordx4 v[64:65], v[48:51], off offset:528 nt
	v_readlane_b32 s88, v254, 24
	v_cvt_pk_bf16_f32 v52, v52, v53
	v_cvt_pk_bf16_f32 v53, v54, v55
	v_cvt_pk_bf16_f32 v54, v48, v49
	v_cvt_pk_bf16_f32 v55, v50, v51
	ds_write_b128 v215, v[52:55]
	s_waitcnt lgkmcnt(0)
	ds_read_u16 v48, v212
	ds_read_u16 v49, v212 offset:64
	ds_read_u16 v50, v212 offset:128
	ds_read_u16 v51, v212 offset:192
	ds_read_u16 v52, v212 offset:512
	ds_read_u16 v53, v212 offset:576
	ds_read_u16 v54, v212 offset:640
	ds_read_u16 v55, v212 offset:704
	s_waitcnt lgkmcnt(6)
	v_lshl_or_b32 v48, v49, 16, v48
	s_waitcnt lgkmcnt(4)
	v_lshl_or_b32 v49, v51, 16, v50
	s_waitcnt lgkmcnt(2)
	v_lshl_or_b32 v50, v53, 16, v52
	v_or_b32_e32 v52, v75, v132
	v_mad_i64_i32 v[52:53], s[0:1], v74, v52, v[66:67]
	v_lshlrev_b64 v[52:53], 13, v[52:53]
	v_lshl_add_u64 v[52:53], v[60:61], 0, v[52:53]
	v_lshl_add_u64 v[52:53], v[52:53], 0, v[148:149]
	v_lshl_add_u64 v[52:53], v[52:53], 0, v[68:69]
	v_lshl_add_u64 v[52:53], v[52:53], 0, v[70:71]
	v_lshl_add_u64 v[52:53], v[52:53], 0, v[72:73]
	s_waitcnt lgkmcnt(0)
	v_lshl_or_b32 v51, v55, 16, v54
	v_lshl_add_u64 v[52:53], v[52:53], 0, v[128:129]
	global_store_dwordx4 v[52:53], v[48:51], off nt
	v_readlane_b32 s89, v254, 25
	s_waitcnt lgkmcnt(0)
	v_readlane_b32 s88, v255, 40
	v_readlane_b32 s89, v255, 41
	s_mov_b32 s84, s7
	v_readlane_b32 s86, v254, 22
	v_readlane_b32 s87, v254, 23
	v_readlane_b32 s90, v254, 26
	v_readlane_b32 s91, v254, 27
	v_readlane_b32 s77, v254, 1
	v_readlane_b32 s78, v254, 2
	v_readlane_b32 s79, v254, 3
; #define LAS __attribute__((address_space(3)))
;     DI void operator()(const f32x4 (&acc)[2][2][4][2], const Unit& u, int wr, int wc, int fr, int fq, const Pre& pre) const {
;     ...
;         if (third == 2) {
;             LAS unsigned char* ws = scr + (wr * 4 + wc) * 1024; const int ln = fr + 16 * fq, dl = ln & 31, hf = ln >> 5;
;             LAS unsigned char* wsw = ws + fr * 64 + fq * 16; const LAS unsigned char* wsr = ws + hf * 256 + dl * 2;
; #pragma unroll
;             for (int ai = 0; ai < 2; ++ai)
; #pragma unroll
;                 for (int m = 0; m < 4; ++m) { const int row = row0 + ai * 128 + m * 16; const float r = rs[ai][m];
;                     const bool smp = row >= NTP; const int s = row - NTP; const int b = smp ? (s >> 6) : row / TP, key = smp ? 1024 + (s & 63) : row - b * TP, nkt = smp ? 34 : 129;
; #pragma unroll
;                     for (int bj = 0; bj < 2; ++bj) { const int cs = cb + bj * 128; const f32x4 v0 = acc[ai][bj][m][0] * r, v1 = acc[ai][bj][m][1] * r;
;                         if (row < NT) { const int h = cs >> 7, d = cs & 127;
;                             float* ov = out + (smp ? O_VS + (size_t)s * 1024 : O_VP + (size_t)row * 1024) + cs; *(f32x4*)ov = v0; *(f32x4*)(ov + 4) = v1;
;                             u32x4v o; o.x = pk2(v0[0], v0[1]); o.y = pk2(v0[2], v0[3]); o.z = pk2(v1[0], v1[1]); o.w = pk2(v1[2], v1[3]);
;                             *(LAS u32x4v*)wsw = o;
;                             asm volatile("s_waitcnt lgkmcnt(0)" ::: "memory");
;                             u32x4v t;
;                             t.x = (unsigned)*(const LAS unsigned short*)(wsr) | ((unsigned)*(const LAS unsigned short*)(wsr + 64) << 16);
;                             t.y = (unsigned)*(const LAS unsigned short*)(wsr + 128) | ((unsigned)*(const LAS unsigned short*)(wsr + 192) << 16);
;                             t.z = (unsigned)*(const LAS unsigned short*)(wsr + 512) | ((unsigned)*(const LAS unsigned short*)(wsr + 576) << 16);
;                             t.w = (unsigned)*(const LAS unsigned short*)(wsr + 640) | ((unsigned)*(const LAS unsigned short*)(wsr + 704) << 16);
;                             *(u32x4v*)((smp ? VTS : VTP) + vf_index(b * 8 + h, nkt, key - fr, d & ~31) + ln * 8) = t;
;                             asm volatile("s_waitcnt lgkmcnt(0)" ::: "memory"); } } }
.LBB0_2007:
	s_or_b64 exec, exec, s[10:11]
	s_movk_i32 s0, 0x7fef
	v_cmp_lt_i32_e32 vcc, s0, v180
	s_movk_i32 s0, 0x7ff0
	v_add_u32_e32 v48, 0x90, v180
	v_cmp_gt_i32_e64 s[0:1], s0, v180
	s_and_saveexec_b64 s[10:11], s[0:1]
	s_xor_b64 s[0:1], exec, s[10:11]
	v_mul_hi_i32 v49, v48, s18
	v_lshrrev_b32_e32 v50, 31, v49
	v_ashrrev_i32_e32 v49, 11, v49
	v_add_u32_e32 v49, v49, v50
	s_or_saveexec_b64 s[0:1], s[0:1]
	v_add_u32_e32 v148, 0xffff8010, v180
	s_xor_b64 exec, exec, s[0:1]
	v_lshrrev_b32_e32 v49, 6, v148
	s_or_b64 exec, exec, s[0:1]
	s_mov_b32 s0, 0x81f0
	v_cmp_gt_i32_e64 s[0:1], s0, v180
	s_and_saveexec_b64 s[10:11], s[0:1]
	s_cbranch_execz .LBB0_2013
	v_mad_u64_u32 v[50:51], s[0:1], v49, s19, v[48:49]
	v_lshlrev_b32_e32 v59, 3, v49
	v_ashrrev_i32_e32 v49, 31, v48
	v_lshlrev_b64 v[52:53], 10, v[148:149]
	v_lshlrev_b64 v[48:49], 10, v[48:49]
	v_lshl_add_u64 v[52:53], v[52:53], 0, s[40:41]
	v_lshl_add_u64 v[48:49], v[48:49], 0, s[42:43]
	v_readlane_b32 s76, v254, 12
	v_cndmask_b32_e32 v49, v49, v53, vcc
	v_cndmask_b32_e32 v48, v48, v52, vcc
	v_readlane_b32 s84, v254, 20
	v_readlane_b32 s85, v254, 21
	v_mov_b32_e32 v131, v149
	v_pk_mul_f32 v[46:47], v[46:47], v[182:183] op_sel_hi:[1,0]
	v_lshl_add_u64 v[48:49], v[48:49], 2, s[84:85]
	v_pk_mul_f32 v[44:45], v[44:45], v[182:183] op_sel_hi:[1,0]
	v_lshl_add_u64 v[48:49], v[48:49], 0, v[130:131]
	v_pk_mul_f32 v[42:43], v[42:43], v[182:183] op_sel_hi:[1,0]
	v_pk_mul_f32 v[40:41], v[40:41], v[182:183] op_sel_hi:[1,0]
	global_store_dwordx4 v[48:49], v[44:47], off nt
	global_store_dwordx4 v[48:49], v[40:43], off offset:16 nt
	v_readlane_b32 s77, v254, 13
	v_cvt_pk_bf16_f32 v44, v44, v45
	v_cvt_pk_bf16_f32 v45, v46, v47
	v_cvt_pk_bf16_f32 v46, v40, v41
	v_cvt_pk_bf16_f32 v47, v42, v43
	ds_write_b128 v215, v[44:47]
	s_waitcnt lgkmcnt(0)
	ds_read_u16 v40, v212
	ds_read_u16 v41, v212 offset:64
	ds_read_u16 v42, v212 offset:128
	ds_read_u16 v43, v212 offset:192
	ds_read_u16 v44, v212 offset:512
	ds_read_u16 v45, v212 offset:576
	ds_read_u16 v46, v212 offset:640
	ds_read_u16 v47, v212 offset:704
	v_readlane_b32 s78, v254, 14
	v_readlane_b32 s79, v254, 15
	v_readlane_b32 s80, v254, 16
	v_readlane_b32 s81, v254, 17
	v_readlane_b32 s82, v254, 18
	v_readlane_b32 s83, v254, 19
	v_cndmask_b32_e32 v50, v50, v209, vcc
	v_readlane_b32 s76, v254, 0
	v_sub_u32_e32 v54, v50, v151
	v_readlane_b32 s81, v254, 5
	v_readlane_b32 s83, v254, 7
	v_lshrrev_b32_e32 v50, 2, v54
	s_waitcnt lgkmcnt(0)
	v_lshl_or_b32 v40, v41, 16, v40
	v_lshl_or_b32 v41, v43, 16, v42
	v_lshl_or_b32 v42, v45, 16, v44
	v_readlane_b32 s80, v254, 4
	v_readlane_b32 s82, v254, 6
	v_mov_b32_e32 v44, s81
	v_mov_b32_e32 v45, s83
	v_and_or_b32 v55, v50, 4, s70
	v_ashrrev_i32_e32 v50, 5, v54
	s_lshr_b32 s0, s45, 7
	v_lshl_or_b32 v43, v47, 16, v46
	v_cndmask_b32_e32 v45, v44, v45, vcc
	v_mov_b32_e32 v44, s80
	v_mov_b32_e32 v46, s82
	v_cndmask_b32_e64 v58, v216, 34, vcc
	v_ashrrev_i32_e32 v51, 31, v50
	v_cndmask_b32_e32 v44, v44, v46, vcc
	v_or_b32_e32 v46, s0, v59
	v_mad_i64_i32 v[46:47], s[0:1], v58, v46, v[50:51]
	v_lshlrev_b64 v[46:47], 13, v[46:47]
	v_lshlrev_b32_e32 v148, 10, v55
	v_lshl_add_u64 v[46:47], v[44:45], 0, v[46:47]
	v_lshlrev_b32_e32 v52, 7, v54
	v_lshl_add_u64 v[46:47], v[46:47], 0, v[148:149]
	v_and_b32_e32 v52, 0x200, v52
	v_mov_b32_e32 v53, v149
	v_and_b32_e32 v56, 3, v54
	v_lshl_add_u64 v[46:47], v[46:47], 0, v[52:53]
	v_and_b32_e32 v54, 8, v54
	v_mov_b32_e32 v55, v149
	v_lshl_add_u64 v[46:47], v[46:47], 0, v[54:55]
	v_lshlrev_b32_e32 v56, 1, v56
	v_mov_b32_e32 v57, v149
	v_lshl_add_u64 v[46:47], v[46:47], 0, v[56:57]
	v_mov_b32_e32 v129, v149
	v_lshl_add_u64 v[46:47], v[46:47], 0, v[128:129]
	global_store_dwordx4 v[46:47], v[40:43], off nt
	v_pk_mul_f32 v[38:39], v[38:39], v[182:183] op_sel_hi:[1,0]
	v_pk_mul_f32 v[36:37], v[36:37], v[182:183] op_sel_hi:[1,0]
	s_waitcnt lgkmcnt(0)
	v_pk_mul_f32 v[34:35], v[34:35], v[182:183] op_sel_hi:[1,0]
	v_pk_mul_f32 v[32:33], v[32:33], v[182:183] op_sel_hi:[1,0]
	global_store_dwordx4 v[48:49], v[36:39], off offset:512 nt
	global_store_dwordx4 v[48:49], v[32:35], off offset:528 nt
	v_readlane_b32 s88, v254, 24
	v_cvt_pk_bf16_f32 v36, v36, v37
	v_cvt_pk_bf16_f32 v37, v38, v39
	v_cvt_pk_bf16_f32 v38, v32, v33
	v_cvt_pk_bf16_f32 v39, v34, v35
	ds_write_b128 v215, v[36:39]
	s_waitcnt lgkmcnt(0)
	ds_read_u16 v32, v212
	ds_read_u16 v33, v212 offset:64
	ds_read_u16 v34, v212 offset:128
	ds_read_u16 v35, v212 offset:192
	ds_read_u16 v36, v212 offset:512
	ds_read_u16 v37, v212 offset:576
	ds_read_u16 v38, v212 offset:640
	ds_read_u16 v39, v212 offset:704
	s_waitcnt lgkmcnt(6)
	v_lshl_or_b32 v32, v33, 16, v32
	s_waitcnt lgkmcnt(4)
	v_lshl_or_b32 v33, v35, 16, v34
	s_waitcnt lgkmcnt(2)
	v_lshl_or_b32 v34, v37, 16, v36
	v_or_b32_e32 v36, v59, v132
	v_mad_i64_i32 v[36:37], s[0:1], v58, v36, v[50:51]
	v_lshlrev_b64 v[36:37], 13, v[36:37]
	v_lshl_add_u64 v[36:37], v[44:45], 0, v[36:37]
	v_lshl_add_u64 v[36:37], v[36:37], 0, v[148:149]
	v_lshl_add_u64 v[36:37], v[36:37], 0, v[52:53]
	v_lshl_add_u64 v[36:37], v[36:37], 0, v[54:55]
	v_lshl_add_u64 v[36:37], v[36:37], 0, v[56:57]
	s_waitcnt lgkmcnt(0)
	v_lshl_or_b32 v35, v39, 16, v38
	v_lshl_add_u64 v[36:37], v[36:37], 0, v[128:129]
	global_store_dwordx4 v[36:37], v[32:35], off nt
	v_readlane_b32 s89, v254, 25
	s_waitcnt lgkmcnt(0)
	v_readlane_b32 s88, v255, 40
	v_readlane_b32 s89, v255, 41
	s_mov_b32 s84, s7
	v_readlane_b32 s86, v254, 22
	v_readlane_b32 s87, v254, 23
	v_readlane_b32 s90, v254, 26
	v_readlane_b32 s91, v254, 27
	v_readlane_b32 s77, v254, 1
	v_readlane_b32 s78, v254, 2
	v_readlane_b32 s79, v254, 3

; #define LAS __attribute__((address_space(3)))
;     DI void operator()(const f32x4 (&acc)[2][2][4][2], const Unit& u, int wr, int wc, int fr, int fq, const Pre& pre) const {
;     ...
;         if (third == 2) {
;             LAS unsigned char* ws = scr + (wr * 4 + wc) * 1024; const int ln = fr + 16 * fq, dl = ln & 31, hf = ln >> 5;
;             LAS unsigned char* wsw = ws + fr * 64 + fq * 16; const LAS unsigned char* wsr = ws + hf * 256 + dl * 2;
; #pragma unroll
;             for (int ai = 0; ai < 2; ++ai)
; #pragma unroll
;                 for (int m = 0; m < 4; ++m) { const int row = row0 + ai * 128 + m * 16; const float r = rs[ai][m];
;                     const bool smp = row >= NTP; const int s = row - NTP; const int b = smp ? (s >> 6) : row / TP, key = smp ? 1024 + (s & 63) : row - b * TP, nkt = smp ? 34 : 129;
; #pragma unroll
;                     for (int bj = 0; bj < 2; ++bj) { const int cs = cb + bj * 128; const f32x4 v0 = acc[ai][bj][m][0] * r, v1 = acc[ai][bj][m][1] * r;
;                         if (row < NT) { const int h = cs >> 7, d = cs & 127;
;                             float* ov = out + (smp ? O_VS + (size_t)s * 1024 : O_VP + (size_t)row * 1024) + cs; *(f32x4*)ov = v0; *(f32x4*)(ov + 4) = v1;
;                             u32x4v o; o.x = pk2(v0[0], v0[1]); o.y = pk2(v0[2], v0[3]); o.z = pk2(v1[0], v1[1]); o.w = pk2(v1[2], v1[3]);
;                             *(LAS u32x4v*)wsw = o;
;                             asm volatile("s_waitcnt lgkmcnt(0)" ::: "memory");
;                             u32x4v t;
;                             t.x = (unsigned)*(const LAS unsigned short*)(wsr) | ((unsigned)*(const LAS unsigned short*)(wsr + 64) << 16);
;                             t.y = (unsigned)*(const LAS unsigned short*)(wsr + 128) | ((unsigned)*(const LAS unsigned short*)(wsr + 192) << 16);
;                             t.z = (unsigned)*(const LAS unsigned short*)(wsr + 512) | ((unsigned)*(const LAS unsigned short*)(wsr + 576) << 16);
;                             t.w = (unsigned)*(const LAS unsigned short*)(wsr + 640) | ((unsigned)*(const LAS unsigned short*)(wsr + 704) << 16);
;                             *(u32x4v*)((smp ? VTS : VTP) + vf_index(b * 8 + h, nkt, key - fr, d & ~31) + ln * 8) = t;
;                             asm volatile("s_waitcnt lgkmcnt(0)" ::: "memory"); } } }
.LBB0_2016:
	v_mad_u64_u32 v[34:35], s[0:1], v33, s19, v[32:33]
	v_lshlrev_b32_e32 v43, 3, v33
	v_ashrrev_i32_e32 v33, 31, v32
	v_lshlrev_b64 v[36:37], 10, v[148:149]
	v_lshlrev_b64 v[32:33], 10, v[32:33]
	v_lshl_add_u64 v[36:37], v[36:37], 0, s[40:41]
	v_lshl_add_u64 v[32:33], v[32:33], 0, s[42:43]
	v_readlane_b32 s76, v254, 12
	v_cndmask_b32_e32 v33, v33, v37, vcc
	v_cndmask_b32_e32 v32, v32, v36, vcc
	v_readlane_b32 s84, v254, 20
	v_readlane_b32 s85, v254, 21
	v_mov_b32_e32 v131, v149
	v_pk_mul_f32 v[30:31], v[30:31], v[182:183] op_sel:[0,1]
	v_lshl_add_u64 v[32:33], v[32:33], 2, s[84:85]
	v_pk_mul_f32 v[28:29], v[28:29], v[182:183] op_sel:[0,1]
	v_lshl_add_u64 v[32:33], v[32:33], 0, v[130:131]
	v_pk_mul_f32 v[26:27], v[26:27], v[182:183] op_sel:[0,1]
	v_pk_mul_f32 v[24:25], v[24:25], v[182:183] op_sel:[0,1]
	global_store_dwordx4 v[32:33], v[28:31], off nt
	global_store_dwordx4 v[32:33], v[24:27], off offset:16 nt
	v_readlane_b32 s77, v254, 13
	v_cvt_pk_bf16_f32 v28, v28, v29
	v_cvt_pk_bf16_f32 v29, v30, v31
	v_cvt_pk_bf16_f32 v30, v24, v25
	v_cvt_pk_bf16_f32 v31, v26, v27
	ds_write_b128 v215, v[28:31]
	s_waitcnt lgkmcnt(0)
	ds_read_u16 v24, v212
	ds_read_u16 v25, v212 offset:64
	ds_read_u16 v26, v212 offset:128
	ds_read_u16 v27, v212 offset:192
	ds_read_u16 v28, v212 offset:512
	ds_read_u16 v29, v212 offset:576
	ds_read_u16 v30, v212 offset:640
	ds_read_u16 v31, v212 offset:704
	v_readlane_b32 s78, v254, 14
	v_readlane_b32 s79, v254, 15
	v_readlane_b32 s80, v254, 16
	v_readlane_b32 s81, v254, 17
	v_readlane_b32 s82, v254, 18
	v_readlane_b32 s83, v254, 19
	v_cndmask_b32_e32 v34, v34, v210, vcc
	v_readlane_b32 s76, v254, 0
	v_sub_u32_e32 v38, v34, v151
	v_readlane_b32 s81, v254, 5
	v_readlane_b32 s83, v254, 7
	v_lshrrev_b32_e32 v34, 2, v38
	s_waitcnt lgkmcnt(0)
	v_lshl_or_b32 v24, v25, 16, v24
	v_lshl_or_b32 v25, v27, 16, v26
	v_lshl_or_b32 v26, v29, 16, v28
	v_readlane_b32 s80, v254, 4
	v_readlane_b32 s82, v254, 6
	v_mov_b32_e32 v28, s81
	v_mov_b32_e32 v29, s83
	v_and_or_b32 v39, v34, 4, s70
	v_ashrrev_i32_e32 v34, 5, v38
	s_lshr_b32 s0, s45, 7
	v_lshl_or_b32 v27, v31, 16, v30
	v_cndmask_b32_e32 v29, v28, v29, vcc
	v_mov_b32_e32 v28, s80
	v_mov_b32_e32 v30, s82
	v_cndmask_b32_e64 v42, v216, 34, vcc
	v_ashrrev_i32_e32 v35, 31, v34
	v_cndmask_b32_e32 v28, v28, v30, vcc
	v_or_b32_e32 v30, s0, v43
	v_mad_i64_i32 v[30:31], s[0:1], v42, v30, v[34:35]
	v_lshlrev_b64 v[30:31], 13, v[30:31]
	v_lshlrev_b32_e32 v148, 10, v39
	v_lshl_add_u64 v[30:31], v[28:29], 0, v[30:31]
	v_lshlrev_b32_e32 v36, 7, v38
	v_lshl_add_u64 v[30:31], v[30:31], 0, v[148:149]
	v_and_b32_e32 v36, 0x200, v36
	v_mov_b32_e32 v37, v149
	v_and_b32_e32 v40, 3, v38
	v_lshl_add_u64 v[30:31], v[30:31], 0, v[36:37]
	v_and_b32_e32 v38, 8, v38
	v_mov_b32_e32 v39, v149
	v_lshl_add_u64 v[30:31], v[30:31], 0, v[38:39]
	v_lshlrev_b32_e32 v40, 1, v40
	v_mov_b32_e32 v41, v149
	v_lshl_add_u64 v[30:31], v[30:31], 0, v[40:41]
	v_mov_b32_e32 v129, v149
	v_lshl_add_u64 v[30:31], v[30:31], 0, v[128:129]
	global_store_dwordx4 v[30:31], v[24:27], off nt
	v_pk_mul_f32 v[22:23], v[22:23], v[182:183] op_sel:[0,1]
	v_pk_mul_f32 v[20:21], v[20:21], v[182:183] op_sel:[0,1]
	s_waitcnt lgkmcnt(0)
	v_pk_mul_f32 v[18:19], v[18:19], v[182:183] op_sel:[0,1]
	v_pk_mul_f32 v[16:17], v[16:17], v[182:183] op_sel:[0,1]
	global_store_dwordx4 v[32:33], v[20:23], off offset:512 nt
	global_store_dwordx4 v[32:33], v[16:19], off offset:528 nt
	v_readlane_b32 s88, v254, 24
	v_cvt_pk_bf16_f32 v20, v20, v21
	v_cvt_pk_bf16_f32 v21, v22, v23
	v_cvt_pk_bf16_f32 v22, v16, v17
	v_cvt_pk_bf16_f32 v23, v18, v19
	ds_write_b128 v215, v[20:23]
	s_waitcnt lgkmcnt(0)
	ds_read_u16 v16, v212
	ds_read_u16 v17, v212 offset:64
	ds_read_u16 v18, v212 offset:128
	ds_read_u16 v19, v212 offset:192
	ds_read_u16 v20, v212 offset:512
	ds_read_u16 v21, v212 offset:576
	ds_read_u16 v22, v212 offset:640
	ds_read_u16 v23, v212 offset:704
	s_waitcnt lgkmcnt(6)
	v_lshl_or_b32 v16, v17, 16, v16
	s_waitcnt lgkmcnt(4)
	v_lshl_or_b32 v17, v19, 16, v18
	s_waitcnt lgkmcnt(2)
	v_lshl_or_b32 v18, v21, 16, v20
	v_or_b32_e32 v20, v43, v132
	v_mad_i64_i32 v[20:21], s[0:1], v42, v20, v[34:35]
	v_lshlrev_b64 v[20:21], 13, v[20:21]
	v_lshl_add_u64 v[20:21], v[28:29], 0, v[20:21]
	v_lshl_add_u64 v[20:21], v[20:21], 0, v[148:149]
	v_lshl_add_u64 v[20:21], v[20:21], 0, v[36:37]
	v_lshl_add_u64 v[20:21], v[20:21], 0, v[38:39]
	v_lshl_add_u64 v[20:21], v[20:21], 0, v[40:41]
	s_waitcnt lgkmcnt(0)
	v_lshl_or_b32 v19, v23, 16, v22
	v_lshl_add_u64 v[20:21], v[20:21], 0, v[128:129]
	global_store_dwordx4 v[20:21], v[16:19], off nt
	v_readlane_b32 s89, v254, 25
	s_waitcnt lgkmcnt(0)
	v_readlane_b32 s88, v255, 40
	v_readlane_b32 s89, v255, 41
	s_mov_b32 s84, s7
	v_readlane_b32 s86, v254, 22
	v_readlane_b32 s87, v254, 23
	v_readlane_b32 s90, v254, 26
	v_readlane_b32 s91, v254, 27
	v_readlane_b32 s77, v254, 1
	v_readlane_b32 s78, v254, 2
	v_readlane_b32 s79, v254, 3

; #define LAS __attribute__((address_space(3)))
;     DI void operator()(const f32x4 (&acc)[2][2][4][2], const Unit& u, int wr, int wc, int fr, int fq, const Pre& pre) const {
;     ...
;         if (third == 2) {
;             LAS unsigned char* ws = scr + (wr * 4 + wc) * 1024; const int ln = fr + 16 * fq, dl = ln & 31, hf = ln >> 5;
;             LAS unsigned char* wsw = ws + fr * 64 + fq * 16; const LAS unsigned char* wsr = ws + hf * 256 + dl * 2;
; #pragma unroll
;             for (int ai = 0; ai < 2; ++ai)
; #pragma unroll
;                 for (int m = 0; m < 4; ++m) { const int row = row0 + ai * 128 + m * 16; const float r = rs[ai][m];
;                     const bool smp = row >= NTP; const int s = row - NTP; const int b = smp ? (s >> 6) : row / TP, key = smp ? 1024 + (s & 63) : row - b * TP, nkt = smp ? 34 : 129;
; #pragma unroll
;                     for (int bj = 0; bj < 2; ++bj) { const int cs = cb + bj * 128; const f32x4 v0 = acc[ai][bj][m][0] * r, v1 = acc[ai][bj][m][1] * r;
;                         if (row < NT) { const int h = cs >> 7, d = cs & 127;
;                             float* ov = out + (smp ? O_VS + (size_t)s * 1024 : O_VP + (size_t)row * 1024) + cs; *(f32x4*)ov = v0; *(f32x4*)(ov + 4) = v1;
;                             u32x4v o; o.x = pk2(v0[0], v0[1]); o.y = pk2(v0[2], v0[3]); o.z = pk2(v1[0], v1[1]); o.w = pk2(v1[2], v1[3]);
;                             *(LAS u32x4v*)wsw = o;
;                             asm volatile("s_waitcnt lgkmcnt(0)" ::: "memory");
;                             u32x4v t;
;                             t.x = (unsigned)*(const LAS unsigned short*)(wsr) | ((unsigned)*(const LAS unsigned short*)(wsr + 64) << 16);
;                             t.y = (unsigned)*(const LAS unsigned short*)(wsr + 128) | ((unsigned)*(const LAS unsigned short*)(wsr + 192) << 16);
;                             t.z = (unsigned)*(const LAS unsigned short*)(wsr + 512) | ((unsigned)*(const LAS unsigned short*)(wsr + 576) << 16);
;                             t.w = (unsigned)*(const LAS unsigned short*)(wsr + 640) | ((unsigned)*(const LAS unsigned short*)(wsr + 704) << 16);
;                             *(u32x4v*)((smp ? VTS : VTP) + vf_index(b * 8 + h, nkt, key - fr, d & ~31) + ln * 8) = t;
;                             asm volatile("s_waitcnt lgkmcnt(0)" ::: "memory"); } } }
.LBB0_2030:
	v_mad_u64_u32 v[18:19], s[0:1], v17, s19, v[16:17]
	v_lshlrev_b32_e32 v27, 3, v17
	v_ashrrev_i32_e32 v17, 31, v16
	v_lshlrev_b64 v[20:21], 10, v[148:149]
	v_lshlrev_b64 v[16:17], 10, v[16:17]
	v_lshl_add_u64 v[20:21], v[20:21], 0, s[40:41]
	v_lshl_add_u64 v[16:17], v[16:17], 0, s[42:43]
	v_readlane_b32 s76, v254, 12
	v_cndmask_b32_e32 v17, v17, v21, vcc
	v_cndmask_b32_e32 v16, v16, v20, vcc
	v_readlane_b32 s84, v254, 20
	v_readlane_b32 s85, v254, 21
	v_mov_b32_e32 v131, v149
	v_pk_mul_f32 v[14:15], v[14:15], v[184:185] op_sel_hi:[1,0]
	v_lshl_add_u64 v[16:17], v[16:17], 2, s[84:85]
	v_pk_mul_f32 v[12:13], v[12:13], v[184:185] op_sel_hi:[1,0]
	v_lshl_add_u64 v[16:17], v[16:17], 0, v[130:131]
	v_pk_mul_f32 v[10:11], v[10:11], v[184:185] op_sel_hi:[1,0]
	v_pk_mul_f32 v[8:9], v[8:9], v[184:185] op_sel_hi:[1,0]
	global_store_dwordx4 v[16:17], v[12:15], off nt
	global_store_dwordx4 v[16:17], v[8:11], off offset:16 nt
	v_readlane_b32 s77, v254, 13
	v_cvt_pk_bf16_f32 v12, v12, v13
	v_cvt_pk_bf16_f32 v13, v14, v15
	v_cvt_pk_bf16_f32 v14, v8, v9
	v_cvt_pk_bf16_f32 v15, v10, v11
	ds_write_b128 v215, v[12:15]
	s_waitcnt lgkmcnt(0)
	ds_read_u16 v8, v212
	ds_read_u16 v9, v212 offset:64
	ds_read_u16 v10, v212 offset:128
	ds_read_u16 v11, v212 offset:192
	ds_read_u16 v12, v212 offset:512
	ds_read_u16 v13, v212 offset:576
	ds_read_u16 v14, v212 offset:640
	ds_read_u16 v15, v212 offset:704
	v_readlane_b32 s78, v254, 14
	v_readlane_b32 s79, v254, 15
	v_readlane_b32 s80, v254, 16
	v_readlane_b32 s81, v254, 17
	v_readlane_b32 s82, v254, 18
	v_readlane_b32 s83, v254, 19
	v_cndmask_b32_e32 v18, v18, v211, vcc
	v_readlane_b32 s76, v254, 0
	v_sub_u32_e32 v22, v18, v151
	v_readlane_b32 s81, v254, 5
	v_readlane_b32 s83, v254, 7
	v_lshrrev_b32_e32 v18, 2, v22
	s_waitcnt lgkmcnt(0)
	v_lshl_or_b32 v8, v9, 16, v8
	v_lshl_or_b32 v9, v11, 16, v10
	v_lshl_or_b32 v10, v13, 16, v12
	v_readlane_b32 s80, v254, 4
	v_readlane_b32 s82, v254, 6
	v_mov_b32_e32 v12, s81
	v_mov_b32_e32 v13, s83
	v_and_or_b32 v23, v18, 4, s70
	v_ashrrev_i32_e32 v18, 5, v22
	s_lshr_b32 s0, s45, 7
	v_lshl_or_b32 v11, v15, 16, v14
	v_cndmask_b32_e32 v13, v12, v13, vcc
	v_mov_b32_e32 v12, s80
	v_mov_b32_e32 v14, s82
	v_cndmask_b32_e64 v26, v216, 34, vcc
	v_ashrrev_i32_e32 v19, 31, v18
	v_cndmask_b32_e32 v12, v12, v14, vcc
	v_or_b32_e32 v14, s0, v27
	v_mad_i64_i32 v[14:15], s[0:1], v26, v14, v[18:19]
	v_lshlrev_b64 v[14:15], 13, v[14:15]
	v_lshlrev_b32_e32 v148, 10, v23
	v_lshl_add_u64 v[14:15], v[12:13], 0, v[14:15]
	v_lshlrev_b32_e32 v20, 7, v22
	v_lshl_add_u64 v[14:15], v[14:15], 0, v[148:149]
	v_and_b32_e32 v20, 0x200, v20
	v_mov_b32_e32 v21, v149
	v_and_b32_e32 v24, 3, v22
	v_lshl_add_u64 v[14:15], v[14:15], 0, v[20:21]
	v_and_b32_e32 v22, 8, v22
	v_mov_b32_e32 v23, v149
	v_lshl_add_u64 v[14:15], v[14:15], 0, v[22:23]
	v_lshlrev_b32_e32 v24, 1, v24
	v_mov_b32_e32 v25, v149
	v_lshl_add_u64 v[14:15], v[14:15], 0, v[24:25]
	v_mov_b32_e32 v129, v149
	v_lshl_add_u64 v[14:15], v[14:15], 0, v[128:129]
	global_store_dwordx4 v[14:15], v[8:11], off nt
	v_pk_mul_f32 v[6:7], v[6:7], v[184:185] op_sel_hi:[1,0]
	v_pk_mul_f32 v[4:5], v[4:5], v[184:185] op_sel_hi:[1,0]
	s_waitcnt lgkmcnt(0)
	v_pk_mul_f32 v[2:3], v[2:3], v[184:185] op_sel_hi:[1,0]
	v_pk_mul_f32 v[0:1], v[0:1], v[184:185] op_sel_hi:[1,0]
	global_store_dwordx4 v[16:17], v[4:7], off offset:512 nt
	global_store_dwordx4 v[16:17], v[0:3], off offset:528 nt
	v_readlane_b32 s88, v254, 24
	v_cvt_pk_bf16_f32 v4, v4, v5
	v_cvt_pk_bf16_f32 v5, v6, v7
	v_cvt_pk_bf16_f32 v6, v0, v1
	v_cvt_pk_bf16_f32 v7, v2, v3
	ds_write_b128 v215, v[4:7]
	s_waitcnt lgkmcnt(0)
	ds_read_u16 v0, v212
	ds_read_u16 v1, v212 offset:64
	ds_read_u16 v2, v212 offset:128
	ds_read_u16 v3, v212 offset:192
	ds_read_u16 v4, v212 offset:512
	ds_read_u16 v5, v212 offset:576
	ds_read_u16 v6, v212 offset:640
	ds_read_u16 v7, v212 offset:704
	s_waitcnt lgkmcnt(6)
	v_lshl_or_b32 v0, v1, 16, v0
	s_waitcnt lgkmcnt(4)
	v_lshl_or_b32 v1, v3, 16, v2
	s_waitcnt lgkmcnt(2)
	v_lshl_or_b32 v2, v5, 16, v4
	v_or_b32_e32 v4, v27, v132
	v_mad_i64_i32 v[4:5], s[0:1], v26, v4, v[18:19]
	v_lshlrev_b64 v[4:5], 13, v[4:5]
	v_lshl_add_u64 v[4:5], v[12:13], 0, v[4:5]
	v_lshl_add_u64 v[4:5], v[4:5], 0, v[148:149]
	v_lshl_add_u64 v[4:5], v[4:5], 0, v[20:21]
	v_lshl_add_u64 v[4:5], v[4:5], 0, v[22:23]
	v_lshl_add_u64 v[4:5], v[4:5], 0, v[24:25]
	s_waitcnt lgkmcnt(0)
	v_lshl_or_b32 v3, v7, 16, v6
	v_lshl_add_u64 v[4:5], v[4:5], 0, v[128:129]
	global_store_dwordx4 v[4:5], v[0:3], off nt
	v_readlane_b32 s89, v254, 25
	s_waitcnt lgkmcnt(0)
	v_readlane_b32 s88, v255, 40
	v_readlane_b32 s89, v255, 41
	s_mov_b32 s84, s7
	v_readlane_b32 s86, v254, 22
	v_readlane_b32 s87, v254, 23
	v_readlane_b32 s90, v254, 26
	v_readlane_b32 s91, v254, 27
	v_readlane_b32 s77, v254, 1
	v_readlane_b32 s78, v254, 2
	v_readlane_b32 s79, v254, 3
	s_branch .LBB0_1838

; #define LAS __attribute__((address_space(3)))
; DI unsigned pk2(float lo, float hi) { unsigned r; asm volatile("v_cvt_pk_bf16_f32 %0, %1, %2" : "=v"(r) : "v"(lo), "v"(hi)); return r; }
; DI void attn_phase(const Prm& p, LAS unsigned char* lds, int wave, int gw, int NGW, int lane) {
;     ...
; #pragma unroll
;         for (int db = 0; db < 4; ++db)
; #pragma unroll
;             for (int i = 0; i < 4; ++i) { u32x2 ov; ov.x = pk2(o[db][4 * i], o[db][4 * i + 1]); ov.y = pk2(o[db][4 * i + 2], o[db][4 * i + 3]);
;                 *(LAS u32x2*)(wl + q * 272 + (32 * db + 8 * i + 4 * half) * 2) = ov; }
; #pragma unroll
;         for (int k = 0; k < 8; ++k) { const int r = (lane >> 4) + 4 * k, ch = lane & 15;
;             const u32x4v v = *(const LAS u32x4v*)(wl + r * 272 + ch * 16);
;             if (smp || qpos0 + r < TP) *(u32x4v*)(p.O + (size_t)(qrow0 + r) * 1024 + h * 128 + ch * 8) = v; }
.LBB0_2118:
	v_cvt_pk_bf16_f32 v48, v48, v49
	v_cvt_pk_bf16_f32 v49, v50, v51
	s_nop 3
	ds_write_b64 v166, v[48:49]
	v_cvt_pk_bf16_f32 v48, v52, v53
	v_cvt_pk_bf16_f32 v49, v54, v55
	ds_write_b64 v166, v[48:49] offset:16
	v_cvt_pk_bf16_f32 v48, v56, v57
	v_cvt_pk_bf16_f32 v49, v58, v59
	ds_write_b64 v166, v[48:49] offset:32
	v_cvt_pk_bf16_f32 v48, v60, v61
	v_cvt_pk_bf16_f32 v49, v62, v63
	ds_write_b64 v166, v[48:49] offset:48
	v_cvt_pk_bf16_f32 v32, v32, v33
	v_cvt_pk_bf16_f32 v33, v34, v35
	ds_write_b64 v166, v[32:33] offset:64
	v_cvt_pk_bf16_f32 v32, v36, v37
	v_cvt_pk_bf16_f32 v33, v38, v39
	ds_write_b64 v166, v[32:33] offset:80
	v_cvt_pk_bf16_f32 v32, v40, v41
	v_cvt_pk_bf16_f32 v33, v42, v43
	ds_write_b64 v166, v[32:33] offset:96
	v_cvt_pk_bf16_f32 v32, v44, v45
	v_cvt_pk_bf16_f32 v33, v46, v47
	ds_write_b64 v166, v[32:33] offset:112
	v_cvt_pk_bf16_f32 v16, v16, v17
	v_cvt_pk_bf16_f32 v17, v18, v19
	ds_write_b64 v166, v[16:17] offset:128
	v_cvt_pk_bf16_f32 v16, v20, v21
	v_cvt_pk_bf16_f32 v17, v22, v23
	ds_write_b64 v166, v[16:17] offset:144
	v_cvt_pk_bf16_f32 v16, v24, v25
	v_cvt_pk_bf16_f32 v17, v26, v27
	ds_write_b64 v166, v[16:17] offset:160
	v_cvt_pk_bf16_f32 v16, v28, v29
	v_cvt_pk_bf16_f32 v17, v30, v31
	ds_write_b64 v166, v[16:17] offset:176
	v_cvt_pk_bf16_f32 v0, v0, v1
	v_cvt_pk_bf16_f32 v1, v2, v3
	ds_write_b64 v166, v[0:1] offset:192
	v_cvt_pk_bf16_f32 v0, v4, v5
	v_cvt_pk_bf16_f32 v1, v6, v7
	ds_write_b64 v166, v[0:1] offset:208
	v_cvt_pk_bf16_f32 v0, v8, v9
	v_cvt_pk_bf16_f32 v1, v10, v11
	ds_write_b64 v166, v[0:1] offset:224
	v_cvt_pk_bf16_f32 v0, v12, v13
	v_cvt_pk_bf16_f32 v1, v14, v15
	ds_write_b64 v166, v[0:1] offset:240
	v_or_b32_e32 v0, s18, v155
	v_cmp_gt_i32_e32 vcc, s3, v0
	s_or_b64 s[20:21], s[10:11], vcc
	v_lshlrev_b32_e32 v0, 1, v146
	s_and_saveexec_b64 s[14:15], s[20:21]
	s_cbranch_execz .LBB0_2120
	v_add_u32_e32 v2, s17, v155
	v_ashrrev_i32_e32 v3, 31, v2
	v_lshlrev_b64 v[6:7], 11, v[2:3]
	ds_read_b128 v[2:5], v171
	v_lshl_add_u64 v[6:7], s[92:93], 0, v[6:7]
	v_lshl_add_u64 v[6:7], s[12:13], 1, v[6:7]
	v_mov_b32_e32 v1, v145
	v_lshl_add_u64 v[6:7], v[6:7], 0, v[0:1]
	s_waitcnt lgkmcnt(0)
	global_store_dwordx4 v[6:7], v[2:5], off nt
.LBB0_2120:
	s_or_b64 exec, exec, s[14:15]
	v_or_b32_e32 v1, s18, v147
	v_cmp_gt_i32_e32 vcc, s3, v1
	s_or_b64 s[20:21], s[10:11], vcc
	s_and_saveexec_b64 s[14:15], s[20:21]
	s_cbranch_execz .LBB0_2122
	v_add_u32_e32 v2, s17, v147
	v_ashrrev_i32_e32 v3, 31, v2
	v_lshlrev_b64 v[6:7], 11, v[2:3]
	ds_read_b128 v[2:5], v171 offset:1088
	v_lshl_add_u64 v[6:7], s[92:93], 0, v[6:7]
	v_lshl_add_u64 v[6:7], s[12:13], 1, v[6:7]
	v_mov_b32_e32 v1, v145
	v_lshl_add_u64 v[6:7], v[6:7], 0, v[0:1]
	s_waitcnt lgkmcnt(0)
	global_store_dwordx4 v[6:7], v[2:5], off nt
.LBB0_2122:
	s_or_b64 exec, exec, s[14:15]
	v_or_b32_e32 v1, s18, v157
	v_cmp_gt_i32_e32 vcc, s3, v1
	s_or_b64 s[20:21], s[10:11], vcc
	s_and_saveexec_b64 s[14:15], s[20:21]
	s_cbranch_execz .LBB0_2124
	v_add_u32_e32 v2, s17, v157
	v_ashrrev_i32_e32 v3, 31, v2
	v_lshlrev_b64 v[6:7], 11, v[2:3]
	ds_read_b128 v[2:5], v171 offset:2176
	v_lshl_add_u64 v[6:7], s[92:93], 0, v[6:7]
	v_lshl_add_u64 v[6:7], s[12:13], 1, v[6:7]
	v_mov_b32_e32 v1, v145
	v_lshl_add_u64 v[6:7], v[6:7], 0, v[0:1]
	s_waitcnt lgkmcnt(0)
	global_store_dwordx4 v[6:7], v[2:5], off nt
.LBB0_2124:
	s_or_b64 exec, exec, s[14:15]
	v_or_b32_e32 v1, s18, v160
	v_cmp_gt_i32_e32 vcc, s3, v1
	s_or_b64 s[20:21], s[10:11], vcc
	s_and_saveexec_b64 s[14:15], s[20:21]
	s_cbranch_execz .LBB0_2126
	v_add_u32_e32 v2, s17, v160
	v_ashrrev_i32_e32 v3, 31, v2
	v_lshlrev_b64 v[6:7], 11, v[2:3]
	ds_read_b128 v[2:5], v171 offset:3264
	v_lshl_add_u64 v[6:7], s[92:93], 0, v[6:7]
	v_lshl_add_u64 v[6:7], s[12:13], 1, v[6:7]
	v_mov_b32_e32 v1, v145
	v_lshl_add_u64 v[6:7], v[6:7], 0, v[0:1]
	s_waitcnt lgkmcnt(0)
	global_store_dwordx4 v[6:7], v[2:5], off nt
.LBB0_2126:
	s_or_b64 exec, exec, s[14:15]
	v_or_b32_e32 v1, s18, v161
	v_cmp_gt_i32_e32 vcc, s3, v1
	s_or_b64 s[20:21], s[10:11], vcc
	s_and_saveexec_b64 s[14:15], s[20:21]
	s_cbranch_execz .LBB0_2128
	v_add_u32_e32 v2, s17, v161
	v_ashrrev_i32_e32 v3, 31, v2
	v_lshlrev_b64 v[6:7], 11, v[2:3]
	ds_read_b128 v[2:5], v171 offset:4352
	v_lshl_add_u64 v[6:7], s[92:93], 0, v[6:7]
	v_lshl_add_u64 v[6:7], s[12:13], 1, v[6:7]
	v_mov_b32_e32 v1, v145
	v_lshl_add_u64 v[6:7], v[6:7], 0, v[0:1]
	s_waitcnt lgkmcnt(0)
	global_store_dwordx4 v[6:7], v[2:5], off nt
.LBB0_2128:
	s_or_b64 exec, exec, s[14:15]
	v_or_b32_e32 v1, s18, v162
	v_cmp_gt_i32_e32 vcc, s3, v1
	s_or_b64 s[20:21], s[10:11], vcc
	s_and_saveexec_b64 s[14:15], s[20:21]
	s_cbranch_execz .LBB0_2130
	v_add_u32_e32 v2, s17, v162
	v_ashrrev_i32_e32 v3, 31, v2
	v_lshlrev_b64 v[6:7], 11, v[2:3]
	ds_read_b128 v[2:5], v171 offset:5440
	v_lshl_add_u64 v[6:7], s[92:93], 0, v[6:7]
	v_lshl_add_u64 v[6:7], s[12:13], 1, v[6:7]
	v_mov_b32_e32 v1, v145
	v_lshl_add_u64 v[6:7], v[6:7], 0, v[0:1]
	s_waitcnt lgkmcnt(0)
	global_store_dwordx4 v[6:7], v[2:5], off nt
.LBB0_2130:
	s_or_b64 exec, exec, s[14:15]
	v_or_b32_e32 v1, s18, v163
	v_cmp_gt_i32_e32 vcc, s3, v1
	s_or_b64 s[20:21], s[10:11], vcc
	s_and_saveexec_b64 s[14:15], s[20:21]
	s_cbranch_execz .LBB0_2132
	v_add_u32_e32 v2, s17, v163
	v_ashrrev_i32_e32 v3, 31, v2
	v_lshlrev_b64 v[6:7], 11, v[2:3]
	ds_read_b128 v[2:5], v171 offset:6528
	v_lshl_add_u64 v[6:7], s[92:93], 0, v[6:7]
	v_lshl_add_u64 v[6:7], s[12:13], 1, v[6:7]
	v_mov_b32_e32 v1, v145
	v_lshl_add_u64 v[6:7], v[6:7], 0, v[0:1]
	s_waitcnt lgkmcnt(0)
	global_store_dwordx4 v[6:7], v[2:5], off nt
.LBB0_2132:
	s_or_b64 exec, exec, s[14:15]
	v_or_b32_e32 v1, s18, v164
	v_cmp_gt_i32_e32 vcc, s3, v1
	s_or_b64 s[14:15], s[10:11], vcc
	s_and_saveexec_b64 s[10:11], s[14:15]
	s_cbranch_execz .LBB0_2102
	v_add_u32_e32 v2, s17, v164
	v_ashrrev_i32_e32 v3, 31, v2
	v_lshlrev_b64 v[6:7], 11, v[2:3]
	ds_read_b128 v[2:5], v171 offset:7616
	v_lshl_add_u64 v[6:7], s[92:93], 0, v[6:7]
	v_lshl_add_u64 v[6:7], s[12:13], 1, v[6:7]
	v_mov_b32_e32 v1, v145
	v_lshl_add_u64 v[0:1], v[6:7], 0, v[0:1]
	s_waitcnt lgkmcnt(0)
	global_store_dwordx4 v[0:1], v[2:5], off nt
	s_branch .LBB0_2102

; template <class Epi, class Sched>
; __device__ __forceinline__ void gemm_phase(PG8_LAS unsigned char* lds, const Gemm g, const Sched& S, const Epi& E) {
;     ...
;             else { f32x4* pp = (f32x4*)g.part + (size_t)cur.part * 32 * 512 + tid;
; #pragma unroll
;                 for (int a = 0; a < 2; ++a)
; #pragma unroll
;                     for (int b = 0; b < 2; ++b)
; #pragma unroll
;                         for (int m = 0; m < 4; ++m)
; #pragma unroll
;                             for (int n = 0; n < 2; ++n) pp[(size_t)(((a * 2 + b) * 4 + m) * 2 + n) * 512] = acc[a][b][m][n]; }
.LBB0_2253:
	s_lshl_b64 s[46:47], s[12:13], 18
	v_lshl_add_u64 v[128:129], v[166:167], 0, s[46:47]
	v_add_co_u32_e32 v130, vcc, 0x2000, v128
	s_mov_b32 s12, 0x10000
	s_nop 0
	v_addc_co_u32_e32 v131, vcc, 0, v129, vcc
	global_store_dwordx4 v[130:131], v[120:123], off nt
	v_add_co_u32_e32 v130, vcc, 0x4000, v128
	global_store_dwordx4 v[128:129], v[124:127], off nt
	s_nop 0
	v_addc_co_u32_e32 v131, vcc, 0, v129, vcc
	global_store_dwordx4 v[130:131], v[108:111], off nt
	v_add_co_u32_e32 v130, vcc, 0x6000, v128
	s_mov_b64 s[46:47], 0
	s_nop 0
	v_addc_co_u32_e32 v131, vcc, 0, v129, vcc
	global_store_dwordx4 v[130:131], v[104:107], off nt
	v_add_co_u32_e32 v130, vcc, 0x8000, v128
	s_nop 1
	v_addc_co_u32_e32 v131, vcc, 0, v129, vcc
	global_store_dwordx4 v[130:131], v[92:95], off nt
	v_add_co_u32_e32 v130, vcc, 0xa000, v128
	s_nop 1
	v_addc_co_u32_e32 v131, vcc, 0, v129, vcc
	global_store_dwordx4 v[130:131], v[88:91], off nt
	v_add_co_u32_e32 v130, vcc, 0xc000, v128
	s_nop 1
	v_addc_co_u32_e32 v131, vcc, 0, v129, vcc
	global_store_dwordx4 v[130:131], v[76:79], off nt
	v_add_co_u32_e32 v130, vcc, 0xe000, v128
	s_nop 1
	v_addc_co_u32_e32 v131, vcc, 0, v129, vcc
	global_store_dwordx4 v[130:131], v[72:75], off nt
	v_add_co_u32_e32 v130, vcc, s12, v128
	s_mov_b32 s12, 0x12000
	s_nop 0
	v_addc_co_u32_e32 v131, vcc, 0, v129, vcc
	global_store_dwordx4 v[130:131], v[116:119], off nt
	v_add_co_u32_e32 v130, vcc, s12, v128
	s_mov_b32 s12, 0x14000
	s_nop 0
	v_addc_co_u32_e32 v131, vcc, 0, v129, vcc
	global_store_dwordx4 v[130:131], v[112:115], off nt
	v_add_co_u32_e32 v130, vcc, s12, v128
	s_mov_b32 s12, 0x16000
	s_nop 0
	v_addc_co_u32_e32 v131, vcc, 0, v129, vcc
	global_store_dwordx4 v[130:131], v[100:103], off nt
	v_add_co_u32_e32 v130, vcc, s12, v128
	s_mov_b32 s12, 0x18000
	s_nop 0
	v_addc_co_u32_e32 v131, vcc, 0, v129, vcc
	global_store_dwordx4 v[130:131], v[96:99], off nt
	v_add_co_u32_e32 v130, vcc, s12, v128
	s_mov_b32 s12, 0x1a000
	s_nop 0
	v_addc_co_u32_e32 v131, vcc, 0, v129, vcc
	global_store_dwordx4 v[130:131], v[84:87], off nt
	v_add_co_u32_e32 v130, vcc, s12, v128
	s_mov_b32 s12, 0x1c000
	s_nop 0
	v_addc_co_u32_e32 v131, vcc, 0, v129, vcc
	global_store_dwordx4 v[130:131], v[80:83], off nt
	v_add_co_u32_e32 v130, vcc, s12, v128
	s_mov_b32 s12, 0x1e000
	s_nop 0
	v_addc_co_u32_e32 v131, vcc, 0, v129, vcc
	global_store_dwordx4 v[130:131], v[68:71], off nt
	v_add_co_u32_e32 v130, vcc, s12, v128
	s_mov_b32 s12, 0x20000
	s_nop 0
	v_addc_co_u32_e32 v131, vcc, 0, v129, vcc
	global_store_dwordx4 v[130:131], v[64:67], off nt
	v_add_co_u32_e32 v130, vcc, s12, v128
	s_mov_b32 s12, 0x22000
	s_nop 0
	v_addc_co_u32_e32 v131, vcc, 0, v129, vcc
	global_store_dwordx4 v[130:131], v[60:63], off nt
	v_add_co_u32_e32 v130, vcc, s12, v128
	s_mov_b32 s12, 0x24000
	s_nop 0
	v_addc_co_u32_e32 v131, vcc, 0, v129, vcc
	global_store_dwordx4 v[130:131], v[56:59], off nt
	v_add_co_u32_e32 v130, vcc, s12, v128
	s_mov_b32 s12, 0x26000
	s_nop 0
	v_addc_co_u32_e32 v131, vcc, 0, v129, vcc
	global_store_dwordx4 v[130:131], v[44:47], off nt
	v_add_co_u32_e32 v130, vcc, s12, v128
	s_mov_b32 s12, 0x28000
	s_nop 0
	v_addc_co_u32_e32 v131, vcc, 0, v129, vcc
	global_store_dwordx4 v[130:131], v[40:43], off nt
	v_add_co_u32_e32 v130, vcc, s12, v128
	s_mov_b32 s12, 0x2a000
	s_nop 0
	v_addc_co_u32_e32 v131, vcc, 0, v129, vcc
	global_store_dwordx4 v[130:131], v[28:31], off nt
	v_add_co_u32_e32 v130, vcc, s12, v128
	s_mov_b32 s12, 0x2c000
	s_nop 0
	v_addc_co_u32_e32 v131, vcc, 0, v129, vcc
	global_store_dwordx4 v[130:131], v[24:27], off nt
	v_add_co_u32_e32 v130, vcc, s12, v128
	s_mov_b32 s12, 0x2e000
	s_nop 0
	v_addc_co_u32_e32 v131, vcc, 0, v129, vcc
	global_store_dwordx4 v[130:131], v[12:15], off nt
	v_add_co_u32_e32 v130, vcc, s12, v128
	s_mov_b32 s12, 0x30000
	s_nop 0
	v_addc_co_u32_e32 v131, vcc, 0, v129, vcc
	global_store_dwordx4 v[130:131], v[8:11], off nt
	v_add_co_u32_e32 v130, vcc, s12, v128
	s_mov_b32 s12, 0x32000
	s_nop 0
	v_addc_co_u32_e32 v131, vcc, 0, v129, vcc
	global_store_dwordx4 v[130:131], v[52:55], off nt
	v_add_co_u32_e32 v130, vcc, s12, v128
	s_mov_b32 s12, 0x34000
	s_nop 0
	v_addc_co_u32_e32 v131, vcc, 0, v129, vcc
	global_store_dwordx4 v[130:131], v[48:51], off nt
	v_add_co_u32_e32 v130, vcc, s12, v128
	s_mov_b32 s12, 0x36000
	s_nop 0
	v_addc_co_u32_e32 v131, vcc, 0, v129, vcc
	global_store_dwordx4 v[130:131], v[36:39], off nt
	v_add_co_u32_e32 v130, vcc, s12, v128
	s_mov_b32 s12, 0x38000
	s_nop 0
	v_addc_co_u32_e32 v131, vcc, 0, v129, vcc
	global_store_dwordx4 v[130:131], v[32:35], off nt
	v_add_co_u32_e32 v130, vcc, s12, v128
	s_mov_b32 s12, 0x3a000
	s_nop 0
	v_addc_co_u32_e32 v131, vcc, 0, v129, vcc
	global_store_dwordx4 v[130:131], v[20:23], off nt
	v_add_co_u32_e32 v130, vcc, s12, v128
	s_nop 1
	v_addc_co_u32_e32 v131, vcc, 0, v129, vcc
	global_store_dwordx4 v[130:131], v[16:19], off nt
	v_add_co_u32_e32 v130, vcc, 0x3c000, v128
	s_nop 1
	v_addc_co_u32_e32 v131, vcc, 0, v129, vcc
	v_add_co_u32_e32 v128, vcc, 0x3e000, v128
	global_store_dwordx4 v[130:131], v[4:7], off nt
	s_nop 0
	v_addc_co_u32_e32 v129, vcc, 0, v129, vcc
	global_store_dwordx4 v[128:129], v[0:3], off nt
; DI unsigned pk2(float lo, float hi) { unsigned r; asm volatile("v_cvt_pk_bf16_f32 %0, %1, %2" : "=v"(r) : "v"(lo), "v"(hi)); return r; }
; DI float bflo(unsigned u) { return __uint_as_float(u << 16); }
; DI float bfhi(unsigned u) { return __uint_as_float(u & 0xffff0000u); }
;     DI float upd(u32x4v* px, const u32x4v x, const f32x4 v0, const f32x4 v1) const {
;         u32x4v o; o.x = pk2(bflo(x.x) + v0[0], bfhi(x.x) + v0[1]); o.y = pk2(bflo(x.y) + v0[2], bfhi(x.y) + v0[3]);
;         o.z = pk2(bflo(x.z) + v1[0], bfhi(x.z) + v1[1]); o.w = pk2(bflo(x.w) + v1[2], bfhi(x.w) + v1[3]); *px = o;
;         const float a0 = bflo(o.x), a1 = bfhi(o.x), a2 = bflo(o.y), a3 = bfhi(o.y), a4 = bflo(o.z), a5 = bfhi(o.z), a6 = bflo(o.w), a7 = bfhi(o.w);
;         return ((a0 * a0 + a1 * a1) + (a2 * a2 + a3 * a3)) + ((a4 * a4 + a5 * a5) + (a6 * a6 + a7 * a7));
;     }
;     DI void operator()(const f32x4 (&acc)[2][2][4][2], const Unit& u, int wr, int wc, int fr, int fq, const Pre& pre) const {
;         const int cb = u.pn * 256 + wc * 32 + 8 * fq, row0 = u.pm * 256 + wr * 64 + fr;
; #pragma unroll
;         for (int ai = 0; ai < 2; ++ai) {
;             u32x4v x[4][2];
; #pragma unroll
;             for (int m = 0; m < 4; ++m)
; #pragma unroll
;                 for (int bj = 0; bj < 2; ++bj) x[m][bj] = *(const u32x4v*)(XB + (size_t)(row0 + ai * 128 + m * 16) * 1024 + cb + bj * 128);
; #pragma unroll
;             for (int m = 0; m < 4; ++m) { const int row = row0 + ai * 128 + m * 16;
;                 float ss = upd((u32x4v*)(XB + (size_t)row * 1024 + cb), x[m][0], acc[ai][0][m][0], acc[ai][0][m][1])
;                          + upd((u32x4v*)(XB + (size_t)row * 1024 + cb + 128), x[m][1], acc[ai][1][m][0], acc[ai][1][m][1]);
;                 ss += __shfl_xor(ss, 16); ss += __shfl_xor(ss, 32);
;                 if (fq == 0) SSQ[(size_t)row * 16 + u.pn * 4 + wc] = ss; } }
.LBB0_2254:
	s_andn2_b64 vcc, exec, s[46:47]
	s_cbranch_vccnz .LBB0_2222
	v_readlane_b32 s60, v254, 28
	v_lshl_or_b32 v174, s26, 8, v157
	v_readlane_b32 s61, v254, 29
	v_readlane_b32 s62, v254, 30
	v_readlane_b32 s63, v254, 31
	v_readlane_b32 s64, v254, 32
	v_readlane_b32 s65, v254, 33
	v_readlane_b32 s66, v254, 34
	v_readlane_b32 s67, v254, 35
	v_readlane_b32 s68, v254, 36
	v_readlane_b32 s69, v254, 37
	v_lshl_add_u32 v176, s42, 8, v153
	v_ashrrev_i32_e32 v175, 31, v174
	v_readlane_b32 s70, v254, 38
	v_readlane_b32 s71, v254, 39
	v_readlane_b32 s72, v254, 40
	v_readlane_b32 s73, v254, 41
	v_readlane_b32 s74, v254, 42
	v_readlane_b32 s75, v254, 43
	s_mov_b64 s[60:61], s[68:69]
	v_lshlrev_b64 v[128:129], 1, v[174:175]
	s_mov_b64 s[64:65], s[72:73]
	v_ashrrev_i32_e32 v177, 31, v176
	v_lshl_add_u64 v[178:179], s[64:65], 0, v[128:129]
	v_lshlrev_b64 v[130:131], 11, v[176:177]
	v_lshl_add_u64 v[132:133], v[178:179], 0, v[130:131]
	global_load_dwordx4 v[196:199], v[132:133], off
	global_load_dwordx4 v[200:203], v[132:133], off offset:256
	v_or_b32_e32 v186, 16, v176
	v_or_b32_e32 v182, 32, v176
	v_or_b32_e32 v180, 48, v176
	v_ashrrev_i32_e32 v187, 31, v186
	v_ashrrev_i32_e32 v183, 31, v182
	v_ashrrev_i32_e32 v181, 31, v180
	v_lshlrev_b64 v[190:191], 11, v[186:187]
	v_lshlrev_b64 v[188:189], 11, v[182:183]
	v_lshlrev_b64 v[184:185], 11, v[180:181]
	v_lshl_add_u64 v[130:131], s[64:65], 0, v[130:131]
	v_lshl_add_u64 v[132:133], v[178:179], 0, v[190:191]
	v_lshl_add_u64 v[134:135], v[178:179], 0, v[188:189]
	v_lshl_add_u64 v[204:205], v[178:179], 0, v[184:185]
	v_lshl_add_u64 v[206:207], v[130:131], 0, v[128:129]
	global_load_dwordx4 v[148:151], v[132:133], off
	global_load_dwordx4 v[144:147], v[132:133], off offset:256
	global_load_dwordx4 v[140:143], v[134:135], off
	global_load_dwordx4 v[136:139], v[134:135], off offset:256
	s_nop 0
	global_load_dwordx4 v[132:135], v[204:205], off
	global_load_dwordx4 v[128:131], v[204:205], off offset:256
	s_lshl_b32 s26, s26, 2
	s_mov_b64 s[66:67], s[74:75]
	s_ashr_i32 s27, s26, 31
	s_mov_b64 s[62:63], s[70:71]
	s_waitcnt vmcnt(0)
	v_lshlrev_b32_e32 v204, 16, v196
	v_and_b32_e32 v196, 0xffff0000, v196
	v_lshlrev_b32_e32 v205, 16, v197
	v_and_b32_e32 v197, 0xffff0000, v197
	v_lshlrev_b32_e32 v208, 16, v198
	v_and_b32_e32 v198, 0xffff0000, v198
	v_lshlrev_b32_e32 v209, 16, v199
	v_and_b32_e32 v199, 0xffff0000, v199
	v_lshlrev_b32_e32 v212, 16, v202
	v_and_b32_e32 v202, 0xffff0000, v202
	v_lshlrev_b32_e32 v213, 16, v203
	v_and_b32_e32 v203, 0xffff0000, v203
	v_add_f32_e32 v124, v124, v204
	v_add_f32_e32 v125, v125, v196
	v_add_f32_e32 v126, v126, v205
	v_add_f32_e32 v127, v127, v197
	v_add_f32_e32 v120, v120, v208
	v_add_f32_e32 v121, v121, v198
	v_add_f32_e32 v122, v122, v209
	v_add_f32_e32 v123, v123, v199
	v_add_f32_e32 v196, v112, v212
	v_add_f32_e32 v197, v113, v202
	v_add_f32_e32 v198, v114, v213
	v_add_f32_e32 v199, v115, v203
	v_cvt_pk_bf16_f32 v112, v124, v125
	v_cvt_pk_bf16_f32 v113, v126, v127
	v_cvt_pk_bf16_f32 v114, v120, v121
	v_cvt_pk_bf16_f32 v115, v122, v123
	global_store_dwordx4 v[206:207], v[112:115], off nt
	v_lshlrev_b32_e32 v120, 16, v112
	v_lshlrev_b32_e32 v121, 16, v113
	v_and_b32_e32 v112, 0xffff0000, v112
	v_and_b32_e32 v113, 0xffff0000, v113
	v_lshlrev_b32_e32 v122, 16, v114
	v_and_b32_e32 v114, 0xffff0000, v114
	v_lshlrev_b32_e32 v123, 16, v115
	v_and_b32_e32 v115, 0xffff0000, v115
	v_lshlrev_b32_e32 v210, 16, v200
	v_and_b32_e32 v200, 0xffff0000, v200
	v_lshlrev_b32_e32 v211, 16, v201
	v_mul_f32_e32 v112, v112, v112
	v_mul_f32_e32 v113, v113, v113
	v_mul_f32_e32 v114, v114, v114
	v_mul_f32_e32 v115, v115, v115
	v_and_b32_e32 v201, 0xffff0000, v201
	v_add_f32_e32 v116, v116, v210
	v_add_f32_e32 v117, v117, v200
	v_add_f32_e32 v118, v118, v211
	v_fmac_f32_e32 v112, v120, v120
	v_fmac_f32_e32 v113, v121, v121
	v_fmac_f32_e32 v114, v122, v122
	v_fmac_f32_e32 v115, v123, v123
	v_add_f32_e32 v119, v119, v201
	v_cvt_pk_bf16_f32 v116, v116, v117
	v_cvt_pk_bf16_f32 v117, v118, v119
	v_cvt_pk_bf16_f32 v118, v196, v197
	v_add_f32_e32 v112, v112, v113
	v_add_f32_e32 v113, v114, v115
	v_and_b32_e32 v115, 0xffff0000, v118
	v_cvt_pk_bf16_f32 v119, v198, v199
	v_and_b32_e32 v125, 0xffff0000, v116
	v_add_f32_e32 v112, v112, v113
	v_and_b32_e32 v113, 0xffff0000, v117
	v_lshlrev_b32_e32 v114, 16, v118
	v_and_b32_e32 v121, 0xffff0000, v119
	v_mul_f32_e32 v115, v115, v115
	v_lshlrev_b32_e32 v124, 16, v116
	v_lshlrev_b32_e32 v126, 16, v117
	v_lshlrev_b32_e32 v120, 16, v119
	v_mul_f32_e32 v122, v125, v125
	v_mul_f32_e32 v113, v113, v113
	v_fmac_f32_e32 v115, v114, v114
	v_mul_f32_e32 v114, v121, v121
	v_fmac_f32_e32 v122, v124, v124
	v_fmac_f32_e32 v113, v126, v126
	v_fmac_f32_e32 v114, v120, v120
	v_add_f32_e32 v113, v122, v113
	v_add_f32_e32 v114, v115, v114
	v_add_f32_e32 v113, v113, v114
	v_and_b32_e32 v114, 64, v195
	v_add_f32_e32 v113, v112, v113
	v_xor_b32_e32 v112, 16, v195
	v_add_u32_e32 v115, 64, v114
	v_cmp_lt_i32_e32 vcc, v112, v115
	global_store_dwordx4 v[206:207], v[116:119], off offset:256 nt
	s_nop 0
	v_cndmask_b32_e32 v112, v195, v112, vcc
	v_lshlrev_b32_e32 v112, 2, v112
	ds_bpermute_b32 v114, v112, v113
	s_waitcnt lgkmcnt(0)
	v_add_f32_e32 v114, v113, v114
	v_xor_b32_e32 v113, 32, v195
	v_cmp_lt_i32_e32 vcc, v113, v115
	s_nop 1
	v_cndmask_b32_e32 v113, v195, v113, vcc
	v_lshlrev_b32_e32 v113, 2, v113
	ds_bpermute_b32 v115, v113, v114
	s_and_saveexec_b64 s[42:43], s[0:1]
	s_cbranch_execz .LBB0_2257
	v_lshlrev_b64 v[116:117], 6, v[176:177]
	v_lshl_add_u64 v[116:117], s[66:67], 0, v[116:117]
	v_lshl_add_u64 v[116:117], s[26:27], 2, v[116:117]
	s_lshl_b32 s12, s17, 2
	v_lshl_add_u64 v[116:117], v[116:117], 0, s[12:13]
	s_waitcnt lgkmcnt(0)
	v_add_f32_e32 v114, v114, v115
	global_store_dword v[116:117], v114, off
; DI unsigned pk2(float lo, float hi) { unsigned r; asm volatile("v_cvt_pk_bf16_f32 %0, %1, %2" : "=v"(r) : "v"(lo), "v"(hi)); return r; }
; DI float bflo(unsigned u) { return __uint_as_float(u << 16); }
; DI float bfhi(unsigned u) { return __uint_as_float(u & 0xffff0000u); }
;     DI float upd(u32x4v* px, const u32x4v x, const f32x4 v0, const f32x4 v1) const {
;         u32x4v o; o.x = pk2(bflo(x.x) + v0[0], bfhi(x.x) + v0[1]); o.y = pk2(bflo(x.y) + v0[2], bfhi(x.y) + v0[3]);
;         o.z = pk2(bflo(x.z) + v1[0], bfhi(x.z) + v1[1]); o.w = pk2(bflo(x.w) + v1[2], bfhi(x.w) + v1[3]); *px = o;
;         const float a0 = bflo(o.x), a1 = bfhi(o.x), a2 = bflo(o.y), a3 = bfhi(o.y), a4 = bflo(o.z), a5 = bfhi(o.z), a6 = bflo(o.w), a7 = bfhi(o.w);
;         return ((a0 * a0 + a1 * a1) + (a2 * a2 + a3 * a3)) + ((a4 * a4 + a5 * a5) + (a6 * a6 + a7 * a7));
;     }
;     DI void operator()(const f32x4 (&acc)[2][2][4][2], const Unit& u, int wr, int wc, int fr, int fq, const Pre& pre) const {
;         const int cb = u.pn * 256 + wc * 32 + 8 * fq, row0 = u.pm * 256 + wr * 64 + fr;
; #pragma unroll
;         for (int ai = 0; ai < 2; ++ai) {
;             u32x4v x[4][2];
; #pragma unroll
;             for (int m = 0; m < 4; ++m)
; #pragma unroll
;                 for (int bj = 0; bj < 2; ++bj) x[m][bj] = *(const u32x4v*)(XB + (size_t)(row0 + ai * 128 + m * 16) * 1024 + cb + bj * 128);
; #pragma unroll
;             for (int m = 0; m < 4; ++m) { const int row = row0 + ai * 128 + m * 16;
;                 float ss = upd((u32x4v*)(XB + (size_t)row * 1024 + cb), x[m][0], acc[ai][0][m][0], acc[ai][0][m][1])
;                          + upd((u32x4v*)(XB + (size_t)row * 1024 + cb + 128), x[m][1], acc[ai][1][m][0], acc[ai][1][m][1]);
;                 ss += __shfl_xor(ss, 16); ss += __shfl_xor(ss, 32);
;                 if (fq == 0) SSQ[(size_t)row * 16 + u.pn * 4 + wc] = ss; } }
.LBB0_2257:
	s_or_b64 exec, exec, s[42:43]
	v_lshlrev_b32_e32 v116, 16, v148
	v_add_f32_e32 v108, v108, v116
	v_and_b32_e32 v116, 0xffff0000, v148
	v_add_f32_e32 v109, v109, v116
	v_cvt_pk_bf16_f32 v108, v108, v109
	v_lshlrev_b32_e32 v109, 16, v149
	v_add_f32_e32 v109, v110, v109
	v_and_b32_e32 v110, 0xffff0000, v149
	v_add_f32_e32 v110, v111, v110
	v_cvt_pk_bf16_f32 v109, v109, v110
	v_lshlrev_b32_e32 v110, 16, v150
	v_add_f32_e32 v104, v104, v110
	v_and_b32_e32 v110, 0xffff0000, v150
	v_add_f32_e32 v105, v105, v110
	v_cvt_pk_bf16_f32 v110, v104, v105
	v_and_b32_e32 v105, 0xffff0000, v151
	v_lshlrev_b32_e32 v104, 16, v151
	v_add_f32_e32 v105, v107, v105
	v_add_f32_e32 v104, v106, v104
	v_cvt_pk_bf16_f32 v111, v104, v105
	v_and_b32_e32 v105, 0xffff0000, v108
	s_waitcnt lgkmcnt(0)
	v_lshl_add_u64 v[114:115], s[64:65], 0, v[190:191]
	v_lshlrev_b32_e32 v104, 16, v108
	v_and_b32_e32 v107, 0xffff0000, v109
	v_mul_f32_e32 v105, v105, v105
	v_lshl_add_u64 v[114:115], v[174:175], 1, v[114:115]
	v_lshlrev_b32_e32 v106, 16, v109
	v_fmac_f32_e32 v105, v104, v104
	v_mul_f32_e32 v104, v107, v107
	global_store_dwordx4 v[114:115], v[108:111], off nt
	v_fmac_f32_e32 v104, v106, v106
	v_add_f32_e32 v104, v105, v104
	v_lshlrev_b32_e32 v108, 16, v110
	v_and_b32_e32 v109, 0xffff0000, v110
	v_lshlrev_b32_e32 v110, 16, v111
	v_and_b32_e32 v111, 0xffff0000, v111
	v_mul_f32_e32 v105, v109, v109
	v_mul_f32_e32 v106, v111, v111
	v_fmac_f32_e32 v105, v108, v108
	v_fmac_f32_e32 v106, v110, v110
	v_add_f32_e32 v105, v105, v106
	v_add_f32_e32 v104, v104, v105
	v_lshlrev_b32_e32 v105, 16, v144
	v_add_f32_e32 v100, v100, v105
	v_and_b32_e32 v105, 0xffff0000, v144
	v_add_f32_e32 v101, v101, v105
	v_cvt_pk_bf16_f32 v100, v100, v101
	v_lshlrev_b32_e32 v101, 16, v145
	v_add_f32_e32 v101, v102, v101
	v_and_b32_e32 v102, 0xffff0000, v145
	v_add_f32_e32 v102, v103, v102
	v_cvt_pk_bf16_f32 v101, v101, v102
	v_lshlrev_b32_e32 v102, 16, v146
	v_add_f32_e32 v96, v96, v102
	v_and_b32_e32 v102, 0xffff0000, v146
	v_add_f32_e32 v97, v97, v102
	v_cvt_pk_bf16_f32 v102, v96, v97
	v_and_b32_e32 v97, 0xffff0000, v147
	v_lshlrev_b32_e32 v96, 16, v147
	v_add_f32_e32 v97, v99, v97
	v_add_f32_e32 v96, v98, v96
	v_cvt_pk_bf16_f32 v103, v96, v97
	v_and_b32_e32 v97, 0xffff0000, v100
	v_lshlrev_b32_e32 v96, 16, v100
	v_and_b32_e32 v99, 0xffff0000, v101
	v_mul_f32_e32 v97, v97, v97
	v_lshlrev_b32_e32 v98, 16, v101
	v_fmac_f32_e32 v97, v96, v96
	v_mul_f32_e32 v96, v99, v99
	v_and_b32_e32 v106, 0xffff0000, v102
	v_and_b32_e32 v108, 0xffff0000, v103
	v_fmac_f32_e32 v96, v98, v98
	v_lshlrev_b32_e32 v105, 16, v102
	v_lshlrev_b32_e32 v107, 16, v103
	v_add_f32_e32 v96, v97, v96
	v_mul_f32_e32 v97, v106, v106
	v_mul_f32_e32 v98, v108, v108
	v_fmac_f32_e32 v97, v105, v105
	v_fmac_f32_e32 v98, v107, v107
	v_add_f32_e32 v97, v97, v98
	v_add_f32_e32 v96, v96, v97
	v_add_f32_e32 v96, v104, v96
	ds_bpermute_b32 v97, v112, v96
	global_store_dwordx4 v[114:115], v[100:103], off offset:256 nt
	s_waitcnt lgkmcnt(0)
	v_add_f32_e32 v96, v96, v97
	ds_bpermute_b32 v97, v113, v96
	s_and_saveexec_b64 s[42:43], s[0:1]
	s_cbranch_execz .LBB0_2259
	v_lshlrev_b64 v[98:99], 6, v[186:187]
	v_lshl_add_u64 v[98:99], s[66:67], 0, v[98:99]
	v_lshl_add_u64 v[98:99], s[26:27], 2, v[98:99]
	s_lshl_b32 s12, s17, 2
	v_lshl_add_u64 v[98:99], v[98:99], 0, s[12:13]
	s_waitcnt lgkmcnt(0)
	v_add_f32_e32 v96, v96, v97
	global_store_dword v[98:99], v96, off
.LBB0_2259:
	s_or_b64 exec, exec, s[42:43]
	v_lshlrev_b32_e32 v98, 16, v140
	v_add_f32_e32 v92, v92, v98
	v_and_b32_e32 v98, 0xffff0000, v140
	v_add_f32_e32 v93, v93, v98
	v_cvt_pk_bf16_f32 v92, v92, v93
	v_lshlrev_b32_e32 v93, 16, v141
	v_add_f32_e32 v93, v94, v93
	v_and_b32_e32 v94, 0xffff0000, v141
	v_add_f32_e32 v94, v95, v94
	v_cvt_pk_bf16_f32 v93, v93, v94
	v_lshlrev_b32_e32 v94, 16, v142
	v_add_f32_e32 v88, v88, v94
	v_and_b32_e32 v94, 0xffff0000, v142
	v_add_f32_e32 v89, v89, v94
	v_cvt_pk_bf16_f32 v94, v88, v89
	v_and_b32_e32 v89, 0xffff0000, v143
	v_lshlrev_b32_e32 v88, 16, v143
	v_add_f32_e32 v89, v91, v89
	v_add_f32_e32 v88, v90, v88
	v_cvt_pk_bf16_f32 v95, v88, v89
	v_and_b32_e32 v89, 0xffff0000, v92
	s_waitcnt lgkmcnt(0)
	v_lshl_add_u64 v[96:97], s[64:65], 0, v[188:189]
	v_lshlrev_b32_e32 v88, 16, v92
	v_and_b32_e32 v91, 0xffff0000, v93
	v_mul_f32_e32 v89, v89, v89
	v_lshl_add_u64 v[96:97], v[174:175], 1, v[96:97]
	v_lshlrev_b32_e32 v90, 16, v93
	v_fmac_f32_e32 v89, v88, v88
	v_mul_f32_e32 v88, v91, v91
	global_store_dwordx4 v[96:97], v[92:95], off nt
	v_fmac_f32_e32 v88, v90, v90
	v_add_f32_e32 v88, v89, v88
	v_lshlrev_b32_e32 v92, 16, v94
	v_and_b32_e32 v93, 0xffff0000, v94
	v_lshlrev_b32_e32 v94, 16, v95
	v_and_b32_e32 v95, 0xffff0000, v95
	v_mul_f32_e32 v89, v93, v93
	v_mul_f32_e32 v90, v95, v95
	v_fmac_f32_e32 v89, v92, v92
	v_fmac_f32_e32 v90, v94, v94
	v_add_f32_e32 v89, v89, v90
	v_add_f32_e32 v88, v88, v89
	v_lshlrev_b32_e32 v89, 16, v136
	v_add_f32_e32 v84, v84, v89
	v_and_b32_e32 v89, 0xffff0000, v136
	v_add_f32_e32 v85, v85, v89
	v_cvt_pk_bf16_f32 v84, v84, v85
	v_lshlrev_b32_e32 v85, 16, v137
	v_add_f32_e32 v85, v86, v85
	v_and_b32_e32 v86, 0xffff0000, v137
	v_add_f32_e32 v86, v87, v86
	v_cvt_pk_bf16_f32 v85, v85, v86
	v_lshlrev_b32_e32 v86, 16, v138
	v_add_f32_e32 v80, v80, v86
	v_and_b32_e32 v86, 0xffff0000, v138
	v_add_f32_e32 v81, v81, v86
	v_cvt_pk_bf16_f32 v86, v80, v81
	v_and_b32_e32 v81, 0xffff0000, v139
	v_lshlrev_b32_e32 v80, 16, v139
	v_add_f32_e32 v81, v83, v81
	v_add_f32_e32 v80, v82, v80
	v_cvt_pk_bf16_f32 v87, v80, v81
	v_and_b32_e32 v81, 0xffff0000, v84
	v_lshlrev_b32_e32 v80, 16, v84
	v_and_b32_e32 v83, 0xffff0000, v85
	v_mul_f32_e32 v81, v81, v81
	v_lshlrev_b32_e32 v82, 16, v85
	v_fmac_f32_e32 v81, v80, v80
	v_mul_f32_e32 v80, v83, v83
	v_and_b32_e32 v90, 0xffff0000, v86
	v_and_b32_e32 v92, 0xffff0000, v87
	v_fmac_f32_e32 v80, v82, v82
	v_lshlrev_b32_e32 v89, 16, v86
	v_lshlrev_b32_e32 v91, 16, v87
	v_add_f32_e32 v80, v81, v80
	v_mul_f32_e32 v81, v90, v90
	v_mul_f32_e32 v82, v92, v92
	v_fmac_f32_e32 v81, v89, v89
	v_fmac_f32_e32 v82, v91, v91
	v_add_f32_e32 v81, v81, v82
	v_add_f32_e32 v80, v80, v81
	v_add_f32_e32 v80, v88, v80
	ds_bpermute_b32 v81, v112, v80
	global_store_dwordx4 v[96:97], v[84:87], off offset:256 nt
	s_waitcnt lgkmcnt(0)
	v_add_f32_e32 v80, v80, v81
	ds_bpermute_b32 v81, v113, v80
	s_and_saveexec_b64 s[42:43], s[0:1]
	s_cbranch_execz .LBB0_2261
	v_lshlrev_b64 v[82:83], 6, v[182:183]
	v_lshl_add_u64 v[82:83], s[66:67], 0, v[82:83]
	v_lshl_add_u64 v[82:83], s[26:27], 2, v[82:83]
	s_lshl_b32 s12, s17, 2
	v_lshl_add_u64 v[82:83], v[82:83], 0, s[12:13]
	s_waitcnt lgkmcnt(0)
	v_add_f32_e32 v80, v80, v81
	global_store_dword v[82:83], v80, off
; DI unsigned pk2(float lo, float hi) { unsigned r; asm volatile("v_cvt_pk_bf16_f32 %0, %1, %2" : "=v"(r) : "v"(lo), "v"(hi)); return r; }
; DI float bflo(unsigned u) { return __uint_as_float(u << 16); }
; DI float bfhi(unsigned u) { return __uint_as_float(u & 0xffff0000u); }
;     DI float upd(u32x4v* px, const u32x4v x, const f32x4 v0, const f32x4 v1) const {
;         u32x4v o; o.x = pk2(bflo(x.x) + v0[0], bfhi(x.x) + v0[1]); o.y = pk2(bflo(x.y) + v0[2], bfhi(x.y) + v0[3]);
;         o.z = pk2(bflo(x.z) + v1[0], bfhi(x.z) + v1[1]); o.w = pk2(bflo(x.w) + v1[2], bfhi(x.w) + v1[3]); *px = o;
;         const float a0 = bflo(o.x), a1 = bfhi(o.x), a2 = bflo(o.y), a3 = bfhi(o.y), a4 = bflo(o.z), a5 = bfhi(o.z), a6 = bflo(o.w), a7 = bfhi(o.w);
;         return ((a0 * a0 + a1 * a1) + (a2 * a2 + a3 * a3)) + ((a4 * a4 + a5 * a5) + (a6 * a6 + a7 * a7));
;     }
;     DI void operator()(const f32x4 (&acc)[2][2][4][2], const Unit& u, int wr, int wc, int fr, int fq, const Pre& pre) const {
;         const int cb = u.pn * 256 + wc * 32 + 8 * fq, row0 = u.pm * 256 + wr * 64 + fr;
; #pragma unroll
;         for (int ai = 0; ai < 2; ++ai) {
;             u32x4v x[4][2];
; #pragma unroll
;             for (int m = 0; m < 4; ++m)
; #pragma unroll
;                 for (int bj = 0; bj < 2; ++bj) x[m][bj] = *(const u32x4v*)(XB + (size_t)(row0 + ai * 128 + m * 16) * 1024 + cb + bj * 128);
; #pragma unroll
;             for (int m = 0; m < 4; ++m) { const int row = row0 + ai * 128 + m * 16;
;                 float ss = upd((u32x4v*)(XB + (size_t)row * 1024 + cb), x[m][0], acc[ai][0][m][0], acc[ai][0][m][1])
;                          + upd((u32x4v*)(XB + (size_t)row * 1024 + cb + 128), x[m][1], acc[ai][1][m][0], acc[ai][1][m][1]);
;                 ss += __shfl_xor(ss, 16); ss += __shfl_xor(ss, 32);
;                 if (fq == 0) SSQ[(size_t)row * 16 + u.pn * 4 + wc] = ss; } }
.LBB0_2261:
	s_or_b64 exec, exec, s[42:43]
	v_lshlrev_b32_e32 v82, 16, v132
	v_add_f32_e32 v76, v76, v82
	v_and_b32_e32 v82, 0xffff0000, v132
	v_add_f32_e32 v77, v77, v82
	v_cvt_pk_bf16_f32 v76, v76, v77
	v_lshlrev_b32_e32 v77, 16, v133
	v_add_f32_e32 v77, v78, v77
	v_and_b32_e32 v78, 0xffff0000, v133
	v_add_f32_e32 v78, v79, v78
	v_cvt_pk_bf16_f32 v77, v77, v78
	v_lshlrev_b32_e32 v78, 16, v134
	v_add_f32_e32 v72, v72, v78
	v_and_b32_e32 v78, 0xffff0000, v134
	v_add_f32_e32 v73, v73, v78
	v_cvt_pk_bf16_f32 v78, v72, v73
	v_and_b32_e32 v73, 0xffff0000, v135
	v_lshlrev_b32_e32 v72, 16, v135
	v_add_f32_e32 v73, v75, v73
	v_add_f32_e32 v72, v74, v72
	v_cvt_pk_bf16_f32 v79, v72, v73
	v_and_b32_e32 v73, 0xffff0000, v76
	s_waitcnt lgkmcnt(0)
	v_lshl_add_u64 v[80:81], s[64:65], 0, v[184:185]
	v_lshlrev_b32_e32 v72, 16, v76
	v_and_b32_e32 v75, 0xffff0000, v77
	v_mul_f32_e32 v73, v73, v73
	v_lshl_add_u64 v[80:81], v[174:175], 1, v[80:81]
	v_lshlrev_b32_e32 v74, 16, v77
	v_fmac_f32_e32 v73, v72, v72
	v_mul_f32_e32 v72, v75, v75
	global_store_dwordx4 v[80:81], v[76:79], off nt
	v_fmac_f32_e32 v72, v74, v74
	v_add_f32_e32 v72, v73, v72
	v_lshlrev_b32_e32 v76, 16, v78
	v_and_b32_e32 v77, 0xffff0000, v78
	v_lshlrev_b32_e32 v78, 16, v79
	v_and_b32_e32 v79, 0xffff0000, v79
	v_mul_f32_e32 v73, v77, v77
	v_mul_f32_e32 v74, v79, v79
	v_fmac_f32_e32 v73, v76, v76
	v_fmac_f32_e32 v74, v78, v78
	v_add_f32_e32 v73, v73, v74
	v_add_f32_e32 v72, v72, v73
	v_lshlrev_b32_e32 v73, 16, v128
	v_add_f32_e32 v68, v68, v73
	v_and_b32_e32 v73, 0xffff0000, v128
	v_add_f32_e32 v69, v69, v73
	v_cvt_pk_bf16_f32 v68, v68, v69
	v_lshlrev_b32_e32 v69, 16, v129
	v_add_f32_e32 v69, v70, v69
	v_and_b32_e32 v70, 0xffff0000, v129
	v_add_f32_e32 v70, v71, v70
	v_cvt_pk_bf16_f32 v69, v69, v70
	v_lshlrev_b32_e32 v70, 16, v130
	v_add_f32_e32 v64, v64, v70
	v_and_b32_e32 v70, 0xffff0000, v130
	v_add_f32_e32 v65, v65, v70
	v_cvt_pk_bf16_f32 v70, v64, v65
	v_and_b32_e32 v65, 0xffff0000, v131
	v_lshlrev_b32_e32 v64, 16, v131
	v_add_f32_e32 v65, v67, v65
	v_add_f32_e32 v64, v66, v64
	v_cvt_pk_bf16_f32 v71, v64, v65
	v_and_b32_e32 v65, 0xffff0000, v68
	v_lshlrev_b32_e32 v64, 16, v68
	v_and_b32_e32 v67, 0xffff0000, v69
	v_mul_f32_e32 v65, v65, v65
	v_lshlrev_b32_e32 v66, 16, v69
	v_fmac_f32_e32 v65, v64, v64
	v_mul_f32_e32 v64, v67, v67
	v_and_b32_e32 v74, 0xffff0000, v70
	v_and_b32_e32 v76, 0xffff0000, v71
	v_fmac_f32_e32 v64, v66, v66
	v_lshlrev_b32_e32 v73, 16, v70
	v_lshlrev_b32_e32 v75, 16, v71
	v_add_f32_e32 v64, v65, v64
	v_mul_f32_e32 v65, v74, v74
	v_mul_f32_e32 v66, v76, v76
	v_fmac_f32_e32 v65, v73, v73
	v_fmac_f32_e32 v66, v75, v75
	v_add_f32_e32 v65, v65, v66
	v_add_f32_e32 v64, v64, v65
	v_add_f32_e32 v64, v72, v64
	ds_bpermute_b32 v65, v112, v64
	global_store_dwordx4 v[80:81], v[68:71], off offset:256 nt
	s_waitcnt lgkmcnt(0)
	v_add_f32_e32 v64, v64, v65
	ds_bpermute_b32 v65, v113, v64
	s_and_saveexec_b64 s[42:43], s[0:1]
	s_cbranch_execz .LBB0_2263
	v_lshlrev_b64 v[66:67], 6, v[180:181]
	v_lshl_add_u64 v[66:67], s[66:67], 0, v[66:67]
	v_lshl_add_u64 v[66:67], s[26:27], 2, v[66:67]
	s_lshl_b32 s12, s17, 2
	v_lshl_add_u64 v[66:67], v[66:67], 0, s[12:13]
	s_waitcnt lgkmcnt(0)
	v_add_f32_e32 v64, v64, v65
	global_store_dword v[66:67], v64, off
.LBB0_2263:
	s_or_b64 exec, exec, s[42:43]
	v_add_u32_e32 v98, 0x80, v176
	v_ashrrev_i32_e32 v99, 31, v98
	s_waitcnt lgkmcnt(0)
	v_lshlrev_b64 v[64:65], 11, v[98:99]
	v_lshl_add_u64 v[66:67], v[178:179], 0, v[64:65]
	global_load_dwordx4 v[102:105], v[66:67], off
	global_load_dwordx4 v[106:109], v[66:67], off offset:256
	v_add_u32_e32 v94, 0x90, v176
	v_add_u32_e32 v90, 0xa0, v176
	v_add_u32_e32 v88, 0xb0, v176
	v_ashrrev_i32_e32 v95, 31, v94
	v_ashrrev_i32_e32 v91, 31, v90
	v_ashrrev_i32_e32 v89, 31, v88
	v_lshlrev_b64 v[100:101], 11, v[94:95]
	v_lshlrev_b64 v[96:97], 11, v[90:91]
	v_lshlrev_b64 v[92:93], 11, v[88:89]
	v_lshl_add_u64 v[66:67], v[178:179], 0, v[100:101]
	v_lshl_add_u64 v[68:69], v[178:179], 0, v[96:97]
	v_lshl_add_u64 v[110:111], v[178:179], 0, v[92:93]
	v_lshl_add_u64 v[114:115], s[64:65], 0, v[64:65]
	global_load_dwordx4 v[84:87], v[66:67], off
	global_load_dwordx4 v[80:83], v[66:67], off offset:256
	global_load_dwordx4 v[76:79], v[68:69], off
	global_load_dwordx4 v[72:75], v[68:69], off offset:256
	s_nop 0
	global_load_dwordx4 v[68:71], v[110:111], off
	global_load_dwordx4 v[64:67], v[110:111], off offset:256
	v_lshl_add_u64 v[110:111], v[174:175], 1, v[114:115]
	s_waitcnt vmcnt(7)
	v_lshlrev_b32_e32 v114, 16, v102
	v_and_b32_e32 v102, 0xffff0000, v102
	v_lshlrev_b32_e32 v115, 16, v103
	v_and_b32_e32 v103, 0xffff0000, v103
	v_lshlrev_b32_e32 v116, 16, v104
	v_and_b32_e32 v104, 0xffff0000, v104
	v_lshlrev_b32_e32 v117, 16, v105
	v_and_b32_e32 v105, 0xffff0000, v105
	s_waitcnt vmcnt(6)
; DI unsigned pk2(float lo, float hi) { unsigned r; asm volatile("v_cvt_pk_bf16_f32 %0, %1, %2" : "=v"(r) : "v"(lo), "v"(hi)); return r; }
; DI float bflo(unsigned u) { return __uint_as_float(u << 16); }
; DI float bfhi(unsigned u) { return __uint_as_float(u & 0xffff0000u); }
;     DI float upd(u32x4v* px, const u32x4v x, const f32x4 v0, const f32x4 v1) const {
;         u32x4v o; o.x = pk2(bflo(x.x) + v0[0], bfhi(x.x) + v0[1]); o.y = pk2(bflo(x.y) + v0[2], bfhi(x.y) + v0[3]);
;         o.z = pk2(bflo(x.z) + v1[0], bfhi(x.z) + v1[1]); o.w = pk2(bflo(x.w) + v1[2], bfhi(x.w) + v1[3]); *px = o;
;         const float a0 = bflo(o.x), a1 = bfhi(o.x), a2 = bflo(o.y), a3 = bfhi(o.y), a4 = bflo(o.z), a5 = bfhi(o.z), a6 = bflo(o.w), a7 = bfhi(o.w);
;         return ((a0 * a0 + a1 * a1) + (a2 * a2 + a3 * a3)) + ((a4 * a4 + a5 * a5) + (a6 * a6 + a7 * a7));
;     }
;     DI void operator()(const f32x4 (&acc)[2][2][4][2], const Unit& u, int wr, int wc, int fr, int fq, const Pre& pre) const {
;         const int cb = u.pn * 256 + wc * 32 + 8 * fq, row0 = u.pm * 256 + wr * 64 + fr;
; #pragma unroll
;         for (int ai = 0; ai < 2; ++ai) {
;             u32x4v x[4][2];
; #pragma unroll
;             for (int m = 0; m < 4; ++m)
; #pragma unroll
;                 for (int bj = 0; bj < 2; ++bj) x[m][bj] = *(const u32x4v*)(XB + (size_t)(row0 + ai * 128 + m * 16) * 1024 + cb + bj * 128);
; #pragma unroll
;             for (int m = 0; m < 4; ++m) { const int row = row0 + ai * 128 + m * 16;
;                 float ss = upd((u32x4v*)(XB + (size_t)row * 1024 + cb), x[m][0], acc[ai][0][m][0], acc[ai][0][m][1])
;                          + upd((u32x4v*)(XB + (size_t)row * 1024 + cb + 128), x[m][1], acc[ai][1][m][0], acc[ai][1][m][1]);
;                 ss += __shfl_xor(ss, 16); ss += __shfl_xor(ss, 32);
;                 if (fq == 0) SSQ[(size_t)row * 16 + u.pn * 4 + wc] = ss; } }
	v_lshlrev_b32_e32 v120, 16, v108
	v_and_b32_e32 v108, 0xffff0000, v108
	v_lshlrev_b32_e32 v119, 16, v107
	v_and_b32_e32 v107, 0xffff0000, v107
	v_lshlrev_b32_e32 v121, 16, v109
	v_and_b32_e32 v109, 0xffff0000, v109
	v_add_f32_e32 v60, v60, v114
	v_add_f32_e32 v61, v61, v102
	v_add_f32_e32 v62, v62, v115
	v_add_f32_e32 v63, v63, v103
	v_add_f32_e32 v56, v56, v116
	v_add_f32_e32 v57, v57, v104
	v_add_f32_e32 v59, v59, v105
	v_add_f32_e32 v102, v48, v120
	v_add_f32_e32 v103, v49, v108
	v_cvt_pk_bf16_f32 v48, v60, v61
	v_cvt_pk_bf16_f32 v49, v62, v63
	v_lshlrev_b32_e32 v118, 16, v106
	v_and_b32_e32 v106, 0xffff0000, v106
	v_add_f32_e32 v58, v58, v117
	v_add_f32_e32 v54, v54, v119
	v_add_f32_e32 v55, v55, v107
	v_add_f32_e32 v104, v50, v121
	v_add_f32_e32 v105, v51, v109
	v_cvt_pk_bf16_f32 v50, v56, v57
	v_cvt_pk_bf16_f32 v51, v58, v59
	global_store_dwordx4 v[110:111], v[48:51], off nt
	v_lshlrev_b32_e32 v56, 16, v48
	v_lshlrev_b32_e32 v57, 16, v49
	v_and_b32_e32 v48, 0xffff0000, v48
	v_and_b32_e32 v49, 0xffff0000, v49
	v_and_b32_e32 v59, 0xffff0000, v50
	v_and_b32_e32 v61, 0xffff0000, v51
	v_add_f32_e32 v52, v52, v118
	v_add_f32_e32 v53, v53, v106
	v_lshlrev_b32_e32 v58, 16, v50
	v_lshlrev_b32_e32 v60, 16, v51
	v_cvt_pk_bf16_f32 v50, v52, v53
	v_cvt_pk_bf16_f32 v51, v54, v55
	v_mul_f32_e32 v48, v48, v48
	v_mul_f32_e32 v49, v49, v49
	v_mul_f32_e32 v54, v59, v59
	v_mul_f32_e32 v55, v61, v61
	v_and_b32_e32 v61, 0xffff0000, v50
	v_and_b32_e32 v63, 0xffff0000, v51
	v_fmac_f32_e32 v48, v56, v56
	v_fmac_f32_e32 v49, v57, v57
	v_fmac_f32_e32 v54, v58, v58
	v_fmac_f32_e32 v55, v60, v60
	v_lshlrev_b32_e32 v59, 16, v50
	v_lshlrev_b32_e32 v62, 16, v51
	v_add_f32_e32 v48, v48, v49
	v_add_f32_e32 v49, v54, v55
	v_mul_f32_e32 v55, v61, v61
	v_mul_f32_e32 v56, v63, v63
	v_cvt_pk_bf16_f32 v52, v102, v103
	v_cvt_pk_bf16_f32 v53, v104, v105
	v_fmac_f32_e32 v55, v59, v59
	v_and_b32_e32 v103, 0xffff0000, v52
	v_and_b32_e32 v54, 0xffff0000, v53
	v_fmac_f32_e32 v56, v62, v62
	v_lshlrev_b32_e32 v102, 16, v52
	v_add_f32_e32 v48, v48, v49
	v_lshlrev_b32_e32 v49, 16, v53
	v_add_f32_e32 v55, v55, v56
	v_mul_f32_e32 v56, v103, v103
	v_mul_f32_e32 v54, v54, v54
	v_fmac_f32_e32 v56, v102, v102
	v_fmac_f32_e32 v54, v49, v49
	v_add_f32_e32 v49, v56, v54
	v_add_f32_e32 v49, v55, v49
	v_add_f32_e32 v48, v48, v49
	ds_bpermute_b32 v49, v112, v48
	global_store_dwordx4 v[110:111], v[50:53], off offset:256 nt
	s_waitcnt lgkmcnt(0)
	v_add_f32_e32 v48, v48, v49
	ds_bpermute_b32 v49, v113, v48
	s_and_saveexec_b64 s[42:43], s[0:1]
	s_cbranch_execz .LBB0_2265
	v_lshlrev_b64 v[50:51], 6, v[98:99]
	v_lshl_add_u64 v[50:51], s[66:67], 0, v[50:51]
	v_lshl_add_u64 v[50:51], s[26:27], 2, v[50:51]
	s_lshl_b32 s12, s17, 2
	v_lshl_add_u64 v[50:51], v[50:51], 0, s[12:13]
	s_waitcnt lgkmcnt(0)
	v_add_f32_e32 v48, v48, v49
	global_store_dword v[50:51], v48, off
.LBB0_2265:
	s_or_b64 exec, exec, s[42:43]
	s_waitcnt vmcnt(7)
	v_lshlrev_b32_e32 v50, 16, v84
	v_add_f32_e32 v44, v44, v50
	v_and_b32_e32 v50, 0xffff0000, v84
	v_add_f32_e32 v45, v45, v50
	v_cvt_pk_bf16_f32 v44, v44, v45
	v_lshlrev_b32_e32 v45, 16, v85
	v_add_f32_e32 v45, v46, v45
	v_and_b32_e32 v46, 0xffff0000, v85
	v_add_f32_e32 v46, v47, v46
	v_cvt_pk_bf16_f32 v45, v45, v46
	v_lshlrev_b32_e32 v46, 16, v86
	v_add_f32_e32 v40, v40, v46
	v_and_b32_e32 v46, 0xffff0000, v86
	v_add_f32_e32 v41, v41, v46
	v_cvt_pk_bf16_f32 v46, v40, v41
	v_and_b32_e32 v41, 0xffff0000, v87
	v_lshlrev_b32_e32 v40, 16, v87
	v_add_f32_e32 v41, v43, v41
	v_add_f32_e32 v40, v42, v40
	v_cvt_pk_bf16_f32 v47, v40, v41
	v_and_b32_e32 v41, 0xffff0000, v44
	s_waitcnt lgkmcnt(0)
	v_lshl_add_u64 v[48:49], s[64:65], 0, v[100:101]
	v_lshlrev_b32_e32 v40, 16, v44
	v_and_b32_e32 v43, 0xffff0000, v45
	v_mul_f32_e32 v41, v41, v41
	v_lshl_add_u64 v[48:49], v[174:175], 1, v[48:49]
	v_lshlrev_b32_e32 v42, 16, v45
	v_fmac_f32_e32 v41, v40, v40
	v_mul_f32_e32 v40, v43, v43
	global_store_dwordx4 v[48:49], v[44:47], off nt
	v_fmac_f32_e32 v40, v42, v42
	v_add_f32_e32 v40, v41, v40
	v_lshlrev_b32_e32 v44, 16, v46
	v_and_b32_e32 v45, 0xffff0000, v46
	v_lshlrev_b32_e32 v46, 16, v47
	v_and_b32_e32 v47, 0xffff0000, v47
	v_mul_f32_e32 v41, v45, v45
	v_mul_f32_e32 v42, v47, v47
	v_fmac_f32_e32 v41, v44, v44
	v_fmac_f32_e32 v42, v46, v46
	v_add_f32_e32 v41, v41, v42
	v_add_f32_e32 v40, v40, v41
	s_waitcnt vmcnt(7)
	v_lshlrev_b32_e32 v41, 16, v80
	v_add_f32_e32 v36, v36, v41
	v_and_b32_e32 v41, 0xffff0000, v80
	v_add_f32_e32 v37, v37, v41
	v_cvt_pk_bf16_f32 v36, v36, v37
	v_lshlrev_b32_e32 v37, 16, v81
	v_add_f32_e32 v37, v38, v37
	v_and_b32_e32 v38, 0xffff0000, v81
	v_add_f32_e32 v38, v39, v38
	v_cvt_pk_bf16_f32 v37, v37, v38
	v_lshlrev_b32_e32 v38, 16, v82
	v_add_f32_e32 v32, v32, v38
	v_and_b32_e32 v38, 0xffff0000, v82
	v_add_f32_e32 v33, v33, v38
	v_cvt_pk_bf16_f32 v38, v32, v33
	v_and_b32_e32 v33, 0xffff0000, v83
	v_lshlrev_b32_e32 v32, 16, v83
	v_add_f32_e32 v33, v35, v33
	v_add_f32_e32 v32, v34, v32
	v_cvt_pk_bf16_f32 v39, v32, v33
	v_and_b32_e32 v33, 0xffff0000, v36
	v_lshlrev_b32_e32 v32, 16, v36
	v_and_b32_e32 v35, 0xffff0000, v37
	v_mul_f32_e32 v33, v33, v33
	v_lshlrev_b32_e32 v34, 16, v37
	v_fmac_f32_e32 v33, v32, v32
	v_mul_f32_e32 v32, v35, v35
	v_and_b32_e32 v42, 0xffff0000, v38
	v_and_b32_e32 v44, 0xffff0000, v39
	v_fmac_f32_e32 v32, v34, v34
	v_lshlrev_b32_e32 v41, 16, v38
	v_lshlrev_b32_e32 v43, 16, v39
	v_add_f32_e32 v32, v33, v32
	v_mul_f32_e32 v33, v42, v42
	v_mul_f32_e32 v34, v44, v44
	v_fmac_f32_e32 v33, v41, v41
	v_fmac_f32_e32 v34, v43, v43
	v_add_f32_e32 v33, v33, v34
	v_add_f32_e32 v32, v32, v33
	v_add_f32_e32 v32, v40, v32
	ds_bpermute_b32 v33, v112, v32
	global_store_dwordx4 v[48:49], v[36:39], off offset:256 nt
	s_waitcnt lgkmcnt(0)
	v_add_f32_e32 v32, v32, v33
	ds_bpermute_b32 v33, v113, v32
	s_and_saveexec_b64 s[42:43], s[0:1]
	s_cbranch_execz .LBB0_2267
	v_lshlrev_b64 v[34:35], 6, v[94:95]
	v_lshl_add_u64 v[34:35], s[66:67], 0, v[34:35]
	v_lshl_add_u64 v[34:35], s[26:27], 2, v[34:35]
	s_lshl_b32 s12, s17, 2
	v_lshl_add_u64 v[34:35], v[34:35], 0, s[12:13]
	s_waitcnt lgkmcnt(0)
	v_add_f32_e32 v32, v32, v33
	global_store_dword v[34:35], v32, off
; DI unsigned pk2(float lo, float hi) { unsigned r; asm volatile("v_cvt_pk_bf16_f32 %0, %1, %2" : "=v"(r) : "v"(lo), "v"(hi)); return r; }
; DI float bflo(unsigned u) { return __uint_as_float(u << 16); }
; DI float bfhi(unsigned u) { return __uint_as_float(u & 0xffff0000u); }
;     DI float upd(u32x4v* px, const u32x4v x, const f32x4 v0, const f32x4 v1) const {
;         u32x4v o; o.x = pk2(bflo(x.x) + v0[0], bfhi(x.x) + v0[1]); o.y = pk2(bflo(x.y) + v0[2], bfhi(x.y) + v0[3]);
;         o.z = pk2(bflo(x.z) + v1[0], bfhi(x.z) + v1[1]); o.w = pk2(bflo(x.w) + v1[2], bfhi(x.w) + v1[3]); *px = o;
;         const float a0 = bflo(o.x), a1 = bfhi(o.x), a2 = bflo(o.y), a3 = bfhi(o.y), a4 = bflo(o.z), a5 = bfhi(o.z), a6 = bflo(o.w), a7 = bfhi(o.w);
;         return ((a0 * a0 + a1 * a1) + (a2 * a2 + a3 * a3)) + ((a4 * a4 + a5 * a5) + (a6 * a6 + a7 * a7));
;     DI void operator()(const f32x4 (&acc)[2][2][4][2], const Unit& u, int wr, int wc, int fr, int fq, const Pre& pre) const {
;     ...
;             for (int m = 0; m < 4; ++m) { const int row = row0 + ai * 128 + m * 16;
;                 float ss = upd((u32x4v*)(XB + (size_t)row * 1024 + cb), x[m][0], acc[ai][0][m][0], acc[ai][0][m][1])
;                          + upd((u32x4v*)(XB + (size_t)row * 1024 + cb + 128), x[m][1], acc[ai][1][m][0], acc[ai][1][m][1]);
;                 ss += __shfl_xor(ss, 16); ss += __shfl_xor(ss, 32);
;                 if (fq == 0) SSQ[(size_t)row * 16 + u.pn * 4 + wc] = ss; } }
.LBB0_2267:
	s_or_b64 exec, exec, s[42:43]
	s_waitcnt vmcnt(7)
	v_lshlrev_b32_e32 v34, 16, v76
	v_add_f32_e32 v28, v28, v34
	v_and_b32_e32 v34, 0xffff0000, v76
	v_add_f32_e32 v29, v29, v34
	v_cvt_pk_bf16_f32 v28, v28, v29
	v_lshlrev_b32_e32 v29, 16, v77
	v_add_f32_e32 v29, v30, v29
	v_and_b32_e32 v30, 0xffff0000, v77
	v_add_f32_e32 v30, v31, v30
	v_cvt_pk_bf16_f32 v29, v29, v30
	v_lshlrev_b32_e32 v30, 16, v78
	v_add_f32_e32 v24, v24, v30
	v_and_b32_e32 v30, 0xffff0000, v78
	v_add_f32_e32 v25, v25, v30
	v_cvt_pk_bf16_f32 v30, v24, v25
	v_and_b32_e32 v25, 0xffff0000, v79
	v_lshlrev_b32_e32 v24, 16, v79
	v_add_f32_e32 v25, v27, v25
	v_add_f32_e32 v24, v26, v24
	v_cvt_pk_bf16_f32 v31, v24, v25
	v_and_b32_e32 v25, 0xffff0000, v28
	s_waitcnt lgkmcnt(0)
	v_lshl_add_u64 v[32:33], s[64:65], 0, v[96:97]
	v_lshlrev_b32_e32 v24, 16, v28
	v_and_b32_e32 v27, 0xffff0000, v29
	v_mul_f32_e32 v25, v25, v25
	v_lshl_add_u64 v[32:33], v[174:175], 1, v[32:33]
	v_lshlrev_b32_e32 v26, 16, v29
	v_fmac_f32_e32 v25, v24, v24
	v_mul_f32_e32 v24, v27, v27
	global_store_dwordx4 v[32:33], v[28:31], off nt
	v_fmac_f32_e32 v24, v26, v26
	v_add_f32_e32 v24, v25, v24
	v_lshlrev_b32_e32 v28, 16, v30
	v_and_b32_e32 v29, 0xffff0000, v30
	v_lshlrev_b32_e32 v30, 16, v31
	v_and_b32_e32 v31, 0xffff0000, v31
	v_mul_f32_e32 v25, v29, v29
	v_mul_f32_e32 v26, v31, v31
	v_fmac_f32_e32 v25, v28, v28
	v_fmac_f32_e32 v26, v30, v30
	v_add_f32_e32 v25, v25, v26
	v_add_f32_e32 v24, v24, v25
	s_waitcnt vmcnt(7)
	v_lshlrev_b32_e32 v25, 16, v72
	v_add_f32_e32 v20, v20, v25
	v_and_b32_e32 v25, 0xffff0000, v72
	v_add_f32_e32 v21, v21, v25
	v_cvt_pk_bf16_f32 v20, v20, v21
	v_lshlrev_b32_e32 v21, 16, v73
	v_add_f32_e32 v21, v22, v21
	v_and_b32_e32 v22, 0xffff0000, v73
	v_add_f32_e32 v22, v23, v22
	v_cvt_pk_bf16_f32 v21, v21, v22
	v_lshlrev_b32_e32 v22, 16, v74
	v_add_f32_e32 v16, v16, v22
	v_and_b32_e32 v22, 0xffff0000, v74
	v_add_f32_e32 v17, v17, v22
	v_cvt_pk_bf16_f32 v22, v16, v17
	v_and_b32_e32 v17, 0xffff0000, v75
	v_lshlrev_b32_e32 v16, 16, v75
	v_add_f32_e32 v17, v19, v17
	v_add_f32_e32 v16, v18, v16
	v_cvt_pk_bf16_f32 v23, v16, v17
	v_and_b32_e32 v17, 0xffff0000, v20
	v_lshlrev_b32_e32 v16, 16, v20
	v_and_b32_e32 v19, 0xffff0000, v21
	v_mul_f32_e32 v17, v17, v17
	v_lshlrev_b32_e32 v18, 16, v21
	v_fmac_f32_e32 v17, v16, v16
	v_mul_f32_e32 v16, v19, v19
	v_and_b32_e32 v26, 0xffff0000, v22
	v_and_b32_e32 v28, 0xffff0000, v23
	v_fmac_f32_e32 v16, v18, v18
	v_lshlrev_b32_e32 v25, 16, v22
	v_lshlrev_b32_e32 v27, 16, v23
	v_add_f32_e32 v16, v17, v16
	v_mul_f32_e32 v17, v26, v26
	v_mul_f32_e32 v18, v28, v28
	v_fmac_f32_e32 v17, v25, v25
	v_fmac_f32_e32 v18, v27, v27
	v_add_f32_e32 v17, v17, v18
	v_add_f32_e32 v16, v16, v17
	v_add_f32_e32 v16, v24, v16
	ds_bpermute_b32 v17, v112, v16
	global_store_dwordx4 v[32:33], v[20:23], off offset:256 nt
	s_waitcnt lgkmcnt(0)
	v_add_f32_e32 v16, v16, v17
	ds_bpermute_b32 v17, v113, v16
	s_and_saveexec_b64 s[42:43], s[0:1]
	s_cbranch_execz .LBB0_2269
	v_lshlrev_b64 v[18:19], 6, v[90:91]
	v_lshl_add_u64 v[18:19], s[66:67], 0, v[18:19]
	v_lshl_add_u64 v[18:19], s[26:27], 2, v[18:19]
	s_lshl_b32 s12, s17, 2
	v_lshl_add_u64 v[18:19], v[18:19], 0, s[12:13]
	s_waitcnt lgkmcnt(0)
	v_add_f32_e32 v16, v16, v17
	global_store_dword v[18:19], v16, off
.LBB0_2269:
	s_or_b64 exec, exec, s[42:43]
	s_waitcnt vmcnt(7)
	v_lshlrev_b32_e32 v18, 16, v68
	v_add_f32_e32 v12, v12, v18
	v_and_b32_e32 v18, 0xffff0000, v68
	v_add_f32_e32 v13, v13, v18
	v_cvt_pk_bf16_f32 v12, v12, v13
	v_lshlrev_b32_e32 v13, 16, v69
	v_add_f32_e32 v13, v14, v13
	v_and_b32_e32 v14, 0xffff0000, v69
	v_add_f32_e32 v14, v15, v14
	v_cvt_pk_bf16_f32 v13, v13, v14
	v_lshlrev_b32_e32 v14, 16, v70
	v_add_f32_e32 v8, v8, v14
	v_and_b32_e32 v14, 0xffff0000, v70
	v_add_f32_e32 v9, v9, v14
	v_cvt_pk_bf16_f32 v14, v8, v9
	v_and_b32_e32 v9, 0xffff0000, v71
	v_lshlrev_b32_e32 v8, 16, v71
	v_add_f32_e32 v9, v11, v9
	v_add_f32_e32 v8, v10, v8
	v_cvt_pk_bf16_f32 v15, v8, v9
	v_and_b32_e32 v9, 0xffff0000, v12
	s_waitcnt lgkmcnt(0)
	v_lshl_add_u64 v[16:17], s[64:65], 0, v[92:93]
	v_lshlrev_b32_e32 v8, 16, v12
	v_and_b32_e32 v11, 0xffff0000, v13
	v_mul_f32_e32 v9, v9, v9
	v_lshl_add_u64 v[16:17], v[174:175], 1, v[16:17]
	v_lshlrev_b32_e32 v10, 16, v13
	v_fmac_f32_e32 v9, v8, v8
	v_mul_f32_e32 v8, v11, v11
	global_store_dwordx4 v[16:17], v[12:15], off nt
	v_fmac_f32_e32 v8, v10, v10
	v_add_f32_e32 v8, v9, v8
	v_lshlrev_b32_e32 v12, 16, v14
	v_and_b32_e32 v13, 0xffff0000, v14
	v_lshlrev_b32_e32 v14, 16, v15
	v_and_b32_e32 v15, 0xffff0000, v15
	v_mul_f32_e32 v9, v13, v13
	v_mul_f32_e32 v10, v15, v15
	v_fmac_f32_e32 v9, v12, v12
	v_fmac_f32_e32 v10, v14, v14
	v_add_f32_e32 v9, v9, v10
	v_add_f32_e32 v8, v8, v9
	s_waitcnt vmcnt(7)
	v_lshlrev_b32_e32 v9, 16, v64
	v_add_f32_e32 v4, v4, v9
	v_and_b32_e32 v9, 0xffff0000, v64
	v_add_f32_e32 v5, v5, v9
	v_cvt_pk_bf16_f32 v4, v4, v5
	v_lshlrev_b32_e32 v5, 16, v65
	v_add_f32_e32 v5, v6, v5
	v_and_b32_e32 v6, 0xffff0000, v65
	v_add_f32_e32 v6, v7, v6
	v_cvt_pk_bf16_f32 v5, v5, v6
	v_lshlrev_b32_e32 v6, 16, v66
	v_add_f32_e32 v0, v0, v6
	v_and_b32_e32 v6, 0xffff0000, v66
	v_add_f32_e32 v1, v1, v6
	v_cvt_pk_bf16_f32 v6, v0, v1
	v_and_b32_e32 v1, 0xffff0000, v67
	v_lshlrev_b32_e32 v0, 16, v67
	v_add_f32_e32 v1, v3, v1
	v_add_f32_e32 v0, v2, v0
	v_cvt_pk_bf16_f32 v7, v0, v1
	v_and_b32_e32 v1, 0xffff0000, v4
	v_lshlrev_b32_e32 v0, 16, v4
	v_and_b32_e32 v3, 0xffff0000, v5
	v_mul_f32_e32 v1, v1, v1
	v_lshlrev_b32_e32 v2, 16, v5
	v_fmac_f32_e32 v1, v0, v0
	v_mul_f32_e32 v0, v3, v3
	v_and_b32_e32 v10, 0xffff0000, v6
	v_and_b32_e32 v12, 0xffff0000, v7
	v_fmac_f32_e32 v0, v2, v2
	v_lshlrev_b32_e32 v9, 16, v6
	v_lshlrev_b32_e32 v11, 16, v7
	v_add_f32_e32 v0, v1, v0
	v_mul_f32_e32 v1, v10, v10
	v_mul_f32_e32 v2, v12, v12
	v_fmac_f32_e32 v1, v9, v9
	v_fmac_f32_e32 v2, v11, v11
	v_add_f32_e32 v1, v1, v2
	v_add_f32_e32 v0, v0, v1
	v_add_f32_e32 v0, v8, v0
	ds_bpermute_b32 v1, v112, v0
	global_store_dwordx4 v[16:17], v[4:7], off offset:256 nt
	s_waitcnt lgkmcnt(0)
	v_add_f32_e32 v0, v0, v1
	ds_bpermute_b32 v1, v113, v0
	s_and_saveexec_b64 s[42:43], s[0:1]
	s_cbranch_execz .LBB0_2221
	v_readlane_b32 s60, v254, 28
	v_lshlrev_b64 v[2:3], 6, v[88:89]
	v_readlane_b32 s74, v254, 42
	v_readlane_b32 s75, v254, 43
	s_lshl_b32 s12, s17, 2
	s_waitcnt lgkmcnt(0)
	v_add_f32_e32 v0, v0, v1
	v_lshl_add_u64 v[2:3], s[74:75], 0, v[2:3]
	v_lshl_add_u64 v[2:3], s[26:27], 2, v[2:3]
	v_lshl_add_u64 v[2:3], v[2:3], 0, s[12:13]
	v_readlane_b32 s61, v254, 29
	v_readlane_b32 s62, v254, 30
	v_readlane_b32 s63, v254, 31
	v_readlane_b32 s64, v254, 32
	v_readlane_b32 s65, v254, 33
	v_readlane_b32 s66, v254, 34
	v_readlane_b32 s67, v254, 35
	v_readlane_b32 s68, v254, 36
	v_readlane_b32 s69, v254, 37
	v_readlane_b32 s70, v254, 38
	v_readlane_b32 s71, v254, 39
	v_readlane_b32 s72, v254, 40
	v_readlane_b32 s73, v254, 41
	global_store_dword v[2:3], v0, off
	s_branch .LBB0_2221

;     DI void row(const f32x4 (&a4)[2][2], const Unit& u, int ai, int m, int wr, int wc, int fr, int fq) const {
;         const int cb = u.pn * 256 + wc * 32 + 8 * fq, row = u.pm * 256 + wr * 64 + fr + ai * 128 + m * 16;
;         u32x4v* p0 = (u32x4v*)(XB + (size_t)row * 1024 + cb); u32x4v* p1 = (u32x4v*)(XB + (size_t)row * 1024 + cb + 128);
;         const u32x4v x0 = *p0, x1 = *p1;
;         float ss = upd(p0, x0, a4[0][0], a4[0][1]) + upd(p1, x1, a4[1][0], a4[1][1]);
;         ss += __shfl_xor(ss, 16); ss += __shfl_xor(ss, 32);
;         if (fq == 0) SSQ[(size_t)row * 16 + u.pn * 4 + wc] = ss;
;     }
; template <class Epi> DI void gemm_fixup(int N, int K, const Epi& E, const float* part, int tid) {
;     ...
;     for (int it = blockIdx.x; it < S.ntail * 8; it += gridDim.x) { const int j = it >> 3, ai = (it >> 2) & 1, m = it & 3; Unit u; S.map(S.nwhole * S.G + j, u);
;         f32x4 a4[2][2];
; #pragma unroll
;         for (int b = 0; b < 2; ++b)
; #pragma unroll
;             for (int n = 0; n < 2; ++n) { const f32x4* pp = (const f32x4*)part + ((size_t)(j * S.S) * 32 + (((ai * 2 + b) * 4 + m) * 2 + n)) * 512 + tid;
;                 f32x4 v0 = {0.f, 0.f, 0.f, 0.f}, v1 = v0, v2 = v0, v3 = v0;
;                 for (int sl = 0; sl + 3 < S.S; sl += 4) { v0 += pp[(size_t)sl * 16384]; v1 += pp[(size_t)(sl + 1) * 16384]; v2 += pp[(size_t)(sl + 2) * 16384]; v3 += pp[(size_t)(sl + 3) * 16384]; }
;                 for (int sl = S.S & ~3; sl < S.S; ++sl) v0 += pp[(size_t)sl * 16384];
;                 a4[b][n] = (v0 + v1) + (v2 + v3); }
;         E.row(a4, u, ai, m, wr, wc, fr, fq); }
.LBB0_2363:
	s_add_i32 s8, s15, s16
	s_ashr_i32 s9, s8, 31
	s_lshr_b32 s9, s9, 27
	s_add_i32 s9, s8, s9
	s_ashr_i32 s12, s9, 5
	s_lshl_b32 s13, s12, 3
	s_sub_i32 s12, 0x83, s13
	s_min_i32 s15, s12, 8
	s_abs_i32 s12, s15
	v_cvt_f32_u32_e32 v1, s12
	s_sub_i32 s17, 0, s12
	s_andn2_b32 s9, s9, 31
	s_sub_i32 s8, s8, s9
	v_rcp_iflag_f32_e32 v1, v1
	s_abs_i32 s9, s8
	s_xor_b32 s16, s8, s15
	s_ashr_i32 s16, s16, 31
	v_mul_f32_e32 v1, 0x4f7ffffe, v1
	v_cvt_u32_f32_e32 v1, v1
	v_readlane_b32 s40, v254, 28
	v_readlane_b32 s52, v254, 40
	v_readlane_b32 s53, v254, 41
	v_readfirstlane_b32 s18, v1
	s_mul_i32 s17, s17, s18
	s_mul_hi_u32 s17, s18, s17
	s_add_i32 s18, s18, s17
	s_mul_hi_u32 s17, s9, s18
	s_mul_i32 s18, s17, s12
	s_sub_i32 s9, s9, s18
	s_add_i32 s19, s17, 1
	s_sub_i32 s18, s9, s12
	s_cmp_ge_u32 s9, s12
	s_cselect_b32 s17, s19, s17
	s_cselect_b32 s9, s18, s9
	s_add_i32 s18, s17, 1
	s_cmp_ge_u32 s9, s12
	s_cselect_b32 s9, s18, s17
	s_xor_b32 s9, s9, s16
	s_sub_i32 s12, s9, s16
	s_mul_i32 s9, s12, s15
	s_sub_i32 s8, s8, s9
	s_add_i32 s13, s13, s8
	s_lshl_b32 s8, s13, 8
	s_lshl_b32 s6, s6, 7
	v_lshl_or_b32 v1, s7, 4, v81
	s_or_b32 s6, s8, s6
	v_add_u32_e32 v78, s6, v1
	v_ashrrev_i32_e32 v79, 31, v78
	v_lshl_or_b32 v84, s12, 8, v80
	v_lshlrev_b64 v[86:87], 11, v[78:79]
	v_lshl_add_u64 v[86:87], s[52:53], 0, v[86:87]
	v_ashrrev_i32_e32 v85, 31, v84
	v_lshl_add_u64 v[92:93], v[84:85], 1, v[86:87]
	global_load_dwordx4 v[84:87], v[92:93], off
	global_load_dwordx4 v[88:91], v[92:93], off offset:256
	v_pk_add_f32 v[14:15], v[62:63], v[14:15]
	v_pk_add_f32 v[12:13], v[56:57], v[12:13]
	v_pk_add_f32 v[56:57], v[60:61], v[66:67]
	v_pk_add_f32 v[58:59], v[58:59], v[64:65]
	v_pk_add_f32 v[10:11], v[50:51], v[10:11]
	v_pk_add_f32 v[8:9], v[44:45], v[8:9]
	v_pk_add_f32 v[44:45], v[48:49], v[54:55]
	v_pk_add_f32 v[46:47], v[46:47], v[52:53]
	v_pk_add_f32 v[6:7], v[42:43], v[6:7]
	v_pk_add_f32 v[4:5], v[32:33], v[4:5]
	v_pk_add_f32 v[32:33], v[40:41], v[36:37]
	v_pk_add_f32 v[34:35], v[38:39], v[34:35]
	v_pk_add_f32 v[18:19], v[72:73], v[18:19]
	v_pk_add_f32 v[16:17], v[68:69], v[16:17]
	v_pk_add_f32 v[36:37], v[70:71], v[76:77]
	v_pk_add_f32 v[2:3], v[2:3], v[74:75]
	v_pk_add_f32 v[14:15], v[58:59], v[14:15]
	v_pk_add_f32 v[12:13], v[56:57], v[12:13]
	v_pk_add_f32 v[10:11], v[46:47], v[10:11]
	v_pk_add_f32 v[8:9], v[44:45], v[8:9]
	v_pk_add_f32 v[6:7], v[34:35], v[6:7]
	v_pk_add_f32 v[4:5], v[32:33], v[4:5]
	v_pk_add_f32 v[2:3], v[2:3], v[18:19]
	v_pk_add_f32 v[16:17], v[36:37], v[16:17]
	v_readlane_b32 s41, v254, 29
	v_readlane_b32 s42, v254, 30
	v_readlane_b32 s43, v254, 31
	v_readlane_b32 s44, v254, 32
	v_readlane_b32 s45, v254, 33
	v_readlane_b32 s46, v254, 34
	v_readlane_b32 s47, v254, 35
	v_readlane_b32 s48, v254, 36
	v_readlane_b32 s49, v254, 37
	v_readlane_b32 s50, v254, 38
	v_readlane_b32 s51, v254, 39
	v_readlane_b32 s54, v254, 42
	v_readlane_b32 s55, v254, 43
	s_waitcnt vmcnt(1)
	v_lshlrev_b32_e32 v1, 16, v84
	v_and_b32_e32 v18, 0xffff0000, v84
	v_lshlrev_b32_e32 v19, 16, v85
	v_and_b32_e32 v31, 0xffff0000, v85
	v_lshlrev_b32_e32 v32, 16, v86
	v_and_b32_e32 v33, 0xffff0000, v86
	v_lshlrev_b32_e32 v34, 16, v87
	v_and_b32_e32 v35, 0xffff0000, v87
	s_waitcnt vmcnt(0)
	v_lshlrev_b32_e32 v36, 16, v88
	v_and_b32_e32 v37, 0xffff0000, v88
	v_lshlrev_b32_e32 v38, 16, v89
	v_and_b32_e32 v39, 0xffff0000, v89
	v_lshlrev_b32_e32 v40, 16, v90
	v_and_b32_e32 v41, 0xffff0000, v90
	v_lshlrev_b32_e32 v42, 16, v91
	v_and_b32_e32 v43, 0xffff0000, v91
	v_add_f32_e32 v1, v4, v1
	v_add_f32_e32 v4, v5, v18
	v_add_f32_e32 v5, v6, v19
	v_add_f32_e32 v6, v7, v31
	v_add_f32_e32 v7, v8, v32
	v_add_f32_e32 v8, v9, v33
	v_add_f32_e32 v9, v10, v34
	v_add_f32_e32 v10, v11, v35
	v_add_f32_e32 v11, v12, v36
	v_add_f32_e32 v12, v13, v37
	v_add_f32_e32 v13, v14, v38
	v_add_f32_e32 v14, v15, v39
	v_add_f32_e32 v15, v16, v40
	v_add_f32_e32 v16, v17, v41
	v_add_f32_e32 v17, v2, v42
	v_add_f32_e32 v18, v3, v43
	v_cvt_pk_bf16_f32 v2, v1, v4
	v_cvt_pk_bf16_f32 v3, v5, v6
	v_cvt_pk_bf16_f32 v4, v7, v8
	v_cvt_pk_bf16_f32 v5, v9, v10
	global_store_dwordx4 v[92:93], v[2:5], off nt
	v_lshlrev_b32_e32 v1, 16, v2
	v_lshlrev_b32_e32 v7, 16, v3
	v_and_b32_e32 v2, 0xffff0000, v2
	v_and_b32_e32 v3, 0xffff0000, v3
	v_and_b32_e32 v9, 0xffff0000, v4
	v_and_b32_e32 v19, 0xffff0000, v5
	v_lshlrev_b32_e32 v8, 16, v4
	v_lshlrev_b32_e32 v10, 16, v5
	v_cvt_pk_bf16_f32 v4, v11, v12
	v_mul_f32_e32 v2, v2, v2
	v_mul_f32_e32 v3, v3, v3
	v_mul_f32_e32 v9, v9, v9
	v_mul_f32_e32 v11, v19, v19
	v_fmac_f32_e32 v2, v1, v1
	v_fmac_f32_e32 v3, v7, v7
	v_fmac_f32_e32 v9, v8, v8
	v_fmac_f32_e32 v11, v10, v10
	v_add_f32_e32 v1, v2, v3
	v_add_f32_e32 v2, v9, v11
	v_and_b32_e32 v3, 0xffff0000, v4
	v_cvt_pk_bf16_f32 v5, v13, v14
	v_add_f32_e32 v1, v1, v2
	v_lshlrev_b32_e32 v2, 16, v4
	v_and_b32_e32 v9, 0xffff0000, v5
	v_mul_f32_e32 v3, v3, v3
	v_lshlrev_b32_e32 v8, 16, v5
	v_fmac_f32_e32 v3, v2, v2
	v_mul_f32_e32 v2, v9, v9
	v_cvt_pk_bf16_f32 v6, v15, v16
	v_cvt_pk_bf16_f32 v7, v17, v18
	v_fmac_f32_e32 v2, v8, v8
	v_and_b32_e32 v11, 0xffff0000, v6
	v_and_b32_e32 v13, 0xffff0000, v7
	v_lshlrev_b32_e32 v10, 16, v6
	v_lshlrev_b32_e32 v12, 16, v7
	v_add_f32_e32 v2, v3, v2
	v_mul_f32_e32 v3, v11, v11
	v_mul_f32_e32 v8, v13, v13
	v_fmac_f32_e32 v3, v10, v10
	v_fmac_f32_e32 v8, v12, v12
	v_add_f32_e32 v3, v3, v8
	v_add_f32_e32 v2, v2, v3
	v_and_b32_e32 v3, 64, v82
	v_add_f32_e32 v1, v1, v2
	v_xor_b32_e32 v2, 16, v82
	v_add_u32_e32 v3, 64, v3
	v_cmp_lt_i32_e32 vcc, v2, v3
	global_store_dwordx4 v[92:93], v[4:7], off offset:256 nt
	s_nop 0
	v_cndmask_b32_e32 v2, v82, v2, vcc
	v_lshlrev_b32_e32 v2, 2, v2
	ds_bpermute_b32 v2, v2, v1
	s_waitcnt lgkmcnt(0)
	v_add_f32_e32 v1, v1, v2
	v_xor_b32_e32 v2, 32, v82
	v_cmp_lt_i32_e32 vcc, v2, v3
	s_nop 1
	v_cndmask_b32_e32 v2, v82, v2, vcc
	v_lshlrev_b32_e32 v2, 2, v2
	ds_bpermute_b32 v2, v2, v1
	s_and_saveexec_b64 s[6:7], s[0:1]
	s_xor_b64 s[8:9], exec, s[6:7]
	s_cbranch_execz .LBB0_2337
	v_readlane_b32 s40, v254, 28
	s_waitcnt lgkmcnt(0)
	v_add_f32_e32 v1, v1, v2
	s_lshl_b32 s6, s12, 2
	v_lshlrev_b64 v[2:3], 6, v[78:79]
	v_readlane_b32 s54, v254, 42
	v_readlane_b32 s55, v254, 43
	s_ashr_i32 s7, s6, 31
	v_mov_b32_e32 v31, v0
	v_lshl_add_u64 v[2:3], s[54:55], 0, v[2:3]
	v_lshl_add_u64 v[2:3], s[6:7], 2, v[2:3]
	v_lshl_add_u64 v[2:3], v[2:3], 0, v[30:31]
	v_readlane_b32 s41, v254, 29
	v_readlane_b32 s42, v254, 30
	v_readlane_b32 s43, v254, 31
	v_readlane_b32 s44, v254, 32
	v_readlane_b32 s45, v254, 33
	v_readlane_b32 s46, v254, 34
	v_readlane_b32 s47, v254, 35
	v_readlane_b32 s48, v254, 36
	v_readlane_b32 s49, v254, 37
	v_readlane_b32 s50, v254, 38
	v_readlane_b32 s51, v254, 39
	v_readlane_b32 s52, v254, 40
	v_readlane_b32 s53, v254, 41
	global_store_dword v[2:3], v1, off
	s_branch .LBB0_2337

; template <class Epi, class Sched>
; __device__ __forceinline__ void gemm_phase(PG8_LAS unsigned char* lds, const Gemm g, const Sched& S, const Epi& E) {
;     ...
;             else { f32x4* pp = (f32x4*)g.part + (size_t)cur.part * 32 * 512 + tid;
; #pragma unroll
;                 for (int a = 0; a < 2; ++a)
; #pragma unroll
;                     for (int b = 0; b < 2; ++b)
; #pragma unroll
;                         for (int m = 0; m < 4; ++m)
; #pragma unroll
;                             for (int n = 0; n < 2; ++n) pp[(size_t)(((a * 2 + b) * 4 + m) * 2 + n) * 512] = acc[a][b][m][n]; }
.LBB0_2576:
	s_lshl_b64 s[38:39], s[8:9], 18
	v_lshl_add_u64 v[128:129], v[166:167], 0, s[38:39]
	v_add_co_u32_e32 v130, vcc, 0x2000, v128
	s_mov_b32 s8, 0x10000
	s_nop 0
	v_addc_co_u32_e32 v131, vcc, 0, v129, vcc
	global_store_dwordx4 v[130:131], v[120:123], off nt
	v_add_co_u32_e32 v130, vcc, 0x4000, v128
	global_store_dwordx4 v[128:129], v[124:127], off nt
	s_nop 0
	v_addc_co_u32_e32 v131, vcc, 0, v129, vcc
	global_store_dwordx4 v[130:131], v[108:111], off nt
	v_add_co_u32_e32 v130, vcc, 0x6000, v128
	s_mov_b64 s[38:39], 0
	s_nop 0
	v_addc_co_u32_e32 v131, vcc, 0, v129, vcc
	global_store_dwordx4 v[130:131], v[104:107], off nt
	v_add_co_u32_e32 v130, vcc, 0x8000, v128
	s_nop 1
	v_addc_co_u32_e32 v131, vcc, 0, v129, vcc
	global_store_dwordx4 v[130:131], v[92:95], off nt
	v_add_co_u32_e32 v130, vcc, 0xa000, v128
	s_nop 1
	v_addc_co_u32_e32 v131, vcc, 0, v129, vcc
	global_store_dwordx4 v[130:131], v[88:91], off nt
	v_add_co_u32_e32 v130, vcc, 0xc000, v128
	s_nop 1
	v_addc_co_u32_e32 v131, vcc, 0, v129, vcc
	global_store_dwordx4 v[130:131], v[76:79], off nt
	v_add_co_u32_e32 v130, vcc, 0xe000, v128
	s_nop 1
	v_addc_co_u32_e32 v131, vcc, 0, v129, vcc
	global_store_dwordx4 v[130:131], v[72:75], off nt
	v_add_co_u32_e32 v130, vcc, s8, v128
	s_mov_b32 s8, 0x12000
	s_nop 0
	v_addc_co_u32_e32 v131, vcc, 0, v129, vcc
	global_store_dwordx4 v[130:131], v[116:119], off nt
	v_add_co_u32_e32 v130, vcc, s8, v128
	s_mov_b32 s8, 0x14000
	s_nop 0
	v_addc_co_u32_e32 v131, vcc, 0, v129, vcc
	global_store_dwordx4 v[130:131], v[112:115], off nt
	v_add_co_u32_e32 v130, vcc, s8, v128
	s_mov_b32 s8, 0x16000
	s_nop 0
	v_addc_co_u32_e32 v131, vcc, 0, v129, vcc
	global_store_dwordx4 v[130:131], v[100:103], off nt
	v_add_co_u32_e32 v130, vcc, s8, v128
	s_mov_b32 s8, 0x18000
	s_nop 0
	v_addc_co_u32_e32 v131, vcc, 0, v129, vcc
	global_store_dwordx4 v[130:131], v[96:99], off nt
	v_add_co_u32_e32 v130, vcc, s8, v128
	s_mov_b32 s8, 0x1a000
	s_nop 0
	v_addc_co_u32_e32 v131, vcc, 0, v129, vcc
	global_store_dwordx4 v[130:131], v[84:87], off nt
	v_add_co_u32_e32 v130, vcc, s8, v128
	s_mov_b32 s8, 0x1c000
	s_nop 0
	v_addc_co_u32_e32 v131, vcc, 0, v129, vcc
	global_store_dwordx4 v[130:131], v[80:83], off nt
	v_add_co_u32_e32 v130, vcc, s8, v128
	s_mov_b32 s8, 0x1e000
	s_nop 0
	v_addc_co_u32_e32 v131, vcc, 0, v129, vcc
	global_store_dwordx4 v[130:131], v[68:71], off nt
	v_add_co_u32_e32 v130, vcc, s8, v128
	s_mov_b32 s8, 0x20000
	s_nop 0
	v_addc_co_u32_e32 v131, vcc, 0, v129, vcc
	global_store_dwordx4 v[130:131], v[64:67], off nt
	v_add_co_u32_e32 v130, vcc, s8, v128
	s_nop 1
	v_addc_co_u32_e32 v131, vcc, 0, v129, vcc
	global_store_dwordx4 v[130:131], v[60:63], off nt
	v_add_co_u32_e32 v130, vcc, s55, v128
	s_nop 1
	v_addc_co_u32_e32 v131, vcc, 0, v129, vcc
	global_store_dwordx4 v[130:131], v[56:59], off nt
	v_add_co_u32_e32 v130, vcc, s56, v128
	s_nop 1
	v_addc_co_u32_e32 v131, vcc, 0, v129, vcc
	global_store_dwordx4 v[130:131], v[44:47], off nt
	v_add_co_u32_e32 v130, vcc, s57, v128
	s_nop 1
	v_addc_co_u32_e32 v131, vcc, 0, v129, vcc
	global_store_dwordx4 v[130:131], v[40:43], off nt
	v_add_co_u32_e32 v130, vcc, s58, v128
	s_nop 1
	v_addc_co_u32_e32 v131, vcc, 0, v129, vcc
	global_store_dwordx4 v[130:131], v[28:31], off nt
	v_add_co_u32_e32 v130, vcc, s59, v128
	s_nop 1
	v_addc_co_u32_e32 v131, vcc, 0, v129, vcc
	global_store_dwordx4 v[130:131], v[24:27], off nt
	v_add_co_u32_e32 v130, vcc, s60, v128
	s_nop 1
	v_addc_co_u32_e32 v131, vcc, 0, v129, vcc
	global_store_dwordx4 v[130:131], v[12:15], off nt
	v_add_co_u32_e32 v130, vcc, s61, v128
	s_nop 1
	v_addc_co_u32_e32 v131, vcc, 0, v129, vcc
	global_store_dwordx4 v[130:131], v[8:11], off nt
	v_add_co_u32_e32 v130, vcc, s87, v128
	s_nop 1
	v_addc_co_u32_e32 v131, vcc, 0, v129, vcc
	global_store_dwordx4 v[130:131], v[52:55], off nt
	v_add_co_u32_e32 v130, vcc, s88, v128
	s_nop 1
	v_addc_co_u32_e32 v131, vcc, 0, v129, vcc
	global_store_dwordx4 v[130:131], v[48:51], off nt
	v_add_co_u32_e32 v130, vcc, s89, v128
	s_nop 1
	v_addc_co_u32_e32 v131, vcc, 0, v129, vcc
	global_store_dwordx4 v[130:131], v[36:39], off nt
	v_add_co_u32_e32 v130, vcc, s90, v128
	s_nop 1
	v_addc_co_u32_e32 v131, vcc, 0, v129, vcc
	global_store_dwordx4 v[130:131], v[32:35], off nt
	v_add_co_u32_e32 v130, vcc, s91, v128
	s_nop 1
	v_addc_co_u32_e32 v131, vcc, 0, v129, vcc
	global_store_dwordx4 v[130:131], v[20:23], off nt
	v_add_co_u32_e32 v130, vcc, s92, v128
	s_nop 1
	v_addc_co_u32_e32 v131, vcc, 0, v129, vcc
	global_store_dwordx4 v[130:131], v[16:19], off nt
	v_add_co_u32_e32 v130, vcc, 0x3c000, v128
	s_nop 1
	v_addc_co_u32_e32 v131, vcc, 0, v129, vcc
	v_add_co_u32_e32 v128, vcc, 0x3e000, v128
	global_store_dwordx4 v[130:131], v[4:7], off nt
	s_nop 0
	v_addc_co_u32_e32 v129, vcc, 0, v129, vcc
	global_store_dwordx4 v[128:129], v[0:3], off nt
;     DI void operator()(const f32x4 (&acc)[2][2][4][2], const Unit& u, int wr, int wc, int fr, int fq, const Pre& pre) const {
;         const int cb = u.pn * 256 + wc * 32 + 8 * fq, row0 = u.pm * 256 + wr * 64 + fr;
; #pragma unroll
;         for (int ai = 0; ai < 2; ++ai) {
;             u32x4v x[4][2];
; #pragma unroll
;             for (int m = 0; m < 4; ++m)
; #pragma unroll
;                 for (int bj = 0; bj < 2; ++bj) x[m][bj] = *(const u32x4v*)(XB + (size_t)(row0 + ai * 128 + m * 16) * 1024 + cb + bj * 128);
; #pragma unroll
;             for (int m = 0; m < 4; ++m) { const int row = row0 + ai * 128 + m * 16;
;                 float ss = upd((u32x4v*)(XB + (size_t)row * 1024 + cb), x[m][0], acc[ai][0][m][0], acc[ai][0][m][1])
;                          + upd((u32x4v*)(XB + (size_t)row * 1024 + cb + 128), x[m][1], acc[ai][1][m][0], acc[ai][1][m][1]);
;                 ss += __shfl_xor(ss, 16); ss += __shfl_xor(ss, 32);
;                 if (fq == 0) SSQ[(size_t)row * 16 + u.pn * 4 + wc] = ss; } }
.LBB0_2577:
	s_andn2_b64 vcc, exec, s[38:39]
	s_cbranch_vccnz .LBB0_2545
	v_lshl_or_b32 v174, s18, 8, v157
	v_readlane_b32 s64, v254, 28
	v_lshl_add_u32 v176, s26, 8, v153
	v_ashrrev_i32_e32 v175, 31, v174
	v_readlane_b32 s65, v254, 29
	v_readlane_b32 s66, v254, 30
	v_readlane_b32 s67, v254, 31
	v_readlane_b32 s76, v254, 40
	v_readlane_b32 s77, v254, 41
	v_lshlrev_b64 v[128:129], 1, v[174:175]
	v_readlane_b32 s78, v254, 42
	v_readlane_b32 s79, v254, 43
	s_mov_b64 s[64:65], s[76:77]
	v_ashrrev_i32_e32 v177, 31, v176
	v_lshl_add_u64 v[178:179], s[64:65], 0, v[128:129]
	v_lshlrev_b64 v[130:131], 11, v[176:177]
	v_lshl_add_u64 v[132:133], v[178:179], 0, v[130:131]
	global_load_dwordx4 v[196:199], v[132:133], off
	global_load_dwordx4 v[200:203], v[132:133], off offset:256
	v_or_b32_e32 v186, 16, v176
	v_or_b32_e32 v182, 32, v176
	v_or_b32_e32 v180, 48, v176
	v_ashrrev_i32_e32 v187, 31, v186
	v_ashrrev_i32_e32 v183, 31, v182
	v_ashrrev_i32_e32 v181, 31, v180
	v_lshlrev_b64 v[190:191], 11, v[186:187]
	v_lshlrev_b64 v[188:189], 11, v[182:183]
	v_lshlrev_b64 v[184:185], 11, v[180:181]
	v_lshl_add_u64 v[130:131], s[64:65], 0, v[130:131]
	v_lshl_add_u64 v[132:133], v[178:179], 0, v[190:191]
	v_lshl_add_u64 v[134:135], v[178:179], 0, v[188:189]
	v_lshl_add_u64 v[204:205], v[178:179], 0, v[184:185]
	v_lshl_add_u64 v[206:207], v[130:131], 0, v[128:129]
	global_load_dwordx4 v[148:151], v[132:133], off
	global_load_dwordx4 v[144:147], v[132:133], off offset:256
	global_load_dwordx4 v[140:143], v[134:135], off
	global_load_dwordx4 v[136:139], v[134:135], off offset:256
	s_nop 0
	global_load_dwordx4 v[132:135], v[204:205], off
	global_load_dwordx4 v[128:131], v[204:205], off offset:256
	s_lshl_b32 s18, s18, 2
	s_mov_b64 s[66:67], s[78:79]
	s_ashr_i32 s19, s18, 31
	v_readlane_b32 s68, v254, 32
	v_readlane_b32 s69, v254, 33
	v_readlane_b32 s70, v254, 34
	v_readlane_b32 s71, v254, 35
	v_readlane_b32 s72, v254, 36
	v_readlane_b32 s73, v254, 37
	v_readlane_b32 s74, v254, 38
	v_readlane_b32 s75, v254, 39
	s_waitcnt vmcnt(0)
	v_lshlrev_b32_e32 v204, 16, v196
	v_and_b32_e32 v196, 0xffff0000, v196
	v_lshlrev_b32_e32 v205, 16, v197
	v_and_b32_e32 v197, 0xffff0000, v197
	v_lshlrev_b32_e32 v208, 16, v198
	v_and_b32_e32 v198, 0xffff0000, v198
	v_lshlrev_b32_e32 v209, 16, v199
	v_and_b32_e32 v199, 0xffff0000, v199
	v_lshlrev_b32_e32 v212, 16, v202
	v_and_b32_e32 v202, 0xffff0000, v202
	v_lshlrev_b32_e32 v213, 16, v203
	v_and_b32_e32 v203, 0xffff0000, v203
	v_add_f32_e32 v124, v124, v204
	v_add_f32_e32 v125, v125, v196
	v_add_f32_e32 v126, v126, v205
	v_add_f32_e32 v127, v127, v197
	v_add_f32_e32 v120, v120, v208
	v_add_f32_e32 v121, v121, v198
	v_add_f32_e32 v122, v122, v209
	v_add_f32_e32 v123, v123, v199
	v_add_f32_e32 v196, v112, v212
	v_add_f32_e32 v197, v113, v202
	v_add_f32_e32 v198, v114, v213
	v_add_f32_e32 v199, v115, v203
	v_cvt_pk_bf16_f32 v112, v124, v125
	v_cvt_pk_bf16_f32 v113, v126, v127
	v_cvt_pk_bf16_f32 v114, v120, v121
	v_cvt_pk_bf16_f32 v115, v122, v123
	global_store_dwordx4 v[206:207], v[112:115], off nt
	v_lshlrev_b32_e32 v120, 16, v112
	v_lshlrev_b32_e32 v121, 16, v113
	v_and_b32_e32 v112, 0xffff0000, v112
	v_and_b32_e32 v113, 0xffff0000, v113
	v_lshlrev_b32_e32 v122, 16, v114
	v_and_b32_e32 v114, 0xffff0000, v114
	v_lshlrev_b32_e32 v123, 16, v115
	v_and_b32_e32 v115, 0xffff0000, v115
	v_lshlrev_b32_e32 v210, 16, v200
	v_and_b32_e32 v200, 0xffff0000, v200
	v_lshlrev_b32_e32 v211, 16, v201
	v_mul_f32_e32 v112, v112, v112
	v_mul_f32_e32 v113, v113, v113
	v_mul_f32_e32 v114, v114, v114
	v_mul_f32_e32 v115, v115, v115
	v_and_b32_e32 v201, 0xffff0000, v201
	v_add_f32_e32 v116, v116, v210
	v_add_f32_e32 v117, v117, v200
	v_add_f32_e32 v118, v118, v211
	v_fmac_f32_e32 v112, v120, v120
	v_fmac_f32_e32 v113, v121, v121
	v_fmac_f32_e32 v114, v122, v122
	v_fmac_f32_e32 v115, v123, v123
	v_add_f32_e32 v119, v119, v201
	v_cvt_pk_bf16_f32 v116, v116, v117
	v_cvt_pk_bf16_f32 v117, v118, v119
	v_cvt_pk_bf16_f32 v118, v196, v197
	v_add_f32_e32 v112, v112, v113
	v_add_f32_e32 v113, v114, v115
	v_and_b32_e32 v115, 0xffff0000, v118
	v_cvt_pk_bf16_f32 v119, v198, v199
	v_and_b32_e32 v125, 0xffff0000, v116
	v_add_f32_e32 v112, v112, v113
	v_and_b32_e32 v113, 0xffff0000, v117
	v_lshlrev_b32_e32 v114, 16, v118
	v_and_b32_e32 v121, 0xffff0000, v119
	v_mul_f32_e32 v115, v115, v115
	v_lshlrev_b32_e32 v124, 16, v116
	v_lshlrev_b32_e32 v126, 16, v117
	v_lshlrev_b32_e32 v120, 16, v119
	v_mul_f32_e32 v122, v125, v125
	v_mul_f32_e32 v113, v113, v113
	v_fmac_f32_e32 v115, v114, v114
	v_mul_f32_e32 v114, v121, v121
	v_fmac_f32_e32 v122, v124, v124
	v_fmac_f32_e32 v113, v126, v126
	v_fmac_f32_e32 v114, v120, v120
	v_add_f32_e32 v113, v122, v113
	v_add_f32_e32 v114, v115, v114
	v_add_f32_e32 v113, v113, v114
	v_and_b32_e32 v114, 64, v195
	v_add_f32_e32 v113, v112, v113
	v_xor_b32_e32 v112, 16, v195
	v_add_u32_e32 v115, 64, v114
	v_cmp_lt_i32_e32 vcc, v112, v115
	global_store_dwordx4 v[206:207], v[116:119], off offset:256 nt
	s_nop 0
	v_cndmask_b32_e32 v112, v195, v112, vcc
	v_lshlrev_b32_e32 v112, 2, v112
	ds_bpermute_b32 v114, v112, v113
	s_waitcnt lgkmcnt(0)
	v_add_f32_e32 v114, v113, v114
	v_xor_b32_e32 v113, 32, v195
	v_cmp_lt_i32_e32 vcc, v113, v115
	s_nop 1
	v_cndmask_b32_e32 v113, v195, v113, vcc
	v_lshlrev_b32_e32 v113, 2, v113
	ds_bpermute_b32 v115, v113, v114
	s_and_saveexec_b64 s[26:27], s[0:1]
	s_cbranch_execz .LBB0_2580
	v_lshlrev_b64 v[116:117], 6, v[176:177]
	v_lshl_add_u64 v[116:117], s[66:67], 0, v[116:117]
	v_lshl_add_u64 v[116:117], s[18:19], 2, v[116:117]
	s_lshl_b32 s8, s44, 2
	v_lshl_add_u64 v[116:117], v[116:117], 0, s[8:9]
	s_waitcnt lgkmcnt(0)
	v_add_f32_e32 v114, v114, v115
	global_store_dword v[116:117], v114, off
; DI unsigned pk2(float lo, float hi) { unsigned r; asm volatile("v_cvt_pk_bf16_f32 %0, %1, %2" : "=v"(r) : "v"(lo), "v"(hi)); return r; }
; DI float bflo(unsigned u) { return __uint_as_float(u << 16); }
; DI float bfhi(unsigned u) { return __uint_as_float(u & 0xffff0000u); }
;     DI float upd(u32x4v* px, const u32x4v x, const f32x4 v0, const f32x4 v1) const {
;         u32x4v o; o.x = pk2(bflo(x.x) + v0[0], bfhi(x.x) + v0[1]); o.y = pk2(bflo(x.y) + v0[2], bfhi(x.y) + v0[3]);
;         o.z = pk2(bflo(x.z) + v1[0], bfhi(x.z) + v1[1]); o.w = pk2(bflo(x.w) + v1[2], bfhi(x.w) + v1[3]); *px = o;
;         const float a0 = bflo(o.x), a1 = bfhi(o.x), a2 = bflo(o.y), a3 = bfhi(o.y), a4 = bflo(o.z), a5 = bfhi(o.z), a6 = bflo(o.w), a7 = bfhi(o.w);
;         return ((a0 * a0 + a1 * a1) + (a2 * a2 + a3 * a3)) + ((a4 * a4 + a5 * a5) + (a6 * a6 + a7 * a7));
;     DI void operator()(const f32x4 (&acc)[2][2][4][2], const Unit& u, int wr, int wc, int fr, int fq, const Pre& pre) const {
;     ...
;             for (int m = 0; m < 4; ++m) { const int row = row0 + ai * 128 + m * 16;
;                 float ss = upd((u32x4v*)(XB + (size_t)row * 1024 + cb), x[m][0], acc[ai][0][m][0], acc[ai][0][m][1])
;                          + upd((u32x4v*)(XB + (size_t)row * 1024 + cb + 128), x[m][1], acc[ai][1][m][0], acc[ai][1][m][1]);
;                 ss += __shfl_xor(ss, 16); ss += __shfl_xor(ss, 32);
;                 if (fq == 0) SSQ[(size_t)row * 16 + u.pn * 4 + wc] = ss; } }
.LBB0_2580:
	s_or_b64 exec, exec, s[26:27]
	v_lshlrev_b32_e32 v116, 16, v148
	v_add_f32_e32 v108, v108, v116
	v_and_b32_e32 v116, 0xffff0000, v148
	v_add_f32_e32 v109, v109, v116
	v_cvt_pk_bf16_f32 v108, v108, v109
	v_lshlrev_b32_e32 v109, 16, v149
	v_add_f32_e32 v109, v110, v109
	v_and_b32_e32 v110, 0xffff0000, v149
	v_add_f32_e32 v110, v111, v110
	v_cvt_pk_bf16_f32 v109, v109, v110
	v_lshlrev_b32_e32 v110, 16, v150
	v_add_f32_e32 v104, v104, v110
	v_and_b32_e32 v110, 0xffff0000, v150
	v_add_f32_e32 v105, v105, v110
	v_cvt_pk_bf16_f32 v110, v104, v105
	v_and_b32_e32 v105, 0xffff0000, v151
	v_lshlrev_b32_e32 v104, 16, v151
	v_add_f32_e32 v105, v107, v105
	v_add_f32_e32 v104, v106, v104
	v_cvt_pk_bf16_f32 v111, v104, v105
	v_and_b32_e32 v105, 0xffff0000, v108
	s_waitcnt lgkmcnt(0)
	v_lshl_add_u64 v[114:115], s[64:65], 0, v[190:191]
	v_lshlrev_b32_e32 v104, 16, v108
	v_and_b32_e32 v107, 0xffff0000, v109
	v_mul_f32_e32 v105, v105, v105
	v_lshl_add_u64 v[114:115], v[174:175], 1, v[114:115]
	v_lshlrev_b32_e32 v106, 16, v109
	v_fmac_f32_e32 v105, v104, v104
	v_mul_f32_e32 v104, v107, v107
	global_store_dwordx4 v[114:115], v[108:111], off nt
	v_fmac_f32_e32 v104, v106, v106
	v_add_f32_e32 v104, v105, v104
	v_lshlrev_b32_e32 v108, 16, v110
	v_and_b32_e32 v109, 0xffff0000, v110
	v_lshlrev_b32_e32 v110, 16, v111
	v_and_b32_e32 v111, 0xffff0000, v111
	v_mul_f32_e32 v105, v109, v109
	v_mul_f32_e32 v106, v111, v111
	v_fmac_f32_e32 v105, v108, v108
	v_fmac_f32_e32 v106, v110, v110
	v_add_f32_e32 v105, v105, v106
	v_add_f32_e32 v104, v104, v105
	v_lshlrev_b32_e32 v105, 16, v144
	v_add_f32_e32 v100, v100, v105
	v_and_b32_e32 v105, 0xffff0000, v144
	v_add_f32_e32 v101, v101, v105
	v_cvt_pk_bf16_f32 v100, v100, v101
	v_lshlrev_b32_e32 v101, 16, v145
	v_add_f32_e32 v101, v102, v101
	v_and_b32_e32 v102, 0xffff0000, v145
	v_add_f32_e32 v102, v103, v102
	v_cvt_pk_bf16_f32 v101, v101, v102
	v_lshlrev_b32_e32 v102, 16, v146
	v_add_f32_e32 v96, v96, v102
	v_and_b32_e32 v102, 0xffff0000, v146
	v_add_f32_e32 v97, v97, v102
	v_cvt_pk_bf16_f32 v102, v96, v97
	v_and_b32_e32 v97, 0xffff0000, v147
	v_lshlrev_b32_e32 v96, 16, v147
	v_add_f32_e32 v97, v99, v97
	v_add_f32_e32 v96, v98, v96
	v_cvt_pk_bf16_f32 v103, v96, v97
	v_and_b32_e32 v97, 0xffff0000, v100
	v_lshlrev_b32_e32 v96, 16, v100
	v_and_b32_e32 v99, 0xffff0000, v101
	v_mul_f32_e32 v97, v97, v97
	v_lshlrev_b32_e32 v98, 16, v101
	v_fmac_f32_e32 v97, v96, v96
	v_mul_f32_e32 v96, v99, v99
	v_and_b32_e32 v106, 0xffff0000, v102
	v_and_b32_e32 v108, 0xffff0000, v103
	v_fmac_f32_e32 v96, v98, v98
	v_lshlrev_b32_e32 v105, 16, v102
	v_lshlrev_b32_e32 v107, 16, v103
	v_add_f32_e32 v96, v97, v96
	v_mul_f32_e32 v97, v106, v106
	v_mul_f32_e32 v98, v108, v108
	v_fmac_f32_e32 v97, v105, v105
	v_fmac_f32_e32 v98, v107, v107
	v_add_f32_e32 v97, v97, v98
	v_add_f32_e32 v96, v96, v97
	v_add_f32_e32 v96, v104, v96
	ds_bpermute_b32 v97, v112, v96
	global_store_dwordx4 v[114:115], v[100:103], off offset:256 nt
	s_waitcnt lgkmcnt(0)
	v_add_f32_e32 v96, v96, v97
	ds_bpermute_b32 v97, v113, v96
	s_and_saveexec_b64 s[26:27], s[0:1]
	s_cbranch_execz .LBB0_2582
	v_lshlrev_b64 v[98:99], 6, v[186:187]
	v_lshl_add_u64 v[98:99], s[66:67], 0, v[98:99]
	v_lshl_add_u64 v[98:99], s[18:19], 2, v[98:99]
	s_lshl_b32 s8, s44, 2
	v_lshl_add_u64 v[98:99], v[98:99], 0, s[8:9]
	s_waitcnt lgkmcnt(0)
	v_add_f32_e32 v96, v96, v97
	global_store_dword v[98:99], v96, off
.LBB0_2582:
	s_or_b64 exec, exec, s[26:27]
	v_lshlrev_b32_e32 v98, 16, v140
	v_add_f32_e32 v92, v92, v98
	v_and_b32_e32 v98, 0xffff0000, v140
	v_add_f32_e32 v93, v93, v98
	v_cvt_pk_bf16_f32 v92, v92, v93
	v_lshlrev_b32_e32 v93, 16, v141
	v_add_f32_e32 v93, v94, v93
	v_and_b32_e32 v94, 0xffff0000, v141
	v_add_f32_e32 v94, v95, v94
	v_cvt_pk_bf16_f32 v93, v93, v94
	v_lshlrev_b32_e32 v94, 16, v142
	v_add_f32_e32 v88, v88, v94
	v_and_b32_e32 v94, 0xffff0000, v142
	v_add_f32_e32 v89, v89, v94
	v_cvt_pk_bf16_f32 v94, v88, v89
	v_and_b32_e32 v89, 0xffff0000, v143
	v_lshlrev_b32_e32 v88, 16, v143
	v_add_f32_e32 v89, v91, v89
	v_add_f32_e32 v88, v90, v88
	v_cvt_pk_bf16_f32 v95, v88, v89
	v_and_b32_e32 v89, 0xffff0000, v92
	s_waitcnt lgkmcnt(0)
	v_lshl_add_u64 v[96:97], s[64:65], 0, v[188:189]
	v_lshlrev_b32_e32 v88, 16, v92
	v_and_b32_e32 v91, 0xffff0000, v93
	v_mul_f32_e32 v89, v89, v89
	v_lshl_add_u64 v[96:97], v[174:175], 1, v[96:97]
	v_lshlrev_b32_e32 v90, 16, v93
	v_fmac_f32_e32 v89, v88, v88
	v_mul_f32_e32 v88, v91, v91
	global_store_dwordx4 v[96:97], v[92:95], off nt
	v_fmac_f32_e32 v88, v90, v90
	v_add_f32_e32 v88, v89, v88
	v_lshlrev_b32_e32 v92, 16, v94
	v_and_b32_e32 v93, 0xffff0000, v94
	v_lshlrev_b32_e32 v94, 16, v95
	v_and_b32_e32 v95, 0xffff0000, v95
	v_mul_f32_e32 v89, v93, v93
	v_mul_f32_e32 v90, v95, v95
	v_fmac_f32_e32 v89, v92, v92
	v_fmac_f32_e32 v90, v94, v94
	v_add_f32_e32 v89, v89, v90
	v_add_f32_e32 v88, v88, v89
	v_lshlrev_b32_e32 v89, 16, v136
	v_add_f32_e32 v84, v84, v89
	v_and_b32_e32 v89, 0xffff0000, v136
	v_add_f32_e32 v85, v85, v89
	v_cvt_pk_bf16_f32 v84, v84, v85
	v_lshlrev_b32_e32 v85, 16, v137
	v_add_f32_e32 v85, v86, v85
	v_and_b32_e32 v86, 0xffff0000, v137
	v_add_f32_e32 v86, v87, v86
	v_cvt_pk_bf16_f32 v85, v85, v86
	v_lshlrev_b32_e32 v86, 16, v138
	v_add_f32_e32 v80, v80, v86
	v_and_b32_e32 v86, 0xffff0000, v138
	v_add_f32_e32 v81, v81, v86
	v_cvt_pk_bf16_f32 v86, v80, v81
	v_and_b32_e32 v81, 0xffff0000, v139
	v_lshlrev_b32_e32 v80, 16, v139
	v_add_f32_e32 v81, v83, v81
	v_add_f32_e32 v80, v82, v80
	v_cvt_pk_bf16_f32 v87, v80, v81
	v_and_b32_e32 v81, 0xffff0000, v84
	v_lshlrev_b32_e32 v80, 16, v84
	v_and_b32_e32 v83, 0xffff0000, v85
	v_mul_f32_e32 v81, v81, v81
	v_lshlrev_b32_e32 v82, 16, v85
	v_fmac_f32_e32 v81, v80, v80
	v_mul_f32_e32 v80, v83, v83
	v_and_b32_e32 v90, 0xffff0000, v86
	v_and_b32_e32 v92, 0xffff0000, v87
	v_fmac_f32_e32 v80, v82, v82
	v_lshlrev_b32_e32 v89, 16, v86
	v_lshlrev_b32_e32 v91, 16, v87
	v_add_f32_e32 v80, v81, v80
	v_mul_f32_e32 v81, v90, v90
	v_mul_f32_e32 v82, v92, v92
	v_fmac_f32_e32 v81, v89, v89
	v_fmac_f32_e32 v82, v91, v91
	v_add_f32_e32 v81, v81, v82
	v_add_f32_e32 v80, v80, v81
	v_add_f32_e32 v80, v88, v80
	ds_bpermute_b32 v81, v112, v80
	global_store_dwordx4 v[96:97], v[84:87], off offset:256 nt
	s_waitcnt lgkmcnt(0)
	v_add_f32_e32 v80, v80, v81
	ds_bpermute_b32 v81, v113, v80
	s_and_saveexec_b64 s[26:27], s[0:1]
	s_cbranch_execz .LBB0_2584
	v_lshlrev_b64 v[82:83], 6, v[182:183]
	v_lshl_add_u64 v[82:83], s[66:67], 0, v[82:83]
	v_lshl_add_u64 v[82:83], s[18:19], 2, v[82:83]
	s_lshl_b32 s8, s44, 2
	v_lshl_add_u64 v[82:83], v[82:83], 0, s[8:9]
	s_waitcnt lgkmcnt(0)
	v_add_f32_e32 v80, v80, v81
	global_store_dword v[82:83], v80, off
;     DI void operator()(const f32x4 (&acc)[2][2][4][2], const Unit& u, int wr, int wc, int fr, int fq, const Pre& pre) const {
;         const int cb = u.pn * 256 + wc * 32 + 8 * fq, row0 = u.pm * 256 + wr * 64 + fr;
; #pragma unroll
;         for (int ai = 0; ai < 2; ++ai) {
;             u32x4v x[4][2];
; #pragma unroll
;             for (int m = 0; m < 4; ++m)
; #pragma unroll
;                 for (int bj = 0; bj < 2; ++bj) x[m][bj] = *(const u32x4v*)(XB + (size_t)(row0 + ai * 128 + m * 16) * 1024 + cb + bj * 128);
; #pragma unroll
;             for (int m = 0; m < 4; ++m) { const int row = row0 + ai * 128 + m * 16;
;                 float ss = upd((u32x4v*)(XB + (size_t)row * 1024 + cb), x[m][0], acc[ai][0][m][0], acc[ai][0][m][1])
;                          + upd((u32x4v*)(XB + (size_t)row * 1024 + cb + 128), x[m][1], acc[ai][1][m][0], acc[ai][1][m][1]);
;                 ss += __shfl_xor(ss, 16); ss += __shfl_xor(ss, 32);
;                 if (fq == 0) SSQ[(size_t)row * 16 + u.pn * 4 + wc] = ss; } }
.LBB0_2584:
	s_or_b64 exec, exec, s[26:27]
	v_lshlrev_b32_e32 v82, 16, v132
	v_add_f32_e32 v76, v76, v82
	v_and_b32_e32 v82, 0xffff0000, v132
	v_add_f32_e32 v77, v77, v82
	v_cvt_pk_bf16_f32 v76, v76, v77
	v_lshlrev_b32_e32 v77, 16, v133
	v_add_f32_e32 v77, v78, v77
	v_and_b32_e32 v78, 0xffff0000, v133
	v_add_f32_e32 v78, v79, v78
	v_cvt_pk_bf16_f32 v77, v77, v78
	v_lshlrev_b32_e32 v78, 16, v134
	v_add_f32_e32 v72, v72, v78
	v_and_b32_e32 v78, 0xffff0000, v134
	v_add_f32_e32 v73, v73, v78
	v_cvt_pk_bf16_f32 v78, v72, v73
	v_and_b32_e32 v73, 0xffff0000, v135
	v_lshlrev_b32_e32 v72, 16, v135
	v_add_f32_e32 v73, v75, v73
	v_add_f32_e32 v72, v74, v72
	v_cvt_pk_bf16_f32 v79, v72, v73
	v_and_b32_e32 v73, 0xffff0000, v76
	s_waitcnt lgkmcnt(0)
	v_lshl_add_u64 v[80:81], s[64:65], 0, v[184:185]
	v_lshlrev_b32_e32 v72, 16, v76
	v_and_b32_e32 v75, 0xffff0000, v77
	v_mul_f32_e32 v73, v73, v73
	v_lshl_add_u64 v[80:81], v[174:175], 1, v[80:81]
	v_lshlrev_b32_e32 v74, 16, v77
	v_fmac_f32_e32 v73, v72, v72
	v_mul_f32_e32 v72, v75, v75
	global_store_dwordx4 v[80:81], v[76:79], off nt
	v_fmac_f32_e32 v72, v74, v74
	v_add_f32_e32 v72, v73, v72
	v_lshlrev_b32_e32 v76, 16, v78
	v_and_b32_e32 v77, 0xffff0000, v78
	v_lshlrev_b32_e32 v78, 16, v79
	v_and_b32_e32 v79, 0xffff0000, v79
	v_mul_f32_e32 v73, v77, v77
	v_mul_f32_e32 v74, v79, v79
	v_fmac_f32_e32 v73, v76, v76
	v_fmac_f32_e32 v74, v78, v78
	v_add_f32_e32 v73, v73, v74
	v_add_f32_e32 v72, v72, v73
	v_lshlrev_b32_e32 v73, 16, v128
	v_add_f32_e32 v68, v68, v73
	v_and_b32_e32 v73, 0xffff0000, v128
	v_add_f32_e32 v69, v69, v73
	v_cvt_pk_bf16_f32 v68, v68, v69
	v_lshlrev_b32_e32 v69, 16, v129
	v_add_f32_e32 v69, v70, v69
	v_and_b32_e32 v70, 0xffff0000, v129
	v_add_f32_e32 v70, v71, v70
	v_cvt_pk_bf16_f32 v69, v69, v70
	v_lshlrev_b32_e32 v70, 16, v130
	v_add_f32_e32 v64, v64, v70
	v_and_b32_e32 v70, 0xffff0000, v130
	v_add_f32_e32 v65, v65, v70
	v_cvt_pk_bf16_f32 v70, v64, v65
	v_and_b32_e32 v65, 0xffff0000, v131
	v_lshlrev_b32_e32 v64, 16, v131
	v_add_f32_e32 v65, v67, v65
	v_add_f32_e32 v64, v66, v64
	v_cvt_pk_bf16_f32 v71, v64, v65
	v_and_b32_e32 v65, 0xffff0000, v68
	v_lshlrev_b32_e32 v64, 16, v68
	v_and_b32_e32 v67, 0xffff0000, v69
	v_mul_f32_e32 v65, v65, v65
	v_lshlrev_b32_e32 v66, 16, v69
	v_fmac_f32_e32 v65, v64, v64
	v_mul_f32_e32 v64, v67, v67
	v_and_b32_e32 v74, 0xffff0000, v70
	v_and_b32_e32 v76, 0xffff0000, v71
	v_fmac_f32_e32 v64, v66, v66
	v_lshlrev_b32_e32 v73, 16, v70
	v_lshlrev_b32_e32 v75, 16, v71
	v_add_f32_e32 v64, v65, v64
	v_mul_f32_e32 v65, v74, v74
	v_mul_f32_e32 v66, v76, v76
	v_fmac_f32_e32 v65, v73, v73
	v_fmac_f32_e32 v66, v75, v75
	v_add_f32_e32 v65, v65, v66
	v_add_f32_e32 v64, v64, v65
	v_add_f32_e32 v64, v72, v64
	ds_bpermute_b32 v65, v112, v64
	global_store_dwordx4 v[80:81], v[68:71], off offset:256 nt
	s_waitcnt lgkmcnt(0)
	v_add_f32_e32 v64, v64, v65
	ds_bpermute_b32 v65, v113, v64
	s_and_saveexec_b64 s[26:27], s[0:1]
	s_cbranch_execz .LBB0_2586
	v_lshlrev_b64 v[66:67], 6, v[180:181]
	v_lshl_add_u64 v[66:67], s[66:67], 0, v[66:67]
	v_lshl_add_u64 v[66:67], s[18:19], 2, v[66:67]
	s_lshl_b32 s8, s44, 2
	v_lshl_add_u64 v[66:67], v[66:67], 0, s[8:9]
	s_waitcnt lgkmcnt(0)
	v_add_f32_e32 v64, v64, v65
	global_store_dword v[66:67], v64, off
.LBB0_2586:
	s_or_b64 exec, exec, s[26:27]
	v_add_u32_e32 v98, 0x80, v176
	v_ashrrev_i32_e32 v99, 31, v98
	s_waitcnt lgkmcnt(0)
	v_lshlrev_b64 v[64:65], 11, v[98:99]
	v_lshl_add_u64 v[66:67], v[178:179], 0, v[64:65]
	global_load_dwordx4 v[102:105], v[66:67], off
	global_load_dwordx4 v[106:109], v[66:67], off offset:256
	v_add_u32_e32 v94, 0x90, v176
	v_add_u32_e32 v90, 0xa0, v176
	v_add_u32_e32 v88, 0xb0, v176
	v_ashrrev_i32_e32 v95, 31, v94
	v_ashrrev_i32_e32 v91, 31, v90
	v_ashrrev_i32_e32 v89, 31, v88
	v_lshlrev_b64 v[100:101], 11, v[94:95]
	v_lshlrev_b64 v[96:97], 11, v[90:91]
	v_lshlrev_b64 v[92:93], 11, v[88:89]
	v_lshl_add_u64 v[66:67], v[178:179], 0, v[100:101]
	v_lshl_add_u64 v[68:69], v[178:179], 0, v[96:97]
	v_lshl_add_u64 v[110:111], v[178:179], 0, v[92:93]
	v_lshl_add_u64 v[114:115], s[64:65], 0, v[64:65]
	global_load_dwordx4 v[84:87], v[66:67], off
	global_load_dwordx4 v[80:83], v[66:67], off offset:256
	global_load_dwordx4 v[76:79], v[68:69], off
	global_load_dwordx4 v[72:75], v[68:69], off offset:256
	s_nop 0
	global_load_dwordx4 v[68:71], v[110:111], off
	global_load_dwordx4 v[64:67], v[110:111], off offset:256
	v_lshl_add_u64 v[110:111], v[174:175], 1, v[114:115]
	s_waitcnt vmcnt(7)
	v_lshlrev_b32_e32 v114, 16, v102
	v_and_b32_e32 v102, 0xffff0000, v102
	v_lshlrev_b32_e32 v115, 16, v103
	v_and_b32_e32 v103, 0xffff0000, v103
	v_lshlrev_b32_e32 v116, 16, v104
	v_and_b32_e32 v104, 0xffff0000, v104
	v_lshlrev_b32_e32 v117, 16, v105
	v_and_b32_e32 v105, 0xffff0000, v105
	s_waitcnt vmcnt(6)
;     DI void operator()(const f32x4 (&acc)[2][2][4][2], const Unit& u, int wr, int wc, int fr, int fq, const Pre& pre) const {
;         const int cb = u.pn * 256 + wc * 32 + 8 * fq, row0 = u.pm * 256 + wr * 64 + fr;
; #pragma unroll
;         for (int ai = 0; ai < 2; ++ai) {
;             u32x4v x[4][2];
; #pragma unroll
;             for (int m = 0; m < 4; ++m)
; #pragma unroll
;                 for (int bj = 0; bj < 2; ++bj) x[m][bj] = *(const u32x4v*)(XB + (size_t)(row0 + ai * 128 + m * 16) * 1024 + cb + bj * 128);
; #pragma unroll
;             for (int m = 0; m < 4; ++m) { const int row = row0 + ai * 128 + m * 16;
;                 float ss = upd((u32x4v*)(XB + (size_t)row * 1024 + cb), x[m][0], acc[ai][0][m][0], acc[ai][0][m][1])
;                          + upd((u32x4v*)(XB + (size_t)row * 1024 + cb + 128), x[m][1], acc[ai][1][m][0], acc[ai][1][m][1]);
;                 ss += __shfl_xor(ss, 16); ss += __shfl_xor(ss, 32);
;                 if (fq == 0) SSQ[(size_t)row * 16 + u.pn * 4 + wc] = ss; } }
	v_lshlrev_b32_e32 v120, 16, v108
	v_and_b32_e32 v108, 0xffff0000, v108
	v_lshlrev_b32_e32 v119, 16, v107
	v_and_b32_e32 v107, 0xffff0000, v107
	v_lshlrev_b32_e32 v121, 16, v109
	v_and_b32_e32 v109, 0xffff0000, v109
	v_add_f32_e32 v60, v60, v114
	v_add_f32_e32 v61, v61, v102
	v_add_f32_e32 v62, v62, v115
	v_add_f32_e32 v63, v63, v103
	v_add_f32_e32 v56, v56, v116
	v_add_f32_e32 v57, v57, v104
	v_add_f32_e32 v59, v59, v105
	v_add_f32_e32 v102, v48, v120
	v_add_f32_e32 v103, v49, v108
	v_cvt_pk_bf16_f32 v48, v60, v61
	v_cvt_pk_bf16_f32 v49, v62, v63
	v_lshlrev_b32_e32 v118, 16, v106
	v_and_b32_e32 v106, 0xffff0000, v106
	v_add_f32_e32 v58, v58, v117
	v_add_f32_e32 v54, v54, v119
	v_add_f32_e32 v55, v55, v107
	v_add_f32_e32 v104, v50, v121
	v_add_f32_e32 v105, v51, v109
	v_cvt_pk_bf16_f32 v50, v56, v57
	v_cvt_pk_bf16_f32 v51, v58, v59
	global_store_dwordx4 v[110:111], v[48:51], off nt
	v_lshlrev_b32_e32 v56, 16, v48
	v_lshlrev_b32_e32 v57, 16, v49
	v_and_b32_e32 v48, 0xffff0000, v48
	v_and_b32_e32 v49, 0xffff0000, v49
	v_and_b32_e32 v59, 0xffff0000, v50
	v_and_b32_e32 v61, 0xffff0000, v51
	v_add_f32_e32 v52, v52, v118
	v_add_f32_e32 v53, v53, v106
	v_lshlrev_b32_e32 v58, 16, v50
	v_lshlrev_b32_e32 v60, 16, v51
	v_cvt_pk_bf16_f32 v50, v52, v53
	v_cvt_pk_bf16_f32 v51, v54, v55
	v_mul_f32_e32 v48, v48, v48
	v_mul_f32_e32 v49, v49, v49
	v_mul_f32_e32 v54, v59, v59
	v_mul_f32_e32 v55, v61, v61
	v_and_b32_e32 v61, 0xffff0000, v50
	v_and_b32_e32 v63, 0xffff0000, v51
	v_fmac_f32_e32 v48, v56, v56
	v_fmac_f32_e32 v49, v57, v57
	v_fmac_f32_e32 v54, v58, v58
	v_fmac_f32_e32 v55, v60, v60
	v_lshlrev_b32_e32 v59, 16, v50
	v_lshlrev_b32_e32 v62, 16, v51
	v_add_f32_e32 v48, v48, v49
	v_add_f32_e32 v49, v54, v55
	v_mul_f32_e32 v55, v61, v61
	v_mul_f32_e32 v56, v63, v63
	v_cvt_pk_bf16_f32 v52, v102, v103
	v_cvt_pk_bf16_f32 v53, v104, v105
	v_fmac_f32_e32 v55, v59, v59
	v_and_b32_e32 v103, 0xffff0000, v52
	v_and_b32_e32 v54, 0xffff0000, v53
	v_fmac_f32_e32 v56, v62, v62
	v_lshlrev_b32_e32 v102, 16, v52
	v_add_f32_e32 v48, v48, v49
	v_lshlrev_b32_e32 v49, 16, v53
	v_add_f32_e32 v55, v55, v56
	v_mul_f32_e32 v56, v103, v103
	v_mul_f32_e32 v54, v54, v54
	v_fmac_f32_e32 v56, v102, v102
	v_fmac_f32_e32 v54, v49, v49
	v_add_f32_e32 v49, v56, v54
	v_add_f32_e32 v49, v55, v49
	v_add_f32_e32 v48, v48, v49
	ds_bpermute_b32 v49, v112, v48
	global_store_dwordx4 v[110:111], v[50:53], off offset:256 nt
	s_waitcnt lgkmcnt(0)
	v_add_f32_e32 v48, v48, v49
	ds_bpermute_b32 v49, v113, v48
	s_and_saveexec_b64 s[26:27], s[0:1]
	s_cbranch_execz .LBB0_2588
	v_lshlrev_b64 v[50:51], 6, v[98:99]
	v_lshl_add_u64 v[50:51], s[66:67], 0, v[50:51]
	v_lshl_add_u64 v[50:51], s[18:19], 2, v[50:51]
	s_lshl_b32 s8, s44, 2
	v_lshl_add_u64 v[50:51], v[50:51], 0, s[8:9]
	s_waitcnt lgkmcnt(0)
	v_add_f32_e32 v48, v48, v49
	global_store_dword v[50:51], v48, off
.LBB0_2588:
	s_or_b64 exec, exec, s[26:27]
	s_waitcnt vmcnt(7)
	v_lshlrev_b32_e32 v50, 16, v84
	v_add_f32_e32 v44, v44, v50
	v_and_b32_e32 v50, 0xffff0000, v84
	v_add_f32_e32 v45, v45, v50
	v_cvt_pk_bf16_f32 v44, v44, v45
	v_lshlrev_b32_e32 v45, 16, v85
	v_add_f32_e32 v45, v46, v45
	v_and_b32_e32 v46, 0xffff0000, v85
	v_add_f32_e32 v46, v47, v46
	v_cvt_pk_bf16_f32 v45, v45, v46
	v_lshlrev_b32_e32 v46, 16, v86
	v_add_f32_e32 v40, v40, v46
	v_and_b32_e32 v46, 0xffff0000, v86
	v_add_f32_e32 v41, v41, v46
	v_cvt_pk_bf16_f32 v46, v40, v41
	v_and_b32_e32 v41, 0xffff0000, v87
	v_lshlrev_b32_e32 v40, 16, v87
	v_add_f32_e32 v41, v43, v41
	v_add_f32_e32 v40, v42, v40
	v_cvt_pk_bf16_f32 v47, v40, v41
	v_and_b32_e32 v41, 0xffff0000, v44
	s_waitcnt lgkmcnt(0)
	v_lshl_add_u64 v[48:49], s[64:65], 0, v[100:101]
	v_lshlrev_b32_e32 v40, 16, v44
	v_and_b32_e32 v43, 0xffff0000, v45
	v_mul_f32_e32 v41, v41, v41
	v_lshl_add_u64 v[48:49], v[174:175], 1, v[48:49]
	v_lshlrev_b32_e32 v42, 16, v45
	v_fmac_f32_e32 v41, v40, v40
	v_mul_f32_e32 v40, v43, v43
	global_store_dwordx4 v[48:49], v[44:47], off nt
	v_fmac_f32_e32 v40, v42, v42
	v_add_f32_e32 v40, v41, v40
	v_lshlrev_b32_e32 v44, 16, v46
	v_and_b32_e32 v45, 0xffff0000, v46
	v_lshlrev_b32_e32 v46, 16, v47
	v_and_b32_e32 v47, 0xffff0000, v47
	v_mul_f32_e32 v41, v45, v45
	v_mul_f32_e32 v42, v47, v47
	v_fmac_f32_e32 v41, v44, v44
	v_fmac_f32_e32 v42, v46, v46
	v_add_f32_e32 v41, v41, v42
	v_add_f32_e32 v40, v40, v41
	s_waitcnt vmcnt(7)
	v_lshlrev_b32_e32 v41, 16, v80
	v_add_f32_e32 v36, v36, v41
	v_and_b32_e32 v41, 0xffff0000, v80
	v_add_f32_e32 v37, v37, v41
	v_cvt_pk_bf16_f32 v36, v36, v37
	v_lshlrev_b32_e32 v37, 16, v81
	v_add_f32_e32 v37, v38, v37
	v_and_b32_e32 v38, 0xffff0000, v81
	v_add_f32_e32 v38, v39, v38
	v_cvt_pk_bf16_f32 v37, v37, v38
	v_lshlrev_b32_e32 v38, 16, v82
	v_add_f32_e32 v32, v32, v38
	v_and_b32_e32 v38, 0xffff0000, v82
	v_add_f32_e32 v33, v33, v38
	v_cvt_pk_bf16_f32 v38, v32, v33
	v_and_b32_e32 v33, 0xffff0000, v83
	v_lshlrev_b32_e32 v32, 16, v83
	v_add_f32_e32 v33, v35, v33
	v_add_f32_e32 v32, v34, v32
	v_cvt_pk_bf16_f32 v39, v32, v33
	v_and_b32_e32 v33, 0xffff0000, v36
	v_lshlrev_b32_e32 v32, 16, v36
	v_and_b32_e32 v35, 0xffff0000, v37
	v_mul_f32_e32 v33, v33, v33
	v_lshlrev_b32_e32 v34, 16, v37
	v_fmac_f32_e32 v33, v32, v32
	v_mul_f32_e32 v32, v35, v35
	v_and_b32_e32 v42, 0xffff0000, v38
	v_and_b32_e32 v44, 0xffff0000, v39
	v_fmac_f32_e32 v32, v34, v34
	v_lshlrev_b32_e32 v41, 16, v38
	v_lshlrev_b32_e32 v43, 16, v39
	v_add_f32_e32 v32, v33, v32
	v_mul_f32_e32 v33, v42, v42
	v_mul_f32_e32 v34, v44, v44
	v_fmac_f32_e32 v33, v41, v41
	v_fmac_f32_e32 v34, v43, v43
	v_add_f32_e32 v33, v33, v34
	v_add_f32_e32 v32, v32, v33
	v_add_f32_e32 v32, v40, v32
	ds_bpermute_b32 v33, v112, v32
	global_store_dwordx4 v[48:49], v[36:39], off offset:256 nt
	s_waitcnt lgkmcnt(0)
	v_add_f32_e32 v32, v32, v33
	ds_bpermute_b32 v33, v113, v32
	s_and_saveexec_b64 s[26:27], s[0:1]
	s_cbranch_execz .LBB0_2590
	v_lshlrev_b64 v[34:35], 6, v[94:95]
	v_lshl_add_u64 v[34:35], s[66:67], 0, v[34:35]
	v_lshl_add_u64 v[34:35], s[18:19], 2, v[34:35]
	s_lshl_b32 s8, s44, 2
	v_lshl_add_u64 v[34:35], v[34:35], 0, s[8:9]
	s_waitcnt lgkmcnt(0)
	v_add_f32_e32 v32, v32, v33
	global_store_dword v[34:35], v32, off
; DI unsigned pk2(float lo, float hi) { unsigned r; asm volatile("v_cvt_pk_bf16_f32 %0, %1, %2" : "=v"(r) : "v"(lo), "v"(hi)); return r; }
; DI float bflo(unsigned u) { return __uint_as_float(u << 16); }
; DI float bfhi(unsigned u) { return __uint_as_float(u & 0xffff0000u); }
;     DI float upd(u32x4v* px, const u32x4v x, const f32x4 v0, const f32x4 v1) const {
;         u32x4v o; o.x = pk2(bflo(x.x) + v0[0], bfhi(x.x) + v0[1]); o.y = pk2(bflo(x.y) + v0[2], bfhi(x.y) + v0[3]);
;         o.z = pk2(bflo(x.z) + v1[0], bfhi(x.z) + v1[1]); o.w = pk2(bflo(x.w) + v1[2], bfhi(x.w) + v1[3]); *px = o;
;         const float a0 = bflo(o.x), a1 = bfhi(o.x), a2 = bflo(o.y), a3 = bfhi(o.y), a4 = bflo(o.z), a5 = bfhi(o.z), a6 = bflo(o.w), a7 = bfhi(o.w);
;         return ((a0 * a0 + a1 * a1) + (a2 * a2 + a3 * a3)) + ((a4 * a4 + a5 * a5) + (a6 * a6 + a7 * a7));
;     DI void operator()(const f32x4 (&acc)[2][2][4][2], const Unit& u, int wr, int wc, int fr, int fq, const Pre& pre) const {
;     ...
;             for (int m = 0; m < 4; ++m) { const int row = row0 + ai * 128 + m * 16;
;                 float ss = upd((u32x4v*)(XB + (size_t)row * 1024 + cb), x[m][0], acc[ai][0][m][0], acc[ai][0][m][1])
;                          + upd((u32x4v*)(XB + (size_t)row * 1024 + cb + 128), x[m][1], acc[ai][1][m][0], acc[ai][1][m][1]);
;                 ss += __shfl_xor(ss, 16); ss += __shfl_xor(ss, 32);
;                 if (fq == 0) SSQ[(size_t)row * 16 + u.pn * 4 + wc] = ss; } }
.LBB0_2590:
	s_or_b64 exec, exec, s[26:27]
	s_waitcnt vmcnt(7)
	v_lshlrev_b32_e32 v34, 16, v76
	v_add_f32_e32 v28, v28, v34
	v_and_b32_e32 v34, 0xffff0000, v76
	v_add_f32_e32 v29, v29, v34
	v_cvt_pk_bf16_f32 v28, v28, v29
	v_lshlrev_b32_e32 v29, 16, v77
	v_add_f32_e32 v29, v30, v29
	v_and_b32_e32 v30, 0xffff0000, v77
	v_add_f32_e32 v30, v31, v30
	v_cvt_pk_bf16_f32 v29, v29, v30
	v_lshlrev_b32_e32 v30, 16, v78
	v_add_f32_e32 v24, v24, v30
	v_and_b32_e32 v30, 0xffff0000, v78
	v_add_f32_e32 v25, v25, v30
	v_cvt_pk_bf16_f32 v30, v24, v25
	v_and_b32_e32 v25, 0xffff0000, v79
	v_lshlrev_b32_e32 v24, 16, v79
	v_add_f32_e32 v25, v27, v25
	v_add_f32_e32 v24, v26, v24
	v_cvt_pk_bf16_f32 v31, v24, v25
	v_and_b32_e32 v25, 0xffff0000, v28
	s_waitcnt lgkmcnt(0)
	v_lshl_add_u64 v[32:33], s[64:65], 0, v[96:97]
	v_lshlrev_b32_e32 v24, 16, v28
	v_and_b32_e32 v27, 0xffff0000, v29
	v_mul_f32_e32 v25, v25, v25
	v_lshl_add_u64 v[32:33], v[174:175], 1, v[32:33]
	v_lshlrev_b32_e32 v26, 16, v29
	v_fmac_f32_e32 v25, v24, v24
	v_mul_f32_e32 v24, v27, v27
	global_store_dwordx4 v[32:33], v[28:31], off nt
	v_fmac_f32_e32 v24, v26, v26
	v_add_f32_e32 v24, v25, v24
	v_lshlrev_b32_e32 v28, 16, v30
	v_and_b32_e32 v29, 0xffff0000, v30
	v_lshlrev_b32_e32 v30, 16, v31
	v_and_b32_e32 v31, 0xffff0000, v31
	v_mul_f32_e32 v25, v29, v29
	v_mul_f32_e32 v26, v31, v31
	v_fmac_f32_e32 v25, v28, v28
	v_fmac_f32_e32 v26, v30, v30
	v_add_f32_e32 v25, v25, v26
	v_add_f32_e32 v24, v24, v25
	s_waitcnt vmcnt(7)
	v_lshlrev_b32_e32 v25, 16, v72
	v_add_f32_e32 v20, v20, v25
	v_and_b32_e32 v25, 0xffff0000, v72
	v_add_f32_e32 v21, v21, v25
	v_cvt_pk_bf16_f32 v20, v20, v21
	v_lshlrev_b32_e32 v21, 16, v73
	v_add_f32_e32 v21, v22, v21
	v_and_b32_e32 v22, 0xffff0000, v73
	v_add_f32_e32 v22, v23, v22
	v_cvt_pk_bf16_f32 v21, v21, v22
	v_lshlrev_b32_e32 v22, 16, v74
	v_add_f32_e32 v16, v16, v22
	v_and_b32_e32 v22, 0xffff0000, v74
	v_add_f32_e32 v17, v17, v22
	v_cvt_pk_bf16_f32 v22, v16, v17
	v_and_b32_e32 v17, 0xffff0000, v75
	v_lshlrev_b32_e32 v16, 16, v75
	v_add_f32_e32 v17, v19, v17
	v_add_f32_e32 v16, v18, v16
	v_cvt_pk_bf16_f32 v23, v16, v17
	v_and_b32_e32 v17, 0xffff0000, v20
	v_lshlrev_b32_e32 v16, 16, v20
	v_and_b32_e32 v19, 0xffff0000, v21
	v_mul_f32_e32 v17, v17, v17
	v_lshlrev_b32_e32 v18, 16, v21
	v_fmac_f32_e32 v17, v16, v16
	v_mul_f32_e32 v16, v19, v19
	v_and_b32_e32 v26, 0xffff0000, v22
	v_and_b32_e32 v28, 0xffff0000, v23
	v_fmac_f32_e32 v16, v18, v18
	v_lshlrev_b32_e32 v25, 16, v22
	v_lshlrev_b32_e32 v27, 16, v23
	v_add_f32_e32 v16, v17, v16
	v_mul_f32_e32 v17, v26, v26
	v_mul_f32_e32 v18, v28, v28
	v_fmac_f32_e32 v17, v25, v25
	v_fmac_f32_e32 v18, v27, v27
	v_add_f32_e32 v17, v17, v18
	v_add_f32_e32 v16, v16, v17
	v_add_f32_e32 v16, v24, v16
	ds_bpermute_b32 v17, v112, v16
	global_store_dwordx4 v[32:33], v[20:23], off offset:256 nt
	s_waitcnt lgkmcnt(0)
	v_add_f32_e32 v16, v16, v17
	ds_bpermute_b32 v17, v113, v16
	s_and_saveexec_b64 s[26:27], s[0:1]
	s_cbranch_execz .LBB0_2592
	v_lshlrev_b64 v[18:19], 6, v[90:91]
	v_lshl_add_u64 v[18:19], s[66:67], 0, v[18:19]
	v_lshl_add_u64 v[18:19], s[18:19], 2, v[18:19]
	s_lshl_b32 s8, s44, 2
	v_lshl_add_u64 v[18:19], v[18:19], 0, s[8:9]
	s_waitcnt lgkmcnt(0)
	v_add_f32_e32 v16, v16, v17
	global_store_dword v[18:19], v16, off
.LBB0_2592:
	s_or_b64 exec, exec, s[26:27]
	s_waitcnt vmcnt(7)
	v_lshlrev_b32_e32 v18, 16, v68
	v_add_f32_e32 v12, v12, v18
	v_and_b32_e32 v18, 0xffff0000, v68
	v_add_f32_e32 v13, v13, v18
	v_cvt_pk_bf16_f32 v12, v12, v13
	v_lshlrev_b32_e32 v13, 16, v69
	v_add_f32_e32 v13, v14, v13
	v_and_b32_e32 v14, 0xffff0000, v69
	v_add_f32_e32 v14, v15, v14
	v_cvt_pk_bf16_f32 v13, v13, v14
	v_lshlrev_b32_e32 v14, 16, v70
	v_add_f32_e32 v8, v8, v14
	v_and_b32_e32 v14, 0xffff0000, v70
	v_add_f32_e32 v9, v9, v14
	v_cvt_pk_bf16_f32 v14, v8, v9
	v_and_b32_e32 v9, 0xffff0000, v71
	v_lshlrev_b32_e32 v8, 16, v71
	v_add_f32_e32 v9, v11, v9
	v_add_f32_e32 v8, v10, v8
	v_cvt_pk_bf16_f32 v15, v8, v9
	v_and_b32_e32 v9, 0xffff0000, v12
	s_waitcnt lgkmcnt(0)
	v_lshl_add_u64 v[16:17], s[64:65], 0, v[92:93]
	v_lshlrev_b32_e32 v8, 16, v12
	v_and_b32_e32 v11, 0xffff0000, v13
	v_mul_f32_e32 v9, v9, v9
	v_lshl_add_u64 v[16:17], v[174:175], 1, v[16:17]
	v_lshlrev_b32_e32 v10, 16, v13
	v_fmac_f32_e32 v9, v8, v8
	v_mul_f32_e32 v8, v11, v11
	global_store_dwordx4 v[16:17], v[12:15], off nt
	v_fmac_f32_e32 v8, v10, v10
	v_add_f32_e32 v8, v9, v8
	v_lshlrev_b32_e32 v12, 16, v14
	v_and_b32_e32 v13, 0xffff0000, v14
	v_lshlrev_b32_e32 v14, 16, v15
	v_and_b32_e32 v15, 0xffff0000, v15
	v_mul_f32_e32 v9, v13, v13
	v_mul_f32_e32 v10, v15, v15
	v_fmac_f32_e32 v9, v12, v12
	v_fmac_f32_e32 v10, v14, v14
	v_add_f32_e32 v9, v9, v10
	v_add_f32_e32 v8, v8, v9
	s_waitcnt vmcnt(7)
	v_lshlrev_b32_e32 v9, 16, v64
	v_add_f32_e32 v4, v4, v9
	v_and_b32_e32 v9, 0xffff0000, v64
	v_add_f32_e32 v5, v5, v9
	v_cvt_pk_bf16_f32 v4, v4, v5
	v_lshlrev_b32_e32 v5, 16, v65
	v_add_f32_e32 v5, v6, v5
	v_and_b32_e32 v6, 0xffff0000, v65
	v_add_f32_e32 v6, v7, v6
	v_cvt_pk_bf16_f32 v5, v5, v6
	v_lshlrev_b32_e32 v6, 16, v66
	v_add_f32_e32 v0, v0, v6
	v_and_b32_e32 v6, 0xffff0000, v66
	v_add_f32_e32 v1, v1, v6
	v_cvt_pk_bf16_f32 v6, v0, v1
	v_and_b32_e32 v1, 0xffff0000, v67
	v_lshlrev_b32_e32 v0, 16, v67
	v_add_f32_e32 v1, v3, v1
	v_add_f32_e32 v0, v2, v0
	v_cvt_pk_bf16_f32 v7, v0, v1
	v_and_b32_e32 v1, 0xffff0000, v4
	v_lshlrev_b32_e32 v0, 16, v4
	v_and_b32_e32 v3, 0xffff0000, v5
	v_mul_f32_e32 v1, v1, v1
	v_lshlrev_b32_e32 v2, 16, v5
	v_fmac_f32_e32 v1, v0, v0
	v_mul_f32_e32 v0, v3, v3
	v_and_b32_e32 v10, 0xffff0000, v6
	v_and_b32_e32 v12, 0xffff0000, v7
	v_fmac_f32_e32 v0, v2, v2
	v_lshlrev_b32_e32 v9, 16, v6
	v_lshlrev_b32_e32 v11, 16, v7
	v_add_f32_e32 v0, v1, v0
	v_mul_f32_e32 v1, v10, v10
	v_mul_f32_e32 v2, v12, v12
	v_fmac_f32_e32 v1, v9, v9
	v_fmac_f32_e32 v2, v11, v11
	v_add_f32_e32 v1, v1, v2
	v_add_f32_e32 v0, v0, v1
	v_add_f32_e32 v0, v8, v0
	ds_bpermute_b32 v1, v112, v0
	global_store_dwordx4 v[16:17], v[4:7], off offset:256 nt
	s_waitcnt lgkmcnt(0)
	v_add_f32_e32 v0, v0, v1
	ds_bpermute_b32 v1, v113, v0
	s_and_saveexec_b64 s[26:27], s[0:1]
	s_cbranch_execz .LBB0_2544
	v_readlane_b32 s64, v254, 28
	v_lshlrev_b64 v[2:3], 6, v[88:89]
	v_readlane_b32 s78, v254, 42
	v_readlane_b32 s79, v254, 43
	s_lshl_b32 s8, s44, 2
	s_waitcnt lgkmcnt(0)
	v_add_f32_e32 v0, v0, v1
	v_lshl_add_u64 v[2:3], s[78:79], 0, v[2:3]
	v_lshl_add_u64 v[2:3], s[18:19], 2, v[2:3]
	v_lshl_add_u64 v[2:3], v[2:3], 0, s[8:9]
	v_readlane_b32 s65, v254, 29
	v_readlane_b32 s66, v254, 30
	v_readlane_b32 s67, v254, 31
	v_readlane_b32 s68, v254, 32
	v_readlane_b32 s69, v254, 33
	v_readlane_b32 s70, v254, 34
	v_readlane_b32 s71, v254, 35
	v_readlane_b32 s72, v254, 36
	v_readlane_b32 s73, v254, 37
	v_readlane_b32 s74, v254, 38
	v_readlane_b32 s75, v254, 39
	v_readlane_b32 s76, v254, 40
	v_readlane_b32 s77, v254, 41
	global_store_dword v[2:3], v0, off
	s_branch .LBB0_2544

;     DI void row(const f32x4 (&a4)[2][2], const Unit& u, int ai, int m, int wr, int wc, int fr, int fq) const {
;         const int cb = u.pn * 256 + wc * 32 + 8 * fq, row = u.pm * 256 + wr * 64 + fr + ai * 128 + m * 16;
;         u32x4v* p0 = (u32x4v*)(XB + (size_t)row * 1024 + cb); u32x4v* p1 = (u32x4v*)(XB + (size_t)row * 1024 + cb + 128);
;         const u32x4v x0 = *p0, x1 = *p1;
;         float ss = upd(p0, x0, a4[0][0], a4[0][1]) + upd(p1, x1, a4[1][0], a4[1][1]);
;         ss += __shfl_xor(ss, 16); ss += __shfl_xor(ss, 32);
;         if (fq == 0) SSQ[(size_t)row * 16 + u.pn * 4 + wc] = ss;
;     }
; template <class Epi> DI void gemm_fixup(int N, int K, const Epi& E, const float* part, int tid) {
;     ...
;     for (int it = blockIdx.x; it < S.ntail * 8; it += gridDim.x) { const int j = it >> 3, ai = (it >> 2) & 1, m = it & 3; Unit u; S.map(S.nwhole * S.G + j, u);
;         f32x4 a4[2][2];
; #pragma unroll
;         for (int b = 0; b < 2; ++b)
; #pragma unroll
;             for (int n = 0; n < 2; ++n) { const f32x4* pp = (const f32x4*)part + ((size_t)(j * S.S) * 32 + (((ai * 2 + b) * 4 + m) * 2 + n)) * 512 + tid;
;                 f32x4 v0 = {0.f, 0.f, 0.f, 0.f}, v1 = v0, v2 = v0, v3 = v0;
;                 for (int sl = 0; sl + 3 < S.S; sl += 4) { v0 += pp[(size_t)sl * 16384]; v1 += pp[(size_t)(sl + 1) * 16384]; v2 += pp[(size_t)(sl + 2) * 16384]; v3 += pp[(size_t)(sl + 3) * 16384]; }
;                 for (int sl = S.S & ~3; sl < S.S; ++sl) v0 += pp[(size_t)sl * 16384];
;                 a4[b][n] = (v0 + v1) + (v2 + v3); }
;         E.row(a4, u, ai, m, wr, wc, fr, fq); }
.LBB0_2693:
	s_add_i32 s4, s21, s24
	s_ashr_i32 s5, s4, 31
	s_lshr_b32 s5, s5, 27
	s_add_i32 s5, s4, s5
	s_ashr_i32 s14, s5, 5
	s_lshl_b32 s15, s14, 3
	s_sub_i32 s14, 0x83, s15
	s_min_i32 s21, s14, 8
	s_abs_i32 s14, s21
	v_cvt_f32_u32_e32 v1, s14
	s_sub_i32 s24, 0, s14
	s_andn2_b32 s5, s5, 31
	s_sub_i32 s4, s4, s5
	v_rcp_iflag_f32_e32 v1, v1
	s_abs_i32 s5, s4
	s_xor_b32 s22, s4, s21
	s_ashr_i32 s22, s22, 31
	v_mul_f32_e32 v1, 0x4f7ffffe, v1
	v_cvt_u32_f32_e32 v1, v1
	v_readlane_b32 s44, v254, 28
	v_readlane_b32 s56, v254, 40
	v_readlane_b32 s57, v254, 41
	v_readfirstlane_b32 s25, v1
	s_mul_i32 s24, s24, s25
	s_mul_hi_u32 s24, s25, s24
	s_add_i32 s25, s25, s24
	s_mul_hi_u32 s24, s5, s25
	s_mul_i32 s25, s24, s14
	s_sub_i32 s5, s5, s25
	s_add_i32 s26, s24, 1
	s_sub_i32 s25, s5, s14
	s_cmp_ge_u32 s5, s14
	s_cselect_b32 s24, s26, s24
	s_cselect_b32 s5, s25, s5
	s_add_i32 s25, s24, 1
	s_cmp_ge_u32 s5, s14
	s_cselect_b32 s5, s25, s24
	s_xor_b32 s5, s5, s22
	s_sub_i32 s14, s5, s22
	s_mul_i32 s5, s14, s21
	s_sub_i32 s4, s4, s5
	s_and_b32 s23, s23, 1
	s_add_i32 s15, s15, s4
	s_and_b32 s4, s84, 3
	s_lshl_b32 s5, s15, 8
	s_lshl_b32 s15, s23, 7
	v_lshl_or_b32 v1, s4, 4, v87
	s_or_b32 s4, s5, s15
	v_add_u32_e32 v2, s4, v1
	v_ashrrev_i32_e32 v3, 31, v2
	v_lshl_or_b32 v90, s14, 8, v86
	v_lshlrev_b64 v[92:93], 11, v[2:3]
	v_lshl_add_u64 v[92:93], s[56:57], 0, v[92:93]
	v_ashrrev_i32_e32 v91, 31, v90
	v_lshl_add_u64 v[98:99], v[90:91], 1, v[92:93]
	global_load_dwordx4 v[90:93], v[98:99], off
	global_load_dwordx4 v[94:97], v[98:99], off offset:256
	v_pk_add_f32 v[6:7], v[48:49], v[6:7]
	v_pk_add_f32 v[4:5], v[46:47], v[4:5]
	v_pk_add_f32 v[38:39], v[44:45], v[38:39]
	v_pk_add_f32 v[40:41], v[42:43], v[40:41]
	v_pk_add_f32 v[10:11], v[60:61], v[10:11]
	v_pk_add_f32 v[8:9], v[58:59], v[8:9]
	v_pk_add_f32 v[50:51], v[56:57], v[50:51]
	v_pk_add_f32 v[52:53], v[54:55], v[52:53]
	v_pk_add_f32 v[16:17], v[82:83], v[16:17]
	v_pk_add_f32 v[42:43], v[80:81], v[74:75]
	v_pk_add_f32 v[6:7], v[40:41], v[6:7]
	v_pk_add_f32 v[4:5], v[38:39], v[4:5]
	v_pk_add_f32 v[14:15], v[72:73], v[14:15]
	v_pk_add_f32 v[12:13], v[70:71], v[12:13]
	v_pk_add_f32 v[62:63], v[68:69], v[62:63]
	v_pk_add_f32 v[64:65], v[66:67], v[64:65]
	v_pk_add_f32 v[18:19], v[84:85], v[18:19]
	v_pk_add_f32 v[44:45], v[78:79], v[76:77]
	v_pk_add_f32 v[10:11], v[52:53], v[10:11]
	v_pk_add_f32 v[8:9], v[50:51], v[8:9]
	v_pk_add_f32 v[16:17], v[42:43], v[16:17]
	v_pk_add_f32 v[14:15], v[64:65], v[14:15]
	v_pk_add_f32 v[12:13], v[62:63], v[12:13]
	v_pk_add_f32 v[18:19], v[44:45], v[18:19]
	v_readlane_b32 s45, v254, 29
	v_readlane_b32 s46, v254, 30
	v_readlane_b32 s47, v254, 31
	v_readlane_b32 s48, v254, 32
	v_readlane_b32 s49, v254, 33
	v_readlane_b32 s50, v254, 34
	v_readlane_b32 s51, v254, 35
	v_readlane_b32 s52, v254, 36
	v_readlane_b32 s53, v254, 37
	v_readlane_b32 s54, v254, 38
	v_readlane_b32 s55, v254, 39
	v_readlane_b32 s58, v254, 42
	v_readlane_b32 s59, v254, 43
	s_waitcnt vmcnt(1)
	v_lshlrev_b32_e32 v1, 16, v90
	v_and_b32_e32 v37, 0xffff0000, v90
	v_lshlrev_b32_e32 v38, 16, v91
	v_and_b32_e32 v39, 0xffff0000, v91
	v_lshlrev_b32_e32 v40, 16, v92
	v_and_b32_e32 v41, 0xffff0000, v92
	v_lshlrev_b32_e32 v42, 16, v93
	v_add_f32_e32 v1, v4, v1
	v_add_f32_e32 v4, v5, v37
	v_add_f32_e32 v5, v6, v38
	v_and_b32_e32 v43, 0xffff0000, v93
	s_waitcnt vmcnt(0)
	v_lshlrev_b32_e32 v44, 16, v94
	v_and_b32_e32 v45, 0xffff0000, v94
	v_lshlrev_b32_e32 v46, 16, v95
	v_and_b32_e32 v47, 0xffff0000, v95
	v_lshlrev_b32_e32 v48, 16, v96
	v_and_b32_e32 v49, 0xffff0000, v96
	v_lshlrev_b32_e32 v50, 16, v97
	v_add_f32_e32 v6, v7, v39
	v_add_f32_e32 v7, v8, v40
	v_add_f32_e32 v8, v9, v41
	v_add_f32_e32 v9, v10, v42
	v_cvt_pk_bf16_f32 v4, v1, v4
	v_cvt_pk_bf16_f32 v5, v5, v6
	v_add_f32_e32 v10, v11, v43
	v_add_f32_e32 v11, v12, v44
	v_add_f32_e32 v12, v13, v45
	v_add_f32_e32 v13, v14, v46
	v_add_f32_e32 v14, v15, v47
	v_add_f32_e32 v15, v16, v48
	v_add_f32_e32 v16, v17, v49
	v_add_f32_e32 v17, v18, v50
	v_cvt_pk_bf16_f32 v6, v7, v8
	v_cvt_pk_bf16_f32 v7, v9, v10
	global_store_dwordx4 v[98:99], v[4:7], off nt
	v_lshlrev_b32_e32 v1, 16, v4
	v_lshlrev_b32_e32 v9, 16, v5
	v_and_b32_e32 v4, 0xffff0000, v4
	v_and_b32_e32 v5, 0xffff0000, v5
	v_and_b32_e32 v18, 0xffff0000, v6
	v_and_b32_e32 v38, 0xffff0000, v7
	v_lshlrev_b32_e32 v10, 16, v6
	v_lshlrev_b32_e32 v37, 16, v7
	v_cvt_pk_bf16_f32 v6, v11, v12
	v_mul_f32_e32 v4, v4, v4
	v_mul_f32_e32 v5, v5, v5
	v_mul_f32_e32 v11, v18, v18
	v_mul_f32_e32 v12, v38, v38
	v_fmac_f32_e32 v4, v1, v1
	v_fmac_f32_e32 v5, v9, v9
	v_fmac_f32_e32 v11, v10, v10
	v_fmac_f32_e32 v12, v37, v37
	v_add_f32_e32 v1, v4, v5
	v_add_f32_e32 v4, v11, v12
	v_add_f32_e32 v1, v1, v4
	v_and_b32_e32 v4, 0xffff0000, v97
	v_add_f32_e32 v4, v19, v4
	v_and_b32_e32 v5, 0xffff0000, v6
	v_cvt_pk_bf16_f32 v7, v13, v14
	v_cvt_pk_bf16_f32 v8, v15, v16
	v_cvt_pk_bf16_f32 v9, v17, v4
	v_lshlrev_b32_e32 v4, 16, v6
	v_and_b32_e32 v11, 0xffff0000, v7
	v_mul_f32_e32 v5, v5, v5
	v_lshlrev_b32_e32 v10, 16, v7
	v_fmac_f32_e32 v5, v4, v4
	v_mul_f32_e32 v4, v11, v11
	v_and_b32_e32 v13, 0xffff0000, v8
	v_and_b32_e32 v15, 0xffff0000, v9
	v_fmac_f32_e32 v4, v10, v10
	v_lshlrev_b32_e32 v12, 16, v8
	v_lshlrev_b32_e32 v14, 16, v9
	v_add_f32_e32 v4, v5, v4
	v_mul_f32_e32 v5, v13, v13
	v_mul_f32_e32 v10, v15, v15
	v_fmac_f32_e32 v5, v12, v12
	v_fmac_f32_e32 v10, v14, v14
	v_add_f32_e32 v5, v5, v10
	v_add_f32_e32 v4, v4, v5
	v_and_b32_e32 v5, 64, v88
	v_add_f32_e32 v1, v1, v4
	v_xor_b32_e32 v4, 16, v88
	v_add_u32_e32 v5, 64, v5
	v_cmp_lt_i32_e32 vcc, v4, v5
	global_store_dwordx4 v[98:99], v[6:9], off offset:256 nt
	s_nop 0
	v_cndmask_b32_e32 v4, v88, v4, vcc
	v_lshlrev_b32_e32 v4, 2, v4
	ds_bpermute_b32 v4, v4, v1
	s_waitcnt lgkmcnt(0)
	v_add_f32_e32 v1, v1, v4
	v_xor_b32_e32 v4, 32, v88
	v_cmp_lt_i32_e32 vcc, v4, v5
	s_nop 1
	v_cndmask_b32_e32 v4, v88, v4, vcc
	v_lshlrev_b32_e32 v4, 2, v4
	ds_bpermute_b32 v4, v4, v1
	s_and_saveexec_b64 s[4:5], s[0:1]
	s_xor_b64 s[4:5], exec, s[4:5]
	s_cbranch_execz .LBB0_2660
	v_readlane_b32 s44, v254, 28
	s_lshl_b32 s14, s14, 2
	v_lshlrev_b64 v[2:3], 6, v[2:3]
	v_readlane_b32 s58, v254, 42
	v_readlane_b32 s59, v254, 43
	s_ashr_i32 s15, s14, 31
	v_mov_b32_e32 v37, v0
	v_lshl_add_u64 v[2:3], s[58:59], 0, v[2:3]
	v_lshl_add_u64 v[2:3], s[14:15], 2, v[2:3]
	s_waitcnt lgkmcnt(0)
	v_add_f32_e32 v1, v1, v4
	v_lshl_add_u64 v[2:3], v[2:3], 0, v[36:37]
	v_readlane_b32 s45, v254, 29
	v_readlane_b32 s46, v254, 30
	v_readlane_b32 s47, v254, 31
	v_readlane_b32 s48, v254, 32
	v_readlane_b32 s49, v254, 33
	v_readlane_b32 s50, v254, 34
	v_readlane_b32 s51, v254, 35
	v_readlane_b32 s52, v254, 36
	v_readlane_b32 s53, v254, 37
	v_readlane_b32 s54, v254, 38
	v_readlane_b32 s55, v254, 39
	v_readlane_b32 s56, v254, 40
	v_readlane_b32 s57, v254, 41
	global_store_dword v[2:3], v1, off
	s_branch .LBB0_2660

; DI float bflo(unsigned u) { return __uint_as_float(u << 16); }
; DI float bfhi(unsigned u) { return __uint_as_float(u & 0xffff0000u); }
; DI float row_rinv(const float* SSQ, int row) {
;     const f32x4* s = (const f32x4*)(SSQ + (size_t)row * 16); f32x4 a = s[0] + s[1] + s[2] + s[3];
;     return rsqrtf(((a.x + a.y) + (a.z + a.w)) * (1.f / 1024.f) + EPSN);
; }
; DI void final_norm(const Prm& p, int gw, int NGW, int lane) {
;     for (int r = gw; r < 32768 + 512; r += NGW) {
;         int grow; float* dst;
;         if (r < 32768) { const int b = r >> 12, t = r & 4095; grow = b * TP + 16 + t; dst = p.out + O_YP + (size_t)r * 1024; } else { grow = NTP + (r - 32768); dst = p.out + O_YS + (size_t)(r - 32768) * 1024; }
;         u32x2 x[4];
; #pragma unroll
;         for (int j = 0; j < 4; ++j) x[j] = ((const u32x2*)(p.XB + (size_t)grow * 1024))[lane + 64 * j];
;         const float rr = row_rinv(p.SSQ, grow);
; #pragma unroll
;         for (int j = 0; j < 4; ++j) { f32x4 v; v.x = bflo(x[j].x); v.y = bfhi(x[j].x); v.z = bflo(x[j].y); v.w = bfhi(x[j].y); ((f32x4*)dst)[lane + 64 * j] = v * rr * ((const f32x4*)p.ln_final)[lane + 64 * j]; }
;     }
.Lfn_compute:
	v_pk_add_f32 v[10:11], v[10:11], v[14:15]
	v_pk_add_f32 v[8:9], v[8:9], v[12:13]
	v_pk_add_f32 v[10:11], v[10:11], v[18:19]
	v_pk_add_f32 v[8:9], v[8:9], v[16:17]
	v_pk_add_f32 v[10:11], v[10:11], v[22:23]
	v_pk_add_f32 v[8:9], v[8:9], v[20:21]
	s_nop 0
	v_mov_b32_e32 v13, v10
	v_mov_b32_e32 v12, v9
	v_mov_b32_e32 v9, v11
	s_nop 0
	v_pk_add_f32 v[8:9], v[12:13], v[8:9]
	s_nop 0
	v_add_f32_e32 v7, v8, v9
	v_fmamk_f32 v7, v7, 0x3a800000, v0
	v_cmp_gt_f32_e32 vcc, s13, v7
	v_mul_f32_e32 v8, 0x4b800000, v7
	s_nop 1
	v_cndmask_b32_e32 v7, v7, v8, vcc
	v_rsq_f32_e32 v7, v7
	s_nop 0
	v_mul_f32_e32 v10, 0x45800000, v7
	v_cndmask_b32_e32 v12, v7, v10, vcc
	v_lshlrev_b32_e32 v100, 16, v30
	v_and_b32_e32 v101, 0xffff0000, v30
	v_lshlrev_b32_e32 v102, 16, v31
	v_and_b32_e32 v103, 0xffff0000, v31
	v_pk_mul_f32 v[100:101], v[12:13], v[100:101] op_sel_hi:[0,1]
	v_pk_mul_f32 v[102:103], v[12:13], v[102:103] op_sel_hi:[0,1]
	v_pk_mul_f32 v[84:85], v[40:41], v[100:101]
	v_pk_mul_f32 v[86:87], v[42:43], v[102:103]
	global_store_dwordx4 v6, v[84:87], s[24:25] offset:0 nt
	v_lshlrev_b32_e32 v100, 16, v32
	v_and_b32_e32 v101, 0xffff0000, v32
	v_lshlrev_b32_e32 v102, 16, v33
	v_and_b32_e32 v103, 0xffff0000, v33
	v_pk_mul_f32 v[100:101], v[12:13], v[100:101] op_sel_hi:[0,1]
	v_pk_mul_f32 v[102:103], v[12:13], v[102:103] op_sel_hi:[0,1]
	v_pk_mul_f32 v[88:89], v[44:45], v[100:101]
	v_pk_mul_f32 v[90:91], v[46:47], v[102:103]
	global_store_dwordx4 v6, v[88:91], s[24:25] offset:1024 nt
	v_lshlrev_b32_e32 v100, 16, v34
	v_and_b32_e32 v101, 0xffff0000, v34
	v_lshlrev_b32_e32 v102, 16, v35
	v_and_b32_e32 v103, 0xffff0000, v35
	v_pk_mul_f32 v[100:101], v[12:13], v[100:101] op_sel_hi:[0,1]
	v_pk_mul_f32 v[102:103], v[12:13], v[102:103] op_sel_hi:[0,1]
	v_pk_mul_f32 v[92:93], v[48:49], v[100:101]
	v_pk_mul_f32 v[94:95], v[50:51], v[102:103]
	global_store_dwordx4 v6, v[92:95], s[24:25] offset:2048 nt
	v_lshlrev_b32_e32 v100, 16, v36
	v_and_b32_e32 v101, 0xffff0000, v36
	v_lshlrev_b32_e32 v102, 16, v37
	v_and_b32_e32 v103, 0xffff0000, v37
	v_pk_mul_f32 v[100:101], v[12:13], v[100:101] op_sel_hi:[0,1]
	v_pk_mul_f32 v[102:103], v[12:13], v[102:103] op_sel_hi:[0,1]
	v_pk_mul_f32 v[96:97], v[52:53], v[100:101]
	v_pk_mul_f32 v[98:99], v[54:55], v[102:103]
	global_store_dwordx4 v6, v[96:99], s[24:25] offset:3072 nt
	s_cmp_lt_i32 s37, 0x8200
	s_cbranch_scc0 .LBB0_2754
	s_mov_b32 s34, s37
	s_mov_b64 s[24:25], s[28:29]
	s_waitcnt vmcnt(4)
	v_mov_b64_e32 v[30:31], v[60:61]
	v_mov_b64_e32 v[32:33], v[62:63]
	v_mov_b64_e32 v[34:35], v[64:65]
	v_mov_b64_e32 v[36:37], v[66:67]
	v_mov_b64_e32 v[8:9], v[68:69]
	v_mov_b64_e32 v[10:11], v[70:71]
	v_mov_b64_e32 v[12:13], v[72:73]
	v_mov_b64_e32 v[14:15], v[74:75]
	v_mov_b64_e32 v[16:17], v[76:77]
	v_mov_b64_e32 v[18:19], v[78:79]
	v_mov_b64_e32 v[20:21], v[80:81]
	v_mov_b64_e32 v[22:23], v[82:83]
	s_branch .Lfn_loop
